# comb8 = comb7 + the duplicated post-barrier s_waitcnt lgkmcnt(0) in front of every GEMM MFMA cluster removed (counter already drained before the barrier)
# baseline (speedup 1.0000x reference)
; #define PG8_STAGE(bufoff, gbase, voff) do { _Pragma("unroll") for (int _i = 0; _i < 2; ++_i) \
;         __builtin_amdgcn_global_load_lds((const unsigned*)((const char*)(gbase) + (voff)[_i]), (LAS unsigned*)(lds + (bufoff) + ldsw + _i * 8192), 16, 0, 0); } while (0)
; #define PG8_LDA(dst, b, h) do { _Pragma("unroll") for (int m = 0; m < 4; ++m) _Pragma("unroll") for (int k = 0; k < 2; ++k) dst[m][k] = *(const LAS bf16x8*)(lds + PG8_SA(b, h) + aoff + m * 2048 + k * 1024); } while (0)
; #define PG8_LDB(dst, b, h) do { _Pragma("unroll") for (int n = 0; n < 2; ++n) _Pragma("unroll") for (int k = 0; k < 2; ++k) dst[n][k] = *(const LAS bf16x8*)(lds + PG8_SB(b, h) + boff + n * 2048 + k * 1024); } while (0)
; #define PG8_MMA(ai, bj, At, Bt) do { __builtin_amdgcn_s_setprio(1); _Pragma("unroll") for (int m = 0; m < 4; ++m) _Pragma("unroll") for (int n = 0; n < 2; ++n) _Pragma("unroll") for (int k = 0; k < 2; ++k) \
;         acc[ai][bj][m][n] = __builtin_amdgcn_mfma_f32_16x16x32_bf16(Bt[n][k], At[m][k], acc[ai][bj][m][n], 0, 0, 0); __builtin_amdgcn_s_setprio(0); } while (0)
; template <class Epi>
; __device__ __forceinline__ void gemm_phase(LAS unsigned char* lds, const Gemm g, int G, int c, const Epi& E) {
;     ...
;         const bool has_next = S.next(ui + 1, nxt);
;         const char* nA = has_next ? (const char*)(g.A + (size_t)nxt.pb * g.sA) + (size_t)nxt.pm * 2 * hstepA : cA;
;         const char* nB = has_next ? (const char*)(g.Bt + (size_t)nxt.pb * g.sB) + (size_t)nxt.pn * 2 * hstepB : cB;
; #pragma nounroll
;         for (int t = 0; t < nt; t += 2) {
;             const bool last = (t == nt - 2);
;             const char* a1 = cA + (size_t)(t + 1) * kstep;
;             const char* a2 = last ? nA : cA + (size_t)(t + 2) * kstep; const char* b2 = last ? nB : cB + (size_t)(t + 2) * kstep;
;             const char* a3 = a2 + kstep; const char* b3 = b2 + kstep;
;             PG8_LDB(B0, 0, 0); PG8_LDB(B1, 0, 1); PG8_SCHED; PG8_LDA(At, 0, 0); PG8_STAGE(PG8_SA(1, 1), a1 + hstepA, voffA);
;             PG8_WAIT_V(8); PG8_WAIT_L(0); PG8_BAR; PG8_MMA(0, 0, At, B0); PG8_MMA(0, 1, At, B1); PG8_BAR; PG8_SCHED;
;             PG8_LDA(At, 0, 1); PG8_STAGE(PG8_SB(0, 0), b2, voffB); PG8_STAGE(PG8_SB(0, 1), b2 + hstepB, voffB); PG8_STAGE(PG8_SA(0, 0), a2, voffA);
;             PG8_WAIT_V(8); PG8_WAIT_L(0); PG8_BAR; PG8_MMA(1, 0, At, B0); PG8_MMA(1, 1, At, B1); PG8_BAR; PG8_SCHED;
.LBB0_235:
	s_ashr_i32 s43, s42, 31
	s_lshl_b64 s[52:53], s[42:43], 19
	s_add_u32 s52, s30, s52
	s_addc_u32 s53, s31, s53
	s_and_b64 s[4:5], s[4:5], exec
	s_cselect_b32 s7, s53, s55
	s_cselect_b32 s43, s52, s54
	s_add_u32 s4, s56, 0x40080
	s_addc_u32 s5, s57, 0
	s_add_u32 s45, s54, 0x100
	s_addc_u32 s84, s55, 0
	s_mov_b32 s85, -2
	s_waitcnt lgkmcnt(0)
	ds_read_b128 v[146:149], v152
	ds_read_b128 v[158:161], v152 offset:1024
	ds_read_b128 v[162:165], v152 offset:2048
	ds_read_b128 v[166:169], v152 offset:3072
	ds_read_b128 v[170:173], v153
	ds_read_b128 v[174:177], v153 offset:1024
	ds_read_b128 v[178:181], v153 offset:2048
	ds_read_b128 v[182:185], v153 offset:3072
	s_add_u32 s33, s4, 0xfffc0080
	s_addc_u32 s54, s5, -1
	s_cmp_eq_u32 s85, 12
	s_cselect_b32 s57, s47, s54
	s_cselect_b32 s56, s46, s33
	s_cselect_b32 s55, s7, s84
	s_cselect_b32 s54, s43, s45
	v_lshl_add_u64 v[218:219], s[4:5], 0, v[138:139]
	s_add_i32 m0, s11, 0xc000
	ds_read_b128 v[186:189], v154
	ds_read_b128 v[190:193], v154 offset:1024
	ds_read_b128 v[194:197], v154 offset:2048
	ds_read_b128 v[198:201], v154 offset:3072
	ds_read_b128 v[202:205], v154 offset:4096
	ds_read_b128 v[206:209], v154 offset:5120
	ds_read_b128 v[210:213], v154 offset:6144
	ds_read_b128 v[214:217], v154 offset:7168
	global_load_lds_dwordx4 v[218:219], off
	v_lshl_add_u64 v[218:219], s[4:5], 0, v[140:141]
	s_add_i32 m0, s11, 0xe000
	s_nop 0
	global_load_lds_dwordx4 v[218:219], off
	s_waitcnt vmcnt(8)
	s_waitcnt lgkmcnt(0)
	s_barrier
	s_setprio 0
	v_mfma_f32_16x16x32_bf16 v[126:129], v[146:149], v[186:189], 0
	v_mfma_f32_16x16x32_bf16 v[122:125], v[162:165], v[186:189], 0
	v_mfma_f32_16x16x32_bf16 v[110:113], v[146:149], v[194:197], 0
	v_mfma_f32_16x16x32_bf16 v[106:109], v[162:165], v[194:197], 0
	v_mfma_f32_16x16x32_bf16 v[94:97], v[146:149], v[202:205], 0
	v_mfma_f32_16x16x32_bf16 v[90:93], v[162:165], v[202:205], 0
	v_mfma_f32_16x16x32_bf16 v[78:81], v[146:149], v[210:213], 0
	v_mfma_f32_16x16x32_bf16 v[74:77], v[162:165], v[210:213], 0
	v_mfma_f32_16x16x32_bf16 v[126:129], v[158:161], v[190:193], v[126:129]
	v_mfma_f32_16x16x32_bf16 v[122:125], v[166:169], v[190:193], v[122:125]
	v_mfma_f32_16x16x32_bf16 v[110:113], v[158:161], v[198:201], v[110:113]
	v_mfma_f32_16x16x32_bf16 v[106:109], v[166:169], v[198:201], v[106:109]
	v_mfma_f32_16x16x32_bf16 v[94:97], v[158:161], v[206:209], v[94:97]
	v_mfma_f32_16x16x32_bf16 v[90:93], v[166:169], v[206:209], v[90:93]
	v_mfma_f32_16x16x32_bf16 v[78:81], v[158:161], v[214:217], v[78:81]
	v_mfma_f32_16x16x32_bf16 v[74:77], v[166:169], v[214:217], v[74:77]
	s_setprio 2
	s_setprio 0
	v_mfma_f32_16x16x32_bf16 v[118:121], v[170:173], v[186:189], 0
	v_mfma_f32_16x16x32_bf16 v[114:117], v[178:181], v[186:189], 0
	v_mfma_f32_16x16x32_bf16 v[102:105], v[170:173], v[194:197], 0
	v_mfma_f32_16x16x32_bf16 v[98:101], v[178:181], v[194:197], 0
	v_mfma_f32_16x16x32_bf16 v[86:89], v[170:173], v[202:205], 0
	v_mfma_f32_16x16x32_bf16 v[82:85], v[178:181], v[202:205], 0
	v_mfma_f32_16x16x32_bf16 v[70:73], v[170:173], v[210:213], 0
	v_mfma_f32_16x16x32_bf16 v[66:69], v[178:181], v[210:213], 0
	v_mfma_f32_16x16x32_bf16 v[118:121], v[174:177], v[190:193], v[118:121]
	v_mfma_f32_16x16x32_bf16 v[114:117], v[182:185], v[190:193], v[114:117]
	v_mfma_f32_16x16x32_bf16 v[102:105], v[174:177], v[198:201], v[102:105]
	v_mfma_f32_16x16x32_bf16 v[98:101], v[182:185], v[198:201], v[98:101]
	v_mfma_f32_16x16x32_bf16 v[86:89], v[174:177], v[206:209], v[86:89]
	v_mfma_f32_16x16x32_bf16 v[82:85], v[182:185], v[206:209], v[82:85]
	v_mfma_f32_16x16x32_bf16 v[70:73], v[174:177], v[214:217], v[70:73]
	v_mfma_f32_16x16x32_bf16 v[66:69], v[182:185], v[214:217], v[66:69]
	s_setprio 2
	s_barrier
	s_add_i32 s33, s79, s60
	v_lshl_add_u64 v[218:219], s[54:55], 0, v[132:133]
	s_mov_b32 m0, s33
	ds_read_b128 v[186:189], v154 offset:16384
	ds_read_b128 v[190:193], v154 offset:17408
	ds_read_b128 v[194:197], v154 offset:18432
	ds_read_b128 v[198:201], v154 offset:19456
	ds_read_b128 v[202:205], v154 offset:20480
	ds_read_b128 v[206:209], v154 offset:21504
	ds_read_b128 v[210:213], v154 offset:22528
	ds_read_b128 v[214:217], v154 offset:23552
	global_load_lds_dwordx4 v[218:219], off
	s_add_i32 m0, s33, 0x2000
	s_add_u32 s62, s54, 0x40000
	v_lshl_add_u64 v[220:221], s[54:55], 0, v[136:137]
	s_addc_u32 s63, s55, 0
	s_add_i32 s33, s80, s60
	global_load_lds_dwordx4 v[220:221], off
	v_lshl_add_u64 v[222:223], s[62:63], 0, v[132:133]
	s_mov_b32 m0, s33
	v_lshl_add_u64 v[224:225], s[56:57], 0, v[134:135]
	global_load_lds_dwordx4 v[222:223], off
	v_lshl_add_u64 v[222:223], s[62:63], 0, v[136:137]
	s_add_i32 m0, s33, 0x2000
	s_nop 0
	global_load_lds_dwordx4 v[222:223], off
	v_lshl_add_u64 v[222:223], s[56:57], 0, v[130:131]
	s_mov_b32 m0, s11
	s_nop 0
	global_load_lds_dwordx4 v[222:223], off
	s_mov_b32 m0, s61
	s_nop 0
	global_load_lds_dwordx4 v[224:225], off
	s_waitcnt vmcnt(8)
	s_waitcnt lgkmcnt(0)
	s_barrier
; #define PG8_STAGE(bufoff, gbase, voff) do { _Pragma("unroll") for (int _i = 0; _i < 2; ++_i) \
;         __builtin_amdgcn_global_load_lds((const unsigned*)((const char*)(gbase) + (voff)[_i]), (LAS unsigned*)(lds + (bufoff) + ldsw + _i * 8192), 16, 0, 0); } while (0)
; #define PG8_LDA(dst, b, h) do { _Pragma("unroll") for (int m = 0; m < 4; ++m) _Pragma("unroll") for (int k = 0; k < 2; ++k) dst[m][k] = *(const LAS bf16x8*)(lds + PG8_SA(b, h) + aoff + m * 2048 + k * 1024); } while (0)
; #define PG8_LDB(dst, b, h) do { _Pragma("unroll") for (int n = 0; n < 2; ++n) _Pragma("unroll") for (int k = 0; k < 2; ++k) dst[n][k] = *(const LAS bf16x8*)(lds + PG8_SB(b, h) + boff + n * 2048 + k * 1024); } while (0)
; #define PG8_MMA(ai, bj, At, Bt) do { __builtin_amdgcn_s_setprio(1); _Pragma("unroll") for (int m = 0; m < 4; ++m) _Pragma("unroll") for (int n = 0; n < 2; ++n) _Pragma("unroll") for (int k = 0; k < 2; ++k) \
;         acc[ai][bj][m][n] = __builtin_amdgcn_mfma_f32_16x16x32_bf16(Bt[n][k], At[m][k], acc[ai][bj][m][n], 0, 0, 0); __builtin_amdgcn_s_setprio(0); } while (0)
; #define PG8_WAIT_V(n) asm volatile("s_waitcnt vmcnt(" #n ")" ::: "memory")
; #define PG8_WAIT_L(n) asm volatile("s_waitcnt lgkmcnt(" #n ")" ::: "memory")
; #define PG8_BAR __builtin_amdgcn_s_barrier()
; #define PG8_SCHED __builtin_amdgcn_sched_barrier(0)
; template <class Epi>
; __device__ __forceinline__ void gemm_phase(LAS unsigned char* lds, const Gemm g, int G, int c, const Epi& E) {
;     ...
;             PG8_WAIT_V(8); PG8_WAIT_L(0); PG8_BAR; PG8_MMA(1, 0, At, B0); PG8_MMA(1, 1, At, B1); PG8_BAR; PG8_SCHED;
;             PG8_LDB(B0, 1, 0); PG8_LDB(B1, 1, 1); PG8_SCHED; PG8_LDA(At, 1, 0); PG8_STAGE(PG8_SA(0, 1), a2 + hstepA, voffA);
;             PG8_WAIT_V(8); PG8_WAIT_L(0); PG8_BAR; PG8_MMA(0, 0, At, B0); PG8_MMA(0, 1, At, B1); PG8_BAR; PG8_SCHED;
	s_setprio 0
	v_mfma_f32_16x16x32_bf16 v[62:65], v[146:149], v[186:189], 0
	v_mfma_f32_16x16x32_bf16 v[58:61], v[162:165], v[186:189], 0
	v_mfma_f32_16x16x32_bf16 v[46:49], v[146:149], v[194:197], 0
	v_mfma_f32_16x16x32_bf16 v[42:45], v[162:165], v[194:197], 0
	v_mfma_f32_16x16x32_bf16 v[30:33], v[146:149], v[202:205], 0
	v_mfma_f32_16x16x32_bf16 v[26:29], v[162:165], v[202:205], 0
	v_mfma_f32_16x16x32_bf16 v[14:17], v[146:149], v[210:213], 0
	v_mfma_f32_16x16x32_bf16 v[10:13], v[162:165], v[210:213], 0
	v_mfma_f32_16x16x32_bf16 v[62:65], v[158:161], v[190:193], v[62:65]
	v_mfma_f32_16x16x32_bf16 v[58:61], v[166:169], v[190:193], v[58:61]
	v_mfma_f32_16x16x32_bf16 v[46:49], v[158:161], v[198:201], v[46:49]
	v_mfma_f32_16x16x32_bf16 v[42:45], v[166:169], v[198:201], v[42:45]
	v_mfma_f32_16x16x32_bf16 v[30:33], v[158:161], v[206:209], v[30:33]
	v_mfma_f32_16x16x32_bf16 v[26:29], v[166:169], v[206:209], v[26:29]
	v_mfma_f32_16x16x32_bf16 v[14:17], v[158:161], v[214:217], v[14:17]
	v_mfma_f32_16x16x32_bf16 v[10:13], v[166:169], v[214:217], v[10:13]
	s_setprio 2
	s_setprio 0
	v_mfma_f32_16x16x32_bf16 v[54:57], v[170:173], v[186:189], 0
	v_mfma_f32_16x16x32_bf16 v[50:53], v[178:181], v[186:189], 0
	v_mfma_f32_16x16x32_bf16 v[38:41], v[170:173], v[194:197], 0
	v_mfma_f32_16x16x32_bf16 v[34:37], v[178:181], v[194:197], 0
	v_mfma_f32_16x16x32_bf16 v[22:25], v[170:173], v[202:205], 0
	v_mfma_f32_16x16x32_bf16 v[18:21], v[178:181], v[202:205], 0
	v_mfma_f32_16x16x32_bf16 v[6:9], v[170:173], v[210:213], 0
	v_mfma_f32_16x16x32_bf16 v[2:5], v[178:181], v[210:213], 0
	v_mfma_f32_16x16x32_bf16 v[54:57], v[174:177], v[190:193], v[54:57]
	v_mfma_f32_16x16x32_bf16 v[50:53], v[182:185], v[190:193], v[50:53]
	v_mfma_f32_16x16x32_bf16 v[38:41], v[174:177], v[198:201], v[38:41]
	v_mfma_f32_16x16x32_bf16 v[34:37], v[182:185], v[198:201], v[34:37]
	v_mfma_f32_16x16x32_bf16 v[22:25], v[174:177], v[206:209], v[22:25]
	v_mfma_f32_16x16x32_bf16 v[18:21], v[182:185], v[206:209], v[18:21]
	v_mfma_f32_16x16x32_bf16 v[6:9], v[174:177], v[214:217], v[6:9]
	v_mfma_f32_16x16x32_bf16 v[2:5], v[182:185], v[214:217], v[2:5]
	s_setprio 2
	s_barrier
	s_add_i32 s33, 0, 0x18000
	v_add_u32_e32 v157, s33, v151
	s_add_i32 s62, 0, 0x1c000
	ds_read_b128 v[146:149], v157
	ds_read_b128 v[158:161], v157 offset:1024
	ds_read_b128 v[162:165], v157 offset:2048
	ds_read_b128 v[166:169], v157 offset:3072
	v_add_u32_e32 v157, s62, v151
	ds_read_b128 v[170:173], v157
	ds_read_b128 v[174:177], v157 offset:1024
	ds_read_b128 v[178:181], v157 offset:2048
	ds_read_b128 v[182:185], v157 offset:3072
	s_add_u32 s56, s56, 0x40000
	s_addc_u32 s57, s57, 0
	s_mov_b32 m0, s66
	v_lshl_add_u64 v[226:227], s[56:57], 0, v[130:131]
	ds_read_b128 v[186:189], v154 offset:32768
	ds_read_b128 v[190:193], v154 offset:33792
	ds_read_b128 v[194:197], v154 offset:34816
	ds_read_b128 v[198:201], v154 offset:35840
	ds_read_b128 v[202:205], v154 offset:36864
	ds_read_b128 v[206:209], v154 offset:37888
	ds_read_b128 v[210:213], v154 offset:38912
	ds_read_b128 v[214:217], v154 offset:39936
	global_load_lds_dwordx4 v[226:227], off
	v_lshl_add_u64 v[226:227], s[56:57], 0, v[134:135]
	s_mov_b32 m0, s67
	s_nop 0
	global_load_lds_dwordx4 v[226:227], off
	s_waitcnt vmcnt(8)
	s_waitcnt lgkmcnt(0)
	s_barrier
	s_setprio 0
	v_mfma_f32_16x16x32_bf16 v[126:129], v[146:149], v[186:189], v[126:129]
	v_mfma_f32_16x16x32_bf16 v[122:125], v[162:165], v[186:189], v[122:125]
	v_mfma_f32_16x16x32_bf16 v[110:113], v[146:149], v[194:197], v[110:113]
	v_mfma_f32_16x16x32_bf16 v[106:109], v[162:165], v[194:197], v[106:109]
	v_mfma_f32_16x16x32_bf16 v[94:97], v[146:149], v[202:205], v[94:97]
	v_mfma_f32_16x16x32_bf16 v[90:93], v[162:165], v[202:205], v[90:93]
	v_mfma_f32_16x16x32_bf16 v[78:81], v[146:149], v[210:213], v[78:81]
	v_mfma_f32_16x16x32_bf16 v[74:77], v[162:165], v[210:213], v[74:77]
	v_mfma_f32_16x16x32_bf16 v[126:129], v[158:161], v[190:193], v[126:129]
	v_mfma_f32_16x16x32_bf16 v[122:125], v[166:169], v[190:193], v[122:125]
	v_mfma_f32_16x16x32_bf16 v[110:113], v[158:161], v[198:201], v[110:113]
	v_mfma_f32_16x16x32_bf16 v[106:109], v[166:169], v[198:201], v[106:109]
	v_mfma_f32_16x16x32_bf16 v[94:97], v[158:161], v[206:209], v[94:97]
	v_mfma_f32_16x16x32_bf16 v[90:93], v[166:169], v[206:209], v[90:93]
	v_mfma_f32_16x16x32_bf16 v[78:81], v[158:161], v[214:217], v[78:81]
	v_mfma_f32_16x16x32_bf16 v[74:77], v[166:169], v[214:217], v[74:77]
	s_setprio 2
	s_setprio 0
	v_mfma_f32_16x16x32_bf16 v[118:121], v[170:173], v[186:189], v[118:121]
	v_mfma_f32_16x16x32_bf16 v[114:117], v[178:181], v[186:189], v[114:117]
	v_mfma_f32_16x16x32_bf16 v[102:105], v[170:173], v[194:197], v[102:105]
	v_mfma_f32_16x16x32_bf16 v[98:101], v[178:181], v[194:197], v[98:101]
	v_mfma_f32_16x16x32_bf16 v[86:89], v[170:173], v[202:205], v[86:89]
	v_mfma_f32_16x16x32_bf16 v[82:85], v[178:181], v[202:205], v[82:85]
	v_mfma_f32_16x16x32_bf16 v[70:73], v[170:173], v[210:213], v[70:73]
	v_mfma_f32_16x16x32_bf16 v[66:69], v[178:181], v[210:213], v[66:69]
	v_mfma_f32_16x16x32_bf16 v[118:121], v[174:177], v[190:193], v[118:121]
	v_mfma_f32_16x16x32_bf16 v[114:117], v[182:185], v[190:193], v[114:117]
	v_mfma_f32_16x16x32_bf16 v[102:105], v[174:177], v[198:201], v[102:105]
	v_mfma_f32_16x16x32_bf16 v[98:101], v[182:185], v[198:201], v[98:101]
	v_mfma_f32_16x16x32_bf16 v[86:89], v[174:177], v[206:209], v[86:89]
	v_mfma_f32_16x16x32_bf16 v[82:85], v[182:185], v[206:209], v[82:85]
	v_mfma_f32_16x16x32_bf16 v[70:73], v[174:177], v[214:217], v[70:73]
	v_mfma_f32_16x16x32_bf16 v[66:69], v[182:185], v[214:217], v[66:69]
	s_setprio 2
	s_barrier
; #define PG8_STAGE(bufoff, gbase, voff) do { _Pragma("unroll") for (int _i = 0; _i < 2; ++_i) \
;         __builtin_amdgcn_global_load_lds((const unsigned*)((const char*)(gbase) + (voff)[_i]), (LAS unsigned*)(lds + (bufoff) + ldsw + _i * 8192), 16, 0, 0); } while (0)
; #define PG8_LDA(dst, b, h) do { _Pragma("unroll") for (int m = 0; m < 4; ++m) _Pragma("unroll") for (int k = 0; k < 2; ++k) dst[m][k] = *(const LAS bf16x8*)(lds + PG8_SA(b, h) + aoff + m * 2048 + k * 1024); } while (0)
; #define PG8_LDB(dst, b, h) do { _Pragma("unroll") for (int n = 0; n < 2; ++n) _Pragma("unroll") for (int k = 0; k < 2; ++k) dst[n][k] = *(const LAS bf16x8*)(lds + PG8_SB(b, h) + boff + n * 2048 + k * 1024); } while (0)
; #define PG8_WAIT_V(n) asm volatile("s_waitcnt vmcnt(" #n ")" ::: "memory")
; #define PG8_WAIT_L(n) asm volatile("s_waitcnt lgkmcnt(" #n ")" ::: "memory")
; template <class Epi>
; __device__ __forceinline__ void gemm_phase(LAS unsigned char* lds, const Gemm g, int G, int c, const Epi& E) {
;     ...
;         for (int t = 0; t < nt; t += 2) {
;             const bool last = (t == nt - 2);
;             const char* a1 = cA + (size_t)(t + 1) * kstep;
;             const char* a2 = last ? nA : cA + (size_t)(t + 2) * kstep; const char* b2 = last ? nB : cB + (size_t)(t + 2) * kstep;
;             const char* a3 = a2 + kstep; const char* b3 = b2 + kstep;
;             PG8_LDB(B0, 0, 0); PG8_LDB(B1, 0, 1); PG8_SCHED; PG8_LDA(At, 0, 0); PG8_STAGE(PG8_SA(1, 1), a1 + hstepA, voffA);
;             PG8_WAIT_V(8); PG8_WAIT_L(0); PG8_BAR; PG8_MMA(0, 0, At, B0); PG8_MMA(0, 1, At, B1); PG8_BAR; PG8_SCHED;
;             PG8_LDA(At, 0, 1); PG8_STAGE(PG8_SB(0, 0), b2, voffB); PG8_STAGE(PG8_SB(0, 1), b2 + hstepB, voffB); PG8_STAGE(PG8_SA(0, 0), a2, voffA);
;             PG8_WAIT_V(8); PG8_WAIT_L(0); PG8_BAR; PG8_MMA(1, 0, At, B0); PG8_MMA(1, 1, At, B1); PG8_BAR; PG8_SCHED;
;             PG8_LDB(B0, 1, 0); PG8_LDB(B1, 1, 1); PG8_SCHED; PG8_LDA(At, 1, 0); PG8_STAGE(PG8_SA(0, 1), a2 + hstepA, voffA);
;             PG8_WAIT_V(8); PG8_WAIT_L(0); PG8_BAR; PG8_MMA(0, 0, At, B0); PG8_MMA(0, 1, At, B1); PG8_BAR; PG8_SCHED;
;             PG8_LDA(At, 1, 1); PG8_STAGE(PG8_SB(1, 0), b3, voffB); PG8_STAGE(PG8_SB(1, 1), b3 + hstepB, voffB); PG8_STAGE(PG8_SA(1, 0), a3, voffA);
;             PG8_WAIT_V(8); PG8_WAIT_L(0); PG8_BAR; PG8_MMA(1, 0, At, B0); PG8_MMA(1, 1, At, B1); PG8_BAR; PG8_SCHED;
	s_add_i32 s33, s33, s60
	v_lshl_add_u64 v[218:219], v[218:219], 0, s[20:21]
	s_mov_b32 m0, s33
	ds_read_b128 v[186:189], v154 offset:49152
	ds_read_b128 v[190:193], v154 offset:50176
	ds_read_b128 v[194:197], v154 offset:51200
	ds_read_b128 v[198:201], v154 offset:52224
	ds_read_b128 v[202:205], v154 offset:53248
	ds_read_b128 v[206:209], v154 offset:54272
	ds_read_b128 v[210:213], v154 offset:55296
	ds_read_b128 v[214:217], v154 offset:56320
	global_load_lds_dwordx4 v[218:219], off
	s_add_i32 m0, s33, 0x2000
	s_add_u32 s54, s54, 0x40080
	v_lshl_add_u64 v[218:219], v[220:221], 0, s[20:21]
	s_addc_u32 s55, s55, 0
	s_add_i32 s33, s62, s60
	global_load_lds_dwordx4 v[218:219], off
	v_lshl_add_u64 v[218:219], s[54:55], 0, v[132:133]
	s_mov_b32 m0, s33
	s_nop 0
	global_load_lds_dwordx4 v[218:219], off
	v_lshl_add_u64 v[218:219], s[54:55], 0, v[136:137]
	s_add_i32 m0, s33, 0x2000
	s_nop 0
	global_load_lds_dwordx4 v[218:219], off
	v_lshl_add_u64 v[218:219], v[222:223], 0, s[20:21]
	s_mov_b32 m0, s71
	s_nop 0
	global_load_lds_dwordx4 v[218:219], off
	v_lshl_add_u64 v[218:219], v[224:225], 0, s[20:21]
	s_mov_b32 m0, s72
	s_nop 0
	global_load_lds_dwordx4 v[218:219], off
	s_waitcnt vmcnt(8)
	s_waitcnt lgkmcnt(0)
	s_barrier
	s_setprio 0
	v_mfma_f32_16x16x32_bf16 v[62:65], v[146:149], v[186:189], v[62:65]
	v_mfma_f32_16x16x32_bf16 v[58:61], v[162:165], v[186:189], v[58:61]
	v_mfma_f32_16x16x32_bf16 v[46:49], v[146:149], v[194:197], v[46:49]
	v_mfma_f32_16x16x32_bf16 v[42:45], v[162:165], v[194:197], v[42:45]
	v_mfma_f32_16x16x32_bf16 v[30:33], v[146:149], v[202:205], v[30:33]
	v_mfma_f32_16x16x32_bf16 v[26:29], v[162:165], v[202:205], v[26:29]
	v_mfma_f32_16x16x32_bf16 v[14:17], v[146:149], v[210:213], v[14:17]
	v_mfma_f32_16x16x32_bf16 v[10:13], v[162:165], v[210:213], v[10:13]
	v_mfma_f32_16x16x32_bf16 v[62:65], v[158:161], v[190:193], v[62:65]
	v_mfma_f32_16x16x32_bf16 v[58:61], v[166:169], v[190:193], v[58:61]
	v_mfma_f32_16x16x32_bf16 v[46:49], v[158:161], v[198:201], v[46:49]
	v_mfma_f32_16x16x32_bf16 v[42:45], v[166:169], v[198:201], v[42:45]
	v_mfma_f32_16x16x32_bf16 v[30:33], v[158:161], v[206:209], v[30:33]
	v_mfma_f32_16x16x32_bf16 v[26:29], v[166:169], v[206:209], v[26:29]
	v_mfma_f32_16x16x32_bf16 v[14:17], v[158:161], v[214:217], v[14:17]
	v_mfma_f32_16x16x32_bf16 v[10:13], v[166:169], v[214:217], v[10:13]
	s_setprio 2
	s_setprio 0
	v_mfma_f32_16x16x32_bf16 v[54:57], v[170:173], v[186:189], v[54:57]
	v_mfma_f32_16x16x32_bf16 v[50:53], v[178:181], v[186:189], v[50:53]
	v_mfma_f32_16x16x32_bf16 v[38:41], v[170:173], v[194:197], v[38:41]
	v_mfma_f32_16x16x32_bf16 v[34:37], v[178:181], v[194:197], v[34:37]
	v_mfma_f32_16x16x32_bf16 v[22:25], v[170:173], v[202:205], v[22:25]
	v_mfma_f32_16x16x32_bf16 v[18:21], v[178:181], v[202:205], v[18:21]
	v_mfma_f32_16x16x32_bf16 v[6:9], v[170:173], v[210:213], v[6:9]
	v_mfma_f32_16x16x32_bf16 v[2:5], v[178:181], v[210:213], v[2:5]
	v_mfma_f32_16x16x32_bf16 v[54:57], v[174:177], v[190:193], v[54:57]
	v_mfma_f32_16x16x32_bf16 v[50:53], v[182:185], v[190:193], v[50:53]
	v_mfma_f32_16x16x32_bf16 v[38:41], v[174:177], v[198:201], v[38:41]
	v_mfma_f32_16x16x32_bf16 v[34:37], v[182:185], v[198:201], v[34:37]
	v_mfma_f32_16x16x32_bf16 v[22:25], v[174:177], v[206:209], v[22:25]
	v_mfma_f32_16x16x32_bf16 v[18:21], v[182:185], v[206:209], v[18:21]
	v_mfma_f32_16x16x32_bf16 v[6:9], v[174:177], v[214:217], v[6:9]
	v_mfma_f32_16x16x32_bf16 v[2:5], v[182:185], v[214:217], v[2:5]
	s_setprio 2
	s_barrier
	s_add_i32 s85, s85, 2
	s_add_u32 s4, s4, 0x100
	s_addc_u32 s5, s5, 0
	s_add_u32 s45, s45, 0x100
	s_addc_u32 s84, s84, 0
	s_cmp_gt_u32 s85, 13
	s_cbranch_scc0 .LBB0_236
.LBB0_236:
	ds_read_b128 v[146:149], v152
	ds_read_b128 v[158:161], v152 offset:1024
	ds_read_b128 v[162:165], v152 offset:2048
	ds_read_b128 v[166:169], v152 offset:3072
	ds_read_b128 v[170:173], v153
	ds_read_b128 v[174:177], v153 offset:1024
	ds_read_b128 v[178:181], v153 offset:2048
	ds_read_b128 v[182:185], v153 offset:3072
	s_add_u32 s33, s4, 0xfffc0080
	s_addc_u32 s54, s5, -1
	s_cmp_eq_u32 s85, 12
	s_cselect_b32 s57, s47, s54
	s_cselect_b32 s56, s46, s33
	s_cselect_b32 s55, s7, s84
	s_cselect_b32 s54, s43, s45
	v_lshl_add_u64 v[218:219], s[4:5], 0, v[138:139]
	s_add_i32 m0, s11, 0xc000
	ds_read_b128 v[186:189], v154
	ds_read_b128 v[190:193], v154 offset:1024
	ds_read_b128 v[194:197], v154 offset:2048
	ds_read_b128 v[198:201], v154 offset:3072
	ds_read_b128 v[202:205], v154 offset:4096
	ds_read_b128 v[206:209], v154 offset:5120
	ds_read_b128 v[210:213], v154 offset:6144
	ds_read_b128 v[214:217], v154 offset:7168
	global_load_lds_dwordx4 v[218:219], off
	v_lshl_add_u64 v[218:219], s[4:5], 0, v[140:141]
	s_add_i32 m0, s11, 0xe000
	s_nop 0
	global_load_lds_dwordx4 v[218:219], off
	s_waitcnt vmcnt(8)
	s_waitcnt lgkmcnt(0)
	s_barrier
; #define PG8_STAGE(bufoff, gbase, voff) do { _Pragma("unroll") for (int _i = 0; _i < 2; ++_i) \
;         __builtin_amdgcn_global_load_lds((const unsigned*)((const char*)(gbase) + (voff)[_i]), (LAS unsigned*)(lds + (bufoff) + ldsw + _i * 8192), 16, 0, 0); } while (0)
; #define PG8_LDA(dst, b, h) do { _Pragma("unroll") for (int m = 0; m < 4; ++m) _Pragma("unroll") for (int k = 0; k < 2; ++k) dst[m][k] = *(const LAS bf16x8*)(lds + PG8_SA(b, h) + aoff + m * 2048 + k * 1024); } while (0)
; #define PG8_LDB(dst, b, h) do { _Pragma("unroll") for (int n = 0; n < 2; ++n) _Pragma("unroll") for (int k = 0; k < 2; ++k) dst[n][k] = *(const LAS bf16x8*)(lds + PG8_SB(b, h) + boff + n * 2048 + k * 1024); } while (0)
; #define PG8_MMA(ai, bj, At, Bt) do { __builtin_amdgcn_s_setprio(1); _Pragma("unroll") for (int m = 0; m < 4; ++m) _Pragma("unroll") for (int n = 0; n < 2; ++n) _Pragma("unroll") for (int k = 0; k < 2; ++k) \
;         acc[ai][bj][m][n] = __builtin_amdgcn_mfma_f32_16x16x32_bf16(Bt[n][k], At[m][k], acc[ai][bj][m][n], 0, 0, 0); __builtin_amdgcn_s_setprio(0); } while (0)
; #define PG8_WAIT_V(n) asm volatile("s_waitcnt vmcnt(" #n ")" ::: "memory")
; #define PG8_WAIT_L(n) asm volatile("s_waitcnt lgkmcnt(" #n ")" ::: "memory")
; #define PG8_BAR __builtin_amdgcn_s_barrier()
; #define PG8_SCHED __builtin_amdgcn_sched_barrier(0)
; template <class Epi>
; __device__ __forceinline__ void gemm_phase(LAS unsigned char* lds, const Gemm g, int G, int c, const Epi& E) {
;     ...
;             PG8_WAIT_V(8); PG8_WAIT_L(0); PG8_BAR; PG8_MMA(0, 0, At, B0); PG8_MMA(0, 1, At, B1); PG8_BAR; PG8_SCHED;
;             PG8_LDA(At, 0, 1); PG8_STAGE(PG8_SB(0, 0), b2, voffB); PG8_STAGE(PG8_SB(0, 1), b2 + hstepB, voffB); PG8_STAGE(PG8_SA(0, 0), a2, voffA);
;             PG8_WAIT_V(8); PG8_WAIT_L(0); PG8_BAR; PG8_MMA(1, 0, At, B0); PG8_MMA(1, 1, At, B1); PG8_BAR; PG8_SCHED;
;             PG8_LDB(B0, 1, 0); PG8_LDB(B1, 1, 1); PG8_SCHED; PG8_LDA(At, 1, 0); PG8_STAGE(PG8_SA(0, 1), a2 + hstepA, voffA);
;             PG8_WAIT_V(8); PG8_WAIT_L(0); PG8_BAR; PG8_MMA(0, 0, At, B0); PG8_MMA(0, 1, At, B1); PG8_BAR; PG8_SCHED;
;             PG8_LDA(At, 1, 1); PG8_STAGE(PG8_SB(1, 0), b3, voffB); PG8_STAGE(PG8_SB(1, 1), b3 + hstepB, voffB); PG8_STAGE(PG8_SA(1, 0), a3, voffA);
	s_setprio 0
	v_mfma_f32_16x16x32_bf16 v[126:129], v[146:149], v[186:189], v[126:129]
	v_mfma_f32_16x16x32_bf16 v[122:125], v[162:165], v[186:189], v[122:125]
	v_mfma_f32_16x16x32_bf16 v[110:113], v[146:149], v[194:197], v[110:113]
	v_mfma_f32_16x16x32_bf16 v[106:109], v[162:165], v[194:197], v[106:109]
	v_mfma_f32_16x16x32_bf16 v[94:97], v[146:149], v[202:205], v[94:97]
	v_mfma_f32_16x16x32_bf16 v[90:93], v[162:165], v[202:205], v[90:93]
	v_mfma_f32_16x16x32_bf16 v[78:81], v[146:149], v[210:213], v[78:81]
	v_mfma_f32_16x16x32_bf16 v[74:77], v[162:165], v[210:213], v[74:77]
	v_mfma_f32_16x16x32_bf16 v[126:129], v[158:161], v[190:193], v[126:129]
	v_mfma_f32_16x16x32_bf16 v[122:125], v[166:169], v[190:193], v[122:125]
	v_mfma_f32_16x16x32_bf16 v[110:113], v[158:161], v[198:201], v[110:113]
	v_mfma_f32_16x16x32_bf16 v[106:109], v[166:169], v[198:201], v[106:109]
	v_mfma_f32_16x16x32_bf16 v[94:97], v[158:161], v[206:209], v[94:97]
	v_mfma_f32_16x16x32_bf16 v[90:93], v[166:169], v[206:209], v[90:93]
	v_mfma_f32_16x16x32_bf16 v[78:81], v[158:161], v[214:217], v[78:81]
	v_mfma_f32_16x16x32_bf16 v[74:77], v[166:169], v[214:217], v[74:77]
	s_setprio 2
	s_setprio 0
	v_mfma_f32_16x16x32_bf16 v[118:121], v[170:173], v[186:189], v[118:121]
	v_mfma_f32_16x16x32_bf16 v[114:117], v[178:181], v[186:189], v[114:117]
	v_mfma_f32_16x16x32_bf16 v[102:105], v[170:173], v[194:197], v[102:105]
	v_mfma_f32_16x16x32_bf16 v[98:101], v[178:181], v[194:197], v[98:101]
	v_mfma_f32_16x16x32_bf16 v[86:89], v[170:173], v[202:205], v[86:89]
	v_mfma_f32_16x16x32_bf16 v[82:85], v[178:181], v[202:205], v[82:85]
	v_mfma_f32_16x16x32_bf16 v[70:73], v[170:173], v[210:213], v[70:73]
	v_mfma_f32_16x16x32_bf16 v[66:69], v[178:181], v[210:213], v[66:69]
	v_mfma_f32_16x16x32_bf16 v[118:121], v[174:177], v[190:193], v[118:121]
	v_mfma_f32_16x16x32_bf16 v[114:117], v[182:185], v[190:193], v[114:117]
	v_mfma_f32_16x16x32_bf16 v[102:105], v[174:177], v[198:201], v[102:105]
	v_mfma_f32_16x16x32_bf16 v[98:101], v[182:185], v[198:201], v[98:101]
	v_mfma_f32_16x16x32_bf16 v[86:89], v[174:177], v[206:209], v[86:89]
	v_mfma_f32_16x16x32_bf16 v[82:85], v[182:185], v[206:209], v[82:85]
	v_mfma_f32_16x16x32_bf16 v[70:73], v[174:177], v[214:217], v[70:73]
	v_mfma_f32_16x16x32_bf16 v[66:69], v[182:185], v[214:217], v[66:69]
	s_setprio 2
	s_barrier
	s_add_i32 s33, s79, s60
	v_lshl_add_u64 v[218:219], s[54:55], 0, v[132:133]
	s_mov_b32 m0, s33
	ds_read_b128 v[186:189], v154 offset:16384
	ds_read_b128 v[190:193], v154 offset:17408
	ds_read_b128 v[194:197], v154 offset:18432
	ds_read_b128 v[198:201], v154 offset:19456
	ds_read_b128 v[202:205], v154 offset:20480
	ds_read_b128 v[206:209], v154 offset:21504
	ds_read_b128 v[210:213], v154 offset:22528
	ds_read_b128 v[214:217], v154 offset:23552
	global_load_lds_dwordx4 v[218:219], off
	s_add_i32 m0, s33, 0x2000
	s_add_u32 s62, s54, 0x40000
	v_lshl_add_u64 v[220:221], s[54:55], 0, v[136:137]
	s_addc_u32 s63, s55, 0
	s_add_i32 s33, s80, s60
	global_load_lds_dwordx4 v[220:221], off
	v_lshl_add_u64 v[222:223], s[62:63], 0, v[132:133]
	s_mov_b32 m0, s33
	v_lshl_add_u64 v[224:225], s[56:57], 0, v[134:135]
	global_load_lds_dwordx4 v[222:223], off
	v_lshl_add_u64 v[222:223], s[62:63], 0, v[136:137]
	s_add_i32 m0, s33, 0x2000
	s_nop 0
	global_load_lds_dwordx4 v[222:223], off
	v_lshl_add_u64 v[222:223], s[56:57], 0, v[130:131]
	s_mov_b32 m0, s11
	s_nop 0
	global_load_lds_dwordx4 v[222:223], off
	s_mov_b32 m0, s61
	s_nop 0
	global_load_lds_dwordx4 v[224:225], off
	s_waitcnt vmcnt(8)
	s_waitcnt lgkmcnt(0)
	s_barrier
	s_setprio 0
	v_mfma_f32_16x16x32_bf16 v[62:65], v[146:149], v[186:189], v[62:65]
	v_mfma_f32_16x16x32_bf16 v[58:61], v[162:165], v[186:189], v[58:61]
	v_mfma_f32_16x16x32_bf16 v[46:49], v[146:149], v[194:197], v[46:49]
	v_mfma_f32_16x16x32_bf16 v[42:45], v[162:165], v[194:197], v[42:45]
	v_mfma_f32_16x16x32_bf16 v[30:33], v[146:149], v[202:205], v[30:33]
	v_mfma_f32_16x16x32_bf16 v[26:29], v[162:165], v[202:205], v[26:29]
	v_mfma_f32_16x16x32_bf16 v[14:17], v[146:149], v[210:213], v[14:17]
	v_mfma_f32_16x16x32_bf16 v[10:13], v[162:165], v[210:213], v[10:13]
	v_mfma_f32_16x16x32_bf16 v[62:65], v[158:161], v[190:193], v[62:65]
	v_mfma_f32_16x16x32_bf16 v[58:61], v[166:169], v[190:193], v[58:61]
	v_mfma_f32_16x16x32_bf16 v[46:49], v[158:161], v[198:201], v[46:49]
	v_mfma_f32_16x16x32_bf16 v[42:45], v[166:169], v[198:201], v[42:45]
	v_mfma_f32_16x16x32_bf16 v[30:33], v[158:161], v[206:209], v[30:33]
	v_mfma_f32_16x16x32_bf16 v[26:29], v[166:169], v[206:209], v[26:29]
	v_mfma_f32_16x16x32_bf16 v[14:17], v[158:161], v[214:217], v[14:17]
	v_mfma_f32_16x16x32_bf16 v[10:13], v[166:169], v[214:217], v[10:13]
	s_setprio 2
	s_setprio 0
	v_mfma_f32_16x16x32_bf16 v[54:57], v[170:173], v[186:189], v[54:57]
	v_mfma_f32_16x16x32_bf16 v[50:53], v[178:181], v[186:189], v[50:53]
	v_mfma_f32_16x16x32_bf16 v[38:41], v[170:173], v[194:197], v[38:41]
	v_mfma_f32_16x16x32_bf16 v[34:37], v[178:181], v[194:197], v[34:37]
	v_mfma_f32_16x16x32_bf16 v[22:25], v[170:173], v[202:205], v[22:25]
	v_mfma_f32_16x16x32_bf16 v[18:21], v[178:181], v[202:205], v[18:21]
	v_mfma_f32_16x16x32_bf16 v[6:9], v[170:173], v[210:213], v[6:9]
	v_mfma_f32_16x16x32_bf16 v[2:5], v[178:181], v[210:213], v[2:5]
	v_mfma_f32_16x16x32_bf16 v[54:57], v[174:177], v[190:193], v[54:57]
	v_mfma_f32_16x16x32_bf16 v[50:53], v[182:185], v[190:193], v[50:53]
	v_mfma_f32_16x16x32_bf16 v[38:41], v[174:177], v[198:201], v[38:41]
	v_mfma_f32_16x16x32_bf16 v[34:37], v[182:185], v[198:201], v[34:37]
	v_mfma_f32_16x16x32_bf16 v[22:25], v[174:177], v[206:209], v[22:25]
	v_mfma_f32_16x16x32_bf16 v[18:21], v[182:185], v[206:209], v[18:21]
	v_mfma_f32_16x16x32_bf16 v[6:9], v[174:177], v[214:217], v[6:9]
	v_mfma_f32_16x16x32_bf16 v[2:5], v[182:185], v[214:217], v[2:5]
	s_setprio 2
	s_barrier
; #define PG8_STAGE(bufoff, gbase, voff) do { _Pragma("unroll") for (int _i = 0; _i < 2; ++_i) \
;         __builtin_amdgcn_global_load_lds((const unsigned*)((const char*)(gbase) + (voff)[_i]), (LAS unsigned*)(lds + (bufoff) + ldsw + _i * 8192), 16, 0, 0); } while (0)
; #define PG8_LDA(dst, b, h) do { _Pragma("unroll") for (int m = 0; m < 4; ++m) _Pragma("unroll") for (int k = 0; k < 2; ++k) dst[m][k] = *(const LAS bf16x8*)(lds + PG8_SA(b, h) + aoff + m * 2048 + k * 1024); } while (0)
; #define PG8_LDB(dst, b, h) do { _Pragma("unroll") for (int n = 0; n < 2; ++n) _Pragma("unroll") for (int k = 0; k < 2; ++k) dst[n][k] = *(const LAS bf16x8*)(lds + PG8_SB(b, h) + boff + n * 2048 + k * 1024); } while (0)
; #define PG8_MMA(ai, bj, At, Bt) do { __builtin_amdgcn_s_setprio(1); _Pragma("unroll") for (int m = 0; m < 4; ++m) _Pragma("unroll") for (int n = 0; n < 2; ++n) _Pragma("unroll") for (int k = 0; k < 2; ++k) \
;         acc[ai][bj][m][n] = __builtin_amdgcn_mfma_f32_16x16x32_bf16(Bt[n][k], At[m][k], acc[ai][bj][m][n], 0, 0, 0); __builtin_amdgcn_s_setprio(0); } while (0)
; #define PG8_WAIT_V(n) asm volatile("s_waitcnt vmcnt(" #n ")" ::: "memory")
; #define PG8_WAIT_L(n) asm volatile("s_waitcnt lgkmcnt(" #n ")" ::: "memory")
; #define PG8_BAR __builtin_amdgcn_s_barrier()
; #define PG8_SCHED __builtin_amdgcn_sched_barrier(0)
; template <class Epi>
; __device__ __forceinline__ void gemm_phase(LAS unsigned char* lds, const Gemm g, int G, int c, const Epi& E) {
;     ...
;             PG8_LDB(B0, 1, 0); PG8_LDB(B1, 1, 1); PG8_SCHED; PG8_LDA(At, 1, 0); PG8_STAGE(PG8_SA(0, 1), a2 + hstepA, voffA);
;             PG8_WAIT_V(8); PG8_WAIT_L(0); PG8_BAR; PG8_MMA(0, 0, At, B0); PG8_MMA(0, 1, At, B1); PG8_BAR; PG8_SCHED;
	s_add_i32 s33, 0, 0x18000
	v_add_u32_e32 v157, s33, v151
	s_add_i32 s62, 0, 0x1c000
	ds_read_b128 v[146:149], v157
	ds_read_b128 v[158:161], v157 offset:1024
	ds_read_b128 v[162:165], v157 offset:2048
	ds_read_b128 v[166:169], v157 offset:3072
	v_add_u32_e32 v157, s62, v151
	ds_read_b128 v[170:173], v157
	ds_read_b128 v[174:177], v157 offset:1024
	ds_read_b128 v[178:181], v157 offset:2048
	ds_read_b128 v[182:185], v157 offset:3072
	s_add_u32 s56, s56, 0x40000
	s_addc_u32 s57, s57, 0
	s_mov_b32 m0, s66
	v_lshl_add_u64 v[226:227], s[56:57], 0, v[130:131]
	ds_read_b128 v[186:189], v154 offset:32768
	ds_read_b128 v[190:193], v154 offset:33792
	ds_read_b128 v[194:197], v154 offset:34816
	ds_read_b128 v[198:201], v154 offset:35840
	ds_read_b128 v[202:205], v154 offset:36864
	ds_read_b128 v[206:209], v154 offset:37888
	ds_read_b128 v[210:213], v154 offset:38912
	ds_read_b128 v[214:217], v154 offset:39936
	global_load_lds_dwordx4 v[226:227], off
	v_lshl_add_u64 v[226:227], s[56:57], 0, v[134:135]
	s_mov_b32 m0, s67
	s_nop 0
	global_load_lds_dwordx4 v[226:227], off
	s_waitcnt vmcnt(8)
	s_waitcnt lgkmcnt(0)
	s_barrier
	s_setprio 0
	v_mfma_f32_16x16x32_bf16 v[126:129], v[146:149], v[186:189], v[126:129]
	v_mfma_f32_16x16x32_bf16 v[122:125], v[162:165], v[186:189], v[122:125]
	v_mfma_f32_16x16x32_bf16 v[110:113], v[146:149], v[194:197], v[110:113]
	v_mfma_f32_16x16x32_bf16 v[106:109], v[162:165], v[194:197], v[106:109]
	v_mfma_f32_16x16x32_bf16 v[94:97], v[146:149], v[202:205], v[94:97]
	v_mfma_f32_16x16x32_bf16 v[90:93], v[162:165], v[202:205], v[90:93]
	v_mfma_f32_16x16x32_bf16 v[78:81], v[146:149], v[210:213], v[78:81]
	v_mfma_f32_16x16x32_bf16 v[74:77], v[162:165], v[210:213], v[74:77]
	v_mfma_f32_16x16x32_bf16 v[126:129], v[158:161], v[190:193], v[126:129]
	v_mfma_f32_16x16x32_bf16 v[122:125], v[166:169], v[190:193], v[122:125]
	v_mfma_f32_16x16x32_bf16 v[110:113], v[158:161], v[198:201], v[110:113]
	v_mfma_f32_16x16x32_bf16 v[106:109], v[166:169], v[198:201], v[106:109]
	v_mfma_f32_16x16x32_bf16 v[94:97], v[158:161], v[206:209], v[94:97]
	v_mfma_f32_16x16x32_bf16 v[90:93], v[166:169], v[206:209], v[90:93]
	v_mfma_f32_16x16x32_bf16 v[78:81], v[158:161], v[214:217], v[78:81]
	v_mfma_f32_16x16x32_bf16 v[74:77], v[166:169], v[214:217], v[74:77]
	s_setprio 2
	s_setprio 0
	v_mfma_f32_16x16x32_bf16 v[118:121], v[170:173], v[186:189], v[118:121]
	v_mfma_f32_16x16x32_bf16 v[114:117], v[178:181], v[186:189], v[114:117]
	v_mfma_f32_16x16x32_bf16 v[102:105], v[170:173], v[194:197], v[102:105]
	v_mfma_f32_16x16x32_bf16 v[98:101], v[178:181], v[194:197], v[98:101]
	v_mfma_f32_16x16x32_bf16 v[86:89], v[170:173], v[202:205], v[86:89]
	v_mfma_f32_16x16x32_bf16 v[82:85], v[178:181], v[202:205], v[82:85]
	v_mfma_f32_16x16x32_bf16 v[70:73], v[170:173], v[210:213], v[70:73]
	v_mfma_f32_16x16x32_bf16 v[66:69], v[178:181], v[210:213], v[66:69]
	v_mfma_f32_16x16x32_bf16 v[118:121], v[174:177], v[190:193], v[118:121]
	v_mfma_f32_16x16x32_bf16 v[114:117], v[182:185], v[190:193], v[114:117]
	v_mfma_f32_16x16x32_bf16 v[102:105], v[174:177], v[198:201], v[102:105]
	v_mfma_f32_16x16x32_bf16 v[98:101], v[182:185], v[198:201], v[98:101]
	v_mfma_f32_16x16x32_bf16 v[86:89], v[174:177], v[206:209], v[86:89]
	v_mfma_f32_16x16x32_bf16 v[82:85], v[182:185], v[206:209], v[82:85]
	v_mfma_f32_16x16x32_bf16 v[70:73], v[174:177], v[214:217], v[70:73]
	v_mfma_f32_16x16x32_bf16 v[66:69], v[182:185], v[214:217], v[66:69]
	s_setprio 2
	s_barrier
; #define PG8_STAGE(bufoff, gbase, voff) do { _Pragma("unroll") for (int _i = 0; _i < 2; ++_i) \
;         __builtin_amdgcn_global_load_lds((const unsigned*)((const char*)(gbase) + (voff)[_i]), (LAS unsigned*)(lds + (bufoff) + ldsw + _i * 8192), 16, 0, 0); } while (0)
; #define PG8_LDA(dst, b, h) do { _Pragma("unroll") for (int m = 0; m < 4; ++m) _Pragma("unroll") for (int k = 0; k < 2; ++k) dst[m][k] = *(const LAS bf16x8*)(lds + PG8_SA(b, h) + aoff + m * 2048 + k * 1024); } while (0)
; #define PG8_MMA(ai, bj, At, Bt) do { __builtin_amdgcn_s_setprio(1); _Pragma("unroll") for (int m = 0; m < 4; ++m) _Pragma("unroll") for (int n = 0; n < 2; ++n) _Pragma("unroll") for (int k = 0; k < 2; ++k) \
;         acc[ai][bj][m][n] = __builtin_amdgcn_mfma_f32_16x16x32_bf16(Bt[n][k], At[m][k], acc[ai][bj][m][n], 0, 0, 0); __builtin_amdgcn_s_setprio(0); } while (0)
; #define PG8_WAIT_V(n) asm volatile("s_waitcnt vmcnt(" #n ")" ::: "memory")
; #define PG8_WAIT_L(n) asm volatile("s_waitcnt lgkmcnt(" #n ")" ::: "memory")
; #define PG8_BAR __builtin_amdgcn_s_barrier()
; #define PG8_SCHED __builtin_amdgcn_sched_barrier(0)
; template <class Epi>
; __device__ __forceinline__ void gemm_phase(LAS unsigned char* lds, const Gemm g, int G, int c, const Epi& E) {
;     ...
;             PG8_LDA(At, 1, 1); PG8_STAGE(PG8_SB(1, 0), b3, voffB); PG8_STAGE(PG8_SB(1, 1), b3 + hstepB, voffB); PG8_STAGE(PG8_SA(1, 0), a3, voffA);
;             PG8_WAIT_V(8); PG8_WAIT_L(0); PG8_BAR; PG8_MMA(1, 0, At, B0); PG8_MMA(1, 1, At, B1); PG8_BAR; PG8_SCHED;
;         }
;         if (wr == 0) PG8_BAR;
	s_add_i32 s33, s33, s60
	v_lshl_add_u64 v[218:219], v[218:219], 0, s[20:21]
	s_mov_b32 m0, s33
	ds_read_b128 v[186:189], v154 offset:49152
	ds_read_b128 v[190:193], v154 offset:50176
	ds_read_b128 v[194:197], v154 offset:51200
	ds_read_b128 v[198:201], v154 offset:52224
	ds_read_b128 v[202:205], v154 offset:53248
	ds_read_b128 v[206:209], v154 offset:54272
	ds_read_b128 v[210:213], v154 offset:55296
	ds_read_b128 v[214:217], v154 offset:56320
	global_load_lds_dwordx4 v[218:219], off
	s_add_i32 m0, s33, 0x2000
	s_add_u32 s54, s54, 0x40080
	v_lshl_add_u64 v[218:219], v[220:221], 0, s[20:21]
	s_addc_u32 s55, s55, 0
	s_add_i32 s33, s62, s60
	global_load_lds_dwordx4 v[218:219], off
	v_lshl_add_u64 v[218:219], s[54:55], 0, v[132:133]
	s_mov_b32 m0, s33
	s_nop 0
	global_load_lds_dwordx4 v[218:219], off
	v_lshl_add_u64 v[218:219], s[54:55], 0, v[136:137]
	s_add_i32 m0, s33, 0x2000
	s_nop 0
	global_load_lds_dwordx4 v[218:219], off
	v_lshl_add_u64 v[218:219], v[222:223], 0, s[20:21]
	s_mov_b32 m0, s71
	s_nop 0
	global_load_lds_dwordx4 v[218:219], off
	v_lshl_add_u64 v[218:219], v[224:225], 0, s[20:21]
	s_mov_b32 m0, s72
	s_nop 0
	global_load_lds_dwordx4 v[218:219], off
	s_waitcnt vmcnt(8)
	s_waitcnt lgkmcnt(0)
	s_barrier
	s_setprio 0
	v_mfma_f32_16x16x32_bf16 v[62:65], v[146:149], v[186:189], v[62:65]
	v_mfma_f32_16x16x32_bf16 v[58:61], v[162:165], v[186:189], v[58:61]
	v_mfma_f32_16x16x32_bf16 v[46:49], v[146:149], v[194:197], v[46:49]
	v_mfma_f32_16x16x32_bf16 v[42:45], v[162:165], v[194:197], v[42:45]
	v_mfma_f32_16x16x32_bf16 v[30:33], v[146:149], v[202:205], v[30:33]
	v_mfma_f32_16x16x32_bf16 v[26:29], v[162:165], v[202:205], v[26:29]
	v_mfma_f32_16x16x32_bf16 v[14:17], v[146:149], v[210:213], v[14:17]
	v_mfma_f32_16x16x32_bf16 v[10:13], v[162:165], v[210:213], v[10:13]
	v_mfma_f32_16x16x32_bf16 v[62:65], v[158:161], v[190:193], v[62:65]
	v_mfma_f32_16x16x32_bf16 v[58:61], v[166:169], v[190:193], v[58:61]
	v_mfma_f32_16x16x32_bf16 v[46:49], v[158:161], v[198:201], v[46:49]
	v_mfma_f32_16x16x32_bf16 v[42:45], v[166:169], v[198:201], v[42:45]
	v_mfma_f32_16x16x32_bf16 v[30:33], v[158:161], v[206:209], v[30:33]
	v_mfma_f32_16x16x32_bf16 v[26:29], v[166:169], v[206:209], v[26:29]
	v_mfma_f32_16x16x32_bf16 v[14:17], v[158:161], v[214:217], v[14:17]
	v_mfma_f32_16x16x32_bf16 v[10:13], v[166:169], v[214:217], v[10:13]
	s_setprio 2
	s_setprio 0
	v_mfma_f32_16x16x32_bf16 v[54:57], v[170:173], v[186:189], v[54:57]
	v_mfma_f32_16x16x32_bf16 v[50:53], v[178:181], v[186:189], v[50:53]
	v_mfma_f32_16x16x32_bf16 v[38:41], v[170:173], v[194:197], v[38:41]
	v_mfma_f32_16x16x32_bf16 v[34:37], v[178:181], v[194:197], v[34:37]
	v_mfma_f32_16x16x32_bf16 v[22:25], v[170:173], v[202:205], v[22:25]
	v_mfma_f32_16x16x32_bf16 v[18:21], v[178:181], v[202:205], v[18:21]
	v_mfma_f32_16x16x32_bf16 v[6:9], v[170:173], v[210:213], v[6:9]
	v_mfma_f32_16x16x32_bf16 v[2:5], v[178:181], v[210:213], v[2:5]
	v_mfma_f32_16x16x32_bf16 v[54:57], v[174:177], v[190:193], v[54:57]
	v_mfma_f32_16x16x32_bf16 v[50:53], v[182:185], v[190:193], v[50:53]
	v_mfma_f32_16x16x32_bf16 v[38:41], v[174:177], v[198:201], v[38:41]
	v_mfma_f32_16x16x32_bf16 v[34:37], v[182:185], v[198:201], v[34:37]
	v_mfma_f32_16x16x32_bf16 v[22:25], v[174:177], v[206:209], v[22:25]
	v_mfma_f32_16x16x32_bf16 v[18:21], v[182:185], v[206:209], v[18:21]
	v_mfma_f32_16x16x32_bf16 v[6:9], v[174:177], v[214:217], v[6:9]
	v_mfma_f32_16x16x32_bf16 v[2:5], v[182:185], v[214:217], v[2:5]
	s_setprio 2
	s_barrier
	s_add_i32 s85, s85, 2
	s_add_u32 s4, s4, 0x100
	s_addc_u32 s5, s5, 0
	s_add_u32 s45, s45, 0x100
	s_addc_u32 s84, s84, 0
	s_cmp_gt_u32 s85, 13
	s_cbranch_scc0 .LBB0_236
	s_and_b64 vcc, exec, s[22:23]
	s_cbranch_vccz .LBB0_239
	s_barrier

; #define PG8_STAGE(bufoff, gbase, voff) do { _Pragma("unroll") for (int _i = 0; _i < 2; ++_i) \
;         __builtin_amdgcn_global_load_lds((const unsigned*)((const char*)(gbase) + (voff)[_i]), (LAS unsigned*)(lds + (bufoff) + ldsw + _i * 8192), 16, 0, 0); } while (0)
; #define PG8_LDA(dst, b, h) do { _Pragma("unroll") for (int m = 0; m < 4; ++m) _Pragma("unroll") for (int k = 0; k < 2; ++k) dst[m][k] = *(const LAS bf16x8*)(lds + PG8_SA(b, h) + aoff + m * 2048 + k * 1024); } while (0)
; #define PG8_LDB(dst, b, h) do { _Pragma("unroll") for (int n = 0; n < 2; ++n) _Pragma("unroll") for (int k = 0; k < 2; ++k) dst[n][k] = *(const LAS bf16x8*)(lds + PG8_SB(b, h) + boff + n * 2048 + k * 1024); } while (0)
; #define PG8_MMA(ai, bj, At, Bt) do { __builtin_amdgcn_s_setprio(1); _Pragma("unroll") for (int m = 0; m < 4; ++m) _Pragma("unroll") for (int n = 0; n < 2; ++n) _Pragma("unroll") for (int k = 0; k < 2; ++k) \
;         acc[ai][bj][m][n] = __builtin_amdgcn_mfma_f32_16x16x32_bf16(Bt[n][k], At[m][k], acc[ai][bj][m][n], 0, 0, 0); __builtin_amdgcn_s_setprio(0); } while (0)
; #define PG8_WAIT_V(n) asm volatile("s_waitcnt vmcnt(" #n ")" ::: "memory")
; #define PG8_WAIT_L(n) asm volatile("s_waitcnt lgkmcnt(" #n ")" ::: "memory")
; #define PG8_BAR __builtin_amdgcn_s_barrier()
; #define PG8_SCHED __builtin_amdgcn_sched_barrier(0)
; template <class Epi>
; __device__ __forceinline__ void gemm_phase(LAS unsigned char* lds, const Gemm g, int G, int c, const Epi& E) {
;     ...
;         for (int t = 0; t < nt; t += 2) {
;             const bool last = (t == nt - 2);
;             const char* a1 = cA + (size_t)(t + 1) * kstep;
;             const char* a2 = last ? nA : cA + (size_t)(t + 2) * kstep; const char* b2 = last ? nB : cB + (size_t)(t + 2) * kstep;
;             const char* a3 = a2 + kstep; const char* b3 = b2 + kstep;
;             PG8_LDB(B0, 0, 0); PG8_LDB(B1, 0, 1); PG8_SCHED; PG8_LDA(At, 0, 0); PG8_STAGE(PG8_SA(1, 1), a1 + hstepA, voffA);
;             PG8_WAIT_V(8); PG8_WAIT_L(0); PG8_BAR; PG8_MMA(0, 0, At, B0); PG8_MMA(0, 1, At, B1); PG8_BAR; PG8_SCHED;
;             PG8_LDA(At, 0, 1); PG8_STAGE(PG8_SB(0, 0), b2, voffB); PG8_STAGE(PG8_SB(0, 1), b2 + hstepB, voffB); PG8_STAGE(PG8_SA(0, 0), a2, voffA);
.LBB0_367:
	s_mov_b32 s13, 0
	s_mov_b64 s[22:23], -1
	s_mov_b64 s[24:25], 0
	s_add_u32 s33, s20, s13
	s_addc_u32 s42, s21, 0
	s_add_u32 s43, s33, 0x100
	s_addc_u32 s44, s42, 0
	s_and_b64 s[38:39], s[24:25], exec
	s_cselect_b32 s45, s5, s44
	s_cselect_b32 s44, s4, s43
	s_add_u32 s13, s18, s13
	s_addc_u32 s38, s19, 0
	s_add_u32 s13, s13, 0x100
	s_addc_u32 s38, s38, 0
	s_and_b64 s[24:25], s[24:25], exec
	s_cselect_b32 s47, s17, s38
	s_cselect_b32 s46, s16, s13
	s_add_u32 s54, s33, 0xb0080
	s_addc_u32 s55, s42, 0
	s_add_i32 s65, s81, s56
	ds_read_b128 v[142:145], v148
	ds_read_b128 v[152:155], v148 offset:1024
	ds_read_b128 v[156:159], v148 offset:2048
	ds_read_b128 v[160:163], v148 offset:3072
	ds_read_b128 v[164:167], v149
	ds_read_b128 v[168:171], v149 offset:1024
	ds_read_b128 v[172:175], v149 offset:2048
	ds_read_b128 v[176:179], v149 offset:3072
	s_add_i32 m0, s57, 0xc000
	s_add_i32 s74, s57, 0xe000
	s_add_i32 s62, s65, 0x2000
	s_add_u32 s52, s46, 0xb0000
	s_addc_u32 s53, s47, 0
	s_add_i32 s64, s82, s56
	s_add_i32 s63, s64, 0x2000
	s_add_i32 s73, 0, 0x18000
	s_add_i32 s33, 0, 0x1c000
	s_add_u32 s42, s44, 0xb0000
	s_addc_u32 s43, s45, 0
	s_add_i32 s88, s73, s56
	s_add_i32 s38, s88, 0x2000
	s_add_u32 s24, s46, 0xb0080
	s_addc_u32 s25, s47, 0
	s_add_i32 s39, s33, s56
	s_add_i32 s13, s39, 0x2000
	v_lshl_add_u64 v[212:213], s[54:55], 0, v[136:137]
	ds_read_b128 v[180:183], v150
	ds_read_b128 v[184:187], v150 offset:1024
	ds_read_b128 v[188:191], v150 offset:2048
	ds_read_b128 v[192:195], v150 offset:3072
	ds_read_b128 v[196:199], v150 offset:4096
	ds_read_b128 v[200:203], v150 offset:5120
	ds_read_b128 v[204:207], v150 offset:6144
	ds_read_b128 v[208:211], v150 offset:7168
	global_load_lds_dwordx4 v[212:213], off
	v_lshl_add_u64 v[212:213], s[54:55], 0, v[132:133]
	s_mov_b32 m0, s74
	s_nop 0
	global_load_lds_dwordx4 v[212:213], off
	s_waitcnt vmcnt(8)
	s_waitcnt lgkmcnt(0)
	s_barrier
	s_setprio 0
	v_mfma_f32_16x16x32_bf16 v[126:129], v[142:145], v[180:183], 0
	v_mfma_f32_16x16x32_bf16 v[122:125], v[156:159], v[180:183], 0
	v_mfma_f32_16x16x32_bf16 v[118:121], v[142:145], v[188:191], 0
	v_mfma_f32_16x16x32_bf16 v[110:113], v[156:159], v[188:191], 0
	v_mfma_f32_16x16x32_bf16 v[102:105], v[142:145], v[196:199], 0
	v_mfma_f32_16x16x32_bf16 v[94:97], v[156:159], v[196:199], 0
	v_mfma_f32_16x16x32_bf16 v[86:89], v[142:145], v[204:207], 0
	v_mfma_f32_16x16x32_bf16 v[78:81], v[156:159], v[204:207], 0
	v_mfma_f32_16x16x32_bf16 v[126:129], v[152:155], v[184:187], v[126:129]
	v_mfma_f32_16x16x32_bf16 v[122:125], v[160:163], v[184:187], v[122:125]
	v_mfma_f32_16x16x32_bf16 v[118:121], v[152:155], v[192:195], v[118:121]
	v_mfma_f32_16x16x32_bf16 v[110:113], v[160:163], v[192:195], v[110:113]
	v_mfma_f32_16x16x32_bf16 v[102:105], v[152:155], v[200:203], v[102:105]
	v_mfma_f32_16x16x32_bf16 v[94:97], v[160:163], v[200:203], v[94:97]
	v_mfma_f32_16x16x32_bf16 v[86:89], v[152:155], v[208:211], v[86:89]
	v_mfma_f32_16x16x32_bf16 v[78:81], v[160:163], v[208:211], v[78:81]
	s_setprio 2
	s_setprio 0
	v_mfma_f32_16x16x32_bf16 v[114:117], v[164:167], v[180:183], 0
	v_mfma_f32_16x16x32_bf16 v[106:109], v[172:175], v[180:183], 0
	v_mfma_f32_16x16x32_bf16 v[98:101], v[164:167], v[188:191], 0
	v_mfma_f32_16x16x32_bf16 v[90:93], v[172:175], v[188:191], 0
	v_mfma_f32_16x16x32_bf16 v[82:85], v[164:167], v[196:199], 0
	v_mfma_f32_16x16x32_bf16 v[74:77], v[172:175], v[196:199], 0
	v_mfma_f32_16x16x32_bf16 v[70:73], v[164:167], v[204:207], 0
	v_mfma_f32_16x16x32_bf16 v[66:69], v[172:175], v[204:207], 0
	v_mfma_f32_16x16x32_bf16 v[114:117], v[168:171], v[184:187], v[114:117]
	v_mfma_f32_16x16x32_bf16 v[106:109], v[176:179], v[184:187], v[106:109]
	v_mfma_f32_16x16x32_bf16 v[98:101], v[168:171], v[192:195], v[98:101]
	v_mfma_f32_16x16x32_bf16 v[90:93], v[176:179], v[192:195], v[90:93]
	v_mfma_f32_16x16x32_bf16 v[82:85], v[168:171], v[200:203], v[82:85]
	v_mfma_f32_16x16x32_bf16 v[74:77], v[176:179], v[200:203], v[74:77]
	v_mfma_f32_16x16x32_bf16 v[70:73], v[168:171], v[208:211], v[70:73]
	v_mfma_f32_16x16x32_bf16 v[66:69], v[176:179], v[208:211], v[66:69]
	s_setprio 2
	s_barrier
	s_mov_b32 m0, s65
	v_lshl_add_u64 v[212:213], s[46:47], 0, v[134:135]
	ds_read_b128 v[180:183], v150 offset:16384
	ds_read_b128 v[184:187], v150 offset:17408
	ds_read_b128 v[188:191], v150 offset:18432
	ds_read_b128 v[192:195], v150 offset:19456
	ds_read_b128 v[196:199], v150 offset:20480
	ds_read_b128 v[200:203], v150 offset:21504
	ds_read_b128 v[204:207], v150 offset:22528
	ds_read_b128 v[208:211], v150 offset:23552
	global_load_lds_dwordx4 v[212:213], off
	v_lshl_add_u64 v[214:215], s[46:47], 0, v[130:131]
	s_mov_b32 m0, s62
	v_lshl_add_u64 v[216:217], s[52:53], 0, v[134:135]
	global_load_lds_dwordx4 v[214:215], off
	s_mov_b32 m0, s64
	v_lshl_add_u64 v[218:219], s[44:45], 0, v[132:133]
	global_load_lds_dwordx4 v[216:217], off
	v_lshl_add_u64 v[216:217], s[52:53], 0, v[130:131]
	s_mov_b32 m0, s63
	s_nop 0
	global_load_lds_dwordx4 v[216:217], off
	v_lshl_add_u64 v[216:217], s[44:45], 0, v[136:137]
	s_mov_b32 m0, s57
	s_nop 0
	global_load_lds_dwordx4 v[216:217], off
	s_mov_b32 m0, s58
	s_nop 0
	global_load_lds_dwordx4 v[218:219], off
	s_waitcnt vmcnt(8)
	s_waitcnt lgkmcnt(0)
	s_barrier
; #define PG8_STAGE(bufoff, gbase, voff) do { _Pragma("unroll") for (int _i = 0; _i < 2; ++_i) \
;         __builtin_amdgcn_global_load_lds((const unsigned*)((const char*)(gbase) + (voff)[_i]), (LAS unsigned*)(lds + (bufoff) + ldsw + _i * 8192), 16, 0, 0); } while (0)
; #define PG8_LDA(dst, b, h) do { _Pragma("unroll") for (int m = 0; m < 4; ++m) _Pragma("unroll") for (int k = 0; k < 2; ++k) dst[m][k] = *(const LAS bf16x8*)(lds + PG8_SA(b, h) + aoff + m * 2048 + k * 1024); } while (0)
; #define PG8_LDB(dst, b, h) do { _Pragma("unroll") for (int n = 0; n < 2; ++n) _Pragma("unroll") for (int k = 0; k < 2; ++k) dst[n][k] = *(const LAS bf16x8*)(lds + PG8_SB(b, h) + boff + n * 2048 + k * 1024); } while (0)
; #define PG8_MMA(ai, bj, At, Bt) do { __builtin_amdgcn_s_setprio(1); _Pragma("unroll") for (int m = 0; m < 4; ++m) _Pragma("unroll") for (int n = 0; n < 2; ++n) _Pragma("unroll") for (int k = 0; k < 2; ++k) \
;         acc[ai][bj][m][n] = __builtin_amdgcn_mfma_f32_16x16x32_bf16(Bt[n][k], At[m][k], acc[ai][bj][m][n], 0, 0, 0); __builtin_amdgcn_s_setprio(0); } while (0)
; #define PG8_WAIT_V(n) asm volatile("s_waitcnt vmcnt(" #n ")" ::: "memory")
; #define PG8_WAIT_L(n) asm volatile("s_waitcnt lgkmcnt(" #n ")" ::: "memory")
; #define PG8_BAR __builtin_amdgcn_s_barrier()
; #define PG8_SCHED __builtin_amdgcn_sched_barrier(0)
; template <class Epi>
; __device__ __forceinline__ void gemm_phase(LAS unsigned char* lds, const Gemm g, int G, int c, const Epi& E) {
;     ...
;             PG8_WAIT_V(8); PG8_WAIT_L(0); PG8_BAR; PG8_MMA(1, 0, At, B0); PG8_MMA(1, 1, At, B1); PG8_BAR; PG8_SCHED;
;             PG8_LDB(B0, 1, 0); PG8_LDB(B1, 1, 1); PG8_SCHED; PG8_LDA(At, 1, 0); PG8_STAGE(PG8_SA(0, 1), a2 + hstepA, voffA);
;             PG8_WAIT_V(8); PG8_WAIT_L(0); PG8_BAR; PG8_MMA(0, 0, At, B0); PG8_MMA(0, 1, At, B1); PG8_BAR; PG8_SCHED;
	s_setprio 0
	v_mfma_f32_16x16x32_bf16 v[62:65], v[142:145], v[180:183], 0
	v_mfma_f32_16x16x32_bf16 v[58:61], v[156:159], v[180:183], 0
	v_mfma_f32_16x16x32_bf16 v[54:57], v[142:145], v[188:191], 0
	v_mfma_f32_16x16x32_bf16 v[46:49], v[156:159], v[188:191], 0
	v_mfma_f32_16x16x32_bf16 v[38:41], v[142:145], v[196:199], 0
	v_mfma_f32_16x16x32_bf16 v[30:33], v[156:159], v[196:199], 0
	v_mfma_f32_16x16x32_bf16 v[22:25], v[142:145], v[204:207], 0
	v_mfma_f32_16x16x32_bf16 v[14:17], v[156:159], v[204:207], 0
	v_mfma_f32_16x16x32_bf16 v[62:65], v[152:155], v[184:187], v[62:65]
	v_mfma_f32_16x16x32_bf16 v[58:61], v[160:163], v[184:187], v[58:61]
	v_mfma_f32_16x16x32_bf16 v[54:57], v[152:155], v[192:195], v[54:57]
	v_mfma_f32_16x16x32_bf16 v[46:49], v[160:163], v[192:195], v[46:49]
	v_mfma_f32_16x16x32_bf16 v[38:41], v[152:155], v[200:203], v[38:41]
	v_mfma_f32_16x16x32_bf16 v[30:33], v[160:163], v[200:203], v[30:33]
	v_mfma_f32_16x16x32_bf16 v[22:25], v[152:155], v[208:211], v[22:25]
	v_mfma_f32_16x16x32_bf16 v[14:17], v[160:163], v[208:211], v[14:17]
	s_setprio 2
	s_setprio 0
	v_mfma_f32_16x16x32_bf16 v[50:53], v[164:167], v[180:183], 0
	v_mfma_f32_16x16x32_bf16 v[42:45], v[172:175], v[180:183], 0
	v_mfma_f32_16x16x32_bf16 v[34:37], v[164:167], v[188:191], 0
	v_mfma_f32_16x16x32_bf16 v[26:29], v[172:175], v[188:191], 0
	v_mfma_f32_16x16x32_bf16 v[18:21], v[164:167], v[196:199], 0
	v_mfma_f32_16x16x32_bf16 v[10:13], v[172:175], v[196:199], 0
	v_mfma_f32_16x16x32_bf16 v[6:9], v[164:167], v[204:207], 0
	v_mfma_f32_16x16x32_bf16 v[2:5], v[172:175], v[204:207], 0
	v_mfma_f32_16x16x32_bf16 v[50:53], v[168:171], v[184:187], v[50:53]
	v_mfma_f32_16x16x32_bf16 v[42:45], v[176:179], v[184:187], v[42:45]
	v_mfma_f32_16x16x32_bf16 v[34:37], v[168:171], v[192:195], v[34:37]
	v_mfma_f32_16x16x32_bf16 v[26:29], v[176:179], v[192:195], v[26:29]
	v_mfma_f32_16x16x32_bf16 v[18:21], v[168:171], v[200:203], v[18:21]
	v_mfma_f32_16x16x32_bf16 v[10:13], v[176:179], v[200:203], v[10:13]
	v_mfma_f32_16x16x32_bf16 v[6:9], v[168:171], v[208:211], v[6:9]
	v_mfma_f32_16x16x32_bf16 v[2:5], v[176:179], v[208:211], v[2:5]
	s_setprio 2
	s_barrier
	v_add_u32_e32 v151, s73, v147
	ds_read_b128 v[142:145], v151
	ds_read_b128 v[152:155], v151 offset:1024
	ds_read_b128 v[156:159], v151 offset:2048
	ds_read_b128 v[160:163], v151 offset:3072
	v_add_u32_e32 v151, s33, v147
	ds_read_b128 v[164:167], v151
	ds_read_b128 v[168:171], v151 offset:1024
	ds_read_b128 v[172:175], v151 offset:2048
	ds_read_b128 v[176:179], v151 offset:3072
	s_mov_b32 m0, s59
	v_lshl_add_u64 v[220:221], s[42:43], 0, v[136:137]
	ds_read_b128 v[180:183], v150 offset:32768
	ds_read_b128 v[184:187], v150 offset:33792
	ds_read_b128 v[188:191], v150 offset:34816
	ds_read_b128 v[192:195], v150 offset:35840
	ds_read_b128 v[196:199], v150 offset:36864
	ds_read_b128 v[200:203], v150 offset:37888
	ds_read_b128 v[204:207], v150 offset:38912
	ds_read_b128 v[208:211], v150 offset:39936
	global_load_lds_dwordx4 v[220:221], off
	v_lshl_add_u64 v[220:221], s[42:43], 0, v[132:133]
	s_mov_b32 m0, s60
	s_nop 0
	global_load_lds_dwordx4 v[220:221], off
	s_waitcnt vmcnt(8)
	s_waitcnt lgkmcnt(0)
	s_barrier
	s_setprio 0
	v_mfma_f32_16x16x32_bf16 v[126:129], v[142:145], v[180:183], v[126:129]
	v_mfma_f32_16x16x32_bf16 v[122:125], v[156:159], v[180:183], v[122:125]
	v_mfma_f32_16x16x32_bf16 v[118:121], v[142:145], v[188:191], v[118:121]
	v_mfma_f32_16x16x32_bf16 v[110:113], v[156:159], v[188:191], v[110:113]
	v_mfma_f32_16x16x32_bf16 v[102:105], v[142:145], v[196:199], v[102:105]
	v_mfma_f32_16x16x32_bf16 v[94:97], v[156:159], v[196:199], v[94:97]
	v_mfma_f32_16x16x32_bf16 v[86:89], v[142:145], v[204:207], v[86:89]
	v_mfma_f32_16x16x32_bf16 v[78:81], v[156:159], v[204:207], v[78:81]
	v_mfma_f32_16x16x32_bf16 v[126:129], v[152:155], v[184:187], v[126:129]
	v_mfma_f32_16x16x32_bf16 v[122:125], v[160:163], v[184:187], v[122:125]
	v_mfma_f32_16x16x32_bf16 v[118:121], v[152:155], v[192:195], v[118:121]
	v_mfma_f32_16x16x32_bf16 v[110:113], v[160:163], v[192:195], v[110:113]
	v_mfma_f32_16x16x32_bf16 v[102:105], v[152:155], v[200:203], v[102:105]
	v_mfma_f32_16x16x32_bf16 v[94:97], v[160:163], v[200:203], v[94:97]
	v_mfma_f32_16x16x32_bf16 v[86:89], v[152:155], v[208:211], v[86:89]
	v_mfma_f32_16x16x32_bf16 v[78:81], v[160:163], v[208:211], v[78:81]
	s_setprio 2
	s_setprio 0
	v_mfma_f32_16x16x32_bf16 v[114:117], v[164:167], v[180:183], v[114:117]
	v_mfma_f32_16x16x32_bf16 v[106:109], v[172:175], v[180:183], v[106:109]
	v_mfma_f32_16x16x32_bf16 v[98:101], v[164:167], v[188:191], v[98:101]
	v_mfma_f32_16x16x32_bf16 v[90:93], v[172:175], v[188:191], v[90:93]
	v_mfma_f32_16x16x32_bf16 v[82:85], v[164:167], v[196:199], v[82:85]
	v_mfma_f32_16x16x32_bf16 v[74:77], v[172:175], v[196:199], v[74:77]
	v_mfma_f32_16x16x32_bf16 v[70:73], v[164:167], v[204:207], v[70:73]
	v_mfma_f32_16x16x32_bf16 v[66:69], v[172:175], v[204:207], v[66:69]
	v_mfma_f32_16x16x32_bf16 v[114:117], v[168:171], v[184:187], v[114:117]
	v_mfma_f32_16x16x32_bf16 v[106:109], v[176:179], v[184:187], v[106:109]
	v_mfma_f32_16x16x32_bf16 v[98:101], v[168:171], v[192:195], v[98:101]
	v_mfma_f32_16x16x32_bf16 v[90:93], v[176:179], v[192:195], v[90:93]
	v_mfma_f32_16x16x32_bf16 v[82:85], v[168:171], v[200:203], v[82:85]
	v_mfma_f32_16x16x32_bf16 v[74:77], v[176:179], v[200:203], v[74:77]
	v_mfma_f32_16x16x32_bf16 v[70:73], v[168:171], v[208:211], v[70:73]
	v_mfma_f32_16x16x32_bf16 v[66:69], v[176:179], v[208:211], v[66:69]
	s_setprio 2
	s_barrier
; #define PG8_STAGE(bufoff, gbase, voff) do { _Pragma("unroll") for (int _i = 0; _i < 2; ++_i) \
;         __builtin_amdgcn_global_load_lds((const unsigned*)((const char*)(gbase) + (voff)[_i]), (LAS unsigned*)(lds + (bufoff) + ldsw + _i * 8192), 16, 0, 0); } while (0)
; #define PG8_LDA(dst, b, h) do { _Pragma("unroll") for (int m = 0; m < 4; ++m) _Pragma("unroll") for (int k = 0; k < 2; ++k) dst[m][k] = *(const LAS bf16x8*)(lds + PG8_SA(b, h) + aoff + m * 2048 + k * 1024); } while (0)
; #define PG8_LDB(dst, b, h) do { _Pragma("unroll") for (int n = 0; n < 2; ++n) _Pragma("unroll") for (int k = 0; k < 2; ++k) dst[n][k] = *(const LAS bf16x8*)(lds + PG8_SB(b, h) + boff + n * 2048 + k * 1024); } while (0)
; #define PG8_WAIT_V(n) asm volatile("s_waitcnt vmcnt(" #n ")" ::: "memory")
; #define PG8_WAIT_L(n) asm volatile("s_waitcnt lgkmcnt(" #n ")" ::: "memory")
; template <class Epi>
; __device__ __forceinline__ void gemm_phase(LAS unsigned char* lds, const Gemm g, int G, int c, const Epi& E) {
;     ...
;         for (int t = 0; t < nt; t += 2) {
;             const bool last = (t == nt - 2);
;             const char* a1 = cA + (size_t)(t + 1) * kstep;
;             const char* a2 = last ? nA : cA + (size_t)(t + 2) * kstep; const char* b2 = last ? nB : cB + (size_t)(t + 2) * kstep;
;             const char* a3 = a2 + kstep; const char* b3 = b2 + kstep;
;             PG8_LDB(B0, 0, 0); PG8_LDB(B1, 0, 1); PG8_SCHED; PG8_LDA(At, 0, 0); PG8_STAGE(PG8_SA(1, 1), a1 + hstepA, voffA);
;             PG8_WAIT_V(8); PG8_WAIT_L(0); PG8_BAR; PG8_MMA(0, 0, At, B0); PG8_MMA(0, 1, At, B1); PG8_BAR; PG8_SCHED;
;             PG8_LDA(At, 0, 1); PG8_STAGE(PG8_SB(0, 0), b2, voffB); PG8_STAGE(PG8_SB(0, 1), b2 + hstepB, voffB); PG8_STAGE(PG8_SA(0, 0), a2, voffA);
;             PG8_WAIT_V(8); PG8_WAIT_L(0); PG8_BAR; PG8_MMA(1, 0, At, B0); PG8_MMA(1, 1, At, B1); PG8_BAR; PG8_SCHED;
;             PG8_LDB(B0, 1, 0); PG8_LDB(B1, 1, 1); PG8_SCHED; PG8_LDA(At, 1, 0); PG8_STAGE(PG8_SA(0, 1), a2 + hstepA, voffA);
;             PG8_WAIT_V(8); PG8_WAIT_L(0); PG8_BAR; PG8_MMA(0, 0, At, B0); PG8_MMA(0, 1, At, B1); PG8_BAR; PG8_SCHED;
;             PG8_LDA(At, 1, 1); PG8_STAGE(PG8_SB(1, 0), b3, voffB); PG8_STAGE(PG8_SB(1, 1), b3 + hstepB, voffB); PG8_STAGE(PG8_SA(1, 0), a3, voffA);
;             PG8_WAIT_V(8); PG8_WAIT_L(0); PG8_BAR; PG8_MMA(1, 0, At, B0); PG8_MMA(1, 1, At, B1); PG8_BAR; PG8_SCHED;
	s_mov_b32 m0, s88
	v_lshl_add_u64 v[212:213], v[212:213], 0, s[8:9]
	ds_read_b128 v[180:183], v150 offset:49152
	ds_read_b128 v[184:187], v150 offset:50176
	ds_read_b128 v[188:191], v150 offset:51200
	ds_read_b128 v[192:195], v150 offset:52224
	ds_read_b128 v[196:199], v150 offset:53248
	ds_read_b128 v[200:203], v150 offset:54272
	ds_read_b128 v[204:207], v150 offset:55296
	ds_read_b128 v[208:211], v150 offset:56320
	global_load_lds_dwordx4 v[212:213], off
	v_lshl_add_u64 v[212:213], v[214:215], 0, s[8:9]
	s_mov_b32 m0, s38
	s_nop 0
	global_load_lds_dwordx4 v[212:213], off
	v_lshl_add_u64 v[212:213], s[24:25], 0, v[134:135]
	s_mov_b32 m0, s39
	s_nop 0
	global_load_lds_dwordx4 v[212:213], off
	v_lshl_add_u64 v[212:213], s[24:25], 0, v[130:131]
	s_mov_b32 m0, s13
	s_nop 0
	global_load_lds_dwordx4 v[212:213], off
	v_lshl_add_u64 v[212:213], v[216:217], 0, s[8:9]
	s_mov_b32 m0, s79
	s_nop 0
	global_load_lds_dwordx4 v[212:213], off
	v_lshl_add_u64 v[212:213], v[218:219], 0, s[8:9]
	s_mov_b32 m0, s80
	s_nop 0
	global_load_lds_dwordx4 v[212:213], off
	s_waitcnt vmcnt(8)
	s_waitcnt lgkmcnt(0)
	s_barrier
	s_setprio 0
	v_mfma_f32_16x16x32_bf16 v[62:65], v[142:145], v[180:183], v[62:65]
	v_mfma_f32_16x16x32_bf16 v[58:61], v[156:159], v[180:183], v[58:61]
	v_mfma_f32_16x16x32_bf16 v[54:57], v[142:145], v[188:191], v[54:57]
	v_mfma_f32_16x16x32_bf16 v[46:49], v[156:159], v[188:191], v[46:49]
	v_mfma_f32_16x16x32_bf16 v[38:41], v[142:145], v[196:199], v[38:41]
	v_mfma_f32_16x16x32_bf16 v[30:33], v[156:159], v[196:199], v[30:33]
	v_mfma_f32_16x16x32_bf16 v[22:25], v[142:145], v[204:207], v[22:25]
	v_mfma_f32_16x16x32_bf16 v[14:17], v[156:159], v[204:207], v[14:17]
	v_mfma_f32_16x16x32_bf16 v[62:65], v[152:155], v[184:187], v[62:65]
	v_mfma_f32_16x16x32_bf16 v[58:61], v[160:163], v[184:187], v[58:61]
	v_mfma_f32_16x16x32_bf16 v[54:57], v[152:155], v[192:195], v[54:57]
	v_mfma_f32_16x16x32_bf16 v[46:49], v[160:163], v[192:195], v[46:49]
	v_mfma_f32_16x16x32_bf16 v[38:41], v[152:155], v[200:203], v[38:41]
	v_mfma_f32_16x16x32_bf16 v[30:33], v[160:163], v[200:203], v[30:33]
	v_mfma_f32_16x16x32_bf16 v[22:25], v[152:155], v[208:211], v[22:25]
	v_mfma_f32_16x16x32_bf16 v[14:17], v[160:163], v[208:211], v[14:17]
	s_setprio 2
	s_setprio 0
	v_mfma_f32_16x16x32_bf16 v[50:53], v[164:167], v[180:183], v[50:53]
	v_mfma_f32_16x16x32_bf16 v[42:45], v[172:175], v[180:183], v[42:45]
	v_mfma_f32_16x16x32_bf16 v[34:37], v[164:167], v[188:191], v[34:37]
	v_mfma_f32_16x16x32_bf16 v[26:29], v[172:175], v[188:191], v[26:29]
	v_mfma_f32_16x16x32_bf16 v[18:21], v[164:167], v[196:199], v[18:21]
	v_mfma_f32_16x16x32_bf16 v[10:13], v[172:175], v[196:199], v[10:13]
	v_mfma_f32_16x16x32_bf16 v[6:9], v[164:167], v[204:207], v[6:9]
	v_mfma_f32_16x16x32_bf16 v[2:5], v[172:175], v[204:207], v[2:5]
	v_mfma_f32_16x16x32_bf16 v[50:53], v[168:171], v[184:187], v[50:53]
	v_mfma_f32_16x16x32_bf16 v[42:45], v[176:179], v[184:187], v[42:45]
	v_mfma_f32_16x16x32_bf16 v[34:37], v[168:171], v[192:195], v[34:37]
	v_mfma_f32_16x16x32_bf16 v[26:29], v[176:179], v[192:195], v[26:29]
	v_mfma_f32_16x16x32_bf16 v[18:21], v[168:171], v[200:203], v[18:21]
	v_mfma_f32_16x16x32_bf16 v[10:13], v[176:179], v[200:203], v[10:13]
	v_mfma_f32_16x16x32_bf16 v[6:9], v[168:171], v[208:211], v[6:9]
	v_mfma_f32_16x16x32_bf16 v[2:5], v[176:179], v[208:211], v[2:5]
	s_setprio 2
	s_barrier
	s_movk_i32 s13, 0x100
	s_andn2_b64 vcc, exec, s[22:23]
	s_mov_b64 s[24:25], -1
	s_mov_b64 s[22:23], 0
	s_cbranch_vccz .LBB0_368
.LBB0_368:
	s_add_u32 s33, s20, s13
	s_addc_u32 s42, s21, 0
	s_add_u32 s43, s33, 0x100
	s_addc_u32 s44, s42, 0
	s_and_b64 s[38:39], s[24:25], exec
	s_cselect_b32 s45, s5, s44
	s_cselect_b32 s44, s4, s43
	s_add_u32 s13, s18, s13
	s_addc_u32 s38, s19, 0
	s_add_u32 s13, s13, 0x100
	s_addc_u32 s38, s38, 0
	s_and_b64 s[24:25], s[24:25], exec
	s_cselect_b32 s47, s17, s38
	s_cselect_b32 s46, s16, s13
	s_add_u32 s54, s33, 0xb0080
	s_addc_u32 s55, s42, 0
	s_add_i32 s65, s81, s56
	ds_read_b128 v[142:145], v148
	ds_read_b128 v[152:155], v148 offset:1024
	ds_read_b128 v[156:159], v148 offset:2048
	ds_read_b128 v[160:163], v148 offset:3072
	ds_read_b128 v[164:167], v149
	ds_read_b128 v[168:171], v149 offset:1024
	ds_read_b128 v[172:175], v149 offset:2048
	ds_read_b128 v[176:179], v149 offset:3072
	s_add_i32 m0, s57, 0xc000
	s_add_i32 s74, s57, 0xe000
	s_add_i32 s62, s65, 0x2000
	s_add_u32 s52, s46, 0xb0000
	s_addc_u32 s53, s47, 0
	s_add_i32 s64, s82, s56
	s_add_i32 s63, s64, 0x2000
	s_add_i32 s73, 0, 0x18000
	s_add_i32 s33, 0, 0x1c000
	s_add_u32 s42, s44, 0xb0000
	s_addc_u32 s43, s45, 0
	s_add_i32 s88, s73, s56
	s_add_i32 s38, s88, 0x2000
	s_add_u32 s24, s46, 0xb0080
	s_addc_u32 s25, s47, 0
	s_add_i32 s39, s33, s56
	s_add_i32 s13, s39, 0x2000
	v_lshl_add_u64 v[212:213], s[54:55], 0, v[136:137]
	ds_read_b128 v[180:183], v150
	ds_read_b128 v[184:187], v150 offset:1024
	ds_read_b128 v[188:191], v150 offset:2048
	ds_read_b128 v[192:195], v150 offset:3072
	ds_read_b128 v[196:199], v150 offset:4096
	ds_read_b128 v[200:203], v150 offset:5120
	ds_read_b128 v[204:207], v150 offset:6144
	ds_read_b128 v[208:211], v150 offset:7168
	global_load_lds_dwordx4 v[212:213], off
	v_lshl_add_u64 v[212:213], s[54:55], 0, v[132:133]
	s_mov_b32 m0, s74
	s_nop 0
	global_load_lds_dwordx4 v[212:213], off
	s_waitcnt vmcnt(8)
	s_waitcnt lgkmcnt(0)
	s_barrier
; #define PG8_STAGE(bufoff, gbase, voff) do { _Pragma("unroll") for (int _i = 0; _i < 2; ++_i) \
;         __builtin_amdgcn_global_load_lds((const unsigned*)((const char*)(gbase) + (voff)[_i]), (LAS unsigned*)(lds + (bufoff) + ldsw + _i * 8192), 16, 0, 0); } while (0)
; #define PG8_LDA(dst, b, h) do { _Pragma("unroll") for (int m = 0; m < 4; ++m) _Pragma("unroll") for (int k = 0; k < 2; ++k) dst[m][k] = *(const LAS bf16x8*)(lds + PG8_SA(b, h) + aoff + m * 2048 + k * 1024); } while (0)
; #define PG8_LDB(dst, b, h) do { _Pragma("unroll") for (int n = 0; n < 2; ++n) _Pragma("unroll") for (int k = 0; k < 2; ++k) dst[n][k] = *(const LAS bf16x8*)(lds + PG8_SB(b, h) + boff + n * 2048 + k * 1024); } while (0)
; #define PG8_MMA(ai, bj, At, Bt) do { __builtin_amdgcn_s_setprio(1); _Pragma("unroll") for (int m = 0; m < 4; ++m) _Pragma("unroll") for (int n = 0; n < 2; ++n) _Pragma("unroll") for (int k = 0; k < 2; ++k) \
;         acc[ai][bj][m][n] = __builtin_amdgcn_mfma_f32_16x16x32_bf16(Bt[n][k], At[m][k], acc[ai][bj][m][n], 0, 0, 0); __builtin_amdgcn_s_setprio(0); } while (0)
; #define PG8_WAIT_V(n) asm volatile("s_waitcnt vmcnt(" #n ")" ::: "memory")
; #define PG8_WAIT_L(n) asm volatile("s_waitcnt lgkmcnt(" #n ")" ::: "memory")
; #define PG8_BAR __builtin_amdgcn_s_barrier()
; #define PG8_SCHED __builtin_amdgcn_sched_barrier(0)
; template <class Epi>
; __device__ __forceinline__ void gemm_phase(LAS unsigned char* lds, const Gemm g, int G, int c, const Epi& E) {
;     ...
;             PG8_WAIT_V(8); PG8_WAIT_L(0); PG8_BAR; PG8_MMA(0, 0, At, B0); PG8_MMA(0, 1, At, B1); PG8_BAR; PG8_SCHED;
;             PG8_LDA(At, 0, 1); PG8_STAGE(PG8_SB(0, 0), b2, voffB); PG8_STAGE(PG8_SB(0, 1), b2 + hstepB, voffB); PG8_STAGE(PG8_SA(0, 0), a2, voffA);
;             PG8_WAIT_V(8); PG8_WAIT_L(0); PG8_BAR; PG8_MMA(1, 0, At, B0); PG8_MMA(1, 1, At, B1); PG8_BAR; PG8_SCHED;
;             PG8_LDB(B0, 1, 0); PG8_LDB(B1, 1, 1); PG8_SCHED; PG8_LDA(At, 1, 0); PG8_STAGE(PG8_SA(0, 1), a2 + hstepA, voffA);
;             PG8_WAIT_V(8); PG8_WAIT_L(0); PG8_BAR; PG8_MMA(0, 0, At, B0); PG8_MMA(0, 1, At, B1); PG8_BAR; PG8_SCHED;
;             PG8_LDA(At, 1, 1); PG8_STAGE(PG8_SB(1, 0), b3, voffB); PG8_STAGE(PG8_SB(1, 1), b3 + hstepB, voffB); PG8_STAGE(PG8_SA(1, 0), a3, voffA);
	s_setprio 0
	v_mfma_f32_16x16x32_bf16 v[126:129], v[142:145], v[180:183], v[126:129]
	v_mfma_f32_16x16x32_bf16 v[122:125], v[156:159], v[180:183], v[122:125]
	v_mfma_f32_16x16x32_bf16 v[118:121], v[142:145], v[188:191], v[118:121]
	v_mfma_f32_16x16x32_bf16 v[110:113], v[156:159], v[188:191], v[110:113]
	v_mfma_f32_16x16x32_bf16 v[102:105], v[142:145], v[196:199], v[102:105]
	v_mfma_f32_16x16x32_bf16 v[94:97], v[156:159], v[196:199], v[94:97]
	v_mfma_f32_16x16x32_bf16 v[86:89], v[142:145], v[204:207], v[86:89]
	v_mfma_f32_16x16x32_bf16 v[78:81], v[156:159], v[204:207], v[78:81]
	v_mfma_f32_16x16x32_bf16 v[126:129], v[152:155], v[184:187], v[126:129]
	v_mfma_f32_16x16x32_bf16 v[122:125], v[160:163], v[184:187], v[122:125]
	v_mfma_f32_16x16x32_bf16 v[118:121], v[152:155], v[192:195], v[118:121]
	v_mfma_f32_16x16x32_bf16 v[110:113], v[160:163], v[192:195], v[110:113]
	v_mfma_f32_16x16x32_bf16 v[102:105], v[152:155], v[200:203], v[102:105]
	v_mfma_f32_16x16x32_bf16 v[94:97], v[160:163], v[200:203], v[94:97]
	v_mfma_f32_16x16x32_bf16 v[86:89], v[152:155], v[208:211], v[86:89]
	v_mfma_f32_16x16x32_bf16 v[78:81], v[160:163], v[208:211], v[78:81]
	s_setprio 2
	s_setprio 0
	v_mfma_f32_16x16x32_bf16 v[114:117], v[164:167], v[180:183], v[114:117]
	v_mfma_f32_16x16x32_bf16 v[106:109], v[172:175], v[180:183], v[106:109]
	v_mfma_f32_16x16x32_bf16 v[98:101], v[164:167], v[188:191], v[98:101]
	v_mfma_f32_16x16x32_bf16 v[90:93], v[172:175], v[188:191], v[90:93]
	v_mfma_f32_16x16x32_bf16 v[82:85], v[164:167], v[196:199], v[82:85]
	v_mfma_f32_16x16x32_bf16 v[74:77], v[172:175], v[196:199], v[74:77]
	v_mfma_f32_16x16x32_bf16 v[70:73], v[164:167], v[204:207], v[70:73]
	v_mfma_f32_16x16x32_bf16 v[66:69], v[172:175], v[204:207], v[66:69]
	v_mfma_f32_16x16x32_bf16 v[114:117], v[168:171], v[184:187], v[114:117]
	v_mfma_f32_16x16x32_bf16 v[106:109], v[176:179], v[184:187], v[106:109]
	v_mfma_f32_16x16x32_bf16 v[98:101], v[168:171], v[192:195], v[98:101]
	v_mfma_f32_16x16x32_bf16 v[90:93], v[176:179], v[192:195], v[90:93]
	v_mfma_f32_16x16x32_bf16 v[82:85], v[168:171], v[200:203], v[82:85]
	v_mfma_f32_16x16x32_bf16 v[74:77], v[176:179], v[200:203], v[74:77]
	v_mfma_f32_16x16x32_bf16 v[70:73], v[168:171], v[208:211], v[70:73]
	v_mfma_f32_16x16x32_bf16 v[66:69], v[176:179], v[208:211], v[66:69]
	s_setprio 2
	s_barrier
	s_mov_b32 m0, s65
	v_lshl_add_u64 v[212:213], s[46:47], 0, v[134:135]
	ds_read_b128 v[180:183], v150 offset:16384
	ds_read_b128 v[184:187], v150 offset:17408
	ds_read_b128 v[188:191], v150 offset:18432
	ds_read_b128 v[192:195], v150 offset:19456
	ds_read_b128 v[196:199], v150 offset:20480
	ds_read_b128 v[200:203], v150 offset:21504
	ds_read_b128 v[204:207], v150 offset:22528
	ds_read_b128 v[208:211], v150 offset:23552
	global_load_lds_dwordx4 v[212:213], off
	v_lshl_add_u64 v[214:215], s[46:47], 0, v[130:131]
	s_mov_b32 m0, s62
	v_lshl_add_u64 v[216:217], s[52:53], 0, v[134:135]
	global_load_lds_dwordx4 v[214:215], off
	s_mov_b32 m0, s64
	v_lshl_add_u64 v[218:219], s[44:45], 0, v[132:133]
	global_load_lds_dwordx4 v[216:217], off
	v_lshl_add_u64 v[216:217], s[52:53], 0, v[130:131]
	s_mov_b32 m0, s63
	s_nop 0
	global_load_lds_dwordx4 v[216:217], off
	v_lshl_add_u64 v[216:217], s[44:45], 0, v[136:137]
	s_mov_b32 m0, s57
	s_nop 0
	global_load_lds_dwordx4 v[216:217], off
	s_mov_b32 m0, s58
	s_nop 0
	global_load_lds_dwordx4 v[218:219], off
	s_waitcnt vmcnt(8)
	s_waitcnt lgkmcnt(0)
	s_barrier
	s_setprio 0
	v_mfma_f32_16x16x32_bf16 v[62:65], v[142:145], v[180:183], v[62:65]
	v_mfma_f32_16x16x32_bf16 v[58:61], v[156:159], v[180:183], v[58:61]
	v_mfma_f32_16x16x32_bf16 v[54:57], v[142:145], v[188:191], v[54:57]
	v_mfma_f32_16x16x32_bf16 v[46:49], v[156:159], v[188:191], v[46:49]
	v_mfma_f32_16x16x32_bf16 v[38:41], v[142:145], v[196:199], v[38:41]
	v_mfma_f32_16x16x32_bf16 v[30:33], v[156:159], v[196:199], v[30:33]
	v_mfma_f32_16x16x32_bf16 v[22:25], v[142:145], v[204:207], v[22:25]
	v_mfma_f32_16x16x32_bf16 v[14:17], v[156:159], v[204:207], v[14:17]
	v_mfma_f32_16x16x32_bf16 v[62:65], v[152:155], v[184:187], v[62:65]
	v_mfma_f32_16x16x32_bf16 v[58:61], v[160:163], v[184:187], v[58:61]
	v_mfma_f32_16x16x32_bf16 v[54:57], v[152:155], v[192:195], v[54:57]
	v_mfma_f32_16x16x32_bf16 v[46:49], v[160:163], v[192:195], v[46:49]
	v_mfma_f32_16x16x32_bf16 v[38:41], v[152:155], v[200:203], v[38:41]
	v_mfma_f32_16x16x32_bf16 v[30:33], v[160:163], v[200:203], v[30:33]
	v_mfma_f32_16x16x32_bf16 v[22:25], v[152:155], v[208:211], v[22:25]
	v_mfma_f32_16x16x32_bf16 v[14:17], v[160:163], v[208:211], v[14:17]
	s_setprio 2
	s_setprio 0
	v_mfma_f32_16x16x32_bf16 v[50:53], v[164:167], v[180:183], v[50:53]
	v_mfma_f32_16x16x32_bf16 v[42:45], v[172:175], v[180:183], v[42:45]
	v_mfma_f32_16x16x32_bf16 v[34:37], v[164:167], v[188:191], v[34:37]
	v_mfma_f32_16x16x32_bf16 v[26:29], v[172:175], v[188:191], v[26:29]
	v_mfma_f32_16x16x32_bf16 v[18:21], v[164:167], v[196:199], v[18:21]
	v_mfma_f32_16x16x32_bf16 v[10:13], v[172:175], v[196:199], v[10:13]
	v_mfma_f32_16x16x32_bf16 v[6:9], v[164:167], v[204:207], v[6:9]
	v_mfma_f32_16x16x32_bf16 v[2:5], v[172:175], v[204:207], v[2:5]
	v_mfma_f32_16x16x32_bf16 v[50:53], v[168:171], v[184:187], v[50:53]
	v_mfma_f32_16x16x32_bf16 v[42:45], v[176:179], v[184:187], v[42:45]
	v_mfma_f32_16x16x32_bf16 v[34:37], v[168:171], v[192:195], v[34:37]
	v_mfma_f32_16x16x32_bf16 v[26:29], v[176:179], v[192:195], v[26:29]
	v_mfma_f32_16x16x32_bf16 v[18:21], v[168:171], v[200:203], v[18:21]
	v_mfma_f32_16x16x32_bf16 v[10:13], v[176:179], v[200:203], v[10:13]
	v_mfma_f32_16x16x32_bf16 v[6:9], v[168:171], v[208:211], v[6:9]
	v_mfma_f32_16x16x32_bf16 v[2:5], v[176:179], v[208:211], v[2:5]
	s_setprio 2
	s_barrier
; #define PG8_STAGE(bufoff, gbase, voff) do { _Pragma("unroll") for (int _i = 0; _i < 2; ++_i) \
;         __builtin_amdgcn_global_load_lds((const unsigned*)((const char*)(gbase) + (voff)[_i]), (LAS unsigned*)(lds + (bufoff) + ldsw + _i * 8192), 16, 0, 0); } while (0)
; #define PG8_LDA(dst, b, h) do { _Pragma("unroll") for (int m = 0; m < 4; ++m) _Pragma("unroll") for (int k = 0; k < 2; ++k) dst[m][k] = *(const LAS bf16x8*)(lds + PG8_SA(b, h) + aoff + m * 2048 + k * 1024); } while (0)
; #define PG8_LDB(dst, b, h) do { _Pragma("unroll") for (int n = 0; n < 2; ++n) _Pragma("unroll") for (int k = 0; k < 2; ++k) dst[n][k] = *(const LAS bf16x8*)(lds + PG8_SB(b, h) + boff + n * 2048 + k * 1024); } while (0)
; #define PG8_MMA(ai, bj, At, Bt) do { __builtin_amdgcn_s_setprio(1); _Pragma("unroll") for (int m = 0; m < 4; ++m) _Pragma("unroll") for (int n = 0; n < 2; ++n) _Pragma("unroll") for (int k = 0; k < 2; ++k) \
;         acc[ai][bj][m][n] = __builtin_amdgcn_mfma_f32_16x16x32_bf16(Bt[n][k], At[m][k], acc[ai][bj][m][n], 0, 0, 0); __builtin_amdgcn_s_setprio(0); } while (0)
; #define PG8_WAIT_V(n) asm volatile("s_waitcnt vmcnt(" #n ")" ::: "memory")
; #define PG8_WAIT_L(n) asm volatile("s_waitcnt lgkmcnt(" #n ")" ::: "memory")
; #define PG8_BAR __builtin_amdgcn_s_barrier()
; #define PG8_SCHED __builtin_amdgcn_sched_barrier(0)
; template <class Epi>
; __device__ __forceinline__ void gemm_phase(LAS unsigned char* lds, const Gemm g, int G, int c, const Epi& E) {
;     ...
;             PG8_LDB(B0, 1, 0); PG8_LDB(B1, 1, 1); PG8_SCHED; PG8_LDA(At, 1, 0); PG8_STAGE(PG8_SA(0, 1), a2 + hstepA, voffA);
;             PG8_WAIT_V(8); PG8_WAIT_L(0); PG8_BAR; PG8_MMA(0, 0, At, B0); PG8_MMA(0, 1, At, B1); PG8_BAR; PG8_SCHED;
;             PG8_LDA(At, 1, 1); PG8_STAGE(PG8_SB(1, 0), b3, voffB); PG8_STAGE(PG8_SB(1, 1), b3 + hstepB, voffB); PG8_STAGE(PG8_SA(1, 0), a3, voffA);
;             PG8_WAIT_V(8); PG8_WAIT_L(0); PG8_BAR; PG8_MMA(1, 0, At, B0); PG8_MMA(1, 1, At, B1); PG8_BAR; PG8_SCHED;
;         }
;         if (wr == 0) PG8_BAR;
	v_add_u32_e32 v151, s73, v147
	ds_read_b128 v[142:145], v151
	ds_read_b128 v[152:155], v151 offset:1024
	ds_read_b128 v[156:159], v151 offset:2048
	ds_read_b128 v[160:163], v151 offset:3072
	v_add_u32_e32 v151, s33, v147
	ds_read_b128 v[164:167], v151
	ds_read_b128 v[168:171], v151 offset:1024
	ds_read_b128 v[172:175], v151 offset:2048
	ds_read_b128 v[176:179], v151 offset:3072
	s_mov_b32 m0, s59
	v_lshl_add_u64 v[220:221], s[42:43], 0, v[136:137]
	ds_read_b128 v[180:183], v150 offset:32768
	ds_read_b128 v[184:187], v150 offset:33792
	ds_read_b128 v[188:191], v150 offset:34816
	ds_read_b128 v[192:195], v150 offset:35840
	ds_read_b128 v[196:199], v150 offset:36864
	ds_read_b128 v[200:203], v150 offset:37888
	ds_read_b128 v[204:207], v150 offset:38912
	ds_read_b128 v[208:211], v150 offset:39936
	global_load_lds_dwordx4 v[220:221], off
	v_lshl_add_u64 v[220:221], s[42:43], 0, v[132:133]
	s_mov_b32 m0, s60
	s_nop 0
	global_load_lds_dwordx4 v[220:221], off
	s_waitcnt vmcnt(8)
	s_waitcnt lgkmcnt(0)
	s_barrier
	s_setprio 0
	v_mfma_f32_16x16x32_bf16 v[126:129], v[142:145], v[180:183], v[126:129]
	v_mfma_f32_16x16x32_bf16 v[122:125], v[156:159], v[180:183], v[122:125]
	v_mfma_f32_16x16x32_bf16 v[118:121], v[142:145], v[188:191], v[118:121]
	v_mfma_f32_16x16x32_bf16 v[110:113], v[156:159], v[188:191], v[110:113]
	v_mfma_f32_16x16x32_bf16 v[102:105], v[142:145], v[196:199], v[102:105]
	v_mfma_f32_16x16x32_bf16 v[94:97], v[156:159], v[196:199], v[94:97]
	v_mfma_f32_16x16x32_bf16 v[86:89], v[142:145], v[204:207], v[86:89]
	v_mfma_f32_16x16x32_bf16 v[78:81], v[156:159], v[204:207], v[78:81]
	v_mfma_f32_16x16x32_bf16 v[126:129], v[152:155], v[184:187], v[126:129]
	v_mfma_f32_16x16x32_bf16 v[122:125], v[160:163], v[184:187], v[122:125]
	v_mfma_f32_16x16x32_bf16 v[118:121], v[152:155], v[192:195], v[118:121]
	v_mfma_f32_16x16x32_bf16 v[110:113], v[160:163], v[192:195], v[110:113]
	v_mfma_f32_16x16x32_bf16 v[102:105], v[152:155], v[200:203], v[102:105]
	v_mfma_f32_16x16x32_bf16 v[94:97], v[160:163], v[200:203], v[94:97]
	v_mfma_f32_16x16x32_bf16 v[86:89], v[152:155], v[208:211], v[86:89]
	v_mfma_f32_16x16x32_bf16 v[78:81], v[160:163], v[208:211], v[78:81]
	s_setprio 2
	s_setprio 0
	v_mfma_f32_16x16x32_bf16 v[114:117], v[164:167], v[180:183], v[114:117]
	v_mfma_f32_16x16x32_bf16 v[106:109], v[172:175], v[180:183], v[106:109]
	v_mfma_f32_16x16x32_bf16 v[98:101], v[164:167], v[188:191], v[98:101]
	v_mfma_f32_16x16x32_bf16 v[90:93], v[172:175], v[188:191], v[90:93]
	v_mfma_f32_16x16x32_bf16 v[82:85], v[164:167], v[196:199], v[82:85]
	v_mfma_f32_16x16x32_bf16 v[74:77], v[172:175], v[196:199], v[74:77]
	v_mfma_f32_16x16x32_bf16 v[70:73], v[164:167], v[204:207], v[70:73]
	v_mfma_f32_16x16x32_bf16 v[66:69], v[172:175], v[204:207], v[66:69]
	v_mfma_f32_16x16x32_bf16 v[114:117], v[168:171], v[184:187], v[114:117]
	v_mfma_f32_16x16x32_bf16 v[106:109], v[176:179], v[184:187], v[106:109]
	v_mfma_f32_16x16x32_bf16 v[98:101], v[168:171], v[192:195], v[98:101]
	v_mfma_f32_16x16x32_bf16 v[90:93], v[176:179], v[192:195], v[90:93]
	v_mfma_f32_16x16x32_bf16 v[82:85], v[168:171], v[200:203], v[82:85]
	v_mfma_f32_16x16x32_bf16 v[74:77], v[176:179], v[200:203], v[74:77]
	v_mfma_f32_16x16x32_bf16 v[70:73], v[168:171], v[208:211], v[70:73]
	v_mfma_f32_16x16x32_bf16 v[66:69], v[176:179], v[208:211], v[66:69]
	s_setprio 2
	s_barrier
	s_mov_b32 m0, s88
	v_lshl_add_u64 v[212:213], v[212:213], 0, s[8:9]
	ds_read_b128 v[180:183], v150 offset:49152
	ds_read_b128 v[184:187], v150 offset:50176
	ds_read_b128 v[188:191], v150 offset:51200
	ds_read_b128 v[192:195], v150 offset:52224
	ds_read_b128 v[196:199], v150 offset:53248
	ds_read_b128 v[200:203], v150 offset:54272
	ds_read_b128 v[204:207], v150 offset:55296
	ds_read_b128 v[208:211], v150 offset:56320
	global_load_lds_dwordx4 v[212:213], off
	v_lshl_add_u64 v[212:213], v[214:215], 0, s[8:9]
	s_mov_b32 m0, s38
	s_nop 0
	global_load_lds_dwordx4 v[212:213], off
	v_lshl_add_u64 v[212:213], s[24:25], 0, v[134:135]
	s_mov_b32 m0, s39
	s_nop 0
	global_load_lds_dwordx4 v[212:213], off
	v_lshl_add_u64 v[212:213], s[24:25], 0, v[130:131]
	s_mov_b32 m0, s13
	s_nop 0
	global_load_lds_dwordx4 v[212:213], off
	v_lshl_add_u64 v[212:213], v[216:217], 0, s[8:9]
	s_mov_b32 m0, s79
	s_nop 0
	global_load_lds_dwordx4 v[212:213], off
	v_lshl_add_u64 v[212:213], v[218:219], 0, s[8:9]
	s_mov_b32 m0, s80
	s_nop 0
	global_load_lds_dwordx4 v[212:213], off
	s_waitcnt vmcnt(8)
	s_waitcnt lgkmcnt(0)
	s_barrier
	s_setprio 0
	v_mfma_f32_16x16x32_bf16 v[62:65], v[142:145], v[180:183], v[62:65]
	v_mfma_f32_16x16x32_bf16 v[58:61], v[156:159], v[180:183], v[58:61]
	v_mfma_f32_16x16x32_bf16 v[54:57], v[142:145], v[188:191], v[54:57]
	v_mfma_f32_16x16x32_bf16 v[46:49], v[156:159], v[188:191], v[46:49]
	v_mfma_f32_16x16x32_bf16 v[38:41], v[142:145], v[196:199], v[38:41]
	v_mfma_f32_16x16x32_bf16 v[30:33], v[156:159], v[196:199], v[30:33]
	v_mfma_f32_16x16x32_bf16 v[22:25], v[142:145], v[204:207], v[22:25]
	v_mfma_f32_16x16x32_bf16 v[14:17], v[156:159], v[204:207], v[14:17]
	v_mfma_f32_16x16x32_bf16 v[62:65], v[152:155], v[184:187], v[62:65]
	v_mfma_f32_16x16x32_bf16 v[58:61], v[160:163], v[184:187], v[58:61]
	v_mfma_f32_16x16x32_bf16 v[54:57], v[152:155], v[192:195], v[54:57]
	v_mfma_f32_16x16x32_bf16 v[46:49], v[160:163], v[192:195], v[46:49]
	v_mfma_f32_16x16x32_bf16 v[38:41], v[152:155], v[200:203], v[38:41]
	v_mfma_f32_16x16x32_bf16 v[30:33], v[160:163], v[200:203], v[30:33]
	v_mfma_f32_16x16x32_bf16 v[22:25], v[152:155], v[208:211], v[22:25]
	v_mfma_f32_16x16x32_bf16 v[14:17], v[160:163], v[208:211], v[14:17]
	s_setprio 2
	s_setprio 0
	v_mfma_f32_16x16x32_bf16 v[50:53], v[164:167], v[180:183], v[50:53]
	v_mfma_f32_16x16x32_bf16 v[42:45], v[172:175], v[180:183], v[42:45]
	v_mfma_f32_16x16x32_bf16 v[34:37], v[164:167], v[188:191], v[34:37]
	v_mfma_f32_16x16x32_bf16 v[26:29], v[172:175], v[188:191], v[26:29]
	v_mfma_f32_16x16x32_bf16 v[18:21], v[164:167], v[196:199], v[18:21]
	v_mfma_f32_16x16x32_bf16 v[10:13], v[172:175], v[196:199], v[10:13]
	v_mfma_f32_16x16x32_bf16 v[6:9], v[164:167], v[204:207], v[6:9]
	v_mfma_f32_16x16x32_bf16 v[2:5], v[172:175], v[204:207], v[2:5]
	v_mfma_f32_16x16x32_bf16 v[50:53], v[168:171], v[184:187], v[50:53]
	v_mfma_f32_16x16x32_bf16 v[42:45], v[176:179], v[184:187], v[42:45]
	v_mfma_f32_16x16x32_bf16 v[34:37], v[168:171], v[192:195], v[34:37]
	v_mfma_f32_16x16x32_bf16 v[26:29], v[176:179], v[192:195], v[26:29]
	v_mfma_f32_16x16x32_bf16 v[18:21], v[168:171], v[200:203], v[18:21]
	v_mfma_f32_16x16x32_bf16 v[10:13], v[176:179], v[200:203], v[10:13]
	v_mfma_f32_16x16x32_bf16 v[6:9], v[168:171], v[208:211], v[6:9]
	v_mfma_f32_16x16x32_bf16 v[2:5], v[176:179], v[208:211], v[2:5]
	s_setprio 2
	s_barrier
	s_movk_i32 s13, 0x100
	s_andn2_b64 vcc, exec, s[22:23]
	s_mov_b64 s[24:25], -1
	s_mov_b64 s[22:23], 0
	s_cbranch_vccz .LBB0_368
	s_and_b64 vcc, exec, s[10:11]
	s_cbranch_vccz .LBB0_371
	s_barrier

; #define PG8_STAGE(bufoff, gbase, voff) do { _Pragma("unroll") for (int _i = 0; _i < 2; ++_i) \
;         __builtin_amdgcn_global_load_lds((const unsigned*)((const char*)(gbase) + (voff)[_i]), (LAS unsigned*)(lds + (bufoff) + ldsw + _i * 8192), 16, 0, 0); } while (0)
; #define PG8_LDA(dst, b, h) do { _Pragma("unroll") for (int m = 0; m < 4; ++m) _Pragma("unroll") for (int k = 0; k < 2; ++k) dst[m][k] = *(const LAS bf16x8*)(lds + PG8_SA(b, h) + aoff + m * 2048 + k * 1024); } while (0)
; #define PG8_LDB(dst, b, h) do { _Pragma("unroll") for (int n = 0; n < 2; ++n) _Pragma("unroll") for (int k = 0; k < 2; ++k) dst[n][k] = *(const LAS bf16x8*)(lds + PG8_SB(b, h) + boff + n * 2048 + k * 1024); } while (0)
; #define PG8_MMA(ai, bj, At, Bt) do { __builtin_amdgcn_s_setprio(1); _Pragma("unroll") for (int m = 0; m < 4; ++m) _Pragma("unroll") for (int n = 0; n < 2; ++n) _Pragma("unroll") for (int k = 0; k < 2; ++k) \
;         acc[ai][bj][m][n] = __builtin_amdgcn_mfma_f32_16x16x32_bf16(Bt[n][k], At[m][k], acc[ai][bj][m][n], 0, 0, 0); __builtin_amdgcn_s_setprio(0); } while (0)
; #define PG8_WAIT_V(n) asm volatile("s_waitcnt vmcnt(" #n ")" ::: "memory")
; #define PG8_WAIT_L(n) asm volatile("s_waitcnt lgkmcnt(" #n ")" ::: "memory")
; #define PG8_BAR __builtin_amdgcn_s_barrier()
; #define PG8_SCHED __builtin_amdgcn_sched_barrier(0)
; template <class Epi>
; __device__ __forceinline__ void gemm_phase(LAS unsigned char* lds, const Gemm g, int G, int c, const Epi& E) {
;     ...
;         for (int t = 0; t < nt; t += 2) {
;             const bool last = (t == nt - 2);
;             const char* a1 = cA + (size_t)(t + 1) * kstep;
;             const char* a2 = last ? nA : cA + (size_t)(t + 2) * kstep; const char* b2 = last ? nB : cB + (size_t)(t + 2) * kstep;
;             const char* a3 = a2 + kstep; const char* b3 = b2 + kstep;
;             PG8_LDB(B0, 0, 0); PG8_LDB(B1, 0, 1); PG8_SCHED; PG8_LDA(At, 0, 0); PG8_STAGE(PG8_SA(1, 1), a1 + hstepA, voffA);
;             PG8_WAIT_V(8); PG8_WAIT_L(0); PG8_BAR; PG8_MMA(0, 0, At, B0); PG8_MMA(0, 1, At, B1); PG8_BAR; PG8_SCHED;
;             PG8_LDA(At, 0, 1); PG8_STAGE(PG8_SB(0, 0), b2, voffB); PG8_STAGE(PG8_SB(0, 1), b2 + hstepB, voffB); PG8_STAGE(PG8_SA(0, 0), a2, voffA);
.LBB0_389:
	s_mov_b32 s38, 0
	s_mov_b64 s[4:5], -1
	s_mov_b64 s[10:11], 0
	s_add_u32 s33, s8, s38
	s_addc_u32 s39, s9, 0
	s_add_u32 s56, s33, 0x100
	s_addc_u32 s57, s39, 0
	s_and_b64 s[54:55], s[10:11], exec
	s_cselect_b32 s57, s47, s57
	s_cselect_b32 s56, s46, s56
	s_add_u32 s38, s6, s38
	s_addc_u32 s54, s7, 0
	s_add_u32 s38, s38, 0x100
	s_addc_u32 s54, s54, 0
	s_and_b64 s[10:11], s[10:11], exec
	s_cselect_b32 s59, s53, s54
	s_cselect_b32 s58, s52, s38
	s_add_u32 s66, s33, 0xb0080
	s_addc_u32 s67, s39, 0
	s_add_i32 s65, s87, s14
	ds_read_b128 v[142:145], v160
	ds_read_b128 v[146:149], v160 offset:1024
	ds_read_b128 v[150:153], v160 offset:2048
	ds_read_b128 v[154:157], v160 offset:3072
	ds_read_b128 v[166:169], v161
	ds_read_b128 v[170:173], v161 offset:1024
	ds_read_b128 v[174:177], v161 offset:2048
	ds_read_b128 v[178:181], v161 offset:3072
	s_add_i32 m0, s78, 0xc000
	s_add_i32 s74, s78, 0xe000
	s_add_i32 s62, s65, 0x2000
	s_add_u32 s60, s58, 0xb0000
	s_addc_u32 s61, s59, 0
	s_add_i32 s64, s88, s14
	s_add_i32 s63, s64, 0x2000
	s_add_i32 s73, 0, 0x18000
	s_add_i32 s33, 0, 0x1c000
	s_add_u32 s54, s56, 0xb0000
	s_addc_u32 s55, s57, 0
	s_add_i32 vcc_hi, s73, s14
	s_add_i32 s39, vcc_hi, 0x2000
	s_add_u32 s10, s58, 0xb0080
	s_addc_u32 s11, s59, 0
	s_add_i32 vcc_lo, s33, s14
	s_add_i32 s38, vcc_lo, 0x2000
	v_lshl_add_u64 v[214:215], s[66:67], 0, v[130:131]
	ds_read_b128 v[182:185], v162
	ds_read_b128 v[186:189], v162 offset:1024
	ds_read_b128 v[190:193], v162 offset:2048
	ds_read_b128 v[194:197], v162 offset:3072
	ds_read_b128 v[198:201], v162 offset:4096
	ds_read_b128 v[202:205], v162 offset:5120
	ds_read_b128 v[206:209], v162 offset:6144
	ds_read_b128 v[210:213], v162 offset:7168
	global_load_lds_dwordx4 v[214:215], off
	v_lshl_add_u64 v[214:215], s[66:67], 0, v[134:135]
	s_mov_b32 m0, s74
	s_nop 0
	global_load_lds_dwordx4 v[214:215], off
	s_waitcnt vmcnt(8)
	s_waitcnt lgkmcnt(0)
	s_barrier
	s_setprio 0
	v_mfma_f32_16x16x32_bf16 v[126:129], v[142:145], v[182:185], 0
	v_mfma_f32_16x16x32_bf16 v[122:125], v[150:153], v[182:185], 0
	v_mfma_f32_16x16x32_bf16 v[110:113], v[142:145], v[190:193], 0
	v_mfma_f32_16x16x32_bf16 v[106:109], v[150:153], v[190:193], 0
	v_mfma_f32_16x16x32_bf16 v[94:97], v[142:145], v[198:201], 0
	v_mfma_f32_16x16x32_bf16 v[90:93], v[150:153], v[198:201], 0
	v_mfma_f32_16x16x32_bf16 v[78:81], v[142:145], v[206:209], 0
	v_mfma_f32_16x16x32_bf16 v[74:77], v[150:153], v[206:209], 0
	v_mfma_f32_16x16x32_bf16 v[126:129], v[146:149], v[186:189], v[126:129]
	v_mfma_f32_16x16x32_bf16 v[122:125], v[154:157], v[186:189], v[122:125]
	v_mfma_f32_16x16x32_bf16 v[110:113], v[146:149], v[194:197], v[110:113]
	v_mfma_f32_16x16x32_bf16 v[106:109], v[154:157], v[194:197], v[106:109]
	v_mfma_f32_16x16x32_bf16 v[94:97], v[146:149], v[202:205], v[94:97]
	v_mfma_f32_16x16x32_bf16 v[90:93], v[154:157], v[202:205], v[90:93]
	v_mfma_f32_16x16x32_bf16 v[78:81], v[146:149], v[210:213], v[78:81]
	v_mfma_f32_16x16x32_bf16 v[74:77], v[154:157], v[210:213], v[74:77]
	s_setprio 2
	s_setprio 0
	v_mfma_f32_16x16x32_bf16 v[118:121], v[166:169], v[182:185], 0
	v_mfma_f32_16x16x32_bf16 v[114:117], v[174:177], v[182:185], 0
	v_mfma_f32_16x16x32_bf16 v[102:105], v[166:169], v[190:193], 0
	v_mfma_f32_16x16x32_bf16 v[98:101], v[174:177], v[190:193], 0
	v_mfma_f32_16x16x32_bf16 v[86:89], v[166:169], v[198:201], 0
	v_mfma_f32_16x16x32_bf16 v[82:85], v[174:177], v[198:201], 0
	v_mfma_f32_16x16x32_bf16 v[70:73], v[166:169], v[206:209], 0
	v_mfma_f32_16x16x32_bf16 v[66:69], v[174:177], v[206:209], 0
	v_mfma_f32_16x16x32_bf16 v[118:121], v[170:173], v[186:189], v[118:121]
	v_mfma_f32_16x16x32_bf16 v[114:117], v[178:181], v[186:189], v[114:117]
	v_mfma_f32_16x16x32_bf16 v[102:105], v[170:173], v[194:197], v[102:105]
	v_mfma_f32_16x16x32_bf16 v[98:101], v[178:181], v[194:197], v[98:101]
	v_mfma_f32_16x16x32_bf16 v[86:89], v[170:173], v[202:205], v[86:89]
	v_mfma_f32_16x16x32_bf16 v[82:85], v[178:181], v[202:205], v[82:85]
	v_mfma_f32_16x16x32_bf16 v[70:73], v[170:173], v[210:213], v[70:73]
	v_mfma_f32_16x16x32_bf16 v[66:69], v[178:181], v[210:213], v[66:69]
	s_setprio 2
	s_barrier
	s_mov_b32 m0, s65
	v_lshl_add_u64 v[214:215], s[58:59], 0, v[132:133]
	ds_read_b128 v[182:185], v162 offset:16384
	ds_read_b128 v[186:189], v162 offset:17408
	ds_read_b128 v[190:193], v162 offset:18432
	ds_read_b128 v[194:197], v162 offset:19456
	ds_read_b128 v[198:201], v162 offset:20480
	ds_read_b128 v[202:205], v162 offset:21504
	ds_read_b128 v[206:209], v162 offset:22528
	ds_read_b128 v[210:213], v162 offset:23552
	global_load_lds_dwordx4 v[214:215], off
	v_lshl_add_u64 v[216:217], s[58:59], 0, v[136:137]
	s_mov_b32 m0, s62
	v_lshl_add_u64 v[218:219], s[60:61], 0, v[132:133]
	global_load_lds_dwordx4 v[216:217], off
	s_mov_b32 m0, s64
	v_lshl_add_u64 v[220:221], s[56:57], 0, v[134:135]
	global_load_lds_dwordx4 v[218:219], off
	v_lshl_add_u64 v[218:219], s[60:61], 0, v[136:137]
	s_mov_b32 m0, s63
	s_nop 0
	global_load_lds_dwordx4 v[218:219], off
	v_lshl_add_u64 v[218:219], s[56:57], 0, v[130:131]
	s_mov_b32 m0, s78
	s_nop 0
	global_load_lds_dwordx4 v[218:219], off
	s_mov_b32 m0, s79
	s_nop 0
	global_load_lds_dwordx4 v[220:221], off
	s_waitcnt vmcnt(8)
	s_waitcnt lgkmcnt(0)
	s_barrier
; #define PG8_STAGE(bufoff, gbase, voff) do { _Pragma("unroll") for (int _i = 0; _i < 2; ++_i) \
;         __builtin_amdgcn_global_load_lds((const unsigned*)((const char*)(gbase) + (voff)[_i]), (LAS unsigned*)(lds + (bufoff) + ldsw + _i * 8192), 16, 0, 0); } while (0)
; #define PG8_LDA(dst, b, h) do { _Pragma("unroll") for (int m = 0; m < 4; ++m) _Pragma("unroll") for (int k = 0; k < 2; ++k) dst[m][k] = *(const LAS bf16x8*)(lds + PG8_SA(b, h) + aoff + m * 2048 + k * 1024); } while (0)
; #define PG8_LDB(dst, b, h) do { _Pragma("unroll") for (int n = 0; n < 2; ++n) _Pragma("unroll") for (int k = 0; k < 2; ++k) dst[n][k] = *(const LAS bf16x8*)(lds + PG8_SB(b, h) + boff + n * 2048 + k * 1024); } while (0)
; #define PG8_MMA(ai, bj, At, Bt) do { __builtin_amdgcn_s_setprio(1); _Pragma("unroll") for (int m = 0; m < 4; ++m) _Pragma("unroll") for (int n = 0; n < 2; ++n) _Pragma("unroll") for (int k = 0; k < 2; ++k) \
;         acc[ai][bj][m][n] = __builtin_amdgcn_mfma_f32_16x16x32_bf16(Bt[n][k], At[m][k], acc[ai][bj][m][n], 0, 0, 0); __builtin_amdgcn_s_setprio(0); } while (0)
; #define PG8_WAIT_V(n) asm volatile("s_waitcnt vmcnt(" #n ")" ::: "memory")
; #define PG8_WAIT_L(n) asm volatile("s_waitcnt lgkmcnt(" #n ")" ::: "memory")
; #define PG8_BAR __builtin_amdgcn_s_barrier()
; #define PG8_SCHED __builtin_amdgcn_sched_barrier(0)
; template <class Epi>
; __device__ __forceinline__ void gemm_phase(LAS unsigned char* lds, const Gemm g, int G, int c, const Epi& E) {
;     ...
;             PG8_WAIT_V(8); PG8_WAIT_L(0); PG8_BAR; PG8_MMA(1, 0, At, B0); PG8_MMA(1, 1, At, B1); PG8_BAR; PG8_SCHED;
;             PG8_LDB(B0, 1, 0); PG8_LDB(B1, 1, 1); PG8_SCHED; PG8_LDA(At, 1, 0); PG8_STAGE(PG8_SA(0, 1), a2 + hstepA, voffA);
;             PG8_WAIT_V(8); PG8_WAIT_L(0); PG8_BAR; PG8_MMA(0, 0, At, B0); PG8_MMA(0, 1, At, B1); PG8_BAR; PG8_SCHED;
	s_setprio 0
	v_mfma_f32_16x16x32_bf16 v[62:65], v[142:145], v[182:185], 0
	v_mfma_f32_16x16x32_bf16 v[58:61], v[150:153], v[182:185], 0
	v_mfma_f32_16x16x32_bf16 v[46:49], v[142:145], v[190:193], 0
	v_mfma_f32_16x16x32_bf16 v[42:45], v[150:153], v[190:193], 0
	v_mfma_f32_16x16x32_bf16 v[30:33], v[142:145], v[198:201], 0
	v_mfma_f32_16x16x32_bf16 v[26:29], v[150:153], v[198:201], 0
	v_mfma_f32_16x16x32_bf16 v[14:17], v[142:145], v[206:209], 0
	v_mfma_f32_16x16x32_bf16 v[10:13], v[150:153], v[206:209], 0
	v_mfma_f32_16x16x32_bf16 v[62:65], v[146:149], v[186:189], v[62:65]
	v_mfma_f32_16x16x32_bf16 v[58:61], v[154:157], v[186:189], v[58:61]
	v_mfma_f32_16x16x32_bf16 v[46:49], v[146:149], v[194:197], v[46:49]
	v_mfma_f32_16x16x32_bf16 v[42:45], v[154:157], v[194:197], v[42:45]
	v_mfma_f32_16x16x32_bf16 v[30:33], v[146:149], v[202:205], v[30:33]
	v_mfma_f32_16x16x32_bf16 v[26:29], v[154:157], v[202:205], v[26:29]
	v_mfma_f32_16x16x32_bf16 v[14:17], v[146:149], v[210:213], v[14:17]
	v_mfma_f32_16x16x32_bf16 v[10:13], v[154:157], v[210:213], v[10:13]
	s_setprio 2
	s_setprio 0
	v_mfma_f32_16x16x32_bf16 v[54:57], v[166:169], v[182:185], 0
	v_mfma_f32_16x16x32_bf16 v[50:53], v[174:177], v[182:185], 0
	v_mfma_f32_16x16x32_bf16 v[38:41], v[166:169], v[190:193], 0
	v_mfma_f32_16x16x32_bf16 v[34:37], v[174:177], v[190:193], 0
	v_mfma_f32_16x16x32_bf16 v[22:25], v[166:169], v[198:201], 0
	v_mfma_f32_16x16x32_bf16 v[18:21], v[174:177], v[198:201], 0
	v_mfma_f32_16x16x32_bf16 v[6:9], v[166:169], v[206:209], 0
	v_mfma_f32_16x16x32_bf16 v[2:5], v[174:177], v[206:209], 0
	v_mfma_f32_16x16x32_bf16 v[54:57], v[170:173], v[186:189], v[54:57]
	v_mfma_f32_16x16x32_bf16 v[50:53], v[178:181], v[186:189], v[50:53]
	v_mfma_f32_16x16x32_bf16 v[38:41], v[170:173], v[194:197], v[38:41]
	v_mfma_f32_16x16x32_bf16 v[34:37], v[178:181], v[194:197], v[34:37]
	v_mfma_f32_16x16x32_bf16 v[22:25], v[170:173], v[202:205], v[22:25]
	v_mfma_f32_16x16x32_bf16 v[18:21], v[178:181], v[202:205], v[18:21]
	v_mfma_f32_16x16x32_bf16 v[6:9], v[170:173], v[210:213], v[6:9]
	v_mfma_f32_16x16x32_bf16 v[2:5], v[178:181], v[210:213], v[2:5]
	s_setprio 2
	s_barrier
	v_add_u32_e32 v154, s73, v159
	v_add_u32_e32 v178, s33, v159
	ds_read_b128 v[142:145], v154
	ds_read_b128 v[146:149], v154 offset:1024
	ds_read_b128 v[150:153], v154 offset:2048
	ds_read_b128 v[154:157], v154 offset:3072
	ds_read_b128 v[166:169], v178
	ds_read_b128 v[170:173], v178 offset:1024
	ds_read_b128 v[174:177], v178 offset:2048
	ds_read_b128 v[178:181], v178 offset:3072
	s_mov_b32 m0, s80
	v_lshl_add_u64 v[222:223], s[54:55], 0, v[130:131]
	ds_read_b128 v[182:185], v162 offset:32768
	ds_read_b128 v[186:189], v162 offset:33792
	ds_read_b128 v[190:193], v162 offset:34816
	ds_read_b128 v[194:197], v162 offset:35840
	ds_read_b128 v[198:201], v162 offset:36864
	ds_read_b128 v[202:205], v162 offset:37888
	ds_read_b128 v[206:209], v162 offset:38912
	ds_read_b128 v[210:213], v162 offset:39936
	global_load_lds_dwordx4 v[222:223], off
	v_lshl_add_u64 v[222:223], s[54:55], 0, v[134:135]
	s_mov_b32 m0, s81
	s_nop 0
	global_load_lds_dwordx4 v[222:223], off
	s_waitcnt vmcnt(8)
	s_waitcnt lgkmcnt(0)
	s_barrier
	s_setprio 0
	v_mfma_f32_16x16x32_bf16 v[126:129], v[142:145], v[182:185], v[126:129]
	v_mfma_f32_16x16x32_bf16 v[122:125], v[150:153], v[182:185], v[122:125]
	v_mfma_f32_16x16x32_bf16 v[110:113], v[142:145], v[190:193], v[110:113]
	v_mfma_f32_16x16x32_bf16 v[106:109], v[150:153], v[190:193], v[106:109]
	v_mfma_f32_16x16x32_bf16 v[94:97], v[142:145], v[198:201], v[94:97]
	v_mfma_f32_16x16x32_bf16 v[90:93], v[150:153], v[198:201], v[90:93]
	v_mfma_f32_16x16x32_bf16 v[78:81], v[142:145], v[206:209], v[78:81]
	v_mfma_f32_16x16x32_bf16 v[74:77], v[150:153], v[206:209], v[74:77]
	v_mfma_f32_16x16x32_bf16 v[126:129], v[146:149], v[186:189], v[126:129]
	v_mfma_f32_16x16x32_bf16 v[122:125], v[154:157], v[186:189], v[122:125]
	v_mfma_f32_16x16x32_bf16 v[110:113], v[146:149], v[194:197], v[110:113]
	v_mfma_f32_16x16x32_bf16 v[106:109], v[154:157], v[194:197], v[106:109]
	v_mfma_f32_16x16x32_bf16 v[94:97], v[146:149], v[202:205], v[94:97]
	v_mfma_f32_16x16x32_bf16 v[90:93], v[154:157], v[202:205], v[90:93]
	v_mfma_f32_16x16x32_bf16 v[78:81], v[146:149], v[210:213], v[78:81]
	v_mfma_f32_16x16x32_bf16 v[74:77], v[154:157], v[210:213], v[74:77]
	s_setprio 2
	s_setprio 0
	v_mfma_f32_16x16x32_bf16 v[118:121], v[166:169], v[182:185], v[118:121]
	v_mfma_f32_16x16x32_bf16 v[114:117], v[174:177], v[182:185], v[114:117]
	v_mfma_f32_16x16x32_bf16 v[102:105], v[166:169], v[190:193], v[102:105]
	v_mfma_f32_16x16x32_bf16 v[98:101], v[174:177], v[190:193], v[98:101]
	v_mfma_f32_16x16x32_bf16 v[86:89], v[166:169], v[198:201], v[86:89]
	v_mfma_f32_16x16x32_bf16 v[82:85], v[174:177], v[198:201], v[82:85]
	v_mfma_f32_16x16x32_bf16 v[70:73], v[166:169], v[206:209], v[70:73]
	v_mfma_f32_16x16x32_bf16 v[66:69], v[174:177], v[206:209], v[66:69]
	v_mfma_f32_16x16x32_bf16 v[118:121], v[170:173], v[186:189], v[118:121]
	v_mfma_f32_16x16x32_bf16 v[114:117], v[178:181], v[186:189], v[114:117]
	v_mfma_f32_16x16x32_bf16 v[102:105], v[170:173], v[194:197], v[102:105]
	v_mfma_f32_16x16x32_bf16 v[98:101], v[178:181], v[194:197], v[98:101]
	v_mfma_f32_16x16x32_bf16 v[86:89], v[170:173], v[202:205], v[86:89]
	v_mfma_f32_16x16x32_bf16 v[82:85], v[178:181], v[202:205], v[82:85]
	v_mfma_f32_16x16x32_bf16 v[70:73], v[170:173], v[210:213], v[70:73]
	v_mfma_f32_16x16x32_bf16 v[66:69], v[178:181], v[210:213], v[66:69]
	s_setprio 2
	s_barrier
; #define PG8_STAGE(bufoff, gbase, voff) do { _Pragma("unroll") for (int _i = 0; _i < 2; ++_i) \
;         __builtin_amdgcn_global_load_lds((const unsigned*)((const char*)(gbase) + (voff)[_i]), (LAS unsigned*)(lds + (bufoff) + ldsw + _i * 8192), 16, 0, 0); } while (0)
; #define PG8_LDA(dst, b, h) do { _Pragma("unroll") for (int m = 0; m < 4; ++m) _Pragma("unroll") for (int k = 0; k < 2; ++k) dst[m][k] = *(const LAS bf16x8*)(lds + PG8_SA(b, h) + aoff + m * 2048 + k * 1024); } while (0)
; #define PG8_LDB(dst, b, h) do { _Pragma("unroll") for (int n = 0; n < 2; ++n) _Pragma("unroll") for (int k = 0; k < 2; ++k) dst[n][k] = *(const LAS bf16x8*)(lds + PG8_SB(b, h) + boff + n * 2048 + k * 1024); } while (0)
; #define PG8_WAIT_V(n) asm volatile("s_waitcnt vmcnt(" #n ")" ::: "memory")
; #define PG8_WAIT_L(n) asm volatile("s_waitcnt lgkmcnt(" #n ")" ::: "memory")
; template <class Epi>
; __device__ __forceinline__ void gemm_phase(LAS unsigned char* lds, const Gemm g, int G, int c, const Epi& E) {
;     ...
;         for (int t = 0; t < nt; t += 2) {
;             const bool last = (t == nt - 2);
;             const char* a1 = cA + (size_t)(t + 1) * kstep;
;             const char* a2 = last ? nA : cA + (size_t)(t + 2) * kstep; const char* b2 = last ? nB : cB + (size_t)(t + 2) * kstep;
;             const char* a3 = a2 + kstep; const char* b3 = b2 + kstep;
;             PG8_LDB(B0, 0, 0); PG8_LDB(B1, 0, 1); PG8_SCHED; PG8_LDA(At, 0, 0); PG8_STAGE(PG8_SA(1, 1), a1 + hstepA, voffA);
;             PG8_WAIT_V(8); PG8_WAIT_L(0); PG8_BAR; PG8_MMA(0, 0, At, B0); PG8_MMA(0, 1, At, B1); PG8_BAR; PG8_SCHED;
;             PG8_LDA(At, 0, 1); PG8_STAGE(PG8_SB(0, 0), b2, voffB); PG8_STAGE(PG8_SB(0, 1), b2 + hstepB, voffB); PG8_STAGE(PG8_SA(0, 0), a2, voffA);
;             PG8_WAIT_V(8); PG8_WAIT_L(0); PG8_BAR; PG8_MMA(1, 0, At, B0); PG8_MMA(1, 1, At, B1); PG8_BAR; PG8_SCHED;
;             PG8_LDB(B0, 1, 0); PG8_LDB(B1, 1, 1); PG8_SCHED; PG8_LDA(At, 1, 0); PG8_STAGE(PG8_SA(0, 1), a2 + hstepA, voffA);
;             PG8_WAIT_V(8); PG8_WAIT_L(0); PG8_BAR; PG8_MMA(0, 0, At, B0); PG8_MMA(0, 1, At, B1); PG8_BAR; PG8_SCHED;
;             PG8_LDA(At, 1, 1); PG8_STAGE(PG8_SB(1, 0), b3, voffB); PG8_STAGE(PG8_SB(1, 1), b3 + hstepB, voffB); PG8_STAGE(PG8_SA(1, 0), a3, voffA);
;             PG8_WAIT_V(8); PG8_WAIT_L(0); PG8_BAR; PG8_MMA(1, 0, At, B0); PG8_MMA(1, 1, At, B1); PG8_BAR; PG8_SCHED;
	s_mov_b32 m0, vcc_hi
	v_lshl_add_u64 v[214:215], v[214:215], 0, s[24:25]
	ds_read_b128 v[182:185], v162 offset:49152
	ds_read_b128 v[186:189], v162 offset:50176
	ds_read_b128 v[190:193], v162 offset:51200
	ds_read_b128 v[194:197], v162 offset:52224
	ds_read_b128 v[198:201], v162 offset:53248
	ds_read_b128 v[202:205], v162 offset:54272
	ds_read_b128 v[206:209], v162 offset:55296
	ds_read_b128 v[210:213], v162 offset:56320
	global_load_lds_dwordx4 v[214:215], off
	v_lshl_add_u64 v[214:215], v[216:217], 0, s[24:25]
	s_mov_b32 m0, s39
	s_nop 0
	global_load_lds_dwordx4 v[214:215], off
	v_lshl_add_u64 v[214:215], s[10:11], 0, v[132:133]
	s_mov_b32 m0, vcc_lo
	s_nop 0
	global_load_lds_dwordx4 v[214:215], off
	v_lshl_add_u64 v[214:215], s[10:11], 0, v[136:137]
	s_mov_b32 m0, s38
	s_nop 0
	global_load_lds_dwordx4 v[214:215], off
	v_lshl_add_u64 v[214:215], v[218:219], 0, s[24:25]
	s_mov_b32 m0, s85
	s_nop 0
	global_load_lds_dwordx4 v[214:215], off
	v_lshl_add_u64 v[214:215], v[220:221], 0, s[24:25]
	s_mov_b32 m0, s86
	s_nop 0
	global_load_lds_dwordx4 v[214:215], off
	s_waitcnt vmcnt(8)
	s_waitcnt lgkmcnt(0)
	s_barrier
	s_setprio 0
	v_mfma_f32_16x16x32_bf16 v[62:65], v[142:145], v[182:185], v[62:65]
	v_mfma_f32_16x16x32_bf16 v[58:61], v[150:153], v[182:185], v[58:61]
	v_mfma_f32_16x16x32_bf16 v[46:49], v[142:145], v[190:193], v[46:49]
	v_mfma_f32_16x16x32_bf16 v[42:45], v[150:153], v[190:193], v[42:45]
	v_mfma_f32_16x16x32_bf16 v[30:33], v[142:145], v[198:201], v[30:33]
	v_mfma_f32_16x16x32_bf16 v[26:29], v[150:153], v[198:201], v[26:29]
	v_mfma_f32_16x16x32_bf16 v[14:17], v[142:145], v[206:209], v[14:17]
	v_mfma_f32_16x16x32_bf16 v[10:13], v[150:153], v[206:209], v[10:13]
	v_mfma_f32_16x16x32_bf16 v[62:65], v[146:149], v[186:189], v[62:65]
	v_mfma_f32_16x16x32_bf16 v[58:61], v[154:157], v[186:189], v[58:61]
	v_mfma_f32_16x16x32_bf16 v[46:49], v[146:149], v[194:197], v[46:49]
	v_mfma_f32_16x16x32_bf16 v[42:45], v[154:157], v[194:197], v[42:45]
	v_mfma_f32_16x16x32_bf16 v[30:33], v[146:149], v[202:205], v[30:33]
	v_mfma_f32_16x16x32_bf16 v[26:29], v[154:157], v[202:205], v[26:29]
	v_mfma_f32_16x16x32_bf16 v[14:17], v[146:149], v[210:213], v[14:17]
	v_mfma_f32_16x16x32_bf16 v[10:13], v[154:157], v[210:213], v[10:13]
	s_setprio 2
	s_setprio 0
	v_mfma_f32_16x16x32_bf16 v[54:57], v[166:169], v[182:185], v[54:57]
	v_mfma_f32_16x16x32_bf16 v[50:53], v[174:177], v[182:185], v[50:53]
	v_mfma_f32_16x16x32_bf16 v[38:41], v[166:169], v[190:193], v[38:41]
	v_mfma_f32_16x16x32_bf16 v[34:37], v[174:177], v[190:193], v[34:37]
	v_mfma_f32_16x16x32_bf16 v[22:25], v[166:169], v[198:201], v[22:25]
	v_mfma_f32_16x16x32_bf16 v[18:21], v[174:177], v[198:201], v[18:21]
	v_mfma_f32_16x16x32_bf16 v[6:9], v[166:169], v[206:209], v[6:9]
	v_mfma_f32_16x16x32_bf16 v[2:5], v[174:177], v[206:209], v[2:5]
	v_mfma_f32_16x16x32_bf16 v[54:57], v[170:173], v[186:189], v[54:57]
	v_mfma_f32_16x16x32_bf16 v[50:53], v[178:181], v[186:189], v[50:53]
	v_mfma_f32_16x16x32_bf16 v[38:41], v[170:173], v[194:197], v[38:41]
	v_mfma_f32_16x16x32_bf16 v[34:37], v[178:181], v[194:197], v[34:37]
	v_mfma_f32_16x16x32_bf16 v[22:25], v[170:173], v[202:205], v[22:25]
	v_mfma_f32_16x16x32_bf16 v[18:21], v[178:181], v[202:205], v[18:21]
	v_mfma_f32_16x16x32_bf16 v[6:9], v[170:173], v[210:213], v[6:9]
	v_mfma_f32_16x16x32_bf16 v[2:5], v[178:181], v[210:213], v[2:5]
	s_setprio 2
	s_barrier
	s_movk_i32 s38, 0x100
	s_andn2_b64 vcc, exec, s[4:5]
	s_mov_b64 s[10:11], -1
	s_mov_b64 s[4:5], 0
	s_cbranch_vccz .LBB0_390
.LBB0_390:
	s_add_u32 s33, s8, s38
	s_addc_u32 s39, s9, 0
	s_add_u32 s56, s33, 0x100
	s_addc_u32 s57, s39, 0
	s_and_b64 s[54:55], s[10:11], exec
	s_cselect_b32 s57, s47, s57
	s_cselect_b32 s56, s46, s56
	s_add_u32 s38, s6, s38
	s_addc_u32 s54, s7, 0
	s_add_u32 s38, s38, 0x100
	s_addc_u32 s54, s54, 0
	s_and_b64 s[10:11], s[10:11], exec
	s_cselect_b32 s59, s53, s54
	s_cselect_b32 s58, s52, s38
	s_add_u32 s66, s33, 0xb0080
	s_addc_u32 s67, s39, 0
	s_add_i32 s65, s87, s14
	ds_read_b128 v[142:145], v160
	ds_read_b128 v[146:149], v160 offset:1024
	ds_read_b128 v[150:153], v160 offset:2048
	ds_read_b128 v[154:157], v160 offset:3072
	ds_read_b128 v[166:169], v161
	ds_read_b128 v[170:173], v161 offset:1024
	ds_read_b128 v[174:177], v161 offset:2048
	ds_read_b128 v[178:181], v161 offset:3072
	s_add_i32 m0, s78, 0xc000
	s_add_i32 s74, s78, 0xe000
	s_add_i32 s62, s65, 0x2000
	s_add_u32 s60, s58, 0xb0000
	s_addc_u32 s61, s59, 0
	s_add_i32 s64, s88, s14
	s_add_i32 s63, s64, 0x2000
	s_add_i32 s73, 0, 0x18000
	s_add_i32 s33, 0, 0x1c000
	s_add_u32 s54, s56, 0xb0000
	s_addc_u32 s55, s57, 0
	s_add_i32 vcc_hi, s73, s14
	s_add_i32 s39, vcc_hi, 0x2000
	s_add_u32 s10, s58, 0xb0080
	s_addc_u32 s11, s59, 0
	s_add_i32 vcc_lo, s33, s14
	s_add_i32 s38, vcc_lo, 0x2000
	v_lshl_add_u64 v[214:215], s[66:67], 0, v[130:131]
	ds_read_b128 v[182:185], v162
	ds_read_b128 v[186:189], v162 offset:1024
	ds_read_b128 v[190:193], v162 offset:2048
	ds_read_b128 v[194:197], v162 offset:3072
	ds_read_b128 v[198:201], v162 offset:4096
	ds_read_b128 v[202:205], v162 offset:5120
	ds_read_b128 v[206:209], v162 offset:6144
	ds_read_b128 v[210:213], v162 offset:7168
	global_load_lds_dwordx4 v[214:215], off
	v_lshl_add_u64 v[214:215], s[66:67], 0, v[134:135]
	s_mov_b32 m0, s74
	s_nop 0
	global_load_lds_dwordx4 v[214:215], off
	s_waitcnt vmcnt(8)
	s_waitcnt lgkmcnt(0)
	s_barrier
; #define PG8_STAGE(bufoff, gbase, voff) do { _Pragma("unroll") for (int _i = 0; _i < 2; ++_i) \
;         __builtin_amdgcn_global_load_lds((const unsigned*)((const char*)(gbase) + (voff)[_i]), (LAS unsigned*)(lds + (bufoff) + ldsw + _i * 8192), 16, 0, 0); } while (0)
; #define PG8_LDA(dst, b, h) do { _Pragma("unroll") for (int m = 0; m < 4; ++m) _Pragma("unroll") for (int k = 0; k < 2; ++k) dst[m][k] = *(const LAS bf16x8*)(lds + PG8_SA(b, h) + aoff + m * 2048 + k * 1024); } while (0)
; #define PG8_LDB(dst, b, h) do { _Pragma("unroll") for (int n = 0; n < 2; ++n) _Pragma("unroll") for (int k = 0; k < 2; ++k) dst[n][k] = *(const LAS bf16x8*)(lds + PG8_SB(b, h) + boff + n * 2048 + k * 1024); } while (0)
; #define PG8_MMA(ai, bj, At, Bt) do { __builtin_amdgcn_s_setprio(1); _Pragma("unroll") for (int m = 0; m < 4; ++m) _Pragma("unroll") for (int n = 0; n < 2; ++n) _Pragma("unroll") for (int k = 0; k < 2; ++k) \
;         acc[ai][bj][m][n] = __builtin_amdgcn_mfma_f32_16x16x32_bf16(Bt[n][k], At[m][k], acc[ai][bj][m][n], 0, 0, 0); __builtin_amdgcn_s_setprio(0); } while (0)
; #define PG8_WAIT_V(n) asm volatile("s_waitcnt vmcnt(" #n ")" ::: "memory")
; #define PG8_WAIT_L(n) asm volatile("s_waitcnt lgkmcnt(" #n ")" ::: "memory")
; #define PG8_BAR __builtin_amdgcn_s_barrier()
; #define PG8_SCHED __builtin_amdgcn_sched_barrier(0)
; template <class Epi>
; __device__ __forceinline__ void gemm_phase(LAS unsigned char* lds, const Gemm g, int G, int c, const Epi& E) {
;     ...
;             PG8_WAIT_V(8); PG8_WAIT_L(0); PG8_BAR; PG8_MMA(0, 0, At, B0); PG8_MMA(0, 1, At, B1); PG8_BAR; PG8_SCHED;
;             PG8_LDA(At, 0, 1); PG8_STAGE(PG8_SB(0, 0), b2, voffB); PG8_STAGE(PG8_SB(0, 1), b2 + hstepB, voffB); PG8_STAGE(PG8_SA(0, 0), a2, voffA);
;             PG8_WAIT_V(8); PG8_WAIT_L(0); PG8_BAR; PG8_MMA(1, 0, At, B0); PG8_MMA(1, 1, At, B1); PG8_BAR; PG8_SCHED;
;             PG8_LDB(B0, 1, 0); PG8_LDB(B1, 1, 1); PG8_SCHED; PG8_LDA(At, 1, 0); PG8_STAGE(PG8_SA(0, 1), a2 + hstepA, voffA);
;             PG8_WAIT_V(8); PG8_WAIT_L(0); PG8_BAR; PG8_MMA(0, 0, At, B0); PG8_MMA(0, 1, At, B1); PG8_BAR; PG8_SCHED;
;             PG8_LDA(At, 1, 1); PG8_STAGE(PG8_SB(1, 0), b3, voffB); PG8_STAGE(PG8_SB(1, 1), b3 + hstepB, voffB); PG8_STAGE(PG8_SA(1, 0), a3, voffA);
	s_setprio 0
	v_mfma_f32_16x16x32_bf16 v[126:129], v[142:145], v[182:185], v[126:129]
	v_mfma_f32_16x16x32_bf16 v[122:125], v[150:153], v[182:185], v[122:125]
	v_mfma_f32_16x16x32_bf16 v[110:113], v[142:145], v[190:193], v[110:113]
	v_mfma_f32_16x16x32_bf16 v[106:109], v[150:153], v[190:193], v[106:109]
	v_mfma_f32_16x16x32_bf16 v[94:97], v[142:145], v[198:201], v[94:97]
	v_mfma_f32_16x16x32_bf16 v[90:93], v[150:153], v[198:201], v[90:93]
	v_mfma_f32_16x16x32_bf16 v[78:81], v[142:145], v[206:209], v[78:81]
	v_mfma_f32_16x16x32_bf16 v[74:77], v[150:153], v[206:209], v[74:77]
	v_mfma_f32_16x16x32_bf16 v[126:129], v[146:149], v[186:189], v[126:129]
	v_mfma_f32_16x16x32_bf16 v[122:125], v[154:157], v[186:189], v[122:125]
	v_mfma_f32_16x16x32_bf16 v[110:113], v[146:149], v[194:197], v[110:113]
	v_mfma_f32_16x16x32_bf16 v[106:109], v[154:157], v[194:197], v[106:109]
	v_mfma_f32_16x16x32_bf16 v[94:97], v[146:149], v[202:205], v[94:97]
	v_mfma_f32_16x16x32_bf16 v[90:93], v[154:157], v[202:205], v[90:93]
	v_mfma_f32_16x16x32_bf16 v[78:81], v[146:149], v[210:213], v[78:81]
	v_mfma_f32_16x16x32_bf16 v[74:77], v[154:157], v[210:213], v[74:77]
	s_setprio 2
	s_setprio 0
	v_mfma_f32_16x16x32_bf16 v[118:121], v[166:169], v[182:185], v[118:121]
	v_mfma_f32_16x16x32_bf16 v[114:117], v[174:177], v[182:185], v[114:117]
	v_mfma_f32_16x16x32_bf16 v[102:105], v[166:169], v[190:193], v[102:105]
	v_mfma_f32_16x16x32_bf16 v[98:101], v[174:177], v[190:193], v[98:101]
	v_mfma_f32_16x16x32_bf16 v[86:89], v[166:169], v[198:201], v[86:89]
	v_mfma_f32_16x16x32_bf16 v[82:85], v[174:177], v[198:201], v[82:85]
	v_mfma_f32_16x16x32_bf16 v[70:73], v[166:169], v[206:209], v[70:73]
	v_mfma_f32_16x16x32_bf16 v[66:69], v[174:177], v[206:209], v[66:69]
	v_mfma_f32_16x16x32_bf16 v[118:121], v[170:173], v[186:189], v[118:121]
	v_mfma_f32_16x16x32_bf16 v[114:117], v[178:181], v[186:189], v[114:117]
	v_mfma_f32_16x16x32_bf16 v[102:105], v[170:173], v[194:197], v[102:105]
	v_mfma_f32_16x16x32_bf16 v[98:101], v[178:181], v[194:197], v[98:101]
	v_mfma_f32_16x16x32_bf16 v[86:89], v[170:173], v[202:205], v[86:89]
	v_mfma_f32_16x16x32_bf16 v[82:85], v[178:181], v[202:205], v[82:85]
	v_mfma_f32_16x16x32_bf16 v[70:73], v[170:173], v[210:213], v[70:73]
	v_mfma_f32_16x16x32_bf16 v[66:69], v[178:181], v[210:213], v[66:69]
	s_setprio 2
	s_barrier
	s_mov_b32 m0, s65
	v_lshl_add_u64 v[214:215], s[58:59], 0, v[132:133]
	ds_read_b128 v[182:185], v162 offset:16384
	ds_read_b128 v[186:189], v162 offset:17408
	ds_read_b128 v[190:193], v162 offset:18432
	ds_read_b128 v[194:197], v162 offset:19456
	ds_read_b128 v[198:201], v162 offset:20480
	ds_read_b128 v[202:205], v162 offset:21504
	ds_read_b128 v[206:209], v162 offset:22528
	ds_read_b128 v[210:213], v162 offset:23552
	global_load_lds_dwordx4 v[214:215], off
	v_lshl_add_u64 v[216:217], s[58:59], 0, v[136:137]
	s_mov_b32 m0, s62
	v_lshl_add_u64 v[218:219], s[60:61], 0, v[132:133]
	global_load_lds_dwordx4 v[216:217], off
	s_mov_b32 m0, s64
	v_lshl_add_u64 v[220:221], s[56:57], 0, v[134:135]
	global_load_lds_dwordx4 v[218:219], off
	v_lshl_add_u64 v[218:219], s[60:61], 0, v[136:137]
	s_mov_b32 m0, s63
	s_nop 0
	global_load_lds_dwordx4 v[218:219], off
	v_lshl_add_u64 v[218:219], s[56:57], 0, v[130:131]
	s_mov_b32 m0, s78
	s_nop 0
	global_load_lds_dwordx4 v[218:219], off
	s_mov_b32 m0, s79
	s_nop 0
	global_load_lds_dwordx4 v[220:221], off
	s_waitcnt vmcnt(8)
	s_waitcnt lgkmcnt(0)
	s_barrier
	s_setprio 0
	v_mfma_f32_16x16x32_bf16 v[62:65], v[142:145], v[182:185], v[62:65]
	v_mfma_f32_16x16x32_bf16 v[58:61], v[150:153], v[182:185], v[58:61]
	v_mfma_f32_16x16x32_bf16 v[46:49], v[142:145], v[190:193], v[46:49]
	v_mfma_f32_16x16x32_bf16 v[42:45], v[150:153], v[190:193], v[42:45]
	v_mfma_f32_16x16x32_bf16 v[30:33], v[142:145], v[198:201], v[30:33]
	v_mfma_f32_16x16x32_bf16 v[26:29], v[150:153], v[198:201], v[26:29]
	v_mfma_f32_16x16x32_bf16 v[14:17], v[142:145], v[206:209], v[14:17]
	v_mfma_f32_16x16x32_bf16 v[10:13], v[150:153], v[206:209], v[10:13]
	v_mfma_f32_16x16x32_bf16 v[62:65], v[146:149], v[186:189], v[62:65]
	v_mfma_f32_16x16x32_bf16 v[58:61], v[154:157], v[186:189], v[58:61]
	v_mfma_f32_16x16x32_bf16 v[46:49], v[146:149], v[194:197], v[46:49]
	v_mfma_f32_16x16x32_bf16 v[42:45], v[154:157], v[194:197], v[42:45]
	v_mfma_f32_16x16x32_bf16 v[30:33], v[146:149], v[202:205], v[30:33]
	v_mfma_f32_16x16x32_bf16 v[26:29], v[154:157], v[202:205], v[26:29]
	v_mfma_f32_16x16x32_bf16 v[14:17], v[146:149], v[210:213], v[14:17]
	v_mfma_f32_16x16x32_bf16 v[10:13], v[154:157], v[210:213], v[10:13]
	s_setprio 2
	s_setprio 0
	v_mfma_f32_16x16x32_bf16 v[54:57], v[166:169], v[182:185], v[54:57]
	v_mfma_f32_16x16x32_bf16 v[50:53], v[174:177], v[182:185], v[50:53]
	v_mfma_f32_16x16x32_bf16 v[38:41], v[166:169], v[190:193], v[38:41]
	v_mfma_f32_16x16x32_bf16 v[34:37], v[174:177], v[190:193], v[34:37]
	v_mfma_f32_16x16x32_bf16 v[22:25], v[166:169], v[198:201], v[22:25]
	v_mfma_f32_16x16x32_bf16 v[18:21], v[174:177], v[198:201], v[18:21]
	v_mfma_f32_16x16x32_bf16 v[6:9], v[166:169], v[206:209], v[6:9]
	v_mfma_f32_16x16x32_bf16 v[2:5], v[174:177], v[206:209], v[2:5]
	v_mfma_f32_16x16x32_bf16 v[54:57], v[170:173], v[186:189], v[54:57]
	v_mfma_f32_16x16x32_bf16 v[50:53], v[178:181], v[186:189], v[50:53]
	v_mfma_f32_16x16x32_bf16 v[38:41], v[170:173], v[194:197], v[38:41]
	v_mfma_f32_16x16x32_bf16 v[34:37], v[178:181], v[194:197], v[34:37]
	v_mfma_f32_16x16x32_bf16 v[22:25], v[170:173], v[202:205], v[22:25]
	v_mfma_f32_16x16x32_bf16 v[18:21], v[178:181], v[202:205], v[18:21]
	v_mfma_f32_16x16x32_bf16 v[6:9], v[170:173], v[210:213], v[6:9]
	v_mfma_f32_16x16x32_bf16 v[2:5], v[178:181], v[210:213], v[2:5]
	s_setprio 2
	s_barrier
; #define PG8_STAGE(bufoff, gbase, voff) do { _Pragma("unroll") for (int _i = 0; _i < 2; ++_i) \
;         __builtin_amdgcn_global_load_lds((const unsigned*)((const char*)(gbase) + (voff)[_i]), (LAS unsigned*)(lds + (bufoff) + ldsw + _i * 8192), 16, 0, 0); } while (0)
; #define PG8_LDA(dst, b, h) do { _Pragma("unroll") for (int m = 0; m < 4; ++m) _Pragma("unroll") for (int k = 0; k < 2; ++k) dst[m][k] = *(const LAS bf16x8*)(lds + PG8_SA(b, h) + aoff + m * 2048 + k * 1024); } while (0)
; #define PG8_LDB(dst, b, h) do { _Pragma("unroll") for (int n = 0; n < 2; ++n) _Pragma("unroll") for (int k = 0; k < 2; ++k) dst[n][k] = *(const LAS bf16x8*)(lds + PG8_SB(b, h) + boff + n * 2048 + k * 1024); } while (0)
; #define PG8_MMA(ai, bj, At, Bt) do { __builtin_amdgcn_s_setprio(1); _Pragma("unroll") for (int m = 0; m < 4; ++m) _Pragma("unroll") for (int n = 0; n < 2; ++n) _Pragma("unroll") for (int k = 0; k < 2; ++k) \
;         acc[ai][bj][m][n] = __builtin_amdgcn_mfma_f32_16x16x32_bf16(Bt[n][k], At[m][k], acc[ai][bj][m][n], 0, 0, 0); __builtin_amdgcn_s_setprio(0); } while (0)
; #define PG8_WAIT_V(n) asm volatile("s_waitcnt vmcnt(" #n ")" ::: "memory")
; #define PG8_WAIT_L(n) asm volatile("s_waitcnt lgkmcnt(" #n ")" ::: "memory")
; #define PG8_BAR __builtin_amdgcn_s_barrier()
; #define PG8_SCHED __builtin_amdgcn_sched_barrier(0)
; template <class Epi>
; __device__ __forceinline__ void gemm_phase(LAS unsigned char* lds, const Gemm g, int G, int c, const Epi& E) {
;     ...
;             PG8_LDB(B0, 1, 0); PG8_LDB(B1, 1, 1); PG8_SCHED; PG8_LDA(At, 1, 0); PG8_STAGE(PG8_SA(0, 1), a2 + hstepA, voffA);
;             PG8_WAIT_V(8); PG8_WAIT_L(0); PG8_BAR; PG8_MMA(0, 0, At, B0); PG8_MMA(0, 1, At, B1); PG8_BAR; PG8_SCHED;
;             PG8_LDA(At, 1, 1); PG8_STAGE(PG8_SB(1, 0), b3, voffB); PG8_STAGE(PG8_SB(1, 1), b3 + hstepB, voffB); PG8_STAGE(PG8_SA(1, 0), a3, voffA);
;             PG8_WAIT_V(8); PG8_WAIT_L(0); PG8_BAR; PG8_MMA(1, 0, At, B0); PG8_MMA(1, 1, At, B1); PG8_BAR; PG8_SCHED;
;         }
;         if (wr == 0) PG8_BAR;
	v_add_u32_e32 v154, s73, v159
	v_add_u32_e32 v178, s33, v159
	ds_read_b128 v[142:145], v154
	ds_read_b128 v[146:149], v154 offset:1024
	ds_read_b128 v[150:153], v154 offset:2048
	ds_read_b128 v[154:157], v154 offset:3072
	ds_read_b128 v[166:169], v178
	ds_read_b128 v[170:173], v178 offset:1024
	ds_read_b128 v[174:177], v178 offset:2048
	ds_read_b128 v[178:181], v178 offset:3072
	s_mov_b32 m0, s80
	v_lshl_add_u64 v[222:223], s[54:55], 0, v[130:131]
	ds_read_b128 v[182:185], v162 offset:32768
	ds_read_b128 v[186:189], v162 offset:33792
	ds_read_b128 v[190:193], v162 offset:34816
	ds_read_b128 v[194:197], v162 offset:35840
	ds_read_b128 v[198:201], v162 offset:36864
	ds_read_b128 v[202:205], v162 offset:37888
	ds_read_b128 v[206:209], v162 offset:38912
	ds_read_b128 v[210:213], v162 offset:39936
	global_load_lds_dwordx4 v[222:223], off
	v_lshl_add_u64 v[222:223], s[54:55], 0, v[134:135]
	s_mov_b32 m0, s81
	s_nop 0
	global_load_lds_dwordx4 v[222:223], off
	s_waitcnt vmcnt(8)
	s_waitcnt lgkmcnt(0)
	s_barrier
	s_setprio 0
	v_mfma_f32_16x16x32_bf16 v[126:129], v[142:145], v[182:185], v[126:129]
	v_mfma_f32_16x16x32_bf16 v[122:125], v[150:153], v[182:185], v[122:125]
	v_mfma_f32_16x16x32_bf16 v[110:113], v[142:145], v[190:193], v[110:113]
	v_mfma_f32_16x16x32_bf16 v[106:109], v[150:153], v[190:193], v[106:109]
	v_mfma_f32_16x16x32_bf16 v[94:97], v[142:145], v[198:201], v[94:97]
	v_mfma_f32_16x16x32_bf16 v[90:93], v[150:153], v[198:201], v[90:93]
	v_mfma_f32_16x16x32_bf16 v[78:81], v[142:145], v[206:209], v[78:81]
	v_mfma_f32_16x16x32_bf16 v[74:77], v[150:153], v[206:209], v[74:77]
	v_mfma_f32_16x16x32_bf16 v[126:129], v[146:149], v[186:189], v[126:129]
	v_mfma_f32_16x16x32_bf16 v[122:125], v[154:157], v[186:189], v[122:125]
	v_mfma_f32_16x16x32_bf16 v[110:113], v[146:149], v[194:197], v[110:113]
	v_mfma_f32_16x16x32_bf16 v[106:109], v[154:157], v[194:197], v[106:109]
	v_mfma_f32_16x16x32_bf16 v[94:97], v[146:149], v[202:205], v[94:97]
	v_mfma_f32_16x16x32_bf16 v[90:93], v[154:157], v[202:205], v[90:93]
	v_mfma_f32_16x16x32_bf16 v[78:81], v[146:149], v[210:213], v[78:81]
	v_mfma_f32_16x16x32_bf16 v[74:77], v[154:157], v[210:213], v[74:77]
	s_setprio 2
	s_setprio 0
	v_mfma_f32_16x16x32_bf16 v[118:121], v[166:169], v[182:185], v[118:121]
	v_mfma_f32_16x16x32_bf16 v[114:117], v[174:177], v[182:185], v[114:117]
	v_mfma_f32_16x16x32_bf16 v[102:105], v[166:169], v[190:193], v[102:105]
	v_mfma_f32_16x16x32_bf16 v[98:101], v[174:177], v[190:193], v[98:101]
	v_mfma_f32_16x16x32_bf16 v[86:89], v[166:169], v[198:201], v[86:89]
	v_mfma_f32_16x16x32_bf16 v[82:85], v[174:177], v[198:201], v[82:85]
	v_mfma_f32_16x16x32_bf16 v[70:73], v[166:169], v[206:209], v[70:73]
	v_mfma_f32_16x16x32_bf16 v[66:69], v[174:177], v[206:209], v[66:69]
	v_mfma_f32_16x16x32_bf16 v[118:121], v[170:173], v[186:189], v[118:121]
	v_mfma_f32_16x16x32_bf16 v[114:117], v[178:181], v[186:189], v[114:117]
	v_mfma_f32_16x16x32_bf16 v[102:105], v[170:173], v[194:197], v[102:105]
	v_mfma_f32_16x16x32_bf16 v[98:101], v[178:181], v[194:197], v[98:101]
	v_mfma_f32_16x16x32_bf16 v[86:89], v[170:173], v[202:205], v[86:89]
	v_mfma_f32_16x16x32_bf16 v[82:85], v[178:181], v[202:205], v[82:85]
	v_mfma_f32_16x16x32_bf16 v[70:73], v[170:173], v[210:213], v[70:73]
	v_mfma_f32_16x16x32_bf16 v[66:69], v[178:181], v[210:213], v[66:69]
	s_setprio 2
	s_barrier
	s_mov_b32 m0, vcc_hi
	v_lshl_add_u64 v[214:215], v[214:215], 0, s[24:25]
	ds_read_b128 v[182:185], v162 offset:49152
	ds_read_b128 v[186:189], v162 offset:50176
	ds_read_b128 v[190:193], v162 offset:51200
	ds_read_b128 v[194:197], v162 offset:52224
	ds_read_b128 v[198:201], v162 offset:53248
	ds_read_b128 v[202:205], v162 offset:54272
	ds_read_b128 v[206:209], v162 offset:55296
	ds_read_b128 v[210:213], v162 offset:56320
	global_load_lds_dwordx4 v[214:215], off
	v_lshl_add_u64 v[214:215], v[216:217], 0, s[24:25]
	s_mov_b32 m0, s39
	s_nop 0
	global_load_lds_dwordx4 v[214:215], off
	v_lshl_add_u64 v[214:215], s[10:11], 0, v[132:133]
	s_mov_b32 m0, vcc_lo
	s_nop 0
	global_load_lds_dwordx4 v[214:215], off
	v_lshl_add_u64 v[214:215], s[10:11], 0, v[136:137]
	s_mov_b32 m0, s38
	s_nop 0
	global_load_lds_dwordx4 v[214:215], off
	v_lshl_add_u64 v[214:215], v[218:219], 0, s[24:25]
	s_mov_b32 m0, s85
	s_nop 0
	global_load_lds_dwordx4 v[214:215], off
	v_lshl_add_u64 v[214:215], v[220:221], 0, s[24:25]
	s_mov_b32 m0, s86
	s_nop 0
	global_load_lds_dwordx4 v[214:215], off
	s_waitcnt vmcnt(8)
	s_waitcnt lgkmcnt(0)
	s_barrier
	s_setprio 0
	v_mfma_f32_16x16x32_bf16 v[62:65], v[142:145], v[182:185], v[62:65]
	v_mfma_f32_16x16x32_bf16 v[58:61], v[150:153], v[182:185], v[58:61]
	v_mfma_f32_16x16x32_bf16 v[46:49], v[142:145], v[190:193], v[46:49]
	v_mfma_f32_16x16x32_bf16 v[42:45], v[150:153], v[190:193], v[42:45]
	v_mfma_f32_16x16x32_bf16 v[30:33], v[142:145], v[198:201], v[30:33]
	v_mfma_f32_16x16x32_bf16 v[26:29], v[150:153], v[198:201], v[26:29]
	v_mfma_f32_16x16x32_bf16 v[14:17], v[142:145], v[206:209], v[14:17]
	v_mfma_f32_16x16x32_bf16 v[10:13], v[150:153], v[206:209], v[10:13]
	v_mfma_f32_16x16x32_bf16 v[62:65], v[146:149], v[186:189], v[62:65]
	v_mfma_f32_16x16x32_bf16 v[58:61], v[154:157], v[186:189], v[58:61]
	v_mfma_f32_16x16x32_bf16 v[46:49], v[146:149], v[194:197], v[46:49]
	v_mfma_f32_16x16x32_bf16 v[42:45], v[154:157], v[194:197], v[42:45]
	v_mfma_f32_16x16x32_bf16 v[30:33], v[146:149], v[202:205], v[30:33]
	v_mfma_f32_16x16x32_bf16 v[26:29], v[154:157], v[202:205], v[26:29]
	v_mfma_f32_16x16x32_bf16 v[14:17], v[146:149], v[210:213], v[14:17]
	v_mfma_f32_16x16x32_bf16 v[10:13], v[154:157], v[210:213], v[10:13]
	s_setprio 2
	s_setprio 0
	v_mfma_f32_16x16x32_bf16 v[54:57], v[166:169], v[182:185], v[54:57]
	v_mfma_f32_16x16x32_bf16 v[50:53], v[174:177], v[182:185], v[50:53]
	v_mfma_f32_16x16x32_bf16 v[38:41], v[166:169], v[190:193], v[38:41]
	v_mfma_f32_16x16x32_bf16 v[34:37], v[174:177], v[190:193], v[34:37]
	v_mfma_f32_16x16x32_bf16 v[22:25], v[166:169], v[198:201], v[22:25]
	v_mfma_f32_16x16x32_bf16 v[18:21], v[174:177], v[198:201], v[18:21]
	v_mfma_f32_16x16x32_bf16 v[6:9], v[166:169], v[206:209], v[6:9]
	v_mfma_f32_16x16x32_bf16 v[2:5], v[174:177], v[206:209], v[2:5]
	v_mfma_f32_16x16x32_bf16 v[54:57], v[170:173], v[186:189], v[54:57]
	v_mfma_f32_16x16x32_bf16 v[50:53], v[178:181], v[186:189], v[50:53]
	v_mfma_f32_16x16x32_bf16 v[38:41], v[170:173], v[194:197], v[38:41]
	v_mfma_f32_16x16x32_bf16 v[34:37], v[178:181], v[194:197], v[34:37]
	v_mfma_f32_16x16x32_bf16 v[22:25], v[170:173], v[202:205], v[22:25]
	v_mfma_f32_16x16x32_bf16 v[18:21], v[178:181], v[202:205], v[18:21]
	v_mfma_f32_16x16x32_bf16 v[6:9], v[170:173], v[210:213], v[6:9]
	v_mfma_f32_16x16x32_bf16 v[2:5], v[178:181], v[210:213], v[2:5]
	s_setprio 2
	s_barrier
	s_movk_i32 s38, 0x100
	s_andn2_b64 vcc, exec, s[4:5]
	s_mov_b64 s[10:11], -1
	s_mov_b64 s[4:5], 0
	s_cbranch_vccz .LBB0_390
	s_and_b64 vcc, exec, s[44:45]
	s_cbranch_vccz .LBB0_393
	s_barrier

; #define PG8_STAGE(bufoff, gbase, voff) do { _Pragma("unroll") for (int _i = 0; _i < 2; ++_i) \
;         __builtin_amdgcn_global_load_lds((const unsigned*)((const char*)(gbase) + (voff)[_i]), (LAS unsigned*)(lds + (bufoff) + ldsw + _i * 8192), 16, 0, 0); } while (0)
; #define PG8_LDA(dst, b, h) do { _Pragma("unroll") for (int m = 0; m < 4; ++m) _Pragma("unroll") for (int k = 0; k < 2; ++k) dst[m][k] = *(const LAS bf16x8*)(lds + PG8_SA(b, h) + aoff + m * 2048 + k * 1024); } while (0)
; #define PG8_LDB(dst, b, h) do { _Pragma("unroll") for (int n = 0; n < 2; ++n) _Pragma("unroll") for (int k = 0; k < 2; ++k) dst[n][k] = *(const LAS bf16x8*)(lds + PG8_SB(b, h) + boff + n * 2048 + k * 1024); } while (0)
; #define PG8_MMA(ai, bj, At, Bt) do { __builtin_amdgcn_s_setprio(1); _Pragma("unroll") for (int m = 0; m < 4; ++m) _Pragma("unroll") for (int n = 0; n < 2; ++n) _Pragma("unroll") for (int k = 0; k < 2; ++k) \
;         acc[ai][bj][m][n] = __builtin_amdgcn_mfma_f32_16x16x32_bf16(Bt[n][k], At[m][k], acc[ai][bj][m][n], 0, 0, 0); __builtin_amdgcn_s_setprio(0); } while (0)
; #define PG8_WAIT_V(n) asm volatile("s_waitcnt vmcnt(" #n ")" ::: "memory")
; #define PG8_WAIT_L(n) asm volatile("s_waitcnt lgkmcnt(" #n ")" ::: "memory")
; #define PG8_BAR __builtin_amdgcn_s_barrier()
; #define PG8_SCHED __builtin_amdgcn_sched_barrier(0)
; template <class Epi>
; __device__ __forceinline__ void gemm_phase(LAS unsigned char* lds, const Gemm g, int G, int c, const Epi& E) {
;     ...
;             const bool last = (t == nt - 2);
;             const char* a1 = cA + (size_t)(t + 1) * kstep;
;             const char* a2 = last ? nA : cA + (size_t)(t + 2) * kstep; const char* b2 = last ? nB : cB + (size_t)(t + 2) * kstep;
;             const char* a3 = a2 + kstep; const char* b3 = b2 + kstep;
;             PG8_LDB(B0, 0, 0); PG8_LDB(B1, 0, 1); PG8_SCHED; PG8_LDA(At, 0, 0); PG8_STAGE(PG8_SA(1, 1), a1 + hstepA, voffA);
;             PG8_WAIT_V(8); PG8_WAIT_L(0); PG8_BAR; PG8_MMA(0, 0, At, B0); PG8_MMA(0, 1, At, B1); PG8_BAR; PG8_SCHED;
;             PG8_LDA(At, 0, 1); PG8_STAGE(PG8_SB(0, 0), b2, voffB); PG8_STAGE(PG8_SB(0, 1), b2 + hstepB, voffB); PG8_STAGE(PG8_SA(0, 0), a2, voffA);
;             PG8_WAIT_V(8); PG8_WAIT_L(0); PG8_BAR; PG8_MMA(1, 0, At, B0); PG8_MMA(1, 1, At, B1); PG8_BAR; PG8_SCHED;
.LBB0_475:
	s_mov_b32 s38, 0
	s_mov_b64 s[4:5], -1
	s_mov_b64 s[10:11], 0
	s_waitcnt lgkmcnt(0)
	s_add_u32 s33, s8, s38
	s_addc_u32 s39, s9, 0
	s_add_u32 s56, s33, 0x100
	s_addc_u32 s57, s39, 0
	s_and_b64 s[54:55], s[10:11], exec
	s_cselect_b32 s57, s47, s57
	s_cselect_b32 s56, s46, s56
	s_add_u32 s38, s6, s38
	s_addc_u32 s54, s7, 0
	s_add_u32 s38, s38, 0x100
	s_addc_u32 s54, s54, 0
	s_and_b64 s[10:11], s[10:11], exec
	s_cselect_b32 s59, s53, s54
	s_cselect_b32 s58, s52, s38
	s_add_u32 s66, s33, 0xb0080
	ds_read_b128 v[130:133], v166
	ds_read_b128 v[134:137], v166 offset:1024
	ds_read_b128 v[150:153], v166 offset:2048
	ds_read_b128 v[154:157], v166 offset:3072
	ds_read_b128 v[158:161], v167
	ds_read_b128 v[172:175], v167 offset:1024
	ds_read_b128 v[176:179], v167 offset:2048
	ds_read_b128 v[180:183], v167 offset:3072
	s_addc_u32 s67, s39, 0
	s_add_i32 s63, s95, s83
	s_add_i32 m0, s86, 0xc000
	s_add_i32 s64, s86, 0xe000
	s_add_i32 s74, s63, 0x2000
	s_add_u32 s60, s58, 0xb0000
	s_addc_u32 s61, s59, 0
	s_add_i32 s75, s96, s83
	s_add_i32 s62, s75, 0x2000
	s_add_i32 vcc_hi, 0, 0x18000
	s_add_i32 vcc_lo, 0, 0x1c000
	s_add_u32 s54, s56, 0xb0000
	s_addc_u32 s55, s57, 0
	s_add_i32 s39, vcc_hi, s83
	s_add_i32 s73, s39, 0x2000
	s_add_u32 s10, s58, 0xb0080
	s_addc_u32 s11, s59, 0
	s_add_i32 s38, vcc_lo, s83
	s_add_i32 s33, s38, 0x2000
	v_lshl_add_u64 v[162:163], s[66:67], 0, v[138:139]
	ds_read_b128 v[184:187], v168
	ds_read_b128 v[188:191], v168 offset:1024
	ds_read_b128 v[192:195], v168 offset:2048
	ds_read_b128 v[196:199], v168 offset:3072
	ds_read_b128 v[200:203], v168 offset:4096
	ds_read_b128 v[204:207], v168 offset:5120
	ds_read_b128 v[208:211], v168 offset:6144
	ds_read_b128 v[212:215], v168 offset:7168
	global_load_lds_dwordx4 v[162:163], off
	v_lshl_add_u64 v[162:163], s[66:67], 0, v[142:143]
	s_mov_b32 m0, s64
	s_nop 0
	global_load_lds_dwordx4 v[162:163], off
	s_waitcnt vmcnt(8)
	s_waitcnt lgkmcnt(0)
	s_barrier
	s_setprio 0
	v_mfma_f32_16x16x32_bf16 v[126:129], v[130:133], v[184:187], 0
	v_mfma_f32_16x16x32_bf16 v[122:125], v[150:153], v[184:187], 0
	v_mfma_f32_16x16x32_bf16 v[110:113], v[130:133], v[192:195], 0
	v_mfma_f32_16x16x32_bf16 v[106:109], v[150:153], v[192:195], 0
	v_mfma_f32_16x16x32_bf16 v[94:97], v[130:133], v[200:203], 0
	v_mfma_f32_16x16x32_bf16 v[90:93], v[150:153], v[200:203], 0
	v_mfma_f32_16x16x32_bf16 v[78:81], v[130:133], v[208:211], 0
	v_mfma_f32_16x16x32_bf16 v[74:77], v[150:153], v[208:211], 0
	v_mfma_f32_16x16x32_bf16 v[126:129], v[134:137], v[188:191], v[126:129]
	v_mfma_f32_16x16x32_bf16 v[122:125], v[154:157], v[188:191], v[122:125]
	v_mfma_f32_16x16x32_bf16 v[110:113], v[134:137], v[196:199], v[110:113]
	v_mfma_f32_16x16x32_bf16 v[106:109], v[154:157], v[196:199], v[106:109]
	v_mfma_f32_16x16x32_bf16 v[94:97], v[134:137], v[204:207], v[94:97]
	v_mfma_f32_16x16x32_bf16 v[90:93], v[154:157], v[204:207], v[90:93]
	v_mfma_f32_16x16x32_bf16 v[78:81], v[134:137], v[212:215], v[78:81]
	v_mfma_f32_16x16x32_bf16 v[74:77], v[154:157], v[212:215], v[74:77]
	s_setprio 2
	s_setprio 0
	v_mfma_f32_16x16x32_bf16 v[118:121], v[158:161], v[184:187], 0
	v_mfma_f32_16x16x32_bf16 v[114:117], v[176:179], v[184:187], 0
	v_mfma_f32_16x16x32_bf16 v[102:105], v[158:161], v[192:195], 0
	v_mfma_f32_16x16x32_bf16 v[98:101], v[176:179], v[192:195], 0
	v_mfma_f32_16x16x32_bf16 v[86:89], v[158:161], v[200:203], 0
	v_mfma_f32_16x16x32_bf16 v[82:85], v[176:179], v[200:203], 0
	v_mfma_f32_16x16x32_bf16 v[70:73], v[158:161], v[208:211], 0
	v_mfma_f32_16x16x32_bf16 v[66:69], v[176:179], v[208:211], 0
	v_mfma_f32_16x16x32_bf16 v[118:121], v[172:175], v[188:191], v[118:121]
	v_mfma_f32_16x16x32_bf16 v[114:117], v[180:183], v[188:191], v[114:117]
	v_mfma_f32_16x16x32_bf16 v[102:105], v[172:175], v[196:199], v[102:105]
	v_mfma_f32_16x16x32_bf16 v[98:101], v[180:183], v[196:199], v[98:101]
	v_mfma_f32_16x16x32_bf16 v[86:89], v[172:175], v[204:207], v[86:89]
	v_mfma_f32_16x16x32_bf16 v[82:85], v[180:183], v[204:207], v[82:85]
	v_mfma_f32_16x16x32_bf16 v[70:73], v[172:175], v[212:215], v[70:73]
	v_mfma_f32_16x16x32_bf16 v[66:69], v[180:183], v[212:215], v[66:69]
	s_setprio 2
	s_barrier
	s_mov_b32 m0, s63
	v_lshl_add_u64 v[162:163], s[58:59], 0, v[140:141]
	ds_read_b128 v[184:187], v168 offset:16384
	ds_read_b128 v[188:191], v168 offset:17408
	ds_read_b128 v[192:195], v168 offset:18432
	ds_read_b128 v[196:199], v168 offset:19456
	ds_read_b128 v[200:203], v168 offset:20480
	ds_read_b128 v[204:207], v168 offset:21504
	ds_read_b128 v[208:211], v168 offset:22528
	ds_read_b128 v[212:215], v168 offset:23552
	global_load_lds_dwordx4 v[162:163], off
	v_lshl_add_u64 v[216:217], s[58:59], 0, v[144:145]
	s_mov_b32 m0, s74
	v_lshl_add_u64 v[218:219], s[60:61], 0, v[140:141]
	global_load_lds_dwordx4 v[216:217], off
	s_mov_b32 m0, s75
	v_lshl_add_u64 v[220:221], s[56:57], 0, v[142:143]
	global_load_lds_dwordx4 v[218:219], off
	v_lshl_add_u64 v[218:219], s[60:61], 0, v[144:145]
	s_mov_b32 m0, s62
	s_nop 0
	global_load_lds_dwordx4 v[218:219], off
	v_lshl_add_u64 v[218:219], s[56:57], 0, v[138:139]
	s_mov_b32 m0, s86
	s_nop 0
	global_load_lds_dwordx4 v[218:219], off
	s_mov_b32 m0, s87
	s_nop 0
	global_load_lds_dwordx4 v[220:221], off
	s_waitcnt vmcnt(8)
	s_waitcnt lgkmcnt(0)
	s_barrier
; #define PG8_STAGE(bufoff, gbase, voff) do { _Pragma("unroll") for (int _i = 0; _i < 2; ++_i) \
;         __builtin_amdgcn_global_load_lds((const unsigned*)((const char*)(gbase) + (voff)[_i]), (LAS unsigned*)(lds + (bufoff) + ldsw + _i * 8192), 16, 0, 0); } while (0)
; #define PG8_LDA(dst, b, h) do { _Pragma("unroll") for (int m = 0; m < 4; ++m) _Pragma("unroll") for (int k = 0; k < 2; ++k) dst[m][k] = *(const LAS bf16x8*)(lds + PG8_SA(b, h) + aoff + m * 2048 + k * 1024); } while (0)
; #define PG8_LDB(dst, b, h) do { _Pragma("unroll") for (int n = 0; n < 2; ++n) _Pragma("unroll") for (int k = 0; k < 2; ++k) dst[n][k] = *(const LAS bf16x8*)(lds + PG8_SB(b, h) + boff + n * 2048 + k * 1024); } while (0)
; #define PG8_MMA(ai, bj, At, Bt) do { __builtin_amdgcn_s_setprio(1); _Pragma("unroll") for (int m = 0; m < 4; ++m) _Pragma("unroll") for (int n = 0; n < 2; ++n) _Pragma("unroll") for (int k = 0; k < 2; ++k) \
;         acc[ai][bj][m][n] = __builtin_amdgcn_mfma_f32_16x16x32_bf16(Bt[n][k], At[m][k], acc[ai][bj][m][n], 0, 0, 0); __builtin_amdgcn_s_setprio(0); } while (0)
; #define PG8_WAIT_V(n) asm volatile("s_waitcnt vmcnt(" #n ")" ::: "memory")
; #define PG8_WAIT_L(n) asm volatile("s_waitcnt lgkmcnt(" #n ")" ::: "memory")
; #define PG8_BAR __builtin_amdgcn_s_barrier()
; #define PG8_SCHED __builtin_amdgcn_sched_barrier(0)
; template <class Epi>
; __device__ __forceinline__ void gemm_phase(LAS unsigned char* lds, const Gemm g, int G, int c, const Epi& E) {
;     ...
;             PG8_WAIT_V(8); PG8_WAIT_L(0); PG8_BAR; PG8_MMA(1, 0, At, B0); PG8_MMA(1, 1, At, B1); PG8_BAR; PG8_SCHED;
;             PG8_LDB(B0, 1, 0); PG8_LDB(B1, 1, 1); PG8_SCHED; PG8_LDA(At, 1, 0); PG8_STAGE(PG8_SA(0, 1), a2 + hstepA, voffA);
;             PG8_WAIT_V(8); PG8_WAIT_L(0); PG8_BAR; PG8_MMA(0, 0, At, B0); PG8_MMA(0, 1, At, B1); PG8_BAR; PG8_SCHED;
;             PG8_LDA(At, 1, 1); PG8_STAGE(PG8_SB(1, 0), b3, voffB); PG8_STAGE(PG8_SB(1, 1), b3 + hstepB, voffB); PG8_STAGE(PG8_SA(1, 0), a3, voffA);
	s_setprio 0
	v_mfma_f32_16x16x32_bf16 v[62:65], v[130:133], v[184:187], 0
	v_mfma_f32_16x16x32_bf16 v[58:61], v[150:153], v[184:187], 0
	v_mfma_f32_16x16x32_bf16 v[46:49], v[130:133], v[192:195], 0
	v_mfma_f32_16x16x32_bf16 v[42:45], v[150:153], v[192:195], 0
	v_mfma_f32_16x16x32_bf16 v[30:33], v[130:133], v[200:203], 0
	v_mfma_f32_16x16x32_bf16 v[26:29], v[150:153], v[200:203], 0
	v_mfma_f32_16x16x32_bf16 v[14:17], v[130:133], v[208:211], 0
	v_mfma_f32_16x16x32_bf16 v[10:13], v[150:153], v[208:211], 0
	v_mfma_f32_16x16x32_bf16 v[62:65], v[134:137], v[188:191], v[62:65]
	v_mfma_f32_16x16x32_bf16 v[58:61], v[154:157], v[188:191], v[58:61]
	v_mfma_f32_16x16x32_bf16 v[46:49], v[134:137], v[196:199], v[46:49]
	v_mfma_f32_16x16x32_bf16 v[42:45], v[154:157], v[196:199], v[42:45]
	v_mfma_f32_16x16x32_bf16 v[30:33], v[134:137], v[204:207], v[30:33]
	v_mfma_f32_16x16x32_bf16 v[26:29], v[154:157], v[204:207], v[26:29]
	v_mfma_f32_16x16x32_bf16 v[14:17], v[134:137], v[212:215], v[14:17]
	v_mfma_f32_16x16x32_bf16 v[10:13], v[154:157], v[212:215], v[10:13]
	s_setprio 2
	s_setprio 0
	v_mfma_f32_16x16x32_bf16 v[54:57], v[158:161], v[184:187], 0
	v_mfma_f32_16x16x32_bf16 v[50:53], v[176:179], v[184:187], 0
	v_mfma_f32_16x16x32_bf16 v[38:41], v[158:161], v[192:195], 0
	v_mfma_f32_16x16x32_bf16 v[34:37], v[176:179], v[192:195], 0
	v_mfma_f32_16x16x32_bf16 v[22:25], v[158:161], v[200:203], 0
	v_mfma_f32_16x16x32_bf16 v[18:21], v[176:179], v[200:203], 0
	v_mfma_f32_16x16x32_bf16 v[6:9], v[158:161], v[208:211], 0
	v_mfma_f32_16x16x32_bf16 v[2:5], v[176:179], v[208:211], 0
	v_mfma_f32_16x16x32_bf16 v[54:57], v[172:175], v[188:191], v[54:57]
	v_mfma_f32_16x16x32_bf16 v[50:53], v[180:183], v[188:191], v[50:53]
	v_mfma_f32_16x16x32_bf16 v[38:41], v[172:175], v[196:199], v[38:41]
	v_mfma_f32_16x16x32_bf16 v[34:37], v[180:183], v[196:199], v[34:37]
	v_mfma_f32_16x16x32_bf16 v[22:25], v[172:175], v[204:207], v[22:25]
	v_mfma_f32_16x16x32_bf16 v[18:21], v[180:183], v[204:207], v[18:21]
	v_mfma_f32_16x16x32_bf16 v[6:9], v[172:175], v[212:215], v[6:9]
	v_mfma_f32_16x16x32_bf16 v[2:5], v[180:183], v[212:215], v[2:5]
	s_setprio 2
	s_barrier
	v_add_u32_e32 v154, vcc_hi, v165
	v_add_u32_e32 v180, vcc_lo, v165
	ds_read_b128 v[130:133], v154
	ds_read_b128 v[134:137], v154 offset:1024
	ds_read_b128 v[150:153], v154 offset:2048
	ds_read_b128 v[154:157], v154 offset:3072
	ds_read_b128 v[158:161], v180
	ds_read_b128 v[172:175], v180 offset:1024
	ds_read_b128 v[176:179], v180 offset:2048
	ds_read_b128 v[180:183], v180 offset:3072
	s_mov_b32 m0, s88
	v_lshl_add_u64 v[222:223], s[54:55], 0, v[138:139]
	ds_read_b128 v[184:187], v168 offset:32768
	ds_read_b128 v[188:191], v168 offset:33792
	ds_read_b128 v[192:195], v168 offset:34816
	ds_read_b128 v[196:199], v168 offset:35840
	ds_read_b128 v[200:203], v168 offset:36864
	ds_read_b128 v[204:207], v168 offset:37888
	ds_read_b128 v[208:211], v168 offset:38912
	ds_read_b128 v[212:215], v168 offset:39936
	global_load_lds_dwordx4 v[222:223], off
	v_lshl_add_u64 v[222:223], s[54:55], 0, v[142:143]
	s_mov_b32 m0, s89
	s_nop 0
	global_load_lds_dwordx4 v[222:223], off
	s_waitcnt vmcnt(8)
	s_waitcnt lgkmcnt(0)
	s_barrier
	s_setprio 0
	v_mfma_f32_16x16x32_bf16 v[126:129], v[130:133], v[184:187], v[126:129]
	v_mfma_f32_16x16x32_bf16 v[122:125], v[150:153], v[184:187], v[122:125]
	v_mfma_f32_16x16x32_bf16 v[110:113], v[130:133], v[192:195], v[110:113]
	v_mfma_f32_16x16x32_bf16 v[106:109], v[150:153], v[192:195], v[106:109]
	v_mfma_f32_16x16x32_bf16 v[94:97], v[130:133], v[200:203], v[94:97]
	v_mfma_f32_16x16x32_bf16 v[90:93], v[150:153], v[200:203], v[90:93]
	v_mfma_f32_16x16x32_bf16 v[78:81], v[130:133], v[208:211], v[78:81]
	v_mfma_f32_16x16x32_bf16 v[74:77], v[150:153], v[208:211], v[74:77]
	v_mfma_f32_16x16x32_bf16 v[126:129], v[134:137], v[188:191], v[126:129]
	v_mfma_f32_16x16x32_bf16 v[122:125], v[154:157], v[188:191], v[122:125]
	v_mfma_f32_16x16x32_bf16 v[110:113], v[134:137], v[196:199], v[110:113]
	v_mfma_f32_16x16x32_bf16 v[106:109], v[154:157], v[196:199], v[106:109]
	v_mfma_f32_16x16x32_bf16 v[94:97], v[134:137], v[204:207], v[94:97]
	v_mfma_f32_16x16x32_bf16 v[90:93], v[154:157], v[204:207], v[90:93]
	v_mfma_f32_16x16x32_bf16 v[78:81], v[134:137], v[212:215], v[78:81]
	v_mfma_f32_16x16x32_bf16 v[74:77], v[154:157], v[212:215], v[74:77]
	s_setprio 2
	s_setprio 0
	v_mfma_f32_16x16x32_bf16 v[118:121], v[158:161], v[184:187], v[118:121]
	v_mfma_f32_16x16x32_bf16 v[114:117], v[176:179], v[184:187], v[114:117]
	v_mfma_f32_16x16x32_bf16 v[102:105], v[158:161], v[192:195], v[102:105]
	v_mfma_f32_16x16x32_bf16 v[98:101], v[176:179], v[192:195], v[98:101]
	v_mfma_f32_16x16x32_bf16 v[86:89], v[158:161], v[200:203], v[86:89]
	v_mfma_f32_16x16x32_bf16 v[82:85], v[176:179], v[200:203], v[82:85]
	v_mfma_f32_16x16x32_bf16 v[70:73], v[158:161], v[208:211], v[70:73]
	v_mfma_f32_16x16x32_bf16 v[66:69], v[176:179], v[208:211], v[66:69]
	v_mfma_f32_16x16x32_bf16 v[118:121], v[172:175], v[188:191], v[118:121]
	v_mfma_f32_16x16x32_bf16 v[114:117], v[180:183], v[188:191], v[114:117]
	v_mfma_f32_16x16x32_bf16 v[102:105], v[172:175], v[196:199], v[102:105]
	v_mfma_f32_16x16x32_bf16 v[98:101], v[180:183], v[196:199], v[98:101]
	v_mfma_f32_16x16x32_bf16 v[86:89], v[172:175], v[204:207], v[86:89]
	v_mfma_f32_16x16x32_bf16 v[82:85], v[180:183], v[204:207], v[82:85]
	v_mfma_f32_16x16x32_bf16 v[70:73], v[172:175], v[212:215], v[70:73]
	v_mfma_f32_16x16x32_bf16 v[66:69], v[180:183], v[212:215], v[66:69]
	s_setprio 2
	s_barrier
; #define PG8_STAGE(bufoff, gbase, voff) do { _Pragma("unroll") for (int _i = 0; _i < 2; ++_i) \
;         __builtin_amdgcn_global_load_lds((const unsigned*)((const char*)(gbase) + (voff)[_i]), (LAS unsigned*)(lds + (bufoff) + ldsw + _i * 8192), 16, 0, 0); } while (0)
; #define PG8_LDA(dst, b, h) do { _Pragma("unroll") for (int m = 0; m < 4; ++m) _Pragma("unroll") for (int k = 0; k < 2; ++k) dst[m][k] = *(const LAS bf16x8*)(lds + PG8_SA(b, h) + aoff + m * 2048 + k * 1024); } while (0)
; #define PG8_LDB(dst, b, h) do { _Pragma("unroll") for (int n = 0; n < 2; ++n) _Pragma("unroll") for (int k = 0; k < 2; ++k) dst[n][k] = *(const LAS bf16x8*)(lds + PG8_SB(b, h) + boff + n * 2048 + k * 1024); } while (0)
; #define PG8_MMA(ai, bj, At, Bt) do { __builtin_amdgcn_s_setprio(1); _Pragma("unroll") for (int m = 0; m < 4; ++m) _Pragma("unroll") for (int n = 0; n < 2; ++n) _Pragma("unroll") for (int k = 0; k < 2; ++k) \
;         acc[ai][bj][m][n] = __builtin_amdgcn_mfma_f32_16x16x32_bf16(Bt[n][k], At[m][k], acc[ai][bj][m][n], 0, 0, 0); __builtin_amdgcn_s_setprio(0); } while (0)
; #define PG8_WAIT_V(n) asm volatile("s_waitcnt vmcnt(" #n ")" ::: "memory")
; #define PG8_WAIT_L(n) asm volatile("s_waitcnt lgkmcnt(" #n ")" ::: "memory")
; #define PG8_BAR __builtin_amdgcn_s_barrier()
; #define PG8_SCHED __builtin_amdgcn_sched_barrier(0)
; template <class Epi>
; __device__ __forceinline__ void gemm_phase(LAS unsigned char* lds, const Gemm g, int G, int c, const Epi& E) {
;     ...
;             const bool last = (t == nt - 2);
;             const char* a1 = cA + (size_t)(t + 1) * kstep;
;             const char* a2 = last ? nA : cA + (size_t)(t + 2) * kstep; const char* b2 = last ? nB : cB + (size_t)(t + 2) * kstep;
;             const char* a3 = a2 + kstep; const char* b3 = b2 + kstep;
;             PG8_LDB(B0, 0, 0); PG8_LDB(B1, 0, 1); PG8_SCHED; PG8_LDA(At, 0, 0); PG8_STAGE(PG8_SA(1, 1), a1 + hstepA, voffA);
;     ...
;             PG8_LDA(At, 1, 1); PG8_STAGE(PG8_SB(1, 0), b3, voffB); PG8_STAGE(PG8_SB(1, 1), b3 + hstepB, voffB); PG8_STAGE(PG8_SA(1, 0), a3, voffA);
;             PG8_WAIT_V(8); PG8_WAIT_L(0); PG8_BAR; PG8_MMA(1, 0, At, B0); PG8_MMA(1, 1, At, B1); PG8_BAR; PG8_SCHED;
	s_mov_b32 m0, s39
	v_lshl_add_u64 v[162:163], v[162:163], 0, s[24:25]
	ds_read_b128 v[184:187], v168 offset:49152
	ds_read_b128 v[188:191], v168 offset:50176
	ds_read_b128 v[192:195], v168 offset:51200
	ds_read_b128 v[196:199], v168 offset:52224
	ds_read_b128 v[200:203], v168 offset:53248
	ds_read_b128 v[204:207], v168 offset:54272
	ds_read_b128 v[208:211], v168 offset:55296
	ds_read_b128 v[212:215], v168 offset:56320
	global_load_lds_dwordx4 v[162:163], off
	v_lshl_add_u64 v[162:163], v[216:217], 0, s[24:25]
	s_mov_b32 m0, s73
	s_nop 0
	global_load_lds_dwordx4 v[162:163], off
	v_lshl_add_u64 v[162:163], s[10:11], 0, v[140:141]
	s_mov_b32 m0, s38
	s_nop 0
	global_load_lds_dwordx4 v[162:163], off
	v_lshl_add_u64 v[162:163], s[10:11], 0, v[144:145]
	s_mov_b32 m0, s33
	s_nop 0
	global_load_lds_dwordx4 v[162:163], off
	v_lshl_add_u64 v[162:163], v[218:219], 0, s[24:25]
	s_mov_b32 m0, s93
	s_nop 0
	global_load_lds_dwordx4 v[162:163], off
	v_lshl_add_u64 v[162:163], v[220:221], 0, s[24:25]
	s_mov_b32 m0, s94
	s_nop 0
	global_load_lds_dwordx4 v[162:163], off
	s_waitcnt vmcnt(8)
	s_waitcnt lgkmcnt(0)
	s_barrier
	s_setprio 0
	v_mfma_f32_16x16x32_bf16 v[62:65], v[130:133], v[184:187], v[62:65]
	v_mfma_f32_16x16x32_bf16 v[58:61], v[150:153], v[184:187], v[58:61]
	v_mfma_f32_16x16x32_bf16 v[46:49], v[130:133], v[192:195], v[46:49]
	v_mfma_f32_16x16x32_bf16 v[42:45], v[150:153], v[192:195], v[42:45]
	v_mfma_f32_16x16x32_bf16 v[30:33], v[130:133], v[200:203], v[30:33]
	v_mfma_f32_16x16x32_bf16 v[26:29], v[150:153], v[200:203], v[26:29]
	v_mfma_f32_16x16x32_bf16 v[14:17], v[130:133], v[208:211], v[14:17]
	v_mfma_f32_16x16x32_bf16 v[10:13], v[150:153], v[208:211], v[10:13]
	v_mfma_f32_16x16x32_bf16 v[62:65], v[134:137], v[188:191], v[62:65]
	v_mfma_f32_16x16x32_bf16 v[58:61], v[154:157], v[188:191], v[58:61]
	v_mfma_f32_16x16x32_bf16 v[46:49], v[134:137], v[196:199], v[46:49]
	v_mfma_f32_16x16x32_bf16 v[42:45], v[154:157], v[196:199], v[42:45]
	v_mfma_f32_16x16x32_bf16 v[30:33], v[134:137], v[204:207], v[30:33]
	v_mfma_f32_16x16x32_bf16 v[26:29], v[154:157], v[204:207], v[26:29]
	v_mfma_f32_16x16x32_bf16 v[14:17], v[134:137], v[212:215], v[14:17]
	v_mfma_f32_16x16x32_bf16 v[10:13], v[154:157], v[212:215], v[10:13]
	s_setprio 2
	s_setprio 0
	v_mfma_f32_16x16x32_bf16 v[54:57], v[158:161], v[184:187], v[54:57]
	v_mfma_f32_16x16x32_bf16 v[50:53], v[176:179], v[184:187], v[50:53]
	v_mfma_f32_16x16x32_bf16 v[38:41], v[158:161], v[192:195], v[38:41]
	v_mfma_f32_16x16x32_bf16 v[34:37], v[176:179], v[192:195], v[34:37]
	v_mfma_f32_16x16x32_bf16 v[22:25], v[158:161], v[200:203], v[22:25]
	v_mfma_f32_16x16x32_bf16 v[18:21], v[176:179], v[200:203], v[18:21]
	v_mfma_f32_16x16x32_bf16 v[6:9], v[158:161], v[208:211], v[6:9]
	v_mfma_f32_16x16x32_bf16 v[2:5], v[176:179], v[208:211], v[2:5]
	v_mfma_f32_16x16x32_bf16 v[54:57], v[172:175], v[188:191], v[54:57]
	v_mfma_f32_16x16x32_bf16 v[50:53], v[180:183], v[188:191], v[50:53]
	v_mfma_f32_16x16x32_bf16 v[38:41], v[172:175], v[196:199], v[38:41]
	v_mfma_f32_16x16x32_bf16 v[34:37], v[180:183], v[196:199], v[34:37]
	v_mfma_f32_16x16x32_bf16 v[22:25], v[172:175], v[204:207], v[22:25]
	v_mfma_f32_16x16x32_bf16 v[18:21], v[180:183], v[204:207], v[18:21]
	v_mfma_f32_16x16x32_bf16 v[6:9], v[172:175], v[212:215], v[6:9]
	v_mfma_f32_16x16x32_bf16 v[2:5], v[180:183], v[212:215], v[2:5]
	s_setprio 2
	s_barrier
	s_movk_i32 s38, 0x100
	s_andn2_b64 vcc, exec, s[4:5]
	s_mov_b64 s[10:11], -1
	s_mov_b64 s[4:5], 0
	s_cbranch_vccz .LBB0_476
.LBB0_476:
	s_add_u32 s33, s8, s38
	s_addc_u32 s39, s9, 0
	s_add_u32 s56, s33, 0x100
	s_addc_u32 s57, s39, 0
	s_and_b64 s[54:55], s[10:11], exec
	s_cselect_b32 s57, s47, s57
	s_cselect_b32 s56, s46, s56
	s_add_u32 s38, s6, s38
	s_addc_u32 s54, s7, 0
	s_add_u32 s38, s38, 0x100
	s_addc_u32 s54, s54, 0
	s_and_b64 s[10:11], s[10:11], exec
	s_cselect_b32 s59, s53, s54
	s_cselect_b32 s58, s52, s38
	s_add_u32 s66, s33, 0xb0080
	ds_read_b128 v[130:133], v166
	ds_read_b128 v[134:137], v166 offset:1024
	ds_read_b128 v[150:153], v166 offset:2048
	ds_read_b128 v[154:157], v166 offset:3072
	ds_read_b128 v[158:161], v167
	ds_read_b128 v[172:175], v167 offset:1024
	ds_read_b128 v[176:179], v167 offset:2048
	ds_read_b128 v[180:183], v167 offset:3072
	s_addc_u32 s67, s39, 0
	s_add_i32 s63, s95, s83
	s_add_i32 m0, s86, 0xc000
	s_add_i32 s64, s86, 0xe000
	s_add_i32 s74, s63, 0x2000
	s_add_u32 s60, s58, 0xb0000
	s_addc_u32 s61, s59, 0
	s_add_i32 s75, s96, s83
	s_add_i32 s62, s75, 0x2000
	s_add_i32 vcc_hi, 0, 0x18000
	s_add_i32 vcc_lo, 0, 0x1c000
	s_add_u32 s54, s56, 0xb0000
	s_addc_u32 s55, s57, 0
	s_add_i32 s39, vcc_hi, s83
	s_add_i32 s73, s39, 0x2000
	s_add_u32 s10, s58, 0xb0080
	s_addc_u32 s11, s59, 0
	s_add_i32 s38, vcc_lo, s83
	s_add_i32 s33, s38, 0x2000
	v_lshl_add_u64 v[162:163], s[66:67], 0, v[138:139]
	ds_read_b128 v[184:187], v168
	ds_read_b128 v[188:191], v168 offset:1024
	ds_read_b128 v[192:195], v168 offset:2048
	ds_read_b128 v[196:199], v168 offset:3072
	ds_read_b128 v[200:203], v168 offset:4096
	ds_read_b128 v[204:207], v168 offset:5120
	ds_read_b128 v[208:211], v168 offset:6144
	ds_read_b128 v[212:215], v168 offset:7168
	global_load_lds_dwordx4 v[162:163], off
	v_lshl_add_u64 v[162:163], s[66:67], 0, v[142:143]
	s_mov_b32 m0, s64
	s_nop 0
	global_load_lds_dwordx4 v[162:163], off
	s_waitcnt vmcnt(8)
	s_waitcnt lgkmcnt(0)
	s_barrier
; #define PG8_STAGE(bufoff, gbase, voff) do { _Pragma("unroll") for (int _i = 0; _i < 2; ++_i) \
;         __builtin_amdgcn_global_load_lds((const unsigned*)((const char*)(gbase) + (voff)[_i]), (LAS unsigned*)(lds + (bufoff) + ldsw + _i * 8192), 16, 0, 0); } while (0)
; #define PG8_LDA(dst, b, h) do { _Pragma("unroll") for (int m = 0; m < 4; ++m) _Pragma("unroll") for (int k = 0; k < 2; ++k) dst[m][k] = *(const LAS bf16x8*)(lds + PG8_SA(b, h) + aoff + m * 2048 + k * 1024); } while (0)
; #define PG8_MMA(ai, bj, At, Bt) do { __builtin_amdgcn_s_setprio(1); _Pragma("unroll") for (int m = 0; m < 4; ++m) _Pragma("unroll") for (int n = 0; n < 2; ++n) _Pragma("unroll") for (int k = 0; k < 2; ++k) \
;         acc[ai][bj][m][n] = __builtin_amdgcn_mfma_f32_16x16x32_bf16(Bt[n][k], At[m][k], acc[ai][bj][m][n], 0, 0, 0); __builtin_amdgcn_s_setprio(0); } while (0)
; #define PG8_WAIT_V(n) asm volatile("s_waitcnt vmcnt(" #n ")" ::: "memory")
; #define PG8_WAIT_L(n) asm volatile("s_waitcnt lgkmcnt(" #n ")" ::: "memory")
; #define PG8_BAR __builtin_amdgcn_s_barrier()
; #define PG8_SCHED __builtin_amdgcn_sched_barrier(0)
; template <class Epi>
; __device__ __forceinline__ void gemm_phase(LAS unsigned char* lds, const Gemm g, int G, int c, const Epi& E) {
;     ...
;             PG8_WAIT_V(8); PG8_WAIT_L(0); PG8_BAR; PG8_MMA(0, 0, At, B0); PG8_MMA(0, 1, At, B1); PG8_BAR; PG8_SCHED;
;             PG8_LDA(At, 0, 1); PG8_STAGE(PG8_SB(0, 0), b2, voffB); PG8_STAGE(PG8_SB(0, 1), b2 + hstepB, voffB); PG8_STAGE(PG8_SA(0, 0), a2, voffA);
;             PG8_WAIT_V(8); PG8_WAIT_L(0); PG8_BAR; PG8_MMA(1, 0, At, B0); PG8_MMA(1, 1, At, B1); PG8_BAR; PG8_SCHED;
	s_setprio 0
	v_mfma_f32_16x16x32_bf16 v[126:129], v[130:133], v[184:187], v[126:129]
	v_mfma_f32_16x16x32_bf16 v[122:125], v[150:153], v[184:187], v[122:125]
	v_mfma_f32_16x16x32_bf16 v[110:113], v[130:133], v[192:195], v[110:113]
	v_mfma_f32_16x16x32_bf16 v[106:109], v[150:153], v[192:195], v[106:109]
	v_mfma_f32_16x16x32_bf16 v[94:97], v[130:133], v[200:203], v[94:97]
	v_mfma_f32_16x16x32_bf16 v[90:93], v[150:153], v[200:203], v[90:93]
	v_mfma_f32_16x16x32_bf16 v[78:81], v[130:133], v[208:211], v[78:81]
	v_mfma_f32_16x16x32_bf16 v[74:77], v[150:153], v[208:211], v[74:77]
	v_mfma_f32_16x16x32_bf16 v[126:129], v[134:137], v[188:191], v[126:129]
	v_mfma_f32_16x16x32_bf16 v[122:125], v[154:157], v[188:191], v[122:125]
	v_mfma_f32_16x16x32_bf16 v[110:113], v[134:137], v[196:199], v[110:113]
	v_mfma_f32_16x16x32_bf16 v[106:109], v[154:157], v[196:199], v[106:109]
	v_mfma_f32_16x16x32_bf16 v[94:97], v[134:137], v[204:207], v[94:97]
	v_mfma_f32_16x16x32_bf16 v[90:93], v[154:157], v[204:207], v[90:93]
	v_mfma_f32_16x16x32_bf16 v[78:81], v[134:137], v[212:215], v[78:81]
	v_mfma_f32_16x16x32_bf16 v[74:77], v[154:157], v[212:215], v[74:77]
	s_setprio 2
	s_setprio 0
	v_mfma_f32_16x16x32_bf16 v[118:121], v[158:161], v[184:187], v[118:121]
	v_mfma_f32_16x16x32_bf16 v[114:117], v[176:179], v[184:187], v[114:117]
	v_mfma_f32_16x16x32_bf16 v[102:105], v[158:161], v[192:195], v[102:105]
	v_mfma_f32_16x16x32_bf16 v[98:101], v[176:179], v[192:195], v[98:101]
	v_mfma_f32_16x16x32_bf16 v[86:89], v[158:161], v[200:203], v[86:89]
	v_mfma_f32_16x16x32_bf16 v[82:85], v[176:179], v[200:203], v[82:85]
	v_mfma_f32_16x16x32_bf16 v[70:73], v[158:161], v[208:211], v[70:73]
	v_mfma_f32_16x16x32_bf16 v[66:69], v[176:179], v[208:211], v[66:69]
	v_mfma_f32_16x16x32_bf16 v[118:121], v[172:175], v[188:191], v[118:121]
	v_mfma_f32_16x16x32_bf16 v[114:117], v[180:183], v[188:191], v[114:117]
	v_mfma_f32_16x16x32_bf16 v[102:105], v[172:175], v[196:199], v[102:105]
	v_mfma_f32_16x16x32_bf16 v[98:101], v[180:183], v[196:199], v[98:101]
	v_mfma_f32_16x16x32_bf16 v[86:89], v[172:175], v[204:207], v[86:89]
	v_mfma_f32_16x16x32_bf16 v[82:85], v[180:183], v[204:207], v[82:85]
	v_mfma_f32_16x16x32_bf16 v[70:73], v[172:175], v[212:215], v[70:73]
	v_mfma_f32_16x16x32_bf16 v[66:69], v[180:183], v[212:215], v[66:69]
	s_setprio 2
	s_barrier
	s_mov_b32 m0, s63
	v_lshl_add_u64 v[162:163], s[58:59], 0, v[140:141]
	ds_read_b128 v[184:187], v168 offset:16384
	ds_read_b128 v[188:191], v168 offset:17408
	ds_read_b128 v[192:195], v168 offset:18432
	ds_read_b128 v[196:199], v168 offset:19456
	ds_read_b128 v[200:203], v168 offset:20480
	ds_read_b128 v[204:207], v168 offset:21504
	ds_read_b128 v[208:211], v168 offset:22528
	ds_read_b128 v[212:215], v168 offset:23552
	global_load_lds_dwordx4 v[162:163], off
	v_lshl_add_u64 v[216:217], s[58:59], 0, v[144:145]
	s_mov_b32 m0, s74
	v_lshl_add_u64 v[218:219], s[60:61], 0, v[140:141]
	global_load_lds_dwordx4 v[216:217], off
	s_mov_b32 m0, s75
	v_lshl_add_u64 v[220:221], s[56:57], 0, v[142:143]
	global_load_lds_dwordx4 v[218:219], off
	v_lshl_add_u64 v[218:219], s[60:61], 0, v[144:145]
	s_mov_b32 m0, s62
	s_nop 0
	global_load_lds_dwordx4 v[218:219], off
	v_lshl_add_u64 v[218:219], s[56:57], 0, v[138:139]
	s_mov_b32 m0, s86
	s_nop 0
	global_load_lds_dwordx4 v[218:219], off
	s_mov_b32 m0, s87
	s_nop 0
	global_load_lds_dwordx4 v[220:221], off
	s_waitcnt vmcnt(8)
	s_waitcnt lgkmcnt(0)
	s_barrier
	s_setprio 0
	v_mfma_f32_16x16x32_bf16 v[62:65], v[130:133], v[184:187], v[62:65]
	v_mfma_f32_16x16x32_bf16 v[58:61], v[150:153], v[184:187], v[58:61]
	v_mfma_f32_16x16x32_bf16 v[46:49], v[130:133], v[192:195], v[46:49]
	v_mfma_f32_16x16x32_bf16 v[42:45], v[150:153], v[192:195], v[42:45]
	v_mfma_f32_16x16x32_bf16 v[30:33], v[130:133], v[200:203], v[30:33]
	v_mfma_f32_16x16x32_bf16 v[26:29], v[150:153], v[200:203], v[26:29]
	v_mfma_f32_16x16x32_bf16 v[14:17], v[130:133], v[208:211], v[14:17]
	v_mfma_f32_16x16x32_bf16 v[10:13], v[150:153], v[208:211], v[10:13]
	v_mfma_f32_16x16x32_bf16 v[62:65], v[134:137], v[188:191], v[62:65]
	v_mfma_f32_16x16x32_bf16 v[58:61], v[154:157], v[188:191], v[58:61]
	v_mfma_f32_16x16x32_bf16 v[46:49], v[134:137], v[196:199], v[46:49]
	v_mfma_f32_16x16x32_bf16 v[42:45], v[154:157], v[196:199], v[42:45]
	v_mfma_f32_16x16x32_bf16 v[30:33], v[134:137], v[204:207], v[30:33]
	v_mfma_f32_16x16x32_bf16 v[26:29], v[154:157], v[204:207], v[26:29]
	v_mfma_f32_16x16x32_bf16 v[14:17], v[134:137], v[212:215], v[14:17]
	v_mfma_f32_16x16x32_bf16 v[10:13], v[154:157], v[212:215], v[10:13]
	s_setprio 2
	s_setprio 0
	v_mfma_f32_16x16x32_bf16 v[54:57], v[158:161], v[184:187], v[54:57]
	v_mfma_f32_16x16x32_bf16 v[50:53], v[176:179], v[184:187], v[50:53]
	v_mfma_f32_16x16x32_bf16 v[38:41], v[158:161], v[192:195], v[38:41]
	v_mfma_f32_16x16x32_bf16 v[34:37], v[176:179], v[192:195], v[34:37]
	v_mfma_f32_16x16x32_bf16 v[22:25], v[158:161], v[200:203], v[22:25]
	v_mfma_f32_16x16x32_bf16 v[18:21], v[176:179], v[200:203], v[18:21]
	v_mfma_f32_16x16x32_bf16 v[6:9], v[158:161], v[208:211], v[6:9]
	v_mfma_f32_16x16x32_bf16 v[2:5], v[176:179], v[208:211], v[2:5]
	v_mfma_f32_16x16x32_bf16 v[54:57], v[172:175], v[188:191], v[54:57]
	v_mfma_f32_16x16x32_bf16 v[50:53], v[180:183], v[188:191], v[50:53]
	v_mfma_f32_16x16x32_bf16 v[38:41], v[172:175], v[196:199], v[38:41]
	v_mfma_f32_16x16x32_bf16 v[34:37], v[180:183], v[196:199], v[34:37]
	v_mfma_f32_16x16x32_bf16 v[22:25], v[172:175], v[204:207], v[22:25]
	v_mfma_f32_16x16x32_bf16 v[18:21], v[180:183], v[204:207], v[18:21]
	v_mfma_f32_16x16x32_bf16 v[6:9], v[172:175], v[212:215], v[6:9]
	v_mfma_f32_16x16x32_bf16 v[2:5], v[180:183], v[212:215], v[2:5]
	s_setprio 2
	s_barrier
; #define PG8_STAGE(bufoff, gbase, voff) do { _Pragma("unroll") for (int _i = 0; _i < 2; ++_i) \
;         __builtin_amdgcn_global_load_lds((const unsigned*)((const char*)(gbase) + (voff)[_i]), (LAS unsigned*)(lds + (bufoff) + ldsw + _i * 8192), 16, 0, 0); } while (0)
; #define PG8_LDA(dst, b, h) do { _Pragma("unroll") for (int m = 0; m < 4; ++m) _Pragma("unroll") for (int k = 0; k < 2; ++k) dst[m][k] = *(const LAS bf16x8*)(lds + PG8_SA(b, h) + aoff + m * 2048 + k * 1024); } while (0)
; #define PG8_LDB(dst, b, h) do { _Pragma("unroll") for (int n = 0; n < 2; ++n) _Pragma("unroll") for (int k = 0; k < 2; ++k) dst[n][k] = *(const LAS bf16x8*)(lds + PG8_SB(b, h) + boff + n * 2048 + k * 1024); } while (0)
; #define PG8_MMA(ai, bj, At, Bt) do { __builtin_amdgcn_s_setprio(1); _Pragma("unroll") for (int m = 0; m < 4; ++m) _Pragma("unroll") for (int n = 0; n < 2; ++n) _Pragma("unroll") for (int k = 0; k < 2; ++k) \
;         acc[ai][bj][m][n] = __builtin_amdgcn_mfma_f32_16x16x32_bf16(Bt[n][k], At[m][k], acc[ai][bj][m][n], 0, 0, 0); __builtin_amdgcn_s_setprio(0); } while (0)
; #define PG8_WAIT_V(n) asm volatile("s_waitcnt vmcnt(" #n ")" ::: "memory")
; #define PG8_WAIT_L(n) asm volatile("s_waitcnt lgkmcnt(" #n ")" ::: "memory")
; #define PG8_BAR __builtin_amdgcn_s_barrier()
; #define PG8_SCHED __builtin_amdgcn_sched_barrier(0)
; template <class Epi>
; __device__ __forceinline__ void gemm_phase(LAS unsigned char* lds, const Gemm g, int G, int c, const Epi& E) {
;     ...
;             PG8_LDB(B0, 1, 0); PG8_LDB(B1, 1, 1); PG8_SCHED; PG8_LDA(At, 1, 0); PG8_STAGE(PG8_SA(0, 1), a2 + hstepA, voffA);
;             PG8_WAIT_V(8); PG8_WAIT_L(0); PG8_BAR; PG8_MMA(0, 0, At, B0); PG8_MMA(0, 1, At, B1); PG8_BAR; PG8_SCHED;
;             PG8_LDA(At, 1, 1); PG8_STAGE(PG8_SB(1, 0), b3, voffB); PG8_STAGE(PG8_SB(1, 1), b3 + hstepB, voffB); PG8_STAGE(PG8_SA(1, 0), a3, voffA);
;             PG8_WAIT_V(8); PG8_WAIT_L(0); PG8_BAR; PG8_MMA(1, 0, At, B0); PG8_MMA(1, 1, At, B1); PG8_BAR; PG8_SCHED;
;         }
;         if (wr == 0) PG8_BAR;
	v_add_u32_e32 v154, vcc_hi, v165
	v_add_u32_e32 v180, vcc_lo, v165
	ds_read_b128 v[130:133], v154
	ds_read_b128 v[134:137], v154 offset:1024
	ds_read_b128 v[150:153], v154 offset:2048
	ds_read_b128 v[154:157], v154 offset:3072
	ds_read_b128 v[158:161], v180
	ds_read_b128 v[172:175], v180 offset:1024
	ds_read_b128 v[176:179], v180 offset:2048
	ds_read_b128 v[180:183], v180 offset:3072
	s_mov_b32 m0, s88
	v_lshl_add_u64 v[222:223], s[54:55], 0, v[138:139]
	ds_read_b128 v[184:187], v168 offset:32768
	ds_read_b128 v[188:191], v168 offset:33792
	ds_read_b128 v[192:195], v168 offset:34816
	ds_read_b128 v[196:199], v168 offset:35840
	ds_read_b128 v[200:203], v168 offset:36864
	ds_read_b128 v[204:207], v168 offset:37888
	ds_read_b128 v[208:211], v168 offset:38912
	ds_read_b128 v[212:215], v168 offset:39936
	global_load_lds_dwordx4 v[222:223], off
	v_lshl_add_u64 v[222:223], s[54:55], 0, v[142:143]
	s_mov_b32 m0, s89
	s_nop 0
	global_load_lds_dwordx4 v[222:223], off
	s_waitcnt vmcnt(8)
	s_waitcnt lgkmcnt(0)
	s_barrier
	s_setprio 0
	v_mfma_f32_16x16x32_bf16 v[126:129], v[130:133], v[184:187], v[126:129]
	v_mfma_f32_16x16x32_bf16 v[122:125], v[150:153], v[184:187], v[122:125]
	v_mfma_f32_16x16x32_bf16 v[110:113], v[130:133], v[192:195], v[110:113]
	v_mfma_f32_16x16x32_bf16 v[106:109], v[150:153], v[192:195], v[106:109]
	v_mfma_f32_16x16x32_bf16 v[94:97], v[130:133], v[200:203], v[94:97]
	v_mfma_f32_16x16x32_bf16 v[90:93], v[150:153], v[200:203], v[90:93]
	v_mfma_f32_16x16x32_bf16 v[78:81], v[130:133], v[208:211], v[78:81]
	v_mfma_f32_16x16x32_bf16 v[74:77], v[150:153], v[208:211], v[74:77]
	v_mfma_f32_16x16x32_bf16 v[126:129], v[134:137], v[188:191], v[126:129]
	v_mfma_f32_16x16x32_bf16 v[122:125], v[154:157], v[188:191], v[122:125]
	v_mfma_f32_16x16x32_bf16 v[110:113], v[134:137], v[196:199], v[110:113]
	v_mfma_f32_16x16x32_bf16 v[106:109], v[154:157], v[196:199], v[106:109]
	v_mfma_f32_16x16x32_bf16 v[94:97], v[134:137], v[204:207], v[94:97]
	v_mfma_f32_16x16x32_bf16 v[90:93], v[154:157], v[204:207], v[90:93]
	v_mfma_f32_16x16x32_bf16 v[78:81], v[134:137], v[212:215], v[78:81]
	v_mfma_f32_16x16x32_bf16 v[74:77], v[154:157], v[212:215], v[74:77]
	s_setprio 2
	s_setprio 0
	v_mfma_f32_16x16x32_bf16 v[118:121], v[158:161], v[184:187], v[118:121]
	v_mfma_f32_16x16x32_bf16 v[114:117], v[176:179], v[184:187], v[114:117]
	v_mfma_f32_16x16x32_bf16 v[102:105], v[158:161], v[192:195], v[102:105]
	v_mfma_f32_16x16x32_bf16 v[98:101], v[176:179], v[192:195], v[98:101]
	v_mfma_f32_16x16x32_bf16 v[86:89], v[158:161], v[200:203], v[86:89]
	v_mfma_f32_16x16x32_bf16 v[82:85], v[176:179], v[200:203], v[82:85]
	v_mfma_f32_16x16x32_bf16 v[70:73], v[158:161], v[208:211], v[70:73]
	v_mfma_f32_16x16x32_bf16 v[66:69], v[176:179], v[208:211], v[66:69]
	v_mfma_f32_16x16x32_bf16 v[118:121], v[172:175], v[188:191], v[118:121]
	v_mfma_f32_16x16x32_bf16 v[114:117], v[180:183], v[188:191], v[114:117]
	v_mfma_f32_16x16x32_bf16 v[102:105], v[172:175], v[196:199], v[102:105]
	v_mfma_f32_16x16x32_bf16 v[98:101], v[180:183], v[196:199], v[98:101]
	v_mfma_f32_16x16x32_bf16 v[86:89], v[172:175], v[204:207], v[86:89]
	v_mfma_f32_16x16x32_bf16 v[82:85], v[180:183], v[204:207], v[82:85]
	v_mfma_f32_16x16x32_bf16 v[70:73], v[172:175], v[212:215], v[70:73]
	v_mfma_f32_16x16x32_bf16 v[66:69], v[180:183], v[212:215], v[66:69]
	s_setprio 2
	s_barrier
	s_mov_b32 m0, s39
	v_lshl_add_u64 v[162:163], v[162:163], 0, s[24:25]
	ds_read_b128 v[184:187], v168 offset:49152
	ds_read_b128 v[188:191], v168 offset:50176
	ds_read_b128 v[192:195], v168 offset:51200
	ds_read_b128 v[196:199], v168 offset:52224
	ds_read_b128 v[200:203], v168 offset:53248
	ds_read_b128 v[204:207], v168 offset:54272
	ds_read_b128 v[208:211], v168 offset:55296
	ds_read_b128 v[212:215], v168 offset:56320
	global_load_lds_dwordx4 v[162:163], off
	v_lshl_add_u64 v[162:163], v[216:217], 0, s[24:25]
	s_mov_b32 m0, s73
	s_nop 0
	global_load_lds_dwordx4 v[162:163], off
	v_lshl_add_u64 v[162:163], s[10:11], 0, v[140:141]
	s_mov_b32 m0, s38
	s_nop 0
	global_load_lds_dwordx4 v[162:163], off
	v_lshl_add_u64 v[162:163], s[10:11], 0, v[144:145]
	s_mov_b32 m0, s33
	s_nop 0
	global_load_lds_dwordx4 v[162:163], off
	v_lshl_add_u64 v[162:163], v[218:219], 0, s[24:25]
	s_mov_b32 m0, s93
	s_nop 0
	global_load_lds_dwordx4 v[162:163], off
	v_lshl_add_u64 v[162:163], v[220:221], 0, s[24:25]
	s_mov_b32 m0, s94
	s_nop 0
	global_load_lds_dwordx4 v[162:163], off
	s_waitcnt vmcnt(8)
	s_waitcnt lgkmcnt(0)
	s_barrier
	s_setprio 0
	v_mfma_f32_16x16x32_bf16 v[62:65], v[130:133], v[184:187], v[62:65]
	v_mfma_f32_16x16x32_bf16 v[58:61], v[150:153], v[184:187], v[58:61]
	v_mfma_f32_16x16x32_bf16 v[46:49], v[130:133], v[192:195], v[46:49]
	v_mfma_f32_16x16x32_bf16 v[42:45], v[150:153], v[192:195], v[42:45]
	v_mfma_f32_16x16x32_bf16 v[30:33], v[130:133], v[200:203], v[30:33]
	v_mfma_f32_16x16x32_bf16 v[26:29], v[150:153], v[200:203], v[26:29]
	v_mfma_f32_16x16x32_bf16 v[14:17], v[130:133], v[208:211], v[14:17]
	v_mfma_f32_16x16x32_bf16 v[10:13], v[150:153], v[208:211], v[10:13]
	v_mfma_f32_16x16x32_bf16 v[62:65], v[134:137], v[188:191], v[62:65]
	v_mfma_f32_16x16x32_bf16 v[58:61], v[154:157], v[188:191], v[58:61]
	v_mfma_f32_16x16x32_bf16 v[46:49], v[134:137], v[196:199], v[46:49]
	v_mfma_f32_16x16x32_bf16 v[42:45], v[154:157], v[196:199], v[42:45]
	v_mfma_f32_16x16x32_bf16 v[30:33], v[134:137], v[204:207], v[30:33]
	v_mfma_f32_16x16x32_bf16 v[26:29], v[154:157], v[204:207], v[26:29]
	v_mfma_f32_16x16x32_bf16 v[14:17], v[134:137], v[212:215], v[14:17]
	v_mfma_f32_16x16x32_bf16 v[10:13], v[154:157], v[212:215], v[10:13]
	s_setprio 2
	s_setprio 0
	v_mfma_f32_16x16x32_bf16 v[54:57], v[158:161], v[184:187], v[54:57]
	v_mfma_f32_16x16x32_bf16 v[50:53], v[176:179], v[184:187], v[50:53]
	v_mfma_f32_16x16x32_bf16 v[38:41], v[158:161], v[192:195], v[38:41]
	v_mfma_f32_16x16x32_bf16 v[34:37], v[176:179], v[192:195], v[34:37]
	v_mfma_f32_16x16x32_bf16 v[22:25], v[158:161], v[200:203], v[22:25]
	v_mfma_f32_16x16x32_bf16 v[18:21], v[176:179], v[200:203], v[18:21]
	v_mfma_f32_16x16x32_bf16 v[6:9], v[158:161], v[208:211], v[6:9]
	v_mfma_f32_16x16x32_bf16 v[2:5], v[176:179], v[208:211], v[2:5]
	v_mfma_f32_16x16x32_bf16 v[54:57], v[172:175], v[188:191], v[54:57]
	v_mfma_f32_16x16x32_bf16 v[50:53], v[180:183], v[188:191], v[50:53]
	v_mfma_f32_16x16x32_bf16 v[38:41], v[172:175], v[196:199], v[38:41]
	v_mfma_f32_16x16x32_bf16 v[34:37], v[180:183], v[196:199], v[34:37]
	v_mfma_f32_16x16x32_bf16 v[22:25], v[172:175], v[204:207], v[22:25]
	v_mfma_f32_16x16x32_bf16 v[18:21], v[180:183], v[204:207], v[18:21]
	v_mfma_f32_16x16x32_bf16 v[6:9], v[172:175], v[212:215], v[6:9]
	v_mfma_f32_16x16x32_bf16 v[2:5], v[180:183], v[212:215], v[2:5]
	s_setprio 2
	s_barrier
	s_movk_i32 s38, 0x100
	s_andn2_b64 vcc, exec, s[4:5]
	s_mov_b64 s[10:11], -1
	s_mov_b64 s[4:5], 0
	s_cbranch_vccz .LBB0_476
	s_and_b64 vcc, exec, s[44:45]
	s_cbranch_vccz .LBB0_479
	s_barrier

; #define PG8_STAGE(bufoff, gbase, voff) do { _Pragma("unroll") for (int _i = 0; _i < 2; ++_i) \
;         __builtin_amdgcn_global_load_lds((const unsigned*)((const char*)(gbase) + (voff)[_i]), (LAS unsigned*)(lds + (bufoff) + ldsw + _i * 8192), 16, 0, 0); } while (0)
; #define PG8_LDA(dst, b, h) do { _Pragma("unroll") for (int m = 0; m < 4; ++m) _Pragma("unroll") for (int k = 0; k < 2; ++k) dst[m][k] = *(const LAS bf16x8*)(lds + PG8_SA(b, h) + aoff + m * 2048 + k * 1024); } while (0)
; #define PG8_LDB(dst, b, h) do { _Pragma("unroll") for (int n = 0; n < 2; ++n) _Pragma("unroll") for (int k = 0; k < 2; ++k) dst[n][k] = *(const LAS bf16x8*)(lds + PG8_SB(b, h) + boff + n * 2048 + k * 1024); } while (0)
; #define PG8_MMA(ai, bj, At, Bt) do { __builtin_amdgcn_s_setprio(1); _Pragma("unroll") for (int m = 0; m < 4; ++m) _Pragma("unroll") for (int n = 0; n < 2; ++n) _Pragma("unroll") for (int k = 0; k < 2; ++k) \
;         acc[ai][bj][m][n] = __builtin_amdgcn_mfma_f32_16x16x32_bf16(Bt[n][k], At[m][k], acc[ai][bj][m][n], 0, 0, 0); __builtin_amdgcn_s_setprio(0); } while (0)
; #define PG8_WAIT_V(n) asm volatile("s_waitcnt vmcnt(" #n ")" ::: "memory")
; #define PG8_WAIT_L(n) asm volatile("s_waitcnt lgkmcnt(" #n ")" ::: "memory")
; #define PG8_BAR __builtin_amdgcn_s_barrier()
; #define PG8_SCHED __builtin_amdgcn_sched_barrier(0)
; template <class Epi>
; __device__ __forceinline__ void gemm_phase(LAS unsigned char* lds, const Gemm g, int G, int c, const Epi& E) {
;     ...
;             const bool last = (t == nt - 2);
;             const char* a1 = cA + (size_t)(t + 1) * kstep;
;             const char* a2 = last ? nA : cA + (size_t)(t + 2) * kstep; const char* b2 = last ? nB : cB + (size_t)(t + 2) * kstep;
;             const char* a3 = a2 + kstep; const char* b3 = b2 + kstep;
;             PG8_LDB(B0, 0, 0); PG8_LDB(B1, 0, 1); PG8_SCHED; PG8_LDA(At, 0, 0); PG8_STAGE(PG8_SA(1, 1), a1 + hstepA, voffA);
;             PG8_WAIT_V(8); PG8_WAIT_L(0); PG8_BAR; PG8_MMA(0, 0, At, B0); PG8_MMA(0, 1, At, B1); PG8_BAR; PG8_SCHED;
;             PG8_LDA(At, 0, 1); PG8_STAGE(PG8_SB(0, 0), b2, voffB); PG8_STAGE(PG8_SB(0, 1), b2 + hstepB, voffB); PG8_STAGE(PG8_SA(0, 0), a2, voffA);
;             PG8_WAIT_V(8); PG8_WAIT_L(0); PG8_BAR; PG8_MMA(1, 0, At, B0); PG8_MMA(1, 1, At, B1); PG8_BAR; PG8_SCHED;
.LBB0_593:
	s_mov_b32 s38, 0
	s_mov_b64 s[4:5], -1
	s_mov_b64 s[54:55], 0
	s_waitcnt lgkmcnt(0)
	s_add_u32 s33, s8, s38
	s_addc_u32 s62, s9, 0
	s_add_u32 s39, s33, 0x100
	s_addc_u32 s58, s62, 0
	s_and_b64 s[56:57], s[54:55], exec
	s_cselect_b32 s59, s45, s58
	s_cselect_b32 s58, s44, s39
	s_add_u32 s38, s6, s38
	s_addc_u32 s39, s7, 0
	s_add_u32 s56, s38, 0x100
	s_addc_u32 s57, s39, 0
	s_and_b64 s[38:39], s[54:55], exec
	s_cselect_b32 s61, s47, s57
	s_cselect_b32 s60, s46, s56
	s_add_u32 s68, s33, 0xb0080
	s_addc_u32 s69, s62, 0
	s_add_i32 s63, s86, s23
	ds_read_b128 v[142:145], v166
	ds_read_b128 v[146:149], v166 offset:1024
	ds_read_b128 v[150:153], v166 offset:2048
	ds_read_b128 v[154:157], v166 offset:3072
	ds_read_b128 v[158:161], v167
	ds_read_b128 v[170:173], v167 offset:1024
	ds_read_b128 v[174:177], v167 offset:2048
	ds_read_b128 v[178:181], v167 offset:3072
	s_add_i32 m0, s72, 0xc000
	s_add_i32 s64, s72, 0xe000
	s_add_i32 s74, s63, 0x2000
	s_add_u32 s66, s60, 0xb0000
	s_addc_u32 s67, s61, 0
	s_add_i32 s62, s87, s23
	s_add_i32 s75, s62, 0x2000
	s_add_i32 s97, 0, 0x18000
	s_add_i32 s33, 0, 0x1c000
	s_add_u32 s56, s58, 0xb0000
	s_addc_u32 s57, s59, 0
	s_add_i32 s96, s97, s23
	s_add_i32 s39, s96, 0x2000
	s_add_u32 s54, s60, 0xb0080
	s_addc_u32 s55, s61, 0
	s_add_i32 s95, s33, s23
	s_add_i32 s38, s95, 0x2000
	v_lshl_add_u64 v[162:163], s[68:69], 0, v[136:137]
	ds_read_b128 v[182:185], v168
	ds_read_b128 v[186:189], v168 offset:1024
	ds_read_b128 v[190:193], v168 offset:2048
	ds_read_b128 v[194:197], v168 offset:3072
	ds_read_b128 v[198:201], v168 offset:4096
	ds_read_b128 v[202:205], v168 offset:5120
	ds_read_b128 v[206:209], v168 offset:6144
	ds_read_b128 v[210:213], v168 offset:7168
	global_load_lds_dwordx4 v[162:163], off
	v_lshl_add_u64 v[162:163], s[68:69], 0, v[132:133]
	s_mov_b32 m0, s64
	s_nop 0
	global_load_lds_dwordx4 v[162:163], off
	s_waitcnt vmcnt(8)
	s_waitcnt lgkmcnt(0)
	s_barrier
	s_setprio 0
	v_mfma_f32_16x16x32_bf16 v[126:129], v[142:145], v[182:185], 0
	v_mfma_f32_16x16x32_bf16 v[122:125], v[150:153], v[182:185], 0
	v_mfma_f32_16x16x32_bf16 v[110:113], v[142:145], v[190:193], 0
	v_mfma_f32_16x16x32_bf16 v[106:109], v[150:153], v[190:193], 0
	v_mfma_f32_16x16x32_bf16 v[94:97], v[142:145], v[198:201], 0
	v_mfma_f32_16x16x32_bf16 v[90:93], v[150:153], v[198:201], 0
	v_mfma_f32_16x16x32_bf16 v[78:81], v[142:145], v[206:209], 0
	v_mfma_f32_16x16x32_bf16 v[74:77], v[150:153], v[206:209], 0
	v_mfma_f32_16x16x32_bf16 v[126:129], v[146:149], v[186:189], v[126:129]
	v_mfma_f32_16x16x32_bf16 v[122:125], v[154:157], v[186:189], v[122:125]
	v_mfma_f32_16x16x32_bf16 v[110:113], v[146:149], v[194:197], v[110:113]
	v_mfma_f32_16x16x32_bf16 v[106:109], v[154:157], v[194:197], v[106:109]
	v_mfma_f32_16x16x32_bf16 v[94:97], v[146:149], v[202:205], v[94:97]
	v_mfma_f32_16x16x32_bf16 v[90:93], v[154:157], v[202:205], v[90:93]
	v_mfma_f32_16x16x32_bf16 v[78:81], v[146:149], v[210:213], v[78:81]
	v_mfma_f32_16x16x32_bf16 v[74:77], v[154:157], v[210:213], v[74:77]
	s_setprio 2
	s_setprio 0
	v_mfma_f32_16x16x32_bf16 v[118:121], v[158:161], v[182:185], 0
	v_mfma_f32_16x16x32_bf16 v[114:117], v[174:177], v[182:185], 0
	v_mfma_f32_16x16x32_bf16 v[102:105], v[158:161], v[190:193], 0
	v_mfma_f32_16x16x32_bf16 v[98:101], v[174:177], v[190:193], 0
	v_mfma_f32_16x16x32_bf16 v[86:89], v[158:161], v[198:201], 0
	v_mfma_f32_16x16x32_bf16 v[82:85], v[174:177], v[198:201], 0
	v_mfma_f32_16x16x32_bf16 v[70:73], v[158:161], v[206:209], 0
	v_mfma_f32_16x16x32_bf16 v[66:69], v[174:177], v[206:209], 0
	v_mfma_f32_16x16x32_bf16 v[118:121], v[170:173], v[186:189], v[118:121]
	v_mfma_f32_16x16x32_bf16 v[114:117], v[178:181], v[186:189], v[114:117]
	v_mfma_f32_16x16x32_bf16 v[102:105], v[170:173], v[194:197], v[102:105]
	v_mfma_f32_16x16x32_bf16 v[98:101], v[178:181], v[194:197], v[98:101]
	v_mfma_f32_16x16x32_bf16 v[86:89], v[170:173], v[202:205], v[86:89]
	v_mfma_f32_16x16x32_bf16 v[82:85], v[178:181], v[202:205], v[82:85]
	v_mfma_f32_16x16x32_bf16 v[70:73], v[170:173], v[210:213], v[70:73]
	v_mfma_f32_16x16x32_bf16 v[66:69], v[178:181], v[210:213], v[66:69]
	s_setprio 2
	s_barrier
	s_mov_b32 m0, s63
	v_lshl_add_u64 v[162:163], s[60:61], 0, v[134:135]
	ds_read_b128 v[182:185], v168 offset:16384
	ds_read_b128 v[186:189], v168 offset:17408
	ds_read_b128 v[190:193], v168 offset:18432
	ds_read_b128 v[194:197], v168 offset:19456
	ds_read_b128 v[198:201], v168 offset:20480
	ds_read_b128 v[202:205], v168 offset:21504
	ds_read_b128 v[206:209], v168 offset:22528
	ds_read_b128 v[210:213], v168 offset:23552
	global_load_lds_dwordx4 v[162:163], off
	v_lshl_add_u64 v[214:215], s[60:61], 0, v[130:131]
	s_mov_b32 m0, s74
	v_lshl_add_u64 v[216:217], s[66:67], 0, v[134:135]
	global_load_lds_dwordx4 v[214:215], off
	s_mov_b32 m0, s62
	v_lshl_add_u64 v[218:219], s[58:59], 0, v[132:133]
	global_load_lds_dwordx4 v[216:217], off
	v_lshl_add_u64 v[216:217], s[66:67], 0, v[130:131]
	s_mov_b32 m0, s75
	s_nop 0
	global_load_lds_dwordx4 v[216:217], off
	v_lshl_add_u64 v[216:217], s[58:59], 0, v[136:137]
	s_mov_b32 m0, s72
	s_nop 0
	global_load_lds_dwordx4 v[216:217], off
	s_mov_b32 m0, s73
	s_nop 0
	global_load_lds_dwordx4 v[218:219], off
	s_waitcnt vmcnt(8)
	s_waitcnt lgkmcnt(0)
	s_barrier
; #define PG8_STAGE(bufoff, gbase, voff) do { _Pragma("unroll") for (int _i = 0; _i < 2; ++_i) \
;         __builtin_amdgcn_global_load_lds((const unsigned*)((const char*)(gbase) + (voff)[_i]), (LAS unsigned*)(lds + (bufoff) + ldsw + _i * 8192), 16, 0, 0); } while (0)
; #define PG8_LDA(dst, b, h) do { _Pragma("unroll") for (int m = 0; m < 4; ++m) _Pragma("unroll") for (int k = 0; k < 2; ++k) dst[m][k] = *(const LAS bf16x8*)(lds + PG8_SA(b, h) + aoff + m * 2048 + k * 1024); } while (0)
; #define PG8_LDB(dst, b, h) do { _Pragma("unroll") for (int n = 0; n < 2; ++n) _Pragma("unroll") for (int k = 0; k < 2; ++k) dst[n][k] = *(const LAS bf16x8*)(lds + PG8_SB(b, h) + boff + n * 2048 + k * 1024); } while (0)
; #define PG8_MMA(ai, bj, At, Bt) do { __builtin_amdgcn_s_setprio(1); _Pragma("unroll") for (int m = 0; m < 4; ++m) _Pragma("unroll") for (int n = 0; n < 2; ++n) _Pragma("unroll") for (int k = 0; k < 2; ++k) \
;         acc[ai][bj][m][n] = __builtin_amdgcn_mfma_f32_16x16x32_bf16(Bt[n][k], At[m][k], acc[ai][bj][m][n], 0, 0, 0); __builtin_amdgcn_s_setprio(0); } while (0)
; #define PG8_WAIT_V(n) asm volatile("s_waitcnt vmcnt(" #n ")" ::: "memory")
; #define PG8_WAIT_L(n) asm volatile("s_waitcnt lgkmcnt(" #n ")" ::: "memory")
; #define PG8_BAR __builtin_amdgcn_s_barrier()
; #define PG8_SCHED __builtin_amdgcn_sched_barrier(0)
; template <class Epi>
; __device__ __forceinline__ void gemm_phase(LAS unsigned char* lds, const Gemm g, int G, int c, const Epi& E) {
;     ...
;             PG8_WAIT_V(8); PG8_WAIT_L(0); PG8_BAR; PG8_MMA(1, 0, At, B0); PG8_MMA(1, 1, At, B1); PG8_BAR; PG8_SCHED;
;             PG8_LDB(B0, 1, 0); PG8_LDB(B1, 1, 1); PG8_SCHED; PG8_LDA(At, 1, 0); PG8_STAGE(PG8_SA(0, 1), a2 + hstepA, voffA);
;             PG8_WAIT_V(8); PG8_WAIT_L(0); PG8_BAR; PG8_MMA(0, 0, At, B0); PG8_MMA(0, 1, At, B1); PG8_BAR; PG8_SCHED;
;             PG8_LDA(At, 1, 1); PG8_STAGE(PG8_SB(1, 0), b3, voffB); PG8_STAGE(PG8_SB(1, 1), b3 + hstepB, voffB); PG8_STAGE(PG8_SA(1, 0), a3, voffA);
	s_setprio 0
	v_mfma_f32_16x16x32_bf16 v[62:65], v[142:145], v[182:185], 0
	v_mfma_f32_16x16x32_bf16 v[58:61], v[150:153], v[182:185], 0
	v_mfma_f32_16x16x32_bf16 v[46:49], v[142:145], v[190:193], 0
	v_mfma_f32_16x16x32_bf16 v[42:45], v[150:153], v[190:193], 0
	v_mfma_f32_16x16x32_bf16 v[30:33], v[142:145], v[198:201], 0
	v_mfma_f32_16x16x32_bf16 v[26:29], v[150:153], v[198:201], 0
	v_mfma_f32_16x16x32_bf16 v[14:17], v[142:145], v[206:209], 0
	v_mfma_f32_16x16x32_bf16 v[10:13], v[150:153], v[206:209], 0
	v_mfma_f32_16x16x32_bf16 v[62:65], v[146:149], v[186:189], v[62:65]
	v_mfma_f32_16x16x32_bf16 v[58:61], v[154:157], v[186:189], v[58:61]
	v_mfma_f32_16x16x32_bf16 v[46:49], v[146:149], v[194:197], v[46:49]
	v_mfma_f32_16x16x32_bf16 v[42:45], v[154:157], v[194:197], v[42:45]
	v_mfma_f32_16x16x32_bf16 v[30:33], v[146:149], v[202:205], v[30:33]
	v_mfma_f32_16x16x32_bf16 v[26:29], v[154:157], v[202:205], v[26:29]
	v_mfma_f32_16x16x32_bf16 v[14:17], v[146:149], v[210:213], v[14:17]
	v_mfma_f32_16x16x32_bf16 v[10:13], v[154:157], v[210:213], v[10:13]
	s_setprio 2
	s_setprio 0
	v_mfma_f32_16x16x32_bf16 v[54:57], v[158:161], v[182:185], 0
	v_mfma_f32_16x16x32_bf16 v[50:53], v[174:177], v[182:185], 0
	v_mfma_f32_16x16x32_bf16 v[38:41], v[158:161], v[190:193], 0
	v_mfma_f32_16x16x32_bf16 v[34:37], v[174:177], v[190:193], 0
	v_mfma_f32_16x16x32_bf16 v[22:25], v[158:161], v[198:201], 0
	v_mfma_f32_16x16x32_bf16 v[18:21], v[174:177], v[198:201], 0
	v_mfma_f32_16x16x32_bf16 v[6:9], v[158:161], v[206:209], 0
	v_mfma_f32_16x16x32_bf16 v[2:5], v[174:177], v[206:209], 0
	v_mfma_f32_16x16x32_bf16 v[54:57], v[170:173], v[186:189], v[54:57]
	v_mfma_f32_16x16x32_bf16 v[50:53], v[178:181], v[186:189], v[50:53]
	v_mfma_f32_16x16x32_bf16 v[38:41], v[170:173], v[194:197], v[38:41]
	v_mfma_f32_16x16x32_bf16 v[34:37], v[178:181], v[194:197], v[34:37]
	v_mfma_f32_16x16x32_bf16 v[22:25], v[170:173], v[202:205], v[22:25]
	v_mfma_f32_16x16x32_bf16 v[18:21], v[178:181], v[202:205], v[18:21]
	v_mfma_f32_16x16x32_bf16 v[6:9], v[170:173], v[210:213], v[6:9]
	v_mfma_f32_16x16x32_bf16 v[2:5], v[178:181], v[210:213], v[2:5]
	s_setprio 2
	s_barrier
	v_add_u32_e32 v154, s97, v165
	v_add_u32_e32 v178, s33, v165
	ds_read_b128 v[142:145], v154
	ds_read_b128 v[146:149], v154 offset:1024
	ds_read_b128 v[150:153], v154 offset:2048
	ds_read_b128 v[154:157], v154 offset:3072
	ds_read_b128 v[158:161], v178
	ds_read_b128 v[170:173], v178 offset:1024
	ds_read_b128 v[174:177], v178 offset:2048
	ds_read_b128 v[178:181], v178 offset:3072
	s_mov_b32 m0, s78
	v_lshl_add_u64 v[220:221], s[56:57], 0, v[136:137]
	ds_read_b128 v[182:185], v168 offset:32768
	ds_read_b128 v[186:189], v168 offset:33792
	ds_read_b128 v[190:193], v168 offset:34816
	ds_read_b128 v[194:197], v168 offset:35840
	ds_read_b128 v[198:201], v168 offset:36864
	ds_read_b128 v[202:205], v168 offset:37888
	ds_read_b128 v[206:209], v168 offset:38912
	ds_read_b128 v[210:213], v168 offset:39936
	global_load_lds_dwordx4 v[220:221], off
	v_lshl_add_u64 v[220:221], s[56:57], 0, v[132:133]
	s_mov_b32 m0, s81
	s_nop 0
	global_load_lds_dwordx4 v[220:221], off
	s_waitcnt vmcnt(8)
	s_waitcnt lgkmcnt(0)
	s_barrier
	s_setprio 0
	v_mfma_f32_16x16x32_bf16 v[126:129], v[142:145], v[182:185], v[126:129]
	v_mfma_f32_16x16x32_bf16 v[122:125], v[150:153], v[182:185], v[122:125]
	v_mfma_f32_16x16x32_bf16 v[110:113], v[142:145], v[190:193], v[110:113]
	v_mfma_f32_16x16x32_bf16 v[106:109], v[150:153], v[190:193], v[106:109]
	v_mfma_f32_16x16x32_bf16 v[94:97], v[142:145], v[198:201], v[94:97]
	v_mfma_f32_16x16x32_bf16 v[90:93], v[150:153], v[198:201], v[90:93]
	v_mfma_f32_16x16x32_bf16 v[78:81], v[142:145], v[206:209], v[78:81]
	v_mfma_f32_16x16x32_bf16 v[74:77], v[150:153], v[206:209], v[74:77]
	v_mfma_f32_16x16x32_bf16 v[126:129], v[146:149], v[186:189], v[126:129]
	v_mfma_f32_16x16x32_bf16 v[122:125], v[154:157], v[186:189], v[122:125]
	v_mfma_f32_16x16x32_bf16 v[110:113], v[146:149], v[194:197], v[110:113]
	v_mfma_f32_16x16x32_bf16 v[106:109], v[154:157], v[194:197], v[106:109]
	v_mfma_f32_16x16x32_bf16 v[94:97], v[146:149], v[202:205], v[94:97]
	v_mfma_f32_16x16x32_bf16 v[90:93], v[154:157], v[202:205], v[90:93]
	v_mfma_f32_16x16x32_bf16 v[78:81], v[146:149], v[210:213], v[78:81]
	v_mfma_f32_16x16x32_bf16 v[74:77], v[154:157], v[210:213], v[74:77]
	s_setprio 2
	s_setprio 0
	v_mfma_f32_16x16x32_bf16 v[118:121], v[158:161], v[182:185], v[118:121]
	v_mfma_f32_16x16x32_bf16 v[114:117], v[174:177], v[182:185], v[114:117]
	v_mfma_f32_16x16x32_bf16 v[102:105], v[158:161], v[190:193], v[102:105]
	v_mfma_f32_16x16x32_bf16 v[98:101], v[174:177], v[190:193], v[98:101]
	v_mfma_f32_16x16x32_bf16 v[86:89], v[158:161], v[198:201], v[86:89]
	v_mfma_f32_16x16x32_bf16 v[82:85], v[174:177], v[198:201], v[82:85]
	v_mfma_f32_16x16x32_bf16 v[70:73], v[158:161], v[206:209], v[70:73]
	v_mfma_f32_16x16x32_bf16 v[66:69], v[174:177], v[206:209], v[66:69]
	v_mfma_f32_16x16x32_bf16 v[118:121], v[170:173], v[186:189], v[118:121]
	v_mfma_f32_16x16x32_bf16 v[114:117], v[178:181], v[186:189], v[114:117]
	v_mfma_f32_16x16x32_bf16 v[102:105], v[170:173], v[194:197], v[102:105]
	v_mfma_f32_16x16x32_bf16 v[98:101], v[178:181], v[194:197], v[98:101]
	v_mfma_f32_16x16x32_bf16 v[86:89], v[170:173], v[202:205], v[86:89]
	v_mfma_f32_16x16x32_bf16 v[82:85], v[178:181], v[202:205], v[82:85]
	v_mfma_f32_16x16x32_bf16 v[70:73], v[170:173], v[210:213], v[70:73]
	v_mfma_f32_16x16x32_bf16 v[66:69], v[178:181], v[210:213], v[66:69]
	s_setprio 2
	s_barrier
; #define PG8_STAGE(bufoff, gbase, voff) do { _Pragma("unroll") for (int _i = 0; _i < 2; ++_i) \
;         __builtin_amdgcn_global_load_lds((const unsigned*)((const char*)(gbase) + (voff)[_i]), (LAS unsigned*)(lds + (bufoff) + ldsw + _i * 8192), 16, 0, 0); } while (0)
; #define PG8_LDA(dst, b, h) do { _Pragma("unroll") for (int m = 0; m < 4; ++m) _Pragma("unroll") for (int k = 0; k < 2; ++k) dst[m][k] = *(const LAS bf16x8*)(lds + PG8_SA(b, h) + aoff + m * 2048 + k * 1024); } while (0)
; #define PG8_LDB(dst, b, h) do { _Pragma("unroll") for (int n = 0; n < 2; ++n) _Pragma("unroll") for (int k = 0; k < 2; ++k) dst[n][k] = *(const LAS bf16x8*)(lds + PG8_SB(b, h) + boff + n * 2048 + k * 1024); } while (0)
; #define PG8_MMA(ai, bj, At, Bt) do { __builtin_amdgcn_s_setprio(1); _Pragma("unroll") for (int m = 0; m < 4; ++m) _Pragma("unroll") for (int n = 0; n < 2; ++n) _Pragma("unroll") for (int k = 0; k < 2; ++k) \
;         acc[ai][bj][m][n] = __builtin_amdgcn_mfma_f32_16x16x32_bf16(Bt[n][k], At[m][k], acc[ai][bj][m][n], 0, 0, 0); __builtin_amdgcn_s_setprio(0); } while (0)
; #define PG8_WAIT_V(n) asm volatile("s_waitcnt vmcnt(" #n ")" ::: "memory")
; #define PG8_WAIT_L(n) asm volatile("s_waitcnt lgkmcnt(" #n ")" ::: "memory")
; #define PG8_BAR __builtin_amdgcn_s_barrier()
; #define PG8_SCHED __builtin_amdgcn_sched_barrier(0)
; template <class Epi>
; __device__ __forceinline__ void gemm_phase(LAS unsigned char* lds, const Gemm g, int G, int c, const Epi& E) {
;     ...
;             const bool last = (t == nt - 2);
;             const char* a1 = cA + (size_t)(t + 1) * kstep;
;             const char* a2 = last ? nA : cA + (size_t)(t + 2) * kstep; const char* b2 = last ? nB : cB + (size_t)(t + 2) * kstep;
;             const char* a3 = a2 + kstep; const char* b3 = b2 + kstep;
;             PG8_LDB(B0, 0, 0); PG8_LDB(B1, 0, 1); PG8_SCHED; PG8_LDA(At, 0, 0); PG8_STAGE(PG8_SA(1, 1), a1 + hstepA, voffA);
;     ...
;             PG8_LDA(At, 1, 1); PG8_STAGE(PG8_SB(1, 0), b3, voffB); PG8_STAGE(PG8_SB(1, 1), b3 + hstepB, voffB); PG8_STAGE(PG8_SA(1, 0), a3, voffA);
;             PG8_WAIT_V(8); PG8_WAIT_L(0); PG8_BAR; PG8_MMA(1, 0, At, B0); PG8_MMA(1, 1, At, B1); PG8_BAR; PG8_SCHED;
	s_mov_b32 m0, s96
	v_lshl_add_u64 v[162:163], v[162:163], 0, s[18:19]
	ds_read_b128 v[182:185], v168 offset:49152
	ds_read_b128 v[186:189], v168 offset:50176
	ds_read_b128 v[190:193], v168 offset:51200
	ds_read_b128 v[194:197], v168 offset:52224
	ds_read_b128 v[198:201], v168 offset:53248
	ds_read_b128 v[202:205], v168 offset:54272
	ds_read_b128 v[206:209], v168 offset:55296
	ds_read_b128 v[210:213], v168 offset:56320
	global_load_lds_dwordx4 v[162:163], off
	v_lshl_add_u64 v[162:163], v[214:215], 0, s[18:19]
	s_mov_b32 m0, s39
	s_nop 0
	global_load_lds_dwordx4 v[162:163], off
	v_lshl_add_u64 v[162:163], s[54:55], 0, v[134:135]
	s_mov_b32 m0, s95
	s_nop 0
	global_load_lds_dwordx4 v[162:163], off
	v_lshl_add_u64 v[162:163], s[54:55], 0, v[130:131]
	s_mov_b32 m0, s38
	s_nop 0
	global_load_lds_dwordx4 v[162:163], off
	v_lshl_add_u64 v[162:163], v[216:217], 0, s[18:19]
	s_mov_b32 m0, s84
	s_nop 0
	global_load_lds_dwordx4 v[162:163], off
	v_lshl_add_u64 v[162:163], v[218:219], 0, s[18:19]
	s_mov_b32 m0, s85
	s_nop 0
	global_load_lds_dwordx4 v[162:163], off
	s_waitcnt vmcnt(8)
	s_waitcnt lgkmcnt(0)
	s_barrier
	s_setprio 0
	v_mfma_f32_16x16x32_bf16 v[62:65], v[142:145], v[182:185], v[62:65]
	v_mfma_f32_16x16x32_bf16 v[58:61], v[150:153], v[182:185], v[58:61]
	v_mfma_f32_16x16x32_bf16 v[46:49], v[142:145], v[190:193], v[46:49]
	v_mfma_f32_16x16x32_bf16 v[42:45], v[150:153], v[190:193], v[42:45]
	v_mfma_f32_16x16x32_bf16 v[30:33], v[142:145], v[198:201], v[30:33]
	v_mfma_f32_16x16x32_bf16 v[26:29], v[150:153], v[198:201], v[26:29]
	v_mfma_f32_16x16x32_bf16 v[14:17], v[142:145], v[206:209], v[14:17]
	v_mfma_f32_16x16x32_bf16 v[10:13], v[150:153], v[206:209], v[10:13]
	v_mfma_f32_16x16x32_bf16 v[62:65], v[146:149], v[186:189], v[62:65]
	v_mfma_f32_16x16x32_bf16 v[58:61], v[154:157], v[186:189], v[58:61]
	v_mfma_f32_16x16x32_bf16 v[46:49], v[146:149], v[194:197], v[46:49]
	v_mfma_f32_16x16x32_bf16 v[42:45], v[154:157], v[194:197], v[42:45]
	v_mfma_f32_16x16x32_bf16 v[30:33], v[146:149], v[202:205], v[30:33]
	v_mfma_f32_16x16x32_bf16 v[26:29], v[154:157], v[202:205], v[26:29]
	v_mfma_f32_16x16x32_bf16 v[14:17], v[146:149], v[210:213], v[14:17]
	v_mfma_f32_16x16x32_bf16 v[10:13], v[154:157], v[210:213], v[10:13]
	s_setprio 2
	s_setprio 0
	v_mfma_f32_16x16x32_bf16 v[54:57], v[158:161], v[182:185], v[54:57]
	v_mfma_f32_16x16x32_bf16 v[50:53], v[174:177], v[182:185], v[50:53]
	v_mfma_f32_16x16x32_bf16 v[38:41], v[158:161], v[190:193], v[38:41]
	v_mfma_f32_16x16x32_bf16 v[34:37], v[174:177], v[190:193], v[34:37]
	v_mfma_f32_16x16x32_bf16 v[22:25], v[158:161], v[198:201], v[22:25]
	v_mfma_f32_16x16x32_bf16 v[18:21], v[174:177], v[198:201], v[18:21]
	v_mfma_f32_16x16x32_bf16 v[6:9], v[158:161], v[206:209], v[6:9]
	v_mfma_f32_16x16x32_bf16 v[2:5], v[174:177], v[206:209], v[2:5]
	v_mfma_f32_16x16x32_bf16 v[54:57], v[170:173], v[186:189], v[54:57]
	v_mfma_f32_16x16x32_bf16 v[50:53], v[178:181], v[186:189], v[50:53]
	v_mfma_f32_16x16x32_bf16 v[38:41], v[170:173], v[194:197], v[38:41]
	v_mfma_f32_16x16x32_bf16 v[34:37], v[178:181], v[194:197], v[34:37]
	v_mfma_f32_16x16x32_bf16 v[22:25], v[170:173], v[202:205], v[22:25]
	v_mfma_f32_16x16x32_bf16 v[18:21], v[178:181], v[202:205], v[18:21]
	v_mfma_f32_16x16x32_bf16 v[6:9], v[170:173], v[210:213], v[6:9]
	v_mfma_f32_16x16x32_bf16 v[2:5], v[178:181], v[210:213], v[2:5]
	s_setprio 2
	s_barrier
	s_movk_i32 s38, 0x100
	s_andn2_b64 vcc, exec, s[4:5]
	s_mov_b64 s[54:55], -1
	s_mov_b64 s[4:5], 0
	s_cbranch_vccz .LBB0_594
.LBB0_594:
	s_add_u32 s33, s8, s38
	s_addc_u32 s62, s9, 0
	s_add_u32 s39, s33, 0x100
	s_addc_u32 s58, s62, 0
	s_and_b64 s[56:57], s[54:55], exec
	s_cselect_b32 s59, s45, s58
	s_cselect_b32 s58, s44, s39
	s_add_u32 s38, s6, s38
	s_addc_u32 s39, s7, 0
	s_add_u32 s56, s38, 0x100
	s_addc_u32 s57, s39, 0
	s_and_b64 s[38:39], s[54:55], exec
	s_cselect_b32 s61, s47, s57
	s_cselect_b32 s60, s46, s56
	s_add_u32 s68, s33, 0xb0080
	s_addc_u32 s69, s62, 0
	s_add_i32 s63, s86, s23
	ds_read_b128 v[142:145], v166
	ds_read_b128 v[146:149], v166 offset:1024
	ds_read_b128 v[150:153], v166 offset:2048
	ds_read_b128 v[154:157], v166 offset:3072
	ds_read_b128 v[158:161], v167
	ds_read_b128 v[170:173], v167 offset:1024
	ds_read_b128 v[174:177], v167 offset:2048
	ds_read_b128 v[178:181], v167 offset:3072
	s_add_i32 m0, s72, 0xc000
	s_add_i32 s64, s72, 0xe000
	s_add_i32 s74, s63, 0x2000
	s_add_u32 s66, s60, 0xb0000
	s_addc_u32 s67, s61, 0
	s_add_i32 s62, s87, s23
	s_add_i32 s75, s62, 0x2000
	s_add_i32 s97, 0, 0x18000
	s_add_i32 s33, 0, 0x1c000
	s_add_u32 s56, s58, 0xb0000
	s_addc_u32 s57, s59, 0
	s_add_i32 s96, s97, s23
	s_add_i32 s39, s96, 0x2000
	s_add_u32 s54, s60, 0xb0080
	s_addc_u32 s55, s61, 0
	s_add_i32 s95, s33, s23
	s_add_i32 s38, s95, 0x2000
	v_lshl_add_u64 v[162:163], s[68:69], 0, v[136:137]
	ds_read_b128 v[182:185], v168
	ds_read_b128 v[186:189], v168 offset:1024
	ds_read_b128 v[190:193], v168 offset:2048
	ds_read_b128 v[194:197], v168 offset:3072
	ds_read_b128 v[198:201], v168 offset:4096
	ds_read_b128 v[202:205], v168 offset:5120
	ds_read_b128 v[206:209], v168 offset:6144
	ds_read_b128 v[210:213], v168 offset:7168
	global_load_lds_dwordx4 v[162:163], off
	v_lshl_add_u64 v[162:163], s[68:69], 0, v[132:133]
	s_mov_b32 m0, s64
	s_nop 0
	global_load_lds_dwordx4 v[162:163], off
	s_waitcnt vmcnt(8)
	s_waitcnt lgkmcnt(0)
	s_barrier
; #define PG8_STAGE(bufoff, gbase, voff) do { _Pragma("unroll") for (int _i = 0; _i < 2; ++_i) \
;         __builtin_amdgcn_global_load_lds((const unsigned*)((const char*)(gbase) + (voff)[_i]), (LAS unsigned*)(lds + (bufoff) + ldsw + _i * 8192), 16, 0, 0); } while (0)
; #define PG8_LDA(dst, b, h) do { _Pragma("unroll") for (int m = 0; m < 4; ++m) _Pragma("unroll") for (int k = 0; k < 2; ++k) dst[m][k] = *(const LAS bf16x8*)(lds + PG8_SA(b, h) + aoff + m * 2048 + k * 1024); } while (0)
; #define PG8_MMA(ai, bj, At, Bt) do { __builtin_amdgcn_s_setprio(1); _Pragma("unroll") for (int m = 0; m < 4; ++m) _Pragma("unroll") for (int n = 0; n < 2; ++n) _Pragma("unroll") for (int k = 0; k < 2; ++k) \
;         acc[ai][bj][m][n] = __builtin_amdgcn_mfma_f32_16x16x32_bf16(Bt[n][k], At[m][k], acc[ai][bj][m][n], 0, 0, 0); __builtin_amdgcn_s_setprio(0); } while (0)
; #define PG8_WAIT_V(n) asm volatile("s_waitcnt vmcnt(" #n ")" ::: "memory")
; #define PG8_WAIT_L(n) asm volatile("s_waitcnt lgkmcnt(" #n ")" ::: "memory")
; #define PG8_BAR __builtin_amdgcn_s_barrier()
; #define PG8_SCHED __builtin_amdgcn_sched_barrier(0)
; template <class Epi>
; __device__ __forceinline__ void gemm_phase(LAS unsigned char* lds, const Gemm g, int G, int c, const Epi& E) {
;     ...
;             PG8_WAIT_V(8); PG8_WAIT_L(0); PG8_BAR; PG8_MMA(0, 0, At, B0); PG8_MMA(0, 1, At, B1); PG8_BAR; PG8_SCHED;
;             PG8_LDA(At, 0, 1); PG8_STAGE(PG8_SB(0, 0), b2, voffB); PG8_STAGE(PG8_SB(0, 1), b2 + hstepB, voffB); PG8_STAGE(PG8_SA(0, 0), a2, voffA);
;             PG8_WAIT_V(8); PG8_WAIT_L(0); PG8_BAR; PG8_MMA(1, 0, At, B0); PG8_MMA(1, 1, At, B1); PG8_BAR; PG8_SCHED;
	s_setprio 0
	v_mfma_f32_16x16x32_bf16 v[126:129], v[142:145], v[182:185], v[126:129]
	v_mfma_f32_16x16x32_bf16 v[122:125], v[150:153], v[182:185], v[122:125]
	v_mfma_f32_16x16x32_bf16 v[110:113], v[142:145], v[190:193], v[110:113]
	v_mfma_f32_16x16x32_bf16 v[106:109], v[150:153], v[190:193], v[106:109]
	v_mfma_f32_16x16x32_bf16 v[94:97], v[142:145], v[198:201], v[94:97]
	v_mfma_f32_16x16x32_bf16 v[90:93], v[150:153], v[198:201], v[90:93]
	v_mfma_f32_16x16x32_bf16 v[78:81], v[142:145], v[206:209], v[78:81]
	v_mfma_f32_16x16x32_bf16 v[74:77], v[150:153], v[206:209], v[74:77]
	v_mfma_f32_16x16x32_bf16 v[126:129], v[146:149], v[186:189], v[126:129]
	v_mfma_f32_16x16x32_bf16 v[122:125], v[154:157], v[186:189], v[122:125]
	v_mfma_f32_16x16x32_bf16 v[110:113], v[146:149], v[194:197], v[110:113]
	v_mfma_f32_16x16x32_bf16 v[106:109], v[154:157], v[194:197], v[106:109]
	v_mfma_f32_16x16x32_bf16 v[94:97], v[146:149], v[202:205], v[94:97]
	v_mfma_f32_16x16x32_bf16 v[90:93], v[154:157], v[202:205], v[90:93]
	v_mfma_f32_16x16x32_bf16 v[78:81], v[146:149], v[210:213], v[78:81]
	v_mfma_f32_16x16x32_bf16 v[74:77], v[154:157], v[210:213], v[74:77]
	s_setprio 2
	s_setprio 0
	v_mfma_f32_16x16x32_bf16 v[118:121], v[158:161], v[182:185], v[118:121]
	v_mfma_f32_16x16x32_bf16 v[114:117], v[174:177], v[182:185], v[114:117]
	v_mfma_f32_16x16x32_bf16 v[102:105], v[158:161], v[190:193], v[102:105]
	v_mfma_f32_16x16x32_bf16 v[98:101], v[174:177], v[190:193], v[98:101]
	v_mfma_f32_16x16x32_bf16 v[86:89], v[158:161], v[198:201], v[86:89]
	v_mfma_f32_16x16x32_bf16 v[82:85], v[174:177], v[198:201], v[82:85]
	v_mfma_f32_16x16x32_bf16 v[70:73], v[158:161], v[206:209], v[70:73]
	v_mfma_f32_16x16x32_bf16 v[66:69], v[174:177], v[206:209], v[66:69]
	v_mfma_f32_16x16x32_bf16 v[118:121], v[170:173], v[186:189], v[118:121]
	v_mfma_f32_16x16x32_bf16 v[114:117], v[178:181], v[186:189], v[114:117]
	v_mfma_f32_16x16x32_bf16 v[102:105], v[170:173], v[194:197], v[102:105]
	v_mfma_f32_16x16x32_bf16 v[98:101], v[178:181], v[194:197], v[98:101]
	v_mfma_f32_16x16x32_bf16 v[86:89], v[170:173], v[202:205], v[86:89]
	v_mfma_f32_16x16x32_bf16 v[82:85], v[178:181], v[202:205], v[82:85]
	v_mfma_f32_16x16x32_bf16 v[70:73], v[170:173], v[210:213], v[70:73]
	v_mfma_f32_16x16x32_bf16 v[66:69], v[178:181], v[210:213], v[66:69]
	s_setprio 2
	s_barrier
	s_mov_b32 m0, s63
	v_lshl_add_u64 v[162:163], s[60:61], 0, v[134:135]
	ds_read_b128 v[182:185], v168 offset:16384
	ds_read_b128 v[186:189], v168 offset:17408
	ds_read_b128 v[190:193], v168 offset:18432
	ds_read_b128 v[194:197], v168 offset:19456
	ds_read_b128 v[198:201], v168 offset:20480
	ds_read_b128 v[202:205], v168 offset:21504
	ds_read_b128 v[206:209], v168 offset:22528
	ds_read_b128 v[210:213], v168 offset:23552
	global_load_lds_dwordx4 v[162:163], off
	v_lshl_add_u64 v[214:215], s[60:61], 0, v[130:131]
	s_mov_b32 m0, s74
	v_lshl_add_u64 v[216:217], s[66:67], 0, v[134:135]
	global_load_lds_dwordx4 v[214:215], off
	s_mov_b32 m0, s62
	v_lshl_add_u64 v[218:219], s[58:59], 0, v[132:133]
	global_load_lds_dwordx4 v[216:217], off
	v_lshl_add_u64 v[216:217], s[66:67], 0, v[130:131]
	s_mov_b32 m0, s75
	s_nop 0
	global_load_lds_dwordx4 v[216:217], off
	v_lshl_add_u64 v[216:217], s[58:59], 0, v[136:137]
	s_mov_b32 m0, s72
	s_nop 0
	global_load_lds_dwordx4 v[216:217], off
	s_mov_b32 m0, s73
	s_nop 0
	global_load_lds_dwordx4 v[218:219], off
	s_waitcnt vmcnt(8)
	s_waitcnt lgkmcnt(0)
	s_barrier
	s_setprio 0
	v_mfma_f32_16x16x32_bf16 v[62:65], v[142:145], v[182:185], v[62:65]
	v_mfma_f32_16x16x32_bf16 v[58:61], v[150:153], v[182:185], v[58:61]
	v_mfma_f32_16x16x32_bf16 v[46:49], v[142:145], v[190:193], v[46:49]
	v_mfma_f32_16x16x32_bf16 v[42:45], v[150:153], v[190:193], v[42:45]
	v_mfma_f32_16x16x32_bf16 v[30:33], v[142:145], v[198:201], v[30:33]
	v_mfma_f32_16x16x32_bf16 v[26:29], v[150:153], v[198:201], v[26:29]
	v_mfma_f32_16x16x32_bf16 v[14:17], v[142:145], v[206:209], v[14:17]
	v_mfma_f32_16x16x32_bf16 v[10:13], v[150:153], v[206:209], v[10:13]
	v_mfma_f32_16x16x32_bf16 v[62:65], v[146:149], v[186:189], v[62:65]
	v_mfma_f32_16x16x32_bf16 v[58:61], v[154:157], v[186:189], v[58:61]
	v_mfma_f32_16x16x32_bf16 v[46:49], v[146:149], v[194:197], v[46:49]
	v_mfma_f32_16x16x32_bf16 v[42:45], v[154:157], v[194:197], v[42:45]
	v_mfma_f32_16x16x32_bf16 v[30:33], v[146:149], v[202:205], v[30:33]
	v_mfma_f32_16x16x32_bf16 v[26:29], v[154:157], v[202:205], v[26:29]
	v_mfma_f32_16x16x32_bf16 v[14:17], v[146:149], v[210:213], v[14:17]
	v_mfma_f32_16x16x32_bf16 v[10:13], v[154:157], v[210:213], v[10:13]
	s_setprio 2
	s_setprio 0
	v_mfma_f32_16x16x32_bf16 v[54:57], v[158:161], v[182:185], v[54:57]
	v_mfma_f32_16x16x32_bf16 v[50:53], v[174:177], v[182:185], v[50:53]
	v_mfma_f32_16x16x32_bf16 v[38:41], v[158:161], v[190:193], v[38:41]
	v_mfma_f32_16x16x32_bf16 v[34:37], v[174:177], v[190:193], v[34:37]
	v_mfma_f32_16x16x32_bf16 v[22:25], v[158:161], v[198:201], v[22:25]
	v_mfma_f32_16x16x32_bf16 v[18:21], v[174:177], v[198:201], v[18:21]
	v_mfma_f32_16x16x32_bf16 v[6:9], v[158:161], v[206:209], v[6:9]
	v_mfma_f32_16x16x32_bf16 v[2:5], v[174:177], v[206:209], v[2:5]
	v_mfma_f32_16x16x32_bf16 v[54:57], v[170:173], v[186:189], v[54:57]
	v_mfma_f32_16x16x32_bf16 v[50:53], v[178:181], v[186:189], v[50:53]
	v_mfma_f32_16x16x32_bf16 v[38:41], v[170:173], v[194:197], v[38:41]
	v_mfma_f32_16x16x32_bf16 v[34:37], v[178:181], v[194:197], v[34:37]
	v_mfma_f32_16x16x32_bf16 v[22:25], v[170:173], v[202:205], v[22:25]
	v_mfma_f32_16x16x32_bf16 v[18:21], v[178:181], v[202:205], v[18:21]
	v_mfma_f32_16x16x32_bf16 v[6:9], v[170:173], v[210:213], v[6:9]
	v_mfma_f32_16x16x32_bf16 v[2:5], v[178:181], v[210:213], v[2:5]
	s_setprio 2
	s_barrier
; #define PG8_STAGE(bufoff, gbase, voff) do { _Pragma("unroll") for (int _i = 0; _i < 2; ++_i) \
;         __builtin_amdgcn_global_load_lds((const unsigned*)((const char*)(gbase) + (voff)[_i]), (LAS unsigned*)(lds + (bufoff) + ldsw + _i * 8192), 16, 0, 0); } while (0)
; #define PG8_LDA(dst, b, h) do { _Pragma("unroll") for (int m = 0; m < 4; ++m) _Pragma("unroll") for (int k = 0; k < 2; ++k) dst[m][k] = *(const LAS bf16x8*)(lds + PG8_SA(b, h) + aoff + m * 2048 + k * 1024); } while (0)
; #define PG8_LDB(dst, b, h) do { _Pragma("unroll") for (int n = 0; n < 2; ++n) _Pragma("unroll") for (int k = 0; k < 2; ++k) dst[n][k] = *(const LAS bf16x8*)(lds + PG8_SB(b, h) + boff + n * 2048 + k * 1024); } while (0)
; #define PG8_MMA(ai, bj, At, Bt) do { __builtin_amdgcn_s_setprio(1); _Pragma("unroll") for (int m = 0; m < 4; ++m) _Pragma("unroll") for (int n = 0; n < 2; ++n) _Pragma("unroll") for (int k = 0; k < 2; ++k) \
;         acc[ai][bj][m][n] = __builtin_amdgcn_mfma_f32_16x16x32_bf16(Bt[n][k], At[m][k], acc[ai][bj][m][n], 0, 0, 0); __builtin_amdgcn_s_setprio(0); } while (0)
; #define PG8_WAIT_V(n) asm volatile("s_waitcnt vmcnt(" #n ")" ::: "memory")
; #define PG8_WAIT_L(n) asm volatile("s_waitcnt lgkmcnt(" #n ")" ::: "memory")
; #define PG8_BAR __builtin_amdgcn_s_barrier()
; #define PG8_SCHED __builtin_amdgcn_sched_barrier(0)
; template <class Epi>
; __device__ __forceinline__ void gemm_phase(LAS unsigned char* lds, const Gemm g, int G, int c, const Epi& E) {
;     ...
;             PG8_LDB(B0, 1, 0); PG8_LDB(B1, 1, 1); PG8_SCHED; PG8_LDA(At, 1, 0); PG8_STAGE(PG8_SA(0, 1), a2 + hstepA, voffA);
;             PG8_WAIT_V(8); PG8_WAIT_L(0); PG8_BAR; PG8_MMA(0, 0, At, B0); PG8_MMA(0, 1, At, B1); PG8_BAR; PG8_SCHED;
;             PG8_LDA(At, 1, 1); PG8_STAGE(PG8_SB(1, 0), b3, voffB); PG8_STAGE(PG8_SB(1, 1), b3 + hstepB, voffB); PG8_STAGE(PG8_SA(1, 0), a3, voffA);
;             PG8_WAIT_V(8); PG8_WAIT_L(0); PG8_BAR; PG8_MMA(1, 0, At, B0); PG8_MMA(1, 1, At, B1); PG8_BAR; PG8_SCHED;
;         }
;         if (wr == 0) PG8_BAR;
	v_add_u32_e32 v154, s97, v165
	v_add_u32_e32 v178, s33, v165
	ds_read_b128 v[142:145], v154
	ds_read_b128 v[146:149], v154 offset:1024
	ds_read_b128 v[150:153], v154 offset:2048
	ds_read_b128 v[154:157], v154 offset:3072
	ds_read_b128 v[158:161], v178
	ds_read_b128 v[170:173], v178 offset:1024
	ds_read_b128 v[174:177], v178 offset:2048
	ds_read_b128 v[178:181], v178 offset:3072
	s_mov_b32 m0, s78
	v_lshl_add_u64 v[220:221], s[56:57], 0, v[136:137]
	ds_read_b128 v[182:185], v168 offset:32768
	ds_read_b128 v[186:189], v168 offset:33792
	ds_read_b128 v[190:193], v168 offset:34816
	ds_read_b128 v[194:197], v168 offset:35840
	ds_read_b128 v[198:201], v168 offset:36864
	ds_read_b128 v[202:205], v168 offset:37888
	ds_read_b128 v[206:209], v168 offset:38912
	ds_read_b128 v[210:213], v168 offset:39936
	global_load_lds_dwordx4 v[220:221], off
	v_lshl_add_u64 v[220:221], s[56:57], 0, v[132:133]
	s_mov_b32 m0, s81
	s_nop 0
	global_load_lds_dwordx4 v[220:221], off
	s_waitcnt vmcnt(8)
	s_waitcnt lgkmcnt(0)
	s_barrier
	s_setprio 0
	v_mfma_f32_16x16x32_bf16 v[126:129], v[142:145], v[182:185], v[126:129]
	v_mfma_f32_16x16x32_bf16 v[122:125], v[150:153], v[182:185], v[122:125]
	v_mfma_f32_16x16x32_bf16 v[110:113], v[142:145], v[190:193], v[110:113]
	v_mfma_f32_16x16x32_bf16 v[106:109], v[150:153], v[190:193], v[106:109]
	v_mfma_f32_16x16x32_bf16 v[94:97], v[142:145], v[198:201], v[94:97]
	v_mfma_f32_16x16x32_bf16 v[90:93], v[150:153], v[198:201], v[90:93]
	v_mfma_f32_16x16x32_bf16 v[78:81], v[142:145], v[206:209], v[78:81]
	v_mfma_f32_16x16x32_bf16 v[74:77], v[150:153], v[206:209], v[74:77]
	v_mfma_f32_16x16x32_bf16 v[126:129], v[146:149], v[186:189], v[126:129]
	v_mfma_f32_16x16x32_bf16 v[122:125], v[154:157], v[186:189], v[122:125]
	v_mfma_f32_16x16x32_bf16 v[110:113], v[146:149], v[194:197], v[110:113]
	v_mfma_f32_16x16x32_bf16 v[106:109], v[154:157], v[194:197], v[106:109]
	v_mfma_f32_16x16x32_bf16 v[94:97], v[146:149], v[202:205], v[94:97]
	v_mfma_f32_16x16x32_bf16 v[90:93], v[154:157], v[202:205], v[90:93]
	v_mfma_f32_16x16x32_bf16 v[78:81], v[146:149], v[210:213], v[78:81]
	v_mfma_f32_16x16x32_bf16 v[74:77], v[154:157], v[210:213], v[74:77]
	s_setprio 2
	s_setprio 0
	v_mfma_f32_16x16x32_bf16 v[118:121], v[158:161], v[182:185], v[118:121]
	v_mfma_f32_16x16x32_bf16 v[114:117], v[174:177], v[182:185], v[114:117]
	v_mfma_f32_16x16x32_bf16 v[102:105], v[158:161], v[190:193], v[102:105]
	v_mfma_f32_16x16x32_bf16 v[98:101], v[174:177], v[190:193], v[98:101]
	v_mfma_f32_16x16x32_bf16 v[86:89], v[158:161], v[198:201], v[86:89]
	v_mfma_f32_16x16x32_bf16 v[82:85], v[174:177], v[198:201], v[82:85]
	v_mfma_f32_16x16x32_bf16 v[70:73], v[158:161], v[206:209], v[70:73]
	v_mfma_f32_16x16x32_bf16 v[66:69], v[174:177], v[206:209], v[66:69]
	v_mfma_f32_16x16x32_bf16 v[118:121], v[170:173], v[186:189], v[118:121]
	v_mfma_f32_16x16x32_bf16 v[114:117], v[178:181], v[186:189], v[114:117]
	v_mfma_f32_16x16x32_bf16 v[102:105], v[170:173], v[194:197], v[102:105]
	v_mfma_f32_16x16x32_bf16 v[98:101], v[178:181], v[194:197], v[98:101]
	v_mfma_f32_16x16x32_bf16 v[86:89], v[170:173], v[202:205], v[86:89]
	v_mfma_f32_16x16x32_bf16 v[82:85], v[178:181], v[202:205], v[82:85]
	v_mfma_f32_16x16x32_bf16 v[70:73], v[170:173], v[210:213], v[70:73]
	v_mfma_f32_16x16x32_bf16 v[66:69], v[178:181], v[210:213], v[66:69]
	s_setprio 2
	s_barrier
	s_mov_b32 m0, s96
	v_lshl_add_u64 v[162:163], v[162:163], 0, s[18:19]
	ds_read_b128 v[182:185], v168 offset:49152
	ds_read_b128 v[186:189], v168 offset:50176
	ds_read_b128 v[190:193], v168 offset:51200
	ds_read_b128 v[194:197], v168 offset:52224
	ds_read_b128 v[198:201], v168 offset:53248
	ds_read_b128 v[202:205], v168 offset:54272
	ds_read_b128 v[206:209], v168 offset:55296
	ds_read_b128 v[210:213], v168 offset:56320
	global_load_lds_dwordx4 v[162:163], off
	v_lshl_add_u64 v[162:163], v[214:215], 0, s[18:19]
	s_mov_b32 m0, s39
	s_nop 0
	global_load_lds_dwordx4 v[162:163], off
	v_lshl_add_u64 v[162:163], s[54:55], 0, v[134:135]
	s_mov_b32 m0, s95
	s_nop 0
	global_load_lds_dwordx4 v[162:163], off
	v_lshl_add_u64 v[162:163], s[54:55], 0, v[130:131]
	s_mov_b32 m0, s38
	s_nop 0
	global_load_lds_dwordx4 v[162:163], off
	v_lshl_add_u64 v[162:163], v[216:217], 0, s[18:19]
	s_mov_b32 m0, s84
	s_nop 0
	global_load_lds_dwordx4 v[162:163], off
	v_lshl_add_u64 v[162:163], v[218:219], 0, s[18:19]
	s_mov_b32 m0, s85
	s_nop 0
	global_load_lds_dwordx4 v[162:163], off
	s_waitcnt vmcnt(8)
	s_waitcnt lgkmcnt(0)
	s_barrier
	s_setprio 0
	v_mfma_f32_16x16x32_bf16 v[62:65], v[142:145], v[182:185], v[62:65]
	v_mfma_f32_16x16x32_bf16 v[58:61], v[150:153], v[182:185], v[58:61]
	v_mfma_f32_16x16x32_bf16 v[46:49], v[142:145], v[190:193], v[46:49]
	v_mfma_f32_16x16x32_bf16 v[42:45], v[150:153], v[190:193], v[42:45]
	v_mfma_f32_16x16x32_bf16 v[30:33], v[142:145], v[198:201], v[30:33]
	v_mfma_f32_16x16x32_bf16 v[26:29], v[150:153], v[198:201], v[26:29]
	v_mfma_f32_16x16x32_bf16 v[14:17], v[142:145], v[206:209], v[14:17]
	v_mfma_f32_16x16x32_bf16 v[10:13], v[150:153], v[206:209], v[10:13]
	v_mfma_f32_16x16x32_bf16 v[62:65], v[146:149], v[186:189], v[62:65]
	v_mfma_f32_16x16x32_bf16 v[58:61], v[154:157], v[186:189], v[58:61]
	v_mfma_f32_16x16x32_bf16 v[46:49], v[146:149], v[194:197], v[46:49]
	v_mfma_f32_16x16x32_bf16 v[42:45], v[154:157], v[194:197], v[42:45]
	v_mfma_f32_16x16x32_bf16 v[30:33], v[146:149], v[202:205], v[30:33]
	v_mfma_f32_16x16x32_bf16 v[26:29], v[154:157], v[202:205], v[26:29]
	v_mfma_f32_16x16x32_bf16 v[14:17], v[146:149], v[210:213], v[14:17]
	v_mfma_f32_16x16x32_bf16 v[10:13], v[154:157], v[210:213], v[10:13]
	s_setprio 2
	s_setprio 0
	v_mfma_f32_16x16x32_bf16 v[54:57], v[158:161], v[182:185], v[54:57]
	v_mfma_f32_16x16x32_bf16 v[50:53], v[174:177], v[182:185], v[50:53]
	v_mfma_f32_16x16x32_bf16 v[38:41], v[158:161], v[190:193], v[38:41]
	v_mfma_f32_16x16x32_bf16 v[34:37], v[174:177], v[190:193], v[34:37]
	v_mfma_f32_16x16x32_bf16 v[22:25], v[158:161], v[198:201], v[22:25]
	v_mfma_f32_16x16x32_bf16 v[18:21], v[174:177], v[198:201], v[18:21]
	v_mfma_f32_16x16x32_bf16 v[6:9], v[158:161], v[206:209], v[6:9]
	v_mfma_f32_16x16x32_bf16 v[2:5], v[174:177], v[206:209], v[2:5]
	v_mfma_f32_16x16x32_bf16 v[54:57], v[170:173], v[186:189], v[54:57]
	v_mfma_f32_16x16x32_bf16 v[50:53], v[178:181], v[186:189], v[50:53]
	v_mfma_f32_16x16x32_bf16 v[38:41], v[170:173], v[194:197], v[38:41]
	v_mfma_f32_16x16x32_bf16 v[34:37], v[178:181], v[194:197], v[34:37]
	v_mfma_f32_16x16x32_bf16 v[22:25], v[170:173], v[202:205], v[22:25]
	v_mfma_f32_16x16x32_bf16 v[18:21], v[178:181], v[202:205], v[18:21]
	v_mfma_f32_16x16x32_bf16 v[6:9], v[170:173], v[210:213], v[6:9]
	v_mfma_f32_16x16x32_bf16 v[2:5], v[178:181], v[210:213], v[2:5]
	s_setprio 2
	s_barrier
	s_movk_i32 s38, 0x100
	s_andn2_b64 vcc, exec, s[4:5]
	s_mov_b64 s[54:55], -1
	s_mov_b64 s[4:5], 0
	s_cbranch_vccz .LBB0_594
	s_and_b64 vcc, exec, s[20:21]
	s_cbranch_vccz .LBB0_597
	s_barrier

; #define PG8_STAGE(bufoff, gbase, voff) do { _Pragma("unroll") for (int _i = 0; _i < 2; ++_i) \
;         __builtin_amdgcn_global_load_lds((const unsigned*)((const char*)(gbase) + (voff)[_i]), (LAS unsigned*)(lds + (bufoff) + ldsw + _i * 8192), 16, 0, 0); } while (0)
; #define PG8_LDA(dst, b, h) do { _Pragma("unroll") for (int m = 0; m < 4; ++m) _Pragma("unroll") for (int k = 0; k < 2; ++k) dst[m][k] = *(const LAS bf16x8*)(lds + PG8_SA(b, h) + aoff + m * 2048 + k * 1024); } while (0)
; #define PG8_LDB(dst, b, h) do { _Pragma("unroll") for (int n = 0; n < 2; ++n) _Pragma("unroll") for (int k = 0; k < 2; ++k) dst[n][k] = *(const LAS bf16x8*)(lds + PG8_SB(b, h) + boff + n * 2048 + k * 1024); } while (0)
; #define PG8_MMA(ai, bj, At, Bt) do { __builtin_amdgcn_s_setprio(1); _Pragma("unroll") for (int m = 0; m < 4; ++m) _Pragma("unroll") for (int n = 0; n < 2; ++n) _Pragma("unroll") for (int k = 0; k < 2; ++k) \
;         acc[ai][bj][m][n] = __builtin_amdgcn_mfma_f32_16x16x32_bf16(Bt[n][k], At[m][k], acc[ai][bj][m][n], 0, 0, 0); __builtin_amdgcn_s_setprio(0); } while (0)
; #define PG8_WAIT_V(n) asm volatile("s_waitcnt vmcnt(" #n ")" ::: "memory")
; #define PG8_WAIT_L(n) asm volatile("s_waitcnt lgkmcnt(" #n ")" ::: "memory")
; #define PG8_BAR __builtin_amdgcn_s_barrier()
; #define PG8_SCHED __builtin_amdgcn_sched_barrier(0)
; template <class Epi>
; __device__ __forceinline__ void gemm_phase(LAS unsigned char* lds, const Gemm g, int G, int c, const Epi& E) {
;     ...
;             const bool last = (t == nt - 2);
;             const char* a1 = cA + (size_t)(t + 1) * kstep;
;             const char* a2 = last ? nA : cA + (size_t)(t + 2) * kstep; const char* b2 = last ? nB : cB + (size_t)(t + 2) * kstep;
;             const char* a3 = a2 + kstep; const char* b3 = b2 + kstep;
;             PG8_LDB(B0, 0, 0); PG8_LDB(B1, 0, 1); PG8_SCHED; PG8_LDA(At, 0, 0); PG8_STAGE(PG8_SA(1, 1), a1 + hstepA, voffA);
;             PG8_WAIT_V(8); PG8_WAIT_L(0); PG8_BAR; PG8_MMA(0, 0, At, B0); PG8_MMA(0, 1, At, B1); PG8_BAR; PG8_SCHED;
;             PG8_LDA(At, 0, 1); PG8_STAGE(PG8_SB(0, 0), b2, voffB); PG8_STAGE(PG8_SB(0, 1), b2 + hstepB, voffB); PG8_STAGE(PG8_SA(0, 0), a2, voffA);
;             PG8_WAIT_V(8); PG8_WAIT_L(0); PG8_BAR; PG8_MMA(1, 0, At, B0); PG8_MMA(1, 1, At, B1); PG8_BAR; PG8_SCHED;
.LBB0_764:
	s_ashr_i32 s15, s14, 31
	s_lshl_b64 s[18:19], s[14:15], 21
	s_add_u32 s18, s57, s18
	s_addc_u32 s19, s58, s19
	s_and_b64 s[24:25], s[2:3], exec
	s_cselect_b32 s15, s19, s45
	s_cselect_b32 s78, s18, s44
	s_ashr_i32 s11, s10, 31
	s_lshl_b64 s[24:25], s[10:11], 21
	s_add_u32 s11, s59, s24
	s_addc_u32 s33, s60, s25
	s_ashr_i32 s13, s12, 31
	s_lshl_b64 s[24:25], s[12:13], 21
	s_add_u32 s24, s11, s24
	s_addc_u32 s25, s33, s25
	s_and_b64 s[52:53], s[2:3], exec
	s_cselect_b32 s11, s25, s47
	s_cselect_b32 s13, s24, s46
	s_add_u32 s44, s44, 0x100080
	s_addc_u32 s45, s45, 0
	s_add_u32 s81, s46, 0x100
	s_addc_u32 s82, s47, 0
	s_mov_b32 s83, -2
	ds_read_b128 v[146:149], v152
	ds_read_b128 v[156:159], v152 offset:1024
	ds_read_b128 v[160:163], v152 offset:2048
	ds_read_b128 v[164:167], v152 offset:3072
	ds_read_b128 v[168:171], v153
	ds_read_b128 v[172:175], v153 offset:1024
	ds_read_b128 v[176:179], v153 offset:2048
	ds_read_b128 v[180:183], v153 offset:3072
	s_add_u32 s33, s44, 0xfff00080
	s_addc_u32 s46, s45, -1
	s_cmp_eq_u32 s83, 60
	s_cselect_b32 s53, s15, s46
	s_cselect_b32 s52, s78, s33
	s_cselect_b32 s47, s11, s82
	s_cselect_b32 s46, s13, s81
	v_lshl_add_u64 v[216:217], s[44:45], 0, v[138:139]
	s_add_i32 m0, s17, 0xc000
	ds_read_b128 v[184:187], v154
	ds_read_b128 v[188:191], v154 offset:1024
	ds_read_b128 v[192:195], v154 offset:2048
	ds_read_b128 v[196:199], v154 offset:3072
	ds_read_b128 v[200:203], v154 offset:4096
	ds_read_b128 v[204:207], v154 offset:5120
	ds_read_b128 v[208:211], v154 offset:6144
	ds_read_b128 v[212:215], v154 offset:7168
	global_load_lds_dwordx4 v[216:217], off
	v_lshl_add_u64 v[216:217], s[44:45], 0, v[140:141]
	s_add_i32 m0, s17, 0xe000
	s_nop 0
	global_load_lds_dwordx4 v[216:217], off
	s_waitcnt vmcnt(8)
	s_waitcnt lgkmcnt(0)
	s_barrier
	s_setprio 0
	v_mfma_f32_16x16x32_bf16 v[126:129], v[146:149], v[184:187], 0
	v_mfma_f32_16x16x32_bf16 v[122:125], v[160:163], v[184:187], 0
	v_mfma_f32_16x16x32_bf16 v[118:121], v[146:149], v[192:195], 0
	v_mfma_f32_16x16x32_bf16 v[110:113], v[160:163], v[192:195], 0
	v_mfma_f32_16x16x32_bf16 v[102:105], v[146:149], v[200:203], 0
	v_mfma_f32_16x16x32_bf16 v[94:97], v[160:163], v[200:203], 0
	v_mfma_f32_16x16x32_bf16 v[86:89], v[146:149], v[208:211], 0
	v_mfma_f32_16x16x32_bf16 v[78:81], v[160:163], v[208:211], 0
	v_mfma_f32_16x16x32_bf16 v[126:129], v[156:159], v[188:191], v[126:129]
	v_mfma_f32_16x16x32_bf16 v[122:125], v[164:167], v[188:191], v[122:125]
	v_mfma_f32_16x16x32_bf16 v[118:121], v[156:159], v[196:199], v[118:121]
	v_mfma_f32_16x16x32_bf16 v[110:113], v[164:167], v[196:199], v[110:113]
	v_mfma_f32_16x16x32_bf16 v[102:105], v[156:159], v[204:207], v[102:105]
	v_mfma_f32_16x16x32_bf16 v[94:97], v[164:167], v[204:207], v[94:97]
	v_mfma_f32_16x16x32_bf16 v[86:89], v[156:159], v[212:215], v[86:89]
	v_mfma_f32_16x16x32_bf16 v[78:81], v[164:167], v[212:215], v[78:81]
	s_setprio 2
	s_setprio 0
	v_mfma_f32_16x16x32_bf16 v[114:117], v[168:171], v[184:187], 0
	v_mfma_f32_16x16x32_bf16 v[106:109], v[176:179], v[184:187], 0
	v_mfma_f32_16x16x32_bf16 v[98:101], v[168:171], v[192:195], 0
	v_mfma_f32_16x16x32_bf16 v[90:93], v[176:179], v[192:195], 0
	v_mfma_f32_16x16x32_bf16 v[82:85], v[168:171], v[200:203], 0
	v_mfma_f32_16x16x32_bf16 v[74:77], v[176:179], v[200:203], 0
	v_mfma_f32_16x16x32_bf16 v[70:73], v[168:171], v[208:211], 0
	v_mfma_f32_16x16x32_bf16 v[66:69], v[176:179], v[208:211], 0
	v_mfma_f32_16x16x32_bf16 v[114:117], v[172:175], v[188:191], v[114:117]
	v_mfma_f32_16x16x32_bf16 v[106:109], v[180:183], v[188:191], v[106:109]
	v_mfma_f32_16x16x32_bf16 v[98:101], v[172:175], v[196:199], v[98:101]
	v_mfma_f32_16x16x32_bf16 v[90:93], v[180:183], v[196:199], v[90:93]
	v_mfma_f32_16x16x32_bf16 v[82:85], v[172:175], v[204:207], v[82:85]
	v_mfma_f32_16x16x32_bf16 v[74:77], v[180:183], v[204:207], v[74:77]
	v_mfma_f32_16x16x32_bf16 v[70:73], v[172:175], v[212:215], v[70:73]
	v_mfma_f32_16x16x32_bf16 v[66:69], v[180:183], v[212:215], v[66:69]
	s_setprio 2
	s_barrier
	s_add_i32 s33, s72, s61
	v_lshl_add_u64 v[216:217], s[46:47], 0, v[134:135]
	s_mov_b32 m0, s33
	ds_read_b128 v[184:187], v154 offset:16384
	ds_read_b128 v[188:191], v154 offset:17408
	ds_read_b128 v[192:195], v154 offset:18432
	ds_read_b128 v[196:199], v154 offset:19456
	ds_read_b128 v[200:203], v154 offset:20480
	ds_read_b128 v[204:207], v154 offset:21504
	ds_read_b128 v[208:211], v154 offset:22528
	ds_read_b128 v[212:215], v154 offset:23552
	global_load_lds_dwordx4 v[216:217], off
	s_add_i32 m0, s33, 0x2000
	s_add_u32 s62, s46, 0x100000
	v_lshl_add_u64 v[218:219], s[46:47], 0, v[130:131]
	s_addc_u32 s63, s47, 0
	s_add_i32 s33, s73, s61
	global_load_lds_dwordx4 v[218:219], off
	v_lshl_add_u64 v[220:221], s[62:63], 0, v[134:135]
	s_mov_b32 m0, s33
	v_lshl_add_u64 v[224:225], s[52:53], 0, v[132:133]
	global_load_lds_dwordx4 v[220:221], off
	v_lshl_add_u64 v[220:221], s[62:63], 0, v[130:131]
	s_add_i32 m0, s33, 0x2000
	s_nop 0
	global_load_lds_dwordx4 v[220:221], off
	v_lshl_add_u64 v[220:221], s[52:53], 0, v[136:137]
	s_mov_b32 m0, s17
	s_nop 0
	global_load_lds_dwordx4 v[220:221], off
	s_mov_b32 m0, s39
	s_nop 0
	global_load_lds_dwordx4 v[224:225], off
	s_waitcnt vmcnt(8)
	s_waitcnt lgkmcnt(0)
	s_barrier
; #define PG8_STAGE(bufoff, gbase, voff) do { _Pragma("unroll") for (int _i = 0; _i < 2; ++_i) \
;         __builtin_amdgcn_global_load_lds((const unsigned*)((const char*)(gbase) + (voff)[_i]), (LAS unsigned*)(lds + (bufoff) + ldsw + _i * 8192), 16, 0, 0); } while (0)
; #define PG8_LDA(dst, b, h) do { _Pragma("unroll") for (int m = 0; m < 4; ++m) _Pragma("unroll") for (int k = 0; k < 2; ++k) dst[m][k] = *(const LAS bf16x8*)(lds + PG8_SA(b, h) + aoff + m * 2048 + k * 1024); } while (0)
; #define PG8_LDB(dst, b, h) do { _Pragma("unroll") for (int n = 0; n < 2; ++n) _Pragma("unroll") for (int k = 0; k < 2; ++k) dst[n][k] = *(const LAS bf16x8*)(lds + PG8_SB(b, h) + boff + n * 2048 + k * 1024); } while (0)
; #define PG8_MMA(ai, bj, At, Bt) do { __builtin_amdgcn_s_setprio(1); _Pragma("unroll") for (int m = 0; m < 4; ++m) _Pragma("unroll") for (int n = 0; n < 2; ++n) _Pragma("unroll") for (int k = 0; k < 2; ++k) \
;         acc[ai][bj][m][n] = __builtin_amdgcn_mfma_f32_16x16x32_bf16(Bt[n][k], At[m][k], acc[ai][bj][m][n], 0, 0, 0); __builtin_amdgcn_s_setprio(0); } while (0)
; #define PG8_WAIT_V(n) asm volatile("s_waitcnt vmcnt(" #n ")" ::: "memory")
; #define PG8_WAIT_L(n) asm volatile("s_waitcnt lgkmcnt(" #n ")" ::: "memory")
; #define PG8_BAR __builtin_amdgcn_s_barrier()
; #define PG8_SCHED __builtin_amdgcn_sched_barrier(0)
; template <class Epi>
; __device__ __forceinline__ void gemm_phase(LAS unsigned char* lds, const Gemm g, int G, int c, const Epi& E) {
;     ...
;             PG8_WAIT_V(8); PG8_WAIT_L(0); PG8_BAR; PG8_MMA(1, 0, At, B0); PG8_MMA(1, 1, At, B1); PG8_BAR; PG8_SCHED;
;             PG8_LDB(B0, 1, 0); PG8_LDB(B1, 1, 1); PG8_SCHED; PG8_LDA(At, 1, 0); PG8_STAGE(PG8_SA(0, 1), a2 + hstepA, voffA);
;             PG8_WAIT_V(8); PG8_WAIT_L(0); PG8_BAR; PG8_MMA(0, 0, At, B0); PG8_MMA(0, 1, At, B1); PG8_BAR; PG8_SCHED;
;             PG8_LDA(At, 1, 1); PG8_STAGE(PG8_SB(1, 0), b3, voffB); PG8_STAGE(PG8_SB(1, 1), b3 + hstepB, voffB); PG8_STAGE(PG8_SA(1, 0), a3, voffA);
	s_setprio 0
	v_mfma_f32_16x16x32_bf16 v[62:65], v[146:149], v[184:187], 0
	v_mfma_f32_16x16x32_bf16 v[58:61], v[160:163], v[184:187], 0
	v_mfma_f32_16x16x32_bf16 v[54:57], v[146:149], v[192:195], 0
	v_mfma_f32_16x16x32_bf16 v[46:49], v[160:163], v[192:195], 0
	v_mfma_f32_16x16x32_bf16 v[38:41], v[146:149], v[200:203], 0
	v_mfma_f32_16x16x32_bf16 v[30:33], v[160:163], v[200:203], 0
	v_mfma_f32_16x16x32_bf16 v[22:25], v[146:149], v[208:211], 0
	v_mfma_f32_16x16x32_bf16 v[14:17], v[160:163], v[208:211], 0
	v_mfma_f32_16x16x32_bf16 v[62:65], v[156:159], v[188:191], v[62:65]
	v_mfma_f32_16x16x32_bf16 v[58:61], v[164:167], v[188:191], v[58:61]
	v_mfma_f32_16x16x32_bf16 v[54:57], v[156:159], v[196:199], v[54:57]
	v_mfma_f32_16x16x32_bf16 v[46:49], v[164:167], v[196:199], v[46:49]
	v_mfma_f32_16x16x32_bf16 v[38:41], v[156:159], v[204:207], v[38:41]
	v_mfma_f32_16x16x32_bf16 v[30:33], v[164:167], v[204:207], v[30:33]
	v_mfma_f32_16x16x32_bf16 v[22:25], v[156:159], v[212:215], v[22:25]
	v_mfma_f32_16x16x32_bf16 v[14:17], v[164:167], v[212:215], v[14:17]
	s_setprio 2
	s_setprio 0
	v_mfma_f32_16x16x32_bf16 v[50:53], v[168:171], v[184:187], 0
	v_mfma_f32_16x16x32_bf16 v[42:45], v[176:179], v[184:187], 0
	v_mfma_f32_16x16x32_bf16 v[34:37], v[168:171], v[192:195], 0
	v_mfma_f32_16x16x32_bf16 v[26:29], v[176:179], v[192:195], 0
	v_mfma_f32_16x16x32_bf16 v[18:21], v[168:171], v[200:203], 0
	v_mfma_f32_16x16x32_bf16 v[10:13], v[176:179], v[200:203], 0
	v_mfma_f32_16x16x32_bf16 v[6:9], v[168:171], v[208:211], 0
	v_mfma_f32_16x16x32_bf16 v[2:5], v[176:179], v[208:211], 0
	v_mfma_f32_16x16x32_bf16 v[50:53], v[172:175], v[188:191], v[50:53]
	v_mfma_f32_16x16x32_bf16 v[42:45], v[180:183], v[188:191], v[42:45]
	v_mfma_f32_16x16x32_bf16 v[34:37], v[172:175], v[196:199], v[34:37]
	v_mfma_f32_16x16x32_bf16 v[26:29], v[180:183], v[196:199], v[26:29]
	v_mfma_f32_16x16x32_bf16 v[18:21], v[172:175], v[204:207], v[18:21]
	v_mfma_f32_16x16x32_bf16 v[10:13], v[180:183], v[204:207], v[10:13]
	v_mfma_f32_16x16x32_bf16 v[6:9], v[172:175], v[212:215], v[6:9]
	v_mfma_f32_16x16x32_bf16 v[2:5], v[180:183], v[212:215], v[2:5]
	s_setprio 2
	s_barrier
	s_add_i32 s33, 0, 0x18000
	v_add_u32_e32 v155, s33, v151
	s_add_i32 s62, 0, 0x1c000
	ds_read_b128 v[146:149], v155
	ds_read_b128 v[156:159], v155 offset:1024
	ds_read_b128 v[160:163], v155 offset:2048
	ds_read_b128 v[164:167], v155 offset:3072
	v_add_u32_e32 v155, s62, v151
	ds_read_b128 v[168:171], v155
	ds_read_b128 v[172:175], v155 offset:1024
	ds_read_b128 v[176:179], v155 offset:2048
	ds_read_b128 v[180:183], v155 offset:3072
	s_add_u32 s52, s52, 0x100000
	s_addc_u32 s53, s53, 0
	s_mov_b32 m0, s43
	v_lshl_add_u64 v[226:227], s[52:53], 0, v[136:137]
	ds_read_b128 v[184:187], v154 offset:32768
	ds_read_b128 v[188:191], v154 offset:33792
	ds_read_b128 v[192:195], v154 offset:34816
	ds_read_b128 v[196:199], v154 offset:35840
	ds_read_b128 v[200:203], v154 offset:36864
	ds_read_b128 v[204:207], v154 offset:37888
	ds_read_b128 v[208:211], v154 offset:38912
	ds_read_b128 v[212:215], v154 offset:39936
	global_load_lds_dwordx4 v[226:227], off
	v_lshl_add_u64 v[226:227], s[52:53], 0, v[132:133]
	s_mov_b32 m0, s66
	s_nop 0
	global_load_lds_dwordx4 v[226:227], off
	s_waitcnt vmcnt(8)
	s_waitcnt lgkmcnt(0)
	s_barrier
	s_setprio 0
	v_mfma_f32_16x16x32_bf16 v[126:129], v[146:149], v[184:187], v[126:129]
	v_mfma_f32_16x16x32_bf16 v[122:125], v[160:163], v[184:187], v[122:125]
	v_mfma_f32_16x16x32_bf16 v[118:121], v[146:149], v[192:195], v[118:121]
	v_mfma_f32_16x16x32_bf16 v[110:113], v[160:163], v[192:195], v[110:113]
	v_mfma_f32_16x16x32_bf16 v[102:105], v[146:149], v[200:203], v[102:105]
	v_mfma_f32_16x16x32_bf16 v[94:97], v[160:163], v[200:203], v[94:97]
	v_mfma_f32_16x16x32_bf16 v[86:89], v[146:149], v[208:211], v[86:89]
	v_mfma_f32_16x16x32_bf16 v[78:81], v[160:163], v[208:211], v[78:81]
	v_mfma_f32_16x16x32_bf16 v[126:129], v[156:159], v[188:191], v[126:129]
	v_mfma_f32_16x16x32_bf16 v[122:125], v[164:167], v[188:191], v[122:125]
	v_mfma_f32_16x16x32_bf16 v[118:121], v[156:159], v[196:199], v[118:121]
	v_mfma_f32_16x16x32_bf16 v[110:113], v[164:167], v[196:199], v[110:113]
	v_mfma_f32_16x16x32_bf16 v[102:105], v[156:159], v[204:207], v[102:105]
	v_mfma_f32_16x16x32_bf16 v[94:97], v[164:167], v[204:207], v[94:97]
	v_mfma_f32_16x16x32_bf16 v[86:89], v[156:159], v[212:215], v[86:89]
	v_mfma_f32_16x16x32_bf16 v[78:81], v[164:167], v[212:215], v[78:81]
	s_setprio 2
	s_setprio 0
	v_mfma_f32_16x16x32_bf16 v[114:117], v[168:171], v[184:187], v[114:117]
	v_mfma_f32_16x16x32_bf16 v[106:109], v[176:179], v[184:187], v[106:109]
	v_mfma_f32_16x16x32_bf16 v[98:101], v[168:171], v[192:195], v[98:101]
	v_mfma_f32_16x16x32_bf16 v[90:93], v[176:179], v[192:195], v[90:93]
	v_mfma_f32_16x16x32_bf16 v[82:85], v[168:171], v[200:203], v[82:85]
	v_mfma_f32_16x16x32_bf16 v[74:77], v[176:179], v[200:203], v[74:77]
	v_mfma_f32_16x16x32_bf16 v[70:73], v[168:171], v[208:211], v[70:73]
	v_mfma_f32_16x16x32_bf16 v[66:69], v[176:179], v[208:211], v[66:69]
	v_mfma_f32_16x16x32_bf16 v[114:117], v[172:175], v[188:191], v[114:117]
	v_mfma_f32_16x16x32_bf16 v[106:109], v[180:183], v[188:191], v[106:109]
	v_mfma_f32_16x16x32_bf16 v[98:101], v[172:175], v[196:199], v[98:101]
	v_mfma_f32_16x16x32_bf16 v[90:93], v[180:183], v[196:199], v[90:93]
	v_mfma_f32_16x16x32_bf16 v[82:85], v[172:175], v[204:207], v[82:85]
	v_mfma_f32_16x16x32_bf16 v[74:77], v[180:183], v[204:207], v[74:77]
	v_mfma_f32_16x16x32_bf16 v[70:73], v[172:175], v[212:215], v[70:73]
	v_mfma_f32_16x16x32_bf16 v[66:69], v[180:183], v[212:215], v[66:69]
	s_setprio 2
	s_barrier
; #define PG8_STAGE(bufoff, gbase, voff) do { _Pragma("unroll") for (int _i = 0; _i < 2; ++_i) \
;         __builtin_amdgcn_global_load_lds((const unsigned*)((const char*)(gbase) + (voff)[_i]), (LAS unsigned*)(lds + (bufoff) + ldsw + _i * 8192), 16, 0, 0); } while (0)
; #define PG8_LDA(dst, b, h) do { _Pragma("unroll") for (int m = 0; m < 4; ++m) _Pragma("unroll") for (int k = 0; k < 2; ++k) dst[m][k] = *(const LAS bf16x8*)(lds + PG8_SA(b, h) + aoff + m * 2048 + k * 1024); } while (0)
; #define PG8_LDB(dst, b, h) do { _Pragma("unroll") for (int n = 0; n < 2; ++n) _Pragma("unroll") for (int k = 0; k < 2; ++k) dst[n][k] = *(const LAS bf16x8*)(lds + PG8_SB(b, h) + boff + n * 2048 + k * 1024); } while (0)
; #define PG8_MMA(ai, bj, At, Bt) do { __builtin_amdgcn_s_setprio(1); _Pragma("unroll") for (int m = 0; m < 4; ++m) _Pragma("unroll") for (int n = 0; n < 2; ++n) _Pragma("unroll") for (int k = 0; k < 2; ++k) \
;         acc[ai][bj][m][n] = __builtin_amdgcn_mfma_f32_16x16x32_bf16(Bt[n][k], At[m][k], acc[ai][bj][m][n], 0, 0, 0); __builtin_amdgcn_s_setprio(0); } while (0)
; #define PG8_WAIT_V(n) asm volatile("s_waitcnt vmcnt(" #n ")" ::: "memory")
; #define PG8_WAIT_L(n) asm volatile("s_waitcnt lgkmcnt(" #n ")" ::: "memory")
; #define PG8_BAR __builtin_amdgcn_s_barrier()
; #define PG8_SCHED __builtin_amdgcn_sched_barrier(0)
; template <class Epi>
; __device__ __forceinline__ void gemm_phase(LAS unsigned char* lds, const Gemm g, int G, int c, const Epi& E) {
;     ...
;             const bool last = (t == nt - 2);
;             const char* a1 = cA + (size_t)(t + 1) * kstep;
;             const char* a2 = last ? nA : cA + (size_t)(t + 2) * kstep; const char* b2 = last ? nB : cB + (size_t)(t + 2) * kstep;
;             const char* a3 = a2 + kstep; const char* b3 = b2 + kstep;
;             PG8_LDB(B0, 0, 0); PG8_LDB(B1, 0, 1); PG8_SCHED; PG8_LDA(At, 0, 0); PG8_STAGE(PG8_SA(1, 1), a1 + hstepA, voffA);
;     ...
;             PG8_LDA(At, 1, 1); PG8_STAGE(PG8_SB(1, 0), b3, voffB); PG8_STAGE(PG8_SB(1, 1), b3 + hstepB, voffB); PG8_STAGE(PG8_SA(1, 0), a3, voffA);
;             PG8_WAIT_V(8); PG8_WAIT_L(0); PG8_BAR; PG8_MMA(1, 0, At, B0); PG8_MMA(1, 1, At, B1); PG8_BAR; PG8_SCHED;
	s_add_i32 s33, s33, s61
	v_lshl_add_u64 v[216:217], v[216:217], 0, s[6:7]
	s_mov_b32 m0, s33
	ds_read_b128 v[184:187], v154 offset:49152
	ds_read_b128 v[188:191], v154 offset:50176
	ds_read_b128 v[192:195], v154 offset:51200
	ds_read_b128 v[196:199], v154 offset:52224
	ds_read_b128 v[200:203], v154 offset:53248
	ds_read_b128 v[204:207], v154 offset:54272
	ds_read_b128 v[208:211], v154 offset:55296
	ds_read_b128 v[212:215], v154 offset:56320
	global_load_lds_dwordx4 v[216:217], off
	s_add_i32 m0, s33, 0x2000
	s_add_u32 s46, s46, 0x100080
	v_lshl_add_u64 v[216:217], v[218:219], 0, s[6:7]
	s_addc_u32 s47, s47, 0
	s_add_i32 s33, s62, s61
	global_load_lds_dwordx4 v[216:217], off
	v_lshl_add_u64 v[216:217], s[46:47], 0, v[134:135]
	s_mov_b32 m0, s33
	s_nop 0
	global_load_lds_dwordx4 v[216:217], off
	v_lshl_add_u64 v[216:217], s[46:47], 0, v[130:131]
	s_add_i32 m0, s33, 0x2000
	s_nop 0
	global_load_lds_dwordx4 v[216:217], off
	v_lshl_add_u64 v[216:217], v[220:221], 0, s[6:7]
	s_mov_b32 m0, s70
	s_nop 0
	global_load_lds_dwordx4 v[216:217], off
	v_lshl_add_u64 v[216:217], v[224:225], 0, s[6:7]
	s_mov_b32 m0, s71
	s_nop 0
	global_load_lds_dwordx4 v[216:217], off
	s_waitcnt vmcnt(8)
	s_waitcnt lgkmcnt(0)
	s_barrier
	s_setprio 0
	v_mfma_f32_16x16x32_bf16 v[62:65], v[146:149], v[184:187], v[62:65]
	v_mfma_f32_16x16x32_bf16 v[58:61], v[160:163], v[184:187], v[58:61]
	v_mfma_f32_16x16x32_bf16 v[54:57], v[146:149], v[192:195], v[54:57]
	v_mfma_f32_16x16x32_bf16 v[46:49], v[160:163], v[192:195], v[46:49]
	v_mfma_f32_16x16x32_bf16 v[38:41], v[146:149], v[200:203], v[38:41]
	v_mfma_f32_16x16x32_bf16 v[30:33], v[160:163], v[200:203], v[30:33]
	v_mfma_f32_16x16x32_bf16 v[22:25], v[146:149], v[208:211], v[22:25]
	v_mfma_f32_16x16x32_bf16 v[14:17], v[160:163], v[208:211], v[14:17]
	v_mfma_f32_16x16x32_bf16 v[62:65], v[156:159], v[188:191], v[62:65]
	v_mfma_f32_16x16x32_bf16 v[58:61], v[164:167], v[188:191], v[58:61]
	v_mfma_f32_16x16x32_bf16 v[54:57], v[156:159], v[196:199], v[54:57]
	v_mfma_f32_16x16x32_bf16 v[46:49], v[164:167], v[196:199], v[46:49]
	v_mfma_f32_16x16x32_bf16 v[38:41], v[156:159], v[204:207], v[38:41]
	v_mfma_f32_16x16x32_bf16 v[30:33], v[164:167], v[204:207], v[30:33]
	v_mfma_f32_16x16x32_bf16 v[22:25], v[156:159], v[212:215], v[22:25]
	v_mfma_f32_16x16x32_bf16 v[14:17], v[164:167], v[212:215], v[14:17]
	s_setprio 2
	s_setprio 0
	v_mfma_f32_16x16x32_bf16 v[50:53], v[168:171], v[184:187], v[50:53]
	v_mfma_f32_16x16x32_bf16 v[42:45], v[176:179], v[184:187], v[42:45]
	v_mfma_f32_16x16x32_bf16 v[34:37], v[168:171], v[192:195], v[34:37]
	v_mfma_f32_16x16x32_bf16 v[26:29], v[176:179], v[192:195], v[26:29]
	v_mfma_f32_16x16x32_bf16 v[18:21], v[168:171], v[200:203], v[18:21]
	v_mfma_f32_16x16x32_bf16 v[10:13], v[176:179], v[200:203], v[10:13]
	v_mfma_f32_16x16x32_bf16 v[6:9], v[168:171], v[208:211], v[6:9]
	v_mfma_f32_16x16x32_bf16 v[2:5], v[176:179], v[208:211], v[2:5]
	v_mfma_f32_16x16x32_bf16 v[50:53], v[172:175], v[188:191], v[50:53]
	v_mfma_f32_16x16x32_bf16 v[42:45], v[180:183], v[188:191], v[42:45]
	v_mfma_f32_16x16x32_bf16 v[34:37], v[172:175], v[196:199], v[34:37]
	v_mfma_f32_16x16x32_bf16 v[26:29], v[180:183], v[196:199], v[26:29]
	v_mfma_f32_16x16x32_bf16 v[18:21], v[172:175], v[204:207], v[18:21]
	v_mfma_f32_16x16x32_bf16 v[10:13], v[180:183], v[204:207], v[10:13]
	v_mfma_f32_16x16x32_bf16 v[6:9], v[172:175], v[212:215], v[6:9]
	v_mfma_f32_16x16x32_bf16 v[2:5], v[180:183], v[212:215], v[2:5]
	s_setprio 2
	s_barrier
	s_add_i32 s83, s83, 2
	s_add_u32 s44, s44, 0x100
	s_addc_u32 s45, s45, 0
	s_add_u32 s81, s81, 0x100
	s_addc_u32 s82, s82, 0
	s_cmp_gt_u32 s83, 61
	s_cbranch_scc0 .LBB0_765
.LBB0_765:
	ds_read_b128 v[146:149], v152
	ds_read_b128 v[156:159], v152 offset:1024
	ds_read_b128 v[160:163], v152 offset:2048
	ds_read_b128 v[164:167], v152 offset:3072
	ds_read_b128 v[168:171], v153
	ds_read_b128 v[172:175], v153 offset:1024
	ds_read_b128 v[176:179], v153 offset:2048
	ds_read_b128 v[180:183], v153 offset:3072
	s_add_u32 s33, s44, 0xfff00080
	s_addc_u32 s46, s45, -1
	s_cmp_eq_u32 s83, 60
	s_cselect_b32 s53, s15, s46
	s_cselect_b32 s52, s78, s33
	s_cselect_b32 s47, s11, s82
	s_cselect_b32 s46, s13, s81
	v_lshl_add_u64 v[216:217], s[44:45], 0, v[138:139]
	s_add_i32 m0, s17, 0xc000
	ds_read_b128 v[184:187], v154
	ds_read_b128 v[188:191], v154 offset:1024
	ds_read_b128 v[192:195], v154 offset:2048
	ds_read_b128 v[196:199], v154 offset:3072
	ds_read_b128 v[200:203], v154 offset:4096
	ds_read_b128 v[204:207], v154 offset:5120
	ds_read_b128 v[208:211], v154 offset:6144
	ds_read_b128 v[212:215], v154 offset:7168
	global_load_lds_dwordx4 v[216:217], off
	v_lshl_add_u64 v[216:217], s[44:45], 0, v[140:141]
	s_add_i32 m0, s17, 0xe000
	s_nop 0
	global_load_lds_dwordx4 v[216:217], off
	s_waitcnt vmcnt(8)
	s_waitcnt lgkmcnt(0)
	s_barrier
; #define PG8_STAGE(bufoff, gbase, voff) do { _Pragma("unroll") for (int _i = 0; _i < 2; ++_i) \
;         __builtin_amdgcn_global_load_lds((const unsigned*)((const char*)(gbase) + (voff)[_i]), (LAS unsigned*)(lds + (bufoff) + ldsw + _i * 8192), 16, 0, 0); } while (0)
; #define PG8_LDA(dst, b, h) do { _Pragma("unroll") for (int m = 0; m < 4; ++m) _Pragma("unroll") for (int k = 0; k < 2; ++k) dst[m][k] = *(const LAS bf16x8*)(lds + PG8_SA(b, h) + aoff + m * 2048 + k * 1024); } while (0)
; #define PG8_MMA(ai, bj, At, Bt) do { __builtin_amdgcn_s_setprio(1); _Pragma("unroll") for (int m = 0; m < 4; ++m) _Pragma("unroll") for (int n = 0; n < 2; ++n) _Pragma("unroll") for (int k = 0; k < 2; ++k) \
;         acc[ai][bj][m][n] = __builtin_amdgcn_mfma_f32_16x16x32_bf16(Bt[n][k], At[m][k], acc[ai][bj][m][n], 0, 0, 0); __builtin_amdgcn_s_setprio(0); } while (0)
; #define PG8_WAIT_V(n) asm volatile("s_waitcnt vmcnt(" #n ")" ::: "memory")
; #define PG8_WAIT_L(n) asm volatile("s_waitcnt lgkmcnt(" #n ")" ::: "memory")
; #define PG8_BAR __builtin_amdgcn_s_barrier()
; #define PG8_SCHED __builtin_amdgcn_sched_barrier(0)
; template <class Epi>
; __device__ __forceinline__ void gemm_phase(LAS unsigned char* lds, const Gemm g, int G, int c, const Epi& E) {
;     ...
;             PG8_WAIT_V(8); PG8_WAIT_L(0); PG8_BAR; PG8_MMA(0, 0, At, B0); PG8_MMA(0, 1, At, B1); PG8_BAR; PG8_SCHED;
;             PG8_LDA(At, 0, 1); PG8_STAGE(PG8_SB(0, 0), b2, voffB); PG8_STAGE(PG8_SB(0, 1), b2 + hstepB, voffB); PG8_STAGE(PG8_SA(0, 0), a2, voffA);
;             PG8_WAIT_V(8); PG8_WAIT_L(0); PG8_BAR; PG8_MMA(1, 0, At, B0); PG8_MMA(1, 1, At, B1); PG8_BAR; PG8_SCHED;
	s_setprio 0
	v_mfma_f32_16x16x32_bf16 v[126:129], v[146:149], v[184:187], v[126:129]
	v_mfma_f32_16x16x32_bf16 v[122:125], v[160:163], v[184:187], v[122:125]
	v_mfma_f32_16x16x32_bf16 v[118:121], v[146:149], v[192:195], v[118:121]
	v_mfma_f32_16x16x32_bf16 v[110:113], v[160:163], v[192:195], v[110:113]
	v_mfma_f32_16x16x32_bf16 v[102:105], v[146:149], v[200:203], v[102:105]
	v_mfma_f32_16x16x32_bf16 v[94:97], v[160:163], v[200:203], v[94:97]
	v_mfma_f32_16x16x32_bf16 v[86:89], v[146:149], v[208:211], v[86:89]
	v_mfma_f32_16x16x32_bf16 v[78:81], v[160:163], v[208:211], v[78:81]
	v_mfma_f32_16x16x32_bf16 v[126:129], v[156:159], v[188:191], v[126:129]
	v_mfma_f32_16x16x32_bf16 v[122:125], v[164:167], v[188:191], v[122:125]
	v_mfma_f32_16x16x32_bf16 v[118:121], v[156:159], v[196:199], v[118:121]
	v_mfma_f32_16x16x32_bf16 v[110:113], v[164:167], v[196:199], v[110:113]
	v_mfma_f32_16x16x32_bf16 v[102:105], v[156:159], v[204:207], v[102:105]
	v_mfma_f32_16x16x32_bf16 v[94:97], v[164:167], v[204:207], v[94:97]
	v_mfma_f32_16x16x32_bf16 v[86:89], v[156:159], v[212:215], v[86:89]
	v_mfma_f32_16x16x32_bf16 v[78:81], v[164:167], v[212:215], v[78:81]
	s_setprio 2
	s_setprio 0
	v_mfma_f32_16x16x32_bf16 v[114:117], v[168:171], v[184:187], v[114:117]
	v_mfma_f32_16x16x32_bf16 v[106:109], v[176:179], v[184:187], v[106:109]
	v_mfma_f32_16x16x32_bf16 v[98:101], v[168:171], v[192:195], v[98:101]
	v_mfma_f32_16x16x32_bf16 v[90:93], v[176:179], v[192:195], v[90:93]
	v_mfma_f32_16x16x32_bf16 v[82:85], v[168:171], v[200:203], v[82:85]
	v_mfma_f32_16x16x32_bf16 v[74:77], v[176:179], v[200:203], v[74:77]
	v_mfma_f32_16x16x32_bf16 v[70:73], v[168:171], v[208:211], v[70:73]
	v_mfma_f32_16x16x32_bf16 v[66:69], v[176:179], v[208:211], v[66:69]
	v_mfma_f32_16x16x32_bf16 v[114:117], v[172:175], v[188:191], v[114:117]
	v_mfma_f32_16x16x32_bf16 v[106:109], v[180:183], v[188:191], v[106:109]
	v_mfma_f32_16x16x32_bf16 v[98:101], v[172:175], v[196:199], v[98:101]
	v_mfma_f32_16x16x32_bf16 v[90:93], v[180:183], v[196:199], v[90:93]
	v_mfma_f32_16x16x32_bf16 v[82:85], v[172:175], v[204:207], v[82:85]
	v_mfma_f32_16x16x32_bf16 v[74:77], v[180:183], v[204:207], v[74:77]
	v_mfma_f32_16x16x32_bf16 v[70:73], v[172:175], v[212:215], v[70:73]
	v_mfma_f32_16x16x32_bf16 v[66:69], v[180:183], v[212:215], v[66:69]
	s_setprio 2
	s_barrier
	s_add_i32 s33, s72, s61
	v_lshl_add_u64 v[216:217], s[46:47], 0, v[134:135]
	s_mov_b32 m0, s33
	ds_read_b128 v[184:187], v154 offset:16384
	ds_read_b128 v[188:191], v154 offset:17408
	ds_read_b128 v[192:195], v154 offset:18432
	ds_read_b128 v[196:199], v154 offset:19456
	ds_read_b128 v[200:203], v154 offset:20480
	ds_read_b128 v[204:207], v154 offset:21504
	ds_read_b128 v[208:211], v154 offset:22528
	ds_read_b128 v[212:215], v154 offset:23552
	global_load_lds_dwordx4 v[216:217], off
	s_add_i32 m0, s33, 0x2000
	s_add_u32 s62, s46, 0x100000
	v_lshl_add_u64 v[218:219], s[46:47], 0, v[130:131]
	s_addc_u32 s63, s47, 0
	s_add_i32 s33, s73, s61
	global_load_lds_dwordx4 v[218:219], off
	v_lshl_add_u64 v[220:221], s[62:63], 0, v[134:135]
	s_mov_b32 m0, s33
	v_lshl_add_u64 v[224:225], s[52:53], 0, v[132:133]
	global_load_lds_dwordx4 v[220:221], off
	v_lshl_add_u64 v[220:221], s[62:63], 0, v[130:131]
	s_add_i32 m0, s33, 0x2000
	s_nop 0
	global_load_lds_dwordx4 v[220:221], off
	v_lshl_add_u64 v[220:221], s[52:53], 0, v[136:137]
	s_mov_b32 m0, s17
	s_nop 0
	global_load_lds_dwordx4 v[220:221], off
	s_mov_b32 m0, s39
	s_nop 0
	global_load_lds_dwordx4 v[224:225], off
	s_waitcnt vmcnt(8)
	s_waitcnt lgkmcnt(0)
	s_barrier
	s_setprio 0
	v_mfma_f32_16x16x32_bf16 v[62:65], v[146:149], v[184:187], v[62:65]
	v_mfma_f32_16x16x32_bf16 v[58:61], v[160:163], v[184:187], v[58:61]
	v_mfma_f32_16x16x32_bf16 v[54:57], v[146:149], v[192:195], v[54:57]
	v_mfma_f32_16x16x32_bf16 v[46:49], v[160:163], v[192:195], v[46:49]
	v_mfma_f32_16x16x32_bf16 v[38:41], v[146:149], v[200:203], v[38:41]
	v_mfma_f32_16x16x32_bf16 v[30:33], v[160:163], v[200:203], v[30:33]
	v_mfma_f32_16x16x32_bf16 v[22:25], v[146:149], v[208:211], v[22:25]
	v_mfma_f32_16x16x32_bf16 v[14:17], v[160:163], v[208:211], v[14:17]
	v_mfma_f32_16x16x32_bf16 v[62:65], v[156:159], v[188:191], v[62:65]
	v_mfma_f32_16x16x32_bf16 v[58:61], v[164:167], v[188:191], v[58:61]
	v_mfma_f32_16x16x32_bf16 v[54:57], v[156:159], v[196:199], v[54:57]
	v_mfma_f32_16x16x32_bf16 v[46:49], v[164:167], v[196:199], v[46:49]
	v_mfma_f32_16x16x32_bf16 v[38:41], v[156:159], v[204:207], v[38:41]
	v_mfma_f32_16x16x32_bf16 v[30:33], v[164:167], v[204:207], v[30:33]
	v_mfma_f32_16x16x32_bf16 v[22:25], v[156:159], v[212:215], v[22:25]
	v_mfma_f32_16x16x32_bf16 v[14:17], v[164:167], v[212:215], v[14:17]
	s_setprio 2
	s_setprio 0
	v_mfma_f32_16x16x32_bf16 v[50:53], v[168:171], v[184:187], v[50:53]
	v_mfma_f32_16x16x32_bf16 v[42:45], v[176:179], v[184:187], v[42:45]
	v_mfma_f32_16x16x32_bf16 v[34:37], v[168:171], v[192:195], v[34:37]
	v_mfma_f32_16x16x32_bf16 v[26:29], v[176:179], v[192:195], v[26:29]
	v_mfma_f32_16x16x32_bf16 v[18:21], v[168:171], v[200:203], v[18:21]
	v_mfma_f32_16x16x32_bf16 v[10:13], v[176:179], v[200:203], v[10:13]
	v_mfma_f32_16x16x32_bf16 v[6:9], v[168:171], v[208:211], v[6:9]
	v_mfma_f32_16x16x32_bf16 v[2:5], v[176:179], v[208:211], v[2:5]
	v_mfma_f32_16x16x32_bf16 v[50:53], v[172:175], v[188:191], v[50:53]
	v_mfma_f32_16x16x32_bf16 v[42:45], v[180:183], v[188:191], v[42:45]
	v_mfma_f32_16x16x32_bf16 v[34:37], v[172:175], v[196:199], v[34:37]
	v_mfma_f32_16x16x32_bf16 v[26:29], v[180:183], v[196:199], v[26:29]
	v_mfma_f32_16x16x32_bf16 v[18:21], v[172:175], v[204:207], v[18:21]
	v_mfma_f32_16x16x32_bf16 v[10:13], v[180:183], v[204:207], v[10:13]
	v_mfma_f32_16x16x32_bf16 v[6:9], v[172:175], v[212:215], v[6:9]
	v_mfma_f32_16x16x32_bf16 v[2:5], v[180:183], v[212:215], v[2:5]
	s_setprio 2
	s_barrier
; #define PG8_STAGE(bufoff, gbase, voff) do { _Pragma("unroll") for (int _i = 0; _i < 2; ++_i) \
;         __builtin_amdgcn_global_load_lds((const unsigned*)((const char*)(gbase) + (voff)[_i]), (LAS unsigned*)(lds + (bufoff) + ldsw + _i * 8192), 16, 0, 0); } while (0)
; #define PG8_LDA(dst, b, h) do { _Pragma("unroll") for (int m = 0; m < 4; ++m) _Pragma("unroll") for (int k = 0; k < 2; ++k) dst[m][k] = *(const LAS bf16x8*)(lds + PG8_SA(b, h) + aoff + m * 2048 + k * 1024); } while (0)
; #define PG8_LDB(dst, b, h) do { _Pragma("unroll") for (int n = 0; n < 2; ++n) _Pragma("unroll") for (int k = 0; k < 2; ++k) dst[n][k] = *(const LAS bf16x8*)(lds + PG8_SB(b, h) + boff + n * 2048 + k * 1024); } while (0)
; #define PG8_MMA(ai, bj, At, Bt) do { __builtin_amdgcn_s_setprio(1); _Pragma("unroll") for (int m = 0; m < 4; ++m) _Pragma("unroll") for (int n = 0; n < 2; ++n) _Pragma("unroll") for (int k = 0; k < 2; ++k) \
;         acc[ai][bj][m][n] = __builtin_amdgcn_mfma_f32_16x16x32_bf16(Bt[n][k], At[m][k], acc[ai][bj][m][n], 0, 0, 0); __builtin_amdgcn_s_setprio(0); } while (0)
; #define PG8_WAIT_V(n) asm volatile("s_waitcnt vmcnt(" #n ")" ::: "memory")
; #define PG8_WAIT_L(n) asm volatile("s_waitcnt lgkmcnt(" #n ")" ::: "memory")
; #define PG8_BAR __builtin_amdgcn_s_barrier()
; #define PG8_SCHED __builtin_amdgcn_sched_barrier(0)
; template <class Epi>
; __device__ __forceinline__ void gemm_phase(LAS unsigned char* lds, const Gemm g, int G, int c, const Epi& E) {
;     ...
;             PG8_LDB(B0, 1, 0); PG8_LDB(B1, 1, 1); PG8_SCHED; PG8_LDA(At, 1, 0); PG8_STAGE(PG8_SA(0, 1), a2 + hstepA, voffA);
;             PG8_WAIT_V(8); PG8_WAIT_L(0); PG8_BAR; PG8_MMA(0, 0, At, B0); PG8_MMA(0, 1, At, B1); PG8_BAR; PG8_SCHED;
	s_add_i32 s33, 0, 0x18000
	v_add_u32_e32 v155, s33, v151
	s_add_i32 s62, 0, 0x1c000
	ds_read_b128 v[146:149], v155
	ds_read_b128 v[156:159], v155 offset:1024
	ds_read_b128 v[160:163], v155 offset:2048
	ds_read_b128 v[164:167], v155 offset:3072
	v_add_u32_e32 v155, s62, v151
	ds_read_b128 v[168:171], v155
	ds_read_b128 v[172:175], v155 offset:1024
	ds_read_b128 v[176:179], v155 offset:2048
	ds_read_b128 v[180:183], v155 offset:3072
	s_add_u32 s52, s52, 0x100000
	s_addc_u32 s53, s53, 0
	s_mov_b32 m0, s43
	v_lshl_add_u64 v[226:227], s[52:53], 0, v[136:137]
	ds_read_b128 v[184:187], v154 offset:32768
	ds_read_b128 v[188:191], v154 offset:33792
	ds_read_b128 v[192:195], v154 offset:34816
	ds_read_b128 v[196:199], v154 offset:35840
	ds_read_b128 v[200:203], v154 offset:36864
	ds_read_b128 v[204:207], v154 offset:37888
	ds_read_b128 v[208:211], v154 offset:38912
	ds_read_b128 v[212:215], v154 offset:39936
	global_load_lds_dwordx4 v[226:227], off
	v_lshl_add_u64 v[226:227], s[52:53], 0, v[132:133]
	s_mov_b32 m0, s66
	s_nop 0
	global_load_lds_dwordx4 v[226:227], off
	s_waitcnt vmcnt(8)
	s_waitcnt lgkmcnt(0)
	s_barrier
	s_setprio 0
	v_mfma_f32_16x16x32_bf16 v[126:129], v[146:149], v[184:187], v[126:129]
	v_mfma_f32_16x16x32_bf16 v[122:125], v[160:163], v[184:187], v[122:125]
	v_mfma_f32_16x16x32_bf16 v[118:121], v[146:149], v[192:195], v[118:121]
	v_mfma_f32_16x16x32_bf16 v[110:113], v[160:163], v[192:195], v[110:113]
	v_mfma_f32_16x16x32_bf16 v[102:105], v[146:149], v[200:203], v[102:105]
	v_mfma_f32_16x16x32_bf16 v[94:97], v[160:163], v[200:203], v[94:97]
	v_mfma_f32_16x16x32_bf16 v[86:89], v[146:149], v[208:211], v[86:89]
	v_mfma_f32_16x16x32_bf16 v[78:81], v[160:163], v[208:211], v[78:81]
	v_mfma_f32_16x16x32_bf16 v[126:129], v[156:159], v[188:191], v[126:129]
	v_mfma_f32_16x16x32_bf16 v[122:125], v[164:167], v[188:191], v[122:125]
	v_mfma_f32_16x16x32_bf16 v[118:121], v[156:159], v[196:199], v[118:121]
	v_mfma_f32_16x16x32_bf16 v[110:113], v[164:167], v[196:199], v[110:113]
	v_mfma_f32_16x16x32_bf16 v[102:105], v[156:159], v[204:207], v[102:105]
	v_mfma_f32_16x16x32_bf16 v[94:97], v[164:167], v[204:207], v[94:97]
	v_mfma_f32_16x16x32_bf16 v[86:89], v[156:159], v[212:215], v[86:89]
	v_mfma_f32_16x16x32_bf16 v[78:81], v[164:167], v[212:215], v[78:81]
	s_setprio 2
	s_setprio 0
	v_mfma_f32_16x16x32_bf16 v[114:117], v[168:171], v[184:187], v[114:117]
	v_mfma_f32_16x16x32_bf16 v[106:109], v[176:179], v[184:187], v[106:109]
	v_mfma_f32_16x16x32_bf16 v[98:101], v[168:171], v[192:195], v[98:101]
	v_mfma_f32_16x16x32_bf16 v[90:93], v[176:179], v[192:195], v[90:93]
	v_mfma_f32_16x16x32_bf16 v[82:85], v[168:171], v[200:203], v[82:85]
	v_mfma_f32_16x16x32_bf16 v[74:77], v[176:179], v[200:203], v[74:77]
	v_mfma_f32_16x16x32_bf16 v[70:73], v[168:171], v[208:211], v[70:73]
	v_mfma_f32_16x16x32_bf16 v[66:69], v[176:179], v[208:211], v[66:69]
	v_mfma_f32_16x16x32_bf16 v[114:117], v[172:175], v[188:191], v[114:117]
	v_mfma_f32_16x16x32_bf16 v[106:109], v[180:183], v[188:191], v[106:109]
	v_mfma_f32_16x16x32_bf16 v[98:101], v[172:175], v[196:199], v[98:101]
	v_mfma_f32_16x16x32_bf16 v[90:93], v[180:183], v[196:199], v[90:93]
	v_mfma_f32_16x16x32_bf16 v[82:85], v[172:175], v[204:207], v[82:85]
	v_mfma_f32_16x16x32_bf16 v[74:77], v[180:183], v[204:207], v[74:77]
	v_mfma_f32_16x16x32_bf16 v[70:73], v[172:175], v[212:215], v[70:73]
	v_mfma_f32_16x16x32_bf16 v[66:69], v[180:183], v[212:215], v[66:69]
	s_setprio 2
	s_barrier
; #define PG8_STAGE(bufoff, gbase, voff) do { _Pragma("unroll") for (int _i = 0; _i < 2; ++_i) \
;         __builtin_amdgcn_global_load_lds((const unsigned*)((const char*)(gbase) + (voff)[_i]), (LAS unsigned*)(lds + (bufoff) + ldsw + _i * 8192), 16, 0, 0); } while (0)
; #define PG8_LDA(dst, b, h) do { _Pragma("unroll") for (int m = 0; m < 4; ++m) _Pragma("unroll") for (int k = 0; k < 2; ++k) dst[m][k] = *(const LAS bf16x8*)(lds + PG8_SA(b, h) + aoff + m * 2048 + k * 1024); } while (0)
; #define PG8_MMA(ai, bj, At, Bt) do { __builtin_amdgcn_s_setprio(1); _Pragma("unroll") for (int m = 0; m < 4; ++m) _Pragma("unroll") for (int n = 0; n < 2; ++n) _Pragma("unroll") for (int k = 0; k < 2; ++k) \
;         acc[ai][bj][m][n] = __builtin_amdgcn_mfma_f32_16x16x32_bf16(Bt[n][k], At[m][k], acc[ai][bj][m][n], 0, 0, 0); __builtin_amdgcn_s_setprio(0); } while (0)
; #define PG8_WAIT_V(n) asm volatile("s_waitcnt vmcnt(" #n ")" ::: "memory")
; #define PG8_WAIT_L(n) asm volatile("s_waitcnt lgkmcnt(" #n ")" ::: "memory")
; #define PG8_BAR __builtin_amdgcn_s_barrier()
; #define PG8_SCHED __builtin_amdgcn_sched_barrier(0)
; template <class Epi>
; __device__ __forceinline__ void gemm_phase(LAS unsigned char* lds, const Gemm g, int G, int c, const Epi& E) {
;     ...
;             PG8_LDA(At, 1, 1); PG8_STAGE(PG8_SB(1, 0), b3, voffB); PG8_STAGE(PG8_SB(1, 1), b3 + hstepB, voffB); PG8_STAGE(PG8_SA(1, 0), a3, voffA);
;             PG8_WAIT_V(8); PG8_WAIT_L(0); PG8_BAR; PG8_MMA(1, 0, At, B0); PG8_MMA(1, 1, At, B1); PG8_BAR; PG8_SCHED;
;         }
;         if (wr == 0) PG8_BAR;
	s_add_i32 s33, s33, s61
	v_lshl_add_u64 v[216:217], v[216:217], 0, s[6:7]
	s_mov_b32 m0, s33
	ds_read_b128 v[184:187], v154 offset:49152
	ds_read_b128 v[188:191], v154 offset:50176
	ds_read_b128 v[192:195], v154 offset:51200
	ds_read_b128 v[196:199], v154 offset:52224
	ds_read_b128 v[200:203], v154 offset:53248
	ds_read_b128 v[204:207], v154 offset:54272
	ds_read_b128 v[208:211], v154 offset:55296
	ds_read_b128 v[212:215], v154 offset:56320
	global_load_lds_dwordx4 v[216:217], off
	s_add_i32 m0, s33, 0x2000
	s_add_u32 s46, s46, 0x100080
	v_lshl_add_u64 v[216:217], v[218:219], 0, s[6:7]
	s_addc_u32 s47, s47, 0
	s_add_i32 s33, s62, s61
	global_load_lds_dwordx4 v[216:217], off
	v_lshl_add_u64 v[216:217], s[46:47], 0, v[134:135]
	s_mov_b32 m0, s33
	s_nop 0
	global_load_lds_dwordx4 v[216:217], off
	v_lshl_add_u64 v[216:217], s[46:47], 0, v[130:131]
	s_add_i32 m0, s33, 0x2000
	s_nop 0
	global_load_lds_dwordx4 v[216:217], off
	v_lshl_add_u64 v[216:217], v[220:221], 0, s[6:7]
	s_mov_b32 m0, s70
	s_nop 0
	global_load_lds_dwordx4 v[216:217], off
	v_lshl_add_u64 v[216:217], v[224:225], 0, s[6:7]
	s_mov_b32 m0, s71
	s_nop 0
	global_load_lds_dwordx4 v[216:217], off
	s_waitcnt vmcnt(8)
	s_waitcnt lgkmcnt(0)
	s_barrier
	s_setprio 0
	v_mfma_f32_16x16x32_bf16 v[62:65], v[146:149], v[184:187], v[62:65]
	v_mfma_f32_16x16x32_bf16 v[58:61], v[160:163], v[184:187], v[58:61]
	v_mfma_f32_16x16x32_bf16 v[54:57], v[146:149], v[192:195], v[54:57]
	v_mfma_f32_16x16x32_bf16 v[46:49], v[160:163], v[192:195], v[46:49]
	v_mfma_f32_16x16x32_bf16 v[38:41], v[146:149], v[200:203], v[38:41]
	v_mfma_f32_16x16x32_bf16 v[30:33], v[160:163], v[200:203], v[30:33]
	v_mfma_f32_16x16x32_bf16 v[22:25], v[146:149], v[208:211], v[22:25]
	v_mfma_f32_16x16x32_bf16 v[14:17], v[160:163], v[208:211], v[14:17]
	v_mfma_f32_16x16x32_bf16 v[62:65], v[156:159], v[188:191], v[62:65]
	v_mfma_f32_16x16x32_bf16 v[58:61], v[164:167], v[188:191], v[58:61]
	v_mfma_f32_16x16x32_bf16 v[54:57], v[156:159], v[196:199], v[54:57]
	v_mfma_f32_16x16x32_bf16 v[46:49], v[164:167], v[196:199], v[46:49]
	v_mfma_f32_16x16x32_bf16 v[38:41], v[156:159], v[204:207], v[38:41]
	v_mfma_f32_16x16x32_bf16 v[30:33], v[164:167], v[204:207], v[30:33]
	v_mfma_f32_16x16x32_bf16 v[22:25], v[156:159], v[212:215], v[22:25]
	v_mfma_f32_16x16x32_bf16 v[14:17], v[164:167], v[212:215], v[14:17]
	s_setprio 2
	s_setprio 0
	v_mfma_f32_16x16x32_bf16 v[50:53], v[168:171], v[184:187], v[50:53]
	v_mfma_f32_16x16x32_bf16 v[42:45], v[176:179], v[184:187], v[42:45]
	v_mfma_f32_16x16x32_bf16 v[34:37], v[168:171], v[192:195], v[34:37]
	v_mfma_f32_16x16x32_bf16 v[26:29], v[176:179], v[192:195], v[26:29]
	v_mfma_f32_16x16x32_bf16 v[18:21], v[168:171], v[200:203], v[18:21]
	v_mfma_f32_16x16x32_bf16 v[10:13], v[176:179], v[200:203], v[10:13]
	v_mfma_f32_16x16x32_bf16 v[6:9], v[168:171], v[208:211], v[6:9]
	v_mfma_f32_16x16x32_bf16 v[2:5], v[176:179], v[208:211], v[2:5]
	v_mfma_f32_16x16x32_bf16 v[50:53], v[172:175], v[188:191], v[50:53]
	v_mfma_f32_16x16x32_bf16 v[42:45], v[180:183], v[188:191], v[42:45]
	v_mfma_f32_16x16x32_bf16 v[34:37], v[172:175], v[196:199], v[34:37]
	v_mfma_f32_16x16x32_bf16 v[26:29], v[180:183], v[196:199], v[26:29]
	v_mfma_f32_16x16x32_bf16 v[18:21], v[172:175], v[204:207], v[18:21]
	v_mfma_f32_16x16x32_bf16 v[10:13], v[180:183], v[204:207], v[10:13]
	v_mfma_f32_16x16x32_bf16 v[6:9], v[172:175], v[212:215], v[6:9]
	v_mfma_f32_16x16x32_bf16 v[2:5], v[180:183], v[212:215], v[2:5]
	s_setprio 2
	s_barrier
	s_add_i32 s83, s83, 2
	s_add_u32 s44, s44, 0x100
	s_addc_u32 s45, s45, 0
	s_add_u32 s81, s81, 0x100
	s_addc_u32 s82, s82, 0
	s_cmp_gt_u32 s83, 61
	s_cbranch_scc0 .LBB0_765
	s_and_b64 vcc, exec, s[8:9]
	s_cbranch_vccz .LBB0_768
	s_barrier

; #define PG8_STAGE(bufoff, gbase, voff) do { _Pragma("unroll") for (int _i = 0; _i < 2; ++_i) \
;         __builtin_amdgcn_global_load_lds((const unsigned*)((const char*)(gbase) + (voff)[_i]), (LAS unsigned*)(lds + (bufoff) + ldsw + _i * 8192), 16, 0, 0); } while (0)
; #define PG8_LDA(dst, b, h) do { _Pragma("unroll") for (int m = 0; m < 4; ++m) _Pragma("unroll") for (int k = 0; k < 2; ++k) dst[m][k] = *(const LAS bf16x8*)(lds + PG8_SA(b, h) + aoff + m * 2048 + k * 1024); } while (0)
; #define PG8_LDB(dst, b, h) do { _Pragma("unroll") for (int n = 0; n < 2; ++n) _Pragma("unroll") for (int k = 0; k < 2; ++k) dst[n][k] = *(const LAS bf16x8*)(lds + PG8_SB(b, h) + boff + n * 2048 + k * 1024); } while (0)
; #define PG8_MMA(ai, bj, At, Bt) do { __builtin_amdgcn_s_setprio(1); _Pragma("unroll") for (int m = 0; m < 4; ++m) _Pragma("unroll") for (int n = 0; n < 2; ++n) _Pragma("unroll") for (int k = 0; k < 2; ++k) \
;         acc[ai][bj][m][n] = __builtin_amdgcn_mfma_f32_16x16x32_bf16(Bt[n][k], At[m][k], acc[ai][bj][m][n], 0, 0, 0); __builtin_amdgcn_s_setprio(0); } while (0)
; #define PG8_WAIT_V(n) asm volatile("s_waitcnt vmcnt(" #n ")" ::: "memory")
; #define PG8_WAIT_L(n) asm volatile("s_waitcnt lgkmcnt(" #n ")" ::: "memory")
; #define PG8_BAR __builtin_amdgcn_s_barrier()
; #define PG8_SCHED __builtin_amdgcn_sched_barrier(0)
; template <class Epi>
; __device__ __forceinline__ void gemm_phase(LAS unsigned char* lds, const Gemm g, int G, int c, const Epi& E) {
;     ...
;             const bool last = (t == nt - 2);
;             const char* a1 = cA + (size_t)(t + 1) * kstep;
;             const char* a2 = last ? nA : cA + (size_t)(t + 2) * kstep; const char* b2 = last ? nB : cB + (size_t)(t + 2) * kstep;
;             const char* a3 = a2 + kstep; const char* b3 = b2 + kstep;
;             PG8_LDB(B0, 0, 0); PG8_LDB(B1, 0, 1); PG8_SCHED; PG8_LDA(At, 0, 0); PG8_STAGE(PG8_SA(1, 1), a1 + hstepA, voffA);
;             PG8_WAIT_V(8); PG8_WAIT_L(0); PG8_BAR; PG8_MMA(0, 0, At, B0); PG8_MMA(0, 1, At, B1); PG8_BAR; PG8_SCHED;
;             PG8_LDA(At, 0, 1); PG8_STAGE(PG8_SB(0, 0), b2, voffB); PG8_STAGE(PG8_SB(0, 1), b2 + hstepB, voffB); PG8_STAGE(PG8_SA(0, 0), a2, voffA);
;             PG8_WAIT_V(8); PG8_WAIT_L(0); PG8_BAR; PG8_MMA(1, 0, At, B0); PG8_MMA(1, 1, At, B1); PG8_BAR; PG8_SCHED;
.LBB0_780:
	s_ashr_i32 s25, s24, 31
	s_lshl_b64 s[42:43], s[24:25], 18
	s_add_u32 s42, s59, s42
	s_addc_u32 s43, s60, s43
	s_and_b64 s[52:53], s[38:39], exec
	s_cselect_b32 s25, s43, s47
	s_cselect_b32 s89, s42, s46
	s_add_u32 s90, s46, 0x100
	s_addc_u32 s91, s47, 0
	s_mov_b32 s92, -2
	s_mov_b64 s[46:47], 0
	ds_read_b128 v[150:153], v146
	ds_read_b128 v[154:157], v146 offset:1024
	ds_read_b128 v[158:161], v146 offset:2048
	ds_read_b128 v[162:165], v146 offset:3072
	ds_read_b128 v[166:169], v147
	ds_read_b128 v[170:173], v147 offset:1024
	ds_read_b128 v[174:177], v147 offset:2048
	ds_read_b128 v[178:181], v147 offset:3072
	s_add_u32 s52, s46, 0x100
	s_addc_u32 s53, s47, 0
	s_add_u32 s33, s90, s46
	s_addc_u32 s55, s91, s47
	s_cmp_eq_u32 s92, 4
	s_cselect_b32 s56, 0, s52
	s_cselect_b32 s57, 0, s53
	s_cselect_b32 s54, s89, s33
	s_cselect_b32 s55, s25, s55
	s_add_u32 s56, s2, s56
	s_addc_u32 s57, s3, s57
	s_mov_b32 m0, s83
	v_lshl_add_u64 v[142:143], v[138:139], 0, s[46:47]
	ds_read_b128 v[182:185], v148
	ds_read_b128 v[186:189], v148 offset:1024
	ds_read_b128 v[190:193], v148 offset:2048
	ds_read_b128 v[194:197], v148 offset:3072
	ds_read_b128 v[198:201], v148 offset:4096
	ds_read_b128 v[202:205], v148 offset:5120
	ds_read_b128 v[206:209], v148 offset:6144
	ds_read_b128 v[210:213], v148 offset:7168
	global_load_lds_dwordx4 v[142:143], off
	v_lshl_add_u64 v[142:143], v[140:141], 0, s[46:47]
	s_mov_b32 m0, s84
	s_nop 0
	global_load_lds_dwordx4 v[142:143], off
	s_waitcnt vmcnt(8)
	s_waitcnt lgkmcnt(0)
	s_barrier
	s_setprio 0
	v_mfma_f32_16x16x32_bf16 v[126:129], v[150:153], v[182:185], 0
	v_mfma_f32_16x16x32_bf16 v[122:125], v[158:161], v[182:185], 0
	v_mfma_f32_16x16x32_bf16 v[118:121], v[150:153], v[190:193], 0
	v_mfma_f32_16x16x32_bf16 v[110:113], v[158:161], v[190:193], 0
	v_mfma_f32_16x16x32_bf16 v[102:105], v[150:153], v[198:201], 0
	v_mfma_f32_16x16x32_bf16 v[94:97], v[158:161], v[198:201], 0
	v_mfma_f32_16x16x32_bf16 v[86:89], v[150:153], v[206:209], 0
	v_mfma_f32_16x16x32_bf16 v[78:81], v[158:161], v[206:209], 0
	v_mfma_f32_16x16x32_bf16 v[126:129], v[154:157], v[186:189], v[126:129]
	v_mfma_f32_16x16x32_bf16 v[122:125], v[162:165], v[186:189], v[122:125]
	v_mfma_f32_16x16x32_bf16 v[118:121], v[154:157], v[194:197], v[118:121]
	v_mfma_f32_16x16x32_bf16 v[110:113], v[162:165], v[194:197], v[110:113]
	v_mfma_f32_16x16x32_bf16 v[102:105], v[154:157], v[202:205], v[102:105]
	v_mfma_f32_16x16x32_bf16 v[94:97], v[162:165], v[202:205], v[94:97]
	v_mfma_f32_16x16x32_bf16 v[86:89], v[154:157], v[210:213], v[86:89]
	v_mfma_f32_16x16x32_bf16 v[78:81], v[162:165], v[210:213], v[78:81]
	s_setprio 2
	s_setprio 0
	v_mfma_f32_16x16x32_bf16 v[114:117], v[166:169], v[182:185], 0
	v_mfma_f32_16x16x32_bf16 v[106:109], v[174:177], v[182:185], 0
	v_mfma_f32_16x16x32_bf16 v[98:101], v[166:169], v[190:193], 0
	v_mfma_f32_16x16x32_bf16 v[90:93], v[174:177], v[190:193], 0
	v_mfma_f32_16x16x32_bf16 v[82:85], v[166:169], v[198:201], 0
	v_mfma_f32_16x16x32_bf16 v[74:77], v[174:177], v[198:201], 0
	v_mfma_f32_16x16x32_bf16 v[70:73], v[166:169], v[206:209], 0
	v_mfma_f32_16x16x32_bf16 v[66:69], v[174:177], v[206:209], 0
	v_mfma_f32_16x16x32_bf16 v[114:117], v[170:173], v[186:189], v[114:117]
	v_mfma_f32_16x16x32_bf16 v[106:109], v[178:181], v[186:189], v[106:109]
	v_mfma_f32_16x16x32_bf16 v[98:101], v[170:173], v[194:197], v[98:101]
	v_mfma_f32_16x16x32_bf16 v[90:93], v[178:181], v[194:197], v[90:93]
	v_mfma_f32_16x16x32_bf16 v[82:85], v[170:173], v[202:205], v[82:85]
	v_mfma_f32_16x16x32_bf16 v[74:77], v[178:181], v[202:205], v[74:77]
	v_mfma_f32_16x16x32_bf16 v[70:73], v[170:173], v[210:213], v[70:73]
	v_mfma_f32_16x16x32_bf16 v[66:69], v[178:181], v[210:213], v[66:69]
	s_setprio 2
	s_barrier
	s_mov_b32 m0, s85
	v_lshl_add_u64 v[142:143], s[54:55], 0, v[134:135]
	s_add_u32 s46, s54, 0x20000
	ds_read_b128 v[182:185], v148 offset:16384
	ds_read_b128 v[186:189], v148 offset:17408
	ds_read_b128 v[190:193], v148 offset:18432
	ds_read_b128 v[194:197], v148 offset:19456
	ds_read_b128 v[198:201], v148 offset:20480
	ds_read_b128 v[202:205], v148 offset:21504
	ds_read_b128 v[206:209], v148 offset:22528
	ds_read_b128 v[210:213], v148 offset:23552
	global_load_lds_dwordx4 v[142:143], off
	v_lshl_add_u64 v[214:215], s[54:55], 0, v[130:131]
	s_mov_b32 m0, s86
	s_addc_u32 s47, s55, 0
	global_load_lds_dwordx4 v[214:215], off
	v_lshl_add_u64 v[216:217], s[46:47], 0, v[134:135]
	s_mov_b32 m0, s87
	v_lshl_add_u64 v[218:219], s[56:57], 0, v[132:133]
	global_load_lds_dwordx4 v[216:217], off
	v_lshl_add_u64 v[216:217], s[46:47], 0, v[130:131]
	s_mov_b32 m0, s88
	s_nop 0
	global_load_lds_dwordx4 v[216:217], off
	v_lshl_add_u64 v[216:217], s[56:57], 0, v[136:137]
	s_mov_b32 m0, s45
	s_nop 0
	global_load_lds_dwordx4 v[216:217], off
	s_mov_b32 m0, s61
	s_nop 0
	global_load_lds_dwordx4 v[218:219], off
	s_waitcnt vmcnt(8)
	s_waitcnt lgkmcnt(0)
	s_barrier
; #define PG8_STAGE(bufoff, gbase, voff) do { _Pragma("unroll") for (int _i = 0; _i < 2; ++_i) \
;         __builtin_amdgcn_global_load_lds((const unsigned*)((const char*)(gbase) + (voff)[_i]), (LAS unsigned*)(lds + (bufoff) + ldsw + _i * 8192), 16, 0, 0); } while (0)
; #define PG8_LDA(dst, b, h) do { _Pragma("unroll") for (int m = 0; m < 4; ++m) _Pragma("unroll") for (int k = 0; k < 2; ++k) dst[m][k] = *(const LAS bf16x8*)(lds + PG8_SA(b, h) + aoff + m * 2048 + k * 1024); } while (0)
; #define PG8_LDB(dst, b, h) do { _Pragma("unroll") for (int n = 0; n < 2; ++n) _Pragma("unroll") for (int k = 0; k < 2; ++k) dst[n][k] = *(const LAS bf16x8*)(lds + PG8_SB(b, h) + boff + n * 2048 + k * 1024); } while (0)
; #define PG8_MMA(ai, bj, At, Bt) do { __builtin_amdgcn_s_setprio(1); _Pragma("unroll") for (int m = 0; m < 4; ++m) _Pragma("unroll") for (int n = 0; n < 2; ++n) _Pragma("unroll") for (int k = 0; k < 2; ++k) \
;         acc[ai][bj][m][n] = __builtin_amdgcn_mfma_f32_16x16x32_bf16(Bt[n][k], At[m][k], acc[ai][bj][m][n], 0, 0, 0); __builtin_amdgcn_s_setprio(0); } while (0)
; #define PG8_WAIT_V(n) asm volatile("s_waitcnt vmcnt(" #n ")" ::: "memory")
; #define PG8_WAIT_L(n) asm volatile("s_waitcnt lgkmcnt(" #n ")" ::: "memory")
; #define PG8_BAR __builtin_amdgcn_s_barrier()
; #define PG8_SCHED __builtin_amdgcn_sched_barrier(0)
; template <class Epi>
; __device__ __forceinline__ void gemm_phase(LAS unsigned char* lds, const Gemm g, int G, int c, const Epi& E) {
;     ...
;             PG8_WAIT_V(8); PG8_WAIT_L(0); PG8_BAR; PG8_MMA(1, 0, At, B0); PG8_MMA(1, 1, At, B1); PG8_BAR; PG8_SCHED;
;             PG8_LDB(B0, 1, 0); PG8_LDB(B1, 1, 1); PG8_SCHED; PG8_LDA(At, 1, 0); PG8_STAGE(PG8_SA(0, 1), a2 + hstepA, voffA);
;             PG8_WAIT_V(8); PG8_WAIT_L(0); PG8_BAR; PG8_MMA(0, 0, At, B0); PG8_MMA(0, 1, At, B1); PG8_BAR; PG8_SCHED;
;             PG8_LDA(At, 1, 1); PG8_STAGE(PG8_SB(1, 0), b3, voffB); PG8_STAGE(PG8_SB(1, 1), b3 + hstepB, voffB); PG8_STAGE(PG8_SA(1, 0), a3, voffA);
	s_setprio 0
	v_mfma_f32_16x16x32_bf16 v[62:65], v[150:153], v[182:185], 0
	v_mfma_f32_16x16x32_bf16 v[58:61], v[158:161], v[182:185], 0
	v_mfma_f32_16x16x32_bf16 v[54:57], v[150:153], v[190:193], 0
	v_mfma_f32_16x16x32_bf16 v[46:49], v[158:161], v[190:193], 0
	v_mfma_f32_16x16x32_bf16 v[38:41], v[150:153], v[198:201], 0
	v_mfma_f32_16x16x32_bf16 v[30:33], v[158:161], v[198:201], 0
	v_mfma_f32_16x16x32_bf16 v[22:25], v[150:153], v[206:209], 0
	v_mfma_f32_16x16x32_bf16 v[14:17], v[158:161], v[206:209], 0
	v_mfma_f32_16x16x32_bf16 v[62:65], v[154:157], v[186:189], v[62:65]
	v_mfma_f32_16x16x32_bf16 v[58:61], v[162:165], v[186:189], v[58:61]
	v_mfma_f32_16x16x32_bf16 v[54:57], v[154:157], v[194:197], v[54:57]
	v_mfma_f32_16x16x32_bf16 v[46:49], v[162:165], v[194:197], v[46:49]
	v_mfma_f32_16x16x32_bf16 v[38:41], v[154:157], v[202:205], v[38:41]
	v_mfma_f32_16x16x32_bf16 v[30:33], v[162:165], v[202:205], v[30:33]
	v_mfma_f32_16x16x32_bf16 v[22:25], v[154:157], v[210:213], v[22:25]
	v_mfma_f32_16x16x32_bf16 v[14:17], v[162:165], v[210:213], v[14:17]
	s_setprio 2
	s_setprio 0
	v_mfma_f32_16x16x32_bf16 v[50:53], v[166:169], v[182:185], 0
	v_mfma_f32_16x16x32_bf16 v[42:45], v[174:177], v[182:185], 0
	v_mfma_f32_16x16x32_bf16 v[34:37], v[166:169], v[190:193], 0
	v_mfma_f32_16x16x32_bf16 v[26:29], v[174:177], v[190:193], 0
	v_mfma_f32_16x16x32_bf16 v[18:21], v[166:169], v[198:201], 0
	v_mfma_f32_16x16x32_bf16 v[10:13], v[174:177], v[198:201], 0
	v_mfma_f32_16x16x32_bf16 v[6:9], v[166:169], v[206:209], 0
	v_mfma_f32_16x16x32_bf16 v[2:5], v[174:177], v[206:209], 0
	v_mfma_f32_16x16x32_bf16 v[50:53], v[170:173], v[186:189], v[50:53]
	v_mfma_f32_16x16x32_bf16 v[42:45], v[178:181], v[186:189], v[42:45]
	v_mfma_f32_16x16x32_bf16 v[34:37], v[170:173], v[194:197], v[34:37]
	v_mfma_f32_16x16x32_bf16 v[26:29], v[178:181], v[194:197], v[26:29]
	v_mfma_f32_16x16x32_bf16 v[18:21], v[170:173], v[202:205], v[18:21]
	v_mfma_f32_16x16x32_bf16 v[10:13], v[178:181], v[202:205], v[10:13]
	v_mfma_f32_16x16x32_bf16 v[6:9], v[170:173], v[210:213], v[6:9]
	v_mfma_f32_16x16x32_bf16 v[2:5], v[178:181], v[210:213], v[2:5]
	s_setprio 2
	s_barrier
	s_add_i32 s33, 0, 0x18000
	v_add_u32_e32 v149, s33, v145
	s_add_i32 s62, 0, 0x1c000
	ds_read_b128 v[150:153], v149
	ds_read_b128 v[154:157], v149 offset:1024
	ds_read_b128 v[158:161], v149 offset:2048
	ds_read_b128 v[162:165], v149 offset:3072
	v_add_u32_e32 v149, s62, v145
	ds_read_b128 v[166:169], v149
	ds_read_b128 v[170:173], v149 offset:1024
	ds_read_b128 v[174:177], v149 offset:2048
	ds_read_b128 v[178:181], v149 offset:3072
	s_add_u32 s46, s56, 0x20000
	s_addc_u32 s47, s57, 0
	s_mov_b32 m0, s66
	v_lshl_add_u64 v[220:221], s[46:47], 0, v[136:137]
	ds_read_b128 v[182:185], v148 offset:32768
	ds_read_b128 v[186:189], v148 offset:33792
	ds_read_b128 v[190:193], v148 offset:34816
	ds_read_b128 v[194:197], v148 offset:35840
	ds_read_b128 v[198:201], v148 offset:36864
	ds_read_b128 v[202:205], v148 offset:37888
	ds_read_b128 v[206:209], v148 offset:38912
	ds_read_b128 v[210:213], v148 offset:39936
	global_load_lds_dwordx4 v[220:221], off
	v_lshl_add_u64 v[220:221], s[46:47], 0, v[132:133]
	s_mov_b32 m0, s67
	s_nop 0
	global_load_lds_dwordx4 v[220:221], off
	s_waitcnt vmcnt(8)
	s_waitcnt lgkmcnt(0)
	s_barrier
	s_setprio 0
	v_mfma_f32_16x16x32_bf16 v[126:129], v[150:153], v[182:185], v[126:129]
	v_mfma_f32_16x16x32_bf16 v[122:125], v[158:161], v[182:185], v[122:125]
	v_mfma_f32_16x16x32_bf16 v[118:121], v[150:153], v[190:193], v[118:121]
	v_mfma_f32_16x16x32_bf16 v[110:113], v[158:161], v[190:193], v[110:113]
	v_mfma_f32_16x16x32_bf16 v[102:105], v[150:153], v[198:201], v[102:105]
	v_mfma_f32_16x16x32_bf16 v[94:97], v[158:161], v[198:201], v[94:97]
	v_mfma_f32_16x16x32_bf16 v[86:89], v[150:153], v[206:209], v[86:89]
	v_mfma_f32_16x16x32_bf16 v[78:81], v[158:161], v[206:209], v[78:81]
	v_mfma_f32_16x16x32_bf16 v[126:129], v[154:157], v[186:189], v[126:129]
	v_mfma_f32_16x16x32_bf16 v[122:125], v[162:165], v[186:189], v[122:125]
	v_mfma_f32_16x16x32_bf16 v[118:121], v[154:157], v[194:197], v[118:121]
	v_mfma_f32_16x16x32_bf16 v[110:113], v[162:165], v[194:197], v[110:113]
	v_mfma_f32_16x16x32_bf16 v[102:105], v[154:157], v[202:205], v[102:105]
	v_mfma_f32_16x16x32_bf16 v[94:97], v[162:165], v[202:205], v[94:97]
	v_mfma_f32_16x16x32_bf16 v[86:89], v[154:157], v[210:213], v[86:89]
	v_mfma_f32_16x16x32_bf16 v[78:81], v[162:165], v[210:213], v[78:81]
	s_setprio 2
	s_setprio 0
	v_mfma_f32_16x16x32_bf16 v[114:117], v[166:169], v[182:185], v[114:117]
	v_mfma_f32_16x16x32_bf16 v[106:109], v[174:177], v[182:185], v[106:109]
	v_mfma_f32_16x16x32_bf16 v[98:101], v[166:169], v[190:193], v[98:101]
	v_mfma_f32_16x16x32_bf16 v[90:93], v[174:177], v[190:193], v[90:93]
	v_mfma_f32_16x16x32_bf16 v[82:85], v[166:169], v[198:201], v[82:85]
	v_mfma_f32_16x16x32_bf16 v[74:77], v[174:177], v[198:201], v[74:77]
	v_mfma_f32_16x16x32_bf16 v[70:73], v[166:169], v[206:209], v[70:73]
	v_mfma_f32_16x16x32_bf16 v[66:69], v[174:177], v[206:209], v[66:69]
	v_mfma_f32_16x16x32_bf16 v[114:117], v[170:173], v[186:189], v[114:117]
	v_mfma_f32_16x16x32_bf16 v[106:109], v[178:181], v[186:189], v[106:109]
	v_mfma_f32_16x16x32_bf16 v[98:101], v[170:173], v[194:197], v[98:101]
	v_mfma_f32_16x16x32_bf16 v[90:93], v[178:181], v[194:197], v[90:93]
	v_mfma_f32_16x16x32_bf16 v[82:85], v[170:173], v[202:205], v[82:85]
	v_mfma_f32_16x16x32_bf16 v[74:77], v[178:181], v[202:205], v[74:77]
	v_mfma_f32_16x16x32_bf16 v[70:73], v[170:173], v[210:213], v[70:73]
	v_mfma_f32_16x16x32_bf16 v[66:69], v[178:181], v[210:213], v[66:69]
	s_setprio 2
	s_barrier
; #define PG8_STAGE(bufoff, gbase, voff) do { _Pragma("unroll") for (int _i = 0; _i < 2; ++_i) \
;         __builtin_amdgcn_global_load_lds((const unsigned*)((const char*)(gbase) + (voff)[_i]), (LAS unsigned*)(lds + (bufoff) + ldsw + _i * 8192), 16, 0, 0); } while (0)
; #define PG8_LDA(dst, b, h) do { _Pragma("unroll") for (int m = 0; m < 4; ++m) _Pragma("unroll") for (int k = 0; k < 2; ++k) dst[m][k] = *(const LAS bf16x8*)(lds + PG8_SA(b, h) + aoff + m * 2048 + k * 1024); } while (0)
; #define PG8_LDB(dst, b, h) do { _Pragma("unroll") for (int n = 0; n < 2; ++n) _Pragma("unroll") for (int k = 0; k < 2; ++k) dst[n][k] = *(const LAS bf16x8*)(lds + PG8_SB(b, h) + boff + n * 2048 + k * 1024); } while (0)
; #define PG8_MMA(ai, bj, At, Bt) do { __builtin_amdgcn_s_setprio(1); _Pragma("unroll") for (int m = 0; m < 4; ++m) _Pragma("unroll") for (int n = 0; n < 2; ++n) _Pragma("unroll") for (int k = 0; k < 2; ++k) \
;         acc[ai][bj][m][n] = __builtin_amdgcn_mfma_f32_16x16x32_bf16(Bt[n][k], At[m][k], acc[ai][bj][m][n], 0, 0, 0); __builtin_amdgcn_s_setprio(0); } while (0)
; #define PG8_WAIT_V(n) asm volatile("s_waitcnt vmcnt(" #n ")" ::: "memory")
; #define PG8_WAIT_L(n) asm volatile("s_waitcnt lgkmcnt(" #n ")" ::: "memory")
; #define PG8_BAR __builtin_amdgcn_s_barrier()
; #define PG8_SCHED __builtin_amdgcn_sched_barrier(0)
; template <class Epi>
; __device__ __forceinline__ void gemm_phase(LAS unsigned char* lds, const Gemm g, int G, int c, const Epi& E) {
;     ...
;             const bool last = (t == nt - 2);
;             const char* a1 = cA + (size_t)(t + 1) * kstep;
;             const char* a2 = last ? nA : cA + (size_t)(t + 2) * kstep; const char* b2 = last ? nB : cB + (size_t)(t + 2) * kstep;
;             const char* a3 = a2 + kstep; const char* b3 = b2 + kstep;
;             PG8_LDB(B0, 0, 0); PG8_LDB(B1, 0, 1); PG8_SCHED; PG8_LDA(At, 0, 0); PG8_STAGE(PG8_SA(1, 1), a1 + hstepA, voffA);
;     ...
;             PG8_LDA(At, 1, 1); PG8_STAGE(PG8_SB(1, 0), b3, voffB); PG8_STAGE(PG8_SB(1, 1), b3 + hstepB, voffB); PG8_STAGE(PG8_SA(1, 0), a3, voffA);
;             PG8_WAIT_V(8); PG8_WAIT_L(0); PG8_BAR; PG8_MMA(1, 0, At, B0); PG8_MMA(1, 1, At, B1); PG8_BAR; PG8_SCHED;
	s_add_i32 s33, s33, s58
	v_lshl_add_u64 v[142:143], v[142:143], 0, s[6:7]
	s_mov_b32 m0, s33
	ds_read_b128 v[182:185], v148 offset:49152
	ds_read_b128 v[186:189], v148 offset:50176
	ds_read_b128 v[190:193], v148 offset:51200
	ds_read_b128 v[194:197], v148 offset:52224
	ds_read_b128 v[198:201], v148 offset:53248
	ds_read_b128 v[202:205], v148 offset:54272
	ds_read_b128 v[206:209], v148 offset:55296
	ds_read_b128 v[210:213], v148 offset:56320
	global_load_lds_dwordx4 v[142:143], off
	s_add_i32 m0, s33, 0x2000
	s_add_u32 s46, s54, 0x20080
	v_lshl_add_u64 v[142:143], v[214:215], 0, s[6:7]
	s_addc_u32 s47, s55, 0
	s_add_i32 s33, s62, s58
	global_load_lds_dwordx4 v[142:143], off
	v_lshl_add_u64 v[142:143], s[46:47], 0, v[134:135]
	s_mov_b32 m0, s33
	s_nop 0
	global_load_lds_dwordx4 v[142:143], off
	v_lshl_add_u64 v[142:143], s[46:47], 0, v[130:131]
	s_add_i32 m0, s33, 0x2000
	s_nop 0
	global_load_lds_dwordx4 v[142:143], off
	v_lshl_add_u64 v[142:143], v[216:217], 0, s[6:7]
	s_mov_b32 m0, s71
	s_nop 0
	global_load_lds_dwordx4 v[142:143], off
	v_lshl_add_u64 v[142:143], v[218:219], 0, s[6:7]
	s_mov_b32 m0, s72
	s_nop 0
	global_load_lds_dwordx4 v[142:143], off
	s_waitcnt vmcnt(8)
	s_waitcnt lgkmcnt(0)
	s_barrier
	s_setprio 0
	v_mfma_f32_16x16x32_bf16 v[62:65], v[150:153], v[182:185], v[62:65]
	v_mfma_f32_16x16x32_bf16 v[58:61], v[158:161], v[182:185], v[58:61]
	v_mfma_f32_16x16x32_bf16 v[54:57], v[150:153], v[190:193], v[54:57]
	v_mfma_f32_16x16x32_bf16 v[46:49], v[158:161], v[190:193], v[46:49]
	v_mfma_f32_16x16x32_bf16 v[38:41], v[150:153], v[198:201], v[38:41]
	v_mfma_f32_16x16x32_bf16 v[30:33], v[158:161], v[198:201], v[30:33]
	v_mfma_f32_16x16x32_bf16 v[22:25], v[150:153], v[206:209], v[22:25]
	v_mfma_f32_16x16x32_bf16 v[14:17], v[158:161], v[206:209], v[14:17]
	v_mfma_f32_16x16x32_bf16 v[62:65], v[154:157], v[186:189], v[62:65]
	v_mfma_f32_16x16x32_bf16 v[58:61], v[162:165], v[186:189], v[58:61]
	v_mfma_f32_16x16x32_bf16 v[54:57], v[154:157], v[194:197], v[54:57]
	v_mfma_f32_16x16x32_bf16 v[46:49], v[162:165], v[194:197], v[46:49]
	v_mfma_f32_16x16x32_bf16 v[38:41], v[154:157], v[202:205], v[38:41]
	v_mfma_f32_16x16x32_bf16 v[30:33], v[162:165], v[202:205], v[30:33]
	v_mfma_f32_16x16x32_bf16 v[22:25], v[154:157], v[210:213], v[22:25]
	v_mfma_f32_16x16x32_bf16 v[14:17], v[162:165], v[210:213], v[14:17]
	s_setprio 2
	s_setprio 0
	v_mfma_f32_16x16x32_bf16 v[50:53], v[166:169], v[182:185], v[50:53]
	v_mfma_f32_16x16x32_bf16 v[42:45], v[174:177], v[182:185], v[42:45]
	v_mfma_f32_16x16x32_bf16 v[34:37], v[166:169], v[190:193], v[34:37]
	v_mfma_f32_16x16x32_bf16 v[26:29], v[174:177], v[190:193], v[26:29]
	v_mfma_f32_16x16x32_bf16 v[18:21], v[166:169], v[198:201], v[18:21]
	v_mfma_f32_16x16x32_bf16 v[10:13], v[174:177], v[198:201], v[10:13]
	v_mfma_f32_16x16x32_bf16 v[6:9], v[166:169], v[206:209], v[6:9]
	v_mfma_f32_16x16x32_bf16 v[2:5], v[174:177], v[206:209], v[2:5]
	v_mfma_f32_16x16x32_bf16 v[50:53], v[170:173], v[186:189], v[50:53]
	v_mfma_f32_16x16x32_bf16 v[42:45], v[178:181], v[186:189], v[42:45]
	v_mfma_f32_16x16x32_bf16 v[34:37], v[170:173], v[194:197], v[34:37]
	v_mfma_f32_16x16x32_bf16 v[26:29], v[178:181], v[194:197], v[26:29]
	v_mfma_f32_16x16x32_bf16 v[18:21], v[170:173], v[202:205], v[18:21]
	v_mfma_f32_16x16x32_bf16 v[10:13], v[178:181], v[202:205], v[10:13]
	v_mfma_f32_16x16x32_bf16 v[6:9], v[170:173], v[210:213], v[6:9]
	v_mfma_f32_16x16x32_bf16 v[2:5], v[178:181], v[210:213], v[2:5]
	s_setprio 2
	s_barrier
	s_add_i32 s92, s92, 2
	s_cmp_gt_u32 s92, 5
	s_mov_b64 s[46:47], s[52:53]
	s_cbranch_scc0 .LBB0_781
.LBB0_781:
	ds_read_b128 v[150:153], v146
	ds_read_b128 v[154:157], v146 offset:1024
	ds_read_b128 v[158:161], v146 offset:2048
	ds_read_b128 v[162:165], v146 offset:3072
	ds_read_b128 v[166:169], v147
	ds_read_b128 v[170:173], v147 offset:1024
	ds_read_b128 v[174:177], v147 offset:2048
	ds_read_b128 v[178:181], v147 offset:3072
	s_add_u32 s52, s46, 0x100
	s_addc_u32 s53, s47, 0
	s_add_u32 s33, s90, s46
	s_addc_u32 s55, s91, s47
	s_cmp_eq_u32 s92, 4
	s_cselect_b32 s56, 0, s52
	s_cselect_b32 s57, 0, s53
	s_cselect_b32 s54, s89, s33
	s_cselect_b32 s55, s25, s55
	s_add_u32 s56, s2, s56
	s_addc_u32 s57, s3, s57
	s_mov_b32 m0, s83
	v_lshl_add_u64 v[142:143], v[138:139], 0, s[46:47]
	ds_read_b128 v[182:185], v148
	ds_read_b128 v[186:189], v148 offset:1024
	ds_read_b128 v[190:193], v148 offset:2048
	ds_read_b128 v[194:197], v148 offset:3072
	ds_read_b128 v[198:201], v148 offset:4096
	ds_read_b128 v[202:205], v148 offset:5120
	ds_read_b128 v[206:209], v148 offset:6144
	ds_read_b128 v[210:213], v148 offset:7168
	global_load_lds_dwordx4 v[142:143], off
	v_lshl_add_u64 v[142:143], v[140:141], 0, s[46:47]
	s_mov_b32 m0, s84
	s_nop 0
	global_load_lds_dwordx4 v[142:143], off
	s_waitcnt vmcnt(8)
	s_waitcnt lgkmcnt(0)
	s_barrier
; #define PG8_STAGE(bufoff, gbase, voff) do { _Pragma("unroll") for (int _i = 0; _i < 2; ++_i) \
;         __builtin_amdgcn_global_load_lds((const unsigned*)((const char*)(gbase) + (voff)[_i]), (LAS unsigned*)(lds + (bufoff) + ldsw + _i * 8192), 16, 0, 0); } while (0)
; #define PG8_LDA(dst, b, h) do { _Pragma("unroll") for (int m = 0; m < 4; ++m) _Pragma("unroll") for (int k = 0; k < 2; ++k) dst[m][k] = *(const LAS bf16x8*)(lds + PG8_SA(b, h) + aoff + m * 2048 + k * 1024); } while (0)
; #define PG8_MMA(ai, bj, At, Bt) do { __builtin_amdgcn_s_setprio(1); _Pragma("unroll") for (int m = 0; m < 4; ++m) _Pragma("unroll") for (int n = 0; n < 2; ++n) _Pragma("unroll") for (int k = 0; k < 2; ++k) \
;         acc[ai][bj][m][n] = __builtin_amdgcn_mfma_f32_16x16x32_bf16(Bt[n][k], At[m][k], acc[ai][bj][m][n], 0, 0, 0); __builtin_amdgcn_s_setprio(0); } while (0)
; #define PG8_WAIT_V(n) asm volatile("s_waitcnt vmcnt(" #n ")" ::: "memory")
; #define PG8_WAIT_L(n) asm volatile("s_waitcnt lgkmcnt(" #n ")" ::: "memory")
; #define PG8_BAR __builtin_amdgcn_s_barrier()
; #define PG8_SCHED __builtin_amdgcn_sched_barrier(0)
; template <class Epi>
; __device__ __forceinline__ void gemm_phase(LAS unsigned char* lds, const Gemm g, int G, int c, const Epi& E) {
;     ...
;             PG8_WAIT_V(8); PG8_WAIT_L(0); PG8_BAR; PG8_MMA(0, 0, At, B0); PG8_MMA(0, 1, At, B1); PG8_BAR; PG8_SCHED;
;             PG8_LDA(At, 0, 1); PG8_STAGE(PG8_SB(0, 0), b2, voffB); PG8_STAGE(PG8_SB(0, 1), b2 + hstepB, voffB); PG8_STAGE(PG8_SA(0, 0), a2, voffA);
;             PG8_WAIT_V(8); PG8_WAIT_L(0); PG8_BAR; PG8_MMA(1, 0, At, B0); PG8_MMA(1, 1, At, B1); PG8_BAR; PG8_SCHED;
	s_setprio 0
	v_mfma_f32_16x16x32_bf16 v[126:129], v[150:153], v[182:185], v[126:129]
	v_mfma_f32_16x16x32_bf16 v[122:125], v[158:161], v[182:185], v[122:125]
	v_mfma_f32_16x16x32_bf16 v[118:121], v[150:153], v[190:193], v[118:121]
	v_mfma_f32_16x16x32_bf16 v[110:113], v[158:161], v[190:193], v[110:113]
	v_mfma_f32_16x16x32_bf16 v[102:105], v[150:153], v[198:201], v[102:105]
	v_mfma_f32_16x16x32_bf16 v[94:97], v[158:161], v[198:201], v[94:97]
	v_mfma_f32_16x16x32_bf16 v[86:89], v[150:153], v[206:209], v[86:89]
	v_mfma_f32_16x16x32_bf16 v[78:81], v[158:161], v[206:209], v[78:81]
	v_mfma_f32_16x16x32_bf16 v[126:129], v[154:157], v[186:189], v[126:129]
	v_mfma_f32_16x16x32_bf16 v[122:125], v[162:165], v[186:189], v[122:125]
	v_mfma_f32_16x16x32_bf16 v[118:121], v[154:157], v[194:197], v[118:121]
	v_mfma_f32_16x16x32_bf16 v[110:113], v[162:165], v[194:197], v[110:113]
	v_mfma_f32_16x16x32_bf16 v[102:105], v[154:157], v[202:205], v[102:105]
	v_mfma_f32_16x16x32_bf16 v[94:97], v[162:165], v[202:205], v[94:97]
	v_mfma_f32_16x16x32_bf16 v[86:89], v[154:157], v[210:213], v[86:89]
	v_mfma_f32_16x16x32_bf16 v[78:81], v[162:165], v[210:213], v[78:81]
	s_setprio 2
	s_setprio 0
	v_mfma_f32_16x16x32_bf16 v[114:117], v[166:169], v[182:185], v[114:117]
	v_mfma_f32_16x16x32_bf16 v[106:109], v[174:177], v[182:185], v[106:109]
	v_mfma_f32_16x16x32_bf16 v[98:101], v[166:169], v[190:193], v[98:101]
	v_mfma_f32_16x16x32_bf16 v[90:93], v[174:177], v[190:193], v[90:93]
	v_mfma_f32_16x16x32_bf16 v[82:85], v[166:169], v[198:201], v[82:85]
	v_mfma_f32_16x16x32_bf16 v[74:77], v[174:177], v[198:201], v[74:77]
	v_mfma_f32_16x16x32_bf16 v[70:73], v[166:169], v[206:209], v[70:73]
	v_mfma_f32_16x16x32_bf16 v[66:69], v[174:177], v[206:209], v[66:69]
	v_mfma_f32_16x16x32_bf16 v[114:117], v[170:173], v[186:189], v[114:117]
	v_mfma_f32_16x16x32_bf16 v[106:109], v[178:181], v[186:189], v[106:109]
	v_mfma_f32_16x16x32_bf16 v[98:101], v[170:173], v[194:197], v[98:101]
	v_mfma_f32_16x16x32_bf16 v[90:93], v[178:181], v[194:197], v[90:93]
	v_mfma_f32_16x16x32_bf16 v[82:85], v[170:173], v[202:205], v[82:85]
	v_mfma_f32_16x16x32_bf16 v[74:77], v[178:181], v[202:205], v[74:77]
	v_mfma_f32_16x16x32_bf16 v[70:73], v[170:173], v[210:213], v[70:73]
	v_mfma_f32_16x16x32_bf16 v[66:69], v[178:181], v[210:213], v[66:69]
	s_setprio 2
	s_barrier
	s_mov_b32 m0, s85
	v_lshl_add_u64 v[142:143], s[54:55], 0, v[134:135]
	s_add_u32 s46, s54, 0x20000
	ds_read_b128 v[182:185], v148 offset:16384
	ds_read_b128 v[186:189], v148 offset:17408
	ds_read_b128 v[190:193], v148 offset:18432
	ds_read_b128 v[194:197], v148 offset:19456
	ds_read_b128 v[198:201], v148 offset:20480
	ds_read_b128 v[202:205], v148 offset:21504
	ds_read_b128 v[206:209], v148 offset:22528
	ds_read_b128 v[210:213], v148 offset:23552
	global_load_lds_dwordx4 v[142:143], off
	v_lshl_add_u64 v[214:215], s[54:55], 0, v[130:131]
	s_mov_b32 m0, s86
	s_addc_u32 s47, s55, 0
	global_load_lds_dwordx4 v[214:215], off
	v_lshl_add_u64 v[216:217], s[46:47], 0, v[134:135]
	s_mov_b32 m0, s87
	v_lshl_add_u64 v[218:219], s[56:57], 0, v[132:133]
	global_load_lds_dwordx4 v[216:217], off
	v_lshl_add_u64 v[216:217], s[46:47], 0, v[130:131]
	s_mov_b32 m0, s88
	s_nop 0
	global_load_lds_dwordx4 v[216:217], off
	v_lshl_add_u64 v[216:217], s[56:57], 0, v[136:137]
	s_mov_b32 m0, s45
	s_nop 0
	global_load_lds_dwordx4 v[216:217], off
	s_mov_b32 m0, s61
	s_nop 0
	global_load_lds_dwordx4 v[218:219], off
	s_waitcnt vmcnt(8)
	s_waitcnt lgkmcnt(0)
	s_barrier
	s_setprio 0
	v_mfma_f32_16x16x32_bf16 v[62:65], v[150:153], v[182:185], v[62:65]
	v_mfma_f32_16x16x32_bf16 v[58:61], v[158:161], v[182:185], v[58:61]
	v_mfma_f32_16x16x32_bf16 v[54:57], v[150:153], v[190:193], v[54:57]
	v_mfma_f32_16x16x32_bf16 v[46:49], v[158:161], v[190:193], v[46:49]
	v_mfma_f32_16x16x32_bf16 v[38:41], v[150:153], v[198:201], v[38:41]
	v_mfma_f32_16x16x32_bf16 v[30:33], v[158:161], v[198:201], v[30:33]
	v_mfma_f32_16x16x32_bf16 v[22:25], v[150:153], v[206:209], v[22:25]
	v_mfma_f32_16x16x32_bf16 v[14:17], v[158:161], v[206:209], v[14:17]
	v_mfma_f32_16x16x32_bf16 v[62:65], v[154:157], v[186:189], v[62:65]
	v_mfma_f32_16x16x32_bf16 v[58:61], v[162:165], v[186:189], v[58:61]
	v_mfma_f32_16x16x32_bf16 v[54:57], v[154:157], v[194:197], v[54:57]
	v_mfma_f32_16x16x32_bf16 v[46:49], v[162:165], v[194:197], v[46:49]
	v_mfma_f32_16x16x32_bf16 v[38:41], v[154:157], v[202:205], v[38:41]
	v_mfma_f32_16x16x32_bf16 v[30:33], v[162:165], v[202:205], v[30:33]
	v_mfma_f32_16x16x32_bf16 v[22:25], v[154:157], v[210:213], v[22:25]
	v_mfma_f32_16x16x32_bf16 v[14:17], v[162:165], v[210:213], v[14:17]
	s_setprio 2
	s_setprio 0
	v_mfma_f32_16x16x32_bf16 v[50:53], v[166:169], v[182:185], v[50:53]
	v_mfma_f32_16x16x32_bf16 v[42:45], v[174:177], v[182:185], v[42:45]
	v_mfma_f32_16x16x32_bf16 v[34:37], v[166:169], v[190:193], v[34:37]
	v_mfma_f32_16x16x32_bf16 v[26:29], v[174:177], v[190:193], v[26:29]
	v_mfma_f32_16x16x32_bf16 v[18:21], v[166:169], v[198:201], v[18:21]
	v_mfma_f32_16x16x32_bf16 v[10:13], v[174:177], v[198:201], v[10:13]
	v_mfma_f32_16x16x32_bf16 v[6:9], v[166:169], v[206:209], v[6:9]
	v_mfma_f32_16x16x32_bf16 v[2:5], v[174:177], v[206:209], v[2:5]
	v_mfma_f32_16x16x32_bf16 v[50:53], v[170:173], v[186:189], v[50:53]
	v_mfma_f32_16x16x32_bf16 v[42:45], v[178:181], v[186:189], v[42:45]
	v_mfma_f32_16x16x32_bf16 v[34:37], v[170:173], v[194:197], v[34:37]
	v_mfma_f32_16x16x32_bf16 v[26:29], v[178:181], v[194:197], v[26:29]
	v_mfma_f32_16x16x32_bf16 v[18:21], v[170:173], v[202:205], v[18:21]
	v_mfma_f32_16x16x32_bf16 v[10:13], v[178:181], v[202:205], v[10:13]
	v_mfma_f32_16x16x32_bf16 v[6:9], v[170:173], v[210:213], v[6:9]
	v_mfma_f32_16x16x32_bf16 v[2:5], v[178:181], v[210:213], v[2:5]
	s_setprio 2
	s_barrier
; #define PG8_STAGE(bufoff, gbase, voff) do { _Pragma("unroll") for (int _i = 0; _i < 2; ++_i) \
;         __builtin_amdgcn_global_load_lds((const unsigned*)((const char*)(gbase) + (voff)[_i]), (LAS unsigned*)(lds + (bufoff) + ldsw + _i * 8192), 16, 0, 0); } while (0)
; #define PG8_LDA(dst, b, h) do { _Pragma("unroll") for (int m = 0; m < 4; ++m) _Pragma("unroll") for (int k = 0; k < 2; ++k) dst[m][k] = *(const LAS bf16x8*)(lds + PG8_SA(b, h) + aoff + m * 2048 + k * 1024); } while (0)
; #define PG8_LDB(dst, b, h) do { _Pragma("unroll") for (int n = 0; n < 2; ++n) _Pragma("unroll") for (int k = 0; k < 2; ++k) dst[n][k] = *(const LAS bf16x8*)(lds + PG8_SB(b, h) + boff + n * 2048 + k * 1024); } while (0)
; #define PG8_MMA(ai, bj, At, Bt) do { __builtin_amdgcn_s_setprio(1); _Pragma("unroll") for (int m = 0; m < 4; ++m) _Pragma("unroll") for (int n = 0; n < 2; ++n) _Pragma("unroll") for (int k = 0; k < 2; ++k) \
;         acc[ai][bj][m][n] = __builtin_amdgcn_mfma_f32_16x16x32_bf16(Bt[n][k], At[m][k], acc[ai][bj][m][n], 0, 0, 0); __builtin_amdgcn_s_setprio(0); } while (0)
; #define PG8_WAIT_V(n) asm volatile("s_waitcnt vmcnt(" #n ")" ::: "memory")
; #define PG8_WAIT_L(n) asm volatile("s_waitcnt lgkmcnt(" #n ")" ::: "memory")
; #define PG8_BAR __builtin_amdgcn_s_barrier()
; #define PG8_SCHED __builtin_amdgcn_sched_barrier(0)
; template <class Epi>
; __device__ __forceinline__ void gemm_phase(LAS unsigned char* lds, const Gemm g, int G, int c, const Epi& E) {
;     ...
;             PG8_LDB(B0, 1, 0); PG8_LDB(B1, 1, 1); PG8_SCHED; PG8_LDA(At, 1, 0); PG8_STAGE(PG8_SA(0, 1), a2 + hstepA, voffA);
;             PG8_WAIT_V(8); PG8_WAIT_L(0); PG8_BAR; PG8_MMA(0, 0, At, B0); PG8_MMA(0, 1, At, B1); PG8_BAR; PG8_SCHED;
	s_add_i32 s33, 0, 0x18000
	v_add_u32_e32 v149, s33, v145
	s_add_i32 s62, 0, 0x1c000
	ds_read_b128 v[150:153], v149
	ds_read_b128 v[154:157], v149 offset:1024
	ds_read_b128 v[158:161], v149 offset:2048
	ds_read_b128 v[162:165], v149 offset:3072
	v_add_u32_e32 v149, s62, v145
	ds_read_b128 v[166:169], v149
	ds_read_b128 v[170:173], v149 offset:1024
	ds_read_b128 v[174:177], v149 offset:2048
	ds_read_b128 v[178:181], v149 offset:3072
	s_add_u32 s46, s56, 0x20000
	s_addc_u32 s47, s57, 0
	s_mov_b32 m0, s66
	v_lshl_add_u64 v[220:221], s[46:47], 0, v[136:137]
	ds_read_b128 v[182:185], v148 offset:32768
	ds_read_b128 v[186:189], v148 offset:33792
	ds_read_b128 v[190:193], v148 offset:34816
	ds_read_b128 v[194:197], v148 offset:35840
	ds_read_b128 v[198:201], v148 offset:36864
	ds_read_b128 v[202:205], v148 offset:37888
	ds_read_b128 v[206:209], v148 offset:38912
	ds_read_b128 v[210:213], v148 offset:39936
	global_load_lds_dwordx4 v[220:221], off
	v_lshl_add_u64 v[220:221], s[46:47], 0, v[132:133]
	s_mov_b32 m0, s67
	s_nop 0
	global_load_lds_dwordx4 v[220:221], off
	s_waitcnt vmcnt(8)
	s_waitcnt lgkmcnt(0)
	s_barrier
	s_setprio 0
	v_mfma_f32_16x16x32_bf16 v[126:129], v[150:153], v[182:185], v[126:129]
	v_mfma_f32_16x16x32_bf16 v[122:125], v[158:161], v[182:185], v[122:125]
	v_mfma_f32_16x16x32_bf16 v[118:121], v[150:153], v[190:193], v[118:121]
	v_mfma_f32_16x16x32_bf16 v[110:113], v[158:161], v[190:193], v[110:113]
	v_mfma_f32_16x16x32_bf16 v[102:105], v[150:153], v[198:201], v[102:105]
	v_mfma_f32_16x16x32_bf16 v[94:97], v[158:161], v[198:201], v[94:97]
	v_mfma_f32_16x16x32_bf16 v[86:89], v[150:153], v[206:209], v[86:89]
	v_mfma_f32_16x16x32_bf16 v[78:81], v[158:161], v[206:209], v[78:81]
	v_mfma_f32_16x16x32_bf16 v[126:129], v[154:157], v[186:189], v[126:129]
	v_mfma_f32_16x16x32_bf16 v[122:125], v[162:165], v[186:189], v[122:125]
	v_mfma_f32_16x16x32_bf16 v[118:121], v[154:157], v[194:197], v[118:121]
	v_mfma_f32_16x16x32_bf16 v[110:113], v[162:165], v[194:197], v[110:113]
	v_mfma_f32_16x16x32_bf16 v[102:105], v[154:157], v[202:205], v[102:105]
	v_mfma_f32_16x16x32_bf16 v[94:97], v[162:165], v[202:205], v[94:97]
	v_mfma_f32_16x16x32_bf16 v[86:89], v[154:157], v[210:213], v[86:89]
	v_mfma_f32_16x16x32_bf16 v[78:81], v[162:165], v[210:213], v[78:81]
	s_setprio 2
	s_setprio 0
	v_mfma_f32_16x16x32_bf16 v[114:117], v[166:169], v[182:185], v[114:117]
	v_mfma_f32_16x16x32_bf16 v[106:109], v[174:177], v[182:185], v[106:109]
	v_mfma_f32_16x16x32_bf16 v[98:101], v[166:169], v[190:193], v[98:101]
	v_mfma_f32_16x16x32_bf16 v[90:93], v[174:177], v[190:193], v[90:93]
	v_mfma_f32_16x16x32_bf16 v[82:85], v[166:169], v[198:201], v[82:85]
	v_mfma_f32_16x16x32_bf16 v[74:77], v[174:177], v[198:201], v[74:77]
	v_mfma_f32_16x16x32_bf16 v[70:73], v[166:169], v[206:209], v[70:73]
	v_mfma_f32_16x16x32_bf16 v[66:69], v[174:177], v[206:209], v[66:69]
	v_mfma_f32_16x16x32_bf16 v[114:117], v[170:173], v[186:189], v[114:117]
	v_mfma_f32_16x16x32_bf16 v[106:109], v[178:181], v[186:189], v[106:109]
	v_mfma_f32_16x16x32_bf16 v[98:101], v[170:173], v[194:197], v[98:101]
	v_mfma_f32_16x16x32_bf16 v[90:93], v[178:181], v[194:197], v[90:93]
	v_mfma_f32_16x16x32_bf16 v[82:85], v[170:173], v[202:205], v[82:85]
	v_mfma_f32_16x16x32_bf16 v[74:77], v[178:181], v[202:205], v[74:77]
	v_mfma_f32_16x16x32_bf16 v[70:73], v[170:173], v[210:213], v[70:73]
	v_mfma_f32_16x16x32_bf16 v[66:69], v[178:181], v[210:213], v[66:69]
	s_setprio 2
	s_barrier
; #define PG8_STAGE(bufoff, gbase, voff) do { _Pragma("unroll") for (int _i = 0; _i < 2; ++_i) \
;         __builtin_amdgcn_global_load_lds((const unsigned*)((const char*)(gbase) + (voff)[_i]), (LAS unsigned*)(lds + (bufoff) + ldsw + _i * 8192), 16, 0, 0); } while (0)
; #define PG8_LDA(dst, b, h) do { _Pragma("unroll") for (int m = 0; m < 4; ++m) _Pragma("unroll") for (int k = 0; k < 2; ++k) dst[m][k] = *(const LAS bf16x8*)(lds + PG8_SA(b, h) + aoff + m * 2048 + k * 1024); } while (0)
; #define PG8_MMA(ai, bj, At, Bt) do { __builtin_amdgcn_s_setprio(1); _Pragma("unroll") for (int m = 0; m < 4; ++m) _Pragma("unroll") for (int n = 0; n < 2; ++n) _Pragma("unroll") for (int k = 0; k < 2; ++k) \
;         acc[ai][bj][m][n] = __builtin_amdgcn_mfma_f32_16x16x32_bf16(Bt[n][k], At[m][k], acc[ai][bj][m][n], 0, 0, 0); __builtin_amdgcn_s_setprio(0); } while (0)
; #define PG8_WAIT_V(n) asm volatile("s_waitcnt vmcnt(" #n ")" ::: "memory")
; #define PG8_WAIT_L(n) asm volatile("s_waitcnt lgkmcnt(" #n ")" ::: "memory")
; #define PG8_BAR __builtin_amdgcn_s_barrier()
; #define PG8_SCHED __builtin_amdgcn_sched_barrier(0)
; template <class Epi>
; __device__ __forceinline__ void gemm_phase(LAS unsigned char* lds, const Gemm g, int G, int c, const Epi& E) {
;     ...
;             PG8_LDA(At, 1, 1); PG8_STAGE(PG8_SB(1, 0), b3, voffB); PG8_STAGE(PG8_SB(1, 1), b3 + hstepB, voffB); PG8_STAGE(PG8_SA(1, 0), a3, voffA);
;             PG8_WAIT_V(8); PG8_WAIT_L(0); PG8_BAR; PG8_MMA(1, 0, At, B0); PG8_MMA(1, 1, At, B1); PG8_BAR; PG8_SCHED;
;         }
;         if (wr == 0) PG8_BAR;
	s_add_i32 s33, s33, s58
	v_lshl_add_u64 v[142:143], v[142:143], 0, s[6:7]
	s_mov_b32 m0, s33
	ds_read_b128 v[182:185], v148 offset:49152
	ds_read_b128 v[186:189], v148 offset:50176
	ds_read_b128 v[190:193], v148 offset:51200
	ds_read_b128 v[194:197], v148 offset:52224
	ds_read_b128 v[198:201], v148 offset:53248
	ds_read_b128 v[202:205], v148 offset:54272
	ds_read_b128 v[206:209], v148 offset:55296
	ds_read_b128 v[210:213], v148 offset:56320
	global_load_lds_dwordx4 v[142:143], off
	s_add_i32 m0, s33, 0x2000
	s_add_u32 s46, s54, 0x20080
	v_lshl_add_u64 v[142:143], v[214:215], 0, s[6:7]
	s_addc_u32 s47, s55, 0
	s_add_i32 s33, s62, s58
	global_load_lds_dwordx4 v[142:143], off
	v_lshl_add_u64 v[142:143], s[46:47], 0, v[134:135]
	s_mov_b32 m0, s33
	s_nop 0
	global_load_lds_dwordx4 v[142:143], off
	v_lshl_add_u64 v[142:143], s[46:47], 0, v[130:131]
	s_add_i32 m0, s33, 0x2000
	s_nop 0
	global_load_lds_dwordx4 v[142:143], off
	v_lshl_add_u64 v[142:143], v[216:217], 0, s[6:7]
	s_mov_b32 m0, s71
	s_nop 0
	global_load_lds_dwordx4 v[142:143], off
	v_lshl_add_u64 v[142:143], v[218:219], 0, s[6:7]
	s_mov_b32 m0, s72
	s_nop 0
	global_load_lds_dwordx4 v[142:143], off
	s_waitcnt vmcnt(8)
	s_waitcnt lgkmcnt(0)
	s_barrier
	s_setprio 0
	v_mfma_f32_16x16x32_bf16 v[62:65], v[150:153], v[182:185], v[62:65]
	v_mfma_f32_16x16x32_bf16 v[58:61], v[158:161], v[182:185], v[58:61]
	v_mfma_f32_16x16x32_bf16 v[54:57], v[150:153], v[190:193], v[54:57]
	v_mfma_f32_16x16x32_bf16 v[46:49], v[158:161], v[190:193], v[46:49]
	v_mfma_f32_16x16x32_bf16 v[38:41], v[150:153], v[198:201], v[38:41]
	v_mfma_f32_16x16x32_bf16 v[30:33], v[158:161], v[198:201], v[30:33]
	v_mfma_f32_16x16x32_bf16 v[22:25], v[150:153], v[206:209], v[22:25]
	v_mfma_f32_16x16x32_bf16 v[14:17], v[158:161], v[206:209], v[14:17]
	v_mfma_f32_16x16x32_bf16 v[62:65], v[154:157], v[186:189], v[62:65]
	v_mfma_f32_16x16x32_bf16 v[58:61], v[162:165], v[186:189], v[58:61]
	v_mfma_f32_16x16x32_bf16 v[54:57], v[154:157], v[194:197], v[54:57]
	v_mfma_f32_16x16x32_bf16 v[46:49], v[162:165], v[194:197], v[46:49]
	v_mfma_f32_16x16x32_bf16 v[38:41], v[154:157], v[202:205], v[38:41]
	v_mfma_f32_16x16x32_bf16 v[30:33], v[162:165], v[202:205], v[30:33]
	v_mfma_f32_16x16x32_bf16 v[22:25], v[154:157], v[210:213], v[22:25]
	v_mfma_f32_16x16x32_bf16 v[14:17], v[162:165], v[210:213], v[14:17]
	s_setprio 2
	s_setprio 0
	v_mfma_f32_16x16x32_bf16 v[50:53], v[166:169], v[182:185], v[50:53]
	v_mfma_f32_16x16x32_bf16 v[42:45], v[174:177], v[182:185], v[42:45]
	v_mfma_f32_16x16x32_bf16 v[34:37], v[166:169], v[190:193], v[34:37]
	v_mfma_f32_16x16x32_bf16 v[26:29], v[174:177], v[190:193], v[26:29]
	v_mfma_f32_16x16x32_bf16 v[18:21], v[166:169], v[198:201], v[18:21]
	v_mfma_f32_16x16x32_bf16 v[10:13], v[174:177], v[198:201], v[10:13]
	v_mfma_f32_16x16x32_bf16 v[6:9], v[166:169], v[206:209], v[6:9]
	v_mfma_f32_16x16x32_bf16 v[2:5], v[174:177], v[206:209], v[2:5]
	v_mfma_f32_16x16x32_bf16 v[50:53], v[170:173], v[186:189], v[50:53]
	v_mfma_f32_16x16x32_bf16 v[42:45], v[178:181], v[186:189], v[42:45]
	v_mfma_f32_16x16x32_bf16 v[34:37], v[170:173], v[194:197], v[34:37]
	v_mfma_f32_16x16x32_bf16 v[26:29], v[178:181], v[194:197], v[26:29]
	v_mfma_f32_16x16x32_bf16 v[18:21], v[170:173], v[202:205], v[18:21]
	v_mfma_f32_16x16x32_bf16 v[10:13], v[178:181], v[202:205], v[10:13]
	v_mfma_f32_16x16x32_bf16 v[6:9], v[170:173], v[210:213], v[6:9]
	v_mfma_f32_16x16x32_bf16 v[2:5], v[178:181], v[210:213], v[2:5]
	s_setprio 2
	s_barrier
	s_add_i32 s92, s92, 2
	s_cmp_gt_u32 s92, 5
	s_mov_b64 s[46:47], s[52:53]
	s_cbranch_scc0 .LBB0_781
	s_and_b64 vcc, exec, s[8:9]
	s_cbranch_vccz .LBB0_784
	s_barrier

; #define PG8_STAGE(bufoff, gbase, voff) do { _Pragma("unroll") for (int _i = 0; _i < 2; ++_i) \
;         __builtin_amdgcn_global_load_lds((const unsigned*)((const char*)(gbase) + (voff)[_i]), (LAS unsigned*)(lds + (bufoff) + ldsw + _i * 8192), 16, 0, 0); } while (0)
; #define PG8_LDA(dst, b, h) do { _Pragma("unroll") for (int m = 0; m < 4; ++m) _Pragma("unroll") for (int k = 0; k < 2; ++k) dst[m][k] = *(const LAS bf16x8*)(lds + PG8_SA(b, h) + aoff + m * 2048 + k * 1024); } while (0)
; #define PG8_LDB(dst, b, h) do { _Pragma("unroll") for (int n = 0; n < 2; ++n) _Pragma("unroll") for (int k = 0; k < 2; ++k) dst[n][k] = *(const LAS bf16x8*)(lds + PG8_SB(b, h) + boff + n * 2048 + k * 1024); } while (0)
; #define PG8_MMA(ai, bj, At, Bt) do { __builtin_amdgcn_s_setprio(1); _Pragma("unroll") for (int m = 0; m < 4; ++m) _Pragma("unroll") for (int n = 0; n < 2; ++n) _Pragma("unroll") for (int k = 0; k < 2; ++k) \
;         acc[ai][bj][m][n] = __builtin_amdgcn_mfma_f32_16x16x32_bf16(Bt[n][k], At[m][k], acc[ai][bj][m][n], 0, 0, 0); __builtin_amdgcn_s_setprio(0); } while (0)
; #define PG8_WAIT_V(n) asm volatile("s_waitcnt vmcnt(" #n ")" ::: "memory")
; #define PG8_WAIT_L(n) asm volatile("s_waitcnt lgkmcnt(" #n ")" ::: "memory")
; #define PG8_BAR __builtin_amdgcn_s_barrier()
; #define PG8_SCHED __builtin_amdgcn_sched_barrier(0)
; template <class Epi>
; __device__ __forceinline__ void gemm_phase(LAS unsigned char* lds, const Gemm g, int G, int c, const Epi& E) {
;     ...
;             const bool last = (t == nt - 2);
;             const char* a1 = cA + (size_t)(t + 1) * kstep;
;             const char* a2 = last ? nA : cA + (size_t)(t + 2) * kstep; const char* b2 = last ? nB : cB + (size_t)(t + 2) * kstep;
;             const char* a3 = a2 + kstep; const char* b3 = b2 + kstep;
;             PG8_LDB(B0, 0, 0); PG8_LDB(B1, 0, 1); PG8_SCHED; PG8_LDA(At, 0, 0); PG8_STAGE(PG8_SA(1, 1), a1 + hstepA, voffA);
;             PG8_WAIT_V(8); PG8_WAIT_L(0); PG8_BAR; PG8_MMA(0, 0, At, B0); PG8_MMA(0, 1, At, B1); PG8_BAR; PG8_SCHED;
;             PG8_LDA(At, 0, 1); PG8_STAGE(PG8_SB(0, 0), b2, voffB); PG8_STAGE(PG8_SB(0, 1), b2 + hstepB, voffB); PG8_STAGE(PG8_SA(0, 0), a2, voffA);
;             PG8_WAIT_V(8); PG8_WAIT_L(0); PG8_BAR; PG8_MMA(1, 0, At, B0); PG8_MMA(1, 1, At, B1); PG8_BAR; PG8_SCHED;
.LBB0_902:
	s_ashr_i32 s15, s14, 31
	s_lshl_b64 s[20:21], s[14:15], 19
	s_add_u32 s20, s34, s20
	s_addc_u32 s21, s35, s21
	s_and_b64 s[4:5], s[4:5], exec
	s_cselect_b32 s15, s21, s43
	s_cselect_b32 s17, s20, s42
	s_add_u32 s4, s44, 0x40080
	s_addc_u32 s5, s45, 0
	s_add_u32 s23, s42, 0x100
	s_addc_u32 s39, s43, 0
	s_mov_b32 s46, -2
	s_waitcnt vmcnt(0)
	ds_read_b128 v[130:133], v170
	ds_read_b128 v[134:137], v170 offset:1024
	ds_read_b128 v[138:141], v170 offset:2048
	ds_read_b128 v[142:145], v170 offset:3072
	ds_read_b128 v[162:165], v171
	ds_read_b128 v[174:177], v171 offset:1024
	ds_read_b128 v[178:181], v171 offset:2048
	ds_read_b128 v[182:185], v171 offset:3072
	s_add_u32 s33, s4, 0xfffc0080
	s_addc_u32 s42, s5, -1
	s_cmp_eq_u32 s46, 12
	s_cselect_b32 s45, s19, s42
	s_cselect_b32 s44, s18, s33
	s_cselect_b32 s43, s15, s39
	s_cselect_b32 s42, s17, s23
	v_lshl_add_u64 v[166:167], s[4:5], 0, v[154:155]
	s_add_i32 m0, s25, 0xc000
	ds_read_b128 v[186:189], v172
	ds_read_b128 v[190:193], v172 offset:1024
	ds_read_b128 v[194:197], v172 offset:2048
	ds_read_b128 v[198:201], v172 offset:3072
	ds_read_b128 v[202:205], v172 offset:4096
	ds_read_b128 v[206:209], v172 offset:5120
	ds_read_b128 v[210:213], v172 offset:6144
	ds_read_b128 v[214:217], v172 offset:7168
	global_load_lds_dwordx4 v[166:167], off
	v_lshl_add_u64 v[166:167], s[4:5], 0, v[156:157]
	s_add_i32 m0, s25, 0xe000
	s_nop 0
	global_load_lds_dwordx4 v[166:167], off
	s_waitcnt vmcnt(8)
	s_waitcnt lgkmcnt(0)
	s_barrier
	s_setprio 0
	v_mfma_f32_16x16x32_bf16 v[126:129], v[130:133], v[186:189], 0
	v_mfma_f32_16x16x32_bf16 v[122:125], v[138:141], v[186:189], 0
	v_mfma_f32_16x16x32_bf16 v[110:113], v[130:133], v[194:197], 0
	v_mfma_f32_16x16x32_bf16 v[106:109], v[138:141], v[194:197], 0
	v_mfma_f32_16x16x32_bf16 v[94:97], v[130:133], v[202:205], 0
	v_mfma_f32_16x16x32_bf16 v[90:93], v[138:141], v[202:205], 0
	v_mfma_f32_16x16x32_bf16 v[78:81], v[130:133], v[210:213], 0
	v_mfma_f32_16x16x32_bf16 v[74:77], v[138:141], v[210:213], 0
	v_mfma_f32_16x16x32_bf16 v[126:129], v[134:137], v[190:193], v[126:129]
	v_mfma_f32_16x16x32_bf16 v[122:125], v[142:145], v[190:193], v[122:125]
	v_mfma_f32_16x16x32_bf16 v[110:113], v[134:137], v[198:201], v[110:113]
	v_mfma_f32_16x16x32_bf16 v[106:109], v[142:145], v[198:201], v[106:109]
	v_mfma_f32_16x16x32_bf16 v[94:97], v[134:137], v[206:209], v[94:97]
	v_mfma_f32_16x16x32_bf16 v[90:93], v[142:145], v[206:209], v[90:93]
	v_mfma_f32_16x16x32_bf16 v[78:81], v[134:137], v[214:217], v[78:81]
	v_mfma_f32_16x16x32_bf16 v[74:77], v[142:145], v[214:217], v[74:77]
	s_setprio 2
	s_setprio 0
	v_mfma_f32_16x16x32_bf16 v[118:121], v[162:165], v[186:189], 0
	v_mfma_f32_16x16x32_bf16 v[114:117], v[178:181], v[186:189], 0
	v_mfma_f32_16x16x32_bf16 v[102:105], v[162:165], v[194:197], 0
	v_mfma_f32_16x16x32_bf16 v[98:101], v[178:181], v[194:197], 0
	v_mfma_f32_16x16x32_bf16 v[86:89], v[162:165], v[202:205], 0
	v_mfma_f32_16x16x32_bf16 v[82:85], v[178:181], v[202:205], 0
	v_mfma_f32_16x16x32_bf16 v[70:73], v[162:165], v[210:213], 0
	v_mfma_f32_16x16x32_bf16 v[66:69], v[178:181], v[210:213], 0
	v_mfma_f32_16x16x32_bf16 v[118:121], v[174:177], v[190:193], v[118:121]
	v_mfma_f32_16x16x32_bf16 v[114:117], v[182:185], v[190:193], v[114:117]
	v_mfma_f32_16x16x32_bf16 v[102:105], v[174:177], v[198:201], v[102:105]
	v_mfma_f32_16x16x32_bf16 v[98:101], v[182:185], v[198:201], v[98:101]
	v_mfma_f32_16x16x32_bf16 v[86:89], v[174:177], v[206:209], v[86:89]
	v_mfma_f32_16x16x32_bf16 v[82:85], v[182:185], v[206:209], v[82:85]
	v_mfma_f32_16x16x32_bf16 v[70:73], v[174:177], v[214:217], v[70:73]
	v_mfma_f32_16x16x32_bf16 v[66:69], v[182:185], v[214:217], v[66:69]
	s_setprio 2
	s_barrier
	s_add_i32 s33, s72, s54
	v_lshl_add_u64 v[166:167], s[42:43], 0, v[150:151]
	s_mov_b32 m0, s33
	ds_read_b128 v[186:189], v172 offset:16384
	ds_read_b128 v[190:193], v172 offset:17408
	ds_read_b128 v[194:197], v172 offset:18432
	ds_read_b128 v[198:201], v172 offset:19456
	ds_read_b128 v[202:205], v172 offset:20480
	ds_read_b128 v[206:209], v172 offset:21504
	ds_read_b128 v[210:213], v172 offset:22528
	ds_read_b128 v[214:217], v172 offset:23552
	global_load_lds_dwordx4 v[166:167], off
	s_add_i32 m0, s33, 0x2000
	s_add_u32 s62, s42, 0x40000
	v_lshl_add_u64 v[218:219], s[42:43], 0, v[146:147]
	s_addc_u32 s63, s43, 0
	s_add_i32 s33, s73, s54
	global_load_lds_dwordx4 v[218:219], off
	v_lshl_add_u64 v[220:221], s[62:63], 0, v[150:151]
	s_mov_b32 m0, s33
	v_lshl_add_u64 v[222:223], s[44:45], 0, v[148:149]
	global_load_lds_dwordx4 v[220:221], off
	v_lshl_add_u64 v[220:221], s[62:63], 0, v[146:147]
	s_add_i32 m0, s33, 0x2000
	s_nop 0
	global_load_lds_dwordx4 v[220:221], off
	v_lshl_add_u64 v[220:221], s[44:45], 0, v[152:153]
	s_mov_b32 m0, s25
	s_nop 0
	global_load_lds_dwordx4 v[220:221], off
	s_mov_b32 m0, s57
	s_nop 0
	global_load_lds_dwordx4 v[222:223], off
	s_waitcnt vmcnt(8)
	s_waitcnt lgkmcnt(0)
	s_barrier
; #define PG8_STAGE(bufoff, gbase, voff) do { _Pragma("unroll") for (int _i = 0; _i < 2; ++_i) \
;         __builtin_amdgcn_global_load_lds((const unsigned*)((const char*)(gbase) + (voff)[_i]), (LAS unsigned*)(lds + (bufoff) + ldsw + _i * 8192), 16, 0, 0); } while (0)
; #define PG8_LDA(dst, b, h) do { _Pragma("unroll") for (int m = 0; m < 4; ++m) _Pragma("unroll") for (int k = 0; k < 2; ++k) dst[m][k] = *(const LAS bf16x8*)(lds + PG8_SA(b, h) + aoff + m * 2048 + k * 1024); } while (0)
; #define PG8_LDB(dst, b, h) do { _Pragma("unroll") for (int n = 0; n < 2; ++n) _Pragma("unroll") for (int k = 0; k < 2; ++k) dst[n][k] = *(const LAS bf16x8*)(lds + PG8_SB(b, h) + boff + n * 2048 + k * 1024); } while (0)
; #define PG8_MMA(ai, bj, At, Bt) do { __builtin_amdgcn_s_setprio(1); _Pragma("unroll") for (int m = 0; m < 4; ++m) _Pragma("unroll") for (int n = 0; n < 2; ++n) _Pragma("unroll") for (int k = 0; k < 2; ++k) \
;         acc[ai][bj][m][n] = __builtin_amdgcn_mfma_f32_16x16x32_bf16(Bt[n][k], At[m][k], acc[ai][bj][m][n], 0, 0, 0); __builtin_amdgcn_s_setprio(0); } while (0)
; #define PG8_WAIT_V(n) asm volatile("s_waitcnt vmcnt(" #n ")" ::: "memory")
; #define PG8_WAIT_L(n) asm volatile("s_waitcnt lgkmcnt(" #n ")" ::: "memory")
; #define PG8_BAR __builtin_amdgcn_s_barrier()
; #define PG8_SCHED __builtin_amdgcn_sched_barrier(0)
; template <class Epi>
; __device__ __forceinline__ void gemm_phase(LAS unsigned char* lds, const Gemm g, int G, int c, const Epi& E) {
;     ...
;             PG8_WAIT_V(8); PG8_WAIT_L(0); PG8_BAR; PG8_MMA(1, 0, At, B0); PG8_MMA(1, 1, At, B1); PG8_BAR; PG8_SCHED;
;             PG8_LDB(B0, 1, 0); PG8_LDB(B1, 1, 1); PG8_SCHED; PG8_LDA(At, 1, 0); PG8_STAGE(PG8_SA(0, 1), a2 + hstepA, voffA);
;             PG8_WAIT_V(8); PG8_WAIT_L(0); PG8_BAR; PG8_MMA(0, 0, At, B0); PG8_MMA(0, 1, At, B1); PG8_BAR; PG8_SCHED;
	s_setprio 0
	v_mfma_f32_16x16x32_bf16 v[62:65], v[130:133], v[186:189], 0
	v_mfma_f32_16x16x32_bf16 v[58:61], v[138:141], v[186:189], 0
	v_mfma_f32_16x16x32_bf16 v[46:49], v[130:133], v[194:197], 0
	v_mfma_f32_16x16x32_bf16 v[42:45], v[138:141], v[194:197], 0
	v_mfma_f32_16x16x32_bf16 v[30:33], v[130:133], v[202:205], 0
	v_mfma_f32_16x16x32_bf16 v[26:29], v[138:141], v[202:205], 0
	v_mfma_f32_16x16x32_bf16 v[14:17], v[130:133], v[210:213], 0
	v_mfma_f32_16x16x32_bf16 v[10:13], v[138:141], v[210:213], 0
	v_mfma_f32_16x16x32_bf16 v[62:65], v[134:137], v[190:193], v[62:65]
	v_mfma_f32_16x16x32_bf16 v[58:61], v[142:145], v[190:193], v[58:61]
	v_mfma_f32_16x16x32_bf16 v[46:49], v[134:137], v[198:201], v[46:49]
	v_mfma_f32_16x16x32_bf16 v[42:45], v[142:145], v[198:201], v[42:45]
	v_mfma_f32_16x16x32_bf16 v[30:33], v[134:137], v[206:209], v[30:33]
	v_mfma_f32_16x16x32_bf16 v[26:29], v[142:145], v[206:209], v[26:29]
	v_mfma_f32_16x16x32_bf16 v[14:17], v[134:137], v[214:217], v[14:17]
	v_mfma_f32_16x16x32_bf16 v[10:13], v[142:145], v[214:217], v[10:13]
	s_setprio 2
	s_setprio 0
	v_mfma_f32_16x16x32_bf16 v[54:57], v[162:165], v[186:189], 0
	v_mfma_f32_16x16x32_bf16 v[50:53], v[178:181], v[186:189], 0
	v_mfma_f32_16x16x32_bf16 v[38:41], v[162:165], v[194:197], 0
	v_mfma_f32_16x16x32_bf16 v[34:37], v[178:181], v[194:197], 0
	v_mfma_f32_16x16x32_bf16 v[22:25], v[162:165], v[202:205], 0
	v_mfma_f32_16x16x32_bf16 v[18:21], v[178:181], v[202:205], 0
	v_mfma_f32_16x16x32_bf16 v[6:9], v[162:165], v[210:213], 0
	v_mfma_f32_16x16x32_bf16 v[2:5], v[178:181], v[210:213], 0
	v_mfma_f32_16x16x32_bf16 v[54:57], v[174:177], v[190:193], v[54:57]
	v_mfma_f32_16x16x32_bf16 v[50:53], v[182:185], v[190:193], v[50:53]
	v_mfma_f32_16x16x32_bf16 v[38:41], v[174:177], v[198:201], v[38:41]
	v_mfma_f32_16x16x32_bf16 v[34:37], v[182:185], v[198:201], v[34:37]
	v_mfma_f32_16x16x32_bf16 v[22:25], v[174:177], v[206:209], v[22:25]
	v_mfma_f32_16x16x32_bf16 v[18:21], v[182:185], v[206:209], v[18:21]
	v_mfma_f32_16x16x32_bf16 v[6:9], v[174:177], v[214:217], v[6:9]
	v_mfma_f32_16x16x32_bf16 v[2:5], v[182:185], v[214:217], v[2:5]
	s_setprio 2
	s_barrier
	s_add_i32 s33, 0, 0x18000
	s_add_i32 s47, 0, 0x1c000
	v_add_u32_e32 v142, s33, v169
	v_add_u32_e32 v173, s47, v169
	ds_read_b128 v[130:133], v142
	ds_read_b128 v[134:137], v142 offset:1024
	ds_read_b128 v[138:141], v142 offset:2048
	ds_read_b128 v[142:145], v142 offset:3072
	ds_read_b128 v[162:165], v173
	ds_read_b128 v[174:177], v173 offset:1024
	ds_read_b128 v[178:181], v173 offset:2048
	ds_read_b128 v[182:185], v173 offset:3072
	s_add_u32 s44, s44, 0x40000
	s_addc_u32 s45, s45, 0
	s_mov_b32 m0, s58
	v_lshl_add_u64 v[224:225], s[44:45], 0, v[152:153]
	ds_read_b128 v[186:189], v172 offset:32768
	ds_read_b128 v[190:193], v172 offset:33792
	ds_read_b128 v[194:197], v172 offset:34816
	ds_read_b128 v[198:201], v172 offset:35840
	ds_read_b128 v[202:205], v172 offset:36864
	ds_read_b128 v[206:209], v172 offset:37888
	ds_read_b128 v[210:213], v172 offset:38912
	ds_read_b128 v[214:217], v172 offset:39936
	global_load_lds_dwordx4 v[224:225], off
	v_lshl_add_u64 v[224:225], s[44:45], 0, v[148:149]
	s_mov_b32 m0, s59
	s_nop 0
	global_load_lds_dwordx4 v[224:225], off
	s_waitcnt vmcnt(8)
	s_waitcnt lgkmcnt(0)
	s_barrier
	s_setprio 0
	v_mfma_f32_16x16x32_bf16 v[126:129], v[130:133], v[186:189], v[126:129]
	v_mfma_f32_16x16x32_bf16 v[122:125], v[138:141], v[186:189], v[122:125]
	v_mfma_f32_16x16x32_bf16 v[110:113], v[130:133], v[194:197], v[110:113]
	v_mfma_f32_16x16x32_bf16 v[106:109], v[138:141], v[194:197], v[106:109]
	v_mfma_f32_16x16x32_bf16 v[94:97], v[130:133], v[202:205], v[94:97]
	v_mfma_f32_16x16x32_bf16 v[90:93], v[138:141], v[202:205], v[90:93]
	v_mfma_f32_16x16x32_bf16 v[78:81], v[130:133], v[210:213], v[78:81]
	v_mfma_f32_16x16x32_bf16 v[74:77], v[138:141], v[210:213], v[74:77]
	v_mfma_f32_16x16x32_bf16 v[126:129], v[134:137], v[190:193], v[126:129]
	v_mfma_f32_16x16x32_bf16 v[122:125], v[142:145], v[190:193], v[122:125]
	v_mfma_f32_16x16x32_bf16 v[110:113], v[134:137], v[198:201], v[110:113]
	v_mfma_f32_16x16x32_bf16 v[106:109], v[142:145], v[198:201], v[106:109]
	v_mfma_f32_16x16x32_bf16 v[94:97], v[134:137], v[206:209], v[94:97]
	v_mfma_f32_16x16x32_bf16 v[90:93], v[142:145], v[206:209], v[90:93]
	v_mfma_f32_16x16x32_bf16 v[78:81], v[134:137], v[214:217], v[78:81]
	v_mfma_f32_16x16x32_bf16 v[74:77], v[142:145], v[214:217], v[74:77]
	s_setprio 2
	s_setprio 0
	v_mfma_f32_16x16x32_bf16 v[118:121], v[162:165], v[186:189], v[118:121]
	v_mfma_f32_16x16x32_bf16 v[114:117], v[178:181], v[186:189], v[114:117]
	v_mfma_f32_16x16x32_bf16 v[102:105], v[162:165], v[194:197], v[102:105]
	v_mfma_f32_16x16x32_bf16 v[98:101], v[178:181], v[194:197], v[98:101]
	v_mfma_f32_16x16x32_bf16 v[86:89], v[162:165], v[202:205], v[86:89]
	v_mfma_f32_16x16x32_bf16 v[82:85], v[178:181], v[202:205], v[82:85]
	v_mfma_f32_16x16x32_bf16 v[70:73], v[162:165], v[210:213], v[70:73]
	v_mfma_f32_16x16x32_bf16 v[66:69], v[178:181], v[210:213], v[66:69]
	v_mfma_f32_16x16x32_bf16 v[118:121], v[174:177], v[190:193], v[118:121]
	v_mfma_f32_16x16x32_bf16 v[114:117], v[182:185], v[190:193], v[114:117]
	v_mfma_f32_16x16x32_bf16 v[102:105], v[174:177], v[198:201], v[102:105]
	v_mfma_f32_16x16x32_bf16 v[98:101], v[182:185], v[198:201], v[98:101]
	v_mfma_f32_16x16x32_bf16 v[86:89], v[174:177], v[206:209], v[86:89]
	v_mfma_f32_16x16x32_bf16 v[82:85], v[182:185], v[206:209], v[82:85]
	v_mfma_f32_16x16x32_bf16 v[70:73], v[174:177], v[214:217], v[70:73]
	v_mfma_f32_16x16x32_bf16 v[66:69], v[182:185], v[214:217], v[66:69]
	s_setprio 2
	s_barrier
; #define PG8_STAGE(bufoff, gbase, voff) do { _Pragma("unroll") for (int _i = 0; _i < 2; ++_i) \
;         __builtin_amdgcn_global_load_lds((const unsigned*)((const char*)(gbase) + (voff)[_i]), (LAS unsigned*)(lds + (bufoff) + ldsw + _i * 8192), 16, 0, 0); } while (0)
; #define PG8_LDA(dst, b, h) do { _Pragma("unroll") for (int m = 0; m < 4; ++m) _Pragma("unroll") for (int k = 0; k < 2; ++k) dst[m][k] = *(const LAS bf16x8*)(lds + PG8_SA(b, h) + aoff + m * 2048 + k * 1024); } while (0)
; #define PG8_LDB(dst, b, h) do { _Pragma("unroll") for (int n = 0; n < 2; ++n) _Pragma("unroll") for (int k = 0; k < 2; ++k) dst[n][k] = *(const LAS bf16x8*)(lds + PG8_SB(b, h) + boff + n * 2048 + k * 1024); } while (0)
; #define PG8_MMA(ai, bj, At, Bt) do { __builtin_amdgcn_s_setprio(1); _Pragma("unroll") for (int m = 0; m < 4; ++m) _Pragma("unroll") for (int n = 0; n < 2; ++n) _Pragma("unroll") for (int k = 0; k < 2; ++k) \
;         acc[ai][bj][m][n] = __builtin_amdgcn_mfma_f32_16x16x32_bf16(Bt[n][k], At[m][k], acc[ai][bj][m][n], 0, 0, 0); __builtin_amdgcn_s_setprio(0); } while (0)
; #define PG8_WAIT_V(n) asm volatile("s_waitcnt vmcnt(" #n ")" ::: "memory")
; #define PG8_BAR __builtin_amdgcn_s_barrier()
; template <class Epi>
; __device__ __forceinline__ void gemm_phase(LAS unsigned char* lds, const Gemm g, int G, int c, const Epi& E) {
;     ...
;             PG8_LDB(B0, 0, 0); PG8_LDB(B1, 0, 1); PG8_SCHED; PG8_LDA(At, 0, 0); PG8_STAGE(PG8_SA(1, 1), a1 + hstepA, voffA);
;             PG8_WAIT_V(8); PG8_WAIT_L(0); PG8_BAR; PG8_MMA(0, 0, At, B0); PG8_MMA(0, 1, At, B1); PG8_BAR; PG8_SCHED;
;             PG8_LDA(At, 0, 1); PG8_STAGE(PG8_SB(0, 0), b2, voffB); PG8_STAGE(PG8_SB(0, 1), b2 + hstepB, voffB); PG8_STAGE(PG8_SA(0, 0), a2, voffA);
;             PG8_WAIT_V(8); PG8_WAIT_L(0); PG8_BAR; PG8_MMA(1, 0, At, B0); PG8_MMA(1, 1, At, B1); PG8_BAR; PG8_SCHED;
;             PG8_LDB(B0, 1, 0); PG8_LDB(B1, 1, 1); PG8_SCHED; PG8_LDA(At, 1, 0); PG8_STAGE(PG8_SA(0, 1), a2 + hstepA, voffA);
;             PG8_WAIT_V(8); PG8_WAIT_L(0); PG8_BAR; PG8_MMA(0, 0, At, B0); PG8_MMA(0, 1, At, B1); PG8_BAR; PG8_SCHED;
;             PG8_LDA(At, 1, 1); PG8_STAGE(PG8_SB(1, 0), b3, voffB); PG8_STAGE(PG8_SB(1, 1), b3 + hstepB, voffB); PG8_STAGE(PG8_SA(1, 0), a3, voffA);
;             PG8_WAIT_V(8); PG8_WAIT_L(0); PG8_BAR; PG8_MMA(1, 0, At, B0); PG8_MMA(1, 1, At, B1); PG8_BAR; PG8_SCHED;
	s_add_i32 s33, s33, s54
	v_lshl_add_u64 v[166:167], v[166:167], 0, s[10:11]
	s_mov_b32 m0, s33
	ds_read_b128 v[186:189], v172 offset:49152
	ds_read_b128 v[190:193], v172 offset:50176
	ds_read_b128 v[194:197], v172 offset:51200
	ds_read_b128 v[198:201], v172 offset:52224
	ds_read_b128 v[202:205], v172 offset:53248
	ds_read_b128 v[206:209], v172 offset:54272
	ds_read_b128 v[210:213], v172 offset:55296
	ds_read_b128 v[214:217], v172 offset:56320
	global_load_lds_dwordx4 v[166:167], off
	s_add_i32 m0, s33, 0x2000
	s_add_u32 s42, s42, 0x40080
	v_lshl_add_u64 v[166:167], v[218:219], 0, s[10:11]
	s_addc_u32 s43, s43, 0
	s_add_i32 s33, s47, s54
	global_load_lds_dwordx4 v[166:167], off
	v_lshl_add_u64 v[166:167], s[42:43], 0, v[150:151]
	s_mov_b32 m0, s33
	s_nop 0
	global_load_lds_dwordx4 v[166:167], off
	v_lshl_add_u64 v[166:167], s[42:43], 0, v[146:147]
	s_add_i32 m0, s33, 0x2000
	s_nop 0
	global_load_lds_dwordx4 v[166:167], off
	v_lshl_add_u64 v[166:167], v[220:221], 0, s[10:11]
	s_mov_b32 m0, s69
	s_nop 0
	global_load_lds_dwordx4 v[166:167], off
	v_lshl_add_u64 v[166:167], v[222:223], 0, s[10:11]
	s_mov_b32 m0, s70
	s_nop 0
	global_load_lds_dwordx4 v[166:167], off
	s_waitcnt vmcnt(8)
	s_waitcnt lgkmcnt(0)
	s_barrier
	s_setprio 0
	v_mfma_f32_16x16x32_bf16 v[62:65], v[130:133], v[186:189], v[62:65]
	v_mfma_f32_16x16x32_bf16 v[58:61], v[138:141], v[186:189], v[58:61]
	v_mfma_f32_16x16x32_bf16 v[46:49], v[130:133], v[194:197], v[46:49]
	v_mfma_f32_16x16x32_bf16 v[42:45], v[138:141], v[194:197], v[42:45]
	v_mfma_f32_16x16x32_bf16 v[30:33], v[130:133], v[202:205], v[30:33]
	v_mfma_f32_16x16x32_bf16 v[26:29], v[138:141], v[202:205], v[26:29]
	v_mfma_f32_16x16x32_bf16 v[14:17], v[130:133], v[210:213], v[14:17]
	v_mfma_f32_16x16x32_bf16 v[10:13], v[138:141], v[210:213], v[10:13]
	v_mfma_f32_16x16x32_bf16 v[62:65], v[134:137], v[190:193], v[62:65]
	v_mfma_f32_16x16x32_bf16 v[58:61], v[142:145], v[190:193], v[58:61]
	v_mfma_f32_16x16x32_bf16 v[46:49], v[134:137], v[198:201], v[46:49]
	v_mfma_f32_16x16x32_bf16 v[42:45], v[142:145], v[198:201], v[42:45]
	v_mfma_f32_16x16x32_bf16 v[30:33], v[134:137], v[206:209], v[30:33]
	v_mfma_f32_16x16x32_bf16 v[26:29], v[142:145], v[206:209], v[26:29]
	v_mfma_f32_16x16x32_bf16 v[14:17], v[134:137], v[214:217], v[14:17]
	v_mfma_f32_16x16x32_bf16 v[10:13], v[142:145], v[214:217], v[10:13]
	s_setprio 2
	s_setprio 0
	v_mfma_f32_16x16x32_bf16 v[54:57], v[162:165], v[186:189], v[54:57]
	v_mfma_f32_16x16x32_bf16 v[50:53], v[178:181], v[186:189], v[50:53]
	v_mfma_f32_16x16x32_bf16 v[38:41], v[162:165], v[194:197], v[38:41]
	v_mfma_f32_16x16x32_bf16 v[34:37], v[178:181], v[194:197], v[34:37]
	v_mfma_f32_16x16x32_bf16 v[22:25], v[162:165], v[202:205], v[22:25]
	v_mfma_f32_16x16x32_bf16 v[18:21], v[178:181], v[202:205], v[18:21]
	v_mfma_f32_16x16x32_bf16 v[6:9], v[162:165], v[210:213], v[6:9]
	v_mfma_f32_16x16x32_bf16 v[2:5], v[178:181], v[210:213], v[2:5]
	v_mfma_f32_16x16x32_bf16 v[54:57], v[174:177], v[190:193], v[54:57]
	v_mfma_f32_16x16x32_bf16 v[50:53], v[182:185], v[190:193], v[50:53]
	v_mfma_f32_16x16x32_bf16 v[38:41], v[174:177], v[198:201], v[38:41]
	v_mfma_f32_16x16x32_bf16 v[34:37], v[182:185], v[198:201], v[34:37]
	v_mfma_f32_16x16x32_bf16 v[22:25], v[174:177], v[206:209], v[22:25]
	v_mfma_f32_16x16x32_bf16 v[18:21], v[182:185], v[206:209], v[18:21]
	v_mfma_f32_16x16x32_bf16 v[6:9], v[174:177], v[214:217], v[6:9]
	v_mfma_f32_16x16x32_bf16 v[2:5], v[182:185], v[214:217], v[2:5]
	s_setprio 2
	s_barrier
	s_add_i32 s46, s46, 2
	s_add_u32 s4, s4, 0x100
	s_addc_u32 s5, s5, 0
	s_add_u32 s23, s23, 0x100
	s_addc_u32 s39, s39, 0
	s_cmp_gt_u32 s46, 13
	s_cbranch_scc0 .LBB0_903
.LBB0_903:
	ds_read_b128 v[130:133], v170
	ds_read_b128 v[134:137], v170 offset:1024
	ds_read_b128 v[138:141], v170 offset:2048
	ds_read_b128 v[142:145], v170 offset:3072
	ds_read_b128 v[162:165], v171
	ds_read_b128 v[174:177], v171 offset:1024
	ds_read_b128 v[178:181], v171 offset:2048
	ds_read_b128 v[182:185], v171 offset:3072
	s_add_u32 s33, s4, 0xfffc0080
	s_addc_u32 s42, s5, -1
	s_cmp_eq_u32 s46, 12
	s_cselect_b32 s45, s19, s42
	s_cselect_b32 s44, s18, s33
	s_cselect_b32 s43, s15, s39
	s_cselect_b32 s42, s17, s23
	v_lshl_add_u64 v[166:167], s[4:5], 0, v[154:155]
	s_add_i32 m0, s25, 0xc000
	ds_read_b128 v[186:189], v172
	ds_read_b128 v[190:193], v172 offset:1024
	ds_read_b128 v[194:197], v172 offset:2048
	ds_read_b128 v[198:201], v172 offset:3072
	ds_read_b128 v[202:205], v172 offset:4096
	ds_read_b128 v[206:209], v172 offset:5120
	ds_read_b128 v[210:213], v172 offset:6144
	ds_read_b128 v[214:217], v172 offset:7168
	global_load_lds_dwordx4 v[166:167], off
	v_lshl_add_u64 v[166:167], s[4:5], 0, v[156:157]
	s_add_i32 m0, s25, 0xe000
	s_nop 0
	global_load_lds_dwordx4 v[166:167], off
	s_waitcnt vmcnt(8)
	s_waitcnt lgkmcnt(0)
	s_barrier
; #define PG8_STAGE(bufoff, gbase, voff) do { _Pragma("unroll") for (int _i = 0; _i < 2; ++_i) \
;         __builtin_amdgcn_global_load_lds((const unsigned*)((const char*)(gbase) + (voff)[_i]), (LAS unsigned*)(lds + (bufoff) + ldsw + _i * 8192), 16, 0, 0); } while (0)
; #define PG8_LDA(dst, b, h) do { _Pragma("unroll") for (int m = 0; m < 4; ++m) _Pragma("unroll") for (int k = 0; k < 2; ++k) dst[m][k] = *(const LAS bf16x8*)(lds + PG8_SA(b, h) + aoff + m * 2048 + k * 1024); } while (0)
; #define PG8_MMA(ai, bj, At, Bt) do { __builtin_amdgcn_s_setprio(1); _Pragma("unroll") for (int m = 0; m < 4; ++m) _Pragma("unroll") for (int n = 0; n < 2; ++n) _Pragma("unroll") for (int k = 0; k < 2; ++k) \
;         acc[ai][bj][m][n] = __builtin_amdgcn_mfma_f32_16x16x32_bf16(Bt[n][k], At[m][k], acc[ai][bj][m][n], 0, 0, 0); __builtin_amdgcn_s_setprio(0); } while (0)
; #define PG8_WAIT_V(n) asm volatile("s_waitcnt vmcnt(" #n ")" ::: "memory")
; #define PG8_WAIT_L(n) asm volatile("s_waitcnt lgkmcnt(" #n ")" ::: "memory")
; #define PG8_BAR __builtin_amdgcn_s_barrier()
; #define PG8_SCHED __builtin_amdgcn_sched_barrier(0)
; template <class Epi>
; __device__ __forceinline__ void gemm_phase(LAS unsigned char* lds, const Gemm g, int G, int c, const Epi& E) {
;     ...
;             PG8_WAIT_V(8); PG8_WAIT_L(0); PG8_BAR; PG8_MMA(0, 0, At, B0); PG8_MMA(0, 1, At, B1); PG8_BAR; PG8_SCHED;
;             PG8_LDA(At, 0, 1); PG8_STAGE(PG8_SB(0, 0), b2, voffB); PG8_STAGE(PG8_SB(0, 1), b2 + hstepB, voffB); PG8_STAGE(PG8_SA(0, 0), a2, voffA);
;             PG8_WAIT_V(8); PG8_WAIT_L(0); PG8_BAR; PG8_MMA(1, 0, At, B0); PG8_MMA(1, 1, At, B1); PG8_BAR; PG8_SCHED;
	s_setprio 0
	v_mfma_f32_16x16x32_bf16 v[126:129], v[130:133], v[186:189], v[126:129]
	v_mfma_f32_16x16x32_bf16 v[122:125], v[138:141], v[186:189], v[122:125]
	v_mfma_f32_16x16x32_bf16 v[110:113], v[130:133], v[194:197], v[110:113]
	v_mfma_f32_16x16x32_bf16 v[106:109], v[138:141], v[194:197], v[106:109]
	v_mfma_f32_16x16x32_bf16 v[94:97], v[130:133], v[202:205], v[94:97]
	v_mfma_f32_16x16x32_bf16 v[90:93], v[138:141], v[202:205], v[90:93]
	v_mfma_f32_16x16x32_bf16 v[78:81], v[130:133], v[210:213], v[78:81]
	v_mfma_f32_16x16x32_bf16 v[74:77], v[138:141], v[210:213], v[74:77]
	v_mfma_f32_16x16x32_bf16 v[126:129], v[134:137], v[190:193], v[126:129]
	v_mfma_f32_16x16x32_bf16 v[122:125], v[142:145], v[190:193], v[122:125]
	v_mfma_f32_16x16x32_bf16 v[110:113], v[134:137], v[198:201], v[110:113]
	v_mfma_f32_16x16x32_bf16 v[106:109], v[142:145], v[198:201], v[106:109]
	v_mfma_f32_16x16x32_bf16 v[94:97], v[134:137], v[206:209], v[94:97]
	v_mfma_f32_16x16x32_bf16 v[90:93], v[142:145], v[206:209], v[90:93]
	v_mfma_f32_16x16x32_bf16 v[78:81], v[134:137], v[214:217], v[78:81]
	v_mfma_f32_16x16x32_bf16 v[74:77], v[142:145], v[214:217], v[74:77]
	s_setprio 2
	s_setprio 0
	v_mfma_f32_16x16x32_bf16 v[118:121], v[162:165], v[186:189], v[118:121]
	v_mfma_f32_16x16x32_bf16 v[114:117], v[178:181], v[186:189], v[114:117]
	v_mfma_f32_16x16x32_bf16 v[102:105], v[162:165], v[194:197], v[102:105]
	v_mfma_f32_16x16x32_bf16 v[98:101], v[178:181], v[194:197], v[98:101]
	v_mfma_f32_16x16x32_bf16 v[86:89], v[162:165], v[202:205], v[86:89]
	v_mfma_f32_16x16x32_bf16 v[82:85], v[178:181], v[202:205], v[82:85]
	v_mfma_f32_16x16x32_bf16 v[70:73], v[162:165], v[210:213], v[70:73]
	v_mfma_f32_16x16x32_bf16 v[66:69], v[178:181], v[210:213], v[66:69]
	v_mfma_f32_16x16x32_bf16 v[118:121], v[174:177], v[190:193], v[118:121]
	v_mfma_f32_16x16x32_bf16 v[114:117], v[182:185], v[190:193], v[114:117]
	v_mfma_f32_16x16x32_bf16 v[102:105], v[174:177], v[198:201], v[102:105]
	v_mfma_f32_16x16x32_bf16 v[98:101], v[182:185], v[198:201], v[98:101]
	v_mfma_f32_16x16x32_bf16 v[86:89], v[174:177], v[206:209], v[86:89]
	v_mfma_f32_16x16x32_bf16 v[82:85], v[182:185], v[206:209], v[82:85]
	v_mfma_f32_16x16x32_bf16 v[70:73], v[174:177], v[214:217], v[70:73]
	v_mfma_f32_16x16x32_bf16 v[66:69], v[182:185], v[214:217], v[66:69]
	s_setprio 2
	s_barrier
	s_add_i32 s33, s72, s54
	v_lshl_add_u64 v[166:167], s[42:43], 0, v[150:151]
	s_mov_b32 m0, s33
	ds_read_b128 v[186:189], v172 offset:16384
	ds_read_b128 v[190:193], v172 offset:17408
	ds_read_b128 v[194:197], v172 offset:18432
	ds_read_b128 v[198:201], v172 offset:19456
	ds_read_b128 v[202:205], v172 offset:20480
	ds_read_b128 v[206:209], v172 offset:21504
	ds_read_b128 v[210:213], v172 offset:22528
	ds_read_b128 v[214:217], v172 offset:23552
	global_load_lds_dwordx4 v[166:167], off
	s_add_i32 m0, s33, 0x2000
	s_add_u32 s62, s42, 0x40000
	v_lshl_add_u64 v[218:219], s[42:43], 0, v[146:147]
	s_addc_u32 s63, s43, 0
	s_add_i32 s33, s73, s54
	global_load_lds_dwordx4 v[218:219], off
	v_lshl_add_u64 v[220:221], s[62:63], 0, v[150:151]
	s_mov_b32 m0, s33
	v_lshl_add_u64 v[222:223], s[44:45], 0, v[148:149]
	global_load_lds_dwordx4 v[220:221], off
	v_lshl_add_u64 v[220:221], s[62:63], 0, v[146:147]
	s_add_i32 m0, s33, 0x2000
	s_nop 0
	global_load_lds_dwordx4 v[220:221], off
	v_lshl_add_u64 v[220:221], s[44:45], 0, v[152:153]
	s_mov_b32 m0, s25
	s_nop 0
	global_load_lds_dwordx4 v[220:221], off
	s_mov_b32 m0, s57
	s_nop 0
	global_load_lds_dwordx4 v[222:223], off
	s_waitcnt vmcnt(8)
	s_waitcnt lgkmcnt(0)
	s_barrier
	s_setprio 0
	v_mfma_f32_16x16x32_bf16 v[62:65], v[130:133], v[186:189], v[62:65]
	v_mfma_f32_16x16x32_bf16 v[58:61], v[138:141], v[186:189], v[58:61]
	v_mfma_f32_16x16x32_bf16 v[46:49], v[130:133], v[194:197], v[46:49]
	v_mfma_f32_16x16x32_bf16 v[42:45], v[138:141], v[194:197], v[42:45]
	v_mfma_f32_16x16x32_bf16 v[30:33], v[130:133], v[202:205], v[30:33]
	v_mfma_f32_16x16x32_bf16 v[26:29], v[138:141], v[202:205], v[26:29]
	v_mfma_f32_16x16x32_bf16 v[14:17], v[130:133], v[210:213], v[14:17]
	v_mfma_f32_16x16x32_bf16 v[10:13], v[138:141], v[210:213], v[10:13]
	v_mfma_f32_16x16x32_bf16 v[62:65], v[134:137], v[190:193], v[62:65]
	v_mfma_f32_16x16x32_bf16 v[58:61], v[142:145], v[190:193], v[58:61]
	v_mfma_f32_16x16x32_bf16 v[46:49], v[134:137], v[198:201], v[46:49]
	v_mfma_f32_16x16x32_bf16 v[42:45], v[142:145], v[198:201], v[42:45]
	v_mfma_f32_16x16x32_bf16 v[30:33], v[134:137], v[206:209], v[30:33]
	v_mfma_f32_16x16x32_bf16 v[26:29], v[142:145], v[206:209], v[26:29]
	v_mfma_f32_16x16x32_bf16 v[14:17], v[134:137], v[214:217], v[14:17]
	v_mfma_f32_16x16x32_bf16 v[10:13], v[142:145], v[214:217], v[10:13]
	s_setprio 2
	s_setprio 0
	v_mfma_f32_16x16x32_bf16 v[54:57], v[162:165], v[186:189], v[54:57]
	v_mfma_f32_16x16x32_bf16 v[50:53], v[178:181], v[186:189], v[50:53]
	v_mfma_f32_16x16x32_bf16 v[38:41], v[162:165], v[194:197], v[38:41]
	v_mfma_f32_16x16x32_bf16 v[34:37], v[178:181], v[194:197], v[34:37]
	v_mfma_f32_16x16x32_bf16 v[22:25], v[162:165], v[202:205], v[22:25]
	v_mfma_f32_16x16x32_bf16 v[18:21], v[178:181], v[202:205], v[18:21]
	v_mfma_f32_16x16x32_bf16 v[6:9], v[162:165], v[210:213], v[6:9]
	v_mfma_f32_16x16x32_bf16 v[2:5], v[178:181], v[210:213], v[2:5]
	v_mfma_f32_16x16x32_bf16 v[54:57], v[174:177], v[190:193], v[54:57]
	v_mfma_f32_16x16x32_bf16 v[50:53], v[182:185], v[190:193], v[50:53]
	v_mfma_f32_16x16x32_bf16 v[38:41], v[174:177], v[198:201], v[38:41]
	v_mfma_f32_16x16x32_bf16 v[34:37], v[182:185], v[198:201], v[34:37]
	v_mfma_f32_16x16x32_bf16 v[22:25], v[174:177], v[206:209], v[22:25]
	v_mfma_f32_16x16x32_bf16 v[18:21], v[182:185], v[206:209], v[18:21]
	v_mfma_f32_16x16x32_bf16 v[6:9], v[174:177], v[214:217], v[6:9]
	v_mfma_f32_16x16x32_bf16 v[2:5], v[182:185], v[214:217], v[2:5]
	s_setprio 2
	s_barrier
; #define PG8_STAGE(bufoff, gbase, voff) do { _Pragma("unroll") for (int _i = 0; _i < 2; ++_i) \
;         __builtin_amdgcn_global_load_lds((const unsigned*)((const char*)(gbase) + (voff)[_i]), (LAS unsigned*)(lds + (bufoff) + ldsw + _i * 8192), 16, 0, 0); } while (0)
; #define PG8_LDA(dst, b, h) do { _Pragma("unroll") for (int m = 0; m < 4; ++m) _Pragma("unroll") for (int k = 0; k < 2; ++k) dst[m][k] = *(const LAS bf16x8*)(lds + PG8_SA(b, h) + aoff + m * 2048 + k * 1024); } while (0)
; #define PG8_LDB(dst, b, h) do { _Pragma("unroll") for (int n = 0; n < 2; ++n) _Pragma("unroll") for (int k = 0; k < 2; ++k) dst[n][k] = *(const LAS bf16x8*)(lds + PG8_SB(b, h) + boff + n * 2048 + k * 1024); } while (0)
; #define PG8_MMA(ai, bj, At, Bt) do { __builtin_amdgcn_s_setprio(1); _Pragma("unroll") for (int m = 0; m < 4; ++m) _Pragma("unroll") for (int n = 0; n < 2; ++n) _Pragma("unroll") for (int k = 0; k < 2; ++k) \
;         acc[ai][bj][m][n] = __builtin_amdgcn_mfma_f32_16x16x32_bf16(Bt[n][k], At[m][k], acc[ai][bj][m][n], 0, 0, 0); __builtin_amdgcn_s_setprio(0); } while (0)
; #define PG8_WAIT_V(n) asm volatile("s_waitcnt vmcnt(" #n ")" ::: "memory")
; #define PG8_WAIT_L(n) asm volatile("s_waitcnt lgkmcnt(" #n ")" ::: "memory")
; #define PG8_BAR __builtin_amdgcn_s_barrier()
; #define PG8_SCHED __builtin_amdgcn_sched_barrier(0)
; template <class Epi>
; __device__ __forceinline__ void gemm_phase(LAS unsigned char* lds, const Gemm g, int G, int c, const Epi& E) {
;     ...
;             PG8_LDB(B0, 1, 0); PG8_LDB(B1, 1, 1); PG8_SCHED; PG8_LDA(At, 1, 0); PG8_STAGE(PG8_SA(0, 1), a2 + hstepA, voffA);
;             PG8_WAIT_V(8); PG8_WAIT_L(0); PG8_BAR; PG8_MMA(0, 0, At, B0); PG8_MMA(0, 1, At, B1); PG8_BAR; PG8_SCHED;
	s_add_i32 s33, 0, 0x18000
	s_add_i32 s47, 0, 0x1c000
	v_add_u32_e32 v142, s33, v169
	v_add_u32_e32 v173, s47, v169
	ds_read_b128 v[130:133], v142
	ds_read_b128 v[134:137], v142 offset:1024
	ds_read_b128 v[138:141], v142 offset:2048
	ds_read_b128 v[142:145], v142 offset:3072
	ds_read_b128 v[162:165], v173
	ds_read_b128 v[174:177], v173 offset:1024
	ds_read_b128 v[178:181], v173 offset:2048
	ds_read_b128 v[182:185], v173 offset:3072
	s_add_u32 s44, s44, 0x40000
	s_addc_u32 s45, s45, 0
	s_mov_b32 m0, s58
	v_lshl_add_u64 v[224:225], s[44:45], 0, v[152:153]
	ds_read_b128 v[186:189], v172 offset:32768
	ds_read_b128 v[190:193], v172 offset:33792
	ds_read_b128 v[194:197], v172 offset:34816
	ds_read_b128 v[198:201], v172 offset:35840
	ds_read_b128 v[202:205], v172 offset:36864
	ds_read_b128 v[206:209], v172 offset:37888
	ds_read_b128 v[210:213], v172 offset:38912
	ds_read_b128 v[214:217], v172 offset:39936
	global_load_lds_dwordx4 v[224:225], off
	v_lshl_add_u64 v[224:225], s[44:45], 0, v[148:149]
	s_mov_b32 m0, s59
	s_nop 0
	global_load_lds_dwordx4 v[224:225], off
	s_waitcnt vmcnt(8)
	s_waitcnt lgkmcnt(0)
	s_barrier
	s_setprio 0
	v_mfma_f32_16x16x32_bf16 v[126:129], v[130:133], v[186:189], v[126:129]
	v_mfma_f32_16x16x32_bf16 v[122:125], v[138:141], v[186:189], v[122:125]
	v_mfma_f32_16x16x32_bf16 v[110:113], v[130:133], v[194:197], v[110:113]
	v_mfma_f32_16x16x32_bf16 v[106:109], v[138:141], v[194:197], v[106:109]
	v_mfma_f32_16x16x32_bf16 v[94:97], v[130:133], v[202:205], v[94:97]
	v_mfma_f32_16x16x32_bf16 v[90:93], v[138:141], v[202:205], v[90:93]
	v_mfma_f32_16x16x32_bf16 v[78:81], v[130:133], v[210:213], v[78:81]
	v_mfma_f32_16x16x32_bf16 v[74:77], v[138:141], v[210:213], v[74:77]
	v_mfma_f32_16x16x32_bf16 v[126:129], v[134:137], v[190:193], v[126:129]
	v_mfma_f32_16x16x32_bf16 v[122:125], v[142:145], v[190:193], v[122:125]
	v_mfma_f32_16x16x32_bf16 v[110:113], v[134:137], v[198:201], v[110:113]
	v_mfma_f32_16x16x32_bf16 v[106:109], v[142:145], v[198:201], v[106:109]
	v_mfma_f32_16x16x32_bf16 v[94:97], v[134:137], v[206:209], v[94:97]
	v_mfma_f32_16x16x32_bf16 v[90:93], v[142:145], v[206:209], v[90:93]
	v_mfma_f32_16x16x32_bf16 v[78:81], v[134:137], v[214:217], v[78:81]
	v_mfma_f32_16x16x32_bf16 v[74:77], v[142:145], v[214:217], v[74:77]
	s_setprio 2
	s_setprio 0
	v_mfma_f32_16x16x32_bf16 v[118:121], v[162:165], v[186:189], v[118:121]
	v_mfma_f32_16x16x32_bf16 v[114:117], v[178:181], v[186:189], v[114:117]
	v_mfma_f32_16x16x32_bf16 v[102:105], v[162:165], v[194:197], v[102:105]
	v_mfma_f32_16x16x32_bf16 v[98:101], v[178:181], v[194:197], v[98:101]
	v_mfma_f32_16x16x32_bf16 v[86:89], v[162:165], v[202:205], v[86:89]
	v_mfma_f32_16x16x32_bf16 v[82:85], v[178:181], v[202:205], v[82:85]
	v_mfma_f32_16x16x32_bf16 v[70:73], v[162:165], v[210:213], v[70:73]
	v_mfma_f32_16x16x32_bf16 v[66:69], v[178:181], v[210:213], v[66:69]
	v_mfma_f32_16x16x32_bf16 v[118:121], v[174:177], v[190:193], v[118:121]
	v_mfma_f32_16x16x32_bf16 v[114:117], v[182:185], v[190:193], v[114:117]
	v_mfma_f32_16x16x32_bf16 v[102:105], v[174:177], v[198:201], v[102:105]
	v_mfma_f32_16x16x32_bf16 v[98:101], v[182:185], v[198:201], v[98:101]
	v_mfma_f32_16x16x32_bf16 v[86:89], v[174:177], v[206:209], v[86:89]
	v_mfma_f32_16x16x32_bf16 v[82:85], v[182:185], v[206:209], v[82:85]
	v_mfma_f32_16x16x32_bf16 v[70:73], v[174:177], v[214:217], v[70:73]
	v_mfma_f32_16x16x32_bf16 v[66:69], v[182:185], v[214:217], v[66:69]
	s_setprio 2
	s_barrier
; #define PG8_STAGE(bufoff, gbase, voff) do { _Pragma("unroll") for (int _i = 0; _i < 2; ++_i) \
;         __builtin_amdgcn_global_load_lds((const unsigned*)((const char*)(gbase) + (voff)[_i]), (LAS unsigned*)(lds + (bufoff) + ldsw + _i * 8192), 16, 0, 0); } while (0)
; #define PG8_LDA(dst, b, h) do { _Pragma("unroll") for (int m = 0; m < 4; ++m) _Pragma("unroll") for (int k = 0; k < 2; ++k) dst[m][k] = *(const LAS bf16x8*)(lds + PG8_SA(b, h) + aoff + m * 2048 + k * 1024); } while (0)
; #define PG8_MMA(ai, bj, At, Bt) do { __builtin_amdgcn_s_setprio(1); _Pragma("unroll") for (int m = 0; m < 4; ++m) _Pragma("unroll") for (int n = 0; n < 2; ++n) _Pragma("unroll") for (int k = 0; k < 2; ++k) \
;         acc[ai][bj][m][n] = __builtin_amdgcn_mfma_f32_16x16x32_bf16(Bt[n][k], At[m][k], acc[ai][bj][m][n], 0, 0, 0); __builtin_amdgcn_s_setprio(0); } while (0)
; #define PG8_WAIT_V(n) asm volatile("s_waitcnt vmcnt(" #n ")" ::: "memory")
; #define PG8_WAIT_L(n) asm volatile("s_waitcnt lgkmcnt(" #n ")" ::: "memory")
; #define PG8_BAR __builtin_amdgcn_s_barrier()
; #define PG8_SCHED __builtin_amdgcn_sched_barrier(0)
; template <class Epi>
; __device__ __forceinline__ void gemm_phase(LAS unsigned char* lds, const Gemm g, int G, int c, const Epi& E) {
;     ...
;             PG8_LDA(At, 1, 1); PG8_STAGE(PG8_SB(1, 0), b3, voffB); PG8_STAGE(PG8_SB(1, 1), b3 + hstepB, voffB); PG8_STAGE(PG8_SA(1, 0), a3, voffA);
;             PG8_WAIT_V(8); PG8_WAIT_L(0); PG8_BAR; PG8_MMA(1, 0, At, B0); PG8_MMA(1, 1, At, B1); PG8_BAR; PG8_SCHED;
;         }
;         if (wr == 0) PG8_BAR;
	s_add_i32 s33, s33, s54
	v_lshl_add_u64 v[166:167], v[166:167], 0, s[10:11]
	s_mov_b32 m0, s33
	ds_read_b128 v[186:189], v172 offset:49152
	ds_read_b128 v[190:193], v172 offset:50176
	ds_read_b128 v[194:197], v172 offset:51200
	ds_read_b128 v[198:201], v172 offset:52224
	ds_read_b128 v[202:205], v172 offset:53248
	ds_read_b128 v[206:209], v172 offset:54272
	ds_read_b128 v[210:213], v172 offset:55296
	ds_read_b128 v[214:217], v172 offset:56320
	global_load_lds_dwordx4 v[166:167], off
	s_add_i32 m0, s33, 0x2000
	s_add_u32 s42, s42, 0x40080
	v_lshl_add_u64 v[166:167], v[218:219], 0, s[10:11]
	s_addc_u32 s43, s43, 0
	s_add_i32 s33, s47, s54
	global_load_lds_dwordx4 v[166:167], off
	v_lshl_add_u64 v[166:167], s[42:43], 0, v[150:151]
	s_mov_b32 m0, s33
	s_nop 0
	global_load_lds_dwordx4 v[166:167], off
	v_lshl_add_u64 v[166:167], s[42:43], 0, v[146:147]
	s_add_i32 m0, s33, 0x2000
	s_nop 0
	global_load_lds_dwordx4 v[166:167], off
	v_lshl_add_u64 v[166:167], v[220:221], 0, s[10:11]
	s_mov_b32 m0, s69
	s_nop 0
	global_load_lds_dwordx4 v[166:167], off
	v_lshl_add_u64 v[166:167], v[222:223], 0, s[10:11]
	s_mov_b32 m0, s70
	s_nop 0
	global_load_lds_dwordx4 v[166:167], off
	s_waitcnt vmcnt(8)
	s_waitcnt lgkmcnt(0)
	s_barrier
	s_setprio 0
	v_mfma_f32_16x16x32_bf16 v[62:65], v[130:133], v[186:189], v[62:65]
	v_mfma_f32_16x16x32_bf16 v[58:61], v[138:141], v[186:189], v[58:61]
	v_mfma_f32_16x16x32_bf16 v[46:49], v[130:133], v[194:197], v[46:49]
	v_mfma_f32_16x16x32_bf16 v[42:45], v[138:141], v[194:197], v[42:45]
	v_mfma_f32_16x16x32_bf16 v[30:33], v[130:133], v[202:205], v[30:33]
	v_mfma_f32_16x16x32_bf16 v[26:29], v[138:141], v[202:205], v[26:29]
	v_mfma_f32_16x16x32_bf16 v[14:17], v[130:133], v[210:213], v[14:17]
	v_mfma_f32_16x16x32_bf16 v[10:13], v[138:141], v[210:213], v[10:13]
	v_mfma_f32_16x16x32_bf16 v[62:65], v[134:137], v[190:193], v[62:65]
	v_mfma_f32_16x16x32_bf16 v[58:61], v[142:145], v[190:193], v[58:61]
	v_mfma_f32_16x16x32_bf16 v[46:49], v[134:137], v[198:201], v[46:49]
	v_mfma_f32_16x16x32_bf16 v[42:45], v[142:145], v[198:201], v[42:45]
	v_mfma_f32_16x16x32_bf16 v[30:33], v[134:137], v[206:209], v[30:33]
	v_mfma_f32_16x16x32_bf16 v[26:29], v[142:145], v[206:209], v[26:29]
	v_mfma_f32_16x16x32_bf16 v[14:17], v[134:137], v[214:217], v[14:17]
	v_mfma_f32_16x16x32_bf16 v[10:13], v[142:145], v[214:217], v[10:13]
	s_setprio 2
	s_setprio 0
	v_mfma_f32_16x16x32_bf16 v[54:57], v[162:165], v[186:189], v[54:57]
	v_mfma_f32_16x16x32_bf16 v[50:53], v[178:181], v[186:189], v[50:53]
	v_mfma_f32_16x16x32_bf16 v[38:41], v[162:165], v[194:197], v[38:41]
	v_mfma_f32_16x16x32_bf16 v[34:37], v[178:181], v[194:197], v[34:37]
	v_mfma_f32_16x16x32_bf16 v[22:25], v[162:165], v[202:205], v[22:25]
	v_mfma_f32_16x16x32_bf16 v[18:21], v[178:181], v[202:205], v[18:21]
	v_mfma_f32_16x16x32_bf16 v[6:9], v[162:165], v[210:213], v[6:9]
	v_mfma_f32_16x16x32_bf16 v[2:5], v[178:181], v[210:213], v[2:5]
	v_mfma_f32_16x16x32_bf16 v[54:57], v[174:177], v[190:193], v[54:57]
	v_mfma_f32_16x16x32_bf16 v[50:53], v[182:185], v[190:193], v[50:53]
	v_mfma_f32_16x16x32_bf16 v[38:41], v[174:177], v[198:201], v[38:41]
	v_mfma_f32_16x16x32_bf16 v[34:37], v[182:185], v[198:201], v[34:37]
	v_mfma_f32_16x16x32_bf16 v[22:25], v[174:177], v[206:209], v[22:25]
	v_mfma_f32_16x16x32_bf16 v[18:21], v[182:185], v[206:209], v[18:21]
	v_mfma_f32_16x16x32_bf16 v[6:9], v[174:177], v[214:217], v[6:9]
	v_mfma_f32_16x16x32_bf16 v[2:5], v[182:185], v[214:217], v[2:5]
	s_setprio 2
	s_barrier
	s_add_i32 s46, s46, 2
	s_add_u32 s4, s4, 0x100
	s_addc_u32 s5, s5, 0
	s_add_u32 s23, s23, 0x100
	s_addc_u32 s39, s39, 0
	s_cmp_gt_u32 s46, 13
	s_cbranch_scc0 .LBB0_903
	s_and_b64 vcc, exec, s[12:13]
	s_cbranch_vccz .LBB0_906
	s_barrier

; #define PG8_STAGE(bufoff, gbase, voff) do { _Pragma("unroll") for (int _i = 0; _i < 2; ++_i) \
;         __builtin_amdgcn_global_load_lds((const unsigned*)((const char*)(gbase) + (voff)[_i]), (LAS unsigned*)(lds + (bufoff) + ldsw + _i * 8192), 16, 0, 0); } while (0)
; #define PG8_LDA(dst, b, h) do { _Pragma("unroll") for (int m = 0; m < 4; ++m) _Pragma("unroll") for (int k = 0; k < 2; ++k) dst[m][k] = *(const LAS bf16x8*)(lds + PG8_SA(b, h) + aoff + m * 2048 + k * 1024); } while (0)
; #define PG8_LDB(dst, b, h) do { _Pragma("unroll") for (int n = 0; n < 2; ++n) _Pragma("unroll") for (int k = 0; k < 2; ++k) dst[n][k] = *(const LAS bf16x8*)(lds + PG8_SB(b, h) + boff + n * 2048 + k * 1024); } while (0)
; #define PG8_MMA(ai, bj, At, Bt) do { __builtin_amdgcn_s_setprio(1); _Pragma("unroll") for (int m = 0; m < 4; ++m) _Pragma("unroll") for (int n = 0; n < 2; ++n) _Pragma("unroll") for (int k = 0; k < 2; ++k) \
;         acc[ai][bj][m][n] = __builtin_amdgcn_mfma_f32_16x16x32_bf16(Bt[n][k], At[m][k], acc[ai][bj][m][n], 0, 0, 0); __builtin_amdgcn_s_setprio(0); } while (0)
; #define PG8_WAIT_V(n) asm volatile("s_waitcnt vmcnt(" #n ")" ::: "memory")
; template <class Epi>
; __device__ __forceinline__ void gemm_phase(LAS unsigned char* lds, const Gemm g, int G, int c, const Epi& E) {
;     ...
;         const bool has_next = S.next(ui + 1, nxt);
;         const char* nA = has_next ? (const char*)(g.A + (size_t)nxt.pb * g.sA) + (size_t)nxt.pm * 2 * hstepA : cA;
;         const char* nB = has_next ? (const char*)(g.Bt + (size_t)nxt.pb * g.sB) + (size_t)nxt.pn * 2 * hstepB : cB;
; #pragma nounroll
;         for (int t = 0; t < nt; t += 2) {
;             const bool last = (t == nt - 2);
;             const char* a1 = cA + (size_t)(t + 1) * kstep;
;             const char* a2 = last ? nA : cA + (size_t)(t + 2) * kstep; const char* b2 = last ? nB : cB + (size_t)(t + 2) * kstep;
;             const char* a3 = a2 + kstep; const char* b3 = b2 + kstep;
;             PG8_LDB(B0, 0, 0); PG8_LDB(B1, 0, 1); PG8_SCHED; PG8_LDA(At, 0, 0); PG8_STAGE(PG8_SA(1, 1), a1 + hstepA, voffA);
;             PG8_WAIT_V(8); PG8_WAIT_L(0); PG8_BAR; PG8_MMA(0, 0, At, B0); PG8_MMA(0, 1, At, B1); PG8_BAR; PG8_SCHED;
;             PG8_LDA(At, 0, 1); PG8_STAGE(PG8_SB(0, 0), b2, voffB); PG8_STAGE(PG8_SB(0, 1), b2 + hstepB, voffB); PG8_STAGE(PG8_SA(0, 0), a2, voffA);
.LBB0_1057:
	s_ashr_i32 s17, s16, 31
	s_lshl_b64 s[22:23], s[16:17], 19
	s_add_u32 s22, s35, s22
	s_addc_u32 s23, s42, s23
	s_and_b64 s[4:5], s[4:5], exec
	s_cselect_b32 s17, s23, s39
	s_cselect_b32 s19, s22, s38
	s_add_u32 s4, s40, 0x40080
	s_addc_u32 s5, s41, 0
	s_add_u32 s78, s38, 0x100
	s_addc_u32 s79, s39, 0
	s_mov_b32 s80, -2
	ds_read_b128 v[152:155], v148
	ds_read_b128 v[156:159], v148 offset:1024
	ds_read_b128 v[160:163], v148 offset:2048
	ds_read_b128 v[164:167], v148 offset:3072
	ds_read_b128 v[168:171], v149
	ds_read_b128 v[172:175], v149 offset:1024
	ds_read_b128 v[176:179], v149 offset:2048
	ds_read_b128 v[180:183], v149 offset:3072
	s_add_u32 s33, s4, 0xfffc0080
	s_addc_u32 s38, s5, -1
	s_cmp_eq_u32 s80, 12
	s_cselect_b32 s41, s21, s38
	s_cselect_b32 s40, s20, s33
	s_cselect_b32 s39, s17, s79
	s_cselect_b32 s38, s19, s78
	v_lshl_add_u64 v[216:217], s[4:5], 0, v[138:139]
	s_add_i32 m0, s25, 0xc000
	ds_read_b128 v[184:187], v150
	ds_read_b128 v[188:191], v150 offset:1024
	ds_read_b128 v[192:195], v150 offset:2048
	ds_read_b128 v[196:199], v150 offset:3072
	ds_read_b128 v[200:203], v150 offset:4096
	ds_read_b128 v[204:207], v150 offset:5120
	ds_read_b128 v[208:211], v150 offset:6144
	ds_read_b128 v[212:215], v150 offset:7168
	global_load_lds_dwordx4 v[216:217], off
	v_lshl_add_u64 v[216:217], s[4:5], 0, v[140:141]
	s_add_i32 m0, s25, 0xe000
	s_nop 0
	global_load_lds_dwordx4 v[216:217], off
	s_waitcnt vmcnt(8)
	s_waitcnt lgkmcnt(0)
	s_barrier
	s_setprio 0
	v_mfma_f32_16x16x32_bf16 v[126:129], v[152:155], v[184:187], 0
	v_mfma_f32_16x16x32_bf16 v[122:125], v[160:163], v[184:187], 0
	v_mfma_f32_16x16x32_bf16 v[110:113], v[152:155], v[192:195], 0
	v_mfma_f32_16x16x32_bf16 v[106:109], v[160:163], v[192:195], 0
	v_mfma_f32_16x16x32_bf16 v[94:97], v[152:155], v[200:203], 0
	v_mfma_f32_16x16x32_bf16 v[90:93], v[160:163], v[200:203], 0
	v_mfma_f32_16x16x32_bf16 v[78:81], v[152:155], v[208:211], 0
	v_mfma_f32_16x16x32_bf16 v[74:77], v[160:163], v[208:211], 0
	v_mfma_f32_16x16x32_bf16 v[126:129], v[156:159], v[188:191], v[126:129]
	v_mfma_f32_16x16x32_bf16 v[122:125], v[164:167], v[188:191], v[122:125]
	v_mfma_f32_16x16x32_bf16 v[110:113], v[156:159], v[196:199], v[110:113]
	v_mfma_f32_16x16x32_bf16 v[106:109], v[164:167], v[196:199], v[106:109]
	v_mfma_f32_16x16x32_bf16 v[94:97], v[156:159], v[204:207], v[94:97]
	v_mfma_f32_16x16x32_bf16 v[90:93], v[164:167], v[204:207], v[90:93]
	v_mfma_f32_16x16x32_bf16 v[78:81], v[156:159], v[212:215], v[78:81]
	v_mfma_f32_16x16x32_bf16 v[74:77], v[164:167], v[212:215], v[74:77]
	s_setprio 2
	s_setprio 0
	v_mfma_f32_16x16x32_bf16 v[118:121], v[168:171], v[184:187], 0
	v_mfma_f32_16x16x32_bf16 v[114:117], v[176:179], v[184:187], 0
	v_mfma_f32_16x16x32_bf16 v[102:105], v[168:171], v[192:195], 0
	v_mfma_f32_16x16x32_bf16 v[98:101], v[176:179], v[192:195], 0
	v_mfma_f32_16x16x32_bf16 v[86:89], v[168:171], v[200:203], 0
	v_mfma_f32_16x16x32_bf16 v[82:85], v[176:179], v[200:203], 0
	v_mfma_f32_16x16x32_bf16 v[70:73], v[168:171], v[208:211], 0
	v_mfma_f32_16x16x32_bf16 v[66:69], v[176:179], v[208:211], 0
	v_mfma_f32_16x16x32_bf16 v[118:121], v[172:175], v[188:191], v[118:121]
	v_mfma_f32_16x16x32_bf16 v[114:117], v[180:183], v[188:191], v[114:117]
	v_mfma_f32_16x16x32_bf16 v[102:105], v[172:175], v[196:199], v[102:105]
	v_mfma_f32_16x16x32_bf16 v[98:101], v[180:183], v[196:199], v[98:101]
	v_mfma_f32_16x16x32_bf16 v[86:89], v[172:175], v[204:207], v[86:89]
	v_mfma_f32_16x16x32_bf16 v[82:85], v[180:183], v[204:207], v[82:85]
	v_mfma_f32_16x16x32_bf16 v[70:73], v[172:175], v[212:215], v[70:73]
	v_mfma_f32_16x16x32_bf16 v[66:69], v[180:183], v[212:215], v[66:69]
	s_setprio 2
	s_barrier
	s_add_i32 s33, s60, s46
	v_lshl_add_u64 v[216:217], s[38:39], 0, v[134:135]
	s_mov_b32 m0, s33
	ds_read_b128 v[184:187], v150 offset:16384
	ds_read_b128 v[188:191], v150 offset:17408
	ds_read_b128 v[192:195], v150 offset:18432
	ds_read_b128 v[196:199], v150 offset:19456
	ds_read_b128 v[200:203], v150 offset:20480
	ds_read_b128 v[204:207], v150 offset:21504
	ds_read_b128 v[208:211], v150 offset:22528
	ds_read_b128 v[212:215], v150 offset:23552
	global_load_lds_dwordx4 v[216:217], off
	s_add_i32 m0, s33, 0x2000
	s_add_u32 s62, s38, 0x40000
	v_lshl_add_u64 v[218:219], s[38:39], 0, v[130:131]
	s_addc_u32 s63, s39, 0
	s_add_i32 s33, s61, s46
	global_load_lds_dwordx4 v[218:219], off
	v_lshl_add_u64 v[220:221], s[62:63], 0, v[134:135]
	s_mov_b32 m0, s33
	v_lshl_add_u64 v[222:223], s[40:41], 0, v[132:133]
	global_load_lds_dwordx4 v[220:221], off
	v_lshl_add_u64 v[220:221], s[62:63], 0, v[130:131]
	s_add_i32 m0, s33, 0x2000
	s_nop 0
	global_load_lds_dwordx4 v[220:221], off
	v_lshl_add_u64 v[220:221], s[40:41], 0, v[136:137]
	s_mov_b32 m0, s25
	s_nop 0
	global_load_lds_dwordx4 v[220:221], off
	s_mov_b32 m0, s37
	s_nop 0
	global_load_lds_dwordx4 v[222:223], off
	s_waitcnt vmcnt(8)
	s_waitcnt lgkmcnt(0)
	s_barrier
; #define PG8_STAGE(bufoff, gbase, voff) do { _Pragma("unroll") for (int _i = 0; _i < 2; ++_i) \
;         __builtin_amdgcn_global_load_lds((const unsigned*)((const char*)(gbase) + (voff)[_i]), (LAS unsigned*)(lds + (bufoff) + ldsw + _i * 8192), 16, 0, 0); } while (0)
; #define PG8_LDA(dst, b, h) do { _Pragma("unroll") for (int m = 0; m < 4; ++m) _Pragma("unroll") for (int k = 0; k < 2; ++k) dst[m][k] = *(const LAS bf16x8*)(lds + PG8_SA(b, h) + aoff + m * 2048 + k * 1024); } while (0)
; #define PG8_LDB(dst, b, h) do { _Pragma("unroll") for (int n = 0; n < 2; ++n) _Pragma("unroll") for (int k = 0; k < 2; ++k) dst[n][k] = *(const LAS bf16x8*)(lds + PG8_SB(b, h) + boff + n * 2048 + k * 1024); } while (0)
; #define PG8_MMA(ai, bj, At, Bt) do { __builtin_amdgcn_s_setprio(1); _Pragma("unroll") for (int m = 0; m < 4; ++m) _Pragma("unroll") for (int n = 0; n < 2; ++n) _Pragma("unroll") for (int k = 0; k < 2; ++k) \
;         acc[ai][bj][m][n] = __builtin_amdgcn_mfma_f32_16x16x32_bf16(Bt[n][k], At[m][k], acc[ai][bj][m][n], 0, 0, 0); __builtin_amdgcn_s_setprio(0); } while (0)
; #define PG8_WAIT_V(n) asm volatile("s_waitcnt vmcnt(" #n ")" ::: "memory")
; #define PG8_WAIT_L(n) asm volatile("s_waitcnt lgkmcnt(" #n ")" ::: "memory")
; #define PG8_BAR __builtin_amdgcn_s_barrier()
; #define PG8_SCHED __builtin_amdgcn_sched_barrier(0)
; template <class Epi>
; __device__ __forceinline__ void gemm_phase(LAS unsigned char* lds, const Gemm g, int G, int c, const Epi& E) {
;     ...
;             PG8_WAIT_V(8); PG8_WAIT_L(0); PG8_BAR; PG8_MMA(1, 0, At, B0); PG8_MMA(1, 1, At, B1); PG8_BAR; PG8_SCHED;
;             PG8_LDB(B0, 1, 0); PG8_LDB(B1, 1, 1); PG8_SCHED; PG8_LDA(At, 1, 0); PG8_STAGE(PG8_SA(0, 1), a2 + hstepA, voffA);
;             PG8_WAIT_V(8); PG8_WAIT_L(0); PG8_BAR; PG8_MMA(0, 0, At, B0); PG8_MMA(0, 1, At, B1); PG8_BAR; PG8_SCHED;
	s_setprio 0
	v_mfma_f32_16x16x32_bf16 v[62:65], v[152:155], v[184:187], 0
	v_mfma_f32_16x16x32_bf16 v[58:61], v[160:163], v[184:187], 0
	v_mfma_f32_16x16x32_bf16 v[46:49], v[152:155], v[192:195], 0
	v_mfma_f32_16x16x32_bf16 v[42:45], v[160:163], v[192:195], 0
	v_mfma_f32_16x16x32_bf16 v[30:33], v[152:155], v[200:203], 0
	v_mfma_f32_16x16x32_bf16 v[26:29], v[160:163], v[200:203], 0
	v_mfma_f32_16x16x32_bf16 v[14:17], v[152:155], v[208:211], 0
	v_mfma_f32_16x16x32_bf16 v[10:13], v[160:163], v[208:211], 0
	v_mfma_f32_16x16x32_bf16 v[62:65], v[156:159], v[188:191], v[62:65]
	v_mfma_f32_16x16x32_bf16 v[58:61], v[164:167], v[188:191], v[58:61]
	v_mfma_f32_16x16x32_bf16 v[46:49], v[156:159], v[196:199], v[46:49]
	v_mfma_f32_16x16x32_bf16 v[42:45], v[164:167], v[196:199], v[42:45]
	v_mfma_f32_16x16x32_bf16 v[30:33], v[156:159], v[204:207], v[30:33]
	v_mfma_f32_16x16x32_bf16 v[26:29], v[164:167], v[204:207], v[26:29]
	v_mfma_f32_16x16x32_bf16 v[14:17], v[156:159], v[212:215], v[14:17]
	v_mfma_f32_16x16x32_bf16 v[10:13], v[164:167], v[212:215], v[10:13]
	s_setprio 2
	s_setprio 0
	v_mfma_f32_16x16x32_bf16 v[54:57], v[168:171], v[184:187], 0
	v_mfma_f32_16x16x32_bf16 v[50:53], v[176:179], v[184:187], 0
	v_mfma_f32_16x16x32_bf16 v[38:41], v[168:171], v[192:195], 0
	v_mfma_f32_16x16x32_bf16 v[34:37], v[176:179], v[192:195], 0
	v_mfma_f32_16x16x32_bf16 v[22:25], v[168:171], v[200:203], 0
	v_mfma_f32_16x16x32_bf16 v[18:21], v[176:179], v[200:203], 0
	v_mfma_f32_16x16x32_bf16 v[6:9], v[168:171], v[208:211], 0
	v_mfma_f32_16x16x32_bf16 v[2:5], v[176:179], v[208:211], 0
	v_mfma_f32_16x16x32_bf16 v[54:57], v[172:175], v[188:191], v[54:57]
	v_mfma_f32_16x16x32_bf16 v[50:53], v[180:183], v[188:191], v[50:53]
	v_mfma_f32_16x16x32_bf16 v[38:41], v[172:175], v[196:199], v[38:41]
	v_mfma_f32_16x16x32_bf16 v[34:37], v[180:183], v[196:199], v[34:37]
	v_mfma_f32_16x16x32_bf16 v[22:25], v[172:175], v[204:207], v[22:25]
	v_mfma_f32_16x16x32_bf16 v[18:21], v[180:183], v[204:207], v[18:21]
	v_mfma_f32_16x16x32_bf16 v[6:9], v[172:175], v[212:215], v[6:9]
	v_mfma_f32_16x16x32_bf16 v[2:5], v[180:183], v[212:215], v[2:5]
	s_setprio 2
	s_barrier
	s_add_i32 s33, 0, 0x18000
	s_add_i32 s62, 0, 0x1c000
	v_add_u32_e32 v164, s33, v147
	v_add_u32_e32 v180, s62, v147
	ds_read_b128 v[152:155], v164
	ds_read_b128 v[156:159], v164 offset:1024
	ds_read_b128 v[160:163], v164 offset:2048
	ds_read_b128 v[164:167], v164 offset:3072
	ds_read_b128 v[168:171], v180
	ds_read_b128 v[172:175], v180 offset:1024
	ds_read_b128 v[176:179], v180 offset:2048
	ds_read_b128 v[180:183], v180 offset:3072
	s_add_u32 s40, s40, 0x40000
	s_addc_u32 s41, s41, 0
	s_mov_b32 m0, s47
	v_lshl_add_u64 v[224:225], s[40:41], 0, v[136:137]
	ds_read_b128 v[184:187], v150 offset:32768
	ds_read_b128 v[188:191], v150 offset:33792
	ds_read_b128 v[192:195], v150 offset:34816
	ds_read_b128 v[196:199], v150 offset:35840
	ds_read_b128 v[200:203], v150 offset:36864
	ds_read_b128 v[204:207], v150 offset:37888
	ds_read_b128 v[208:211], v150 offset:38912
	ds_read_b128 v[212:215], v150 offset:39936
	global_load_lds_dwordx4 v[224:225], off
	v_lshl_add_u64 v[224:225], s[40:41], 0, v[132:133]
	s_mov_b32 m0, s52
	s_nop 0
	global_load_lds_dwordx4 v[224:225], off
	s_waitcnt vmcnt(8)
	s_waitcnt lgkmcnt(0)
	s_barrier
	s_setprio 0
	v_mfma_f32_16x16x32_bf16 v[126:129], v[152:155], v[184:187], v[126:129]
	v_mfma_f32_16x16x32_bf16 v[122:125], v[160:163], v[184:187], v[122:125]
	v_mfma_f32_16x16x32_bf16 v[110:113], v[152:155], v[192:195], v[110:113]
	v_mfma_f32_16x16x32_bf16 v[106:109], v[160:163], v[192:195], v[106:109]
	v_mfma_f32_16x16x32_bf16 v[94:97], v[152:155], v[200:203], v[94:97]
	v_mfma_f32_16x16x32_bf16 v[90:93], v[160:163], v[200:203], v[90:93]
	v_mfma_f32_16x16x32_bf16 v[78:81], v[152:155], v[208:211], v[78:81]
	v_mfma_f32_16x16x32_bf16 v[74:77], v[160:163], v[208:211], v[74:77]
	v_mfma_f32_16x16x32_bf16 v[126:129], v[156:159], v[188:191], v[126:129]
	v_mfma_f32_16x16x32_bf16 v[122:125], v[164:167], v[188:191], v[122:125]
	v_mfma_f32_16x16x32_bf16 v[110:113], v[156:159], v[196:199], v[110:113]
	v_mfma_f32_16x16x32_bf16 v[106:109], v[164:167], v[196:199], v[106:109]
	v_mfma_f32_16x16x32_bf16 v[94:97], v[156:159], v[204:207], v[94:97]
	v_mfma_f32_16x16x32_bf16 v[90:93], v[164:167], v[204:207], v[90:93]
	v_mfma_f32_16x16x32_bf16 v[78:81], v[156:159], v[212:215], v[78:81]
	v_mfma_f32_16x16x32_bf16 v[74:77], v[164:167], v[212:215], v[74:77]
	s_setprio 2
	s_setprio 0
	v_mfma_f32_16x16x32_bf16 v[118:121], v[168:171], v[184:187], v[118:121]
	v_mfma_f32_16x16x32_bf16 v[114:117], v[176:179], v[184:187], v[114:117]
	v_mfma_f32_16x16x32_bf16 v[102:105], v[168:171], v[192:195], v[102:105]
	v_mfma_f32_16x16x32_bf16 v[98:101], v[176:179], v[192:195], v[98:101]
	v_mfma_f32_16x16x32_bf16 v[86:89], v[168:171], v[200:203], v[86:89]
	v_mfma_f32_16x16x32_bf16 v[82:85], v[176:179], v[200:203], v[82:85]
	v_mfma_f32_16x16x32_bf16 v[70:73], v[168:171], v[208:211], v[70:73]
	v_mfma_f32_16x16x32_bf16 v[66:69], v[176:179], v[208:211], v[66:69]
	v_mfma_f32_16x16x32_bf16 v[118:121], v[172:175], v[188:191], v[118:121]
	v_mfma_f32_16x16x32_bf16 v[114:117], v[180:183], v[188:191], v[114:117]
	v_mfma_f32_16x16x32_bf16 v[102:105], v[172:175], v[196:199], v[102:105]
	v_mfma_f32_16x16x32_bf16 v[98:101], v[180:183], v[196:199], v[98:101]
	v_mfma_f32_16x16x32_bf16 v[86:89], v[172:175], v[204:207], v[86:89]
	v_mfma_f32_16x16x32_bf16 v[82:85], v[180:183], v[204:207], v[82:85]
	v_mfma_f32_16x16x32_bf16 v[70:73], v[172:175], v[212:215], v[70:73]
	v_mfma_f32_16x16x32_bf16 v[66:69], v[180:183], v[212:215], v[66:69]
	s_setprio 2
	s_barrier
; #define PG8_STAGE(bufoff, gbase, voff) do { _Pragma("unroll") for (int _i = 0; _i < 2; ++_i) \
;         __builtin_amdgcn_global_load_lds((const unsigned*)((const char*)(gbase) + (voff)[_i]), (LAS unsigned*)(lds + (bufoff) + ldsw + _i * 8192), 16, 0, 0); } while (0)
; #define PG8_LDA(dst, b, h) do { _Pragma("unroll") for (int m = 0; m < 4; ++m) _Pragma("unroll") for (int k = 0; k < 2; ++k) dst[m][k] = *(const LAS bf16x8*)(lds + PG8_SA(b, h) + aoff + m * 2048 + k * 1024); } while (0)
; #define PG8_LDB(dst, b, h) do { _Pragma("unroll") for (int n = 0; n < 2; ++n) _Pragma("unroll") for (int k = 0; k < 2; ++k) dst[n][k] = *(const LAS bf16x8*)(lds + PG8_SB(b, h) + boff + n * 2048 + k * 1024); } while (0)
; #define PG8_MMA(ai, bj, At, Bt) do { __builtin_amdgcn_s_setprio(1); _Pragma("unroll") for (int m = 0; m < 4; ++m) _Pragma("unroll") for (int n = 0; n < 2; ++n) _Pragma("unroll") for (int k = 0; k < 2; ++k) \
;         acc[ai][bj][m][n] = __builtin_amdgcn_mfma_f32_16x16x32_bf16(Bt[n][k], At[m][k], acc[ai][bj][m][n], 0, 0, 0); __builtin_amdgcn_s_setprio(0); } while (0)
; #define PG8_WAIT_V(n) asm volatile("s_waitcnt vmcnt(" #n ")" ::: "memory")
; #define PG8_BAR __builtin_amdgcn_s_barrier()
; template <class Epi>
; __device__ __forceinline__ void gemm_phase(LAS unsigned char* lds, const Gemm g, int G, int c, const Epi& E) {
;     ...
;             PG8_LDB(B0, 0, 0); PG8_LDB(B1, 0, 1); PG8_SCHED; PG8_LDA(At, 0, 0); PG8_STAGE(PG8_SA(1, 1), a1 + hstepA, voffA);
;             PG8_WAIT_V(8); PG8_WAIT_L(0); PG8_BAR; PG8_MMA(0, 0, At, B0); PG8_MMA(0, 1, At, B1); PG8_BAR; PG8_SCHED;
;             PG8_LDA(At, 0, 1); PG8_STAGE(PG8_SB(0, 0), b2, voffB); PG8_STAGE(PG8_SB(0, 1), b2 + hstepB, voffB); PG8_STAGE(PG8_SA(0, 0), a2, voffA);
;             PG8_WAIT_V(8); PG8_WAIT_L(0); PG8_BAR; PG8_MMA(1, 0, At, B0); PG8_MMA(1, 1, At, B1); PG8_BAR; PG8_SCHED;
;             PG8_LDB(B0, 1, 0); PG8_LDB(B1, 1, 1); PG8_SCHED; PG8_LDA(At, 1, 0); PG8_STAGE(PG8_SA(0, 1), a2 + hstepA, voffA);
;             PG8_WAIT_V(8); PG8_WAIT_L(0); PG8_BAR; PG8_MMA(0, 0, At, B0); PG8_MMA(0, 1, At, B1); PG8_BAR; PG8_SCHED;
;             PG8_LDA(At, 1, 1); PG8_STAGE(PG8_SB(1, 0), b3, voffB); PG8_STAGE(PG8_SB(1, 1), b3 + hstepB, voffB); PG8_STAGE(PG8_SA(1, 0), a3, voffA);
;             PG8_WAIT_V(8); PG8_WAIT_L(0); PG8_BAR; PG8_MMA(1, 0, At, B0); PG8_MMA(1, 1, At, B1); PG8_BAR; PG8_SCHED;
	s_add_i32 s33, s33, s46
	v_lshl_add_u64 v[216:217], v[216:217], 0, s[12:13]
	s_mov_b32 m0, s33
	ds_read_b128 v[184:187], v150 offset:49152
	ds_read_b128 v[188:191], v150 offset:50176
	ds_read_b128 v[192:195], v150 offset:51200
	ds_read_b128 v[196:199], v150 offset:52224
	ds_read_b128 v[200:203], v150 offset:53248
	ds_read_b128 v[204:207], v150 offset:54272
	ds_read_b128 v[208:211], v150 offset:55296
	ds_read_b128 v[212:215], v150 offset:56320
	global_load_lds_dwordx4 v[216:217], off
	s_add_i32 m0, s33, 0x2000
	s_add_u32 s38, s38, 0x40080
	v_lshl_add_u64 v[216:217], v[218:219], 0, s[12:13]
	s_addc_u32 s39, s39, 0
	s_add_i32 s33, s62, s46
	global_load_lds_dwordx4 v[216:217], off
	v_lshl_add_u64 v[216:217], s[38:39], 0, v[134:135]
	s_mov_b32 m0, s33
	s_nop 0
	global_load_lds_dwordx4 v[216:217], off
	v_lshl_add_u64 v[216:217], s[38:39], 0, v[130:131]
	s_add_i32 m0, s33, 0x2000
	s_nop 0
	global_load_lds_dwordx4 v[216:217], off
	v_lshl_add_u64 v[216:217], v[220:221], 0, s[12:13]
	s_mov_b32 m0, s57
	s_nop 0
	global_load_lds_dwordx4 v[216:217], off
	v_lshl_add_u64 v[216:217], v[222:223], 0, s[12:13]
	s_mov_b32 m0, s58
	s_nop 0
	global_load_lds_dwordx4 v[216:217], off
	s_waitcnt vmcnt(8)
	s_waitcnt lgkmcnt(0)
	s_barrier
	s_setprio 0
	v_mfma_f32_16x16x32_bf16 v[62:65], v[152:155], v[184:187], v[62:65]
	v_mfma_f32_16x16x32_bf16 v[58:61], v[160:163], v[184:187], v[58:61]
	v_mfma_f32_16x16x32_bf16 v[46:49], v[152:155], v[192:195], v[46:49]
	v_mfma_f32_16x16x32_bf16 v[42:45], v[160:163], v[192:195], v[42:45]
	v_mfma_f32_16x16x32_bf16 v[30:33], v[152:155], v[200:203], v[30:33]
	v_mfma_f32_16x16x32_bf16 v[26:29], v[160:163], v[200:203], v[26:29]
	v_mfma_f32_16x16x32_bf16 v[14:17], v[152:155], v[208:211], v[14:17]
	v_mfma_f32_16x16x32_bf16 v[10:13], v[160:163], v[208:211], v[10:13]
	v_mfma_f32_16x16x32_bf16 v[62:65], v[156:159], v[188:191], v[62:65]
	v_mfma_f32_16x16x32_bf16 v[58:61], v[164:167], v[188:191], v[58:61]
	v_mfma_f32_16x16x32_bf16 v[46:49], v[156:159], v[196:199], v[46:49]
	v_mfma_f32_16x16x32_bf16 v[42:45], v[164:167], v[196:199], v[42:45]
	v_mfma_f32_16x16x32_bf16 v[30:33], v[156:159], v[204:207], v[30:33]
	v_mfma_f32_16x16x32_bf16 v[26:29], v[164:167], v[204:207], v[26:29]
	v_mfma_f32_16x16x32_bf16 v[14:17], v[156:159], v[212:215], v[14:17]
	v_mfma_f32_16x16x32_bf16 v[10:13], v[164:167], v[212:215], v[10:13]
	s_setprio 2
	s_setprio 0
	v_mfma_f32_16x16x32_bf16 v[54:57], v[168:171], v[184:187], v[54:57]
	v_mfma_f32_16x16x32_bf16 v[50:53], v[176:179], v[184:187], v[50:53]
	v_mfma_f32_16x16x32_bf16 v[38:41], v[168:171], v[192:195], v[38:41]
	v_mfma_f32_16x16x32_bf16 v[34:37], v[176:179], v[192:195], v[34:37]
	v_mfma_f32_16x16x32_bf16 v[22:25], v[168:171], v[200:203], v[22:25]
	v_mfma_f32_16x16x32_bf16 v[18:21], v[176:179], v[200:203], v[18:21]
	v_mfma_f32_16x16x32_bf16 v[6:9], v[168:171], v[208:211], v[6:9]
	v_mfma_f32_16x16x32_bf16 v[2:5], v[176:179], v[208:211], v[2:5]
	v_mfma_f32_16x16x32_bf16 v[54:57], v[172:175], v[188:191], v[54:57]
	v_mfma_f32_16x16x32_bf16 v[50:53], v[180:183], v[188:191], v[50:53]
	v_mfma_f32_16x16x32_bf16 v[38:41], v[172:175], v[196:199], v[38:41]
	v_mfma_f32_16x16x32_bf16 v[34:37], v[180:183], v[196:199], v[34:37]
	v_mfma_f32_16x16x32_bf16 v[22:25], v[172:175], v[204:207], v[22:25]
	v_mfma_f32_16x16x32_bf16 v[18:21], v[180:183], v[204:207], v[18:21]
	v_mfma_f32_16x16x32_bf16 v[6:9], v[172:175], v[212:215], v[6:9]
	v_mfma_f32_16x16x32_bf16 v[2:5], v[180:183], v[212:215], v[2:5]
	s_setprio 2
	s_barrier
	s_add_i32 s80, s80, 2
	s_add_u32 s4, s4, 0x100
	s_addc_u32 s5, s5, 0
	s_add_u32 s78, s78, 0x100
	s_addc_u32 s79, s79, 0
	s_cmp_gt_u32 s80, 13
	s_cbranch_scc0 .LBB0_1058
.LBB0_1058:
	ds_read_b128 v[152:155], v148
	ds_read_b128 v[156:159], v148 offset:1024
	ds_read_b128 v[160:163], v148 offset:2048
	ds_read_b128 v[164:167], v148 offset:3072
	ds_read_b128 v[168:171], v149
	ds_read_b128 v[172:175], v149 offset:1024
	ds_read_b128 v[176:179], v149 offset:2048
	ds_read_b128 v[180:183], v149 offset:3072
	s_add_u32 s33, s4, 0xfffc0080
	s_addc_u32 s38, s5, -1
	s_cmp_eq_u32 s80, 12
	s_cselect_b32 s41, s21, s38
	s_cselect_b32 s40, s20, s33
	s_cselect_b32 s39, s17, s79
	s_cselect_b32 s38, s19, s78
	v_lshl_add_u64 v[216:217], s[4:5], 0, v[138:139]
	s_add_i32 m0, s25, 0xc000
	ds_read_b128 v[184:187], v150
	ds_read_b128 v[188:191], v150 offset:1024
	ds_read_b128 v[192:195], v150 offset:2048
	ds_read_b128 v[196:199], v150 offset:3072
	ds_read_b128 v[200:203], v150 offset:4096
	ds_read_b128 v[204:207], v150 offset:5120
	ds_read_b128 v[208:211], v150 offset:6144
	ds_read_b128 v[212:215], v150 offset:7168
	global_load_lds_dwordx4 v[216:217], off
	v_lshl_add_u64 v[216:217], s[4:5], 0, v[140:141]
	s_add_i32 m0, s25, 0xe000
	s_nop 0
	global_load_lds_dwordx4 v[216:217], off
	s_waitcnt vmcnt(8)
	s_waitcnt lgkmcnt(0)
	s_barrier
; #define PG8_STAGE(bufoff, gbase, voff) do { _Pragma("unroll") for (int _i = 0; _i < 2; ++_i) \
;         __builtin_amdgcn_global_load_lds((const unsigned*)((const char*)(gbase) + (voff)[_i]), (LAS unsigned*)(lds + (bufoff) + ldsw + _i * 8192), 16, 0, 0); } while (0)
; #define PG8_LDA(dst, b, h) do { _Pragma("unroll") for (int m = 0; m < 4; ++m) _Pragma("unroll") for (int k = 0; k < 2; ++k) dst[m][k] = *(const LAS bf16x8*)(lds + PG8_SA(b, h) + aoff + m * 2048 + k * 1024); } while (0)
; #define PG8_MMA(ai, bj, At, Bt) do { __builtin_amdgcn_s_setprio(1); _Pragma("unroll") for (int m = 0; m < 4; ++m) _Pragma("unroll") for (int n = 0; n < 2; ++n) _Pragma("unroll") for (int k = 0; k < 2; ++k) \
;         acc[ai][bj][m][n] = __builtin_amdgcn_mfma_f32_16x16x32_bf16(Bt[n][k], At[m][k], acc[ai][bj][m][n], 0, 0, 0); __builtin_amdgcn_s_setprio(0); } while (0)
; #define PG8_WAIT_V(n) asm volatile("s_waitcnt vmcnt(" #n ")" ::: "memory")
; #define PG8_WAIT_L(n) asm volatile("s_waitcnt lgkmcnt(" #n ")" ::: "memory")
; #define PG8_BAR __builtin_amdgcn_s_barrier()
; #define PG8_SCHED __builtin_amdgcn_sched_barrier(0)
; template <class Epi>
; __device__ __forceinline__ void gemm_phase(LAS unsigned char* lds, const Gemm g, int G, int c, const Epi& E) {
;     ...
;             PG8_WAIT_V(8); PG8_WAIT_L(0); PG8_BAR; PG8_MMA(0, 0, At, B0); PG8_MMA(0, 1, At, B1); PG8_BAR; PG8_SCHED;
;             PG8_LDA(At, 0, 1); PG8_STAGE(PG8_SB(0, 0), b2, voffB); PG8_STAGE(PG8_SB(0, 1), b2 + hstepB, voffB); PG8_STAGE(PG8_SA(0, 0), a2, voffA);
;             PG8_WAIT_V(8); PG8_WAIT_L(0); PG8_BAR; PG8_MMA(1, 0, At, B0); PG8_MMA(1, 1, At, B1); PG8_BAR; PG8_SCHED;
	s_setprio 0
	v_mfma_f32_16x16x32_bf16 v[126:129], v[152:155], v[184:187], v[126:129]
	v_mfma_f32_16x16x32_bf16 v[122:125], v[160:163], v[184:187], v[122:125]
	v_mfma_f32_16x16x32_bf16 v[110:113], v[152:155], v[192:195], v[110:113]
	v_mfma_f32_16x16x32_bf16 v[106:109], v[160:163], v[192:195], v[106:109]
	v_mfma_f32_16x16x32_bf16 v[94:97], v[152:155], v[200:203], v[94:97]
	v_mfma_f32_16x16x32_bf16 v[90:93], v[160:163], v[200:203], v[90:93]
	v_mfma_f32_16x16x32_bf16 v[78:81], v[152:155], v[208:211], v[78:81]
	v_mfma_f32_16x16x32_bf16 v[74:77], v[160:163], v[208:211], v[74:77]
	v_mfma_f32_16x16x32_bf16 v[126:129], v[156:159], v[188:191], v[126:129]
	v_mfma_f32_16x16x32_bf16 v[122:125], v[164:167], v[188:191], v[122:125]
	v_mfma_f32_16x16x32_bf16 v[110:113], v[156:159], v[196:199], v[110:113]
	v_mfma_f32_16x16x32_bf16 v[106:109], v[164:167], v[196:199], v[106:109]
	v_mfma_f32_16x16x32_bf16 v[94:97], v[156:159], v[204:207], v[94:97]
	v_mfma_f32_16x16x32_bf16 v[90:93], v[164:167], v[204:207], v[90:93]
	v_mfma_f32_16x16x32_bf16 v[78:81], v[156:159], v[212:215], v[78:81]
	v_mfma_f32_16x16x32_bf16 v[74:77], v[164:167], v[212:215], v[74:77]
	s_setprio 2
	s_setprio 0
	v_mfma_f32_16x16x32_bf16 v[118:121], v[168:171], v[184:187], v[118:121]
	v_mfma_f32_16x16x32_bf16 v[114:117], v[176:179], v[184:187], v[114:117]
	v_mfma_f32_16x16x32_bf16 v[102:105], v[168:171], v[192:195], v[102:105]
	v_mfma_f32_16x16x32_bf16 v[98:101], v[176:179], v[192:195], v[98:101]
	v_mfma_f32_16x16x32_bf16 v[86:89], v[168:171], v[200:203], v[86:89]
	v_mfma_f32_16x16x32_bf16 v[82:85], v[176:179], v[200:203], v[82:85]
	v_mfma_f32_16x16x32_bf16 v[70:73], v[168:171], v[208:211], v[70:73]
	v_mfma_f32_16x16x32_bf16 v[66:69], v[176:179], v[208:211], v[66:69]
	v_mfma_f32_16x16x32_bf16 v[118:121], v[172:175], v[188:191], v[118:121]
	v_mfma_f32_16x16x32_bf16 v[114:117], v[180:183], v[188:191], v[114:117]
	v_mfma_f32_16x16x32_bf16 v[102:105], v[172:175], v[196:199], v[102:105]
	v_mfma_f32_16x16x32_bf16 v[98:101], v[180:183], v[196:199], v[98:101]
	v_mfma_f32_16x16x32_bf16 v[86:89], v[172:175], v[204:207], v[86:89]
	v_mfma_f32_16x16x32_bf16 v[82:85], v[180:183], v[204:207], v[82:85]
	v_mfma_f32_16x16x32_bf16 v[70:73], v[172:175], v[212:215], v[70:73]
	v_mfma_f32_16x16x32_bf16 v[66:69], v[180:183], v[212:215], v[66:69]
	s_setprio 2
	s_barrier
	s_add_i32 s33, s60, s46
	v_lshl_add_u64 v[216:217], s[38:39], 0, v[134:135]
	s_mov_b32 m0, s33
	ds_read_b128 v[184:187], v150 offset:16384
	ds_read_b128 v[188:191], v150 offset:17408
	ds_read_b128 v[192:195], v150 offset:18432
	ds_read_b128 v[196:199], v150 offset:19456
	ds_read_b128 v[200:203], v150 offset:20480
	ds_read_b128 v[204:207], v150 offset:21504
	ds_read_b128 v[208:211], v150 offset:22528
	ds_read_b128 v[212:215], v150 offset:23552
	global_load_lds_dwordx4 v[216:217], off
	s_add_i32 m0, s33, 0x2000
	s_add_u32 s62, s38, 0x40000
	v_lshl_add_u64 v[218:219], s[38:39], 0, v[130:131]
	s_addc_u32 s63, s39, 0
	s_add_i32 s33, s61, s46
	global_load_lds_dwordx4 v[218:219], off
	v_lshl_add_u64 v[220:221], s[62:63], 0, v[134:135]
	s_mov_b32 m0, s33
	v_lshl_add_u64 v[222:223], s[40:41], 0, v[132:133]
	global_load_lds_dwordx4 v[220:221], off
	v_lshl_add_u64 v[220:221], s[62:63], 0, v[130:131]
	s_add_i32 m0, s33, 0x2000
	s_nop 0
	global_load_lds_dwordx4 v[220:221], off
	v_lshl_add_u64 v[220:221], s[40:41], 0, v[136:137]
	s_mov_b32 m0, s25
	s_nop 0
	global_load_lds_dwordx4 v[220:221], off
	s_mov_b32 m0, s37
	s_nop 0
	global_load_lds_dwordx4 v[222:223], off
	s_waitcnt vmcnt(8)
	s_waitcnt lgkmcnt(0)
	s_barrier
	s_setprio 0
	v_mfma_f32_16x16x32_bf16 v[62:65], v[152:155], v[184:187], v[62:65]
	v_mfma_f32_16x16x32_bf16 v[58:61], v[160:163], v[184:187], v[58:61]
	v_mfma_f32_16x16x32_bf16 v[46:49], v[152:155], v[192:195], v[46:49]
	v_mfma_f32_16x16x32_bf16 v[42:45], v[160:163], v[192:195], v[42:45]
	v_mfma_f32_16x16x32_bf16 v[30:33], v[152:155], v[200:203], v[30:33]
	v_mfma_f32_16x16x32_bf16 v[26:29], v[160:163], v[200:203], v[26:29]
	v_mfma_f32_16x16x32_bf16 v[14:17], v[152:155], v[208:211], v[14:17]
	v_mfma_f32_16x16x32_bf16 v[10:13], v[160:163], v[208:211], v[10:13]
	v_mfma_f32_16x16x32_bf16 v[62:65], v[156:159], v[188:191], v[62:65]
	v_mfma_f32_16x16x32_bf16 v[58:61], v[164:167], v[188:191], v[58:61]
	v_mfma_f32_16x16x32_bf16 v[46:49], v[156:159], v[196:199], v[46:49]
	v_mfma_f32_16x16x32_bf16 v[42:45], v[164:167], v[196:199], v[42:45]
	v_mfma_f32_16x16x32_bf16 v[30:33], v[156:159], v[204:207], v[30:33]
	v_mfma_f32_16x16x32_bf16 v[26:29], v[164:167], v[204:207], v[26:29]
	v_mfma_f32_16x16x32_bf16 v[14:17], v[156:159], v[212:215], v[14:17]
	v_mfma_f32_16x16x32_bf16 v[10:13], v[164:167], v[212:215], v[10:13]
	s_setprio 2
	s_setprio 0
	v_mfma_f32_16x16x32_bf16 v[54:57], v[168:171], v[184:187], v[54:57]
	v_mfma_f32_16x16x32_bf16 v[50:53], v[176:179], v[184:187], v[50:53]
	v_mfma_f32_16x16x32_bf16 v[38:41], v[168:171], v[192:195], v[38:41]
	v_mfma_f32_16x16x32_bf16 v[34:37], v[176:179], v[192:195], v[34:37]
	v_mfma_f32_16x16x32_bf16 v[22:25], v[168:171], v[200:203], v[22:25]
	v_mfma_f32_16x16x32_bf16 v[18:21], v[176:179], v[200:203], v[18:21]
	v_mfma_f32_16x16x32_bf16 v[6:9], v[168:171], v[208:211], v[6:9]
	v_mfma_f32_16x16x32_bf16 v[2:5], v[176:179], v[208:211], v[2:5]
	v_mfma_f32_16x16x32_bf16 v[54:57], v[172:175], v[188:191], v[54:57]
	v_mfma_f32_16x16x32_bf16 v[50:53], v[180:183], v[188:191], v[50:53]
	v_mfma_f32_16x16x32_bf16 v[38:41], v[172:175], v[196:199], v[38:41]
	v_mfma_f32_16x16x32_bf16 v[34:37], v[180:183], v[196:199], v[34:37]
	v_mfma_f32_16x16x32_bf16 v[22:25], v[172:175], v[204:207], v[22:25]
	v_mfma_f32_16x16x32_bf16 v[18:21], v[180:183], v[204:207], v[18:21]
	v_mfma_f32_16x16x32_bf16 v[6:9], v[172:175], v[212:215], v[6:9]
	v_mfma_f32_16x16x32_bf16 v[2:5], v[180:183], v[212:215], v[2:5]
	s_setprio 2
	s_barrier
; #define PG8_STAGE(bufoff, gbase, voff) do { _Pragma("unroll") for (int _i = 0; _i < 2; ++_i) \
;         __builtin_amdgcn_global_load_lds((const unsigned*)((const char*)(gbase) + (voff)[_i]), (LAS unsigned*)(lds + (bufoff) + ldsw + _i * 8192), 16, 0, 0); } while (0)
; #define PG8_LDA(dst, b, h) do { _Pragma("unroll") for (int m = 0; m < 4; ++m) _Pragma("unroll") for (int k = 0; k < 2; ++k) dst[m][k] = *(const LAS bf16x8*)(lds + PG8_SA(b, h) + aoff + m * 2048 + k * 1024); } while (0)
; #define PG8_LDB(dst, b, h) do { _Pragma("unroll") for (int n = 0; n < 2; ++n) _Pragma("unroll") for (int k = 0; k < 2; ++k) dst[n][k] = *(const LAS bf16x8*)(lds + PG8_SB(b, h) + boff + n * 2048 + k * 1024); } while (0)
; #define PG8_MMA(ai, bj, At, Bt) do { __builtin_amdgcn_s_setprio(1); _Pragma("unroll") for (int m = 0; m < 4; ++m) _Pragma("unroll") for (int n = 0; n < 2; ++n) _Pragma("unroll") for (int k = 0; k < 2; ++k) \
;         acc[ai][bj][m][n] = __builtin_amdgcn_mfma_f32_16x16x32_bf16(Bt[n][k], At[m][k], acc[ai][bj][m][n], 0, 0, 0); __builtin_amdgcn_s_setprio(0); } while (0)
; #define PG8_WAIT_V(n) asm volatile("s_waitcnt vmcnt(" #n ")" ::: "memory")
; #define PG8_WAIT_L(n) asm volatile("s_waitcnt lgkmcnt(" #n ")" ::: "memory")
; #define PG8_BAR __builtin_amdgcn_s_barrier()
; #define PG8_SCHED __builtin_amdgcn_sched_barrier(0)
; template <class Epi>
; __device__ __forceinline__ void gemm_phase(LAS unsigned char* lds, const Gemm g, int G, int c, const Epi& E) {
;     ...
;             PG8_LDB(B0, 1, 0); PG8_LDB(B1, 1, 1); PG8_SCHED; PG8_LDA(At, 1, 0); PG8_STAGE(PG8_SA(0, 1), a2 + hstepA, voffA);
;             PG8_WAIT_V(8); PG8_WAIT_L(0); PG8_BAR; PG8_MMA(0, 0, At, B0); PG8_MMA(0, 1, At, B1); PG8_BAR; PG8_SCHED;
	s_add_i32 s33, 0, 0x18000
	s_add_i32 s62, 0, 0x1c000
	v_add_u32_e32 v164, s33, v147
	v_add_u32_e32 v180, s62, v147
	ds_read_b128 v[152:155], v164
	ds_read_b128 v[156:159], v164 offset:1024
	ds_read_b128 v[160:163], v164 offset:2048
	ds_read_b128 v[164:167], v164 offset:3072
	ds_read_b128 v[168:171], v180
	ds_read_b128 v[172:175], v180 offset:1024
	ds_read_b128 v[176:179], v180 offset:2048
	ds_read_b128 v[180:183], v180 offset:3072
	s_add_u32 s40, s40, 0x40000
	s_addc_u32 s41, s41, 0
	s_mov_b32 m0, s47
	v_lshl_add_u64 v[224:225], s[40:41], 0, v[136:137]
	ds_read_b128 v[184:187], v150 offset:32768
	ds_read_b128 v[188:191], v150 offset:33792
	ds_read_b128 v[192:195], v150 offset:34816
	ds_read_b128 v[196:199], v150 offset:35840
	ds_read_b128 v[200:203], v150 offset:36864
	ds_read_b128 v[204:207], v150 offset:37888
	ds_read_b128 v[208:211], v150 offset:38912
	ds_read_b128 v[212:215], v150 offset:39936
	global_load_lds_dwordx4 v[224:225], off
	v_lshl_add_u64 v[224:225], s[40:41], 0, v[132:133]
	s_mov_b32 m0, s52
	s_nop 0
	global_load_lds_dwordx4 v[224:225], off
	s_waitcnt vmcnt(8)
	s_waitcnt lgkmcnt(0)
	s_barrier
	s_setprio 0
	v_mfma_f32_16x16x32_bf16 v[126:129], v[152:155], v[184:187], v[126:129]
	v_mfma_f32_16x16x32_bf16 v[122:125], v[160:163], v[184:187], v[122:125]
	v_mfma_f32_16x16x32_bf16 v[110:113], v[152:155], v[192:195], v[110:113]
	v_mfma_f32_16x16x32_bf16 v[106:109], v[160:163], v[192:195], v[106:109]
	v_mfma_f32_16x16x32_bf16 v[94:97], v[152:155], v[200:203], v[94:97]
	v_mfma_f32_16x16x32_bf16 v[90:93], v[160:163], v[200:203], v[90:93]
	v_mfma_f32_16x16x32_bf16 v[78:81], v[152:155], v[208:211], v[78:81]
	v_mfma_f32_16x16x32_bf16 v[74:77], v[160:163], v[208:211], v[74:77]
	v_mfma_f32_16x16x32_bf16 v[126:129], v[156:159], v[188:191], v[126:129]
	v_mfma_f32_16x16x32_bf16 v[122:125], v[164:167], v[188:191], v[122:125]
	v_mfma_f32_16x16x32_bf16 v[110:113], v[156:159], v[196:199], v[110:113]
	v_mfma_f32_16x16x32_bf16 v[106:109], v[164:167], v[196:199], v[106:109]
	v_mfma_f32_16x16x32_bf16 v[94:97], v[156:159], v[204:207], v[94:97]
	v_mfma_f32_16x16x32_bf16 v[90:93], v[164:167], v[204:207], v[90:93]
	v_mfma_f32_16x16x32_bf16 v[78:81], v[156:159], v[212:215], v[78:81]
	v_mfma_f32_16x16x32_bf16 v[74:77], v[164:167], v[212:215], v[74:77]
	s_setprio 2
	s_setprio 0
	v_mfma_f32_16x16x32_bf16 v[118:121], v[168:171], v[184:187], v[118:121]
	v_mfma_f32_16x16x32_bf16 v[114:117], v[176:179], v[184:187], v[114:117]
	v_mfma_f32_16x16x32_bf16 v[102:105], v[168:171], v[192:195], v[102:105]
	v_mfma_f32_16x16x32_bf16 v[98:101], v[176:179], v[192:195], v[98:101]
	v_mfma_f32_16x16x32_bf16 v[86:89], v[168:171], v[200:203], v[86:89]
	v_mfma_f32_16x16x32_bf16 v[82:85], v[176:179], v[200:203], v[82:85]
	v_mfma_f32_16x16x32_bf16 v[70:73], v[168:171], v[208:211], v[70:73]
	v_mfma_f32_16x16x32_bf16 v[66:69], v[176:179], v[208:211], v[66:69]
	v_mfma_f32_16x16x32_bf16 v[118:121], v[172:175], v[188:191], v[118:121]
	v_mfma_f32_16x16x32_bf16 v[114:117], v[180:183], v[188:191], v[114:117]
	v_mfma_f32_16x16x32_bf16 v[102:105], v[172:175], v[196:199], v[102:105]
	v_mfma_f32_16x16x32_bf16 v[98:101], v[180:183], v[196:199], v[98:101]
	v_mfma_f32_16x16x32_bf16 v[86:89], v[172:175], v[204:207], v[86:89]
	v_mfma_f32_16x16x32_bf16 v[82:85], v[180:183], v[204:207], v[82:85]
	v_mfma_f32_16x16x32_bf16 v[70:73], v[172:175], v[212:215], v[70:73]
	v_mfma_f32_16x16x32_bf16 v[66:69], v[180:183], v[212:215], v[66:69]
	s_setprio 2
	s_barrier
; #define PG8_STAGE(bufoff, gbase, voff) do { _Pragma("unroll") for (int _i = 0; _i < 2; ++_i) \
;         __builtin_amdgcn_global_load_lds((const unsigned*)((const char*)(gbase) + (voff)[_i]), (LAS unsigned*)(lds + (bufoff) + ldsw + _i * 8192), 16, 0, 0); } while (0)
; #define PG8_LDA(dst, b, h) do { _Pragma("unroll") for (int m = 0; m < 4; ++m) _Pragma("unroll") for (int k = 0; k < 2; ++k) dst[m][k] = *(const LAS bf16x8*)(lds + PG8_SA(b, h) + aoff + m * 2048 + k * 1024); } while (0)
; #define PG8_MMA(ai, bj, At, Bt) do { __builtin_amdgcn_s_setprio(1); _Pragma("unroll") for (int m = 0; m < 4; ++m) _Pragma("unroll") for (int n = 0; n < 2; ++n) _Pragma("unroll") for (int k = 0; k < 2; ++k) \
;         acc[ai][bj][m][n] = __builtin_amdgcn_mfma_f32_16x16x32_bf16(Bt[n][k], At[m][k], acc[ai][bj][m][n], 0, 0, 0); __builtin_amdgcn_s_setprio(0); } while (0)
; #define PG8_WAIT_V(n) asm volatile("s_waitcnt vmcnt(" #n ")" ::: "memory")
; #define PG8_WAIT_L(n) asm volatile("s_waitcnt lgkmcnt(" #n ")" ::: "memory")
; #define PG8_BAR __builtin_amdgcn_s_barrier()
; #define PG8_SCHED __builtin_amdgcn_sched_barrier(0)
; template <class Epi>
; __device__ __forceinline__ void gemm_phase(LAS unsigned char* lds, const Gemm g, int G, int c, const Epi& E) {
;     ...
;             PG8_LDA(At, 1, 1); PG8_STAGE(PG8_SB(1, 0), b3, voffB); PG8_STAGE(PG8_SB(1, 1), b3 + hstepB, voffB); PG8_STAGE(PG8_SA(1, 0), a3, voffA);
;             PG8_WAIT_V(8); PG8_WAIT_L(0); PG8_BAR; PG8_MMA(1, 0, At, B0); PG8_MMA(1, 1, At, B1); PG8_BAR; PG8_SCHED;
;         }
;         if (wr == 0) PG8_BAR;
	s_add_i32 s33, s33, s46
	v_lshl_add_u64 v[216:217], v[216:217], 0, s[12:13]
	s_mov_b32 m0, s33
	ds_read_b128 v[184:187], v150 offset:49152
	ds_read_b128 v[188:191], v150 offset:50176
	ds_read_b128 v[192:195], v150 offset:51200
	ds_read_b128 v[196:199], v150 offset:52224
	ds_read_b128 v[200:203], v150 offset:53248
	ds_read_b128 v[204:207], v150 offset:54272
	ds_read_b128 v[208:211], v150 offset:55296
	ds_read_b128 v[212:215], v150 offset:56320
	global_load_lds_dwordx4 v[216:217], off
	s_add_i32 m0, s33, 0x2000
	s_add_u32 s38, s38, 0x40080
	v_lshl_add_u64 v[216:217], v[218:219], 0, s[12:13]
	s_addc_u32 s39, s39, 0
	s_add_i32 s33, s62, s46
	global_load_lds_dwordx4 v[216:217], off
	v_lshl_add_u64 v[216:217], s[38:39], 0, v[134:135]
	s_mov_b32 m0, s33
	s_nop 0
	global_load_lds_dwordx4 v[216:217], off
	v_lshl_add_u64 v[216:217], s[38:39], 0, v[130:131]
	s_add_i32 m0, s33, 0x2000
	s_nop 0
	global_load_lds_dwordx4 v[216:217], off
	v_lshl_add_u64 v[216:217], v[220:221], 0, s[12:13]
	s_mov_b32 m0, s57
	s_nop 0
	global_load_lds_dwordx4 v[216:217], off
	v_lshl_add_u64 v[216:217], v[222:223], 0, s[12:13]
	s_mov_b32 m0, s58
	s_nop 0
	global_load_lds_dwordx4 v[216:217], off
	s_waitcnt vmcnt(8)
	s_waitcnt lgkmcnt(0)
	s_barrier
	s_setprio 0
	v_mfma_f32_16x16x32_bf16 v[62:65], v[152:155], v[184:187], v[62:65]
	v_mfma_f32_16x16x32_bf16 v[58:61], v[160:163], v[184:187], v[58:61]
	v_mfma_f32_16x16x32_bf16 v[46:49], v[152:155], v[192:195], v[46:49]
	v_mfma_f32_16x16x32_bf16 v[42:45], v[160:163], v[192:195], v[42:45]
	v_mfma_f32_16x16x32_bf16 v[30:33], v[152:155], v[200:203], v[30:33]
	v_mfma_f32_16x16x32_bf16 v[26:29], v[160:163], v[200:203], v[26:29]
	v_mfma_f32_16x16x32_bf16 v[14:17], v[152:155], v[208:211], v[14:17]
	v_mfma_f32_16x16x32_bf16 v[10:13], v[160:163], v[208:211], v[10:13]
	v_mfma_f32_16x16x32_bf16 v[62:65], v[156:159], v[188:191], v[62:65]
	v_mfma_f32_16x16x32_bf16 v[58:61], v[164:167], v[188:191], v[58:61]
	v_mfma_f32_16x16x32_bf16 v[46:49], v[156:159], v[196:199], v[46:49]
	v_mfma_f32_16x16x32_bf16 v[42:45], v[164:167], v[196:199], v[42:45]
	v_mfma_f32_16x16x32_bf16 v[30:33], v[156:159], v[204:207], v[30:33]
	v_mfma_f32_16x16x32_bf16 v[26:29], v[164:167], v[204:207], v[26:29]
	v_mfma_f32_16x16x32_bf16 v[14:17], v[156:159], v[212:215], v[14:17]
	v_mfma_f32_16x16x32_bf16 v[10:13], v[164:167], v[212:215], v[10:13]
	s_setprio 2
	s_setprio 0
	v_mfma_f32_16x16x32_bf16 v[54:57], v[168:171], v[184:187], v[54:57]
	v_mfma_f32_16x16x32_bf16 v[50:53], v[176:179], v[184:187], v[50:53]
	v_mfma_f32_16x16x32_bf16 v[38:41], v[168:171], v[192:195], v[38:41]
	v_mfma_f32_16x16x32_bf16 v[34:37], v[176:179], v[192:195], v[34:37]
	v_mfma_f32_16x16x32_bf16 v[22:25], v[168:171], v[200:203], v[22:25]
	v_mfma_f32_16x16x32_bf16 v[18:21], v[176:179], v[200:203], v[18:21]
	v_mfma_f32_16x16x32_bf16 v[6:9], v[168:171], v[208:211], v[6:9]
	v_mfma_f32_16x16x32_bf16 v[2:5], v[176:179], v[208:211], v[2:5]
	v_mfma_f32_16x16x32_bf16 v[54:57], v[172:175], v[188:191], v[54:57]
	v_mfma_f32_16x16x32_bf16 v[50:53], v[180:183], v[188:191], v[50:53]
	v_mfma_f32_16x16x32_bf16 v[38:41], v[172:175], v[196:199], v[38:41]
	v_mfma_f32_16x16x32_bf16 v[34:37], v[180:183], v[196:199], v[34:37]
	v_mfma_f32_16x16x32_bf16 v[22:25], v[172:175], v[204:207], v[22:25]
	v_mfma_f32_16x16x32_bf16 v[18:21], v[180:183], v[204:207], v[18:21]
	v_mfma_f32_16x16x32_bf16 v[6:9], v[172:175], v[212:215], v[6:9]
	v_mfma_f32_16x16x32_bf16 v[2:5], v[180:183], v[212:215], v[2:5]
	s_setprio 2
	s_barrier
	s_add_i32 s80, s80, 2
	s_add_u32 s4, s4, 0x100
	s_addc_u32 s5, s5, 0
	s_add_u32 s78, s78, 0x100
	s_addc_u32 s79, s79, 0
	s_cmp_gt_u32 s80, 13
	s_cbranch_scc0 .LBB0_1058
	s_and_b64 vcc, exec, s[14:15]
	s_cbranch_vccz .LBB0_1061
	s_barrier

; #define PG8_STAGE(bufoff, gbase, voff) do { _Pragma("unroll") for (int _i = 0; _i < 2; ++_i) \
;         __builtin_amdgcn_global_load_lds((const unsigned*)((const char*)(gbase) + (voff)[_i]), (LAS unsigned*)(lds + (bufoff) + ldsw + _i * 8192), 16, 0, 0); } while (0)
; #define PG8_LDA(dst, b, h) do { _Pragma("unroll") for (int m = 0; m < 4; ++m) _Pragma("unroll") for (int k = 0; k < 2; ++k) dst[m][k] = *(const LAS bf16x8*)(lds + PG8_SA(b, h) + aoff + m * 2048 + k * 1024); } while (0)
; #define PG8_LDB(dst, b, h) do { _Pragma("unroll") for (int n = 0; n < 2; ++n) _Pragma("unroll") for (int k = 0; k < 2; ++k) dst[n][k] = *(const LAS bf16x8*)(lds + PG8_SB(b, h) + boff + n * 2048 + k * 1024); } while (0)
; #define PG8_MMA(ai, bj, At, Bt) do { __builtin_amdgcn_s_setprio(1); _Pragma("unroll") for (int m = 0; m < 4; ++m) _Pragma("unroll") for (int n = 0; n < 2; ++n) _Pragma("unroll") for (int k = 0; k < 2; ++k) \
;         acc[ai][bj][m][n] = __builtin_amdgcn_mfma_f32_16x16x32_bf16(Bt[n][k], At[m][k], acc[ai][bj][m][n], 0, 0, 0); __builtin_amdgcn_s_setprio(0); } while (0)
; #define PG8_WAIT_V(n) asm volatile("s_waitcnt vmcnt(" #n ")" ::: "memory")
; #define PG8_WAIT_L(n) asm volatile("s_waitcnt lgkmcnt(" #n ")" ::: "memory")
; template <class Epi>
; __device__ __forceinline__ void gemm_phase(LAS unsigned char* lds, const Gemm g, int G, int c, const Epi& E) {
;     ...
;         const char* nA = has_next ? (const char*)(g.A + (size_t)nxt.pb * g.sA) + (size_t)nxt.pm * 2 * hstepA : cA;
;         const char* nB = has_next ? (const char*)(g.Bt + (size_t)nxt.pb * g.sB) + (size_t)nxt.pn * 2 * hstepB : cB;
; #pragma nounroll
;         for (int t = 0; t < nt; t += 2) {
;             const bool last = (t == nt - 2);
;             const char* a1 = cA + (size_t)(t + 1) * kstep;
;             const char* a2 = last ? nA : cA + (size_t)(t + 2) * kstep; const char* b2 = last ? nB : cB + (size_t)(t + 2) * kstep;
;             const char* a3 = a2 + kstep; const char* b3 = b2 + kstep;
;             PG8_LDB(B0, 0, 0); PG8_LDB(B1, 0, 1); PG8_SCHED; PG8_LDA(At, 0, 0); PG8_STAGE(PG8_SA(1, 1), a1 + hstepA, voffA);
;             PG8_WAIT_V(8); PG8_WAIT_L(0); PG8_BAR; PG8_MMA(0, 0, At, B0); PG8_MMA(0, 1, At, B1); PG8_BAR; PG8_SCHED;
;             PG8_LDA(At, 0, 1); PG8_STAGE(PG8_SB(0, 0), b2, voffB); PG8_STAGE(PG8_SB(0, 1), b2 + hstepB, voffB); PG8_STAGE(PG8_SA(0, 0), a2, voffA);
.LBB0_1142:
	s_add_u32 s66, s18, 0x100
	s_addc_u32 s67, s19, 0
	s_mov_b32 s68, -2
	s_waitcnt vmcnt(0)
	ds_read_b128 v[122:125], v168
	ds_read_b128 v[126:129], v168 offset:1024
	ds_read_b128 v[130:133], v168 offset:2048
	ds_read_b128 v[134:137], v168 offset:3072
	ds_read_b128 v[162:165], v169
	ds_read_b128 v[172:175], v169 offset:1024
	ds_read_b128 v[176:179], v169 offset:2048
	ds_read_b128 v[180:183], v169 offset:3072
	s_add_u32 s18, s16, 0x100
	s_addc_u32 s19, s17, 0
	s_cmp_eq_u32 s68, 40
	s_cselect_b32 s23, s5, s19
	s_cselect_b32 s22, s4, s18
	s_cselect_b32 s21, s15, s67
	s_cselect_b32 s20, s14, s66
	v_lshl_add_u64 v[216:217], s[16:17], 0, v[154:155]
	s_add_i32 m0, s38, 0xc000
	ds_read_b128 v[184:187], v170
	ds_read_b128 v[188:191], v170 offset:1024
	ds_read_b128 v[192:195], v170 offset:2048
	ds_read_b128 v[196:199], v170 offset:3072
	ds_read_b128 v[200:203], v170 offset:4096
	ds_read_b128 v[204:207], v170 offset:5120
	ds_read_b128 v[208:211], v170 offset:6144
	ds_read_b128 v[212:215], v170 offset:7168
	global_load_lds_dwordx4 v[216:217], off
	v_lshl_add_u64 v[216:217], s[16:17], 0, v[156:157]
	s_add_i32 m0, s38, 0xe000
	s_nop 0
	global_load_lds_dwordx4 v[216:217], off
	s_waitcnt vmcnt(8)
	s_waitcnt lgkmcnt(0)
	s_barrier
	s_setprio 0
	v_mfma_f32_16x16x32_bf16 v[142:145], v[122:125], v[184:187], 0
	v_mfma_f32_16x16x32_bf16 v[138:141], v[130:133], v[184:187], 0
	v_mfma_f32_16x16x32_bf16 v[118:121], v[122:125], v[192:195], 0
	v_mfma_f32_16x16x32_bf16 v[106:109], v[130:133], v[192:195], 0
	v_mfma_f32_16x16x32_bf16 v[102:105], v[122:125], v[200:203], 0
	v_mfma_f32_16x16x32_bf16 v[90:93], v[130:133], v[200:203], 0
	v_mfma_f32_16x16x32_bf16 v[86:89], v[122:125], v[208:211], 0
	v_mfma_f32_16x16x32_bf16 v[74:77], v[130:133], v[208:211], 0
	v_mfma_f32_16x16x32_bf16 v[142:145], v[126:129], v[188:191], v[142:145]
	v_mfma_f32_16x16x32_bf16 v[138:141], v[134:137], v[188:191], v[138:141]
	v_mfma_f32_16x16x32_bf16 v[118:121], v[126:129], v[196:199], v[118:121]
	v_mfma_f32_16x16x32_bf16 v[106:109], v[134:137], v[196:199], v[106:109]
	v_mfma_f32_16x16x32_bf16 v[102:105], v[126:129], v[204:207], v[102:105]
	v_mfma_f32_16x16x32_bf16 v[90:93], v[134:137], v[204:207], v[90:93]
	v_mfma_f32_16x16x32_bf16 v[86:89], v[126:129], v[212:215], v[86:89]
	v_mfma_f32_16x16x32_bf16 v[74:77], v[134:137], v[212:215], v[74:77]
	s_setprio 2
	s_setprio 0
	v_mfma_f32_16x16x32_bf16 v[114:117], v[162:165], v[184:187], 0
	v_mfma_f32_16x16x32_bf16 v[110:113], v[176:179], v[184:187], 0
	v_mfma_f32_16x16x32_bf16 v[98:101], v[162:165], v[192:195], 0
	v_mfma_f32_16x16x32_bf16 v[94:97], v[176:179], v[192:195], 0
	v_mfma_f32_16x16x32_bf16 v[82:85], v[162:165], v[200:203], 0
	v_mfma_f32_16x16x32_bf16 v[78:81], v[176:179], v[200:203], 0
	v_mfma_f32_16x16x32_bf16 v[70:73], v[162:165], v[208:211], 0
	v_mfma_f32_16x16x32_bf16 v[66:69], v[176:179], v[208:211], 0
	v_mfma_f32_16x16x32_bf16 v[114:117], v[172:175], v[188:191], v[114:117]
	v_mfma_f32_16x16x32_bf16 v[110:113], v[180:183], v[188:191], v[110:113]
	v_mfma_f32_16x16x32_bf16 v[98:101], v[172:175], v[196:199], v[98:101]
	v_mfma_f32_16x16x32_bf16 v[94:97], v[180:183], v[196:199], v[94:97]
	v_mfma_f32_16x16x32_bf16 v[82:85], v[172:175], v[204:207], v[82:85]
	v_mfma_f32_16x16x32_bf16 v[78:81], v[180:183], v[204:207], v[78:81]
	v_mfma_f32_16x16x32_bf16 v[70:73], v[172:175], v[212:215], v[70:73]
	v_mfma_f32_16x16x32_bf16 v[66:69], v[180:183], v[212:215], v[66:69]
	s_setprio 2
	s_barrier
	s_add_i32 s16, s54, s36
	v_lshl_add_u64 v[216:217], s[20:21], 0, v[150:151]
	s_mov_b32 m0, s16
	ds_read_b128 v[184:187], v170 offset:16384
	ds_read_b128 v[188:191], v170 offset:17408
	ds_read_b128 v[192:195], v170 offset:18432
	ds_read_b128 v[196:199], v170 offset:19456
	ds_read_b128 v[200:203], v170 offset:20480
	ds_read_b128 v[204:207], v170 offset:21504
	ds_read_b128 v[208:211], v170 offset:22528
	ds_read_b128 v[212:215], v170 offset:23552
	global_load_lds_dwordx4 v[216:217], off
	s_add_i32 m0, s16, 0x2000
	s_add_u32 s16, s20, 0xb0000
	v_lshl_add_u64 v[218:219], s[20:21], 0, v[146:147]
	s_addc_u32 s17, s21, 0
	s_add_i32 s33, s55, s36
	global_load_lds_dwordx4 v[218:219], off
	v_lshl_add_u64 v[220:221], s[16:17], 0, v[150:151]
	s_mov_b32 m0, s33
	v_lshl_add_u64 v[222:223], s[22:23], 0, v[148:149]
	global_load_lds_dwordx4 v[220:221], off
	v_lshl_add_u64 v[220:221], s[16:17], 0, v[146:147]
	s_add_i32 m0, s33, 0x2000
	s_nop 0
	global_load_lds_dwordx4 v[220:221], off
	v_lshl_add_u64 v[220:221], s[22:23], 0, v[152:153]
	s_mov_b32 m0, s38
	s_nop 0
	global_load_lds_dwordx4 v[220:221], off
	s_mov_b32 m0, s39
	s_nop 0
	global_load_lds_dwordx4 v[222:223], off
	s_waitcnt vmcnt(8)
	s_waitcnt lgkmcnt(0)
	s_barrier
; #define PG8_STAGE(bufoff, gbase, voff) do { _Pragma("unroll") for (int _i = 0; _i < 2; ++_i) \
;         __builtin_amdgcn_global_load_lds((const unsigned*)((const char*)(gbase) + (voff)[_i]), (LAS unsigned*)(lds + (bufoff) + ldsw + _i * 8192), 16, 0, 0); } while (0)
; #define PG8_LDA(dst, b, h) do { _Pragma("unroll") for (int m = 0; m < 4; ++m) _Pragma("unroll") for (int k = 0; k < 2; ++k) dst[m][k] = *(const LAS bf16x8*)(lds + PG8_SA(b, h) + aoff + m * 2048 + k * 1024); } while (0)
; #define PG8_LDB(dst, b, h) do { _Pragma("unroll") for (int n = 0; n < 2; ++n) _Pragma("unroll") for (int k = 0; k < 2; ++k) dst[n][k] = *(const LAS bf16x8*)(lds + PG8_SB(b, h) + boff + n * 2048 + k * 1024); } while (0)
; #define PG8_MMA(ai, bj, At, Bt) do { __builtin_amdgcn_s_setprio(1); _Pragma("unroll") for (int m = 0; m < 4; ++m) _Pragma("unroll") for (int n = 0; n < 2; ++n) _Pragma("unroll") for (int k = 0; k < 2; ++k) \
;         acc[ai][bj][m][n] = __builtin_amdgcn_mfma_f32_16x16x32_bf16(Bt[n][k], At[m][k], acc[ai][bj][m][n], 0, 0, 0); __builtin_amdgcn_s_setprio(0); } while (0)
; #define PG8_WAIT_V(n) asm volatile("s_waitcnt vmcnt(" #n ")" ::: "memory")
; #define PG8_WAIT_L(n) asm volatile("s_waitcnt lgkmcnt(" #n ")" ::: "memory")
; #define PG8_BAR __builtin_amdgcn_s_barrier()
; #define PG8_SCHED __builtin_amdgcn_sched_barrier(0)
; template <class Epi>
; __device__ __forceinline__ void gemm_phase(LAS unsigned char* lds, const Gemm g, int G, int c, const Epi& E) {
;     ...
;             PG8_WAIT_V(8); PG8_WAIT_L(0); PG8_BAR; PG8_MMA(1, 0, At, B0); PG8_MMA(1, 1, At, B1); PG8_BAR; PG8_SCHED;
;             PG8_LDB(B0, 1, 0); PG8_LDB(B1, 1, 1); PG8_SCHED; PG8_LDA(At, 1, 0); PG8_STAGE(PG8_SA(0, 1), a2 + hstepA, voffA);
;             PG8_WAIT_V(8); PG8_WAIT_L(0); PG8_BAR; PG8_MMA(0, 0, At, B0); PG8_MMA(0, 1, At, B1); PG8_BAR; PG8_SCHED;
	s_setprio 0
	v_mfma_f32_16x16x32_bf16 v[62:65], v[122:125], v[184:187], 0
	v_mfma_f32_16x16x32_bf16 v[58:61], v[130:133], v[184:187], 0
	v_mfma_f32_16x16x32_bf16 v[54:57], v[122:125], v[192:195], 0
	v_mfma_f32_16x16x32_bf16 v[42:45], v[130:133], v[192:195], 0
	v_mfma_f32_16x16x32_bf16 v[38:41], v[122:125], v[200:203], 0
	v_mfma_f32_16x16x32_bf16 v[26:29], v[130:133], v[200:203], 0
	v_mfma_f32_16x16x32_bf16 v[22:25], v[122:125], v[208:211], 0
	v_mfma_f32_16x16x32_bf16 v[10:13], v[130:133], v[208:211], 0
	v_mfma_f32_16x16x32_bf16 v[62:65], v[126:129], v[188:191], v[62:65]
	v_mfma_f32_16x16x32_bf16 v[58:61], v[134:137], v[188:191], v[58:61]
	v_mfma_f32_16x16x32_bf16 v[54:57], v[126:129], v[196:199], v[54:57]
	v_mfma_f32_16x16x32_bf16 v[42:45], v[134:137], v[196:199], v[42:45]
	v_mfma_f32_16x16x32_bf16 v[38:41], v[126:129], v[204:207], v[38:41]
	v_mfma_f32_16x16x32_bf16 v[26:29], v[134:137], v[204:207], v[26:29]
	v_mfma_f32_16x16x32_bf16 v[22:25], v[126:129], v[212:215], v[22:25]
	v_mfma_f32_16x16x32_bf16 v[10:13], v[134:137], v[212:215], v[10:13]
	s_setprio 2
	s_setprio 0
	v_mfma_f32_16x16x32_bf16 v[50:53], v[162:165], v[184:187], 0
	v_mfma_f32_16x16x32_bf16 v[46:49], v[176:179], v[184:187], 0
	v_mfma_f32_16x16x32_bf16 v[34:37], v[162:165], v[192:195], 0
	v_mfma_f32_16x16x32_bf16 v[30:33], v[176:179], v[192:195], 0
	v_mfma_f32_16x16x32_bf16 v[18:21], v[162:165], v[200:203], 0
	v_mfma_f32_16x16x32_bf16 v[14:17], v[176:179], v[200:203], 0
	v_mfma_f32_16x16x32_bf16 v[6:9], v[162:165], v[208:211], 0
	v_mfma_f32_16x16x32_bf16 v[2:5], v[176:179], v[208:211], 0
	v_mfma_f32_16x16x32_bf16 v[50:53], v[172:175], v[188:191], v[50:53]
	v_mfma_f32_16x16x32_bf16 v[46:49], v[180:183], v[188:191], v[46:49]
	v_mfma_f32_16x16x32_bf16 v[34:37], v[172:175], v[196:199], v[34:37]
	v_mfma_f32_16x16x32_bf16 v[30:33], v[180:183], v[196:199], v[30:33]
	v_mfma_f32_16x16x32_bf16 v[18:21], v[172:175], v[204:207], v[18:21]
	v_mfma_f32_16x16x32_bf16 v[14:17], v[180:183], v[204:207], v[14:17]
	v_mfma_f32_16x16x32_bf16 v[6:9], v[172:175], v[212:215], v[6:9]
	v_mfma_f32_16x16x32_bf16 v[2:5], v[180:183], v[212:215], v[2:5]
	s_setprio 2
	s_barrier
	s_add_i32 s33, 0, 0x18000
	s_add_i32 s62, 0, 0x1c000
	v_add_u32_e32 v134, s33, v167
	v_add_u32_e32 v171, s62, v167
	ds_read_b128 v[122:125], v134
	ds_read_b128 v[126:129], v134 offset:1024
	ds_read_b128 v[130:133], v134 offset:2048
	ds_read_b128 v[134:137], v134 offset:3072
	ds_read_b128 v[162:165], v171
	ds_read_b128 v[172:175], v171 offset:1024
	ds_read_b128 v[176:179], v171 offset:2048
	ds_read_b128 v[180:183], v171 offset:3072
	s_add_u32 s16, s22, 0xb0000
	s_addc_u32 s17, s23, 0
	s_mov_b32 m0, s40
	v_lshl_add_u64 v[224:225], s[16:17], 0, v[152:153]
	ds_read_b128 v[184:187], v170 offset:32768
	ds_read_b128 v[188:191], v170 offset:33792
	ds_read_b128 v[192:195], v170 offset:34816
	ds_read_b128 v[196:199], v170 offset:35840
	ds_read_b128 v[200:203], v170 offset:36864
	ds_read_b128 v[204:207], v170 offset:37888
	ds_read_b128 v[208:211], v170 offset:38912
	ds_read_b128 v[212:215], v170 offset:39936
	global_load_lds_dwordx4 v[224:225], off
	v_lshl_add_u64 v[224:225], s[16:17], 0, v[148:149]
	s_mov_b32 m0, s41
	s_nop 0
	global_load_lds_dwordx4 v[224:225], off
	s_waitcnt vmcnt(8)
	s_waitcnt lgkmcnt(0)
	s_barrier
	s_setprio 0
	v_mfma_f32_16x16x32_bf16 v[142:145], v[122:125], v[184:187], v[142:145]
	v_mfma_f32_16x16x32_bf16 v[138:141], v[130:133], v[184:187], v[138:141]
	v_mfma_f32_16x16x32_bf16 v[118:121], v[122:125], v[192:195], v[118:121]
	v_mfma_f32_16x16x32_bf16 v[106:109], v[130:133], v[192:195], v[106:109]
	v_mfma_f32_16x16x32_bf16 v[102:105], v[122:125], v[200:203], v[102:105]
	v_mfma_f32_16x16x32_bf16 v[90:93], v[130:133], v[200:203], v[90:93]
	v_mfma_f32_16x16x32_bf16 v[86:89], v[122:125], v[208:211], v[86:89]
	v_mfma_f32_16x16x32_bf16 v[74:77], v[130:133], v[208:211], v[74:77]
	v_mfma_f32_16x16x32_bf16 v[142:145], v[126:129], v[188:191], v[142:145]
	v_mfma_f32_16x16x32_bf16 v[138:141], v[134:137], v[188:191], v[138:141]
	v_mfma_f32_16x16x32_bf16 v[118:121], v[126:129], v[196:199], v[118:121]
	v_mfma_f32_16x16x32_bf16 v[106:109], v[134:137], v[196:199], v[106:109]
	v_mfma_f32_16x16x32_bf16 v[102:105], v[126:129], v[204:207], v[102:105]
	v_mfma_f32_16x16x32_bf16 v[90:93], v[134:137], v[204:207], v[90:93]
	v_mfma_f32_16x16x32_bf16 v[86:89], v[126:129], v[212:215], v[86:89]
	v_mfma_f32_16x16x32_bf16 v[74:77], v[134:137], v[212:215], v[74:77]
	s_setprio 2
	s_setprio 0
	v_mfma_f32_16x16x32_bf16 v[114:117], v[162:165], v[184:187], v[114:117]
	v_mfma_f32_16x16x32_bf16 v[110:113], v[176:179], v[184:187], v[110:113]
	v_mfma_f32_16x16x32_bf16 v[98:101], v[162:165], v[192:195], v[98:101]
	v_mfma_f32_16x16x32_bf16 v[94:97], v[176:179], v[192:195], v[94:97]
	v_mfma_f32_16x16x32_bf16 v[82:85], v[162:165], v[200:203], v[82:85]
	v_mfma_f32_16x16x32_bf16 v[78:81], v[176:179], v[200:203], v[78:81]
	v_mfma_f32_16x16x32_bf16 v[70:73], v[162:165], v[208:211], v[70:73]
	v_mfma_f32_16x16x32_bf16 v[66:69], v[176:179], v[208:211], v[66:69]
	v_mfma_f32_16x16x32_bf16 v[114:117], v[172:175], v[188:191], v[114:117]
	v_mfma_f32_16x16x32_bf16 v[110:113], v[180:183], v[188:191], v[110:113]
	v_mfma_f32_16x16x32_bf16 v[98:101], v[172:175], v[196:199], v[98:101]
	v_mfma_f32_16x16x32_bf16 v[94:97], v[180:183], v[196:199], v[94:97]
	v_mfma_f32_16x16x32_bf16 v[82:85], v[172:175], v[204:207], v[82:85]
	v_mfma_f32_16x16x32_bf16 v[78:81], v[180:183], v[204:207], v[78:81]
	v_mfma_f32_16x16x32_bf16 v[70:73], v[172:175], v[212:215], v[70:73]
	v_mfma_f32_16x16x32_bf16 v[66:69], v[180:183], v[212:215], v[66:69]
	s_setprio 2
	s_barrier
; #define PG8_STAGE(bufoff, gbase, voff) do { _Pragma("unroll") for (int _i = 0; _i < 2; ++_i) \
;         __builtin_amdgcn_global_load_lds((const unsigned*)((const char*)(gbase) + (voff)[_i]), (LAS unsigned*)(lds + (bufoff) + ldsw + _i * 8192), 16, 0, 0); } while (0)
; #define PG8_LDA(dst, b, h) do { _Pragma("unroll") for (int m = 0; m < 4; ++m) _Pragma("unroll") for (int k = 0; k < 2; ++k) dst[m][k] = *(const LAS bf16x8*)(lds + PG8_SA(b, h) + aoff + m * 2048 + k * 1024); } while (0)
; #define PG8_LDB(dst, b, h) do { _Pragma("unroll") for (int n = 0; n < 2; ++n) _Pragma("unroll") for (int k = 0; k < 2; ++k) dst[n][k] = *(const LAS bf16x8*)(lds + PG8_SB(b, h) + boff + n * 2048 + k * 1024); } while (0)
; #define PG8_MMA(ai, bj, At, Bt) do { __builtin_amdgcn_s_setprio(1); _Pragma("unroll") for (int m = 0; m < 4; ++m) _Pragma("unroll") for (int n = 0; n < 2; ++n) _Pragma("unroll") for (int k = 0; k < 2; ++k) \
;         acc[ai][bj][m][n] = __builtin_amdgcn_mfma_f32_16x16x32_bf16(Bt[n][k], At[m][k], acc[ai][bj][m][n], 0, 0, 0); __builtin_amdgcn_s_setprio(0); } while (0)
; #define PG8_WAIT_V(n) asm volatile("s_waitcnt vmcnt(" #n ")" ::: "memory")
; #define PG8_BAR __builtin_amdgcn_s_barrier()
; template <class Epi>
; __device__ __forceinline__ void gemm_phase(LAS unsigned char* lds, const Gemm g, int G, int c, const Epi& E) {
;     ...
;             PG8_LDB(B0, 0, 0); PG8_LDB(B1, 0, 1); PG8_SCHED; PG8_LDA(At, 0, 0); PG8_STAGE(PG8_SA(1, 1), a1 + hstepA, voffA);
;             PG8_WAIT_V(8); PG8_WAIT_L(0); PG8_BAR; PG8_MMA(0, 0, At, B0); PG8_MMA(0, 1, At, B1); PG8_BAR; PG8_SCHED;
;             PG8_LDA(At, 0, 1); PG8_STAGE(PG8_SB(0, 0), b2, voffB); PG8_STAGE(PG8_SB(0, 1), b2 + hstepB, voffB); PG8_STAGE(PG8_SA(0, 0), a2, voffA);
;             PG8_WAIT_V(8); PG8_WAIT_L(0); PG8_BAR; PG8_MMA(1, 0, At, B0); PG8_MMA(1, 1, At, B1); PG8_BAR; PG8_SCHED;
;             PG8_LDB(B0, 1, 0); PG8_LDB(B1, 1, 1); PG8_SCHED; PG8_LDA(At, 1, 0); PG8_STAGE(PG8_SA(0, 1), a2 + hstepA, voffA);
;             PG8_WAIT_V(8); PG8_WAIT_L(0); PG8_BAR; PG8_MMA(0, 0, At, B0); PG8_MMA(0, 1, At, B1); PG8_BAR; PG8_SCHED;
;             PG8_LDA(At, 1, 1); PG8_STAGE(PG8_SB(1, 0), b3, voffB); PG8_STAGE(PG8_SB(1, 1), b3 + hstepB, voffB); PG8_STAGE(PG8_SA(1, 0), a3, voffA);
;             PG8_WAIT_V(8); PG8_WAIT_L(0); PG8_BAR; PG8_MMA(1, 0, At, B0); PG8_MMA(1, 1, At, B1); PG8_BAR; PG8_SCHED;
	s_add_i32 s16, s33, s36
	v_lshl_add_u64 v[216:217], v[216:217], 0, s[10:11]
	s_mov_b32 m0, s16
	ds_read_b128 v[184:187], v170 offset:49152
	ds_read_b128 v[188:191], v170 offset:50176
	ds_read_b128 v[192:195], v170 offset:51200
	ds_read_b128 v[196:199], v170 offset:52224
	ds_read_b128 v[200:203], v170 offset:53248
	ds_read_b128 v[204:207], v170 offset:54272
	ds_read_b128 v[208:211], v170 offset:55296
	ds_read_b128 v[212:215], v170 offset:56320
	global_load_lds_dwordx4 v[216:217], off
	s_add_i32 m0, s16, 0x2000
	s_add_u32 s16, s20, 0xb0080
	v_lshl_add_u64 v[216:217], v[218:219], 0, s[10:11]
	s_addc_u32 s17, s21, 0
	s_add_i32 s20, s62, s36
	global_load_lds_dwordx4 v[216:217], off
	v_lshl_add_u64 v[216:217], s[16:17], 0, v[150:151]
	s_mov_b32 m0, s20
	s_nop 0
	global_load_lds_dwordx4 v[216:217], off
	v_lshl_add_u64 v[216:217], s[16:17], 0, v[146:147]
	s_add_i32 m0, s20, 0x2000
	s_nop 0
	global_load_lds_dwordx4 v[216:217], off
	v_lshl_add_u64 v[216:217], v[220:221], 0, s[10:11]
	s_mov_b32 m0, s47
	s_nop 0
	global_load_lds_dwordx4 v[216:217], off
	v_lshl_add_u64 v[216:217], v[222:223], 0, s[10:11]
	s_mov_b32 m0, s52
	s_nop 0
	global_load_lds_dwordx4 v[216:217], off
	s_waitcnt vmcnt(8)
	s_waitcnt lgkmcnt(0)
	s_barrier
	s_setprio 0
	v_mfma_f32_16x16x32_bf16 v[62:65], v[122:125], v[184:187], v[62:65]
	v_mfma_f32_16x16x32_bf16 v[58:61], v[130:133], v[184:187], v[58:61]
	v_mfma_f32_16x16x32_bf16 v[54:57], v[122:125], v[192:195], v[54:57]
	v_mfma_f32_16x16x32_bf16 v[42:45], v[130:133], v[192:195], v[42:45]
	v_mfma_f32_16x16x32_bf16 v[38:41], v[122:125], v[200:203], v[38:41]
	v_mfma_f32_16x16x32_bf16 v[26:29], v[130:133], v[200:203], v[26:29]
	v_mfma_f32_16x16x32_bf16 v[22:25], v[122:125], v[208:211], v[22:25]
	v_mfma_f32_16x16x32_bf16 v[10:13], v[130:133], v[208:211], v[10:13]
	v_mfma_f32_16x16x32_bf16 v[62:65], v[126:129], v[188:191], v[62:65]
	v_mfma_f32_16x16x32_bf16 v[58:61], v[134:137], v[188:191], v[58:61]
	v_mfma_f32_16x16x32_bf16 v[54:57], v[126:129], v[196:199], v[54:57]
	v_mfma_f32_16x16x32_bf16 v[42:45], v[134:137], v[196:199], v[42:45]
	v_mfma_f32_16x16x32_bf16 v[38:41], v[126:129], v[204:207], v[38:41]
	v_mfma_f32_16x16x32_bf16 v[26:29], v[134:137], v[204:207], v[26:29]
	v_mfma_f32_16x16x32_bf16 v[22:25], v[126:129], v[212:215], v[22:25]
	v_mfma_f32_16x16x32_bf16 v[10:13], v[134:137], v[212:215], v[10:13]
	s_setprio 2
	s_setprio 0
	v_mfma_f32_16x16x32_bf16 v[50:53], v[162:165], v[184:187], v[50:53]
	v_mfma_f32_16x16x32_bf16 v[46:49], v[176:179], v[184:187], v[46:49]
	v_mfma_f32_16x16x32_bf16 v[34:37], v[162:165], v[192:195], v[34:37]
	v_mfma_f32_16x16x32_bf16 v[30:33], v[176:179], v[192:195], v[30:33]
	v_mfma_f32_16x16x32_bf16 v[18:21], v[162:165], v[200:203], v[18:21]
	v_mfma_f32_16x16x32_bf16 v[14:17], v[176:179], v[200:203], v[14:17]
	v_mfma_f32_16x16x32_bf16 v[6:9], v[162:165], v[208:211], v[6:9]
	v_mfma_f32_16x16x32_bf16 v[2:5], v[176:179], v[208:211], v[2:5]
	v_mfma_f32_16x16x32_bf16 v[50:53], v[172:175], v[188:191], v[50:53]
	v_mfma_f32_16x16x32_bf16 v[46:49], v[180:183], v[188:191], v[46:49]
	v_mfma_f32_16x16x32_bf16 v[34:37], v[172:175], v[196:199], v[34:37]
	v_mfma_f32_16x16x32_bf16 v[30:33], v[180:183], v[196:199], v[30:33]
	v_mfma_f32_16x16x32_bf16 v[18:21], v[172:175], v[204:207], v[18:21]
	v_mfma_f32_16x16x32_bf16 v[14:17], v[180:183], v[204:207], v[14:17]
	v_mfma_f32_16x16x32_bf16 v[6:9], v[172:175], v[212:215], v[6:9]
	v_mfma_f32_16x16x32_bf16 v[2:5], v[180:183], v[212:215], v[2:5]
	s_setprio 2
	s_barrier
	s_add_i32 s68, s68, 2
	s_add_u32 s66, s66, 0x100
	s_addc_u32 s67, s67, 0
	s_cmp_gt_u32 s68, 41
	s_mov_b64 s[16:17], s[18:19]
	s_cbranch_scc0 .LBB0_1143
.LBB0_1143:
	ds_read_b128 v[122:125], v168
	ds_read_b128 v[126:129], v168 offset:1024
	ds_read_b128 v[130:133], v168 offset:2048
	ds_read_b128 v[134:137], v168 offset:3072
	ds_read_b128 v[162:165], v169
	ds_read_b128 v[172:175], v169 offset:1024
	ds_read_b128 v[176:179], v169 offset:2048
	ds_read_b128 v[180:183], v169 offset:3072
	s_add_u32 s18, s16, 0x100
	s_addc_u32 s19, s17, 0
	s_cmp_eq_u32 s68, 40
	s_cselect_b32 s23, s5, s19
	s_cselect_b32 s22, s4, s18
	s_cselect_b32 s21, s15, s67
	s_cselect_b32 s20, s14, s66
	v_lshl_add_u64 v[216:217], s[16:17], 0, v[154:155]
	s_add_i32 m0, s38, 0xc000
	ds_read_b128 v[184:187], v170
	ds_read_b128 v[188:191], v170 offset:1024
	ds_read_b128 v[192:195], v170 offset:2048
	ds_read_b128 v[196:199], v170 offset:3072
	ds_read_b128 v[200:203], v170 offset:4096
	ds_read_b128 v[204:207], v170 offset:5120
	ds_read_b128 v[208:211], v170 offset:6144
	ds_read_b128 v[212:215], v170 offset:7168
	global_load_lds_dwordx4 v[216:217], off
	v_lshl_add_u64 v[216:217], s[16:17], 0, v[156:157]
	s_add_i32 m0, s38, 0xe000
	s_nop 0
	global_load_lds_dwordx4 v[216:217], off
	s_waitcnt vmcnt(8)
	s_waitcnt lgkmcnt(0)
	s_barrier
; #define PG8_STAGE(bufoff, gbase, voff) do { _Pragma("unroll") for (int _i = 0; _i < 2; ++_i) \
;         __builtin_amdgcn_global_load_lds((const unsigned*)((const char*)(gbase) + (voff)[_i]), (LAS unsigned*)(lds + (bufoff) + ldsw + _i * 8192), 16, 0, 0); } while (0)
; #define PG8_LDA(dst, b, h) do { _Pragma("unroll") for (int m = 0; m < 4; ++m) _Pragma("unroll") for (int k = 0; k < 2; ++k) dst[m][k] = *(const LAS bf16x8*)(lds + PG8_SA(b, h) + aoff + m * 2048 + k * 1024); } while (0)
; #define PG8_MMA(ai, bj, At, Bt) do { __builtin_amdgcn_s_setprio(1); _Pragma("unroll") for (int m = 0; m < 4; ++m) _Pragma("unroll") for (int n = 0; n < 2; ++n) _Pragma("unroll") for (int k = 0; k < 2; ++k) \
;         acc[ai][bj][m][n] = __builtin_amdgcn_mfma_f32_16x16x32_bf16(Bt[n][k], At[m][k], acc[ai][bj][m][n], 0, 0, 0); __builtin_amdgcn_s_setprio(0); } while (0)
; #define PG8_WAIT_V(n) asm volatile("s_waitcnt vmcnt(" #n ")" ::: "memory")
; #define PG8_WAIT_L(n) asm volatile("s_waitcnt lgkmcnt(" #n ")" ::: "memory")
; #define PG8_BAR __builtin_amdgcn_s_barrier()
; #define PG8_SCHED __builtin_amdgcn_sched_barrier(0)
; template <class Epi>
; __device__ __forceinline__ void gemm_phase(LAS unsigned char* lds, const Gemm g, int G, int c, const Epi& E) {
;     ...
;             PG8_WAIT_V(8); PG8_WAIT_L(0); PG8_BAR; PG8_MMA(0, 0, At, B0); PG8_MMA(0, 1, At, B1); PG8_BAR; PG8_SCHED;
;             PG8_LDA(At, 0, 1); PG8_STAGE(PG8_SB(0, 0), b2, voffB); PG8_STAGE(PG8_SB(0, 1), b2 + hstepB, voffB); PG8_STAGE(PG8_SA(0, 0), a2, voffA);
;             PG8_WAIT_V(8); PG8_WAIT_L(0); PG8_BAR; PG8_MMA(1, 0, At, B0); PG8_MMA(1, 1, At, B1); PG8_BAR; PG8_SCHED;
	s_setprio 0
	v_mfma_f32_16x16x32_bf16 v[142:145], v[122:125], v[184:187], v[142:145]
	v_mfma_f32_16x16x32_bf16 v[138:141], v[130:133], v[184:187], v[138:141]
	v_mfma_f32_16x16x32_bf16 v[118:121], v[122:125], v[192:195], v[118:121]
	v_mfma_f32_16x16x32_bf16 v[106:109], v[130:133], v[192:195], v[106:109]
	v_mfma_f32_16x16x32_bf16 v[102:105], v[122:125], v[200:203], v[102:105]
	v_mfma_f32_16x16x32_bf16 v[90:93], v[130:133], v[200:203], v[90:93]
	v_mfma_f32_16x16x32_bf16 v[86:89], v[122:125], v[208:211], v[86:89]
	v_mfma_f32_16x16x32_bf16 v[74:77], v[130:133], v[208:211], v[74:77]
	v_mfma_f32_16x16x32_bf16 v[142:145], v[126:129], v[188:191], v[142:145]
	v_mfma_f32_16x16x32_bf16 v[138:141], v[134:137], v[188:191], v[138:141]
	v_mfma_f32_16x16x32_bf16 v[118:121], v[126:129], v[196:199], v[118:121]
	v_mfma_f32_16x16x32_bf16 v[106:109], v[134:137], v[196:199], v[106:109]
	v_mfma_f32_16x16x32_bf16 v[102:105], v[126:129], v[204:207], v[102:105]
	v_mfma_f32_16x16x32_bf16 v[90:93], v[134:137], v[204:207], v[90:93]
	v_mfma_f32_16x16x32_bf16 v[86:89], v[126:129], v[212:215], v[86:89]
	v_mfma_f32_16x16x32_bf16 v[74:77], v[134:137], v[212:215], v[74:77]
	s_setprio 2
	s_setprio 0
	v_mfma_f32_16x16x32_bf16 v[114:117], v[162:165], v[184:187], v[114:117]
	v_mfma_f32_16x16x32_bf16 v[110:113], v[176:179], v[184:187], v[110:113]
	v_mfma_f32_16x16x32_bf16 v[98:101], v[162:165], v[192:195], v[98:101]
	v_mfma_f32_16x16x32_bf16 v[94:97], v[176:179], v[192:195], v[94:97]
	v_mfma_f32_16x16x32_bf16 v[82:85], v[162:165], v[200:203], v[82:85]
	v_mfma_f32_16x16x32_bf16 v[78:81], v[176:179], v[200:203], v[78:81]
	v_mfma_f32_16x16x32_bf16 v[70:73], v[162:165], v[208:211], v[70:73]
	v_mfma_f32_16x16x32_bf16 v[66:69], v[176:179], v[208:211], v[66:69]
	v_mfma_f32_16x16x32_bf16 v[114:117], v[172:175], v[188:191], v[114:117]
	v_mfma_f32_16x16x32_bf16 v[110:113], v[180:183], v[188:191], v[110:113]
	v_mfma_f32_16x16x32_bf16 v[98:101], v[172:175], v[196:199], v[98:101]
	v_mfma_f32_16x16x32_bf16 v[94:97], v[180:183], v[196:199], v[94:97]
	v_mfma_f32_16x16x32_bf16 v[82:85], v[172:175], v[204:207], v[82:85]
	v_mfma_f32_16x16x32_bf16 v[78:81], v[180:183], v[204:207], v[78:81]
	v_mfma_f32_16x16x32_bf16 v[70:73], v[172:175], v[212:215], v[70:73]
	v_mfma_f32_16x16x32_bf16 v[66:69], v[180:183], v[212:215], v[66:69]
	s_setprio 2
	s_barrier
	s_add_i32 s16, s54, s36
	v_lshl_add_u64 v[216:217], s[20:21], 0, v[150:151]
	s_mov_b32 m0, s16
	ds_read_b128 v[184:187], v170 offset:16384
	ds_read_b128 v[188:191], v170 offset:17408
	ds_read_b128 v[192:195], v170 offset:18432
	ds_read_b128 v[196:199], v170 offset:19456
	ds_read_b128 v[200:203], v170 offset:20480
	ds_read_b128 v[204:207], v170 offset:21504
	ds_read_b128 v[208:211], v170 offset:22528
	ds_read_b128 v[212:215], v170 offset:23552
	global_load_lds_dwordx4 v[216:217], off
	s_add_i32 m0, s16, 0x2000
	s_add_u32 s16, s20, 0xb0000
	v_lshl_add_u64 v[218:219], s[20:21], 0, v[146:147]
	s_addc_u32 s17, s21, 0
	s_add_i32 s33, s55, s36
	global_load_lds_dwordx4 v[218:219], off
	v_lshl_add_u64 v[220:221], s[16:17], 0, v[150:151]
	s_mov_b32 m0, s33
	v_lshl_add_u64 v[222:223], s[22:23], 0, v[148:149]
	global_load_lds_dwordx4 v[220:221], off
	v_lshl_add_u64 v[220:221], s[16:17], 0, v[146:147]
	s_add_i32 m0, s33, 0x2000
	s_nop 0
	global_load_lds_dwordx4 v[220:221], off
	v_lshl_add_u64 v[220:221], s[22:23], 0, v[152:153]
	s_mov_b32 m0, s38
	s_nop 0
	global_load_lds_dwordx4 v[220:221], off
	s_mov_b32 m0, s39
	s_nop 0
	global_load_lds_dwordx4 v[222:223], off
	s_waitcnt vmcnt(8)
	s_waitcnt lgkmcnt(0)
	s_barrier
	s_setprio 0
	v_mfma_f32_16x16x32_bf16 v[62:65], v[122:125], v[184:187], v[62:65]
	v_mfma_f32_16x16x32_bf16 v[58:61], v[130:133], v[184:187], v[58:61]
	v_mfma_f32_16x16x32_bf16 v[54:57], v[122:125], v[192:195], v[54:57]
	v_mfma_f32_16x16x32_bf16 v[42:45], v[130:133], v[192:195], v[42:45]
	v_mfma_f32_16x16x32_bf16 v[38:41], v[122:125], v[200:203], v[38:41]
	v_mfma_f32_16x16x32_bf16 v[26:29], v[130:133], v[200:203], v[26:29]
	v_mfma_f32_16x16x32_bf16 v[22:25], v[122:125], v[208:211], v[22:25]
	v_mfma_f32_16x16x32_bf16 v[10:13], v[130:133], v[208:211], v[10:13]
	v_mfma_f32_16x16x32_bf16 v[62:65], v[126:129], v[188:191], v[62:65]
	v_mfma_f32_16x16x32_bf16 v[58:61], v[134:137], v[188:191], v[58:61]
	v_mfma_f32_16x16x32_bf16 v[54:57], v[126:129], v[196:199], v[54:57]
	v_mfma_f32_16x16x32_bf16 v[42:45], v[134:137], v[196:199], v[42:45]
	v_mfma_f32_16x16x32_bf16 v[38:41], v[126:129], v[204:207], v[38:41]
	v_mfma_f32_16x16x32_bf16 v[26:29], v[134:137], v[204:207], v[26:29]
	v_mfma_f32_16x16x32_bf16 v[22:25], v[126:129], v[212:215], v[22:25]
	v_mfma_f32_16x16x32_bf16 v[10:13], v[134:137], v[212:215], v[10:13]
	s_setprio 2
	s_setprio 0
	v_mfma_f32_16x16x32_bf16 v[50:53], v[162:165], v[184:187], v[50:53]
	v_mfma_f32_16x16x32_bf16 v[46:49], v[176:179], v[184:187], v[46:49]
	v_mfma_f32_16x16x32_bf16 v[34:37], v[162:165], v[192:195], v[34:37]
	v_mfma_f32_16x16x32_bf16 v[30:33], v[176:179], v[192:195], v[30:33]
	v_mfma_f32_16x16x32_bf16 v[18:21], v[162:165], v[200:203], v[18:21]
	v_mfma_f32_16x16x32_bf16 v[14:17], v[176:179], v[200:203], v[14:17]
	v_mfma_f32_16x16x32_bf16 v[6:9], v[162:165], v[208:211], v[6:9]
	v_mfma_f32_16x16x32_bf16 v[2:5], v[176:179], v[208:211], v[2:5]
	v_mfma_f32_16x16x32_bf16 v[50:53], v[172:175], v[188:191], v[50:53]
	v_mfma_f32_16x16x32_bf16 v[46:49], v[180:183], v[188:191], v[46:49]
	v_mfma_f32_16x16x32_bf16 v[34:37], v[172:175], v[196:199], v[34:37]
	v_mfma_f32_16x16x32_bf16 v[30:33], v[180:183], v[196:199], v[30:33]
	v_mfma_f32_16x16x32_bf16 v[18:21], v[172:175], v[204:207], v[18:21]
	v_mfma_f32_16x16x32_bf16 v[14:17], v[180:183], v[204:207], v[14:17]
	v_mfma_f32_16x16x32_bf16 v[6:9], v[172:175], v[212:215], v[6:9]
	v_mfma_f32_16x16x32_bf16 v[2:5], v[180:183], v[212:215], v[2:5]
	s_setprio 2
	s_barrier
; #define PG8_STAGE(bufoff, gbase, voff) do { _Pragma("unroll") for (int _i = 0; _i < 2; ++_i) \
;         __builtin_amdgcn_global_load_lds((const unsigned*)((const char*)(gbase) + (voff)[_i]), (LAS unsigned*)(lds + (bufoff) + ldsw + _i * 8192), 16, 0, 0); } while (0)
; #define PG8_LDA(dst, b, h) do { _Pragma("unroll") for (int m = 0; m < 4; ++m) _Pragma("unroll") for (int k = 0; k < 2; ++k) dst[m][k] = *(const LAS bf16x8*)(lds + PG8_SA(b, h) + aoff + m * 2048 + k * 1024); } while (0)
; #define PG8_LDB(dst, b, h) do { _Pragma("unroll") for (int n = 0; n < 2; ++n) _Pragma("unroll") for (int k = 0; k < 2; ++k) dst[n][k] = *(const LAS bf16x8*)(lds + PG8_SB(b, h) + boff + n * 2048 + k * 1024); } while (0)
; #define PG8_MMA(ai, bj, At, Bt) do { __builtin_amdgcn_s_setprio(1); _Pragma("unroll") for (int m = 0; m < 4; ++m) _Pragma("unroll") for (int n = 0; n < 2; ++n) _Pragma("unroll") for (int k = 0; k < 2; ++k) \
;         acc[ai][bj][m][n] = __builtin_amdgcn_mfma_f32_16x16x32_bf16(Bt[n][k], At[m][k], acc[ai][bj][m][n], 0, 0, 0); __builtin_amdgcn_s_setprio(0); } while (0)
; #define PG8_WAIT_V(n) asm volatile("s_waitcnt vmcnt(" #n ")" ::: "memory")
; #define PG8_WAIT_L(n) asm volatile("s_waitcnt lgkmcnt(" #n ")" ::: "memory")
; #define PG8_BAR __builtin_amdgcn_s_barrier()
; #define PG8_SCHED __builtin_amdgcn_sched_barrier(0)
; template <class Epi>
; __device__ __forceinline__ void gemm_phase(LAS unsigned char* lds, const Gemm g, int G, int c, const Epi& E) {
;     ...
;             PG8_LDB(B0, 1, 0); PG8_LDB(B1, 1, 1); PG8_SCHED; PG8_LDA(At, 1, 0); PG8_STAGE(PG8_SA(0, 1), a2 + hstepA, voffA);
;             PG8_WAIT_V(8); PG8_WAIT_L(0); PG8_BAR; PG8_MMA(0, 0, At, B0); PG8_MMA(0, 1, At, B1); PG8_BAR; PG8_SCHED;
	s_add_i32 s33, 0, 0x18000
	s_add_i32 s62, 0, 0x1c000
	v_add_u32_e32 v134, s33, v167
	v_add_u32_e32 v171, s62, v167
	ds_read_b128 v[122:125], v134
	ds_read_b128 v[126:129], v134 offset:1024
	ds_read_b128 v[130:133], v134 offset:2048
	ds_read_b128 v[134:137], v134 offset:3072
	ds_read_b128 v[162:165], v171
	ds_read_b128 v[172:175], v171 offset:1024
	ds_read_b128 v[176:179], v171 offset:2048
	ds_read_b128 v[180:183], v171 offset:3072
	s_add_u32 s16, s22, 0xb0000
	s_addc_u32 s17, s23, 0
	s_mov_b32 m0, s40
	v_lshl_add_u64 v[224:225], s[16:17], 0, v[152:153]
	ds_read_b128 v[184:187], v170 offset:32768
	ds_read_b128 v[188:191], v170 offset:33792
	ds_read_b128 v[192:195], v170 offset:34816
	ds_read_b128 v[196:199], v170 offset:35840
	ds_read_b128 v[200:203], v170 offset:36864
	ds_read_b128 v[204:207], v170 offset:37888
	ds_read_b128 v[208:211], v170 offset:38912
	ds_read_b128 v[212:215], v170 offset:39936
	global_load_lds_dwordx4 v[224:225], off
	v_lshl_add_u64 v[224:225], s[16:17], 0, v[148:149]
	s_mov_b32 m0, s41
	s_nop 0
	global_load_lds_dwordx4 v[224:225], off
	s_waitcnt vmcnt(8)
	s_waitcnt lgkmcnt(0)
	s_barrier
	s_setprio 0
	v_mfma_f32_16x16x32_bf16 v[142:145], v[122:125], v[184:187], v[142:145]
	v_mfma_f32_16x16x32_bf16 v[138:141], v[130:133], v[184:187], v[138:141]
	v_mfma_f32_16x16x32_bf16 v[118:121], v[122:125], v[192:195], v[118:121]
	v_mfma_f32_16x16x32_bf16 v[106:109], v[130:133], v[192:195], v[106:109]
	v_mfma_f32_16x16x32_bf16 v[102:105], v[122:125], v[200:203], v[102:105]
	v_mfma_f32_16x16x32_bf16 v[90:93], v[130:133], v[200:203], v[90:93]
	v_mfma_f32_16x16x32_bf16 v[86:89], v[122:125], v[208:211], v[86:89]
	v_mfma_f32_16x16x32_bf16 v[74:77], v[130:133], v[208:211], v[74:77]
	v_mfma_f32_16x16x32_bf16 v[142:145], v[126:129], v[188:191], v[142:145]
	v_mfma_f32_16x16x32_bf16 v[138:141], v[134:137], v[188:191], v[138:141]
	v_mfma_f32_16x16x32_bf16 v[118:121], v[126:129], v[196:199], v[118:121]
	v_mfma_f32_16x16x32_bf16 v[106:109], v[134:137], v[196:199], v[106:109]
	v_mfma_f32_16x16x32_bf16 v[102:105], v[126:129], v[204:207], v[102:105]
	v_mfma_f32_16x16x32_bf16 v[90:93], v[134:137], v[204:207], v[90:93]
	v_mfma_f32_16x16x32_bf16 v[86:89], v[126:129], v[212:215], v[86:89]
	v_mfma_f32_16x16x32_bf16 v[74:77], v[134:137], v[212:215], v[74:77]
	s_setprio 2
	s_setprio 0
	v_mfma_f32_16x16x32_bf16 v[114:117], v[162:165], v[184:187], v[114:117]
	v_mfma_f32_16x16x32_bf16 v[110:113], v[176:179], v[184:187], v[110:113]
	v_mfma_f32_16x16x32_bf16 v[98:101], v[162:165], v[192:195], v[98:101]
	v_mfma_f32_16x16x32_bf16 v[94:97], v[176:179], v[192:195], v[94:97]
	v_mfma_f32_16x16x32_bf16 v[82:85], v[162:165], v[200:203], v[82:85]
	v_mfma_f32_16x16x32_bf16 v[78:81], v[176:179], v[200:203], v[78:81]
	v_mfma_f32_16x16x32_bf16 v[70:73], v[162:165], v[208:211], v[70:73]
	v_mfma_f32_16x16x32_bf16 v[66:69], v[176:179], v[208:211], v[66:69]
	v_mfma_f32_16x16x32_bf16 v[114:117], v[172:175], v[188:191], v[114:117]
	v_mfma_f32_16x16x32_bf16 v[110:113], v[180:183], v[188:191], v[110:113]
	v_mfma_f32_16x16x32_bf16 v[98:101], v[172:175], v[196:199], v[98:101]
	v_mfma_f32_16x16x32_bf16 v[94:97], v[180:183], v[196:199], v[94:97]
	v_mfma_f32_16x16x32_bf16 v[82:85], v[172:175], v[204:207], v[82:85]
	v_mfma_f32_16x16x32_bf16 v[78:81], v[180:183], v[204:207], v[78:81]
	v_mfma_f32_16x16x32_bf16 v[70:73], v[172:175], v[212:215], v[70:73]
	v_mfma_f32_16x16x32_bf16 v[66:69], v[180:183], v[212:215], v[66:69]
	s_setprio 2
	s_barrier
; #define PG8_STAGE(bufoff, gbase, voff) do { _Pragma("unroll") for (int _i = 0; _i < 2; ++_i) \
;         __builtin_amdgcn_global_load_lds((const unsigned*)((const char*)(gbase) + (voff)[_i]), (LAS unsigned*)(lds + (bufoff) + ldsw + _i * 8192), 16, 0, 0); } while (0)
; #define PG8_LDA(dst, b, h) do { _Pragma("unroll") for (int m = 0; m < 4; ++m) _Pragma("unroll") for (int k = 0; k < 2; ++k) dst[m][k] = *(const LAS bf16x8*)(lds + PG8_SA(b, h) + aoff + m * 2048 + k * 1024); } while (0)
; #define PG8_MMA(ai, bj, At, Bt) do { __builtin_amdgcn_s_setprio(1); _Pragma("unroll") for (int m = 0; m < 4; ++m) _Pragma("unroll") for (int n = 0; n < 2; ++n) _Pragma("unroll") for (int k = 0; k < 2; ++k) \
;         acc[ai][bj][m][n] = __builtin_amdgcn_mfma_f32_16x16x32_bf16(Bt[n][k], At[m][k], acc[ai][bj][m][n], 0, 0, 0); __builtin_amdgcn_s_setprio(0); } while (0)
; #define PG8_WAIT_V(n) asm volatile("s_waitcnt vmcnt(" #n ")" ::: "memory")
; #define PG8_WAIT_L(n) asm volatile("s_waitcnt lgkmcnt(" #n ")" ::: "memory")
; #define PG8_BAR __builtin_amdgcn_s_barrier()
; #define PG8_SCHED __builtin_amdgcn_sched_barrier(0)
; template <class Epi>
; __device__ __forceinline__ void gemm_phase(LAS unsigned char* lds, const Gemm g, int G, int c, const Epi& E) {
;     ...
;             PG8_LDA(At, 1, 1); PG8_STAGE(PG8_SB(1, 0), b3, voffB); PG8_STAGE(PG8_SB(1, 1), b3 + hstepB, voffB); PG8_STAGE(PG8_SA(1, 0), a3, voffA);
;             PG8_WAIT_V(8); PG8_WAIT_L(0); PG8_BAR; PG8_MMA(1, 0, At, B0); PG8_MMA(1, 1, At, B1); PG8_BAR; PG8_SCHED;
;         }
;         if (wr == 0) PG8_BAR;
	s_add_i32 s16, s33, s36
	v_lshl_add_u64 v[216:217], v[216:217], 0, s[10:11]
	s_mov_b32 m0, s16
	ds_read_b128 v[184:187], v170 offset:49152
	ds_read_b128 v[188:191], v170 offset:50176
	ds_read_b128 v[192:195], v170 offset:51200
	ds_read_b128 v[196:199], v170 offset:52224
	ds_read_b128 v[200:203], v170 offset:53248
	ds_read_b128 v[204:207], v170 offset:54272
	ds_read_b128 v[208:211], v170 offset:55296
	ds_read_b128 v[212:215], v170 offset:56320
	global_load_lds_dwordx4 v[216:217], off
	s_add_i32 m0, s16, 0x2000
	s_add_u32 s16, s20, 0xb0080
	v_lshl_add_u64 v[216:217], v[218:219], 0, s[10:11]
	s_addc_u32 s17, s21, 0
	s_add_i32 s20, s62, s36
	global_load_lds_dwordx4 v[216:217], off
	v_lshl_add_u64 v[216:217], s[16:17], 0, v[150:151]
	s_mov_b32 m0, s20
	s_nop 0
	global_load_lds_dwordx4 v[216:217], off
	v_lshl_add_u64 v[216:217], s[16:17], 0, v[146:147]
	s_add_i32 m0, s20, 0x2000
	s_nop 0
	global_load_lds_dwordx4 v[216:217], off
	v_lshl_add_u64 v[216:217], v[220:221], 0, s[10:11]
	s_mov_b32 m0, s47
	s_nop 0
	global_load_lds_dwordx4 v[216:217], off
	v_lshl_add_u64 v[216:217], v[222:223], 0, s[10:11]
	s_mov_b32 m0, s52
	s_nop 0
	global_load_lds_dwordx4 v[216:217], off
	s_waitcnt vmcnt(8)
	s_waitcnt lgkmcnt(0)
	s_barrier
	s_setprio 0
	v_mfma_f32_16x16x32_bf16 v[62:65], v[122:125], v[184:187], v[62:65]
	v_mfma_f32_16x16x32_bf16 v[58:61], v[130:133], v[184:187], v[58:61]
	v_mfma_f32_16x16x32_bf16 v[54:57], v[122:125], v[192:195], v[54:57]
	v_mfma_f32_16x16x32_bf16 v[42:45], v[130:133], v[192:195], v[42:45]
	v_mfma_f32_16x16x32_bf16 v[38:41], v[122:125], v[200:203], v[38:41]
	v_mfma_f32_16x16x32_bf16 v[26:29], v[130:133], v[200:203], v[26:29]
	v_mfma_f32_16x16x32_bf16 v[22:25], v[122:125], v[208:211], v[22:25]
	v_mfma_f32_16x16x32_bf16 v[10:13], v[130:133], v[208:211], v[10:13]
	v_mfma_f32_16x16x32_bf16 v[62:65], v[126:129], v[188:191], v[62:65]
	v_mfma_f32_16x16x32_bf16 v[58:61], v[134:137], v[188:191], v[58:61]
	v_mfma_f32_16x16x32_bf16 v[54:57], v[126:129], v[196:199], v[54:57]
	v_mfma_f32_16x16x32_bf16 v[42:45], v[134:137], v[196:199], v[42:45]
	v_mfma_f32_16x16x32_bf16 v[38:41], v[126:129], v[204:207], v[38:41]
	v_mfma_f32_16x16x32_bf16 v[26:29], v[134:137], v[204:207], v[26:29]
	v_mfma_f32_16x16x32_bf16 v[22:25], v[126:129], v[212:215], v[22:25]
	v_mfma_f32_16x16x32_bf16 v[10:13], v[134:137], v[212:215], v[10:13]
	s_setprio 2
	s_setprio 0
	v_mfma_f32_16x16x32_bf16 v[50:53], v[162:165], v[184:187], v[50:53]
	v_mfma_f32_16x16x32_bf16 v[46:49], v[176:179], v[184:187], v[46:49]
	v_mfma_f32_16x16x32_bf16 v[34:37], v[162:165], v[192:195], v[34:37]
	v_mfma_f32_16x16x32_bf16 v[30:33], v[176:179], v[192:195], v[30:33]
	v_mfma_f32_16x16x32_bf16 v[18:21], v[162:165], v[200:203], v[18:21]
	v_mfma_f32_16x16x32_bf16 v[14:17], v[176:179], v[200:203], v[14:17]
	v_mfma_f32_16x16x32_bf16 v[6:9], v[162:165], v[208:211], v[6:9]
	v_mfma_f32_16x16x32_bf16 v[2:5], v[176:179], v[208:211], v[2:5]
	v_mfma_f32_16x16x32_bf16 v[50:53], v[172:175], v[188:191], v[50:53]
	v_mfma_f32_16x16x32_bf16 v[46:49], v[180:183], v[188:191], v[46:49]
	v_mfma_f32_16x16x32_bf16 v[34:37], v[172:175], v[196:199], v[34:37]
	v_mfma_f32_16x16x32_bf16 v[30:33], v[180:183], v[196:199], v[30:33]
	v_mfma_f32_16x16x32_bf16 v[18:21], v[172:175], v[204:207], v[18:21]
	v_mfma_f32_16x16x32_bf16 v[14:17], v[180:183], v[204:207], v[14:17]
	v_mfma_f32_16x16x32_bf16 v[6:9], v[172:175], v[212:215], v[6:9]
	v_mfma_f32_16x16x32_bf16 v[2:5], v[180:183], v[212:215], v[2:5]
	s_setprio 2
	s_barrier
	s_add_i32 s68, s68, 2
	s_add_u32 s66, s66, 0x100
	s_addc_u32 s67, s67, 0
	s_cmp_gt_u32 s68, 41
	s_mov_b64 s[16:17], s[18:19]
	s_cbranch_scc0 .LBB0_1143
	s_and_b64 vcc, exec, s[12:13]
	s_cbranch_vccz .LBB0_1146
	s_barrier

; #define PG8_STAGE(bufoff, gbase, voff) do { _Pragma("unroll") for (int _i = 0; _i < 2; ++_i) \
;         __builtin_amdgcn_global_load_lds((const unsigned*)((const char*)(gbase) + (voff)[_i]), (LAS unsigned*)(lds + (bufoff) + ldsw + _i * 8192), 16, 0, 0); } while (0)
; #define PG8_LDA(dst, b, h) do { _Pragma("unroll") for (int m = 0; m < 4; ++m) _Pragma("unroll") for (int k = 0; k < 2; ++k) dst[m][k] = *(const LAS bf16x8*)(lds + PG8_SA(b, h) + aoff + m * 2048 + k * 1024); } while (0)
; #define PG8_LDB(dst, b, h) do { _Pragma("unroll") for (int n = 0; n < 2; ++n) _Pragma("unroll") for (int k = 0; k < 2; ++k) dst[n][k] = *(const LAS bf16x8*)(lds + PG8_SB(b, h) + boff + n * 2048 + k * 1024); } while (0)
; #define PG8_MMA(ai, bj, At, Bt) do { __builtin_amdgcn_s_setprio(1); _Pragma("unroll") for (int m = 0; m < 4; ++m) _Pragma("unroll") for (int n = 0; n < 2; ++n) _Pragma("unroll") for (int k = 0; k < 2; ++k) \
;         acc[ai][bj][m][n] = __builtin_amdgcn_mfma_f32_16x16x32_bf16(Bt[n][k], At[m][k], acc[ai][bj][m][n], 0, 0, 0); __builtin_amdgcn_s_setprio(0); } while (0)
; #define PG8_WAIT_V(n) asm volatile("s_waitcnt vmcnt(" #n ")" ::: "memory")
; template <class Epi>
; __device__ __forceinline__ void gemm_phase(LAS unsigned char* lds, const Gemm g, int G, int c, const Epi& E) {
;     ...
;         const bool has_next = S.next(ui + 1, nxt);
;         const char* nA = has_next ? (const char*)(g.A + (size_t)nxt.pb * g.sA) + (size_t)nxt.pm * 2 * hstepA : cA;
;         const char* nB = has_next ? (const char*)(g.Bt + (size_t)nxt.pb * g.sB) + (size_t)nxt.pn * 2 * hstepB : cB;
; #pragma nounroll
;         for (int t = 0; t < nt; t += 2) {
;             const bool last = (t == nt - 2);
;             const char* a1 = cA + (size_t)(t + 1) * kstep;
;             const char* a2 = last ? nA : cA + (size_t)(t + 2) * kstep; const char* b2 = last ? nB : cB + (size_t)(t + 2) * kstep;
;             const char* a3 = a2 + kstep; const char* b3 = b2 + kstep;
;             PG8_LDB(B0, 0, 0); PG8_LDB(B1, 0, 1); PG8_SCHED; PG8_LDA(At, 0, 0); PG8_STAGE(PG8_SA(1, 1), a1 + hstepA, voffA);
;             PG8_WAIT_V(8); PG8_WAIT_L(0); PG8_BAR; PG8_MMA(0, 0, At, B0); PG8_MMA(0, 1, At, B1); PG8_BAR; PG8_SCHED;
;             PG8_LDA(At, 0, 1); PG8_STAGE(PG8_SB(0, 0), b2, voffB); PG8_STAGE(PG8_SB(0, 1), b2 + hstepB, voffB); PG8_STAGE(PG8_SA(0, 0), a2, voffA);
.LBB0_1296:
	s_ashr_i32 s39, s38, 31
	s_lshl_b64 s[44:45], s[38:39], 19
	s_add_u32 s44, s54, s44
	s_addc_u32 s45, s55, s45
	s_and_b64 s[4:5], s[4:5], exec
	s_cselect_b32 s7, s45, s47
	s_cselect_b32 s39, s44, s46
	s_add_u32 s4, s48, 0x40080
	s_addc_u32 s5, s49, 0
	s_add_u32 s41, s46, 0x100
	s_addc_u32 s80, s47, 0
	s_mov_b32 s81, -2
	s_waitcnt lgkmcnt(0)
	ds_read_b128 v[146:149], v152
	ds_read_b128 v[158:161], v152 offset:1024
	ds_read_b128 v[162:165], v152 offset:2048
	ds_read_b128 v[166:169], v152 offset:3072
	ds_read_b128 v[170:173], v153
	ds_read_b128 v[174:177], v153 offset:1024
	ds_read_b128 v[178:181], v153 offset:2048
	ds_read_b128 v[182:185], v153 offset:3072
	s_add_u32 s33, s4, 0xfffc0080
	s_addc_u32 s46, s5, -1
	s_cmp_eq_u32 s81, 12
	s_cselect_b32 s49, s43, s46
	s_cselect_b32 s48, s42, s33
	s_cselect_b32 s47, s7, s80
	s_cselect_b32 s46, s39, s41
	v_lshl_add_u64 v[218:219], s[4:5], 0, v[138:139]
	s_add_i32 m0, s11, 0xc000
	ds_read_b128 v[186:189], v154
	ds_read_b128 v[190:193], v154 offset:1024
	ds_read_b128 v[194:197], v154 offset:2048
	ds_read_b128 v[198:201], v154 offset:3072
	ds_read_b128 v[202:205], v154 offset:4096
	ds_read_b128 v[206:209], v154 offset:5120
	ds_read_b128 v[210:213], v154 offset:6144
	ds_read_b128 v[214:217], v154 offset:7168
	global_load_lds_dwordx4 v[218:219], off
	v_lshl_add_u64 v[218:219], s[4:5], 0, v[140:141]
	s_add_i32 m0, s11, 0xe000
	s_nop 0
	global_load_lds_dwordx4 v[218:219], off
	s_waitcnt vmcnt(8)
	s_waitcnt lgkmcnt(0)
	s_barrier
	s_setprio 0
	v_mfma_f32_16x16x32_bf16 v[126:129], v[146:149], v[186:189], 0
	v_mfma_f32_16x16x32_bf16 v[122:125], v[162:165], v[186:189], 0
	v_mfma_f32_16x16x32_bf16 v[110:113], v[146:149], v[194:197], 0
	v_mfma_f32_16x16x32_bf16 v[106:109], v[162:165], v[194:197], 0
	v_mfma_f32_16x16x32_bf16 v[94:97], v[146:149], v[202:205], 0
	v_mfma_f32_16x16x32_bf16 v[90:93], v[162:165], v[202:205], 0
	v_mfma_f32_16x16x32_bf16 v[78:81], v[146:149], v[210:213], 0
	v_mfma_f32_16x16x32_bf16 v[74:77], v[162:165], v[210:213], 0
	v_mfma_f32_16x16x32_bf16 v[126:129], v[158:161], v[190:193], v[126:129]
	v_mfma_f32_16x16x32_bf16 v[122:125], v[166:169], v[190:193], v[122:125]
	v_mfma_f32_16x16x32_bf16 v[110:113], v[158:161], v[198:201], v[110:113]
	v_mfma_f32_16x16x32_bf16 v[106:109], v[166:169], v[198:201], v[106:109]
	v_mfma_f32_16x16x32_bf16 v[94:97], v[158:161], v[206:209], v[94:97]
	v_mfma_f32_16x16x32_bf16 v[90:93], v[166:169], v[206:209], v[90:93]
	v_mfma_f32_16x16x32_bf16 v[78:81], v[158:161], v[214:217], v[78:81]
	v_mfma_f32_16x16x32_bf16 v[74:77], v[166:169], v[214:217], v[74:77]
	s_setprio 2
	s_setprio 0
	v_mfma_f32_16x16x32_bf16 v[118:121], v[170:173], v[186:189], 0
	v_mfma_f32_16x16x32_bf16 v[114:117], v[178:181], v[186:189], 0
	v_mfma_f32_16x16x32_bf16 v[102:105], v[170:173], v[194:197], 0
	v_mfma_f32_16x16x32_bf16 v[98:101], v[178:181], v[194:197], 0
	v_mfma_f32_16x16x32_bf16 v[86:89], v[170:173], v[202:205], 0
	v_mfma_f32_16x16x32_bf16 v[82:85], v[178:181], v[202:205], 0
	v_mfma_f32_16x16x32_bf16 v[70:73], v[170:173], v[210:213], 0
	v_mfma_f32_16x16x32_bf16 v[66:69], v[178:181], v[210:213], 0
	v_mfma_f32_16x16x32_bf16 v[118:121], v[174:177], v[190:193], v[118:121]
	v_mfma_f32_16x16x32_bf16 v[114:117], v[182:185], v[190:193], v[114:117]
	v_mfma_f32_16x16x32_bf16 v[102:105], v[174:177], v[198:201], v[102:105]
	v_mfma_f32_16x16x32_bf16 v[98:101], v[182:185], v[198:201], v[98:101]
	v_mfma_f32_16x16x32_bf16 v[86:89], v[174:177], v[206:209], v[86:89]
	v_mfma_f32_16x16x32_bf16 v[82:85], v[182:185], v[206:209], v[82:85]
	v_mfma_f32_16x16x32_bf16 v[70:73], v[174:177], v[214:217], v[70:73]
	v_mfma_f32_16x16x32_bf16 v[66:69], v[182:185], v[214:217], v[66:69]
	s_setprio 2
	s_barrier
	s_add_i32 s33, s71, s56
	v_lshl_add_u64 v[218:219], s[46:47], 0, v[132:133]
	s_mov_b32 m0, s33
	ds_read_b128 v[186:189], v154 offset:16384
	ds_read_b128 v[190:193], v154 offset:17408
	ds_read_b128 v[194:197], v154 offset:18432
	ds_read_b128 v[198:201], v154 offset:19456
	ds_read_b128 v[202:205], v154 offset:20480
	ds_read_b128 v[206:209], v154 offset:21504
	ds_read_b128 v[210:213], v154 offset:22528
	ds_read_b128 v[214:217], v154 offset:23552
	global_load_lds_dwordx4 v[218:219], off
	s_add_i32 m0, s33, 0x2000
	s_add_u32 s62, s46, 0x40000
	v_lshl_add_u64 v[220:221], s[46:47], 0, v[136:137]
	s_addc_u32 s63, s47, 0
	s_add_i32 s33, s72, s56
	global_load_lds_dwordx4 v[220:221], off
	v_lshl_add_u64 v[222:223], s[62:63], 0, v[132:133]
	s_mov_b32 m0, s33
	v_lshl_add_u64 v[224:225], s[48:49], 0, v[134:135]
	global_load_lds_dwordx4 v[222:223], off
	v_lshl_add_u64 v[222:223], s[62:63], 0, v[136:137]
	s_add_i32 m0, s33, 0x2000
	s_nop 0
	global_load_lds_dwordx4 v[222:223], off
	v_lshl_add_u64 v[222:223], s[48:49], 0, v[130:131]
	s_mov_b32 m0, s11
	s_nop 0
	global_load_lds_dwordx4 v[222:223], off
	s_mov_b32 m0, s57
	s_nop 0
	global_load_lds_dwordx4 v[224:225], off
	s_waitcnt vmcnt(8)
	s_waitcnt lgkmcnt(0)
	s_barrier
; #define PG8_STAGE(bufoff, gbase, voff) do { _Pragma("unroll") for (int _i = 0; _i < 2; ++_i) \
;         __builtin_amdgcn_global_load_lds((const unsigned*)((const char*)(gbase) + (voff)[_i]), (LAS unsigned*)(lds + (bufoff) + ldsw + _i * 8192), 16, 0, 0); } while (0)
; #define PG8_LDA(dst, b, h) do { _Pragma("unroll") for (int m = 0; m < 4; ++m) _Pragma("unroll") for (int k = 0; k < 2; ++k) dst[m][k] = *(const LAS bf16x8*)(lds + PG8_SA(b, h) + aoff + m * 2048 + k * 1024); } while (0)
; #define PG8_LDB(dst, b, h) do { _Pragma("unroll") for (int n = 0; n < 2; ++n) _Pragma("unroll") for (int k = 0; k < 2; ++k) dst[n][k] = *(const LAS bf16x8*)(lds + PG8_SB(b, h) + boff + n * 2048 + k * 1024); } while (0)
; #define PG8_MMA(ai, bj, At, Bt) do { __builtin_amdgcn_s_setprio(1); _Pragma("unroll") for (int m = 0; m < 4; ++m) _Pragma("unroll") for (int n = 0; n < 2; ++n) _Pragma("unroll") for (int k = 0; k < 2; ++k) \
;         acc[ai][bj][m][n] = __builtin_amdgcn_mfma_f32_16x16x32_bf16(Bt[n][k], At[m][k], acc[ai][bj][m][n], 0, 0, 0); __builtin_amdgcn_s_setprio(0); } while (0)
; #define PG8_WAIT_V(n) asm volatile("s_waitcnt vmcnt(" #n ")" ::: "memory")
; #define PG8_WAIT_L(n) asm volatile("s_waitcnt lgkmcnt(" #n ")" ::: "memory")
; #define PG8_BAR __builtin_amdgcn_s_barrier()
; #define PG8_SCHED __builtin_amdgcn_sched_barrier(0)
; template <class Epi>
; __device__ __forceinline__ void gemm_phase(LAS unsigned char* lds, const Gemm g, int G, int c, const Epi& E) {
;     ...
;             PG8_WAIT_V(8); PG8_WAIT_L(0); PG8_BAR; PG8_MMA(1, 0, At, B0); PG8_MMA(1, 1, At, B1); PG8_BAR; PG8_SCHED;
;             PG8_LDB(B0, 1, 0); PG8_LDB(B1, 1, 1); PG8_SCHED; PG8_LDA(At, 1, 0); PG8_STAGE(PG8_SA(0, 1), a2 + hstepA, voffA);
;             PG8_WAIT_V(8); PG8_WAIT_L(0); PG8_BAR; PG8_MMA(0, 0, At, B0); PG8_MMA(0, 1, At, B1); PG8_BAR; PG8_SCHED;
	s_setprio 0
	v_mfma_f32_16x16x32_bf16 v[62:65], v[146:149], v[186:189], 0
	v_mfma_f32_16x16x32_bf16 v[58:61], v[162:165], v[186:189], 0
	v_mfma_f32_16x16x32_bf16 v[46:49], v[146:149], v[194:197], 0
	v_mfma_f32_16x16x32_bf16 v[42:45], v[162:165], v[194:197], 0
	v_mfma_f32_16x16x32_bf16 v[30:33], v[146:149], v[202:205], 0
	v_mfma_f32_16x16x32_bf16 v[26:29], v[162:165], v[202:205], 0
	v_mfma_f32_16x16x32_bf16 v[14:17], v[146:149], v[210:213], 0
	v_mfma_f32_16x16x32_bf16 v[10:13], v[162:165], v[210:213], 0
	v_mfma_f32_16x16x32_bf16 v[62:65], v[158:161], v[190:193], v[62:65]
	v_mfma_f32_16x16x32_bf16 v[58:61], v[166:169], v[190:193], v[58:61]
	v_mfma_f32_16x16x32_bf16 v[46:49], v[158:161], v[198:201], v[46:49]
	v_mfma_f32_16x16x32_bf16 v[42:45], v[166:169], v[198:201], v[42:45]
	v_mfma_f32_16x16x32_bf16 v[30:33], v[158:161], v[206:209], v[30:33]
	v_mfma_f32_16x16x32_bf16 v[26:29], v[166:169], v[206:209], v[26:29]
	v_mfma_f32_16x16x32_bf16 v[14:17], v[158:161], v[214:217], v[14:17]
	v_mfma_f32_16x16x32_bf16 v[10:13], v[166:169], v[214:217], v[10:13]
	s_setprio 2
	s_setprio 0
	v_mfma_f32_16x16x32_bf16 v[54:57], v[170:173], v[186:189], 0
	v_mfma_f32_16x16x32_bf16 v[50:53], v[178:181], v[186:189], 0
	v_mfma_f32_16x16x32_bf16 v[38:41], v[170:173], v[194:197], 0
	v_mfma_f32_16x16x32_bf16 v[34:37], v[178:181], v[194:197], 0
	v_mfma_f32_16x16x32_bf16 v[22:25], v[170:173], v[202:205], 0
	v_mfma_f32_16x16x32_bf16 v[18:21], v[178:181], v[202:205], 0
	v_mfma_f32_16x16x32_bf16 v[6:9], v[170:173], v[210:213], 0
	v_mfma_f32_16x16x32_bf16 v[2:5], v[178:181], v[210:213], 0
	v_mfma_f32_16x16x32_bf16 v[54:57], v[174:177], v[190:193], v[54:57]
	v_mfma_f32_16x16x32_bf16 v[50:53], v[182:185], v[190:193], v[50:53]
	v_mfma_f32_16x16x32_bf16 v[38:41], v[174:177], v[198:201], v[38:41]
	v_mfma_f32_16x16x32_bf16 v[34:37], v[182:185], v[198:201], v[34:37]
	v_mfma_f32_16x16x32_bf16 v[22:25], v[174:177], v[206:209], v[22:25]
	v_mfma_f32_16x16x32_bf16 v[18:21], v[182:185], v[206:209], v[18:21]
	v_mfma_f32_16x16x32_bf16 v[6:9], v[174:177], v[214:217], v[6:9]
	v_mfma_f32_16x16x32_bf16 v[2:5], v[182:185], v[214:217], v[2:5]
	s_setprio 2
	s_barrier
	s_add_i32 s33, 0, 0x18000
	v_add_u32_e32 v157, s33, v151
	s_add_i32 s62, 0, 0x1c000
	ds_read_b128 v[146:149], v157
	ds_read_b128 v[158:161], v157 offset:1024
	ds_read_b128 v[162:165], v157 offset:2048
	ds_read_b128 v[166:169], v157 offset:3072
	v_add_u32_e32 v157, s62, v151
	ds_read_b128 v[170:173], v157
	ds_read_b128 v[174:177], v157 offset:1024
	ds_read_b128 v[178:181], v157 offset:2048
	ds_read_b128 v[182:185], v157 offset:3072
	s_add_u32 s48, s48, 0x40000
	s_addc_u32 s49, s49, 0
	s_mov_b32 m0, s58
	v_lshl_add_u64 v[226:227], s[48:49], 0, v[130:131]
	ds_read_b128 v[186:189], v154 offset:32768
	ds_read_b128 v[190:193], v154 offset:33792
	ds_read_b128 v[194:197], v154 offset:34816
	ds_read_b128 v[198:201], v154 offset:35840
	ds_read_b128 v[202:205], v154 offset:36864
	ds_read_b128 v[206:209], v154 offset:37888
	ds_read_b128 v[210:213], v154 offset:38912
	ds_read_b128 v[214:217], v154 offset:39936
	global_load_lds_dwordx4 v[226:227], off
	v_lshl_add_u64 v[226:227], s[48:49], 0, v[134:135]
	s_mov_b32 m0, s59
	s_nop 0
	global_load_lds_dwordx4 v[226:227], off
	s_waitcnt vmcnt(8)
	s_waitcnt lgkmcnt(0)
	s_barrier
	s_setprio 0
	v_mfma_f32_16x16x32_bf16 v[126:129], v[146:149], v[186:189], v[126:129]
	v_mfma_f32_16x16x32_bf16 v[122:125], v[162:165], v[186:189], v[122:125]
	v_mfma_f32_16x16x32_bf16 v[110:113], v[146:149], v[194:197], v[110:113]
	v_mfma_f32_16x16x32_bf16 v[106:109], v[162:165], v[194:197], v[106:109]
	v_mfma_f32_16x16x32_bf16 v[94:97], v[146:149], v[202:205], v[94:97]
	v_mfma_f32_16x16x32_bf16 v[90:93], v[162:165], v[202:205], v[90:93]
	v_mfma_f32_16x16x32_bf16 v[78:81], v[146:149], v[210:213], v[78:81]
	v_mfma_f32_16x16x32_bf16 v[74:77], v[162:165], v[210:213], v[74:77]
	v_mfma_f32_16x16x32_bf16 v[126:129], v[158:161], v[190:193], v[126:129]
	v_mfma_f32_16x16x32_bf16 v[122:125], v[166:169], v[190:193], v[122:125]
	v_mfma_f32_16x16x32_bf16 v[110:113], v[158:161], v[198:201], v[110:113]
	v_mfma_f32_16x16x32_bf16 v[106:109], v[166:169], v[198:201], v[106:109]
	v_mfma_f32_16x16x32_bf16 v[94:97], v[158:161], v[206:209], v[94:97]
	v_mfma_f32_16x16x32_bf16 v[90:93], v[166:169], v[206:209], v[90:93]
	v_mfma_f32_16x16x32_bf16 v[78:81], v[158:161], v[214:217], v[78:81]
	v_mfma_f32_16x16x32_bf16 v[74:77], v[166:169], v[214:217], v[74:77]
	s_setprio 2
	s_setprio 0
	v_mfma_f32_16x16x32_bf16 v[118:121], v[170:173], v[186:189], v[118:121]
	v_mfma_f32_16x16x32_bf16 v[114:117], v[178:181], v[186:189], v[114:117]
	v_mfma_f32_16x16x32_bf16 v[102:105], v[170:173], v[194:197], v[102:105]
	v_mfma_f32_16x16x32_bf16 v[98:101], v[178:181], v[194:197], v[98:101]
	v_mfma_f32_16x16x32_bf16 v[86:89], v[170:173], v[202:205], v[86:89]
	v_mfma_f32_16x16x32_bf16 v[82:85], v[178:181], v[202:205], v[82:85]
	v_mfma_f32_16x16x32_bf16 v[70:73], v[170:173], v[210:213], v[70:73]
	v_mfma_f32_16x16x32_bf16 v[66:69], v[178:181], v[210:213], v[66:69]
	v_mfma_f32_16x16x32_bf16 v[118:121], v[174:177], v[190:193], v[118:121]
	v_mfma_f32_16x16x32_bf16 v[114:117], v[182:185], v[190:193], v[114:117]
	v_mfma_f32_16x16x32_bf16 v[102:105], v[174:177], v[198:201], v[102:105]
	v_mfma_f32_16x16x32_bf16 v[98:101], v[182:185], v[198:201], v[98:101]
	v_mfma_f32_16x16x32_bf16 v[86:89], v[174:177], v[206:209], v[86:89]
	v_mfma_f32_16x16x32_bf16 v[82:85], v[182:185], v[206:209], v[82:85]
	v_mfma_f32_16x16x32_bf16 v[70:73], v[174:177], v[214:217], v[70:73]
	v_mfma_f32_16x16x32_bf16 v[66:69], v[182:185], v[214:217], v[66:69]
	s_setprio 2
	s_barrier
; #define PG8_STAGE(bufoff, gbase, voff) do { _Pragma("unroll") for (int _i = 0; _i < 2; ++_i) \
;         __builtin_amdgcn_global_load_lds((const unsigned*)((const char*)(gbase) + (voff)[_i]), (LAS unsigned*)(lds + (bufoff) + ldsw + _i * 8192), 16, 0, 0); } while (0)
; #define PG8_LDA(dst, b, h) do { _Pragma("unroll") for (int m = 0; m < 4; ++m) _Pragma("unroll") for (int k = 0; k < 2; ++k) dst[m][k] = *(const LAS bf16x8*)(lds + PG8_SA(b, h) + aoff + m * 2048 + k * 1024); } while (0)
; #define PG8_LDB(dst, b, h) do { _Pragma("unroll") for (int n = 0; n < 2; ++n) _Pragma("unroll") for (int k = 0; k < 2; ++k) dst[n][k] = *(const LAS bf16x8*)(lds + PG8_SB(b, h) + boff + n * 2048 + k * 1024); } while (0)
; #define PG8_MMA(ai, bj, At, Bt) do { __builtin_amdgcn_s_setprio(1); _Pragma("unroll") for (int m = 0; m < 4; ++m) _Pragma("unroll") for (int n = 0; n < 2; ++n) _Pragma("unroll") for (int k = 0; k < 2; ++k) \
;         acc[ai][bj][m][n] = __builtin_amdgcn_mfma_f32_16x16x32_bf16(Bt[n][k], At[m][k], acc[ai][bj][m][n], 0, 0, 0); __builtin_amdgcn_s_setprio(0); } while (0)
; #define PG8_WAIT_V(n) asm volatile("s_waitcnt vmcnt(" #n ")" ::: "memory")
; #define PG8_BAR __builtin_amdgcn_s_barrier()
; template <class Epi>
; __device__ __forceinline__ void gemm_phase(LAS unsigned char* lds, const Gemm g, int G, int c, const Epi& E) {
;     ...
;             PG8_LDB(B0, 0, 0); PG8_LDB(B1, 0, 1); PG8_SCHED; PG8_LDA(At, 0, 0); PG8_STAGE(PG8_SA(1, 1), a1 + hstepA, voffA);
;             PG8_WAIT_V(8); PG8_WAIT_L(0); PG8_BAR; PG8_MMA(0, 0, At, B0); PG8_MMA(0, 1, At, B1); PG8_BAR; PG8_SCHED;
;             PG8_LDA(At, 0, 1); PG8_STAGE(PG8_SB(0, 0), b2, voffB); PG8_STAGE(PG8_SB(0, 1), b2 + hstepB, voffB); PG8_STAGE(PG8_SA(0, 0), a2, voffA);
;             PG8_WAIT_V(8); PG8_WAIT_L(0); PG8_BAR; PG8_MMA(1, 0, At, B0); PG8_MMA(1, 1, At, B1); PG8_BAR; PG8_SCHED;
;             PG8_LDB(B0, 1, 0); PG8_LDB(B1, 1, 1); PG8_SCHED; PG8_LDA(At, 1, 0); PG8_STAGE(PG8_SA(0, 1), a2 + hstepA, voffA);
;             PG8_WAIT_V(8); PG8_WAIT_L(0); PG8_BAR; PG8_MMA(0, 0, At, B0); PG8_MMA(0, 1, At, B1); PG8_BAR; PG8_SCHED;
;             PG8_LDA(At, 1, 1); PG8_STAGE(PG8_SB(1, 0), b3, voffB); PG8_STAGE(PG8_SB(1, 1), b3 + hstepB, voffB); PG8_STAGE(PG8_SA(1, 0), a3, voffA);
;             PG8_WAIT_V(8); PG8_WAIT_L(0); PG8_BAR; PG8_MMA(1, 0, At, B0); PG8_MMA(1, 1, At, B1); PG8_BAR; PG8_SCHED;
	s_add_i32 s33, s33, s56
	v_lshl_add_u64 v[218:219], v[218:219], 0, s[20:21]
	s_mov_b32 m0, s33
	ds_read_b128 v[186:189], v154 offset:49152
	ds_read_b128 v[190:193], v154 offset:50176
	ds_read_b128 v[194:197], v154 offset:51200
	ds_read_b128 v[198:201], v154 offset:52224
	ds_read_b128 v[202:205], v154 offset:53248
	ds_read_b128 v[206:209], v154 offset:54272
	ds_read_b128 v[210:213], v154 offset:55296
	ds_read_b128 v[214:217], v154 offset:56320
	global_load_lds_dwordx4 v[218:219], off
	s_add_i32 m0, s33, 0x2000
	s_add_u32 s46, s46, 0x40080
	v_lshl_add_u64 v[218:219], v[220:221], 0, s[20:21]
	s_addc_u32 s47, s47, 0
	s_add_i32 s33, s62, s56
	global_load_lds_dwordx4 v[218:219], off
	v_lshl_add_u64 v[218:219], s[46:47], 0, v[132:133]
	s_mov_b32 m0, s33
	s_nop 0
	global_load_lds_dwordx4 v[218:219], off
	v_lshl_add_u64 v[218:219], s[46:47], 0, v[136:137]
	s_add_i32 m0, s33, 0x2000
	s_nop 0
	global_load_lds_dwordx4 v[218:219], off
	v_lshl_add_u64 v[218:219], v[222:223], 0, s[20:21]
	s_mov_b32 m0, s67
	s_nop 0
	global_load_lds_dwordx4 v[218:219], off
	v_lshl_add_u64 v[218:219], v[224:225], 0, s[20:21]
	s_mov_b32 m0, s68
	s_nop 0
	global_load_lds_dwordx4 v[218:219], off
	s_waitcnt vmcnt(8)
	s_waitcnt lgkmcnt(0)
	s_barrier
	s_setprio 0
	v_mfma_f32_16x16x32_bf16 v[62:65], v[146:149], v[186:189], v[62:65]
	v_mfma_f32_16x16x32_bf16 v[58:61], v[162:165], v[186:189], v[58:61]
	v_mfma_f32_16x16x32_bf16 v[46:49], v[146:149], v[194:197], v[46:49]
	v_mfma_f32_16x16x32_bf16 v[42:45], v[162:165], v[194:197], v[42:45]
	v_mfma_f32_16x16x32_bf16 v[30:33], v[146:149], v[202:205], v[30:33]
	v_mfma_f32_16x16x32_bf16 v[26:29], v[162:165], v[202:205], v[26:29]
	v_mfma_f32_16x16x32_bf16 v[14:17], v[146:149], v[210:213], v[14:17]
	v_mfma_f32_16x16x32_bf16 v[10:13], v[162:165], v[210:213], v[10:13]
	v_mfma_f32_16x16x32_bf16 v[62:65], v[158:161], v[190:193], v[62:65]
	v_mfma_f32_16x16x32_bf16 v[58:61], v[166:169], v[190:193], v[58:61]
	v_mfma_f32_16x16x32_bf16 v[46:49], v[158:161], v[198:201], v[46:49]
	v_mfma_f32_16x16x32_bf16 v[42:45], v[166:169], v[198:201], v[42:45]
	v_mfma_f32_16x16x32_bf16 v[30:33], v[158:161], v[206:209], v[30:33]
	v_mfma_f32_16x16x32_bf16 v[26:29], v[166:169], v[206:209], v[26:29]
	v_mfma_f32_16x16x32_bf16 v[14:17], v[158:161], v[214:217], v[14:17]
	v_mfma_f32_16x16x32_bf16 v[10:13], v[166:169], v[214:217], v[10:13]
	s_setprio 2
	s_setprio 0
	v_mfma_f32_16x16x32_bf16 v[54:57], v[170:173], v[186:189], v[54:57]
	v_mfma_f32_16x16x32_bf16 v[50:53], v[178:181], v[186:189], v[50:53]
	v_mfma_f32_16x16x32_bf16 v[38:41], v[170:173], v[194:197], v[38:41]
	v_mfma_f32_16x16x32_bf16 v[34:37], v[178:181], v[194:197], v[34:37]
	v_mfma_f32_16x16x32_bf16 v[22:25], v[170:173], v[202:205], v[22:25]
	v_mfma_f32_16x16x32_bf16 v[18:21], v[178:181], v[202:205], v[18:21]
	v_mfma_f32_16x16x32_bf16 v[6:9], v[170:173], v[210:213], v[6:9]
	v_mfma_f32_16x16x32_bf16 v[2:5], v[178:181], v[210:213], v[2:5]
	v_mfma_f32_16x16x32_bf16 v[54:57], v[174:177], v[190:193], v[54:57]
	v_mfma_f32_16x16x32_bf16 v[50:53], v[182:185], v[190:193], v[50:53]
	v_mfma_f32_16x16x32_bf16 v[38:41], v[174:177], v[198:201], v[38:41]
	v_mfma_f32_16x16x32_bf16 v[34:37], v[182:185], v[198:201], v[34:37]
	v_mfma_f32_16x16x32_bf16 v[22:25], v[174:177], v[206:209], v[22:25]
	v_mfma_f32_16x16x32_bf16 v[18:21], v[182:185], v[206:209], v[18:21]
	v_mfma_f32_16x16x32_bf16 v[6:9], v[174:177], v[214:217], v[6:9]
	v_mfma_f32_16x16x32_bf16 v[2:5], v[182:185], v[214:217], v[2:5]
	s_setprio 2
	s_barrier
	s_add_i32 s81, s81, 2
	s_add_u32 s4, s4, 0x100
	s_addc_u32 s5, s5, 0
	s_add_u32 s41, s41, 0x100
	s_addc_u32 s80, s80, 0
	s_cmp_gt_u32 s81, 13
	s_cbranch_scc0 .LBB0_1297
.LBB0_1297:
	ds_read_b128 v[146:149], v152
	ds_read_b128 v[158:161], v152 offset:1024
	ds_read_b128 v[162:165], v152 offset:2048
	ds_read_b128 v[166:169], v152 offset:3072
	ds_read_b128 v[170:173], v153
	ds_read_b128 v[174:177], v153 offset:1024
	ds_read_b128 v[178:181], v153 offset:2048
	ds_read_b128 v[182:185], v153 offset:3072
	s_add_u32 s33, s4, 0xfffc0080
	s_addc_u32 s46, s5, -1
	s_cmp_eq_u32 s81, 12
	s_cselect_b32 s49, s43, s46
	s_cselect_b32 s48, s42, s33
	s_cselect_b32 s47, s7, s80
	s_cselect_b32 s46, s39, s41
	v_lshl_add_u64 v[218:219], s[4:5], 0, v[138:139]
	s_add_i32 m0, s11, 0xc000
	ds_read_b128 v[186:189], v154
	ds_read_b128 v[190:193], v154 offset:1024
	ds_read_b128 v[194:197], v154 offset:2048
	ds_read_b128 v[198:201], v154 offset:3072
	ds_read_b128 v[202:205], v154 offset:4096
	ds_read_b128 v[206:209], v154 offset:5120
	ds_read_b128 v[210:213], v154 offset:6144
	ds_read_b128 v[214:217], v154 offset:7168
	global_load_lds_dwordx4 v[218:219], off
	v_lshl_add_u64 v[218:219], s[4:5], 0, v[140:141]
	s_add_i32 m0, s11, 0xe000
	s_nop 0
	global_load_lds_dwordx4 v[218:219], off
	s_waitcnt vmcnt(8)
	s_waitcnt lgkmcnt(0)
	s_barrier
; #define PG8_STAGE(bufoff, gbase, voff) do { _Pragma("unroll") for (int _i = 0; _i < 2; ++_i) \
;         __builtin_amdgcn_global_load_lds((const unsigned*)((const char*)(gbase) + (voff)[_i]), (LAS unsigned*)(lds + (bufoff) + ldsw + _i * 8192), 16, 0, 0); } while (0)
; #define PG8_LDA(dst, b, h) do { _Pragma("unroll") for (int m = 0; m < 4; ++m) _Pragma("unroll") for (int k = 0; k < 2; ++k) dst[m][k] = *(const LAS bf16x8*)(lds + PG8_SA(b, h) + aoff + m * 2048 + k * 1024); } while (0)
; #define PG8_MMA(ai, bj, At, Bt) do { __builtin_amdgcn_s_setprio(1); _Pragma("unroll") for (int m = 0; m < 4; ++m) _Pragma("unroll") for (int n = 0; n < 2; ++n) _Pragma("unroll") for (int k = 0; k < 2; ++k) \
;         acc[ai][bj][m][n] = __builtin_amdgcn_mfma_f32_16x16x32_bf16(Bt[n][k], At[m][k], acc[ai][bj][m][n], 0, 0, 0); __builtin_amdgcn_s_setprio(0); } while (0)
; #define PG8_WAIT_V(n) asm volatile("s_waitcnt vmcnt(" #n ")" ::: "memory")
; #define PG8_WAIT_L(n) asm volatile("s_waitcnt lgkmcnt(" #n ")" ::: "memory")
; #define PG8_BAR __builtin_amdgcn_s_barrier()
; #define PG8_SCHED __builtin_amdgcn_sched_barrier(0)
; template <class Epi>
; __device__ __forceinline__ void gemm_phase(LAS unsigned char* lds, const Gemm g, int G, int c, const Epi& E) {
;     ...
;             PG8_WAIT_V(8); PG8_WAIT_L(0); PG8_BAR; PG8_MMA(0, 0, At, B0); PG8_MMA(0, 1, At, B1); PG8_BAR; PG8_SCHED;
;             PG8_LDA(At, 0, 1); PG8_STAGE(PG8_SB(0, 0), b2, voffB); PG8_STAGE(PG8_SB(0, 1), b2 + hstepB, voffB); PG8_STAGE(PG8_SA(0, 0), a2, voffA);
;             PG8_WAIT_V(8); PG8_WAIT_L(0); PG8_BAR; PG8_MMA(1, 0, At, B0); PG8_MMA(1, 1, At, B1); PG8_BAR; PG8_SCHED;
	s_setprio 0
	v_mfma_f32_16x16x32_bf16 v[126:129], v[146:149], v[186:189], v[126:129]
	v_mfma_f32_16x16x32_bf16 v[122:125], v[162:165], v[186:189], v[122:125]
	v_mfma_f32_16x16x32_bf16 v[110:113], v[146:149], v[194:197], v[110:113]
	v_mfma_f32_16x16x32_bf16 v[106:109], v[162:165], v[194:197], v[106:109]
	v_mfma_f32_16x16x32_bf16 v[94:97], v[146:149], v[202:205], v[94:97]
	v_mfma_f32_16x16x32_bf16 v[90:93], v[162:165], v[202:205], v[90:93]
	v_mfma_f32_16x16x32_bf16 v[78:81], v[146:149], v[210:213], v[78:81]
	v_mfma_f32_16x16x32_bf16 v[74:77], v[162:165], v[210:213], v[74:77]
	v_mfma_f32_16x16x32_bf16 v[126:129], v[158:161], v[190:193], v[126:129]
	v_mfma_f32_16x16x32_bf16 v[122:125], v[166:169], v[190:193], v[122:125]
	v_mfma_f32_16x16x32_bf16 v[110:113], v[158:161], v[198:201], v[110:113]
	v_mfma_f32_16x16x32_bf16 v[106:109], v[166:169], v[198:201], v[106:109]
	v_mfma_f32_16x16x32_bf16 v[94:97], v[158:161], v[206:209], v[94:97]
	v_mfma_f32_16x16x32_bf16 v[90:93], v[166:169], v[206:209], v[90:93]
	v_mfma_f32_16x16x32_bf16 v[78:81], v[158:161], v[214:217], v[78:81]
	v_mfma_f32_16x16x32_bf16 v[74:77], v[166:169], v[214:217], v[74:77]
	s_setprio 2
	s_setprio 0
	v_mfma_f32_16x16x32_bf16 v[118:121], v[170:173], v[186:189], v[118:121]
	v_mfma_f32_16x16x32_bf16 v[114:117], v[178:181], v[186:189], v[114:117]
	v_mfma_f32_16x16x32_bf16 v[102:105], v[170:173], v[194:197], v[102:105]
	v_mfma_f32_16x16x32_bf16 v[98:101], v[178:181], v[194:197], v[98:101]
	v_mfma_f32_16x16x32_bf16 v[86:89], v[170:173], v[202:205], v[86:89]
	v_mfma_f32_16x16x32_bf16 v[82:85], v[178:181], v[202:205], v[82:85]
	v_mfma_f32_16x16x32_bf16 v[70:73], v[170:173], v[210:213], v[70:73]
	v_mfma_f32_16x16x32_bf16 v[66:69], v[178:181], v[210:213], v[66:69]
	v_mfma_f32_16x16x32_bf16 v[118:121], v[174:177], v[190:193], v[118:121]
	v_mfma_f32_16x16x32_bf16 v[114:117], v[182:185], v[190:193], v[114:117]
	v_mfma_f32_16x16x32_bf16 v[102:105], v[174:177], v[198:201], v[102:105]
	v_mfma_f32_16x16x32_bf16 v[98:101], v[182:185], v[198:201], v[98:101]
	v_mfma_f32_16x16x32_bf16 v[86:89], v[174:177], v[206:209], v[86:89]
	v_mfma_f32_16x16x32_bf16 v[82:85], v[182:185], v[206:209], v[82:85]
	v_mfma_f32_16x16x32_bf16 v[70:73], v[174:177], v[214:217], v[70:73]
	v_mfma_f32_16x16x32_bf16 v[66:69], v[182:185], v[214:217], v[66:69]
	s_setprio 2
	s_barrier
	s_add_i32 s33, s71, s56
	v_lshl_add_u64 v[218:219], s[46:47], 0, v[132:133]
	s_mov_b32 m0, s33
	ds_read_b128 v[186:189], v154 offset:16384
	ds_read_b128 v[190:193], v154 offset:17408
	ds_read_b128 v[194:197], v154 offset:18432
	ds_read_b128 v[198:201], v154 offset:19456
	ds_read_b128 v[202:205], v154 offset:20480
	ds_read_b128 v[206:209], v154 offset:21504
	ds_read_b128 v[210:213], v154 offset:22528
	ds_read_b128 v[214:217], v154 offset:23552
	global_load_lds_dwordx4 v[218:219], off
	s_add_i32 m0, s33, 0x2000
	s_add_u32 s62, s46, 0x40000
	v_lshl_add_u64 v[220:221], s[46:47], 0, v[136:137]
	s_addc_u32 s63, s47, 0
	s_add_i32 s33, s72, s56
	global_load_lds_dwordx4 v[220:221], off
	v_lshl_add_u64 v[222:223], s[62:63], 0, v[132:133]
	s_mov_b32 m0, s33
	v_lshl_add_u64 v[224:225], s[48:49], 0, v[134:135]
	global_load_lds_dwordx4 v[222:223], off
	v_lshl_add_u64 v[222:223], s[62:63], 0, v[136:137]
	s_add_i32 m0, s33, 0x2000
	s_nop 0
	global_load_lds_dwordx4 v[222:223], off
	v_lshl_add_u64 v[222:223], s[48:49], 0, v[130:131]
	s_mov_b32 m0, s11
	s_nop 0
	global_load_lds_dwordx4 v[222:223], off
	s_mov_b32 m0, s57
	s_nop 0
	global_load_lds_dwordx4 v[224:225], off
	s_waitcnt vmcnt(8)
	s_waitcnt lgkmcnt(0)
	s_barrier
	s_setprio 0
	v_mfma_f32_16x16x32_bf16 v[62:65], v[146:149], v[186:189], v[62:65]
	v_mfma_f32_16x16x32_bf16 v[58:61], v[162:165], v[186:189], v[58:61]
	v_mfma_f32_16x16x32_bf16 v[46:49], v[146:149], v[194:197], v[46:49]
	v_mfma_f32_16x16x32_bf16 v[42:45], v[162:165], v[194:197], v[42:45]
	v_mfma_f32_16x16x32_bf16 v[30:33], v[146:149], v[202:205], v[30:33]
	v_mfma_f32_16x16x32_bf16 v[26:29], v[162:165], v[202:205], v[26:29]
	v_mfma_f32_16x16x32_bf16 v[14:17], v[146:149], v[210:213], v[14:17]
	v_mfma_f32_16x16x32_bf16 v[10:13], v[162:165], v[210:213], v[10:13]
	v_mfma_f32_16x16x32_bf16 v[62:65], v[158:161], v[190:193], v[62:65]
	v_mfma_f32_16x16x32_bf16 v[58:61], v[166:169], v[190:193], v[58:61]
	v_mfma_f32_16x16x32_bf16 v[46:49], v[158:161], v[198:201], v[46:49]
	v_mfma_f32_16x16x32_bf16 v[42:45], v[166:169], v[198:201], v[42:45]
	v_mfma_f32_16x16x32_bf16 v[30:33], v[158:161], v[206:209], v[30:33]
	v_mfma_f32_16x16x32_bf16 v[26:29], v[166:169], v[206:209], v[26:29]
	v_mfma_f32_16x16x32_bf16 v[14:17], v[158:161], v[214:217], v[14:17]
	v_mfma_f32_16x16x32_bf16 v[10:13], v[166:169], v[214:217], v[10:13]
	s_setprio 2
	s_setprio 0
	v_mfma_f32_16x16x32_bf16 v[54:57], v[170:173], v[186:189], v[54:57]
	v_mfma_f32_16x16x32_bf16 v[50:53], v[178:181], v[186:189], v[50:53]
	v_mfma_f32_16x16x32_bf16 v[38:41], v[170:173], v[194:197], v[38:41]
	v_mfma_f32_16x16x32_bf16 v[34:37], v[178:181], v[194:197], v[34:37]
	v_mfma_f32_16x16x32_bf16 v[22:25], v[170:173], v[202:205], v[22:25]
	v_mfma_f32_16x16x32_bf16 v[18:21], v[178:181], v[202:205], v[18:21]
	v_mfma_f32_16x16x32_bf16 v[6:9], v[170:173], v[210:213], v[6:9]
	v_mfma_f32_16x16x32_bf16 v[2:5], v[178:181], v[210:213], v[2:5]
	v_mfma_f32_16x16x32_bf16 v[54:57], v[174:177], v[190:193], v[54:57]
	v_mfma_f32_16x16x32_bf16 v[50:53], v[182:185], v[190:193], v[50:53]
	v_mfma_f32_16x16x32_bf16 v[38:41], v[174:177], v[198:201], v[38:41]
	v_mfma_f32_16x16x32_bf16 v[34:37], v[182:185], v[198:201], v[34:37]
	v_mfma_f32_16x16x32_bf16 v[22:25], v[174:177], v[206:209], v[22:25]
	v_mfma_f32_16x16x32_bf16 v[18:21], v[182:185], v[206:209], v[18:21]
	v_mfma_f32_16x16x32_bf16 v[6:9], v[174:177], v[214:217], v[6:9]
	v_mfma_f32_16x16x32_bf16 v[2:5], v[182:185], v[214:217], v[2:5]
	s_setprio 2
	s_barrier
; #define PG8_STAGE(bufoff, gbase, voff) do { _Pragma("unroll") for (int _i = 0; _i < 2; ++_i) \
;         __builtin_amdgcn_global_load_lds((const unsigned*)((const char*)(gbase) + (voff)[_i]), (LAS unsigned*)(lds + (bufoff) + ldsw + _i * 8192), 16, 0, 0); } while (0)
; #define PG8_LDA(dst, b, h) do { _Pragma("unroll") for (int m = 0; m < 4; ++m) _Pragma("unroll") for (int k = 0; k < 2; ++k) dst[m][k] = *(const LAS bf16x8*)(lds + PG8_SA(b, h) + aoff + m * 2048 + k * 1024); } while (0)
; #define PG8_LDB(dst, b, h) do { _Pragma("unroll") for (int n = 0; n < 2; ++n) _Pragma("unroll") for (int k = 0; k < 2; ++k) dst[n][k] = *(const LAS bf16x8*)(lds + PG8_SB(b, h) + boff + n * 2048 + k * 1024); } while (0)
; #define PG8_MMA(ai, bj, At, Bt) do { __builtin_amdgcn_s_setprio(1); _Pragma("unroll") for (int m = 0; m < 4; ++m) _Pragma("unroll") for (int n = 0; n < 2; ++n) _Pragma("unroll") for (int k = 0; k < 2; ++k) \
;         acc[ai][bj][m][n] = __builtin_amdgcn_mfma_f32_16x16x32_bf16(Bt[n][k], At[m][k], acc[ai][bj][m][n], 0, 0, 0); __builtin_amdgcn_s_setprio(0); } while (0)
; #define PG8_WAIT_V(n) asm volatile("s_waitcnt vmcnt(" #n ")" ::: "memory")
; #define PG8_WAIT_L(n) asm volatile("s_waitcnt lgkmcnt(" #n ")" ::: "memory")
; #define PG8_BAR __builtin_amdgcn_s_barrier()
; #define PG8_SCHED __builtin_amdgcn_sched_barrier(0)
; template <class Epi>
; __device__ __forceinline__ void gemm_phase(LAS unsigned char* lds, const Gemm g, int G, int c, const Epi& E) {
;     ...
;             PG8_LDB(B0, 1, 0); PG8_LDB(B1, 1, 1); PG8_SCHED; PG8_LDA(At, 1, 0); PG8_STAGE(PG8_SA(0, 1), a2 + hstepA, voffA);
;             PG8_WAIT_V(8); PG8_WAIT_L(0); PG8_BAR; PG8_MMA(0, 0, At, B0); PG8_MMA(0, 1, At, B1); PG8_BAR; PG8_SCHED;
	s_add_i32 s33, 0, 0x18000
	v_add_u32_e32 v157, s33, v151
	s_add_i32 s62, 0, 0x1c000
	ds_read_b128 v[146:149], v157
	ds_read_b128 v[158:161], v157 offset:1024
	ds_read_b128 v[162:165], v157 offset:2048
	ds_read_b128 v[166:169], v157 offset:3072
	v_add_u32_e32 v157, s62, v151
	ds_read_b128 v[170:173], v157
	ds_read_b128 v[174:177], v157 offset:1024
	ds_read_b128 v[178:181], v157 offset:2048
	ds_read_b128 v[182:185], v157 offset:3072
	s_add_u32 s48, s48, 0x40000
	s_addc_u32 s49, s49, 0
	s_mov_b32 m0, s58
	v_lshl_add_u64 v[226:227], s[48:49], 0, v[130:131]
	ds_read_b128 v[186:189], v154 offset:32768
	ds_read_b128 v[190:193], v154 offset:33792
	ds_read_b128 v[194:197], v154 offset:34816
	ds_read_b128 v[198:201], v154 offset:35840
	ds_read_b128 v[202:205], v154 offset:36864
	ds_read_b128 v[206:209], v154 offset:37888
	ds_read_b128 v[210:213], v154 offset:38912
	ds_read_b128 v[214:217], v154 offset:39936
	global_load_lds_dwordx4 v[226:227], off
	v_lshl_add_u64 v[226:227], s[48:49], 0, v[134:135]
	s_mov_b32 m0, s59
	s_nop 0
	global_load_lds_dwordx4 v[226:227], off
	s_waitcnt vmcnt(8)
	s_waitcnt lgkmcnt(0)
	s_barrier
	s_setprio 0
	v_mfma_f32_16x16x32_bf16 v[126:129], v[146:149], v[186:189], v[126:129]
	v_mfma_f32_16x16x32_bf16 v[122:125], v[162:165], v[186:189], v[122:125]
	v_mfma_f32_16x16x32_bf16 v[110:113], v[146:149], v[194:197], v[110:113]
	v_mfma_f32_16x16x32_bf16 v[106:109], v[162:165], v[194:197], v[106:109]
	v_mfma_f32_16x16x32_bf16 v[94:97], v[146:149], v[202:205], v[94:97]
	v_mfma_f32_16x16x32_bf16 v[90:93], v[162:165], v[202:205], v[90:93]
	v_mfma_f32_16x16x32_bf16 v[78:81], v[146:149], v[210:213], v[78:81]
	v_mfma_f32_16x16x32_bf16 v[74:77], v[162:165], v[210:213], v[74:77]
	v_mfma_f32_16x16x32_bf16 v[126:129], v[158:161], v[190:193], v[126:129]
	v_mfma_f32_16x16x32_bf16 v[122:125], v[166:169], v[190:193], v[122:125]
	v_mfma_f32_16x16x32_bf16 v[110:113], v[158:161], v[198:201], v[110:113]
	v_mfma_f32_16x16x32_bf16 v[106:109], v[166:169], v[198:201], v[106:109]
	v_mfma_f32_16x16x32_bf16 v[94:97], v[158:161], v[206:209], v[94:97]
	v_mfma_f32_16x16x32_bf16 v[90:93], v[166:169], v[206:209], v[90:93]
	v_mfma_f32_16x16x32_bf16 v[78:81], v[158:161], v[214:217], v[78:81]
	v_mfma_f32_16x16x32_bf16 v[74:77], v[166:169], v[214:217], v[74:77]
	s_setprio 2
	s_setprio 0
	v_mfma_f32_16x16x32_bf16 v[118:121], v[170:173], v[186:189], v[118:121]
	v_mfma_f32_16x16x32_bf16 v[114:117], v[178:181], v[186:189], v[114:117]
	v_mfma_f32_16x16x32_bf16 v[102:105], v[170:173], v[194:197], v[102:105]
	v_mfma_f32_16x16x32_bf16 v[98:101], v[178:181], v[194:197], v[98:101]
	v_mfma_f32_16x16x32_bf16 v[86:89], v[170:173], v[202:205], v[86:89]
	v_mfma_f32_16x16x32_bf16 v[82:85], v[178:181], v[202:205], v[82:85]
	v_mfma_f32_16x16x32_bf16 v[70:73], v[170:173], v[210:213], v[70:73]
	v_mfma_f32_16x16x32_bf16 v[66:69], v[178:181], v[210:213], v[66:69]
	v_mfma_f32_16x16x32_bf16 v[118:121], v[174:177], v[190:193], v[118:121]
	v_mfma_f32_16x16x32_bf16 v[114:117], v[182:185], v[190:193], v[114:117]
	v_mfma_f32_16x16x32_bf16 v[102:105], v[174:177], v[198:201], v[102:105]
	v_mfma_f32_16x16x32_bf16 v[98:101], v[182:185], v[198:201], v[98:101]
	v_mfma_f32_16x16x32_bf16 v[86:89], v[174:177], v[206:209], v[86:89]
	v_mfma_f32_16x16x32_bf16 v[82:85], v[182:185], v[206:209], v[82:85]
	v_mfma_f32_16x16x32_bf16 v[70:73], v[174:177], v[214:217], v[70:73]
	v_mfma_f32_16x16x32_bf16 v[66:69], v[182:185], v[214:217], v[66:69]
	s_setprio 2
	s_barrier
; #define PG8_STAGE(bufoff, gbase, voff) do { _Pragma("unroll") for (int _i = 0; _i < 2; ++_i) \
;         __builtin_amdgcn_global_load_lds((const unsigned*)((const char*)(gbase) + (voff)[_i]), (LAS unsigned*)(lds + (bufoff) + ldsw + _i * 8192), 16, 0, 0); } while (0)
; #define PG8_LDA(dst, b, h) do { _Pragma("unroll") for (int m = 0; m < 4; ++m) _Pragma("unroll") for (int k = 0; k < 2; ++k) dst[m][k] = *(const LAS bf16x8*)(lds + PG8_SA(b, h) + aoff + m * 2048 + k * 1024); } while (0)
; #define PG8_MMA(ai, bj, At, Bt) do { __builtin_amdgcn_s_setprio(1); _Pragma("unroll") for (int m = 0; m < 4; ++m) _Pragma("unroll") for (int n = 0; n < 2; ++n) _Pragma("unroll") for (int k = 0; k < 2; ++k) \
;         acc[ai][bj][m][n] = __builtin_amdgcn_mfma_f32_16x16x32_bf16(Bt[n][k], At[m][k], acc[ai][bj][m][n], 0, 0, 0); __builtin_amdgcn_s_setprio(0); } while (0)
; #define PG8_WAIT_V(n) asm volatile("s_waitcnt vmcnt(" #n ")" ::: "memory")
; #define PG8_WAIT_L(n) asm volatile("s_waitcnt lgkmcnt(" #n ")" ::: "memory")
; #define PG8_BAR __builtin_amdgcn_s_barrier()
; #define PG8_SCHED __builtin_amdgcn_sched_barrier(0)
; template <class Epi>
; __device__ __forceinline__ void gemm_phase(LAS unsigned char* lds, const Gemm g, int G, int c, const Epi& E) {
;     ...
;             PG8_LDA(At, 1, 1); PG8_STAGE(PG8_SB(1, 0), b3, voffB); PG8_STAGE(PG8_SB(1, 1), b3 + hstepB, voffB); PG8_STAGE(PG8_SA(1, 0), a3, voffA);
;             PG8_WAIT_V(8); PG8_WAIT_L(0); PG8_BAR; PG8_MMA(1, 0, At, B0); PG8_MMA(1, 1, At, B1); PG8_BAR; PG8_SCHED;
;         }
;         if (wr == 0) PG8_BAR;
	s_add_i32 s33, s33, s56
	v_lshl_add_u64 v[218:219], v[218:219], 0, s[20:21]
	s_mov_b32 m0, s33
	ds_read_b128 v[186:189], v154 offset:49152
	ds_read_b128 v[190:193], v154 offset:50176
	ds_read_b128 v[194:197], v154 offset:51200
	ds_read_b128 v[198:201], v154 offset:52224
	ds_read_b128 v[202:205], v154 offset:53248
	ds_read_b128 v[206:209], v154 offset:54272
	ds_read_b128 v[210:213], v154 offset:55296
	ds_read_b128 v[214:217], v154 offset:56320
	global_load_lds_dwordx4 v[218:219], off
	s_add_i32 m0, s33, 0x2000
	s_add_u32 s46, s46, 0x40080
	v_lshl_add_u64 v[218:219], v[220:221], 0, s[20:21]
	s_addc_u32 s47, s47, 0
	s_add_i32 s33, s62, s56
	global_load_lds_dwordx4 v[218:219], off
	v_lshl_add_u64 v[218:219], s[46:47], 0, v[132:133]
	s_mov_b32 m0, s33
	s_nop 0
	global_load_lds_dwordx4 v[218:219], off
	v_lshl_add_u64 v[218:219], s[46:47], 0, v[136:137]
	s_add_i32 m0, s33, 0x2000
	s_nop 0
	global_load_lds_dwordx4 v[218:219], off
	v_lshl_add_u64 v[218:219], v[222:223], 0, s[20:21]
	s_mov_b32 m0, s67
	s_nop 0
	global_load_lds_dwordx4 v[218:219], off
	v_lshl_add_u64 v[218:219], v[224:225], 0, s[20:21]
	s_mov_b32 m0, s68
	s_nop 0
	global_load_lds_dwordx4 v[218:219], off
	s_waitcnt vmcnt(8)
	s_waitcnt lgkmcnt(0)
	s_barrier
	s_setprio 0
	v_mfma_f32_16x16x32_bf16 v[62:65], v[146:149], v[186:189], v[62:65]
	v_mfma_f32_16x16x32_bf16 v[58:61], v[162:165], v[186:189], v[58:61]
	v_mfma_f32_16x16x32_bf16 v[46:49], v[146:149], v[194:197], v[46:49]
	v_mfma_f32_16x16x32_bf16 v[42:45], v[162:165], v[194:197], v[42:45]
	v_mfma_f32_16x16x32_bf16 v[30:33], v[146:149], v[202:205], v[30:33]
	v_mfma_f32_16x16x32_bf16 v[26:29], v[162:165], v[202:205], v[26:29]
	v_mfma_f32_16x16x32_bf16 v[14:17], v[146:149], v[210:213], v[14:17]
	v_mfma_f32_16x16x32_bf16 v[10:13], v[162:165], v[210:213], v[10:13]
	v_mfma_f32_16x16x32_bf16 v[62:65], v[158:161], v[190:193], v[62:65]
	v_mfma_f32_16x16x32_bf16 v[58:61], v[166:169], v[190:193], v[58:61]
	v_mfma_f32_16x16x32_bf16 v[46:49], v[158:161], v[198:201], v[46:49]
	v_mfma_f32_16x16x32_bf16 v[42:45], v[166:169], v[198:201], v[42:45]
	v_mfma_f32_16x16x32_bf16 v[30:33], v[158:161], v[206:209], v[30:33]
	v_mfma_f32_16x16x32_bf16 v[26:29], v[166:169], v[206:209], v[26:29]
	v_mfma_f32_16x16x32_bf16 v[14:17], v[158:161], v[214:217], v[14:17]
	v_mfma_f32_16x16x32_bf16 v[10:13], v[166:169], v[214:217], v[10:13]
	s_setprio 2
	s_setprio 0
	v_mfma_f32_16x16x32_bf16 v[54:57], v[170:173], v[186:189], v[54:57]
	v_mfma_f32_16x16x32_bf16 v[50:53], v[178:181], v[186:189], v[50:53]
	v_mfma_f32_16x16x32_bf16 v[38:41], v[170:173], v[194:197], v[38:41]
	v_mfma_f32_16x16x32_bf16 v[34:37], v[178:181], v[194:197], v[34:37]
	v_mfma_f32_16x16x32_bf16 v[22:25], v[170:173], v[202:205], v[22:25]
	v_mfma_f32_16x16x32_bf16 v[18:21], v[178:181], v[202:205], v[18:21]
	v_mfma_f32_16x16x32_bf16 v[6:9], v[170:173], v[210:213], v[6:9]
	v_mfma_f32_16x16x32_bf16 v[2:5], v[178:181], v[210:213], v[2:5]
	v_mfma_f32_16x16x32_bf16 v[54:57], v[174:177], v[190:193], v[54:57]
	v_mfma_f32_16x16x32_bf16 v[50:53], v[182:185], v[190:193], v[50:53]
	v_mfma_f32_16x16x32_bf16 v[38:41], v[174:177], v[198:201], v[38:41]
	v_mfma_f32_16x16x32_bf16 v[34:37], v[182:185], v[198:201], v[34:37]
	v_mfma_f32_16x16x32_bf16 v[22:25], v[174:177], v[206:209], v[22:25]
	v_mfma_f32_16x16x32_bf16 v[18:21], v[182:185], v[206:209], v[18:21]
	v_mfma_f32_16x16x32_bf16 v[6:9], v[174:177], v[214:217], v[6:9]
	v_mfma_f32_16x16x32_bf16 v[2:5], v[182:185], v[214:217], v[2:5]
	s_setprio 2
	s_barrier
	s_add_i32 s81, s81, 2
	s_add_u32 s4, s4, 0x100
	s_addc_u32 s5, s5, 0
	s_add_u32 s41, s41, 0x100
	s_addc_u32 s80, s80, 0
	s_cmp_gt_u32 s81, 13
	s_cbranch_scc0 .LBB0_1297
	s_and_b64 vcc, exec, s[22:23]
	s_cbranch_vccz .LBB0_1300
	s_barrier

; #define PG8_STAGE(bufoff, gbase, voff) do { _Pragma("unroll") for (int _i = 0; _i < 2; ++_i) \
;         __builtin_amdgcn_global_load_lds((const unsigned*)((const char*)(gbase) + (voff)[_i]), (LAS unsigned*)(lds + (bufoff) + ldsw + _i * 8192), 16, 0, 0); } while (0)
; #define PG8_LDA(dst, b, h) do { _Pragma("unroll") for (int m = 0; m < 4; ++m) _Pragma("unroll") for (int k = 0; k < 2; ++k) dst[m][k] = *(const LAS bf16x8*)(lds + PG8_SA(b, h) + aoff + m * 2048 + k * 1024); } while (0)
; #define PG8_LDB(dst, b, h) do { _Pragma("unroll") for (int n = 0; n < 2; ++n) _Pragma("unroll") for (int k = 0; k < 2; ++k) dst[n][k] = *(const LAS bf16x8*)(lds + PG8_SB(b, h) + boff + n * 2048 + k * 1024); } while (0)
; #define PG8_MMA(ai, bj, At, Bt) do { __builtin_amdgcn_s_setprio(1); _Pragma("unroll") for (int m = 0; m < 4; ++m) _Pragma("unroll") for (int n = 0; n < 2; ++n) _Pragma("unroll") for (int k = 0; k < 2; ++k) \
;         acc[ai][bj][m][n] = __builtin_amdgcn_mfma_f32_16x16x32_bf16(Bt[n][k], At[m][k], acc[ai][bj][m][n], 0, 0, 0); __builtin_amdgcn_s_setprio(0); } while (0)
; #define PG8_WAIT_V(n) asm volatile("s_waitcnt vmcnt(" #n ")" ::: "memory")
; template <class Epi>
; __device__ __forceinline__ void gemm_phase(LAS unsigned char* lds, const Gemm g, int G, int c, const Epi& E) {
;     ...
;         const bool has_next = S.next(ui + 1, nxt);
;         const char* nA = has_next ? (const char*)(g.A + (size_t)nxt.pb * g.sA) + (size_t)nxt.pm * 2 * hstepA : cA;
;         const char* nB = has_next ? (const char*)(g.Bt + (size_t)nxt.pb * g.sB) + (size_t)nxt.pn * 2 * hstepB : cB;
; #pragma nounroll
;         for (int t = 0; t < nt; t += 2) {
;             const bool last = (t == nt - 2);
;             const char* a1 = cA + (size_t)(t + 1) * kstep;
;             const char* a2 = last ? nA : cA + (size_t)(t + 2) * kstep; const char* b2 = last ? nB : cB + (size_t)(t + 2) * kstep;
;             const char* a3 = a2 + kstep; const char* b3 = b2 + kstep;
;             PG8_LDB(B0, 0, 0); PG8_LDB(B1, 0, 1); PG8_SCHED; PG8_LDA(At, 0, 0); PG8_STAGE(PG8_SA(1, 1), a1 + hstepA, voffA);
;             PG8_WAIT_V(8); PG8_WAIT_L(0); PG8_BAR; PG8_MMA(0, 0, At, B0); PG8_MMA(0, 1, At, B1); PG8_BAR; PG8_SCHED;
;             PG8_LDA(At, 0, 1); PG8_STAGE(PG8_SB(0, 0), b2, voffB); PG8_STAGE(PG8_SB(0, 1), b2 + hstepB, voffB); PG8_STAGE(PG8_SA(0, 0), a2, voffA);
.LBB0_1428:
	s_mov_b32 s13, 0
	s_mov_b64 s[20:21], -1
	s_mov_b64 s[22:23], 0
	s_add_u32 s33, s18, s13
	s_addc_u32 s42, s19, 0
	s_add_u32 s38, s33, 0x100
	s_addc_u32 s39, s42, 0
	s_and_b64 s[24:25], s[22:23], exec
	s_cselect_b32 s39, s5, s39
	s_cselect_b32 s38, s4, s38
	s_add_u32 s13, s16, s13
	s_addc_u32 s24, s17, 0
	s_add_u32 s13, s13, 0x100
	s_addc_u32 s24, s24, 0
	s_and_b64 s[22:23], s[22:23], exec
	s_cselect_b32 s41, s15, s24
	s_cselect_b32 s40, s14, s13
	s_add_u32 s44, s33, 0xb0080
	ds_read_b128 v[142:145], v148
	ds_read_b128 v[152:155], v148 offset:1024
	ds_read_b128 v[156:159], v148 offset:2048
	ds_read_b128 v[160:163], v148 offset:3072
	ds_read_b128 v[164:167], v149
	ds_read_b128 v[168:171], v149 offset:1024
	ds_read_b128 v[172:175], v149 offset:2048
	ds_read_b128 v[176:179], v149 offset:3072
	s_addc_u32 s45, s42, 0
	s_add_i32 s65, s72, s48
	s_add_i32 m0, s49, 0xc000
	s_add_i32 s85, s49, 0xe000
	s_add_i32 s62, s65, 0x2000
	s_add_u32 s42, s40, 0xb0000
	s_addc_u32 s43, s41, 0
	s_add_i32 s64, s73, s48
	s_add_i32 s63, s64, 0x2000
	s_add_i32 s84, 0, 0x18000
	s_add_i32 s33, 0, 0x1c000
	s_add_u32 s24, s38, 0xb0000
	s_addc_u32 s25, s39, 0
	s_add_i32 s83, s84, s48
	s_add_i32 s13, s83, 0x2000
	s_add_u32 s22, s40, 0xb0080
	s_addc_u32 s23, s41, 0
	s_add_i32 s75, s33, s48
	s_add_i32 s74, s75, 0x2000
	v_lshl_add_u64 v[212:213], s[44:45], 0, v[136:137]
	ds_read_b128 v[180:183], v150
	ds_read_b128 v[184:187], v150 offset:1024
	ds_read_b128 v[188:191], v150 offset:2048
	ds_read_b128 v[192:195], v150 offset:3072
	ds_read_b128 v[196:199], v150 offset:4096
	ds_read_b128 v[200:203], v150 offset:5120
	ds_read_b128 v[204:207], v150 offset:6144
	ds_read_b128 v[208:211], v150 offset:7168
	global_load_lds_dwordx4 v[212:213], off
	v_lshl_add_u64 v[212:213], s[44:45], 0, v[132:133]
	s_mov_b32 m0, s85
	s_nop 0
	global_load_lds_dwordx4 v[212:213], off
	s_waitcnt vmcnt(8)
	s_waitcnt lgkmcnt(0)
	s_barrier
	s_setprio 0
	v_mfma_f32_16x16x32_bf16 v[126:129], v[142:145], v[180:183], 0
	v_mfma_f32_16x16x32_bf16 v[122:125], v[156:159], v[180:183], 0
	v_mfma_f32_16x16x32_bf16 v[118:121], v[142:145], v[188:191], 0
	v_mfma_f32_16x16x32_bf16 v[110:113], v[156:159], v[188:191], 0
	v_mfma_f32_16x16x32_bf16 v[102:105], v[142:145], v[196:199], 0
	v_mfma_f32_16x16x32_bf16 v[94:97], v[156:159], v[196:199], 0
	v_mfma_f32_16x16x32_bf16 v[86:89], v[142:145], v[204:207], 0
	v_mfma_f32_16x16x32_bf16 v[78:81], v[156:159], v[204:207], 0
	v_mfma_f32_16x16x32_bf16 v[126:129], v[152:155], v[184:187], v[126:129]
	v_mfma_f32_16x16x32_bf16 v[122:125], v[160:163], v[184:187], v[122:125]
	v_mfma_f32_16x16x32_bf16 v[118:121], v[152:155], v[192:195], v[118:121]
	v_mfma_f32_16x16x32_bf16 v[110:113], v[160:163], v[192:195], v[110:113]
	v_mfma_f32_16x16x32_bf16 v[102:105], v[152:155], v[200:203], v[102:105]
	v_mfma_f32_16x16x32_bf16 v[94:97], v[160:163], v[200:203], v[94:97]
	v_mfma_f32_16x16x32_bf16 v[86:89], v[152:155], v[208:211], v[86:89]
	v_mfma_f32_16x16x32_bf16 v[78:81], v[160:163], v[208:211], v[78:81]
	s_setprio 2
	s_setprio 0
	v_mfma_f32_16x16x32_bf16 v[114:117], v[164:167], v[180:183], 0
	v_mfma_f32_16x16x32_bf16 v[106:109], v[172:175], v[180:183], 0
	v_mfma_f32_16x16x32_bf16 v[98:101], v[164:167], v[188:191], 0
	v_mfma_f32_16x16x32_bf16 v[90:93], v[172:175], v[188:191], 0
	v_mfma_f32_16x16x32_bf16 v[82:85], v[164:167], v[196:199], 0
	v_mfma_f32_16x16x32_bf16 v[74:77], v[172:175], v[196:199], 0
	v_mfma_f32_16x16x32_bf16 v[70:73], v[164:167], v[204:207], 0
	v_mfma_f32_16x16x32_bf16 v[66:69], v[172:175], v[204:207], 0
	v_mfma_f32_16x16x32_bf16 v[114:117], v[168:171], v[184:187], v[114:117]
	v_mfma_f32_16x16x32_bf16 v[106:109], v[176:179], v[184:187], v[106:109]
	v_mfma_f32_16x16x32_bf16 v[98:101], v[168:171], v[192:195], v[98:101]
	v_mfma_f32_16x16x32_bf16 v[90:93], v[176:179], v[192:195], v[90:93]
	v_mfma_f32_16x16x32_bf16 v[82:85], v[168:171], v[200:203], v[82:85]
	v_mfma_f32_16x16x32_bf16 v[74:77], v[176:179], v[200:203], v[74:77]
	v_mfma_f32_16x16x32_bf16 v[70:73], v[168:171], v[208:211], v[70:73]
	v_mfma_f32_16x16x32_bf16 v[66:69], v[176:179], v[208:211], v[66:69]
	s_setprio 2
	s_barrier
	s_mov_b32 m0, s65
	v_lshl_add_u64 v[212:213], s[40:41], 0, v[134:135]
	ds_read_b128 v[180:183], v150 offset:16384
	ds_read_b128 v[184:187], v150 offset:17408
	ds_read_b128 v[188:191], v150 offset:18432
	ds_read_b128 v[192:195], v150 offset:19456
	ds_read_b128 v[196:199], v150 offset:20480
	ds_read_b128 v[200:203], v150 offset:21504
	ds_read_b128 v[204:207], v150 offset:22528
	ds_read_b128 v[208:211], v150 offset:23552
	global_load_lds_dwordx4 v[212:213], off
	v_lshl_add_u64 v[214:215], s[40:41], 0, v[130:131]
	s_mov_b32 m0, s62
	v_lshl_add_u64 v[216:217], s[42:43], 0, v[134:135]
	global_load_lds_dwordx4 v[214:215], off
	s_mov_b32 m0, s64
	v_lshl_add_u64 v[218:219], s[38:39], 0, v[132:133]
	global_load_lds_dwordx4 v[216:217], off
	v_lshl_add_u64 v[216:217], s[42:43], 0, v[130:131]
	s_mov_b32 m0, s63
	s_nop 0
	global_load_lds_dwordx4 v[216:217], off
	v_lshl_add_u64 v[216:217], s[38:39], 0, v[136:137]
	s_mov_b32 m0, s49
	s_nop 0
	global_load_lds_dwordx4 v[216:217], off
	s_mov_b32 m0, s52
	s_nop 0
	global_load_lds_dwordx4 v[218:219], off
	s_waitcnt vmcnt(8)
	s_waitcnt lgkmcnt(0)
	s_barrier
; #define PG8_STAGE(bufoff, gbase, voff) do { _Pragma("unroll") for (int _i = 0; _i < 2; ++_i) \
;         __builtin_amdgcn_global_load_lds((const unsigned*)((const char*)(gbase) + (voff)[_i]), (LAS unsigned*)(lds + (bufoff) + ldsw + _i * 8192), 16, 0, 0); } while (0)
; #define PG8_LDA(dst, b, h) do { _Pragma("unroll") for (int m = 0; m < 4; ++m) _Pragma("unroll") for (int k = 0; k < 2; ++k) dst[m][k] = *(const LAS bf16x8*)(lds + PG8_SA(b, h) + aoff + m * 2048 + k * 1024); } while (0)
; #define PG8_LDB(dst, b, h) do { _Pragma("unroll") for (int n = 0; n < 2; ++n) _Pragma("unroll") for (int k = 0; k < 2; ++k) dst[n][k] = *(const LAS bf16x8*)(lds + PG8_SB(b, h) + boff + n * 2048 + k * 1024); } while (0)
; #define PG8_MMA(ai, bj, At, Bt) do { __builtin_amdgcn_s_setprio(1); _Pragma("unroll") for (int m = 0; m < 4; ++m) _Pragma("unroll") for (int n = 0; n < 2; ++n) _Pragma("unroll") for (int k = 0; k < 2; ++k) \
;         acc[ai][bj][m][n] = __builtin_amdgcn_mfma_f32_16x16x32_bf16(Bt[n][k], At[m][k], acc[ai][bj][m][n], 0, 0, 0); __builtin_amdgcn_s_setprio(0); } while (0)
; #define PG8_WAIT_V(n) asm volatile("s_waitcnt vmcnt(" #n ")" ::: "memory")
; #define PG8_WAIT_L(n) asm volatile("s_waitcnt lgkmcnt(" #n ")" ::: "memory")
; #define PG8_BAR __builtin_amdgcn_s_barrier()
; #define PG8_SCHED __builtin_amdgcn_sched_barrier(0)
; template <class Epi>
; __device__ __forceinline__ void gemm_phase(LAS unsigned char* lds, const Gemm g, int G, int c, const Epi& E) {
;     ...
;             PG8_WAIT_V(8); PG8_WAIT_L(0); PG8_BAR; PG8_MMA(1, 0, At, B0); PG8_MMA(1, 1, At, B1); PG8_BAR; PG8_SCHED;
;             PG8_LDB(B0, 1, 0); PG8_LDB(B1, 1, 1); PG8_SCHED; PG8_LDA(At, 1, 0); PG8_STAGE(PG8_SA(0, 1), a2 + hstepA, voffA);
;             PG8_WAIT_V(8); PG8_WAIT_L(0); PG8_BAR; PG8_MMA(0, 0, At, B0); PG8_MMA(0, 1, At, B1); PG8_BAR; PG8_SCHED;
	s_setprio 0
	v_mfma_f32_16x16x32_bf16 v[62:65], v[142:145], v[180:183], 0
	v_mfma_f32_16x16x32_bf16 v[58:61], v[156:159], v[180:183], 0
	v_mfma_f32_16x16x32_bf16 v[54:57], v[142:145], v[188:191], 0
	v_mfma_f32_16x16x32_bf16 v[46:49], v[156:159], v[188:191], 0
	v_mfma_f32_16x16x32_bf16 v[38:41], v[142:145], v[196:199], 0
	v_mfma_f32_16x16x32_bf16 v[30:33], v[156:159], v[196:199], 0
	v_mfma_f32_16x16x32_bf16 v[22:25], v[142:145], v[204:207], 0
	v_mfma_f32_16x16x32_bf16 v[14:17], v[156:159], v[204:207], 0
	v_mfma_f32_16x16x32_bf16 v[62:65], v[152:155], v[184:187], v[62:65]
	v_mfma_f32_16x16x32_bf16 v[58:61], v[160:163], v[184:187], v[58:61]
	v_mfma_f32_16x16x32_bf16 v[54:57], v[152:155], v[192:195], v[54:57]
	v_mfma_f32_16x16x32_bf16 v[46:49], v[160:163], v[192:195], v[46:49]
	v_mfma_f32_16x16x32_bf16 v[38:41], v[152:155], v[200:203], v[38:41]
	v_mfma_f32_16x16x32_bf16 v[30:33], v[160:163], v[200:203], v[30:33]
	v_mfma_f32_16x16x32_bf16 v[22:25], v[152:155], v[208:211], v[22:25]
	v_mfma_f32_16x16x32_bf16 v[14:17], v[160:163], v[208:211], v[14:17]
	s_setprio 2
	s_setprio 0
	v_mfma_f32_16x16x32_bf16 v[50:53], v[164:167], v[180:183], 0
	v_mfma_f32_16x16x32_bf16 v[42:45], v[172:175], v[180:183], 0
	v_mfma_f32_16x16x32_bf16 v[34:37], v[164:167], v[188:191], 0
	v_mfma_f32_16x16x32_bf16 v[26:29], v[172:175], v[188:191], 0
	v_mfma_f32_16x16x32_bf16 v[18:21], v[164:167], v[196:199], 0
	v_mfma_f32_16x16x32_bf16 v[10:13], v[172:175], v[196:199], 0
	v_mfma_f32_16x16x32_bf16 v[6:9], v[164:167], v[204:207], 0
	v_mfma_f32_16x16x32_bf16 v[2:5], v[172:175], v[204:207], 0
	v_mfma_f32_16x16x32_bf16 v[50:53], v[168:171], v[184:187], v[50:53]
	v_mfma_f32_16x16x32_bf16 v[42:45], v[176:179], v[184:187], v[42:45]
	v_mfma_f32_16x16x32_bf16 v[34:37], v[168:171], v[192:195], v[34:37]
	v_mfma_f32_16x16x32_bf16 v[26:29], v[176:179], v[192:195], v[26:29]
	v_mfma_f32_16x16x32_bf16 v[18:21], v[168:171], v[200:203], v[18:21]
	v_mfma_f32_16x16x32_bf16 v[10:13], v[176:179], v[200:203], v[10:13]
	v_mfma_f32_16x16x32_bf16 v[6:9], v[168:171], v[208:211], v[6:9]
	v_mfma_f32_16x16x32_bf16 v[2:5], v[176:179], v[208:211], v[2:5]
	s_setprio 2
	s_barrier
	v_add_u32_e32 v151, s84, v147
	ds_read_b128 v[142:145], v151
	ds_read_b128 v[152:155], v151 offset:1024
	ds_read_b128 v[156:159], v151 offset:2048
	ds_read_b128 v[160:163], v151 offset:3072
	v_add_u32_e32 v151, s33, v147
	ds_read_b128 v[164:167], v151
	ds_read_b128 v[168:171], v151 offset:1024
	ds_read_b128 v[172:175], v151 offset:2048
	ds_read_b128 v[176:179], v151 offset:3072
	s_mov_b32 m0, s53
	v_lshl_add_u64 v[220:221], s[24:25], 0, v[136:137]
	ds_read_b128 v[180:183], v150 offset:32768
	ds_read_b128 v[184:187], v150 offset:33792
	ds_read_b128 v[188:191], v150 offset:34816
	ds_read_b128 v[192:195], v150 offset:35840
	ds_read_b128 v[196:199], v150 offset:36864
	ds_read_b128 v[200:203], v150 offset:37888
	ds_read_b128 v[204:207], v150 offset:38912
	ds_read_b128 v[208:211], v150 offset:39936
	global_load_lds_dwordx4 v[220:221], off
	v_lshl_add_u64 v[220:221], s[24:25], 0, v[132:133]
	s_mov_b32 m0, s54
	s_nop 0
	global_load_lds_dwordx4 v[220:221], off
	s_waitcnt vmcnt(8)
	s_waitcnt lgkmcnt(0)
	s_barrier
	s_setprio 0
	v_mfma_f32_16x16x32_bf16 v[126:129], v[142:145], v[180:183], v[126:129]
	v_mfma_f32_16x16x32_bf16 v[122:125], v[156:159], v[180:183], v[122:125]
	v_mfma_f32_16x16x32_bf16 v[118:121], v[142:145], v[188:191], v[118:121]
	v_mfma_f32_16x16x32_bf16 v[110:113], v[156:159], v[188:191], v[110:113]
	v_mfma_f32_16x16x32_bf16 v[102:105], v[142:145], v[196:199], v[102:105]
	v_mfma_f32_16x16x32_bf16 v[94:97], v[156:159], v[196:199], v[94:97]
	v_mfma_f32_16x16x32_bf16 v[86:89], v[142:145], v[204:207], v[86:89]
	v_mfma_f32_16x16x32_bf16 v[78:81], v[156:159], v[204:207], v[78:81]
	v_mfma_f32_16x16x32_bf16 v[126:129], v[152:155], v[184:187], v[126:129]
	v_mfma_f32_16x16x32_bf16 v[122:125], v[160:163], v[184:187], v[122:125]
	v_mfma_f32_16x16x32_bf16 v[118:121], v[152:155], v[192:195], v[118:121]
	v_mfma_f32_16x16x32_bf16 v[110:113], v[160:163], v[192:195], v[110:113]
	v_mfma_f32_16x16x32_bf16 v[102:105], v[152:155], v[200:203], v[102:105]
	v_mfma_f32_16x16x32_bf16 v[94:97], v[160:163], v[200:203], v[94:97]
	v_mfma_f32_16x16x32_bf16 v[86:89], v[152:155], v[208:211], v[86:89]
	v_mfma_f32_16x16x32_bf16 v[78:81], v[160:163], v[208:211], v[78:81]
	s_setprio 2
	s_setprio 0
	v_mfma_f32_16x16x32_bf16 v[114:117], v[164:167], v[180:183], v[114:117]
	v_mfma_f32_16x16x32_bf16 v[106:109], v[172:175], v[180:183], v[106:109]
	v_mfma_f32_16x16x32_bf16 v[98:101], v[164:167], v[188:191], v[98:101]
	v_mfma_f32_16x16x32_bf16 v[90:93], v[172:175], v[188:191], v[90:93]
	v_mfma_f32_16x16x32_bf16 v[82:85], v[164:167], v[196:199], v[82:85]
	v_mfma_f32_16x16x32_bf16 v[74:77], v[172:175], v[196:199], v[74:77]
	v_mfma_f32_16x16x32_bf16 v[70:73], v[164:167], v[204:207], v[70:73]
	v_mfma_f32_16x16x32_bf16 v[66:69], v[172:175], v[204:207], v[66:69]
	v_mfma_f32_16x16x32_bf16 v[114:117], v[168:171], v[184:187], v[114:117]
	v_mfma_f32_16x16x32_bf16 v[106:109], v[176:179], v[184:187], v[106:109]
	v_mfma_f32_16x16x32_bf16 v[98:101], v[168:171], v[192:195], v[98:101]
	v_mfma_f32_16x16x32_bf16 v[90:93], v[176:179], v[192:195], v[90:93]
	v_mfma_f32_16x16x32_bf16 v[82:85], v[168:171], v[200:203], v[82:85]
	v_mfma_f32_16x16x32_bf16 v[74:77], v[176:179], v[200:203], v[74:77]
	v_mfma_f32_16x16x32_bf16 v[70:73], v[168:171], v[208:211], v[70:73]
	v_mfma_f32_16x16x32_bf16 v[66:69], v[176:179], v[208:211], v[66:69]
	s_setprio 2
	s_barrier
; #define PG8_STAGE(bufoff, gbase, voff) do { _Pragma("unroll") for (int _i = 0; _i < 2; ++_i) \
;         __builtin_amdgcn_global_load_lds((const unsigned*)((const char*)(gbase) + (voff)[_i]), (LAS unsigned*)(lds + (bufoff) + ldsw + _i * 8192), 16, 0, 0); } while (0)
; #define PG8_LDA(dst, b, h) do { _Pragma("unroll") for (int m = 0; m < 4; ++m) _Pragma("unroll") for (int k = 0; k < 2; ++k) dst[m][k] = *(const LAS bf16x8*)(lds + PG8_SA(b, h) + aoff + m * 2048 + k * 1024); } while (0)
; #define PG8_LDB(dst, b, h) do { _Pragma("unroll") for (int n = 0; n < 2; ++n) _Pragma("unroll") for (int k = 0; k < 2; ++k) dst[n][k] = *(const LAS bf16x8*)(lds + PG8_SB(b, h) + boff + n * 2048 + k * 1024); } while (0)
; #define PG8_WAIT_V(n) asm volatile("s_waitcnt vmcnt(" #n ")" ::: "memory")
; #define PG8_WAIT_L(n) asm volatile("s_waitcnt lgkmcnt(" #n ")" ::: "memory")
; template <class Epi>
; __device__ __forceinline__ void gemm_phase(LAS unsigned char* lds, const Gemm g, int G, int c, const Epi& E) {
;     ...
;         for (int t = 0; t < nt; t += 2) {
;             const bool last = (t == nt - 2);
;             const char* a1 = cA + (size_t)(t + 1) * kstep;
;             const char* a2 = last ? nA : cA + (size_t)(t + 2) * kstep; const char* b2 = last ? nB : cB + (size_t)(t + 2) * kstep;
;             const char* a3 = a2 + kstep; const char* b3 = b2 + kstep;
;             PG8_LDB(B0, 0, 0); PG8_LDB(B1, 0, 1); PG8_SCHED; PG8_LDA(At, 0, 0); PG8_STAGE(PG8_SA(1, 1), a1 + hstepA, voffA);
;             PG8_WAIT_V(8); PG8_WAIT_L(0); PG8_BAR; PG8_MMA(0, 0, At, B0); PG8_MMA(0, 1, At, B1); PG8_BAR; PG8_SCHED;
;             PG8_LDA(At, 0, 1); PG8_STAGE(PG8_SB(0, 0), b2, voffB); PG8_STAGE(PG8_SB(0, 1), b2 + hstepB, voffB); PG8_STAGE(PG8_SA(0, 0), a2, voffA);
;             PG8_WAIT_V(8); PG8_WAIT_L(0); PG8_BAR; PG8_MMA(1, 0, At, B0); PG8_MMA(1, 1, At, B1); PG8_BAR; PG8_SCHED;
;             PG8_LDB(B0, 1, 0); PG8_LDB(B1, 1, 1); PG8_SCHED; PG8_LDA(At, 1, 0); PG8_STAGE(PG8_SA(0, 1), a2 + hstepA, voffA);
;             PG8_WAIT_V(8); PG8_WAIT_L(0); PG8_BAR; PG8_MMA(0, 0, At, B0); PG8_MMA(0, 1, At, B1); PG8_BAR; PG8_SCHED;
;             PG8_LDA(At, 1, 1); PG8_STAGE(PG8_SB(1, 0), b3, voffB); PG8_STAGE(PG8_SB(1, 1), b3 + hstepB, voffB); PG8_STAGE(PG8_SA(1, 0), a3, voffA);
;             PG8_WAIT_V(8); PG8_WAIT_L(0); PG8_BAR; PG8_MMA(1, 0, At, B0); PG8_MMA(1, 1, At, B1); PG8_BAR; PG8_SCHED;
	s_mov_b32 m0, s83
	v_lshl_add_u64 v[212:213], v[212:213], 0, s[8:9]
	ds_read_b128 v[180:183], v150 offset:49152
	ds_read_b128 v[184:187], v150 offset:50176
	ds_read_b128 v[188:191], v150 offset:51200
	ds_read_b128 v[192:195], v150 offset:52224
	ds_read_b128 v[196:199], v150 offset:53248
	ds_read_b128 v[200:203], v150 offset:54272
	ds_read_b128 v[204:207], v150 offset:55296
	ds_read_b128 v[208:211], v150 offset:56320
	global_load_lds_dwordx4 v[212:213], off
	v_lshl_add_u64 v[212:213], v[214:215], 0, s[8:9]
	s_mov_b32 m0, s13
	s_nop 0
	global_load_lds_dwordx4 v[212:213], off
	v_lshl_add_u64 v[212:213], s[22:23], 0, v[134:135]
	s_mov_b32 m0, s75
	s_nop 0
	global_load_lds_dwordx4 v[212:213], off
	v_lshl_add_u64 v[212:213], s[22:23], 0, v[130:131]
	s_mov_b32 m0, s74
	s_nop 0
	global_load_lds_dwordx4 v[212:213], off
	v_lshl_add_u64 v[212:213], v[216:217], 0, s[8:9]
	s_mov_b32 m0, s70
	s_nop 0
	global_load_lds_dwordx4 v[212:213], off
	v_lshl_add_u64 v[212:213], v[218:219], 0, s[8:9]
	s_mov_b32 m0, s71
	s_nop 0
	global_load_lds_dwordx4 v[212:213], off
	s_waitcnt vmcnt(8)
	s_waitcnt lgkmcnt(0)
	s_barrier
	s_setprio 0
	v_mfma_f32_16x16x32_bf16 v[62:65], v[142:145], v[180:183], v[62:65]
	v_mfma_f32_16x16x32_bf16 v[58:61], v[156:159], v[180:183], v[58:61]
	v_mfma_f32_16x16x32_bf16 v[54:57], v[142:145], v[188:191], v[54:57]
	v_mfma_f32_16x16x32_bf16 v[46:49], v[156:159], v[188:191], v[46:49]
	v_mfma_f32_16x16x32_bf16 v[38:41], v[142:145], v[196:199], v[38:41]
	v_mfma_f32_16x16x32_bf16 v[30:33], v[156:159], v[196:199], v[30:33]
	v_mfma_f32_16x16x32_bf16 v[22:25], v[142:145], v[204:207], v[22:25]
	v_mfma_f32_16x16x32_bf16 v[14:17], v[156:159], v[204:207], v[14:17]
	v_mfma_f32_16x16x32_bf16 v[62:65], v[152:155], v[184:187], v[62:65]
	v_mfma_f32_16x16x32_bf16 v[58:61], v[160:163], v[184:187], v[58:61]
	v_mfma_f32_16x16x32_bf16 v[54:57], v[152:155], v[192:195], v[54:57]
	v_mfma_f32_16x16x32_bf16 v[46:49], v[160:163], v[192:195], v[46:49]
	v_mfma_f32_16x16x32_bf16 v[38:41], v[152:155], v[200:203], v[38:41]
	v_mfma_f32_16x16x32_bf16 v[30:33], v[160:163], v[200:203], v[30:33]
	v_mfma_f32_16x16x32_bf16 v[22:25], v[152:155], v[208:211], v[22:25]
	v_mfma_f32_16x16x32_bf16 v[14:17], v[160:163], v[208:211], v[14:17]
	s_setprio 2
	s_setprio 0
	v_mfma_f32_16x16x32_bf16 v[50:53], v[164:167], v[180:183], v[50:53]
	v_mfma_f32_16x16x32_bf16 v[42:45], v[172:175], v[180:183], v[42:45]
	v_mfma_f32_16x16x32_bf16 v[34:37], v[164:167], v[188:191], v[34:37]
	v_mfma_f32_16x16x32_bf16 v[26:29], v[172:175], v[188:191], v[26:29]
	v_mfma_f32_16x16x32_bf16 v[18:21], v[164:167], v[196:199], v[18:21]
	v_mfma_f32_16x16x32_bf16 v[10:13], v[172:175], v[196:199], v[10:13]
	v_mfma_f32_16x16x32_bf16 v[6:9], v[164:167], v[204:207], v[6:9]
	v_mfma_f32_16x16x32_bf16 v[2:5], v[172:175], v[204:207], v[2:5]
	v_mfma_f32_16x16x32_bf16 v[50:53], v[168:171], v[184:187], v[50:53]
	v_mfma_f32_16x16x32_bf16 v[42:45], v[176:179], v[184:187], v[42:45]
	v_mfma_f32_16x16x32_bf16 v[34:37], v[168:171], v[192:195], v[34:37]
	v_mfma_f32_16x16x32_bf16 v[26:29], v[176:179], v[192:195], v[26:29]
	v_mfma_f32_16x16x32_bf16 v[18:21], v[168:171], v[200:203], v[18:21]
	v_mfma_f32_16x16x32_bf16 v[10:13], v[176:179], v[200:203], v[10:13]
	v_mfma_f32_16x16x32_bf16 v[6:9], v[168:171], v[208:211], v[6:9]
	v_mfma_f32_16x16x32_bf16 v[2:5], v[176:179], v[208:211], v[2:5]
	s_setprio 2
	s_barrier
	s_movk_i32 s13, 0x100
	s_andn2_b64 vcc, exec, s[20:21]
	s_mov_b64 s[22:23], -1
	s_mov_b64 s[20:21], 0
	s_cbranch_vccz .LBB0_1429
.LBB0_1429:
	s_add_u32 s33, s18, s13
	s_addc_u32 s42, s19, 0
	s_add_u32 s38, s33, 0x100
	s_addc_u32 s39, s42, 0
	s_and_b64 s[24:25], s[22:23], exec
	s_cselect_b32 s39, s5, s39
	s_cselect_b32 s38, s4, s38
	s_add_u32 s13, s16, s13
	s_addc_u32 s24, s17, 0
	s_add_u32 s13, s13, 0x100
	s_addc_u32 s24, s24, 0
	s_and_b64 s[22:23], s[22:23], exec
	s_cselect_b32 s41, s15, s24
	s_cselect_b32 s40, s14, s13
	s_add_u32 s44, s33, 0xb0080
	ds_read_b128 v[142:145], v148
	ds_read_b128 v[152:155], v148 offset:1024
	ds_read_b128 v[156:159], v148 offset:2048
	ds_read_b128 v[160:163], v148 offset:3072
	ds_read_b128 v[164:167], v149
	ds_read_b128 v[168:171], v149 offset:1024
	ds_read_b128 v[172:175], v149 offset:2048
	ds_read_b128 v[176:179], v149 offset:3072
	s_addc_u32 s45, s42, 0
	s_add_i32 s65, s72, s48
	s_add_i32 m0, s49, 0xc000
	s_add_i32 s85, s49, 0xe000
	s_add_i32 s62, s65, 0x2000
	s_add_u32 s42, s40, 0xb0000
	s_addc_u32 s43, s41, 0
	s_add_i32 s64, s73, s48
	s_add_i32 s63, s64, 0x2000
	s_add_i32 s84, 0, 0x18000
	s_add_i32 s33, 0, 0x1c000
	s_add_u32 s24, s38, 0xb0000
	s_addc_u32 s25, s39, 0
	s_add_i32 s83, s84, s48
	s_add_i32 s13, s83, 0x2000
	s_add_u32 s22, s40, 0xb0080
	s_addc_u32 s23, s41, 0
	s_add_i32 s75, s33, s48
	s_add_i32 s74, s75, 0x2000
	v_lshl_add_u64 v[212:213], s[44:45], 0, v[136:137]
	ds_read_b128 v[180:183], v150
	ds_read_b128 v[184:187], v150 offset:1024
	ds_read_b128 v[188:191], v150 offset:2048
	ds_read_b128 v[192:195], v150 offset:3072
	ds_read_b128 v[196:199], v150 offset:4096
	ds_read_b128 v[200:203], v150 offset:5120
	ds_read_b128 v[204:207], v150 offset:6144
	ds_read_b128 v[208:211], v150 offset:7168
	global_load_lds_dwordx4 v[212:213], off
	v_lshl_add_u64 v[212:213], s[44:45], 0, v[132:133]
	s_mov_b32 m0, s85
	s_nop 0
	global_load_lds_dwordx4 v[212:213], off
	s_waitcnt vmcnt(8)
	s_waitcnt lgkmcnt(0)
	s_barrier
; #define PG8_STAGE(bufoff, gbase, voff) do { _Pragma("unroll") for (int _i = 0; _i < 2; ++_i) \
;         __builtin_amdgcn_global_load_lds((const unsigned*)((const char*)(gbase) + (voff)[_i]), (LAS unsigned*)(lds + (bufoff) + ldsw + _i * 8192), 16, 0, 0); } while (0)
; #define PG8_LDA(dst, b, h) do { _Pragma("unroll") for (int m = 0; m < 4; ++m) _Pragma("unroll") for (int k = 0; k < 2; ++k) dst[m][k] = *(const LAS bf16x8*)(lds + PG8_SA(b, h) + aoff + m * 2048 + k * 1024); } while (0)
; #define PG8_LDB(dst, b, h) do { _Pragma("unroll") for (int n = 0; n < 2; ++n) _Pragma("unroll") for (int k = 0; k < 2; ++k) dst[n][k] = *(const LAS bf16x8*)(lds + PG8_SB(b, h) + boff + n * 2048 + k * 1024); } while (0)
; #define PG8_MMA(ai, bj, At, Bt) do { __builtin_amdgcn_s_setprio(1); _Pragma("unroll") for (int m = 0; m < 4; ++m) _Pragma("unroll") for (int n = 0; n < 2; ++n) _Pragma("unroll") for (int k = 0; k < 2; ++k) \
;         acc[ai][bj][m][n] = __builtin_amdgcn_mfma_f32_16x16x32_bf16(Bt[n][k], At[m][k], acc[ai][bj][m][n], 0, 0, 0); __builtin_amdgcn_s_setprio(0); } while (0)
; #define PG8_WAIT_V(n) asm volatile("s_waitcnt vmcnt(" #n ")" ::: "memory")
; #define PG8_WAIT_L(n) asm volatile("s_waitcnt lgkmcnt(" #n ")" ::: "memory")
; #define PG8_BAR __builtin_amdgcn_s_barrier()
; #define PG8_SCHED __builtin_amdgcn_sched_barrier(0)
; template <class Epi>
; __device__ __forceinline__ void gemm_phase(LAS unsigned char* lds, const Gemm g, int G, int c, const Epi& E) {
;     ...
;             PG8_LDB(B0, 0, 0); PG8_LDB(B1, 0, 1); PG8_SCHED; PG8_LDA(At, 0, 0); PG8_STAGE(PG8_SA(1, 1), a1 + hstepA, voffA);
;             PG8_WAIT_V(8); PG8_WAIT_L(0); PG8_BAR; PG8_MMA(0, 0, At, B0); PG8_MMA(0, 1, At, B1); PG8_BAR; PG8_SCHED;
;             PG8_LDA(At, 0, 1); PG8_STAGE(PG8_SB(0, 0), b2, voffB); PG8_STAGE(PG8_SB(0, 1), b2 + hstepB, voffB); PG8_STAGE(PG8_SA(0, 0), a2, voffA);
;             PG8_WAIT_V(8); PG8_WAIT_L(0); PG8_BAR; PG8_MMA(1, 0, At, B0); PG8_MMA(1, 1, At, B1); PG8_BAR; PG8_SCHED;
	s_setprio 0
	v_mfma_f32_16x16x32_bf16 v[126:129], v[142:145], v[180:183], v[126:129]
	v_mfma_f32_16x16x32_bf16 v[122:125], v[156:159], v[180:183], v[122:125]
	v_mfma_f32_16x16x32_bf16 v[118:121], v[142:145], v[188:191], v[118:121]
	v_mfma_f32_16x16x32_bf16 v[110:113], v[156:159], v[188:191], v[110:113]
	v_mfma_f32_16x16x32_bf16 v[102:105], v[142:145], v[196:199], v[102:105]
	v_mfma_f32_16x16x32_bf16 v[94:97], v[156:159], v[196:199], v[94:97]
	v_mfma_f32_16x16x32_bf16 v[86:89], v[142:145], v[204:207], v[86:89]
	v_mfma_f32_16x16x32_bf16 v[78:81], v[156:159], v[204:207], v[78:81]
	v_mfma_f32_16x16x32_bf16 v[126:129], v[152:155], v[184:187], v[126:129]
	v_mfma_f32_16x16x32_bf16 v[122:125], v[160:163], v[184:187], v[122:125]
	v_mfma_f32_16x16x32_bf16 v[118:121], v[152:155], v[192:195], v[118:121]
	v_mfma_f32_16x16x32_bf16 v[110:113], v[160:163], v[192:195], v[110:113]
	v_mfma_f32_16x16x32_bf16 v[102:105], v[152:155], v[200:203], v[102:105]
	v_mfma_f32_16x16x32_bf16 v[94:97], v[160:163], v[200:203], v[94:97]
	v_mfma_f32_16x16x32_bf16 v[86:89], v[152:155], v[208:211], v[86:89]
	v_mfma_f32_16x16x32_bf16 v[78:81], v[160:163], v[208:211], v[78:81]
	s_setprio 2
	s_setprio 0
	v_mfma_f32_16x16x32_bf16 v[114:117], v[164:167], v[180:183], v[114:117]
	v_mfma_f32_16x16x32_bf16 v[106:109], v[172:175], v[180:183], v[106:109]
	v_mfma_f32_16x16x32_bf16 v[98:101], v[164:167], v[188:191], v[98:101]
	v_mfma_f32_16x16x32_bf16 v[90:93], v[172:175], v[188:191], v[90:93]
	v_mfma_f32_16x16x32_bf16 v[82:85], v[164:167], v[196:199], v[82:85]
	v_mfma_f32_16x16x32_bf16 v[74:77], v[172:175], v[196:199], v[74:77]
	v_mfma_f32_16x16x32_bf16 v[70:73], v[164:167], v[204:207], v[70:73]
	v_mfma_f32_16x16x32_bf16 v[66:69], v[172:175], v[204:207], v[66:69]
	v_mfma_f32_16x16x32_bf16 v[114:117], v[168:171], v[184:187], v[114:117]
	v_mfma_f32_16x16x32_bf16 v[106:109], v[176:179], v[184:187], v[106:109]
	v_mfma_f32_16x16x32_bf16 v[98:101], v[168:171], v[192:195], v[98:101]
	v_mfma_f32_16x16x32_bf16 v[90:93], v[176:179], v[192:195], v[90:93]
	v_mfma_f32_16x16x32_bf16 v[82:85], v[168:171], v[200:203], v[82:85]
	v_mfma_f32_16x16x32_bf16 v[74:77], v[176:179], v[200:203], v[74:77]
	v_mfma_f32_16x16x32_bf16 v[70:73], v[168:171], v[208:211], v[70:73]
	v_mfma_f32_16x16x32_bf16 v[66:69], v[176:179], v[208:211], v[66:69]
	s_setprio 2
	s_barrier
	s_mov_b32 m0, s65
	v_lshl_add_u64 v[212:213], s[40:41], 0, v[134:135]
	ds_read_b128 v[180:183], v150 offset:16384
	ds_read_b128 v[184:187], v150 offset:17408
	ds_read_b128 v[188:191], v150 offset:18432
	ds_read_b128 v[192:195], v150 offset:19456
	ds_read_b128 v[196:199], v150 offset:20480
	ds_read_b128 v[200:203], v150 offset:21504
	ds_read_b128 v[204:207], v150 offset:22528
	ds_read_b128 v[208:211], v150 offset:23552
	global_load_lds_dwordx4 v[212:213], off
	v_lshl_add_u64 v[214:215], s[40:41], 0, v[130:131]
	s_mov_b32 m0, s62
	v_lshl_add_u64 v[216:217], s[42:43], 0, v[134:135]
	global_load_lds_dwordx4 v[214:215], off
	s_mov_b32 m0, s64
	v_lshl_add_u64 v[218:219], s[38:39], 0, v[132:133]
	global_load_lds_dwordx4 v[216:217], off
	v_lshl_add_u64 v[216:217], s[42:43], 0, v[130:131]
	s_mov_b32 m0, s63
	s_nop 0
	global_load_lds_dwordx4 v[216:217], off
	v_lshl_add_u64 v[216:217], s[38:39], 0, v[136:137]
	s_mov_b32 m0, s49
	s_nop 0
	global_load_lds_dwordx4 v[216:217], off
	s_mov_b32 m0, s52
	s_nop 0
	global_load_lds_dwordx4 v[218:219], off
	s_waitcnt vmcnt(8)
	s_waitcnt lgkmcnt(0)
	s_barrier
	s_setprio 0
	v_mfma_f32_16x16x32_bf16 v[62:65], v[142:145], v[180:183], v[62:65]
	v_mfma_f32_16x16x32_bf16 v[58:61], v[156:159], v[180:183], v[58:61]
	v_mfma_f32_16x16x32_bf16 v[54:57], v[142:145], v[188:191], v[54:57]
	v_mfma_f32_16x16x32_bf16 v[46:49], v[156:159], v[188:191], v[46:49]
	v_mfma_f32_16x16x32_bf16 v[38:41], v[142:145], v[196:199], v[38:41]
	v_mfma_f32_16x16x32_bf16 v[30:33], v[156:159], v[196:199], v[30:33]
	v_mfma_f32_16x16x32_bf16 v[22:25], v[142:145], v[204:207], v[22:25]
	v_mfma_f32_16x16x32_bf16 v[14:17], v[156:159], v[204:207], v[14:17]
	v_mfma_f32_16x16x32_bf16 v[62:65], v[152:155], v[184:187], v[62:65]
	v_mfma_f32_16x16x32_bf16 v[58:61], v[160:163], v[184:187], v[58:61]
	v_mfma_f32_16x16x32_bf16 v[54:57], v[152:155], v[192:195], v[54:57]
	v_mfma_f32_16x16x32_bf16 v[46:49], v[160:163], v[192:195], v[46:49]
	v_mfma_f32_16x16x32_bf16 v[38:41], v[152:155], v[200:203], v[38:41]
	v_mfma_f32_16x16x32_bf16 v[30:33], v[160:163], v[200:203], v[30:33]
	v_mfma_f32_16x16x32_bf16 v[22:25], v[152:155], v[208:211], v[22:25]
	v_mfma_f32_16x16x32_bf16 v[14:17], v[160:163], v[208:211], v[14:17]
	s_setprio 2
	s_setprio 0
	v_mfma_f32_16x16x32_bf16 v[50:53], v[164:167], v[180:183], v[50:53]
	v_mfma_f32_16x16x32_bf16 v[42:45], v[172:175], v[180:183], v[42:45]
	v_mfma_f32_16x16x32_bf16 v[34:37], v[164:167], v[188:191], v[34:37]
	v_mfma_f32_16x16x32_bf16 v[26:29], v[172:175], v[188:191], v[26:29]
	v_mfma_f32_16x16x32_bf16 v[18:21], v[164:167], v[196:199], v[18:21]
	v_mfma_f32_16x16x32_bf16 v[10:13], v[172:175], v[196:199], v[10:13]
	v_mfma_f32_16x16x32_bf16 v[6:9], v[164:167], v[204:207], v[6:9]
	v_mfma_f32_16x16x32_bf16 v[2:5], v[172:175], v[204:207], v[2:5]
	v_mfma_f32_16x16x32_bf16 v[50:53], v[168:171], v[184:187], v[50:53]
	v_mfma_f32_16x16x32_bf16 v[42:45], v[176:179], v[184:187], v[42:45]
	v_mfma_f32_16x16x32_bf16 v[34:37], v[168:171], v[192:195], v[34:37]
	v_mfma_f32_16x16x32_bf16 v[26:29], v[176:179], v[192:195], v[26:29]
	v_mfma_f32_16x16x32_bf16 v[18:21], v[168:171], v[200:203], v[18:21]
	v_mfma_f32_16x16x32_bf16 v[10:13], v[176:179], v[200:203], v[10:13]
	v_mfma_f32_16x16x32_bf16 v[6:9], v[168:171], v[208:211], v[6:9]
	v_mfma_f32_16x16x32_bf16 v[2:5], v[176:179], v[208:211], v[2:5]
	s_setprio 2
	s_barrier
; #define PG8_STAGE(bufoff, gbase, voff) do { _Pragma("unroll") for (int _i = 0; _i < 2; ++_i) \
;         __builtin_amdgcn_global_load_lds((const unsigned*)((const char*)(gbase) + (voff)[_i]), (LAS unsigned*)(lds + (bufoff) + ldsw + _i * 8192), 16, 0, 0); } while (0)
; #define PG8_LDA(dst, b, h) do { _Pragma("unroll") for (int m = 0; m < 4; ++m) _Pragma("unroll") for (int k = 0; k < 2; ++k) dst[m][k] = *(const LAS bf16x8*)(lds + PG8_SA(b, h) + aoff + m * 2048 + k * 1024); } while (0)
; #define PG8_LDB(dst, b, h) do { _Pragma("unroll") for (int n = 0; n < 2; ++n) _Pragma("unroll") for (int k = 0; k < 2; ++k) dst[n][k] = *(const LAS bf16x8*)(lds + PG8_SB(b, h) + boff + n * 2048 + k * 1024); } while (0)
; #define PG8_MMA(ai, bj, At, Bt) do { __builtin_amdgcn_s_setprio(1); _Pragma("unroll") for (int m = 0; m < 4; ++m) _Pragma("unroll") for (int n = 0; n < 2; ++n) _Pragma("unroll") for (int k = 0; k < 2; ++k) \
;         acc[ai][bj][m][n] = __builtin_amdgcn_mfma_f32_16x16x32_bf16(Bt[n][k], At[m][k], acc[ai][bj][m][n], 0, 0, 0); __builtin_amdgcn_s_setprio(0); } while (0)
; #define PG8_WAIT_V(n) asm volatile("s_waitcnt vmcnt(" #n ")" ::: "memory")
; #define PG8_WAIT_L(n) asm volatile("s_waitcnt lgkmcnt(" #n ")" ::: "memory")
; #define PG8_BAR __builtin_amdgcn_s_barrier()
; #define PG8_SCHED __builtin_amdgcn_sched_barrier(0)
; template <class Epi>
; __device__ __forceinline__ void gemm_phase(LAS unsigned char* lds, const Gemm g, int G, int c, const Epi& E) {
;     ...
;             PG8_LDB(B0, 1, 0); PG8_LDB(B1, 1, 1); PG8_SCHED; PG8_LDA(At, 1, 0); PG8_STAGE(PG8_SA(0, 1), a2 + hstepA, voffA);
;             PG8_WAIT_V(8); PG8_WAIT_L(0); PG8_BAR; PG8_MMA(0, 0, At, B0); PG8_MMA(0, 1, At, B1); PG8_BAR; PG8_SCHED;
;             PG8_LDA(At, 1, 1); PG8_STAGE(PG8_SB(1, 0), b3, voffB); PG8_STAGE(PG8_SB(1, 1), b3 + hstepB, voffB); PG8_STAGE(PG8_SA(1, 0), a3, voffA);
;             PG8_WAIT_V(8); PG8_WAIT_L(0); PG8_BAR; PG8_MMA(1, 0, At, B0); PG8_MMA(1, 1, At, B1); PG8_BAR; PG8_SCHED;
;         }
;         if (wr == 0) PG8_BAR;
	v_add_u32_e32 v151, s84, v147
	ds_read_b128 v[142:145], v151
	ds_read_b128 v[152:155], v151 offset:1024
	ds_read_b128 v[156:159], v151 offset:2048
	ds_read_b128 v[160:163], v151 offset:3072
	v_add_u32_e32 v151, s33, v147
	ds_read_b128 v[164:167], v151
	ds_read_b128 v[168:171], v151 offset:1024
	ds_read_b128 v[172:175], v151 offset:2048
	ds_read_b128 v[176:179], v151 offset:3072
	s_mov_b32 m0, s53
	v_lshl_add_u64 v[220:221], s[24:25], 0, v[136:137]
	ds_read_b128 v[180:183], v150 offset:32768
	ds_read_b128 v[184:187], v150 offset:33792
	ds_read_b128 v[188:191], v150 offset:34816
	ds_read_b128 v[192:195], v150 offset:35840
	ds_read_b128 v[196:199], v150 offset:36864
	ds_read_b128 v[200:203], v150 offset:37888
	ds_read_b128 v[204:207], v150 offset:38912
	ds_read_b128 v[208:211], v150 offset:39936
	global_load_lds_dwordx4 v[220:221], off
	v_lshl_add_u64 v[220:221], s[24:25], 0, v[132:133]
	s_mov_b32 m0, s54
	s_nop 0
	global_load_lds_dwordx4 v[220:221], off
	s_waitcnt vmcnt(8)
	s_waitcnt lgkmcnt(0)
	s_barrier
	s_setprio 0
	v_mfma_f32_16x16x32_bf16 v[126:129], v[142:145], v[180:183], v[126:129]
	v_mfma_f32_16x16x32_bf16 v[122:125], v[156:159], v[180:183], v[122:125]
	v_mfma_f32_16x16x32_bf16 v[118:121], v[142:145], v[188:191], v[118:121]
	v_mfma_f32_16x16x32_bf16 v[110:113], v[156:159], v[188:191], v[110:113]
	v_mfma_f32_16x16x32_bf16 v[102:105], v[142:145], v[196:199], v[102:105]
	v_mfma_f32_16x16x32_bf16 v[94:97], v[156:159], v[196:199], v[94:97]
	v_mfma_f32_16x16x32_bf16 v[86:89], v[142:145], v[204:207], v[86:89]
	v_mfma_f32_16x16x32_bf16 v[78:81], v[156:159], v[204:207], v[78:81]
	v_mfma_f32_16x16x32_bf16 v[126:129], v[152:155], v[184:187], v[126:129]
	v_mfma_f32_16x16x32_bf16 v[122:125], v[160:163], v[184:187], v[122:125]
	v_mfma_f32_16x16x32_bf16 v[118:121], v[152:155], v[192:195], v[118:121]
	v_mfma_f32_16x16x32_bf16 v[110:113], v[160:163], v[192:195], v[110:113]
	v_mfma_f32_16x16x32_bf16 v[102:105], v[152:155], v[200:203], v[102:105]
	v_mfma_f32_16x16x32_bf16 v[94:97], v[160:163], v[200:203], v[94:97]
	v_mfma_f32_16x16x32_bf16 v[86:89], v[152:155], v[208:211], v[86:89]
	v_mfma_f32_16x16x32_bf16 v[78:81], v[160:163], v[208:211], v[78:81]
	s_setprio 2
	s_setprio 0
	v_mfma_f32_16x16x32_bf16 v[114:117], v[164:167], v[180:183], v[114:117]
	v_mfma_f32_16x16x32_bf16 v[106:109], v[172:175], v[180:183], v[106:109]
	v_mfma_f32_16x16x32_bf16 v[98:101], v[164:167], v[188:191], v[98:101]
	v_mfma_f32_16x16x32_bf16 v[90:93], v[172:175], v[188:191], v[90:93]
	v_mfma_f32_16x16x32_bf16 v[82:85], v[164:167], v[196:199], v[82:85]
	v_mfma_f32_16x16x32_bf16 v[74:77], v[172:175], v[196:199], v[74:77]
	v_mfma_f32_16x16x32_bf16 v[70:73], v[164:167], v[204:207], v[70:73]
	v_mfma_f32_16x16x32_bf16 v[66:69], v[172:175], v[204:207], v[66:69]
	v_mfma_f32_16x16x32_bf16 v[114:117], v[168:171], v[184:187], v[114:117]
	v_mfma_f32_16x16x32_bf16 v[106:109], v[176:179], v[184:187], v[106:109]
	v_mfma_f32_16x16x32_bf16 v[98:101], v[168:171], v[192:195], v[98:101]
	v_mfma_f32_16x16x32_bf16 v[90:93], v[176:179], v[192:195], v[90:93]
	v_mfma_f32_16x16x32_bf16 v[82:85], v[168:171], v[200:203], v[82:85]
	v_mfma_f32_16x16x32_bf16 v[74:77], v[176:179], v[200:203], v[74:77]
	v_mfma_f32_16x16x32_bf16 v[70:73], v[168:171], v[208:211], v[70:73]
	v_mfma_f32_16x16x32_bf16 v[66:69], v[176:179], v[208:211], v[66:69]
	s_setprio 2
	s_barrier
	s_mov_b32 m0, s83
	v_lshl_add_u64 v[212:213], v[212:213], 0, s[8:9]
	ds_read_b128 v[180:183], v150 offset:49152
	ds_read_b128 v[184:187], v150 offset:50176
	ds_read_b128 v[188:191], v150 offset:51200
	ds_read_b128 v[192:195], v150 offset:52224
	ds_read_b128 v[196:199], v150 offset:53248
	ds_read_b128 v[200:203], v150 offset:54272
	ds_read_b128 v[204:207], v150 offset:55296
	ds_read_b128 v[208:211], v150 offset:56320
	global_load_lds_dwordx4 v[212:213], off
	v_lshl_add_u64 v[212:213], v[214:215], 0, s[8:9]
	s_mov_b32 m0, s13
	s_nop 0
	global_load_lds_dwordx4 v[212:213], off
	v_lshl_add_u64 v[212:213], s[22:23], 0, v[134:135]
	s_mov_b32 m0, s75
	s_nop 0
	global_load_lds_dwordx4 v[212:213], off
	v_lshl_add_u64 v[212:213], s[22:23], 0, v[130:131]
	s_mov_b32 m0, s74
	s_nop 0
	global_load_lds_dwordx4 v[212:213], off
	v_lshl_add_u64 v[212:213], v[216:217], 0, s[8:9]
	s_mov_b32 m0, s70
	s_nop 0
	global_load_lds_dwordx4 v[212:213], off
	v_lshl_add_u64 v[212:213], v[218:219], 0, s[8:9]
	s_mov_b32 m0, s71
	s_nop 0
	global_load_lds_dwordx4 v[212:213], off
	s_waitcnt vmcnt(8)
	s_waitcnt lgkmcnt(0)
	s_barrier
	s_setprio 0
	v_mfma_f32_16x16x32_bf16 v[62:65], v[142:145], v[180:183], v[62:65]
	v_mfma_f32_16x16x32_bf16 v[58:61], v[156:159], v[180:183], v[58:61]
	v_mfma_f32_16x16x32_bf16 v[54:57], v[142:145], v[188:191], v[54:57]
	v_mfma_f32_16x16x32_bf16 v[46:49], v[156:159], v[188:191], v[46:49]
	v_mfma_f32_16x16x32_bf16 v[38:41], v[142:145], v[196:199], v[38:41]
	v_mfma_f32_16x16x32_bf16 v[30:33], v[156:159], v[196:199], v[30:33]
	v_mfma_f32_16x16x32_bf16 v[22:25], v[142:145], v[204:207], v[22:25]
	v_mfma_f32_16x16x32_bf16 v[14:17], v[156:159], v[204:207], v[14:17]
	v_mfma_f32_16x16x32_bf16 v[62:65], v[152:155], v[184:187], v[62:65]
	v_mfma_f32_16x16x32_bf16 v[58:61], v[160:163], v[184:187], v[58:61]
	v_mfma_f32_16x16x32_bf16 v[54:57], v[152:155], v[192:195], v[54:57]
	v_mfma_f32_16x16x32_bf16 v[46:49], v[160:163], v[192:195], v[46:49]
	v_mfma_f32_16x16x32_bf16 v[38:41], v[152:155], v[200:203], v[38:41]
	v_mfma_f32_16x16x32_bf16 v[30:33], v[160:163], v[200:203], v[30:33]
	v_mfma_f32_16x16x32_bf16 v[22:25], v[152:155], v[208:211], v[22:25]
	v_mfma_f32_16x16x32_bf16 v[14:17], v[160:163], v[208:211], v[14:17]
	s_setprio 2
	s_setprio 0
	v_mfma_f32_16x16x32_bf16 v[50:53], v[164:167], v[180:183], v[50:53]
	v_mfma_f32_16x16x32_bf16 v[42:45], v[172:175], v[180:183], v[42:45]
	v_mfma_f32_16x16x32_bf16 v[34:37], v[164:167], v[188:191], v[34:37]
	v_mfma_f32_16x16x32_bf16 v[26:29], v[172:175], v[188:191], v[26:29]
	v_mfma_f32_16x16x32_bf16 v[18:21], v[164:167], v[196:199], v[18:21]
	v_mfma_f32_16x16x32_bf16 v[10:13], v[172:175], v[196:199], v[10:13]
	v_mfma_f32_16x16x32_bf16 v[6:9], v[164:167], v[204:207], v[6:9]
	v_mfma_f32_16x16x32_bf16 v[2:5], v[172:175], v[204:207], v[2:5]
	v_mfma_f32_16x16x32_bf16 v[50:53], v[168:171], v[184:187], v[50:53]
	v_mfma_f32_16x16x32_bf16 v[42:45], v[176:179], v[184:187], v[42:45]
	v_mfma_f32_16x16x32_bf16 v[34:37], v[168:171], v[192:195], v[34:37]
	v_mfma_f32_16x16x32_bf16 v[26:29], v[176:179], v[192:195], v[26:29]
	v_mfma_f32_16x16x32_bf16 v[18:21], v[168:171], v[200:203], v[18:21]
	v_mfma_f32_16x16x32_bf16 v[10:13], v[176:179], v[200:203], v[10:13]
	v_mfma_f32_16x16x32_bf16 v[6:9], v[168:171], v[208:211], v[6:9]
	v_mfma_f32_16x16x32_bf16 v[2:5], v[176:179], v[208:211], v[2:5]
	s_setprio 2
	s_barrier
	s_movk_i32 s13, 0x100
	s_andn2_b64 vcc, exec, s[20:21]
	s_mov_b64 s[22:23], -1
	s_mov_b64 s[20:21], 0
	s_cbranch_vccz .LBB0_1429
	s_and_b64 vcc, exec, s[10:11]
	s_cbranch_vccz .LBB0_1432
	s_barrier

; #define PG8_STAGE(bufoff, gbase, voff) do { _Pragma("unroll") for (int _i = 0; _i < 2; ++_i) \
;         __builtin_amdgcn_global_load_lds((const unsigned*)((const char*)(gbase) + (voff)[_i]), (LAS unsigned*)(lds + (bufoff) + ldsw + _i * 8192), 16, 0, 0); } while (0)
; #define PG8_LDA(dst, b, h) do { _Pragma("unroll") for (int m = 0; m < 4; ++m) _Pragma("unroll") for (int k = 0; k < 2; ++k) dst[m][k] = *(const LAS bf16x8*)(lds + PG8_SA(b, h) + aoff + m * 2048 + k * 1024); } while (0)
; #define PG8_LDB(dst, b, h) do { _Pragma("unroll") for (int n = 0; n < 2; ++n) _Pragma("unroll") for (int k = 0; k < 2; ++k) dst[n][k] = *(const LAS bf16x8*)(lds + PG8_SB(b, h) + boff + n * 2048 + k * 1024); } while (0)
; #define PG8_MMA(ai, bj, At, Bt) do { __builtin_amdgcn_s_setprio(1); _Pragma("unroll") for (int m = 0; m < 4; ++m) _Pragma("unroll") for (int n = 0; n < 2; ++n) _Pragma("unroll") for (int k = 0; k < 2; ++k) \
;         acc[ai][bj][m][n] = __builtin_amdgcn_mfma_f32_16x16x32_bf16(Bt[n][k], At[m][k], acc[ai][bj][m][n], 0, 0, 0); __builtin_amdgcn_s_setprio(0); } while (0)
; #define PG8_WAIT_V(n) asm volatile("s_waitcnt vmcnt(" #n ")" ::: "memory")
; template <class Epi>
; __device__ __forceinline__ void gemm_phase(LAS unsigned char* lds, const Gemm g, int G, int c, const Epi& E) {
;     ...
;     for (;;) {
;         const bool has_next = S.next(ui + 1, nxt);
;         const char* nA = has_next ? (const char*)(g.A + (size_t)nxt.pb * g.sA) + (size_t)nxt.pm * 2 * hstepA : cA;
;         const char* nB = has_next ? (const char*)(g.Bt + (size_t)nxt.pb * g.sB) + (size_t)nxt.pn * 2 * hstepB : cB;
; #pragma nounroll
;         for (int t = 0; t < nt; t += 2) {
;             const bool last = (t == nt - 2);
;             const char* a1 = cA + (size_t)(t + 1) * kstep;
;             const char* a2 = last ? nA : cA + (size_t)(t + 2) * kstep; const char* b2 = last ? nB : cB + (size_t)(t + 2) * kstep;
;             const char* a3 = a2 + kstep; const char* b3 = b2 + kstep;
;             PG8_LDB(B0, 0, 0); PG8_LDB(B1, 0, 1); PG8_SCHED; PG8_LDA(At, 0, 0); PG8_STAGE(PG8_SA(1, 1), a1 + hstepA, voffA);
;             PG8_WAIT_V(8); PG8_WAIT_L(0); PG8_BAR; PG8_MMA(0, 0, At, B0); PG8_MMA(0, 1, At, B1); PG8_BAR; PG8_SCHED;
;             PG8_LDA(At, 0, 1); PG8_STAGE(PG8_SB(0, 0), b2, voffB); PG8_STAGE(PG8_SB(0, 1), b2 + hstepB, voffB); PG8_STAGE(PG8_SA(0, 0), a2, voffA);
.LBB0_1450:
	s_mov_b32 s44, 0
	s_mov_b64 s[4:5], -1
	s_mov_b64 s[10:11], 0
	s_waitcnt vmcnt(0)
	s_add_u32 s33, s8, s44
	s_addc_u32 s45, s9, 0
	s_add_u32 s48, s33, 0x100
	s_addc_u32 s49, s45, 0
	s_and_b64 s[46:47], s[10:11], exec
	s_cselect_b32 s47, s41, s49
	s_cselect_b32 s46, s40, s48
	s_add_u32 s44, s6, s44
	s_addc_u32 s48, s7, 0
	s_add_u32 s44, s44, 0x100
	s_addc_u32 s48, s48, 0
	s_and_b64 s[10:11], s[10:11], exec
	s_cselect_b32 s49, s43, s48
	s_cselect_b32 s48, s42, s44
	s_add_u32 s54, s33, 0xb0080
	ds_read_b128 v[142:145], v160
	ds_read_b128 v[146:149], v160 offset:1024
	ds_read_b128 v[150:153], v160 offset:2048
	ds_read_b128 v[154:157], v160 offset:3072
	ds_read_b128 v[166:169], v161
	ds_read_b128 v[170:173], v161 offset:1024
	ds_read_b128 v[174:177], v161 offset:2048
	ds_read_b128 v[178:181], v161 offset:3072
	s_addc_u32 s55, s45, 0
	s_add_i32 s65, s82, s66
	s_add_i32 m0, s69, 0xc000
	s_add_i32 s74, s69, 0xe000
	s_add_i32 s62, s65, 0x2000
	s_add_u32 s52, s48, 0xb0000
	s_addc_u32 s53, s49, 0
	s_add_i32 s64, s83, s66
	s_add_i32 s63, s64, 0x2000
	s_add_i32 s97, 0, 0x18000
	s_add_i32 s33, 0, 0x1c000
	s_add_u32 s44, s46, 0xb0000
	s_addc_u32 s45, s47, 0
	s_add_i32 s96, s97, s66
	s_add_i32 s94, s96, 0x2000
	s_add_u32 s10, s48, 0xb0080
	s_addc_u32 s11, s49, 0
	s_add_i32 s95, s33, s66
	s_add_i32 s93, s95, 0x2000
	v_lshl_add_u64 v[214:215], s[54:55], 0, v[130:131]
	ds_read_b128 v[182:185], v162
	ds_read_b128 v[186:189], v162 offset:1024
	ds_read_b128 v[190:193], v162 offset:2048
	ds_read_b128 v[194:197], v162 offset:3072
	ds_read_b128 v[198:201], v162 offset:4096
	ds_read_b128 v[202:205], v162 offset:5120
	ds_read_b128 v[206:209], v162 offset:6144
	ds_read_b128 v[210:213], v162 offset:7168
	global_load_lds_dwordx4 v[214:215], off
	v_lshl_add_u64 v[214:215], s[54:55], 0, v[134:135]
	s_mov_b32 m0, s74
	s_nop 0
	global_load_lds_dwordx4 v[214:215], off
	s_waitcnt vmcnt(8)
	s_waitcnt lgkmcnt(0)
	s_barrier
	s_setprio 0
	v_mfma_f32_16x16x32_bf16 v[126:129], v[142:145], v[182:185], 0
	v_mfma_f32_16x16x32_bf16 v[122:125], v[150:153], v[182:185], 0
	v_mfma_f32_16x16x32_bf16 v[110:113], v[142:145], v[190:193], 0
	v_mfma_f32_16x16x32_bf16 v[106:109], v[150:153], v[190:193], 0
	v_mfma_f32_16x16x32_bf16 v[94:97], v[142:145], v[198:201], 0
	v_mfma_f32_16x16x32_bf16 v[90:93], v[150:153], v[198:201], 0
	v_mfma_f32_16x16x32_bf16 v[78:81], v[142:145], v[206:209], 0
	v_mfma_f32_16x16x32_bf16 v[74:77], v[150:153], v[206:209], 0
	v_mfma_f32_16x16x32_bf16 v[126:129], v[146:149], v[186:189], v[126:129]
	v_mfma_f32_16x16x32_bf16 v[122:125], v[154:157], v[186:189], v[122:125]
	v_mfma_f32_16x16x32_bf16 v[110:113], v[146:149], v[194:197], v[110:113]
	v_mfma_f32_16x16x32_bf16 v[106:109], v[154:157], v[194:197], v[106:109]
	v_mfma_f32_16x16x32_bf16 v[94:97], v[146:149], v[202:205], v[94:97]
	v_mfma_f32_16x16x32_bf16 v[90:93], v[154:157], v[202:205], v[90:93]
	v_mfma_f32_16x16x32_bf16 v[78:81], v[146:149], v[210:213], v[78:81]
	v_mfma_f32_16x16x32_bf16 v[74:77], v[154:157], v[210:213], v[74:77]
	s_setprio 2
	s_setprio 0
	v_mfma_f32_16x16x32_bf16 v[118:121], v[166:169], v[182:185], 0
	v_mfma_f32_16x16x32_bf16 v[114:117], v[174:177], v[182:185], 0
	v_mfma_f32_16x16x32_bf16 v[102:105], v[166:169], v[190:193], 0
	v_mfma_f32_16x16x32_bf16 v[98:101], v[174:177], v[190:193], 0
	v_mfma_f32_16x16x32_bf16 v[86:89], v[166:169], v[198:201], 0
	v_mfma_f32_16x16x32_bf16 v[82:85], v[174:177], v[198:201], 0
	v_mfma_f32_16x16x32_bf16 v[70:73], v[166:169], v[206:209], 0
	v_mfma_f32_16x16x32_bf16 v[66:69], v[174:177], v[206:209], 0
	v_mfma_f32_16x16x32_bf16 v[118:121], v[170:173], v[186:189], v[118:121]
	v_mfma_f32_16x16x32_bf16 v[114:117], v[178:181], v[186:189], v[114:117]
	v_mfma_f32_16x16x32_bf16 v[102:105], v[170:173], v[194:197], v[102:105]
	v_mfma_f32_16x16x32_bf16 v[98:101], v[178:181], v[194:197], v[98:101]
	v_mfma_f32_16x16x32_bf16 v[86:89], v[170:173], v[202:205], v[86:89]
	v_mfma_f32_16x16x32_bf16 v[82:85], v[178:181], v[202:205], v[82:85]
	v_mfma_f32_16x16x32_bf16 v[70:73], v[170:173], v[210:213], v[70:73]
	v_mfma_f32_16x16x32_bf16 v[66:69], v[178:181], v[210:213], v[66:69]
	s_setprio 2
	s_barrier
	s_mov_b32 m0, s65
	v_lshl_add_u64 v[214:215], s[48:49], 0, v[132:133]
	ds_read_b128 v[182:185], v162 offset:16384
	ds_read_b128 v[186:189], v162 offset:17408
	ds_read_b128 v[190:193], v162 offset:18432
	ds_read_b128 v[194:197], v162 offset:19456
	ds_read_b128 v[198:201], v162 offset:20480
	ds_read_b128 v[202:205], v162 offset:21504
	ds_read_b128 v[206:209], v162 offset:22528
	ds_read_b128 v[210:213], v162 offset:23552
	global_load_lds_dwordx4 v[214:215], off
	v_lshl_add_u64 v[216:217], s[48:49], 0, v[136:137]
	s_mov_b32 m0, s62
	v_lshl_add_u64 v[218:219], s[52:53], 0, v[132:133]
	global_load_lds_dwordx4 v[216:217], off
	s_mov_b32 m0, s64
	v_lshl_add_u64 v[220:221], s[46:47], 0, v[134:135]
	global_load_lds_dwordx4 v[218:219], off
	v_lshl_add_u64 v[218:219], s[52:53], 0, v[136:137]
	s_mov_b32 m0, s63
	s_nop 0
	global_load_lds_dwordx4 v[218:219], off
	v_lshl_add_u64 v[218:219], s[46:47], 0, v[130:131]
	s_mov_b32 m0, s69
	s_nop 0
	global_load_lds_dwordx4 v[218:219], off
	s_mov_b32 m0, s70
	s_nop 0
	global_load_lds_dwordx4 v[220:221], off
	s_waitcnt vmcnt(8)
	s_waitcnt lgkmcnt(0)
	s_barrier
; #define PG8_STAGE(bufoff, gbase, voff) do { _Pragma("unroll") for (int _i = 0; _i < 2; ++_i) \
;         __builtin_amdgcn_global_load_lds((const unsigned*)((const char*)(gbase) + (voff)[_i]), (LAS unsigned*)(lds + (bufoff) + ldsw + _i * 8192), 16, 0, 0); } while (0)
; #define PG8_LDA(dst, b, h) do { _Pragma("unroll") for (int m = 0; m < 4; ++m) _Pragma("unroll") for (int k = 0; k < 2; ++k) dst[m][k] = *(const LAS bf16x8*)(lds + PG8_SA(b, h) + aoff + m * 2048 + k * 1024); } while (0)
; #define PG8_LDB(dst, b, h) do { _Pragma("unroll") for (int n = 0; n < 2; ++n) _Pragma("unroll") for (int k = 0; k < 2; ++k) dst[n][k] = *(const LAS bf16x8*)(lds + PG8_SB(b, h) + boff + n * 2048 + k * 1024); } while (0)
; #define PG8_MMA(ai, bj, At, Bt) do { __builtin_amdgcn_s_setprio(1); _Pragma("unroll") for (int m = 0; m < 4; ++m) _Pragma("unroll") for (int n = 0; n < 2; ++n) _Pragma("unroll") for (int k = 0; k < 2; ++k) \
;         acc[ai][bj][m][n] = __builtin_amdgcn_mfma_f32_16x16x32_bf16(Bt[n][k], At[m][k], acc[ai][bj][m][n], 0, 0, 0); __builtin_amdgcn_s_setprio(0); } while (0)
; #define PG8_WAIT_V(n) asm volatile("s_waitcnt vmcnt(" #n ")" ::: "memory")
; #define PG8_WAIT_L(n) asm volatile("s_waitcnt lgkmcnt(" #n ")" ::: "memory")
; #define PG8_BAR __builtin_amdgcn_s_barrier()
; #define PG8_SCHED __builtin_amdgcn_sched_barrier(0)
; template <class Epi>
; __device__ __forceinline__ void gemm_phase(LAS unsigned char* lds, const Gemm g, int G, int c, const Epi& E) {
;     ...
;             PG8_WAIT_V(8); PG8_WAIT_L(0); PG8_BAR; PG8_MMA(0, 0, At, B0); PG8_MMA(0, 1, At, B1); PG8_BAR; PG8_SCHED;
;             PG8_LDA(At, 0, 1); PG8_STAGE(PG8_SB(0, 0), b2, voffB); PG8_STAGE(PG8_SB(0, 1), b2 + hstepB, voffB); PG8_STAGE(PG8_SA(0, 0), a2, voffA);
;             PG8_WAIT_V(8); PG8_WAIT_L(0); PG8_BAR; PG8_MMA(1, 0, At, B0); PG8_MMA(1, 1, At, B1); PG8_BAR; PG8_SCHED;
;             PG8_LDB(B0, 1, 0); PG8_LDB(B1, 1, 1); PG8_SCHED; PG8_LDA(At, 1, 0); PG8_STAGE(PG8_SA(0, 1), a2 + hstepA, voffA);
;             PG8_WAIT_V(8); PG8_WAIT_L(0); PG8_BAR; PG8_MMA(0, 0, At, B0); PG8_MMA(0, 1, At, B1); PG8_BAR; PG8_SCHED;
	s_setprio 0
	v_mfma_f32_16x16x32_bf16 v[62:65], v[142:145], v[182:185], 0
	v_mfma_f32_16x16x32_bf16 v[58:61], v[150:153], v[182:185], 0
	v_mfma_f32_16x16x32_bf16 v[46:49], v[142:145], v[190:193], 0
	v_mfma_f32_16x16x32_bf16 v[42:45], v[150:153], v[190:193], 0
	v_mfma_f32_16x16x32_bf16 v[30:33], v[142:145], v[198:201], 0
	v_mfma_f32_16x16x32_bf16 v[26:29], v[150:153], v[198:201], 0
	v_mfma_f32_16x16x32_bf16 v[14:17], v[142:145], v[206:209], 0
	v_mfma_f32_16x16x32_bf16 v[10:13], v[150:153], v[206:209], 0
	v_mfma_f32_16x16x32_bf16 v[62:65], v[146:149], v[186:189], v[62:65]
	v_mfma_f32_16x16x32_bf16 v[58:61], v[154:157], v[186:189], v[58:61]
	v_mfma_f32_16x16x32_bf16 v[46:49], v[146:149], v[194:197], v[46:49]
	v_mfma_f32_16x16x32_bf16 v[42:45], v[154:157], v[194:197], v[42:45]
	v_mfma_f32_16x16x32_bf16 v[30:33], v[146:149], v[202:205], v[30:33]
	v_mfma_f32_16x16x32_bf16 v[26:29], v[154:157], v[202:205], v[26:29]
	v_mfma_f32_16x16x32_bf16 v[14:17], v[146:149], v[210:213], v[14:17]
	v_mfma_f32_16x16x32_bf16 v[10:13], v[154:157], v[210:213], v[10:13]
	s_setprio 2
	s_setprio 0
	v_mfma_f32_16x16x32_bf16 v[54:57], v[166:169], v[182:185], 0
	v_mfma_f32_16x16x32_bf16 v[50:53], v[174:177], v[182:185], 0
	v_mfma_f32_16x16x32_bf16 v[38:41], v[166:169], v[190:193], 0
	v_mfma_f32_16x16x32_bf16 v[34:37], v[174:177], v[190:193], 0
	v_mfma_f32_16x16x32_bf16 v[22:25], v[166:169], v[198:201], 0
	v_mfma_f32_16x16x32_bf16 v[18:21], v[174:177], v[198:201], 0
	v_mfma_f32_16x16x32_bf16 v[6:9], v[166:169], v[206:209], 0
	v_mfma_f32_16x16x32_bf16 v[2:5], v[174:177], v[206:209], 0
	v_mfma_f32_16x16x32_bf16 v[54:57], v[170:173], v[186:189], v[54:57]
	v_mfma_f32_16x16x32_bf16 v[50:53], v[178:181], v[186:189], v[50:53]
	v_mfma_f32_16x16x32_bf16 v[38:41], v[170:173], v[194:197], v[38:41]
	v_mfma_f32_16x16x32_bf16 v[34:37], v[178:181], v[194:197], v[34:37]
	v_mfma_f32_16x16x32_bf16 v[22:25], v[170:173], v[202:205], v[22:25]
	v_mfma_f32_16x16x32_bf16 v[18:21], v[178:181], v[202:205], v[18:21]
	v_mfma_f32_16x16x32_bf16 v[6:9], v[170:173], v[210:213], v[6:9]
	v_mfma_f32_16x16x32_bf16 v[2:5], v[178:181], v[210:213], v[2:5]
	s_setprio 2
	s_barrier
	v_add_u32_e32 v154, s97, v159
	v_add_u32_e32 v178, s33, v159
	ds_read_b128 v[142:145], v154
	ds_read_b128 v[146:149], v154 offset:1024
	ds_read_b128 v[150:153], v154 offset:2048
	ds_read_b128 v[154:157], v154 offset:3072
	ds_read_b128 v[166:169], v178
	ds_read_b128 v[170:173], v178 offset:1024
	ds_read_b128 v[174:177], v178 offset:2048
	ds_read_b128 v[178:181], v178 offset:3072
	s_mov_b32 m0, s71
	v_lshl_add_u64 v[222:223], s[44:45], 0, v[130:131]
	ds_read_b128 v[182:185], v162 offset:32768
	ds_read_b128 v[186:189], v162 offset:33792
	ds_read_b128 v[190:193], v162 offset:34816
	ds_read_b128 v[194:197], v162 offset:35840
	ds_read_b128 v[198:201], v162 offset:36864
	ds_read_b128 v[202:205], v162 offset:37888
	ds_read_b128 v[206:209], v162 offset:38912
	ds_read_b128 v[210:213], v162 offset:39936
	global_load_lds_dwordx4 v[222:223], off
	v_lshl_add_u64 v[222:223], s[44:45], 0, v[134:135]
	s_mov_b32 m0, s72
	s_nop 0
	global_load_lds_dwordx4 v[222:223], off
	s_waitcnt vmcnt(8)
	s_waitcnt lgkmcnt(0)
	s_barrier
	s_setprio 0
	v_mfma_f32_16x16x32_bf16 v[126:129], v[142:145], v[182:185], v[126:129]
	v_mfma_f32_16x16x32_bf16 v[122:125], v[150:153], v[182:185], v[122:125]
	v_mfma_f32_16x16x32_bf16 v[110:113], v[142:145], v[190:193], v[110:113]
	v_mfma_f32_16x16x32_bf16 v[106:109], v[150:153], v[190:193], v[106:109]
	v_mfma_f32_16x16x32_bf16 v[94:97], v[142:145], v[198:201], v[94:97]
	v_mfma_f32_16x16x32_bf16 v[90:93], v[150:153], v[198:201], v[90:93]
	v_mfma_f32_16x16x32_bf16 v[78:81], v[142:145], v[206:209], v[78:81]
	v_mfma_f32_16x16x32_bf16 v[74:77], v[150:153], v[206:209], v[74:77]
	v_mfma_f32_16x16x32_bf16 v[126:129], v[146:149], v[186:189], v[126:129]
	v_mfma_f32_16x16x32_bf16 v[122:125], v[154:157], v[186:189], v[122:125]
	v_mfma_f32_16x16x32_bf16 v[110:113], v[146:149], v[194:197], v[110:113]
	v_mfma_f32_16x16x32_bf16 v[106:109], v[154:157], v[194:197], v[106:109]
	v_mfma_f32_16x16x32_bf16 v[94:97], v[146:149], v[202:205], v[94:97]
	v_mfma_f32_16x16x32_bf16 v[90:93], v[154:157], v[202:205], v[90:93]
	v_mfma_f32_16x16x32_bf16 v[78:81], v[146:149], v[210:213], v[78:81]
	v_mfma_f32_16x16x32_bf16 v[74:77], v[154:157], v[210:213], v[74:77]
	s_setprio 2
	s_setprio 0
	v_mfma_f32_16x16x32_bf16 v[118:121], v[166:169], v[182:185], v[118:121]
	v_mfma_f32_16x16x32_bf16 v[114:117], v[174:177], v[182:185], v[114:117]
	v_mfma_f32_16x16x32_bf16 v[102:105], v[166:169], v[190:193], v[102:105]
	v_mfma_f32_16x16x32_bf16 v[98:101], v[174:177], v[190:193], v[98:101]
	v_mfma_f32_16x16x32_bf16 v[86:89], v[166:169], v[198:201], v[86:89]
	v_mfma_f32_16x16x32_bf16 v[82:85], v[174:177], v[198:201], v[82:85]
	v_mfma_f32_16x16x32_bf16 v[70:73], v[166:169], v[206:209], v[70:73]
	v_mfma_f32_16x16x32_bf16 v[66:69], v[174:177], v[206:209], v[66:69]
	v_mfma_f32_16x16x32_bf16 v[118:121], v[170:173], v[186:189], v[118:121]
	v_mfma_f32_16x16x32_bf16 v[114:117], v[178:181], v[186:189], v[114:117]
	v_mfma_f32_16x16x32_bf16 v[102:105], v[170:173], v[194:197], v[102:105]
	v_mfma_f32_16x16x32_bf16 v[98:101], v[178:181], v[194:197], v[98:101]
	v_mfma_f32_16x16x32_bf16 v[86:89], v[170:173], v[202:205], v[86:89]
	v_mfma_f32_16x16x32_bf16 v[82:85], v[178:181], v[202:205], v[82:85]
	v_mfma_f32_16x16x32_bf16 v[70:73], v[170:173], v[210:213], v[70:73]
	v_mfma_f32_16x16x32_bf16 v[66:69], v[178:181], v[210:213], v[66:69]
	s_setprio 2
	s_barrier
; #define PG8_STAGE(bufoff, gbase, voff) do { _Pragma("unroll") for (int _i = 0; _i < 2; ++_i) \
;         __builtin_amdgcn_global_load_lds((const unsigned*)((const char*)(gbase) + (voff)[_i]), (LAS unsigned*)(lds + (bufoff) + ldsw + _i * 8192), 16, 0, 0); } while (0)
; #define PG8_LDA(dst, b, h) do { _Pragma("unroll") for (int m = 0; m < 4; ++m) _Pragma("unroll") for (int k = 0; k < 2; ++k) dst[m][k] = *(const LAS bf16x8*)(lds + PG8_SA(b, h) + aoff + m * 2048 + k * 1024); } while (0)
; #define PG8_LDB(dst, b, h) do { _Pragma("unroll") for (int n = 0; n < 2; ++n) _Pragma("unroll") for (int k = 0; k < 2; ++k) dst[n][k] = *(const LAS bf16x8*)(lds + PG8_SB(b, h) + boff + n * 2048 + k * 1024); } while (0)
; #define PG8_WAIT_V(n) asm volatile("s_waitcnt vmcnt(" #n ")" ::: "memory")
; #define PG8_WAIT_L(n) asm volatile("s_waitcnt lgkmcnt(" #n ")" ::: "memory")
; template <class Epi>
; __device__ __forceinline__ void gemm_phase(LAS unsigned char* lds, const Gemm g, int G, int c, const Epi& E) {
;     ...
;         for (int t = 0; t < nt; t += 2) {
;             const bool last = (t == nt - 2);
;             const char* a1 = cA + (size_t)(t + 1) * kstep;
;             const char* a2 = last ? nA : cA + (size_t)(t + 2) * kstep; const char* b2 = last ? nB : cB + (size_t)(t + 2) * kstep;
;             const char* a3 = a2 + kstep; const char* b3 = b2 + kstep;
;             PG8_LDB(B0, 0, 0); PG8_LDB(B1, 0, 1); PG8_SCHED; PG8_LDA(At, 0, 0); PG8_STAGE(PG8_SA(1, 1), a1 + hstepA, voffA);
;             PG8_WAIT_V(8); PG8_WAIT_L(0); PG8_BAR; PG8_MMA(0, 0, At, B0); PG8_MMA(0, 1, At, B1); PG8_BAR; PG8_SCHED;
;             PG8_LDA(At, 0, 1); PG8_STAGE(PG8_SB(0, 0), b2, voffB); PG8_STAGE(PG8_SB(0, 1), b2 + hstepB, voffB); PG8_STAGE(PG8_SA(0, 0), a2, voffA);
;             PG8_WAIT_V(8); PG8_WAIT_L(0); PG8_BAR; PG8_MMA(1, 0, At, B0); PG8_MMA(1, 1, At, B1); PG8_BAR; PG8_SCHED;
;             PG8_LDB(B0, 1, 0); PG8_LDB(B1, 1, 1); PG8_SCHED; PG8_LDA(At, 1, 0); PG8_STAGE(PG8_SA(0, 1), a2 + hstepA, voffA);
;             PG8_WAIT_V(8); PG8_WAIT_L(0); PG8_BAR; PG8_MMA(0, 0, At, B0); PG8_MMA(0, 1, At, B1); PG8_BAR; PG8_SCHED;
;             PG8_LDA(At, 1, 1); PG8_STAGE(PG8_SB(1, 0), b3, voffB); PG8_STAGE(PG8_SB(1, 1), b3 + hstepB, voffB); PG8_STAGE(PG8_SA(1, 0), a3, voffA);
;             PG8_WAIT_V(8); PG8_WAIT_L(0); PG8_BAR; PG8_MMA(1, 0, At, B0); PG8_MMA(1, 1, At, B1); PG8_BAR; PG8_SCHED;
	s_mov_b32 m0, s96
	v_lshl_add_u64 v[214:215], v[214:215], 0, s[22:23]
	ds_read_b128 v[182:185], v162 offset:49152
	ds_read_b128 v[186:189], v162 offset:50176
	ds_read_b128 v[190:193], v162 offset:51200
	ds_read_b128 v[194:197], v162 offset:52224
	ds_read_b128 v[198:201], v162 offset:53248
	ds_read_b128 v[202:205], v162 offset:54272
	ds_read_b128 v[206:209], v162 offset:55296
	ds_read_b128 v[210:213], v162 offset:56320
	global_load_lds_dwordx4 v[214:215], off
	v_lshl_add_u64 v[214:215], v[216:217], 0, s[22:23]
	s_mov_b32 m0, s94
	s_nop 0
	global_load_lds_dwordx4 v[214:215], off
	v_lshl_add_u64 v[214:215], s[10:11], 0, v[132:133]
	s_mov_b32 m0, s95
	s_nop 0
	global_load_lds_dwordx4 v[214:215], off
	v_lshl_add_u64 v[214:215], s[10:11], 0, v[136:137]
	s_mov_b32 m0, s93
	s_nop 0
	global_load_lds_dwordx4 v[214:215], off
	v_lshl_add_u64 v[214:215], v[218:219], 0, s[22:23]
	s_mov_b32 m0, s80
	s_nop 0
	global_load_lds_dwordx4 v[214:215], off
	v_lshl_add_u64 v[214:215], v[220:221], 0, s[22:23]
	s_mov_b32 m0, s81
	s_nop 0
	global_load_lds_dwordx4 v[214:215], off
	s_waitcnt vmcnt(8)
	s_waitcnt lgkmcnt(0)
	s_barrier
	s_setprio 0
	v_mfma_f32_16x16x32_bf16 v[62:65], v[142:145], v[182:185], v[62:65]
	v_mfma_f32_16x16x32_bf16 v[58:61], v[150:153], v[182:185], v[58:61]
	v_mfma_f32_16x16x32_bf16 v[46:49], v[142:145], v[190:193], v[46:49]
	v_mfma_f32_16x16x32_bf16 v[42:45], v[150:153], v[190:193], v[42:45]
	v_mfma_f32_16x16x32_bf16 v[30:33], v[142:145], v[198:201], v[30:33]
	v_mfma_f32_16x16x32_bf16 v[26:29], v[150:153], v[198:201], v[26:29]
	v_mfma_f32_16x16x32_bf16 v[14:17], v[142:145], v[206:209], v[14:17]
	v_mfma_f32_16x16x32_bf16 v[10:13], v[150:153], v[206:209], v[10:13]
	v_mfma_f32_16x16x32_bf16 v[62:65], v[146:149], v[186:189], v[62:65]
	v_mfma_f32_16x16x32_bf16 v[58:61], v[154:157], v[186:189], v[58:61]
	v_mfma_f32_16x16x32_bf16 v[46:49], v[146:149], v[194:197], v[46:49]
	v_mfma_f32_16x16x32_bf16 v[42:45], v[154:157], v[194:197], v[42:45]
	v_mfma_f32_16x16x32_bf16 v[30:33], v[146:149], v[202:205], v[30:33]
	v_mfma_f32_16x16x32_bf16 v[26:29], v[154:157], v[202:205], v[26:29]
	v_mfma_f32_16x16x32_bf16 v[14:17], v[146:149], v[210:213], v[14:17]
	v_mfma_f32_16x16x32_bf16 v[10:13], v[154:157], v[210:213], v[10:13]
	s_setprio 2
	s_setprio 0
	v_mfma_f32_16x16x32_bf16 v[54:57], v[166:169], v[182:185], v[54:57]
	v_mfma_f32_16x16x32_bf16 v[50:53], v[174:177], v[182:185], v[50:53]
	v_mfma_f32_16x16x32_bf16 v[38:41], v[166:169], v[190:193], v[38:41]
	v_mfma_f32_16x16x32_bf16 v[34:37], v[174:177], v[190:193], v[34:37]
	v_mfma_f32_16x16x32_bf16 v[22:25], v[166:169], v[198:201], v[22:25]
	v_mfma_f32_16x16x32_bf16 v[18:21], v[174:177], v[198:201], v[18:21]
	v_mfma_f32_16x16x32_bf16 v[6:9], v[166:169], v[206:209], v[6:9]
	v_mfma_f32_16x16x32_bf16 v[2:5], v[174:177], v[206:209], v[2:5]
	v_mfma_f32_16x16x32_bf16 v[54:57], v[170:173], v[186:189], v[54:57]
	v_mfma_f32_16x16x32_bf16 v[50:53], v[178:181], v[186:189], v[50:53]
	v_mfma_f32_16x16x32_bf16 v[38:41], v[170:173], v[194:197], v[38:41]
	v_mfma_f32_16x16x32_bf16 v[34:37], v[178:181], v[194:197], v[34:37]
	v_mfma_f32_16x16x32_bf16 v[22:25], v[170:173], v[202:205], v[22:25]
	v_mfma_f32_16x16x32_bf16 v[18:21], v[178:181], v[202:205], v[18:21]
	v_mfma_f32_16x16x32_bf16 v[6:9], v[170:173], v[210:213], v[6:9]
	v_mfma_f32_16x16x32_bf16 v[2:5], v[178:181], v[210:213], v[2:5]
	s_setprio 2
	s_barrier
	s_movk_i32 s44, 0x100
	s_andn2_b64 vcc, exec, s[4:5]
	s_mov_b64 s[10:11], -1
	s_mov_b64 s[4:5], 0
	s_cbranch_vccz .LBB0_1451
.LBB0_1451:
	s_add_u32 s33, s8, s44
	s_addc_u32 s45, s9, 0
	s_add_u32 s48, s33, 0x100
	s_addc_u32 s49, s45, 0
	s_and_b64 s[46:47], s[10:11], exec
	s_cselect_b32 s47, s41, s49
	s_cselect_b32 s46, s40, s48
	s_add_u32 s44, s6, s44
	s_addc_u32 s48, s7, 0
	s_add_u32 s44, s44, 0x100
	s_addc_u32 s48, s48, 0
	s_and_b64 s[10:11], s[10:11], exec
	s_cselect_b32 s49, s43, s48
	s_cselect_b32 s48, s42, s44
	s_add_u32 s54, s33, 0xb0080
	ds_read_b128 v[142:145], v160
	ds_read_b128 v[146:149], v160 offset:1024
	ds_read_b128 v[150:153], v160 offset:2048
	ds_read_b128 v[154:157], v160 offset:3072
	ds_read_b128 v[166:169], v161
	ds_read_b128 v[170:173], v161 offset:1024
	ds_read_b128 v[174:177], v161 offset:2048
	ds_read_b128 v[178:181], v161 offset:3072
	s_addc_u32 s55, s45, 0
	s_add_i32 s65, s82, s66
	s_add_i32 m0, s69, 0xc000
	s_add_i32 s74, s69, 0xe000
	s_add_i32 s62, s65, 0x2000
	s_add_u32 s52, s48, 0xb0000
	s_addc_u32 s53, s49, 0
	s_add_i32 s64, s83, s66
	s_add_i32 s63, s64, 0x2000
	s_add_i32 s97, 0, 0x18000
	s_add_i32 s33, 0, 0x1c000
	s_add_u32 s44, s46, 0xb0000
	s_addc_u32 s45, s47, 0
	s_add_i32 s96, s97, s66
	s_add_i32 s94, s96, 0x2000
	s_add_u32 s10, s48, 0xb0080
	s_addc_u32 s11, s49, 0
	s_add_i32 s95, s33, s66
	s_add_i32 s93, s95, 0x2000
	v_lshl_add_u64 v[214:215], s[54:55], 0, v[130:131]
	ds_read_b128 v[182:185], v162
	ds_read_b128 v[186:189], v162 offset:1024
	ds_read_b128 v[190:193], v162 offset:2048
	ds_read_b128 v[194:197], v162 offset:3072
	ds_read_b128 v[198:201], v162 offset:4096
	ds_read_b128 v[202:205], v162 offset:5120
	ds_read_b128 v[206:209], v162 offset:6144
	ds_read_b128 v[210:213], v162 offset:7168
	global_load_lds_dwordx4 v[214:215], off
	v_lshl_add_u64 v[214:215], s[54:55], 0, v[134:135]
	s_mov_b32 m0, s74
	s_nop 0
	global_load_lds_dwordx4 v[214:215], off
	s_waitcnt vmcnt(8)
	s_waitcnt lgkmcnt(0)
	s_barrier
; #define PG8_STAGE(bufoff, gbase, voff) do { _Pragma("unroll") for (int _i = 0; _i < 2; ++_i) \
;         __builtin_amdgcn_global_load_lds((const unsigned*)((const char*)(gbase) + (voff)[_i]), (LAS unsigned*)(lds + (bufoff) + ldsw + _i * 8192), 16, 0, 0); } while (0)
; #define PG8_LDA(dst, b, h) do { _Pragma("unroll") for (int m = 0; m < 4; ++m) _Pragma("unroll") for (int k = 0; k < 2; ++k) dst[m][k] = *(const LAS bf16x8*)(lds + PG8_SA(b, h) + aoff + m * 2048 + k * 1024); } while (0)
; #define PG8_LDB(dst, b, h) do { _Pragma("unroll") for (int n = 0; n < 2; ++n) _Pragma("unroll") for (int k = 0; k < 2; ++k) dst[n][k] = *(const LAS bf16x8*)(lds + PG8_SB(b, h) + boff + n * 2048 + k * 1024); } while (0)
; #define PG8_MMA(ai, bj, At, Bt) do { __builtin_amdgcn_s_setprio(1); _Pragma("unroll") for (int m = 0; m < 4; ++m) _Pragma("unroll") for (int n = 0; n < 2; ++n) _Pragma("unroll") for (int k = 0; k < 2; ++k) \
;         acc[ai][bj][m][n] = __builtin_amdgcn_mfma_f32_16x16x32_bf16(Bt[n][k], At[m][k], acc[ai][bj][m][n], 0, 0, 0); __builtin_amdgcn_s_setprio(0); } while (0)
; #define PG8_WAIT_V(n) asm volatile("s_waitcnt vmcnt(" #n ")" ::: "memory")
; #define PG8_WAIT_L(n) asm volatile("s_waitcnt lgkmcnt(" #n ")" ::: "memory")
; #define PG8_BAR __builtin_amdgcn_s_barrier()
; #define PG8_SCHED __builtin_amdgcn_sched_barrier(0)
; template <class Epi>
; __device__ __forceinline__ void gemm_phase(LAS unsigned char* lds, const Gemm g, int G, int c, const Epi& E) {
;     ...
;             PG8_LDB(B0, 0, 0); PG8_LDB(B1, 0, 1); PG8_SCHED; PG8_LDA(At, 0, 0); PG8_STAGE(PG8_SA(1, 1), a1 + hstepA, voffA);
;             PG8_WAIT_V(8); PG8_WAIT_L(0); PG8_BAR; PG8_MMA(0, 0, At, B0); PG8_MMA(0, 1, At, B1); PG8_BAR; PG8_SCHED;
;             PG8_LDA(At, 0, 1); PG8_STAGE(PG8_SB(0, 0), b2, voffB); PG8_STAGE(PG8_SB(0, 1), b2 + hstepB, voffB); PG8_STAGE(PG8_SA(0, 0), a2, voffA);
;             PG8_WAIT_V(8); PG8_WAIT_L(0); PG8_BAR; PG8_MMA(1, 0, At, B0); PG8_MMA(1, 1, At, B1); PG8_BAR; PG8_SCHED;
	s_setprio 0
	v_mfma_f32_16x16x32_bf16 v[126:129], v[142:145], v[182:185], v[126:129]
	v_mfma_f32_16x16x32_bf16 v[122:125], v[150:153], v[182:185], v[122:125]
	v_mfma_f32_16x16x32_bf16 v[110:113], v[142:145], v[190:193], v[110:113]
	v_mfma_f32_16x16x32_bf16 v[106:109], v[150:153], v[190:193], v[106:109]
	v_mfma_f32_16x16x32_bf16 v[94:97], v[142:145], v[198:201], v[94:97]
	v_mfma_f32_16x16x32_bf16 v[90:93], v[150:153], v[198:201], v[90:93]
	v_mfma_f32_16x16x32_bf16 v[78:81], v[142:145], v[206:209], v[78:81]
	v_mfma_f32_16x16x32_bf16 v[74:77], v[150:153], v[206:209], v[74:77]
	v_mfma_f32_16x16x32_bf16 v[126:129], v[146:149], v[186:189], v[126:129]
	v_mfma_f32_16x16x32_bf16 v[122:125], v[154:157], v[186:189], v[122:125]
	v_mfma_f32_16x16x32_bf16 v[110:113], v[146:149], v[194:197], v[110:113]
	v_mfma_f32_16x16x32_bf16 v[106:109], v[154:157], v[194:197], v[106:109]
	v_mfma_f32_16x16x32_bf16 v[94:97], v[146:149], v[202:205], v[94:97]
	v_mfma_f32_16x16x32_bf16 v[90:93], v[154:157], v[202:205], v[90:93]
	v_mfma_f32_16x16x32_bf16 v[78:81], v[146:149], v[210:213], v[78:81]
	v_mfma_f32_16x16x32_bf16 v[74:77], v[154:157], v[210:213], v[74:77]
	s_setprio 2
	s_setprio 0
	v_mfma_f32_16x16x32_bf16 v[118:121], v[166:169], v[182:185], v[118:121]
	v_mfma_f32_16x16x32_bf16 v[114:117], v[174:177], v[182:185], v[114:117]
	v_mfma_f32_16x16x32_bf16 v[102:105], v[166:169], v[190:193], v[102:105]
	v_mfma_f32_16x16x32_bf16 v[98:101], v[174:177], v[190:193], v[98:101]
	v_mfma_f32_16x16x32_bf16 v[86:89], v[166:169], v[198:201], v[86:89]
	v_mfma_f32_16x16x32_bf16 v[82:85], v[174:177], v[198:201], v[82:85]
	v_mfma_f32_16x16x32_bf16 v[70:73], v[166:169], v[206:209], v[70:73]
	v_mfma_f32_16x16x32_bf16 v[66:69], v[174:177], v[206:209], v[66:69]
	v_mfma_f32_16x16x32_bf16 v[118:121], v[170:173], v[186:189], v[118:121]
	v_mfma_f32_16x16x32_bf16 v[114:117], v[178:181], v[186:189], v[114:117]
	v_mfma_f32_16x16x32_bf16 v[102:105], v[170:173], v[194:197], v[102:105]
	v_mfma_f32_16x16x32_bf16 v[98:101], v[178:181], v[194:197], v[98:101]
	v_mfma_f32_16x16x32_bf16 v[86:89], v[170:173], v[202:205], v[86:89]
	v_mfma_f32_16x16x32_bf16 v[82:85], v[178:181], v[202:205], v[82:85]
	v_mfma_f32_16x16x32_bf16 v[70:73], v[170:173], v[210:213], v[70:73]
	v_mfma_f32_16x16x32_bf16 v[66:69], v[178:181], v[210:213], v[66:69]
	s_setprio 2
	s_barrier
	s_mov_b32 m0, s65
	v_lshl_add_u64 v[214:215], s[48:49], 0, v[132:133]
	ds_read_b128 v[182:185], v162 offset:16384
	ds_read_b128 v[186:189], v162 offset:17408
	ds_read_b128 v[190:193], v162 offset:18432
	ds_read_b128 v[194:197], v162 offset:19456
	ds_read_b128 v[198:201], v162 offset:20480
	ds_read_b128 v[202:205], v162 offset:21504
	ds_read_b128 v[206:209], v162 offset:22528
	ds_read_b128 v[210:213], v162 offset:23552
	global_load_lds_dwordx4 v[214:215], off
	v_lshl_add_u64 v[216:217], s[48:49], 0, v[136:137]
	s_mov_b32 m0, s62
	v_lshl_add_u64 v[218:219], s[52:53], 0, v[132:133]
	global_load_lds_dwordx4 v[216:217], off
	s_mov_b32 m0, s64
	v_lshl_add_u64 v[220:221], s[46:47], 0, v[134:135]
	global_load_lds_dwordx4 v[218:219], off
	v_lshl_add_u64 v[218:219], s[52:53], 0, v[136:137]
	s_mov_b32 m0, s63
	s_nop 0
	global_load_lds_dwordx4 v[218:219], off
	v_lshl_add_u64 v[218:219], s[46:47], 0, v[130:131]
	s_mov_b32 m0, s69
	s_nop 0
	global_load_lds_dwordx4 v[218:219], off
	s_mov_b32 m0, s70
	s_nop 0
	global_load_lds_dwordx4 v[220:221], off
	s_waitcnt vmcnt(8)
	s_waitcnt lgkmcnt(0)
	s_barrier
	s_setprio 0
	v_mfma_f32_16x16x32_bf16 v[62:65], v[142:145], v[182:185], v[62:65]
	v_mfma_f32_16x16x32_bf16 v[58:61], v[150:153], v[182:185], v[58:61]
	v_mfma_f32_16x16x32_bf16 v[46:49], v[142:145], v[190:193], v[46:49]
	v_mfma_f32_16x16x32_bf16 v[42:45], v[150:153], v[190:193], v[42:45]
	v_mfma_f32_16x16x32_bf16 v[30:33], v[142:145], v[198:201], v[30:33]
	v_mfma_f32_16x16x32_bf16 v[26:29], v[150:153], v[198:201], v[26:29]
	v_mfma_f32_16x16x32_bf16 v[14:17], v[142:145], v[206:209], v[14:17]
	v_mfma_f32_16x16x32_bf16 v[10:13], v[150:153], v[206:209], v[10:13]
	v_mfma_f32_16x16x32_bf16 v[62:65], v[146:149], v[186:189], v[62:65]
	v_mfma_f32_16x16x32_bf16 v[58:61], v[154:157], v[186:189], v[58:61]
	v_mfma_f32_16x16x32_bf16 v[46:49], v[146:149], v[194:197], v[46:49]
	v_mfma_f32_16x16x32_bf16 v[42:45], v[154:157], v[194:197], v[42:45]
	v_mfma_f32_16x16x32_bf16 v[30:33], v[146:149], v[202:205], v[30:33]
	v_mfma_f32_16x16x32_bf16 v[26:29], v[154:157], v[202:205], v[26:29]
	v_mfma_f32_16x16x32_bf16 v[14:17], v[146:149], v[210:213], v[14:17]
	v_mfma_f32_16x16x32_bf16 v[10:13], v[154:157], v[210:213], v[10:13]
	s_setprio 2
	s_setprio 0
	v_mfma_f32_16x16x32_bf16 v[54:57], v[166:169], v[182:185], v[54:57]
	v_mfma_f32_16x16x32_bf16 v[50:53], v[174:177], v[182:185], v[50:53]
	v_mfma_f32_16x16x32_bf16 v[38:41], v[166:169], v[190:193], v[38:41]
	v_mfma_f32_16x16x32_bf16 v[34:37], v[174:177], v[190:193], v[34:37]
	v_mfma_f32_16x16x32_bf16 v[22:25], v[166:169], v[198:201], v[22:25]
	v_mfma_f32_16x16x32_bf16 v[18:21], v[174:177], v[198:201], v[18:21]
	v_mfma_f32_16x16x32_bf16 v[6:9], v[166:169], v[206:209], v[6:9]
	v_mfma_f32_16x16x32_bf16 v[2:5], v[174:177], v[206:209], v[2:5]
	v_mfma_f32_16x16x32_bf16 v[54:57], v[170:173], v[186:189], v[54:57]
	v_mfma_f32_16x16x32_bf16 v[50:53], v[178:181], v[186:189], v[50:53]
	v_mfma_f32_16x16x32_bf16 v[38:41], v[170:173], v[194:197], v[38:41]
	v_mfma_f32_16x16x32_bf16 v[34:37], v[178:181], v[194:197], v[34:37]
	v_mfma_f32_16x16x32_bf16 v[22:25], v[170:173], v[202:205], v[22:25]
	v_mfma_f32_16x16x32_bf16 v[18:21], v[178:181], v[202:205], v[18:21]
	v_mfma_f32_16x16x32_bf16 v[6:9], v[170:173], v[210:213], v[6:9]
	v_mfma_f32_16x16x32_bf16 v[2:5], v[178:181], v[210:213], v[2:5]
	s_setprio 2
	s_barrier
; #define PG8_STAGE(bufoff, gbase, voff) do { _Pragma("unroll") for (int _i = 0; _i < 2; ++_i) \
;         __builtin_amdgcn_global_load_lds((const unsigned*)((const char*)(gbase) + (voff)[_i]), (LAS unsigned*)(lds + (bufoff) + ldsw + _i * 8192), 16, 0, 0); } while (0)
; #define PG8_LDA(dst, b, h) do { _Pragma("unroll") for (int m = 0; m < 4; ++m) _Pragma("unroll") for (int k = 0; k < 2; ++k) dst[m][k] = *(const LAS bf16x8*)(lds + PG8_SA(b, h) + aoff + m * 2048 + k * 1024); } while (0)
; #define PG8_LDB(dst, b, h) do { _Pragma("unroll") for (int n = 0; n < 2; ++n) _Pragma("unroll") for (int k = 0; k < 2; ++k) dst[n][k] = *(const LAS bf16x8*)(lds + PG8_SB(b, h) + boff + n * 2048 + k * 1024); } while (0)
; #define PG8_MMA(ai, bj, At, Bt) do { __builtin_amdgcn_s_setprio(1); _Pragma("unroll") for (int m = 0; m < 4; ++m) _Pragma("unroll") for (int n = 0; n < 2; ++n) _Pragma("unroll") for (int k = 0; k < 2; ++k) \
;         acc[ai][bj][m][n] = __builtin_amdgcn_mfma_f32_16x16x32_bf16(Bt[n][k], At[m][k], acc[ai][bj][m][n], 0, 0, 0); __builtin_amdgcn_s_setprio(0); } while (0)
; #define PG8_WAIT_V(n) asm volatile("s_waitcnt vmcnt(" #n ")" ::: "memory")
; #define PG8_WAIT_L(n) asm volatile("s_waitcnt lgkmcnt(" #n ")" ::: "memory")
; #define PG8_BAR __builtin_amdgcn_s_barrier()
; #define PG8_SCHED __builtin_amdgcn_sched_barrier(0)
; template <class Epi>
; __device__ __forceinline__ void gemm_phase(LAS unsigned char* lds, const Gemm g, int G, int c, const Epi& E) {
;     ...
;             PG8_LDB(B0, 1, 0); PG8_LDB(B1, 1, 1); PG8_SCHED; PG8_LDA(At, 1, 0); PG8_STAGE(PG8_SA(0, 1), a2 + hstepA, voffA);
;             PG8_WAIT_V(8); PG8_WAIT_L(0); PG8_BAR; PG8_MMA(0, 0, At, B0); PG8_MMA(0, 1, At, B1); PG8_BAR; PG8_SCHED;
;             PG8_LDA(At, 1, 1); PG8_STAGE(PG8_SB(1, 0), b3, voffB); PG8_STAGE(PG8_SB(1, 1), b3 + hstepB, voffB); PG8_STAGE(PG8_SA(1, 0), a3, voffA);
;             PG8_WAIT_V(8); PG8_WAIT_L(0); PG8_BAR; PG8_MMA(1, 0, At, B0); PG8_MMA(1, 1, At, B1); PG8_BAR; PG8_SCHED;
;         }
;         if (wr == 0) PG8_BAR;
	v_add_u32_e32 v154, s97, v159
	v_add_u32_e32 v178, s33, v159
	ds_read_b128 v[142:145], v154
	ds_read_b128 v[146:149], v154 offset:1024
	ds_read_b128 v[150:153], v154 offset:2048
	ds_read_b128 v[154:157], v154 offset:3072
	ds_read_b128 v[166:169], v178
	ds_read_b128 v[170:173], v178 offset:1024
	ds_read_b128 v[174:177], v178 offset:2048
	ds_read_b128 v[178:181], v178 offset:3072
	s_mov_b32 m0, s71
	v_lshl_add_u64 v[222:223], s[44:45], 0, v[130:131]
	ds_read_b128 v[182:185], v162 offset:32768
	ds_read_b128 v[186:189], v162 offset:33792
	ds_read_b128 v[190:193], v162 offset:34816
	ds_read_b128 v[194:197], v162 offset:35840
	ds_read_b128 v[198:201], v162 offset:36864
	ds_read_b128 v[202:205], v162 offset:37888
	ds_read_b128 v[206:209], v162 offset:38912
	ds_read_b128 v[210:213], v162 offset:39936
	global_load_lds_dwordx4 v[222:223], off
	v_lshl_add_u64 v[222:223], s[44:45], 0, v[134:135]
	s_mov_b32 m0, s72
	s_nop 0
	global_load_lds_dwordx4 v[222:223], off
	s_waitcnt vmcnt(8)
	s_waitcnt lgkmcnt(0)
	s_barrier
	s_setprio 0
	v_mfma_f32_16x16x32_bf16 v[126:129], v[142:145], v[182:185], v[126:129]
	v_mfma_f32_16x16x32_bf16 v[122:125], v[150:153], v[182:185], v[122:125]
	v_mfma_f32_16x16x32_bf16 v[110:113], v[142:145], v[190:193], v[110:113]
	v_mfma_f32_16x16x32_bf16 v[106:109], v[150:153], v[190:193], v[106:109]
	v_mfma_f32_16x16x32_bf16 v[94:97], v[142:145], v[198:201], v[94:97]
	v_mfma_f32_16x16x32_bf16 v[90:93], v[150:153], v[198:201], v[90:93]
	v_mfma_f32_16x16x32_bf16 v[78:81], v[142:145], v[206:209], v[78:81]
	v_mfma_f32_16x16x32_bf16 v[74:77], v[150:153], v[206:209], v[74:77]
	v_mfma_f32_16x16x32_bf16 v[126:129], v[146:149], v[186:189], v[126:129]
	v_mfma_f32_16x16x32_bf16 v[122:125], v[154:157], v[186:189], v[122:125]
	v_mfma_f32_16x16x32_bf16 v[110:113], v[146:149], v[194:197], v[110:113]
	v_mfma_f32_16x16x32_bf16 v[106:109], v[154:157], v[194:197], v[106:109]
	v_mfma_f32_16x16x32_bf16 v[94:97], v[146:149], v[202:205], v[94:97]
	v_mfma_f32_16x16x32_bf16 v[90:93], v[154:157], v[202:205], v[90:93]
	v_mfma_f32_16x16x32_bf16 v[78:81], v[146:149], v[210:213], v[78:81]
	v_mfma_f32_16x16x32_bf16 v[74:77], v[154:157], v[210:213], v[74:77]
	s_setprio 2
	s_setprio 0
	v_mfma_f32_16x16x32_bf16 v[118:121], v[166:169], v[182:185], v[118:121]
	v_mfma_f32_16x16x32_bf16 v[114:117], v[174:177], v[182:185], v[114:117]
	v_mfma_f32_16x16x32_bf16 v[102:105], v[166:169], v[190:193], v[102:105]
	v_mfma_f32_16x16x32_bf16 v[98:101], v[174:177], v[190:193], v[98:101]
	v_mfma_f32_16x16x32_bf16 v[86:89], v[166:169], v[198:201], v[86:89]
	v_mfma_f32_16x16x32_bf16 v[82:85], v[174:177], v[198:201], v[82:85]
	v_mfma_f32_16x16x32_bf16 v[70:73], v[166:169], v[206:209], v[70:73]
	v_mfma_f32_16x16x32_bf16 v[66:69], v[174:177], v[206:209], v[66:69]
	v_mfma_f32_16x16x32_bf16 v[118:121], v[170:173], v[186:189], v[118:121]
	v_mfma_f32_16x16x32_bf16 v[114:117], v[178:181], v[186:189], v[114:117]
	v_mfma_f32_16x16x32_bf16 v[102:105], v[170:173], v[194:197], v[102:105]
	v_mfma_f32_16x16x32_bf16 v[98:101], v[178:181], v[194:197], v[98:101]
	v_mfma_f32_16x16x32_bf16 v[86:89], v[170:173], v[202:205], v[86:89]
	v_mfma_f32_16x16x32_bf16 v[82:85], v[178:181], v[202:205], v[82:85]
	v_mfma_f32_16x16x32_bf16 v[70:73], v[170:173], v[210:213], v[70:73]
	v_mfma_f32_16x16x32_bf16 v[66:69], v[178:181], v[210:213], v[66:69]
	s_setprio 2
	s_barrier
	s_mov_b32 m0, s96
	v_lshl_add_u64 v[214:215], v[214:215], 0, s[22:23]
	ds_read_b128 v[182:185], v162 offset:49152
	ds_read_b128 v[186:189], v162 offset:50176
	ds_read_b128 v[190:193], v162 offset:51200
	ds_read_b128 v[194:197], v162 offset:52224
	ds_read_b128 v[198:201], v162 offset:53248
	ds_read_b128 v[202:205], v162 offset:54272
	ds_read_b128 v[206:209], v162 offset:55296
	ds_read_b128 v[210:213], v162 offset:56320
	global_load_lds_dwordx4 v[214:215], off
	v_lshl_add_u64 v[214:215], v[216:217], 0, s[22:23]
	s_mov_b32 m0, s94
	s_nop 0
	global_load_lds_dwordx4 v[214:215], off
	v_lshl_add_u64 v[214:215], s[10:11], 0, v[132:133]
	s_mov_b32 m0, s95
	s_nop 0
	global_load_lds_dwordx4 v[214:215], off
	v_lshl_add_u64 v[214:215], s[10:11], 0, v[136:137]
	s_mov_b32 m0, s93
	s_nop 0
	global_load_lds_dwordx4 v[214:215], off
	v_lshl_add_u64 v[214:215], v[218:219], 0, s[22:23]
	s_mov_b32 m0, s80
	s_nop 0
	global_load_lds_dwordx4 v[214:215], off
	v_lshl_add_u64 v[214:215], v[220:221], 0, s[22:23]
	s_mov_b32 m0, s81
	s_nop 0
	global_load_lds_dwordx4 v[214:215], off
	s_waitcnt vmcnt(8)
	s_waitcnt lgkmcnt(0)
	s_barrier
	s_setprio 0
	v_mfma_f32_16x16x32_bf16 v[62:65], v[142:145], v[182:185], v[62:65]
	v_mfma_f32_16x16x32_bf16 v[58:61], v[150:153], v[182:185], v[58:61]
	v_mfma_f32_16x16x32_bf16 v[46:49], v[142:145], v[190:193], v[46:49]
	v_mfma_f32_16x16x32_bf16 v[42:45], v[150:153], v[190:193], v[42:45]
	v_mfma_f32_16x16x32_bf16 v[30:33], v[142:145], v[198:201], v[30:33]
	v_mfma_f32_16x16x32_bf16 v[26:29], v[150:153], v[198:201], v[26:29]
	v_mfma_f32_16x16x32_bf16 v[14:17], v[142:145], v[206:209], v[14:17]
	v_mfma_f32_16x16x32_bf16 v[10:13], v[150:153], v[206:209], v[10:13]
	v_mfma_f32_16x16x32_bf16 v[62:65], v[146:149], v[186:189], v[62:65]
	v_mfma_f32_16x16x32_bf16 v[58:61], v[154:157], v[186:189], v[58:61]
	v_mfma_f32_16x16x32_bf16 v[46:49], v[146:149], v[194:197], v[46:49]
	v_mfma_f32_16x16x32_bf16 v[42:45], v[154:157], v[194:197], v[42:45]
	v_mfma_f32_16x16x32_bf16 v[30:33], v[146:149], v[202:205], v[30:33]
	v_mfma_f32_16x16x32_bf16 v[26:29], v[154:157], v[202:205], v[26:29]
	v_mfma_f32_16x16x32_bf16 v[14:17], v[146:149], v[210:213], v[14:17]
	v_mfma_f32_16x16x32_bf16 v[10:13], v[154:157], v[210:213], v[10:13]
	s_setprio 2
	s_setprio 0
	v_mfma_f32_16x16x32_bf16 v[54:57], v[166:169], v[182:185], v[54:57]
	v_mfma_f32_16x16x32_bf16 v[50:53], v[174:177], v[182:185], v[50:53]
	v_mfma_f32_16x16x32_bf16 v[38:41], v[166:169], v[190:193], v[38:41]
	v_mfma_f32_16x16x32_bf16 v[34:37], v[174:177], v[190:193], v[34:37]
	v_mfma_f32_16x16x32_bf16 v[22:25], v[166:169], v[198:201], v[22:25]
	v_mfma_f32_16x16x32_bf16 v[18:21], v[174:177], v[198:201], v[18:21]
	v_mfma_f32_16x16x32_bf16 v[6:9], v[166:169], v[206:209], v[6:9]
	v_mfma_f32_16x16x32_bf16 v[2:5], v[174:177], v[206:209], v[2:5]
	v_mfma_f32_16x16x32_bf16 v[54:57], v[170:173], v[186:189], v[54:57]
	v_mfma_f32_16x16x32_bf16 v[50:53], v[178:181], v[186:189], v[50:53]
	v_mfma_f32_16x16x32_bf16 v[38:41], v[170:173], v[194:197], v[38:41]
	v_mfma_f32_16x16x32_bf16 v[34:37], v[178:181], v[194:197], v[34:37]
	v_mfma_f32_16x16x32_bf16 v[22:25], v[170:173], v[202:205], v[22:25]
	v_mfma_f32_16x16x32_bf16 v[18:21], v[178:181], v[202:205], v[18:21]
	v_mfma_f32_16x16x32_bf16 v[6:9], v[170:173], v[210:213], v[6:9]
	v_mfma_f32_16x16x32_bf16 v[2:5], v[178:181], v[210:213], v[2:5]
	s_setprio 2
	s_barrier
	s_movk_i32 s44, 0x100
	s_andn2_b64 vcc, exec, s[4:5]
	s_mov_b64 s[10:11], -1
	s_mov_b64 s[4:5], 0
	s_cbranch_vccz .LBB0_1451
	s_and_b64 vcc, exec, s[24:25]
	s_cbranch_vccz .LBB0_1454
	s_barrier

; #define PG8_STAGE(bufoff, gbase, voff) do { _Pragma("unroll") for (int _i = 0; _i < 2; ++_i) \
;         __builtin_amdgcn_global_load_lds((const unsigned*)((const char*)(gbase) + (voff)[_i]), (LAS unsigned*)(lds + (bufoff) + ldsw + _i * 8192), 16, 0, 0); } while (0)
; #define PG8_LDA(dst, b, h) do { _Pragma("unroll") for (int m = 0; m < 4; ++m) _Pragma("unroll") for (int k = 0; k < 2; ++k) dst[m][k] = *(const LAS bf16x8*)(lds + PG8_SA(b, h) + aoff + m * 2048 + k * 1024); } while (0)
; #define PG8_LDB(dst, b, h) do { _Pragma("unroll") for (int n = 0; n < 2; ++n) _Pragma("unroll") for (int k = 0; k < 2; ++k) dst[n][k] = *(const LAS bf16x8*)(lds + PG8_SB(b, h) + boff + n * 2048 + k * 1024); } while (0)
; #define PG8_MMA(ai, bj, At, Bt) do { __builtin_amdgcn_s_setprio(1); _Pragma("unroll") for (int m = 0; m < 4; ++m) _Pragma("unroll") for (int n = 0; n < 2; ++n) _Pragma("unroll") for (int k = 0; k < 2; ++k) \
;         acc[ai][bj][m][n] = __builtin_amdgcn_mfma_f32_16x16x32_bf16(Bt[n][k], At[m][k], acc[ai][bj][m][n], 0, 0, 0); __builtin_amdgcn_s_setprio(0); } while (0)
; #define PG8_WAIT_V(n) asm volatile("s_waitcnt vmcnt(" #n ")" ::: "memory")
; template <class Epi>
; __device__ __forceinline__ void gemm_phase(LAS unsigned char* lds, const Gemm g, int G, int c, const Epi& E) {
;     ...
;     for (;;) {
;         const bool has_next = S.next(ui + 1, nxt);
;         const char* nA = has_next ? (const char*)(g.A + (size_t)nxt.pb * g.sA) + (size_t)nxt.pm * 2 * hstepA : cA;
;         const char* nB = has_next ? (const char*)(g.Bt + (size_t)nxt.pb * g.sB) + (size_t)nxt.pn * 2 * hstepB : cB;
; #pragma nounroll
;         for (int t = 0; t < nt; t += 2) {
;             const bool last = (t == nt - 2);
;             const char* a1 = cA + (size_t)(t + 1) * kstep;
;             const char* a2 = last ? nA : cA + (size_t)(t + 2) * kstep; const char* b2 = last ? nB : cB + (size_t)(t + 2) * kstep;
;             const char* a3 = a2 + kstep; const char* b3 = b2 + kstep;
;             PG8_LDB(B0, 0, 0); PG8_LDB(B1, 0, 1); PG8_SCHED; PG8_LDA(At, 0, 0); PG8_STAGE(PG8_SA(1, 1), a1 + hstepA, voffA);
;             PG8_WAIT_V(8); PG8_WAIT_L(0); PG8_BAR; PG8_MMA(0, 0, At, B0); PG8_MMA(0, 1, At, B1); PG8_BAR; PG8_SCHED;
;             PG8_LDA(At, 0, 1); PG8_STAGE(PG8_SB(0, 0), b2, voffB); PG8_STAGE(PG8_SB(0, 1), b2 + hstepB, voffB); PG8_STAGE(PG8_SA(0, 0), a2, voffA);
.LBB0_1536:
	s_mov_b32 s44, 0
	s_mov_b64 s[4:5], -1
	s_mov_b64 s[10:11], 0
	s_waitcnt lgkmcnt(0)
	s_waitcnt vmcnt(0)
	s_add_u32 s33, s8, s44
	s_addc_u32 s45, s9, 0
	s_add_u32 s48, s33, 0x100
	s_addc_u32 s49, s45, 0
	s_and_b64 s[46:47], s[10:11], exec
	s_cselect_b32 s47, s41, s49
	s_cselect_b32 s46, s40, s48
	s_add_u32 s44, s6, s44
	s_addc_u32 s48, s7, 0
	s_add_u32 s44, s44, 0x100
	s_addc_u32 s48, s48, 0
	s_and_b64 s[10:11], s[10:11], exec
	s_cselect_b32 s49, s43, s48
	s_cselect_b32 s48, s42, s44
	s_add_u32 s54, s33, 0xb0080
	ds_read_b128 v[130:133], v166
	ds_read_b128 v[134:137], v166 offset:1024
	ds_read_b128 v[150:153], v166 offset:2048
	ds_read_b128 v[154:157], v166 offset:3072
	ds_read_b128 v[158:161], v167
	ds_read_b128 v[172:175], v167 offset:1024
	ds_read_b128 v[176:179], v167 offset:2048
	ds_read_b128 v[180:183], v167 offset:3072
	s_addc_u32 s55, s45, 0
	s_add_i32 s63, s87, s70
	s_add_i32 m0, s73, 0xc000
	s_add_i32 s64, s73, 0xe000
	s_add_i32 s74, s63, 0x2000
	s_add_u32 s52, s48, 0xb0000
	s_addc_u32 s53, s49, 0
	s_add_i32 s62, s88, s70
	s_add_i32 s75, s62, 0x2000
	s_add_i32 s97, 0, 0x18000
	s_add_i32 s33, 0, 0x1c000
	s_add_u32 s44, s46, 0xb0000
	s_addc_u32 s45, s47, 0
	s_add_i32 s96, s97, s70
	s_add_i32 s94, s96, 0x2000
	s_add_u32 s10, s48, 0xb0080
	s_addc_u32 s11, s49, 0
	s_add_i32 s95, s33, s70
	s_add_i32 s93, s95, 0x2000
	v_lshl_add_u64 v[162:163], s[54:55], 0, v[138:139]
	ds_read_b128 v[184:187], v168
	ds_read_b128 v[188:191], v168 offset:1024
	ds_read_b128 v[192:195], v168 offset:2048
	ds_read_b128 v[196:199], v168 offset:3072
	ds_read_b128 v[200:203], v168 offset:4096
	ds_read_b128 v[204:207], v168 offset:5120
	ds_read_b128 v[208:211], v168 offset:6144
	ds_read_b128 v[212:215], v168 offset:7168
	global_load_lds_dwordx4 v[162:163], off
	v_lshl_add_u64 v[162:163], s[54:55], 0, v[142:143]
	s_mov_b32 m0, s64
	s_nop 0
	global_load_lds_dwordx4 v[162:163], off
	s_waitcnt vmcnt(8)
	s_waitcnt lgkmcnt(0)
	s_barrier
	s_setprio 0
	v_mfma_f32_16x16x32_bf16 v[126:129], v[130:133], v[184:187], 0
	v_mfma_f32_16x16x32_bf16 v[122:125], v[150:153], v[184:187], 0
	v_mfma_f32_16x16x32_bf16 v[110:113], v[130:133], v[192:195], 0
	v_mfma_f32_16x16x32_bf16 v[106:109], v[150:153], v[192:195], 0
	v_mfma_f32_16x16x32_bf16 v[94:97], v[130:133], v[200:203], 0
	v_mfma_f32_16x16x32_bf16 v[90:93], v[150:153], v[200:203], 0
	v_mfma_f32_16x16x32_bf16 v[78:81], v[130:133], v[208:211], 0
	v_mfma_f32_16x16x32_bf16 v[74:77], v[150:153], v[208:211], 0
	v_mfma_f32_16x16x32_bf16 v[126:129], v[134:137], v[188:191], v[126:129]
	v_mfma_f32_16x16x32_bf16 v[122:125], v[154:157], v[188:191], v[122:125]
	v_mfma_f32_16x16x32_bf16 v[110:113], v[134:137], v[196:199], v[110:113]
	v_mfma_f32_16x16x32_bf16 v[106:109], v[154:157], v[196:199], v[106:109]
	v_mfma_f32_16x16x32_bf16 v[94:97], v[134:137], v[204:207], v[94:97]
	v_mfma_f32_16x16x32_bf16 v[90:93], v[154:157], v[204:207], v[90:93]
	v_mfma_f32_16x16x32_bf16 v[78:81], v[134:137], v[212:215], v[78:81]
	v_mfma_f32_16x16x32_bf16 v[74:77], v[154:157], v[212:215], v[74:77]
	s_setprio 2
	s_setprio 0
	v_mfma_f32_16x16x32_bf16 v[118:121], v[158:161], v[184:187], 0
	v_mfma_f32_16x16x32_bf16 v[114:117], v[176:179], v[184:187], 0
	v_mfma_f32_16x16x32_bf16 v[102:105], v[158:161], v[192:195], 0
	v_mfma_f32_16x16x32_bf16 v[98:101], v[176:179], v[192:195], 0
	v_mfma_f32_16x16x32_bf16 v[86:89], v[158:161], v[200:203], 0
	v_mfma_f32_16x16x32_bf16 v[82:85], v[176:179], v[200:203], 0
	v_mfma_f32_16x16x32_bf16 v[70:73], v[158:161], v[208:211], 0
	v_mfma_f32_16x16x32_bf16 v[66:69], v[176:179], v[208:211], 0
	v_mfma_f32_16x16x32_bf16 v[118:121], v[172:175], v[188:191], v[118:121]
	v_mfma_f32_16x16x32_bf16 v[114:117], v[180:183], v[188:191], v[114:117]
	v_mfma_f32_16x16x32_bf16 v[102:105], v[172:175], v[196:199], v[102:105]
	v_mfma_f32_16x16x32_bf16 v[98:101], v[180:183], v[196:199], v[98:101]
	v_mfma_f32_16x16x32_bf16 v[86:89], v[172:175], v[204:207], v[86:89]
	v_mfma_f32_16x16x32_bf16 v[82:85], v[180:183], v[204:207], v[82:85]
	v_mfma_f32_16x16x32_bf16 v[70:73], v[172:175], v[212:215], v[70:73]
	v_mfma_f32_16x16x32_bf16 v[66:69], v[180:183], v[212:215], v[66:69]
	s_setprio 2
	s_barrier
	s_mov_b32 m0, s63
	v_lshl_add_u64 v[162:163], s[48:49], 0, v[140:141]
	ds_read_b128 v[184:187], v168 offset:16384
	ds_read_b128 v[188:191], v168 offset:17408
	ds_read_b128 v[192:195], v168 offset:18432
	ds_read_b128 v[196:199], v168 offset:19456
	ds_read_b128 v[200:203], v168 offset:20480
	ds_read_b128 v[204:207], v168 offset:21504
	ds_read_b128 v[208:211], v168 offset:22528
	ds_read_b128 v[212:215], v168 offset:23552
	global_load_lds_dwordx4 v[162:163], off
	v_lshl_add_u64 v[216:217], s[48:49], 0, v[144:145]
	s_mov_b32 m0, s74
	v_lshl_add_u64 v[218:219], s[52:53], 0, v[140:141]
	global_load_lds_dwordx4 v[216:217], off
	s_mov_b32 m0, s62
	v_lshl_add_u64 v[220:221], s[46:47], 0, v[142:143]
	global_load_lds_dwordx4 v[218:219], off
	v_lshl_add_u64 v[218:219], s[52:53], 0, v[144:145]
	s_mov_b32 m0, s75
	s_nop 0
	global_load_lds_dwordx4 v[218:219], off
	v_lshl_add_u64 v[218:219], s[46:47], 0, v[138:139]
	s_mov_b32 m0, s73
	s_nop 0
	global_load_lds_dwordx4 v[218:219], off
	s_mov_b32 m0, s79
	s_nop 0
	global_load_lds_dwordx4 v[220:221], off
	s_waitcnt vmcnt(8)
	s_waitcnt lgkmcnt(0)
	s_barrier
; #define PG8_STAGE(bufoff, gbase, voff) do { _Pragma("unroll") for (int _i = 0; _i < 2; ++_i) \
;         __builtin_amdgcn_global_load_lds((const unsigned*)((const char*)(gbase) + (voff)[_i]), (LAS unsigned*)(lds + (bufoff) + ldsw + _i * 8192), 16, 0, 0); } while (0)
; #define PG8_LDA(dst, b, h) do { _Pragma("unroll") for (int m = 0; m < 4; ++m) _Pragma("unroll") for (int k = 0; k < 2; ++k) dst[m][k] = *(const LAS bf16x8*)(lds + PG8_SA(b, h) + aoff + m * 2048 + k * 1024); } while (0)
; #define PG8_LDB(dst, b, h) do { _Pragma("unroll") for (int n = 0; n < 2; ++n) _Pragma("unroll") for (int k = 0; k < 2; ++k) dst[n][k] = *(const LAS bf16x8*)(lds + PG8_SB(b, h) + boff + n * 2048 + k * 1024); } while (0)
; #define PG8_MMA(ai, bj, At, Bt) do { __builtin_amdgcn_s_setprio(1); _Pragma("unroll") for (int m = 0; m < 4; ++m) _Pragma("unroll") for (int n = 0; n < 2; ++n) _Pragma("unroll") for (int k = 0; k < 2; ++k) \
;         acc[ai][bj][m][n] = __builtin_amdgcn_mfma_f32_16x16x32_bf16(Bt[n][k], At[m][k], acc[ai][bj][m][n], 0, 0, 0); __builtin_amdgcn_s_setprio(0); } while (0)
; #define PG8_WAIT_V(n) asm volatile("s_waitcnt vmcnt(" #n ")" ::: "memory")
; #define PG8_WAIT_L(n) asm volatile("s_waitcnt lgkmcnt(" #n ")" ::: "memory")
; #define PG8_BAR __builtin_amdgcn_s_barrier()
; #define PG8_SCHED __builtin_amdgcn_sched_barrier(0)
; template <class Epi>
; __device__ __forceinline__ void gemm_phase(LAS unsigned char* lds, const Gemm g, int G, int c, const Epi& E) {
;     ...
;             PG8_WAIT_V(8); PG8_WAIT_L(0); PG8_BAR; PG8_MMA(0, 0, At, B0); PG8_MMA(0, 1, At, B1); PG8_BAR; PG8_SCHED;
;             PG8_LDA(At, 0, 1); PG8_STAGE(PG8_SB(0, 0), b2, voffB); PG8_STAGE(PG8_SB(0, 1), b2 + hstepB, voffB); PG8_STAGE(PG8_SA(0, 0), a2, voffA);
;             PG8_WAIT_V(8); PG8_WAIT_L(0); PG8_BAR; PG8_MMA(1, 0, At, B0); PG8_MMA(1, 1, At, B1); PG8_BAR; PG8_SCHED;
;             PG8_LDB(B0, 1, 0); PG8_LDB(B1, 1, 1); PG8_SCHED; PG8_LDA(At, 1, 0); PG8_STAGE(PG8_SA(0, 1), a2 + hstepA, voffA);
;             PG8_WAIT_V(8); PG8_WAIT_L(0); PG8_BAR; PG8_MMA(0, 0, At, B0); PG8_MMA(0, 1, At, B1); PG8_BAR; PG8_SCHED;
	s_setprio 0
	v_mfma_f32_16x16x32_bf16 v[62:65], v[130:133], v[184:187], 0
	v_mfma_f32_16x16x32_bf16 v[58:61], v[150:153], v[184:187], 0
	v_mfma_f32_16x16x32_bf16 v[46:49], v[130:133], v[192:195], 0
	v_mfma_f32_16x16x32_bf16 v[42:45], v[150:153], v[192:195], 0
	v_mfma_f32_16x16x32_bf16 v[30:33], v[130:133], v[200:203], 0
	v_mfma_f32_16x16x32_bf16 v[26:29], v[150:153], v[200:203], 0
	v_mfma_f32_16x16x32_bf16 v[14:17], v[130:133], v[208:211], 0
	v_mfma_f32_16x16x32_bf16 v[10:13], v[150:153], v[208:211], 0
	v_mfma_f32_16x16x32_bf16 v[62:65], v[134:137], v[188:191], v[62:65]
	v_mfma_f32_16x16x32_bf16 v[58:61], v[154:157], v[188:191], v[58:61]
	v_mfma_f32_16x16x32_bf16 v[46:49], v[134:137], v[196:199], v[46:49]
	v_mfma_f32_16x16x32_bf16 v[42:45], v[154:157], v[196:199], v[42:45]
	v_mfma_f32_16x16x32_bf16 v[30:33], v[134:137], v[204:207], v[30:33]
	v_mfma_f32_16x16x32_bf16 v[26:29], v[154:157], v[204:207], v[26:29]
	v_mfma_f32_16x16x32_bf16 v[14:17], v[134:137], v[212:215], v[14:17]
	v_mfma_f32_16x16x32_bf16 v[10:13], v[154:157], v[212:215], v[10:13]
	s_setprio 2
	s_setprio 0
	v_mfma_f32_16x16x32_bf16 v[54:57], v[158:161], v[184:187], 0
	v_mfma_f32_16x16x32_bf16 v[50:53], v[176:179], v[184:187], 0
	v_mfma_f32_16x16x32_bf16 v[38:41], v[158:161], v[192:195], 0
	v_mfma_f32_16x16x32_bf16 v[34:37], v[176:179], v[192:195], 0
	v_mfma_f32_16x16x32_bf16 v[22:25], v[158:161], v[200:203], 0
	v_mfma_f32_16x16x32_bf16 v[18:21], v[176:179], v[200:203], 0
	v_mfma_f32_16x16x32_bf16 v[6:9], v[158:161], v[208:211], 0
	v_mfma_f32_16x16x32_bf16 v[2:5], v[176:179], v[208:211], 0
	v_mfma_f32_16x16x32_bf16 v[54:57], v[172:175], v[188:191], v[54:57]
	v_mfma_f32_16x16x32_bf16 v[50:53], v[180:183], v[188:191], v[50:53]
	v_mfma_f32_16x16x32_bf16 v[38:41], v[172:175], v[196:199], v[38:41]
	v_mfma_f32_16x16x32_bf16 v[34:37], v[180:183], v[196:199], v[34:37]
	v_mfma_f32_16x16x32_bf16 v[22:25], v[172:175], v[204:207], v[22:25]
	v_mfma_f32_16x16x32_bf16 v[18:21], v[180:183], v[204:207], v[18:21]
	v_mfma_f32_16x16x32_bf16 v[6:9], v[172:175], v[212:215], v[6:9]
	v_mfma_f32_16x16x32_bf16 v[2:5], v[180:183], v[212:215], v[2:5]
	s_setprio 2
	s_barrier
	v_add_u32_e32 v154, s97, v165
	v_add_u32_e32 v180, s33, v165
	ds_read_b128 v[130:133], v154
	ds_read_b128 v[134:137], v154 offset:1024
	ds_read_b128 v[150:153], v154 offset:2048
	ds_read_b128 v[154:157], v154 offset:3072
	ds_read_b128 v[158:161], v180
	ds_read_b128 v[172:175], v180 offset:1024
	ds_read_b128 v[176:179], v180 offset:2048
	ds_read_b128 v[180:183], v180 offset:3072
	s_mov_b32 m0, s80
	v_lshl_add_u64 v[222:223], s[44:45], 0, v[138:139]
	ds_read_b128 v[184:187], v168 offset:32768
	ds_read_b128 v[188:191], v168 offset:33792
	ds_read_b128 v[192:195], v168 offset:34816
	ds_read_b128 v[196:199], v168 offset:35840
	ds_read_b128 v[200:203], v168 offset:36864
	ds_read_b128 v[204:207], v168 offset:37888
	ds_read_b128 v[208:211], v168 offset:38912
	ds_read_b128 v[212:215], v168 offset:39936
	global_load_lds_dwordx4 v[222:223], off
	v_lshl_add_u64 v[222:223], s[44:45], 0, v[142:143]
	s_mov_b32 m0, s81
	s_nop 0
	global_load_lds_dwordx4 v[222:223], off
	s_waitcnt vmcnt(8)
	s_waitcnt lgkmcnt(0)
	s_barrier
	s_setprio 0
	v_mfma_f32_16x16x32_bf16 v[126:129], v[130:133], v[184:187], v[126:129]
	v_mfma_f32_16x16x32_bf16 v[122:125], v[150:153], v[184:187], v[122:125]
	v_mfma_f32_16x16x32_bf16 v[110:113], v[130:133], v[192:195], v[110:113]
	v_mfma_f32_16x16x32_bf16 v[106:109], v[150:153], v[192:195], v[106:109]
	v_mfma_f32_16x16x32_bf16 v[94:97], v[130:133], v[200:203], v[94:97]
	v_mfma_f32_16x16x32_bf16 v[90:93], v[150:153], v[200:203], v[90:93]
	v_mfma_f32_16x16x32_bf16 v[78:81], v[130:133], v[208:211], v[78:81]
	v_mfma_f32_16x16x32_bf16 v[74:77], v[150:153], v[208:211], v[74:77]
	v_mfma_f32_16x16x32_bf16 v[126:129], v[134:137], v[188:191], v[126:129]
	v_mfma_f32_16x16x32_bf16 v[122:125], v[154:157], v[188:191], v[122:125]
	v_mfma_f32_16x16x32_bf16 v[110:113], v[134:137], v[196:199], v[110:113]
	v_mfma_f32_16x16x32_bf16 v[106:109], v[154:157], v[196:199], v[106:109]
	v_mfma_f32_16x16x32_bf16 v[94:97], v[134:137], v[204:207], v[94:97]
	v_mfma_f32_16x16x32_bf16 v[90:93], v[154:157], v[204:207], v[90:93]
	v_mfma_f32_16x16x32_bf16 v[78:81], v[134:137], v[212:215], v[78:81]
	v_mfma_f32_16x16x32_bf16 v[74:77], v[154:157], v[212:215], v[74:77]
	s_setprio 2
	s_setprio 0
	v_mfma_f32_16x16x32_bf16 v[118:121], v[158:161], v[184:187], v[118:121]
	v_mfma_f32_16x16x32_bf16 v[114:117], v[176:179], v[184:187], v[114:117]
	v_mfma_f32_16x16x32_bf16 v[102:105], v[158:161], v[192:195], v[102:105]
	v_mfma_f32_16x16x32_bf16 v[98:101], v[176:179], v[192:195], v[98:101]
	v_mfma_f32_16x16x32_bf16 v[86:89], v[158:161], v[200:203], v[86:89]
	v_mfma_f32_16x16x32_bf16 v[82:85], v[176:179], v[200:203], v[82:85]
	v_mfma_f32_16x16x32_bf16 v[70:73], v[158:161], v[208:211], v[70:73]
	v_mfma_f32_16x16x32_bf16 v[66:69], v[176:179], v[208:211], v[66:69]
	v_mfma_f32_16x16x32_bf16 v[118:121], v[172:175], v[188:191], v[118:121]
	v_mfma_f32_16x16x32_bf16 v[114:117], v[180:183], v[188:191], v[114:117]
	v_mfma_f32_16x16x32_bf16 v[102:105], v[172:175], v[196:199], v[102:105]
	v_mfma_f32_16x16x32_bf16 v[98:101], v[180:183], v[196:199], v[98:101]
	v_mfma_f32_16x16x32_bf16 v[86:89], v[172:175], v[204:207], v[86:89]
	v_mfma_f32_16x16x32_bf16 v[82:85], v[180:183], v[204:207], v[82:85]
	v_mfma_f32_16x16x32_bf16 v[70:73], v[172:175], v[212:215], v[70:73]
	v_mfma_f32_16x16x32_bf16 v[66:69], v[180:183], v[212:215], v[66:69]
	s_setprio 2
	s_barrier
; #define PG8_STAGE(bufoff, gbase, voff) do { _Pragma("unroll") for (int _i = 0; _i < 2; ++_i) \
;         __builtin_amdgcn_global_load_lds((const unsigned*)((const char*)(gbase) + (voff)[_i]), (LAS unsigned*)(lds + (bufoff) + ldsw + _i * 8192), 16, 0, 0); } while (0)
; #define PG8_LDA(dst, b, h) do { _Pragma("unroll") for (int m = 0; m < 4; ++m) _Pragma("unroll") for (int k = 0; k < 2; ++k) dst[m][k] = *(const LAS bf16x8*)(lds + PG8_SA(b, h) + aoff + m * 2048 + k * 1024); } while (0)
; #define PG8_LDB(dst, b, h) do { _Pragma("unroll") for (int n = 0; n < 2; ++n) _Pragma("unroll") for (int k = 0; k < 2; ++k) dst[n][k] = *(const LAS bf16x8*)(lds + PG8_SB(b, h) + boff + n * 2048 + k * 1024); } while (0)
; #define PG8_WAIT_V(n) asm volatile("s_waitcnt vmcnt(" #n ")" ::: "memory")
; #define PG8_WAIT_L(n) asm volatile("s_waitcnt lgkmcnt(" #n ")" ::: "memory")
; template <class Epi>
; __device__ __forceinline__ void gemm_phase(LAS unsigned char* lds, const Gemm g, int G, int c, const Epi& E) {
;     ...
;         for (int t = 0; t < nt; t += 2) {
;             const bool last = (t == nt - 2);
;             const char* a1 = cA + (size_t)(t + 1) * kstep;
;             const char* a2 = last ? nA : cA + (size_t)(t + 2) * kstep; const char* b2 = last ? nB : cB + (size_t)(t + 2) * kstep;
;             const char* a3 = a2 + kstep; const char* b3 = b2 + kstep;
;             PG8_LDB(B0, 0, 0); PG8_LDB(B1, 0, 1); PG8_SCHED; PG8_LDA(At, 0, 0); PG8_STAGE(PG8_SA(1, 1), a1 + hstepA, voffA);
;             PG8_WAIT_V(8); PG8_WAIT_L(0); PG8_BAR; PG8_MMA(0, 0, At, B0); PG8_MMA(0, 1, At, B1); PG8_BAR; PG8_SCHED;
;             PG8_LDA(At, 0, 1); PG8_STAGE(PG8_SB(0, 0), b2, voffB); PG8_STAGE(PG8_SB(0, 1), b2 + hstepB, voffB); PG8_STAGE(PG8_SA(0, 0), a2, voffA);
;             PG8_WAIT_V(8); PG8_WAIT_L(0); PG8_BAR; PG8_MMA(1, 0, At, B0); PG8_MMA(1, 1, At, B1); PG8_BAR; PG8_SCHED;
;             PG8_LDB(B0, 1, 0); PG8_LDB(B1, 1, 1); PG8_SCHED; PG8_LDA(At, 1, 0); PG8_STAGE(PG8_SA(0, 1), a2 + hstepA, voffA);
;             PG8_WAIT_V(8); PG8_WAIT_L(0); PG8_BAR; PG8_MMA(0, 0, At, B0); PG8_MMA(0, 1, At, B1); PG8_BAR; PG8_SCHED;
;             PG8_LDA(At, 1, 1); PG8_STAGE(PG8_SB(1, 0), b3, voffB); PG8_STAGE(PG8_SB(1, 1), b3 + hstepB, voffB); PG8_STAGE(PG8_SA(1, 0), a3, voffA);
;             PG8_WAIT_V(8); PG8_WAIT_L(0); PG8_BAR; PG8_MMA(1, 0, At, B0); PG8_MMA(1, 1, At, B1); PG8_BAR; PG8_SCHED;
	s_mov_b32 m0, s96
	v_lshl_add_u64 v[162:163], v[162:163], 0, s[22:23]
	ds_read_b128 v[184:187], v168 offset:49152
	ds_read_b128 v[188:191], v168 offset:50176
	ds_read_b128 v[192:195], v168 offset:51200
	ds_read_b128 v[196:199], v168 offset:52224
	ds_read_b128 v[200:203], v168 offset:53248
	ds_read_b128 v[204:207], v168 offset:54272
	ds_read_b128 v[208:211], v168 offset:55296
	ds_read_b128 v[212:215], v168 offset:56320
	global_load_lds_dwordx4 v[162:163], off
	v_lshl_add_u64 v[162:163], v[216:217], 0, s[22:23]
	s_mov_b32 m0, s94
	s_nop 0
	global_load_lds_dwordx4 v[162:163], off
	v_lshl_add_u64 v[162:163], s[10:11], 0, v[140:141]
	s_mov_b32 m0, s95
	s_nop 0
	global_load_lds_dwordx4 v[162:163], off
	v_lshl_add_u64 v[162:163], s[10:11], 0, v[144:145]
	s_mov_b32 m0, s93
	s_nop 0
	global_load_lds_dwordx4 v[162:163], off
	v_lshl_add_u64 v[162:163], v[218:219], 0, s[22:23]
	s_mov_b32 m0, s85
	s_nop 0
	global_load_lds_dwordx4 v[162:163], off
	v_lshl_add_u64 v[162:163], v[220:221], 0, s[22:23]
	s_mov_b32 m0, s86
	s_nop 0
	global_load_lds_dwordx4 v[162:163], off
	s_waitcnt vmcnt(8)
	s_waitcnt lgkmcnt(0)
	s_barrier
	s_setprio 0
	v_mfma_f32_16x16x32_bf16 v[62:65], v[130:133], v[184:187], v[62:65]
	v_mfma_f32_16x16x32_bf16 v[58:61], v[150:153], v[184:187], v[58:61]
	v_mfma_f32_16x16x32_bf16 v[46:49], v[130:133], v[192:195], v[46:49]
	v_mfma_f32_16x16x32_bf16 v[42:45], v[150:153], v[192:195], v[42:45]
	v_mfma_f32_16x16x32_bf16 v[30:33], v[130:133], v[200:203], v[30:33]
	v_mfma_f32_16x16x32_bf16 v[26:29], v[150:153], v[200:203], v[26:29]
	v_mfma_f32_16x16x32_bf16 v[14:17], v[130:133], v[208:211], v[14:17]
	v_mfma_f32_16x16x32_bf16 v[10:13], v[150:153], v[208:211], v[10:13]
	v_mfma_f32_16x16x32_bf16 v[62:65], v[134:137], v[188:191], v[62:65]
	v_mfma_f32_16x16x32_bf16 v[58:61], v[154:157], v[188:191], v[58:61]
	v_mfma_f32_16x16x32_bf16 v[46:49], v[134:137], v[196:199], v[46:49]
	v_mfma_f32_16x16x32_bf16 v[42:45], v[154:157], v[196:199], v[42:45]
	v_mfma_f32_16x16x32_bf16 v[30:33], v[134:137], v[204:207], v[30:33]
	v_mfma_f32_16x16x32_bf16 v[26:29], v[154:157], v[204:207], v[26:29]
	v_mfma_f32_16x16x32_bf16 v[14:17], v[134:137], v[212:215], v[14:17]
	v_mfma_f32_16x16x32_bf16 v[10:13], v[154:157], v[212:215], v[10:13]
	s_setprio 2
	s_setprio 0
	v_mfma_f32_16x16x32_bf16 v[54:57], v[158:161], v[184:187], v[54:57]
	v_mfma_f32_16x16x32_bf16 v[50:53], v[176:179], v[184:187], v[50:53]
	v_mfma_f32_16x16x32_bf16 v[38:41], v[158:161], v[192:195], v[38:41]
	v_mfma_f32_16x16x32_bf16 v[34:37], v[176:179], v[192:195], v[34:37]
	v_mfma_f32_16x16x32_bf16 v[22:25], v[158:161], v[200:203], v[22:25]
	v_mfma_f32_16x16x32_bf16 v[18:21], v[176:179], v[200:203], v[18:21]
	v_mfma_f32_16x16x32_bf16 v[6:9], v[158:161], v[208:211], v[6:9]
	v_mfma_f32_16x16x32_bf16 v[2:5], v[176:179], v[208:211], v[2:5]
	v_mfma_f32_16x16x32_bf16 v[54:57], v[172:175], v[188:191], v[54:57]
	v_mfma_f32_16x16x32_bf16 v[50:53], v[180:183], v[188:191], v[50:53]
	v_mfma_f32_16x16x32_bf16 v[38:41], v[172:175], v[196:199], v[38:41]
	v_mfma_f32_16x16x32_bf16 v[34:37], v[180:183], v[196:199], v[34:37]
	v_mfma_f32_16x16x32_bf16 v[22:25], v[172:175], v[204:207], v[22:25]
	v_mfma_f32_16x16x32_bf16 v[18:21], v[180:183], v[204:207], v[18:21]
	v_mfma_f32_16x16x32_bf16 v[6:9], v[172:175], v[212:215], v[6:9]
	v_mfma_f32_16x16x32_bf16 v[2:5], v[180:183], v[212:215], v[2:5]
	s_setprio 2
	s_barrier
	s_movk_i32 s44, 0x100
	s_andn2_b64 vcc, exec, s[4:5]
	s_mov_b64 s[10:11], -1
	s_mov_b64 s[4:5], 0
	s_cbranch_vccz .LBB0_1537
.LBB0_1537:
	s_add_u32 s33, s8, s44
	s_addc_u32 s45, s9, 0
	s_add_u32 s48, s33, 0x100
	s_addc_u32 s49, s45, 0
	s_and_b64 s[46:47], s[10:11], exec
	s_cselect_b32 s47, s41, s49
	s_cselect_b32 s46, s40, s48
	s_add_u32 s44, s6, s44
	s_addc_u32 s48, s7, 0
	s_add_u32 s44, s44, 0x100
	s_addc_u32 s48, s48, 0
	s_and_b64 s[10:11], s[10:11], exec
	s_cselect_b32 s49, s43, s48
	s_cselect_b32 s48, s42, s44
	s_add_u32 s54, s33, 0xb0080
	ds_read_b128 v[130:133], v166
	ds_read_b128 v[134:137], v166 offset:1024
	ds_read_b128 v[150:153], v166 offset:2048
	ds_read_b128 v[154:157], v166 offset:3072
	ds_read_b128 v[158:161], v167
	ds_read_b128 v[172:175], v167 offset:1024
	ds_read_b128 v[176:179], v167 offset:2048
	ds_read_b128 v[180:183], v167 offset:3072
	s_addc_u32 s55, s45, 0
	s_add_i32 s63, s87, s70
	s_add_i32 m0, s73, 0xc000
	s_add_i32 s64, s73, 0xe000
	s_add_i32 s74, s63, 0x2000
	s_add_u32 s52, s48, 0xb0000
	s_addc_u32 s53, s49, 0
	s_add_i32 s62, s88, s70
	s_add_i32 s75, s62, 0x2000
	s_add_i32 s97, 0, 0x18000
	s_add_i32 s33, 0, 0x1c000
	s_add_u32 s44, s46, 0xb0000
	s_addc_u32 s45, s47, 0
	s_add_i32 s96, s97, s70
	s_add_i32 s94, s96, 0x2000
	s_add_u32 s10, s48, 0xb0080
	s_addc_u32 s11, s49, 0
	s_add_i32 s95, s33, s70
	s_add_i32 s93, s95, 0x2000
	v_lshl_add_u64 v[162:163], s[54:55], 0, v[138:139]
	ds_read_b128 v[184:187], v168
	ds_read_b128 v[188:191], v168 offset:1024
	ds_read_b128 v[192:195], v168 offset:2048
	ds_read_b128 v[196:199], v168 offset:3072
	ds_read_b128 v[200:203], v168 offset:4096
	ds_read_b128 v[204:207], v168 offset:5120
	ds_read_b128 v[208:211], v168 offset:6144
	ds_read_b128 v[212:215], v168 offset:7168
	global_load_lds_dwordx4 v[162:163], off
	v_lshl_add_u64 v[162:163], s[54:55], 0, v[142:143]
	s_mov_b32 m0, s64
	s_nop 0
	global_load_lds_dwordx4 v[162:163], off
	s_waitcnt vmcnt(8)
	s_waitcnt lgkmcnt(0)
	s_barrier
; #define PG8_STAGE(bufoff, gbase, voff) do { _Pragma("unroll") for (int _i = 0; _i < 2; ++_i) \
;         __builtin_amdgcn_global_load_lds((const unsigned*)((const char*)(gbase) + (voff)[_i]), (LAS unsigned*)(lds + (bufoff) + ldsw + _i * 8192), 16, 0, 0); } while (0)
; #define PG8_LDA(dst, b, h) do { _Pragma("unroll") for (int m = 0; m < 4; ++m) _Pragma("unroll") for (int k = 0; k < 2; ++k) dst[m][k] = *(const LAS bf16x8*)(lds + PG8_SA(b, h) + aoff + m * 2048 + k * 1024); } while (0)
; #define PG8_LDB(dst, b, h) do { _Pragma("unroll") for (int n = 0; n < 2; ++n) _Pragma("unroll") for (int k = 0; k < 2; ++k) dst[n][k] = *(const LAS bf16x8*)(lds + PG8_SB(b, h) + boff + n * 2048 + k * 1024); } while (0)
; #define PG8_MMA(ai, bj, At, Bt) do { __builtin_amdgcn_s_setprio(1); _Pragma("unroll") for (int m = 0; m < 4; ++m) _Pragma("unroll") for (int n = 0; n < 2; ++n) _Pragma("unroll") for (int k = 0; k < 2; ++k) \
;         acc[ai][bj][m][n] = __builtin_amdgcn_mfma_f32_16x16x32_bf16(Bt[n][k], At[m][k], acc[ai][bj][m][n], 0, 0, 0); __builtin_amdgcn_s_setprio(0); } while (0)
; #define PG8_WAIT_V(n) asm volatile("s_waitcnt vmcnt(" #n ")" ::: "memory")
; #define PG8_WAIT_L(n) asm volatile("s_waitcnt lgkmcnt(" #n ")" ::: "memory")
; #define PG8_BAR __builtin_amdgcn_s_barrier()
; #define PG8_SCHED __builtin_amdgcn_sched_barrier(0)
; template <class Epi>
; __device__ __forceinline__ void gemm_phase(LAS unsigned char* lds, const Gemm g, int G, int c, const Epi& E) {
;     ...
;             PG8_LDB(B0, 0, 0); PG8_LDB(B1, 0, 1); PG8_SCHED; PG8_LDA(At, 0, 0); PG8_STAGE(PG8_SA(1, 1), a1 + hstepA, voffA);
;             PG8_WAIT_V(8); PG8_WAIT_L(0); PG8_BAR; PG8_MMA(0, 0, At, B0); PG8_MMA(0, 1, At, B1); PG8_BAR; PG8_SCHED;
;             PG8_LDA(At, 0, 1); PG8_STAGE(PG8_SB(0, 0), b2, voffB); PG8_STAGE(PG8_SB(0, 1), b2 + hstepB, voffB); PG8_STAGE(PG8_SA(0, 0), a2, voffA);
;             PG8_WAIT_V(8); PG8_WAIT_L(0); PG8_BAR; PG8_MMA(1, 0, At, B0); PG8_MMA(1, 1, At, B1); PG8_BAR; PG8_SCHED;
	s_setprio 0
	v_mfma_f32_16x16x32_bf16 v[126:129], v[130:133], v[184:187], v[126:129]
	v_mfma_f32_16x16x32_bf16 v[122:125], v[150:153], v[184:187], v[122:125]
	v_mfma_f32_16x16x32_bf16 v[110:113], v[130:133], v[192:195], v[110:113]
	v_mfma_f32_16x16x32_bf16 v[106:109], v[150:153], v[192:195], v[106:109]
	v_mfma_f32_16x16x32_bf16 v[94:97], v[130:133], v[200:203], v[94:97]
	v_mfma_f32_16x16x32_bf16 v[90:93], v[150:153], v[200:203], v[90:93]
	v_mfma_f32_16x16x32_bf16 v[78:81], v[130:133], v[208:211], v[78:81]
	v_mfma_f32_16x16x32_bf16 v[74:77], v[150:153], v[208:211], v[74:77]
	v_mfma_f32_16x16x32_bf16 v[126:129], v[134:137], v[188:191], v[126:129]
	v_mfma_f32_16x16x32_bf16 v[122:125], v[154:157], v[188:191], v[122:125]
	v_mfma_f32_16x16x32_bf16 v[110:113], v[134:137], v[196:199], v[110:113]
	v_mfma_f32_16x16x32_bf16 v[106:109], v[154:157], v[196:199], v[106:109]
	v_mfma_f32_16x16x32_bf16 v[94:97], v[134:137], v[204:207], v[94:97]
	v_mfma_f32_16x16x32_bf16 v[90:93], v[154:157], v[204:207], v[90:93]
	v_mfma_f32_16x16x32_bf16 v[78:81], v[134:137], v[212:215], v[78:81]
	v_mfma_f32_16x16x32_bf16 v[74:77], v[154:157], v[212:215], v[74:77]
	s_setprio 2
	s_setprio 0
	v_mfma_f32_16x16x32_bf16 v[118:121], v[158:161], v[184:187], v[118:121]
	v_mfma_f32_16x16x32_bf16 v[114:117], v[176:179], v[184:187], v[114:117]
	v_mfma_f32_16x16x32_bf16 v[102:105], v[158:161], v[192:195], v[102:105]
	v_mfma_f32_16x16x32_bf16 v[98:101], v[176:179], v[192:195], v[98:101]
	v_mfma_f32_16x16x32_bf16 v[86:89], v[158:161], v[200:203], v[86:89]
	v_mfma_f32_16x16x32_bf16 v[82:85], v[176:179], v[200:203], v[82:85]
	v_mfma_f32_16x16x32_bf16 v[70:73], v[158:161], v[208:211], v[70:73]
	v_mfma_f32_16x16x32_bf16 v[66:69], v[176:179], v[208:211], v[66:69]
	v_mfma_f32_16x16x32_bf16 v[118:121], v[172:175], v[188:191], v[118:121]
	v_mfma_f32_16x16x32_bf16 v[114:117], v[180:183], v[188:191], v[114:117]
	v_mfma_f32_16x16x32_bf16 v[102:105], v[172:175], v[196:199], v[102:105]
	v_mfma_f32_16x16x32_bf16 v[98:101], v[180:183], v[196:199], v[98:101]
	v_mfma_f32_16x16x32_bf16 v[86:89], v[172:175], v[204:207], v[86:89]
	v_mfma_f32_16x16x32_bf16 v[82:85], v[180:183], v[204:207], v[82:85]
	v_mfma_f32_16x16x32_bf16 v[70:73], v[172:175], v[212:215], v[70:73]
	v_mfma_f32_16x16x32_bf16 v[66:69], v[180:183], v[212:215], v[66:69]
	s_setprio 2
	s_barrier
	s_mov_b32 m0, s63
	v_lshl_add_u64 v[162:163], s[48:49], 0, v[140:141]
	ds_read_b128 v[184:187], v168 offset:16384
	ds_read_b128 v[188:191], v168 offset:17408
	ds_read_b128 v[192:195], v168 offset:18432
	ds_read_b128 v[196:199], v168 offset:19456
	ds_read_b128 v[200:203], v168 offset:20480
	ds_read_b128 v[204:207], v168 offset:21504
	ds_read_b128 v[208:211], v168 offset:22528
	ds_read_b128 v[212:215], v168 offset:23552
	global_load_lds_dwordx4 v[162:163], off
	v_lshl_add_u64 v[216:217], s[48:49], 0, v[144:145]
	s_mov_b32 m0, s74
	v_lshl_add_u64 v[218:219], s[52:53], 0, v[140:141]
	global_load_lds_dwordx4 v[216:217], off
	s_mov_b32 m0, s62
	v_lshl_add_u64 v[220:221], s[46:47], 0, v[142:143]
	global_load_lds_dwordx4 v[218:219], off
	v_lshl_add_u64 v[218:219], s[52:53], 0, v[144:145]
	s_mov_b32 m0, s75
	s_nop 0
	global_load_lds_dwordx4 v[218:219], off
	v_lshl_add_u64 v[218:219], s[46:47], 0, v[138:139]
	s_mov_b32 m0, s73
	s_nop 0
	global_load_lds_dwordx4 v[218:219], off
	s_mov_b32 m0, s79
	s_nop 0
	global_load_lds_dwordx4 v[220:221], off
	s_waitcnt vmcnt(8)
	s_waitcnt lgkmcnt(0)
	s_barrier
	s_setprio 0
	v_mfma_f32_16x16x32_bf16 v[62:65], v[130:133], v[184:187], v[62:65]
	v_mfma_f32_16x16x32_bf16 v[58:61], v[150:153], v[184:187], v[58:61]
	v_mfma_f32_16x16x32_bf16 v[46:49], v[130:133], v[192:195], v[46:49]
	v_mfma_f32_16x16x32_bf16 v[42:45], v[150:153], v[192:195], v[42:45]
	v_mfma_f32_16x16x32_bf16 v[30:33], v[130:133], v[200:203], v[30:33]
	v_mfma_f32_16x16x32_bf16 v[26:29], v[150:153], v[200:203], v[26:29]
	v_mfma_f32_16x16x32_bf16 v[14:17], v[130:133], v[208:211], v[14:17]
	v_mfma_f32_16x16x32_bf16 v[10:13], v[150:153], v[208:211], v[10:13]
	v_mfma_f32_16x16x32_bf16 v[62:65], v[134:137], v[188:191], v[62:65]
	v_mfma_f32_16x16x32_bf16 v[58:61], v[154:157], v[188:191], v[58:61]
	v_mfma_f32_16x16x32_bf16 v[46:49], v[134:137], v[196:199], v[46:49]
	v_mfma_f32_16x16x32_bf16 v[42:45], v[154:157], v[196:199], v[42:45]
	v_mfma_f32_16x16x32_bf16 v[30:33], v[134:137], v[204:207], v[30:33]
	v_mfma_f32_16x16x32_bf16 v[26:29], v[154:157], v[204:207], v[26:29]
	v_mfma_f32_16x16x32_bf16 v[14:17], v[134:137], v[212:215], v[14:17]
	v_mfma_f32_16x16x32_bf16 v[10:13], v[154:157], v[212:215], v[10:13]
	s_setprio 2
	s_setprio 0
	v_mfma_f32_16x16x32_bf16 v[54:57], v[158:161], v[184:187], v[54:57]
	v_mfma_f32_16x16x32_bf16 v[50:53], v[176:179], v[184:187], v[50:53]
	v_mfma_f32_16x16x32_bf16 v[38:41], v[158:161], v[192:195], v[38:41]
	v_mfma_f32_16x16x32_bf16 v[34:37], v[176:179], v[192:195], v[34:37]
	v_mfma_f32_16x16x32_bf16 v[22:25], v[158:161], v[200:203], v[22:25]
	v_mfma_f32_16x16x32_bf16 v[18:21], v[176:179], v[200:203], v[18:21]
	v_mfma_f32_16x16x32_bf16 v[6:9], v[158:161], v[208:211], v[6:9]
	v_mfma_f32_16x16x32_bf16 v[2:5], v[176:179], v[208:211], v[2:5]
	v_mfma_f32_16x16x32_bf16 v[54:57], v[172:175], v[188:191], v[54:57]
	v_mfma_f32_16x16x32_bf16 v[50:53], v[180:183], v[188:191], v[50:53]
	v_mfma_f32_16x16x32_bf16 v[38:41], v[172:175], v[196:199], v[38:41]
	v_mfma_f32_16x16x32_bf16 v[34:37], v[180:183], v[196:199], v[34:37]
	v_mfma_f32_16x16x32_bf16 v[22:25], v[172:175], v[204:207], v[22:25]
	v_mfma_f32_16x16x32_bf16 v[18:21], v[180:183], v[204:207], v[18:21]
	v_mfma_f32_16x16x32_bf16 v[6:9], v[172:175], v[212:215], v[6:9]
	v_mfma_f32_16x16x32_bf16 v[2:5], v[180:183], v[212:215], v[2:5]
	s_setprio 2
	s_barrier
; #define PG8_STAGE(bufoff, gbase, voff) do { _Pragma("unroll") for (int _i = 0; _i < 2; ++_i) \
;         __builtin_amdgcn_global_load_lds((const unsigned*)((const char*)(gbase) + (voff)[_i]), (LAS unsigned*)(lds + (bufoff) + ldsw + _i * 8192), 16, 0, 0); } while (0)
; #define PG8_LDA(dst, b, h) do { _Pragma("unroll") for (int m = 0; m < 4; ++m) _Pragma("unroll") for (int k = 0; k < 2; ++k) dst[m][k] = *(const LAS bf16x8*)(lds + PG8_SA(b, h) + aoff + m * 2048 + k * 1024); } while (0)
; #define PG8_LDB(dst, b, h) do { _Pragma("unroll") for (int n = 0; n < 2; ++n) _Pragma("unroll") for (int k = 0; k < 2; ++k) dst[n][k] = *(const LAS bf16x8*)(lds + PG8_SB(b, h) + boff + n * 2048 + k * 1024); } while (0)
; #define PG8_MMA(ai, bj, At, Bt) do { __builtin_amdgcn_s_setprio(1); _Pragma("unroll") for (int m = 0; m < 4; ++m) _Pragma("unroll") for (int n = 0; n < 2; ++n) _Pragma("unroll") for (int k = 0; k < 2; ++k) \
;         acc[ai][bj][m][n] = __builtin_amdgcn_mfma_f32_16x16x32_bf16(Bt[n][k], At[m][k], acc[ai][bj][m][n], 0, 0, 0); __builtin_amdgcn_s_setprio(0); } while (0)
; #define PG8_WAIT_V(n) asm volatile("s_waitcnt vmcnt(" #n ")" ::: "memory")
; #define PG8_WAIT_L(n) asm volatile("s_waitcnt lgkmcnt(" #n ")" ::: "memory")
; #define PG8_BAR __builtin_amdgcn_s_barrier()
; #define PG8_SCHED __builtin_amdgcn_sched_barrier(0)
; template <class Epi>
; __device__ __forceinline__ void gemm_phase(LAS unsigned char* lds, const Gemm g, int G, int c, const Epi& E) {
;     ...
;             PG8_LDB(B0, 1, 0); PG8_LDB(B1, 1, 1); PG8_SCHED; PG8_LDA(At, 1, 0); PG8_STAGE(PG8_SA(0, 1), a2 + hstepA, voffA);
;             PG8_WAIT_V(8); PG8_WAIT_L(0); PG8_BAR; PG8_MMA(0, 0, At, B0); PG8_MMA(0, 1, At, B1); PG8_BAR; PG8_SCHED;
;             PG8_LDA(At, 1, 1); PG8_STAGE(PG8_SB(1, 0), b3, voffB); PG8_STAGE(PG8_SB(1, 1), b3 + hstepB, voffB); PG8_STAGE(PG8_SA(1, 0), a3, voffA);
;             PG8_WAIT_V(8); PG8_WAIT_L(0); PG8_BAR; PG8_MMA(1, 0, At, B0); PG8_MMA(1, 1, At, B1); PG8_BAR; PG8_SCHED;
;         }
;         if (wr == 0) PG8_BAR;
	v_add_u32_e32 v154, s97, v165
	v_add_u32_e32 v180, s33, v165
	ds_read_b128 v[130:133], v154
	ds_read_b128 v[134:137], v154 offset:1024
	ds_read_b128 v[150:153], v154 offset:2048
	ds_read_b128 v[154:157], v154 offset:3072
	ds_read_b128 v[158:161], v180
	ds_read_b128 v[172:175], v180 offset:1024
	ds_read_b128 v[176:179], v180 offset:2048
	ds_read_b128 v[180:183], v180 offset:3072
	s_mov_b32 m0, s80
	v_lshl_add_u64 v[222:223], s[44:45], 0, v[138:139]
	ds_read_b128 v[184:187], v168 offset:32768
	ds_read_b128 v[188:191], v168 offset:33792
	ds_read_b128 v[192:195], v168 offset:34816
	ds_read_b128 v[196:199], v168 offset:35840
	ds_read_b128 v[200:203], v168 offset:36864
	ds_read_b128 v[204:207], v168 offset:37888
	ds_read_b128 v[208:211], v168 offset:38912
	ds_read_b128 v[212:215], v168 offset:39936
	global_load_lds_dwordx4 v[222:223], off
	v_lshl_add_u64 v[222:223], s[44:45], 0, v[142:143]
	s_mov_b32 m0, s81
	s_nop 0
	global_load_lds_dwordx4 v[222:223], off
	s_waitcnt vmcnt(8)
	s_waitcnt lgkmcnt(0)
	s_barrier
	s_setprio 0
	v_mfma_f32_16x16x32_bf16 v[126:129], v[130:133], v[184:187], v[126:129]
	v_mfma_f32_16x16x32_bf16 v[122:125], v[150:153], v[184:187], v[122:125]
	v_mfma_f32_16x16x32_bf16 v[110:113], v[130:133], v[192:195], v[110:113]
	v_mfma_f32_16x16x32_bf16 v[106:109], v[150:153], v[192:195], v[106:109]
	v_mfma_f32_16x16x32_bf16 v[94:97], v[130:133], v[200:203], v[94:97]
	v_mfma_f32_16x16x32_bf16 v[90:93], v[150:153], v[200:203], v[90:93]
	v_mfma_f32_16x16x32_bf16 v[78:81], v[130:133], v[208:211], v[78:81]
	v_mfma_f32_16x16x32_bf16 v[74:77], v[150:153], v[208:211], v[74:77]
	v_mfma_f32_16x16x32_bf16 v[126:129], v[134:137], v[188:191], v[126:129]
	v_mfma_f32_16x16x32_bf16 v[122:125], v[154:157], v[188:191], v[122:125]
	v_mfma_f32_16x16x32_bf16 v[110:113], v[134:137], v[196:199], v[110:113]
	v_mfma_f32_16x16x32_bf16 v[106:109], v[154:157], v[196:199], v[106:109]
	v_mfma_f32_16x16x32_bf16 v[94:97], v[134:137], v[204:207], v[94:97]
	v_mfma_f32_16x16x32_bf16 v[90:93], v[154:157], v[204:207], v[90:93]
	v_mfma_f32_16x16x32_bf16 v[78:81], v[134:137], v[212:215], v[78:81]
	v_mfma_f32_16x16x32_bf16 v[74:77], v[154:157], v[212:215], v[74:77]
	s_setprio 2
	s_setprio 0
	v_mfma_f32_16x16x32_bf16 v[118:121], v[158:161], v[184:187], v[118:121]
	v_mfma_f32_16x16x32_bf16 v[114:117], v[176:179], v[184:187], v[114:117]
	v_mfma_f32_16x16x32_bf16 v[102:105], v[158:161], v[192:195], v[102:105]
	v_mfma_f32_16x16x32_bf16 v[98:101], v[176:179], v[192:195], v[98:101]
	v_mfma_f32_16x16x32_bf16 v[86:89], v[158:161], v[200:203], v[86:89]
	v_mfma_f32_16x16x32_bf16 v[82:85], v[176:179], v[200:203], v[82:85]
	v_mfma_f32_16x16x32_bf16 v[70:73], v[158:161], v[208:211], v[70:73]
	v_mfma_f32_16x16x32_bf16 v[66:69], v[176:179], v[208:211], v[66:69]
	v_mfma_f32_16x16x32_bf16 v[118:121], v[172:175], v[188:191], v[118:121]
	v_mfma_f32_16x16x32_bf16 v[114:117], v[180:183], v[188:191], v[114:117]
	v_mfma_f32_16x16x32_bf16 v[102:105], v[172:175], v[196:199], v[102:105]
	v_mfma_f32_16x16x32_bf16 v[98:101], v[180:183], v[196:199], v[98:101]
	v_mfma_f32_16x16x32_bf16 v[86:89], v[172:175], v[204:207], v[86:89]
	v_mfma_f32_16x16x32_bf16 v[82:85], v[180:183], v[204:207], v[82:85]
	v_mfma_f32_16x16x32_bf16 v[70:73], v[172:175], v[212:215], v[70:73]
	v_mfma_f32_16x16x32_bf16 v[66:69], v[180:183], v[212:215], v[66:69]
	s_setprio 2
	s_barrier
	s_mov_b32 m0, s96
	v_lshl_add_u64 v[162:163], v[162:163], 0, s[22:23]
	ds_read_b128 v[184:187], v168 offset:49152
	ds_read_b128 v[188:191], v168 offset:50176
	ds_read_b128 v[192:195], v168 offset:51200
	ds_read_b128 v[196:199], v168 offset:52224
	ds_read_b128 v[200:203], v168 offset:53248
	ds_read_b128 v[204:207], v168 offset:54272
	ds_read_b128 v[208:211], v168 offset:55296
	ds_read_b128 v[212:215], v168 offset:56320
	global_load_lds_dwordx4 v[162:163], off
	v_lshl_add_u64 v[162:163], v[216:217], 0, s[22:23]
	s_mov_b32 m0, s94
	s_nop 0
	global_load_lds_dwordx4 v[162:163], off
	v_lshl_add_u64 v[162:163], s[10:11], 0, v[140:141]
	s_mov_b32 m0, s95
	s_nop 0
	global_load_lds_dwordx4 v[162:163], off
	v_lshl_add_u64 v[162:163], s[10:11], 0, v[144:145]
	s_mov_b32 m0, s93
	s_nop 0
	global_load_lds_dwordx4 v[162:163], off
	v_lshl_add_u64 v[162:163], v[218:219], 0, s[22:23]
	s_mov_b32 m0, s85
	s_nop 0
	global_load_lds_dwordx4 v[162:163], off
	v_lshl_add_u64 v[162:163], v[220:221], 0, s[22:23]
	s_mov_b32 m0, s86
	s_nop 0
	global_load_lds_dwordx4 v[162:163], off
	s_waitcnt vmcnt(8)
	s_waitcnt lgkmcnt(0)
	s_barrier
	s_setprio 0
	v_mfma_f32_16x16x32_bf16 v[62:65], v[130:133], v[184:187], v[62:65]
	v_mfma_f32_16x16x32_bf16 v[58:61], v[150:153], v[184:187], v[58:61]
	v_mfma_f32_16x16x32_bf16 v[46:49], v[130:133], v[192:195], v[46:49]
	v_mfma_f32_16x16x32_bf16 v[42:45], v[150:153], v[192:195], v[42:45]
	v_mfma_f32_16x16x32_bf16 v[30:33], v[130:133], v[200:203], v[30:33]
	v_mfma_f32_16x16x32_bf16 v[26:29], v[150:153], v[200:203], v[26:29]
	v_mfma_f32_16x16x32_bf16 v[14:17], v[130:133], v[208:211], v[14:17]
	v_mfma_f32_16x16x32_bf16 v[10:13], v[150:153], v[208:211], v[10:13]
	v_mfma_f32_16x16x32_bf16 v[62:65], v[134:137], v[188:191], v[62:65]
	v_mfma_f32_16x16x32_bf16 v[58:61], v[154:157], v[188:191], v[58:61]
	v_mfma_f32_16x16x32_bf16 v[46:49], v[134:137], v[196:199], v[46:49]
	v_mfma_f32_16x16x32_bf16 v[42:45], v[154:157], v[196:199], v[42:45]
	v_mfma_f32_16x16x32_bf16 v[30:33], v[134:137], v[204:207], v[30:33]
	v_mfma_f32_16x16x32_bf16 v[26:29], v[154:157], v[204:207], v[26:29]
	v_mfma_f32_16x16x32_bf16 v[14:17], v[134:137], v[212:215], v[14:17]
	v_mfma_f32_16x16x32_bf16 v[10:13], v[154:157], v[212:215], v[10:13]
	s_setprio 2
	s_setprio 0
	v_mfma_f32_16x16x32_bf16 v[54:57], v[158:161], v[184:187], v[54:57]
	v_mfma_f32_16x16x32_bf16 v[50:53], v[176:179], v[184:187], v[50:53]
	v_mfma_f32_16x16x32_bf16 v[38:41], v[158:161], v[192:195], v[38:41]
	v_mfma_f32_16x16x32_bf16 v[34:37], v[176:179], v[192:195], v[34:37]
	v_mfma_f32_16x16x32_bf16 v[22:25], v[158:161], v[200:203], v[22:25]
	v_mfma_f32_16x16x32_bf16 v[18:21], v[176:179], v[200:203], v[18:21]
	v_mfma_f32_16x16x32_bf16 v[6:9], v[158:161], v[208:211], v[6:9]
	v_mfma_f32_16x16x32_bf16 v[2:5], v[176:179], v[208:211], v[2:5]
	v_mfma_f32_16x16x32_bf16 v[54:57], v[172:175], v[188:191], v[54:57]
	v_mfma_f32_16x16x32_bf16 v[50:53], v[180:183], v[188:191], v[50:53]
	v_mfma_f32_16x16x32_bf16 v[38:41], v[172:175], v[196:199], v[38:41]
	v_mfma_f32_16x16x32_bf16 v[34:37], v[180:183], v[196:199], v[34:37]
	v_mfma_f32_16x16x32_bf16 v[22:25], v[172:175], v[204:207], v[22:25]
	v_mfma_f32_16x16x32_bf16 v[18:21], v[180:183], v[204:207], v[18:21]
	v_mfma_f32_16x16x32_bf16 v[6:9], v[172:175], v[212:215], v[6:9]
	v_mfma_f32_16x16x32_bf16 v[2:5], v[180:183], v[212:215], v[2:5]
	s_setprio 2
	s_barrier
	s_movk_i32 s44, 0x100
	s_andn2_b64 vcc, exec, s[4:5]
	s_mov_b64 s[10:11], -1
	s_mov_b64 s[4:5], 0
	s_cbranch_vccz .LBB0_1537
	s_and_b64 vcc, exec, s[24:25]
	s_cbranch_vccz .LBB0_1540
	s_barrier

; #define PG8_STAGE(bufoff, gbase, voff) do { _Pragma("unroll") for (int _i = 0; _i < 2; ++_i) \
;         __builtin_amdgcn_global_load_lds((const unsigned*)((const char*)(gbase) + (voff)[_i]), (LAS unsigned*)(lds + (bufoff) + ldsw + _i * 8192), 16, 0, 0); } while (0)
; #define PG8_LDA(dst, b, h) do { _Pragma("unroll") for (int m = 0; m < 4; ++m) _Pragma("unroll") for (int k = 0; k < 2; ++k) dst[m][k] = *(const LAS bf16x8*)(lds + PG8_SA(b, h) + aoff + m * 2048 + k * 1024); } while (0)
; #define PG8_LDB(dst, b, h) do { _Pragma("unroll") for (int n = 0; n < 2; ++n) _Pragma("unroll") for (int k = 0; k < 2; ++k) dst[n][k] = *(const LAS bf16x8*)(lds + PG8_SB(b, h) + boff + n * 2048 + k * 1024); } while (0)
; #define PG8_MMA(ai, bj, At, Bt) do { __builtin_amdgcn_s_setprio(1); _Pragma("unroll") for (int m = 0; m < 4; ++m) _Pragma("unroll") for (int n = 0; n < 2; ++n) _Pragma("unroll") for (int k = 0; k < 2; ++k) \
;         acc[ai][bj][m][n] = __builtin_amdgcn_mfma_f32_16x16x32_bf16(Bt[n][k], At[m][k], acc[ai][bj][m][n], 0, 0, 0); __builtin_amdgcn_s_setprio(0); } while (0)
; #define PG8_WAIT_V(n) asm volatile("s_waitcnt vmcnt(" #n ")" ::: "memory")
; template <class Epi>
; __device__ __forceinline__ void gemm_phase(LAS unsigned char* lds, const Gemm g, int G, int c, const Epi& E) {
;     ...
;     for (;;) {
;         const bool has_next = S.next(ui + 1, nxt);
;         const char* nA = has_next ? (const char*)(g.A + (size_t)nxt.pb * g.sA) + (size_t)nxt.pm * 2 * hstepA : cA;
;         const char* nB = has_next ? (const char*)(g.Bt + (size_t)nxt.pb * g.sB) + (size_t)nxt.pn * 2 * hstepB : cB;
; #pragma nounroll
;         for (int t = 0; t < nt; t += 2) {
;             const bool last = (t == nt - 2);
;             const char* a1 = cA + (size_t)(t + 1) * kstep;
;             const char* a2 = last ? nA : cA + (size_t)(t + 2) * kstep; const char* b2 = last ? nB : cB + (size_t)(t + 2) * kstep;
;             const char* a3 = a2 + kstep; const char* b3 = b2 + kstep;
;             PG8_LDB(B0, 0, 0); PG8_LDB(B1, 0, 1); PG8_SCHED; PG8_LDA(At, 0, 0); PG8_STAGE(PG8_SA(1, 1), a1 + hstepA, voffA);
;             PG8_WAIT_V(8); PG8_WAIT_L(0); PG8_BAR; PG8_MMA(0, 0, At, B0); PG8_MMA(0, 1, At, B1); PG8_BAR; PG8_SCHED;
;             PG8_LDA(At, 0, 1); PG8_STAGE(PG8_SB(0, 0), b2, voffB); PG8_STAGE(PG8_SB(0, 1), b2 + hstepB, voffB); PG8_STAGE(PG8_SA(0, 0), a2, voffA);
.LBB0_1652:
	s_mov_b32 s48, 0
	s_mov_b64 s[4:5], -1
	s_mov_b64 s[46:47], 0
	s_waitcnt lgkmcnt(0)
	s_waitcnt vmcnt(0)
	s_add_u32 s33, s8, s48
	s_addc_u32 s49, s9, 0
	s_add_u32 s54, s33, 0x100
	s_addc_u32 s55, s49, 0
	s_and_b64 s[52:53], s[46:47], exec
	s_cselect_b32 s53, s41, s55
	s_cselect_b32 s52, s40, s54
	s_add_u32 s48, s6, s48
	s_addc_u32 s54, s7, 0
	s_add_u32 s48, s48, 0x100
	s_addc_u32 s54, s54, 0
	s_and_b64 s[46:47], s[46:47], exec
	s_cselect_b32 s55, s43, s54
	s_cselect_b32 s54, s42, s48
	s_add_u32 s58, s33, 0xb0080
	ds_read_b128 v[142:145], v166
	ds_read_b128 v[146:149], v166 offset:1024
	ds_read_b128 v[150:153], v166 offset:2048
	ds_read_b128 v[154:157], v166 offset:3072
	ds_read_b128 v[158:161], v167
	ds_read_b128 v[170:173], v167 offset:1024
	ds_read_b128 v[174:177], v167 offset:2048
	ds_read_b128 v[178:181], v167 offset:3072
	s_addc_u32 s59, s49, 0
	s_add_i32 s63, s80, s23
	s_add_i32 m0, s68, 0xc000
	s_add_i32 s64, s68, 0xe000
	s_add_i32 s74, s63, 0x2000
	s_add_u32 s56, s54, 0xb0000
	s_addc_u32 s57, s55, 0
	s_add_i32 s62, s81, s23
	s_add_i32 s75, s62, 0x2000
	s_add_i32 s93, 0, 0x18000
	s_add_i32 s33, 0, 0x1c000
	s_add_u32 s48, s52, 0xb0000
	s_addc_u32 s49, s53, 0
	s_add_i32 s92, s93, s23
	s_add_i32 s90, s92, 0x2000
	s_add_u32 s46, s54, 0xb0080
	s_addc_u32 s47, s55, 0
	s_add_i32 s91, s33, s23
	s_add_i32 s89, s91, 0x2000
	v_lshl_add_u64 v[162:163], s[58:59], 0, v[136:137]
	ds_read_b128 v[182:185], v168
	ds_read_b128 v[186:189], v168 offset:1024
	ds_read_b128 v[190:193], v168 offset:2048
	ds_read_b128 v[194:197], v168 offset:3072
	ds_read_b128 v[198:201], v168 offset:4096
	ds_read_b128 v[202:205], v168 offset:5120
	ds_read_b128 v[206:209], v168 offset:6144
	ds_read_b128 v[210:213], v168 offset:7168
	global_load_lds_dwordx4 v[162:163], off
	v_lshl_add_u64 v[162:163], s[58:59], 0, v[132:133]
	s_mov_b32 m0, s64
	s_nop 0
	global_load_lds_dwordx4 v[162:163], off
	s_waitcnt vmcnt(8)
	s_waitcnt lgkmcnt(0)
	s_barrier
	s_setprio 0
	v_mfma_f32_16x16x32_bf16 v[126:129], v[142:145], v[182:185], 0
	v_mfma_f32_16x16x32_bf16 v[122:125], v[150:153], v[182:185], 0
	v_mfma_f32_16x16x32_bf16 v[110:113], v[142:145], v[190:193], 0
	v_mfma_f32_16x16x32_bf16 v[106:109], v[150:153], v[190:193], 0
	v_mfma_f32_16x16x32_bf16 v[94:97], v[142:145], v[198:201], 0
	v_mfma_f32_16x16x32_bf16 v[90:93], v[150:153], v[198:201], 0
	v_mfma_f32_16x16x32_bf16 v[78:81], v[142:145], v[206:209], 0
	v_mfma_f32_16x16x32_bf16 v[74:77], v[150:153], v[206:209], 0
	v_mfma_f32_16x16x32_bf16 v[126:129], v[146:149], v[186:189], v[126:129]
	v_mfma_f32_16x16x32_bf16 v[122:125], v[154:157], v[186:189], v[122:125]
	v_mfma_f32_16x16x32_bf16 v[110:113], v[146:149], v[194:197], v[110:113]
	v_mfma_f32_16x16x32_bf16 v[106:109], v[154:157], v[194:197], v[106:109]
	v_mfma_f32_16x16x32_bf16 v[94:97], v[146:149], v[202:205], v[94:97]
	v_mfma_f32_16x16x32_bf16 v[90:93], v[154:157], v[202:205], v[90:93]
	v_mfma_f32_16x16x32_bf16 v[78:81], v[146:149], v[210:213], v[78:81]
	v_mfma_f32_16x16x32_bf16 v[74:77], v[154:157], v[210:213], v[74:77]
	s_setprio 2
	s_setprio 0
	v_mfma_f32_16x16x32_bf16 v[118:121], v[158:161], v[182:185], 0
	v_mfma_f32_16x16x32_bf16 v[114:117], v[174:177], v[182:185], 0
	v_mfma_f32_16x16x32_bf16 v[102:105], v[158:161], v[190:193], 0
	v_mfma_f32_16x16x32_bf16 v[98:101], v[174:177], v[190:193], 0
	v_mfma_f32_16x16x32_bf16 v[86:89], v[158:161], v[198:201], 0
	v_mfma_f32_16x16x32_bf16 v[82:85], v[174:177], v[198:201], 0
	v_mfma_f32_16x16x32_bf16 v[70:73], v[158:161], v[206:209], 0
	v_mfma_f32_16x16x32_bf16 v[66:69], v[174:177], v[206:209], 0
	v_mfma_f32_16x16x32_bf16 v[118:121], v[170:173], v[186:189], v[118:121]
	v_mfma_f32_16x16x32_bf16 v[114:117], v[178:181], v[186:189], v[114:117]
	v_mfma_f32_16x16x32_bf16 v[102:105], v[170:173], v[194:197], v[102:105]
	v_mfma_f32_16x16x32_bf16 v[98:101], v[178:181], v[194:197], v[98:101]
	v_mfma_f32_16x16x32_bf16 v[86:89], v[170:173], v[202:205], v[86:89]
	v_mfma_f32_16x16x32_bf16 v[82:85], v[178:181], v[202:205], v[82:85]
	v_mfma_f32_16x16x32_bf16 v[70:73], v[170:173], v[210:213], v[70:73]
	v_mfma_f32_16x16x32_bf16 v[66:69], v[178:181], v[210:213], v[66:69]
	s_setprio 2
	s_barrier
	s_mov_b32 m0, s63
	v_lshl_add_u64 v[162:163], s[54:55], 0, v[134:135]
	ds_read_b128 v[182:185], v168 offset:16384
	ds_read_b128 v[186:189], v168 offset:17408
	ds_read_b128 v[190:193], v168 offset:18432
	ds_read_b128 v[194:197], v168 offset:19456
	ds_read_b128 v[198:201], v168 offset:20480
	ds_read_b128 v[202:205], v168 offset:21504
	ds_read_b128 v[206:209], v168 offset:22528
	ds_read_b128 v[210:213], v168 offset:23552
	global_load_lds_dwordx4 v[162:163], off
	v_lshl_add_u64 v[214:215], s[54:55], 0, v[130:131]
	s_mov_b32 m0, s74
	v_lshl_add_u64 v[216:217], s[56:57], 0, v[134:135]
	global_load_lds_dwordx4 v[214:215], off
	s_mov_b32 m0, s62
	v_lshl_add_u64 v[218:219], s[52:53], 0, v[132:133]
	global_load_lds_dwordx4 v[216:217], off
	v_lshl_add_u64 v[216:217], s[56:57], 0, v[130:131]
	s_mov_b32 m0, s75
	s_nop 0
	global_load_lds_dwordx4 v[216:217], off
	v_lshl_add_u64 v[216:217], s[52:53], 0, v[136:137]
	s_mov_b32 m0, s68
	s_nop 0
	global_load_lds_dwordx4 v[216:217], off
	s_mov_b32 m0, s69
	s_nop 0
	global_load_lds_dwordx4 v[218:219], off
	s_waitcnt vmcnt(8)
	s_waitcnt lgkmcnt(0)
	s_barrier
; #define PG8_STAGE(bufoff, gbase, voff) do { _Pragma("unroll") for (int _i = 0; _i < 2; ++_i) \
;         __builtin_amdgcn_global_load_lds((const unsigned*)((const char*)(gbase) + (voff)[_i]), (LAS unsigned*)(lds + (bufoff) + ldsw + _i * 8192), 16, 0, 0); } while (0)
; #define PG8_LDA(dst, b, h) do { _Pragma("unroll") for (int m = 0; m < 4; ++m) _Pragma("unroll") for (int k = 0; k < 2; ++k) dst[m][k] = *(const LAS bf16x8*)(lds + PG8_SA(b, h) + aoff + m * 2048 + k * 1024); } while (0)
; #define PG8_LDB(dst, b, h) do { _Pragma("unroll") for (int n = 0; n < 2; ++n) _Pragma("unroll") for (int k = 0; k < 2; ++k) dst[n][k] = *(const LAS bf16x8*)(lds + PG8_SB(b, h) + boff + n * 2048 + k * 1024); } while (0)
; #define PG8_MMA(ai, bj, At, Bt) do { __builtin_amdgcn_s_setprio(1); _Pragma("unroll") for (int m = 0; m < 4; ++m) _Pragma("unroll") for (int n = 0; n < 2; ++n) _Pragma("unroll") for (int k = 0; k < 2; ++k) \
;         acc[ai][bj][m][n] = __builtin_amdgcn_mfma_f32_16x16x32_bf16(Bt[n][k], At[m][k], acc[ai][bj][m][n], 0, 0, 0); __builtin_amdgcn_s_setprio(0); } while (0)
; #define PG8_WAIT_V(n) asm volatile("s_waitcnt vmcnt(" #n ")" ::: "memory")
; #define PG8_WAIT_L(n) asm volatile("s_waitcnt lgkmcnt(" #n ")" ::: "memory")
; #define PG8_BAR __builtin_amdgcn_s_barrier()
; #define PG8_SCHED __builtin_amdgcn_sched_barrier(0)
; template <class Epi>
; __device__ __forceinline__ void gemm_phase(LAS unsigned char* lds, const Gemm g, int G, int c, const Epi& E) {
;     ...
;             PG8_WAIT_V(8); PG8_WAIT_L(0); PG8_BAR; PG8_MMA(0, 0, At, B0); PG8_MMA(0, 1, At, B1); PG8_BAR; PG8_SCHED;
;             PG8_LDA(At, 0, 1); PG8_STAGE(PG8_SB(0, 0), b2, voffB); PG8_STAGE(PG8_SB(0, 1), b2 + hstepB, voffB); PG8_STAGE(PG8_SA(0, 0), a2, voffA);
;             PG8_WAIT_V(8); PG8_WAIT_L(0); PG8_BAR; PG8_MMA(1, 0, At, B0); PG8_MMA(1, 1, At, B1); PG8_BAR; PG8_SCHED;
;             PG8_LDB(B0, 1, 0); PG8_LDB(B1, 1, 1); PG8_SCHED; PG8_LDA(At, 1, 0); PG8_STAGE(PG8_SA(0, 1), a2 + hstepA, voffA);
;             PG8_WAIT_V(8); PG8_WAIT_L(0); PG8_BAR; PG8_MMA(0, 0, At, B0); PG8_MMA(0, 1, At, B1); PG8_BAR; PG8_SCHED;
	s_setprio 0
	v_mfma_f32_16x16x32_bf16 v[62:65], v[142:145], v[182:185], 0
	v_mfma_f32_16x16x32_bf16 v[58:61], v[150:153], v[182:185], 0
	v_mfma_f32_16x16x32_bf16 v[46:49], v[142:145], v[190:193], 0
	v_mfma_f32_16x16x32_bf16 v[42:45], v[150:153], v[190:193], 0
	v_mfma_f32_16x16x32_bf16 v[30:33], v[142:145], v[198:201], 0
	v_mfma_f32_16x16x32_bf16 v[26:29], v[150:153], v[198:201], 0
	v_mfma_f32_16x16x32_bf16 v[14:17], v[142:145], v[206:209], 0
	v_mfma_f32_16x16x32_bf16 v[10:13], v[150:153], v[206:209], 0
	v_mfma_f32_16x16x32_bf16 v[62:65], v[146:149], v[186:189], v[62:65]
	v_mfma_f32_16x16x32_bf16 v[58:61], v[154:157], v[186:189], v[58:61]
	v_mfma_f32_16x16x32_bf16 v[46:49], v[146:149], v[194:197], v[46:49]
	v_mfma_f32_16x16x32_bf16 v[42:45], v[154:157], v[194:197], v[42:45]
	v_mfma_f32_16x16x32_bf16 v[30:33], v[146:149], v[202:205], v[30:33]
	v_mfma_f32_16x16x32_bf16 v[26:29], v[154:157], v[202:205], v[26:29]
	v_mfma_f32_16x16x32_bf16 v[14:17], v[146:149], v[210:213], v[14:17]
	v_mfma_f32_16x16x32_bf16 v[10:13], v[154:157], v[210:213], v[10:13]
	s_setprio 2
	s_setprio 0
	v_mfma_f32_16x16x32_bf16 v[54:57], v[158:161], v[182:185], 0
	v_mfma_f32_16x16x32_bf16 v[50:53], v[174:177], v[182:185], 0
	v_mfma_f32_16x16x32_bf16 v[38:41], v[158:161], v[190:193], 0
	v_mfma_f32_16x16x32_bf16 v[34:37], v[174:177], v[190:193], 0
	v_mfma_f32_16x16x32_bf16 v[22:25], v[158:161], v[198:201], 0
	v_mfma_f32_16x16x32_bf16 v[18:21], v[174:177], v[198:201], 0
	v_mfma_f32_16x16x32_bf16 v[6:9], v[158:161], v[206:209], 0
	v_mfma_f32_16x16x32_bf16 v[2:5], v[174:177], v[206:209], 0
	v_mfma_f32_16x16x32_bf16 v[54:57], v[170:173], v[186:189], v[54:57]
	v_mfma_f32_16x16x32_bf16 v[50:53], v[178:181], v[186:189], v[50:53]
	v_mfma_f32_16x16x32_bf16 v[38:41], v[170:173], v[194:197], v[38:41]
	v_mfma_f32_16x16x32_bf16 v[34:37], v[178:181], v[194:197], v[34:37]
	v_mfma_f32_16x16x32_bf16 v[22:25], v[170:173], v[202:205], v[22:25]
	v_mfma_f32_16x16x32_bf16 v[18:21], v[178:181], v[202:205], v[18:21]
	v_mfma_f32_16x16x32_bf16 v[6:9], v[170:173], v[210:213], v[6:9]
	v_mfma_f32_16x16x32_bf16 v[2:5], v[178:181], v[210:213], v[2:5]
	s_setprio 2
	s_barrier
	v_add_u32_e32 v154, s93, v165
	v_add_u32_e32 v178, s33, v165
	ds_read_b128 v[142:145], v154
	ds_read_b128 v[146:149], v154 offset:1024
	ds_read_b128 v[150:153], v154 offset:2048
	ds_read_b128 v[154:157], v154 offset:3072
	ds_read_b128 v[158:161], v178
	ds_read_b128 v[170:173], v178 offset:1024
	ds_read_b128 v[174:177], v178 offset:2048
	ds_read_b128 v[178:181], v178 offset:3072
	s_mov_b32 m0, s70
	v_lshl_add_u64 v[220:221], s[48:49], 0, v[136:137]
	ds_read_b128 v[182:185], v168 offset:32768
	ds_read_b128 v[186:189], v168 offset:33792
	ds_read_b128 v[190:193], v168 offset:34816
	ds_read_b128 v[194:197], v168 offset:35840
	ds_read_b128 v[198:201], v168 offset:36864
	ds_read_b128 v[202:205], v168 offset:37888
	ds_read_b128 v[206:209], v168 offset:38912
	ds_read_b128 v[210:213], v168 offset:39936
	global_load_lds_dwordx4 v[220:221], off
	v_lshl_add_u64 v[220:221], s[48:49], 0, v[132:133]
	s_mov_b32 m0, s71
	s_nop 0
	global_load_lds_dwordx4 v[220:221], off
	s_waitcnt vmcnt(8)
	s_waitcnt lgkmcnt(0)
	s_barrier
	s_setprio 0
	v_mfma_f32_16x16x32_bf16 v[126:129], v[142:145], v[182:185], v[126:129]
	v_mfma_f32_16x16x32_bf16 v[122:125], v[150:153], v[182:185], v[122:125]
	v_mfma_f32_16x16x32_bf16 v[110:113], v[142:145], v[190:193], v[110:113]
	v_mfma_f32_16x16x32_bf16 v[106:109], v[150:153], v[190:193], v[106:109]
	v_mfma_f32_16x16x32_bf16 v[94:97], v[142:145], v[198:201], v[94:97]
	v_mfma_f32_16x16x32_bf16 v[90:93], v[150:153], v[198:201], v[90:93]
	v_mfma_f32_16x16x32_bf16 v[78:81], v[142:145], v[206:209], v[78:81]
	v_mfma_f32_16x16x32_bf16 v[74:77], v[150:153], v[206:209], v[74:77]
	v_mfma_f32_16x16x32_bf16 v[126:129], v[146:149], v[186:189], v[126:129]
	v_mfma_f32_16x16x32_bf16 v[122:125], v[154:157], v[186:189], v[122:125]
	v_mfma_f32_16x16x32_bf16 v[110:113], v[146:149], v[194:197], v[110:113]
	v_mfma_f32_16x16x32_bf16 v[106:109], v[154:157], v[194:197], v[106:109]
	v_mfma_f32_16x16x32_bf16 v[94:97], v[146:149], v[202:205], v[94:97]
	v_mfma_f32_16x16x32_bf16 v[90:93], v[154:157], v[202:205], v[90:93]
	v_mfma_f32_16x16x32_bf16 v[78:81], v[146:149], v[210:213], v[78:81]
	v_mfma_f32_16x16x32_bf16 v[74:77], v[154:157], v[210:213], v[74:77]
	s_setprio 2
	s_setprio 0
	v_mfma_f32_16x16x32_bf16 v[118:121], v[158:161], v[182:185], v[118:121]
	v_mfma_f32_16x16x32_bf16 v[114:117], v[174:177], v[182:185], v[114:117]
	v_mfma_f32_16x16x32_bf16 v[102:105], v[158:161], v[190:193], v[102:105]
	v_mfma_f32_16x16x32_bf16 v[98:101], v[174:177], v[190:193], v[98:101]
	v_mfma_f32_16x16x32_bf16 v[86:89], v[158:161], v[198:201], v[86:89]
	v_mfma_f32_16x16x32_bf16 v[82:85], v[174:177], v[198:201], v[82:85]
	v_mfma_f32_16x16x32_bf16 v[70:73], v[158:161], v[206:209], v[70:73]
	v_mfma_f32_16x16x32_bf16 v[66:69], v[174:177], v[206:209], v[66:69]
	v_mfma_f32_16x16x32_bf16 v[118:121], v[170:173], v[186:189], v[118:121]
	v_mfma_f32_16x16x32_bf16 v[114:117], v[178:181], v[186:189], v[114:117]
	v_mfma_f32_16x16x32_bf16 v[102:105], v[170:173], v[194:197], v[102:105]
	v_mfma_f32_16x16x32_bf16 v[98:101], v[178:181], v[194:197], v[98:101]
	v_mfma_f32_16x16x32_bf16 v[86:89], v[170:173], v[202:205], v[86:89]
	v_mfma_f32_16x16x32_bf16 v[82:85], v[178:181], v[202:205], v[82:85]
	v_mfma_f32_16x16x32_bf16 v[70:73], v[170:173], v[210:213], v[70:73]
	v_mfma_f32_16x16x32_bf16 v[66:69], v[178:181], v[210:213], v[66:69]
	s_setprio 2
	s_barrier
; #define PG8_STAGE(bufoff, gbase, voff) do { _Pragma("unroll") for (int _i = 0; _i < 2; ++_i) \
;         __builtin_amdgcn_global_load_lds((const unsigned*)((const char*)(gbase) + (voff)[_i]), (LAS unsigned*)(lds + (bufoff) + ldsw + _i * 8192), 16, 0, 0); } while (0)
; #define PG8_LDA(dst, b, h) do { _Pragma("unroll") for (int m = 0; m < 4; ++m) _Pragma("unroll") for (int k = 0; k < 2; ++k) dst[m][k] = *(const LAS bf16x8*)(lds + PG8_SA(b, h) + aoff + m * 2048 + k * 1024); } while (0)
; #define PG8_LDB(dst, b, h) do { _Pragma("unroll") for (int n = 0; n < 2; ++n) _Pragma("unroll") for (int k = 0; k < 2; ++k) dst[n][k] = *(const LAS bf16x8*)(lds + PG8_SB(b, h) + boff + n * 2048 + k * 1024); } while (0)
; #define PG8_WAIT_V(n) asm volatile("s_waitcnt vmcnt(" #n ")" ::: "memory")
; #define PG8_WAIT_L(n) asm volatile("s_waitcnt lgkmcnt(" #n ")" ::: "memory")
; template <class Epi>
; __device__ __forceinline__ void gemm_phase(LAS unsigned char* lds, const Gemm g, int G, int c, const Epi& E) {
;     ...
;         for (int t = 0; t < nt; t += 2) {
;             const bool last = (t == nt - 2);
;             const char* a1 = cA + (size_t)(t + 1) * kstep;
;             const char* a2 = last ? nA : cA + (size_t)(t + 2) * kstep; const char* b2 = last ? nB : cB + (size_t)(t + 2) * kstep;
;             const char* a3 = a2 + kstep; const char* b3 = b2 + kstep;
;             PG8_LDB(B0, 0, 0); PG8_LDB(B1, 0, 1); PG8_SCHED; PG8_LDA(At, 0, 0); PG8_STAGE(PG8_SA(1, 1), a1 + hstepA, voffA);
;             PG8_WAIT_V(8); PG8_WAIT_L(0); PG8_BAR; PG8_MMA(0, 0, At, B0); PG8_MMA(0, 1, At, B1); PG8_BAR; PG8_SCHED;
;             PG8_LDA(At, 0, 1); PG8_STAGE(PG8_SB(0, 0), b2, voffB); PG8_STAGE(PG8_SB(0, 1), b2 + hstepB, voffB); PG8_STAGE(PG8_SA(0, 0), a2, voffA);
;             PG8_WAIT_V(8); PG8_WAIT_L(0); PG8_BAR; PG8_MMA(1, 0, At, B0); PG8_MMA(1, 1, At, B1); PG8_BAR; PG8_SCHED;
;             PG8_LDB(B0, 1, 0); PG8_LDB(B1, 1, 1); PG8_SCHED; PG8_LDA(At, 1, 0); PG8_STAGE(PG8_SA(0, 1), a2 + hstepA, voffA);
;             PG8_WAIT_V(8); PG8_WAIT_L(0); PG8_BAR; PG8_MMA(0, 0, At, B0); PG8_MMA(0, 1, At, B1); PG8_BAR; PG8_SCHED;
;             PG8_LDA(At, 1, 1); PG8_STAGE(PG8_SB(1, 0), b3, voffB); PG8_STAGE(PG8_SB(1, 1), b3 + hstepB, voffB); PG8_STAGE(PG8_SA(1, 0), a3, voffA);
;             PG8_WAIT_V(8); PG8_WAIT_L(0); PG8_BAR; PG8_MMA(1, 0, At, B0); PG8_MMA(1, 1, At, B1); PG8_BAR; PG8_SCHED;
	s_mov_b32 m0, s92
	v_lshl_add_u64 v[162:163], v[162:163], 0, s[18:19]
	ds_read_b128 v[182:185], v168 offset:49152
	ds_read_b128 v[186:189], v168 offset:50176
	ds_read_b128 v[190:193], v168 offset:51200
	ds_read_b128 v[194:197], v168 offset:52224
	ds_read_b128 v[198:201], v168 offset:53248
	ds_read_b128 v[202:205], v168 offset:54272
	ds_read_b128 v[206:209], v168 offset:55296
	ds_read_b128 v[210:213], v168 offset:56320
	global_load_lds_dwordx4 v[162:163], off
	v_lshl_add_u64 v[162:163], v[214:215], 0, s[18:19]
	s_mov_b32 m0, s90
	s_nop 0
	global_load_lds_dwordx4 v[162:163], off
	v_lshl_add_u64 v[162:163], s[46:47], 0, v[134:135]
	s_mov_b32 m0, s91
	s_nop 0
	global_load_lds_dwordx4 v[162:163], off
	v_lshl_add_u64 v[162:163], s[46:47], 0, v[130:131]
	s_mov_b32 m0, s89
	s_nop 0
	global_load_lds_dwordx4 v[162:163], off
	v_lshl_add_u64 v[162:163], v[216:217], 0, s[18:19]
	s_mov_b32 m0, s78
	s_nop 0
	global_load_lds_dwordx4 v[162:163], off
	v_lshl_add_u64 v[162:163], v[218:219], 0, s[18:19]
	s_mov_b32 m0, s79
	s_nop 0
	global_load_lds_dwordx4 v[162:163], off
	s_waitcnt vmcnt(8)
	s_waitcnt lgkmcnt(0)
	s_barrier
	s_setprio 0
	v_mfma_f32_16x16x32_bf16 v[62:65], v[142:145], v[182:185], v[62:65]
	v_mfma_f32_16x16x32_bf16 v[58:61], v[150:153], v[182:185], v[58:61]
	v_mfma_f32_16x16x32_bf16 v[46:49], v[142:145], v[190:193], v[46:49]
	v_mfma_f32_16x16x32_bf16 v[42:45], v[150:153], v[190:193], v[42:45]
	v_mfma_f32_16x16x32_bf16 v[30:33], v[142:145], v[198:201], v[30:33]
	v_mfma_f32_16x16x32_bf16 v[26:29], v[150:153], v[198:201], v[26:29]
	v_mfma_f32_16x16x32_bf16 v[14:17], v[142:145], v[206:209], v[14:17]
	v_mfma_f32_16x16x32_bf16 v[10:13], v[150:153], v[206:209], v[10:13]
	v_mfma_f32_16x16x32_bf16 v[62:65], v[146:149], v[186:189], v[62:65]
	v_mfma_f32_16x16x32_bf16 v[58:61], v[154:157], v[186:189], v[58:61]
	v_mfma_f32_16x16x32_bf16 v[46:49], v[146:149], v[194:197], v[46:49]
	v_mfma_f32_16x16x32_bf16 v[42:45], v[154:157], v[194:197], v[42:45]
	v_mfma_f32_16x16x32_bf16 v[30:33], v[146:149], v[202:205], v[30:33]
	v_mfma_f32_16x16x32_bf16 v[26:29], v[154:157], v[202:205], v[26:29]
	v_mfma_f32_16x16x32_bf16 v[14:17], v[146:149], v[210:213], v[14:17]
	v_mfma_f32_16x16x32_bf16 v[10:13], v[154:157], v[210:213], v[10:13]
	s_setprio 2
	s_setprio 0
	v_mfma_f32_16x16x32_bf16 v[54:57], v[158:161], v[182:185], v[54:57]
	v_mfma_f32_16x16x32_bf16 v[50:53], v[174:177], v[182:185], v[50:53]
	v_mfma_f32_16x16x32_bf16 v[38:41], v[158:161], v[190:193], v[38:41]
	v_mfma_f32_16x16x32_bf16 v[34:37], v[174:177], v[190:193], v[34:37]
	v_mfma_f32_16x16x32_bf16 v[22:25], v[158:161], v[198:201], v[22:25]
	v_mfma_f32_16x16x32_bf16 v[18:21], v[174:177], v[198:201], v[18:21]
	v_mfma_f32_16x16x32_bf16 v[6:9], v[158:161], v[206:209], v[6:9]
	v_mfma_f32_16x16x32_bf16 v[2:5], v[174:177], v[206:209], v[2:5]
	v_mfma_f32_16x16x32_bf16 v[54:57], v[170:173], v[186:189], v[54:57]
	v_mfma_f32_16x16x32_bf16 v[50:53], v[178:181], v[186:189], v[50:53]
	v_mfma_f32_16x16x32_bf16 v[38:41], v[170:173], v[194:197], v[38:41]
	v_mfma_f32_16x16x32_bf16 v[34:37], v[178:181], v[194:197], v[34:37]
	v_mfma_f32_16x16x32_bf16 v[22:25], v[170:173], v[202:205], v[22:25]
	v_mfma_f32_16x16x32_bf16 v[18:21], v[178:181], v[202:205], v[18:21]
	v_mfma_f32_16x16x32_bf16 v[6:9], v[170:173], v[210:213], v[6:9]
	v_mfma_f32_16x16x32_bf16 v[2:5], v[178:181], v[210:213], v[2:5]
	s_setprio 2
	s_barrier
	s_movk_i32 s48, 0x100
	s_andn2_b64 vcc, exec, s[4:5]
	s_mov_b64 s[46:47], -1
	s_mov_b64 s[4:5], 0
	s_cbranch_vccz .LBB0_1653
.LBB0_1653:
	s_add_u32 s33, s8, s48
	s_addc_u32 s49, s9, 0
	s_add_u32 s54, s33, 0x100
	s_addc_u32 s55, s49, 0
	s_and_b64 s[52:53], s[46:47], exec
	s_cselect_b32 s53, s41, s55
	s_cselect_b32 s52, s40, s54
	s_add_u32 s48, s6, s48
	s_addc_u32 s54, s7, 0
	s_add_u32 s48, s48, 0x100
	s_addc_u32 s54, s54, 0
	s_and_b64 s[46:47], s[46:47], exec
	s_cselect_b32 s55, s43, s54
	s_cselect_b32 s54, s42, s48
	s_add_u32 s58, s33, 0xb0080
	ds_read_b128 v[142:145], v166
	ds_read_b128 v[146:149], v166 offset:1024
	ds_read_b128 v[150:153], v166 offset:2048
	ds_read_b128 v[154:157], v166 offset:3072
	ds_read_b128 v[158:161], v167
	ds_read_b128 v[170:173], v167 offset:1024
	ds_read_b128 v[174:177], v167 offset:2048
	ds_read_b128 v[178:181], v167 offset:3072
	s_addc_u32 s59, s49, 0
	s_add_i32 s63, s80, s23
	s_add_i32 m0, s68, 0xc000
	s_add_i32 s64, s68, 0xe000
	s_add_i32 s74, s63, 0x2000
	s_add_u32 s56, s54, 0xb0000
	s_addc_u32 s57, s55, 0
	s_add_i32 s62, s81, s23
	s_add_i32 s75, s62, 0x2000
	s_add_i32 s93, 0, 0x18000
	s_add_i32 s33, 0, 0x1c000
	s_add_u32 s48, s52, 0xb0000
	s_addc_u32 s49, s53, 0
	s_add_i32 s92, s93, s23
	s_add_i32 s90, s92, 0x2000
	s_add_u32 s46, s54, 0xb0080
	s_addc_u32 s47, s55, 0
	s_add_i32 s91, s33, s23
	s_add_i32 s89, s91, 0x2000
	v_lshl_add_u64 v[162:163], s[58:59], 0, v[136:137]
	ds_read_b128 v[182:185], v168
	ds_read_b128 v[186:189], v168 offset:1024
	ds_read_b128 v[190:193], v168 offset:2048
	ds_read_b128 v[194:197], v168 offset:3072
	ds_read_b128 v[198:201], v168 offset:4096
	ds_read_b128 v[202:205], v168 offset:5120
	ds_read_b128 v[206:209], v168 offset:6144
	ds_read_b128 v[210:213], v168 offset:7168
	global_load_lds_dwordx4 v[162:163], off
	v_lshl_add_u64 v[162:163], s[58:59], 0, v[132:133]
	s_mov_b32 m0, s64
	s_nop 0
	global_load_lds_dwordx4 v[162:163], off
	s_waitcnt vmcnt(8)
	s_waitcnt lgkmcnt(0)
	s_barrier
; #define PG8_STAGE(bufoff, gbase, voff) do { _Pragma("unroll") for (int _i = 0; _i < 2; ++_i) \
;         __builtin_amdgcn_global_load_lds((const unsigned*)((const char*)(gbase) + (voff)[_i]), (LAS unsigned*)(lds + (bufoff) + ldsw + _i * 8192), 16, 0, 0); } while (0)
; #define PG8_LDA(dst, b, h) do { _Pragma("unroll") for (int m = 0; m < 4; ++m) _Pragma("unroll") for (int k = 0; k < 2; ++k) dst[m][k] = *(const LAS bf16x8*)(lds + PG8_SA(b, h) + aoff + m * 2048 + k * 1024); } while (0)
; #define PG8_LDB(dst, b, h) do { _Pragma("unroll") for (int n = 0; n < 2; ++n) _Pragma("unroll") for (int k = 0; k < 2; ++k) dst[n][k] = *(const LAS bf16x8*)(lds + PG8_SB(b, h) + boff + n * 2048 + k * 1024); } while (0)
; #define PG8_MMA(ai, bj, At, Bt) do { __builtin_amdgcn_s_setprio(1); _Pragma("unroll") for (int m = 0; m < 4; ++m) _Pragma("unroll") for (int n = 0; n < 2; ++n) _Pragma("unroll") for (int k = 0; k < 2; ++k) \
;         acc[ai][bj][m][n] = __builtin_amdgcn_mfma_f32_16x16x32_bf16(Bt[n][k], At[m][k], acc[ai][bj][m][n], 0, 0, 0); __builtin_amdgcn_s_setprio(0); } while (0)
; #define PG8_WAIT_V(n) asm volatile("s_waitcnt vmcnt(" #n ")" ::: "memory")
; #define PG8_WAIT_L(n) asm volatile("s_waitcnt lgkmcnt(" #n ")" ::: "memory")
; #define PG8_BAR __builtin_amdgcn_s_barrier()
; #define PG8_SCHED __builtin_amdgcn_sched_barrier(0)
; template <class Epi>
; __device__ __forceinline__ void gemm_phase(LAS unsigned char* lds, const Gemm g, int G, int c, const Epi& E) {
;     ...
;             PG8_LDB(B0, 0, 0); PG8_LDB(B1, 0, 1); PG8_SCHED; PG8_LDA(At, 0, 0); PG8_STAGE(PG8_SA(1, 1), a1 + hstepA, voffA);
;             PG8_WAIT_V(8); PG8_WAIT_L(0); PG8_BAR; PG8_MMA(0, 0, At, B0); PG8_MMA(0, 1, At, B1); PG8_BAR; PG8_SCHED;
;             PG8_LDA(At, 0, 1); PG8_STAGE(PG8_SB(0, 0), b2, voffB); PG8_STAGE(PG8_SB(0, 1), b2 + hstepB, voffB); PG8_STAGE(PG8_SA(0, 0), a2, voffA);
;             PG8_WAIT_V(8); PG8_WAIT_L(0); PG8_BAR; PG8_MMA(1, 0, At, B0); PG8_MMA(1, 1, At, B1); PG8_BAR; PG8_SCHED;
	s_setprio 0
	v_mfma_f32_16x16x32_bf16 v[126:129], v[142:145], v[182:185], v[126:129]
	v_mfma_f32_16x16x32_bf16 v[122:125], v[150:153], v[182:185], v[122:125]
	v_mfma_f32_16x16x32_bf16 v[110:113], v[142:145], v[190:193], v[110:113]
	v_mfma_f32_16x16x32_bf16 v[106:109], v[150:153], v[190:193], v[106:109]
	v_mfma_f32_16x16x32_bf16 v[94:97], v[142:145], v[198:201], v[94:97]
	v_mfma_f32_16x16x32_bf16 v[90:93], v[150:153], v[198:201], v[90:93]
	v_mfma_f32_16x16x32_bf16 v[78:81], v[142:145], v[206:209], v[78:81]
	v_mfma_f32_16x16x32_bf16 v[74:77], v[150:153], v[206:209], v[74:77]
	v_mfma_f32_16x16x32_bf16 v[126:129], v[146:149], v[186:189], v[126:129]
	v_mfma_f32_16x16x32_bf16 v[122:125], v[154:157], v[186:189], v[122:125]
	v_mfma_f32_16x16x32_bf16 v[110:113], v[146:149], v[194:197], v[110:113]
	v_mfma_f32_16x16x32_bf16 v[106:109], v[154:157], v[194:197], v[106:109]
	v_mfma_f32_16x16x32_bf16 v[94:97], v[146:149], v[202:205], v[94:97]
	v_mfma_f32_16x16x32_bf16 v[90:93], v[154:157], v[202:205], v[90:93]
	v_mfma_f32_16x16x32_bf16 v[78:81], v[146:149], v[210:213], v[78:81]
	v_mfma_f32_16x16x32_bf16 v[74:77], v[154:157], v[210:213], v[74:77]
	s_setprio 2
	s_setprio 0
	v_mfma_f32_16x16x32_bf16 v[118:121], v[158:161], v[182:185], v[118:121]
	v_mfma_f32_16x16x32_bf16 v[114:117], v[174:177], v[182:185], v[114:117]
	v_mfma_f32_16x16x32_bf16 v[102:105], v[158:161], v[190:193], v[102:105]
	v_mfma_f32_16x16x32_bf16 v[98:101], v[174:177], v[190:193], v[98:101]
	v_mfma_f32_16x16x32_bf16 v[86:89], v[158:161], v[198:201], v[86:89]
	v_mfma_f32_16x16x32_bf16 v[82:85], v[174:177], v[198:201], v[82:85]
	v_mfma_f32_16x16x32_bf16 v[70:73], v[158:161], v[206:209], v[70:73]
	v_mfma_f32_16x16x32_bf16 v[66:69], v[174:177], v[206:209], v[66:69]
	v_mfma_f32_16x16x32_bf16 v[118:121], v[170:173], v[186:189], v[118:121]
	v_mfma_f32_16x16x32_bf16 v[114:117], v[178:181], v[186:189], v[114:117]
	v_mfma_f32_16x16x32_bf16 v[102:105], v[170:173], v[194:197], v[102:105]
	v_mfma_f32_16x16x32_bf16 v[98:101], v[178:181], v[194:197], v[98:101]
	v_mfma_f32_16x16x32_bf16 v[86:89], v[170:173], v[202:205], v[86:89]
	v_mfma_f32_16x16x32_bf16 v[82:85], v[178:181], v[202:205], v[82:85]
	v_mfma_f32_16x16x32_bf16 v[70:73], v[170:173], v[210:213], v[70:73]
	v_mfma_f32_16x16x32_bf16 v[66:69], v[178:181], v[210:213], v[66:69]
	s_setprio 2
	s_barrier
	s_mov_b32 m0, s63
	v_lshl_add_u64 v[162:163], s[54:55], 0, v[134:135]
	ds_read_b128 v[182:185], v168 offset:16384
	ds_read_b128 v[186:189], v168 offset:17408
	ds_read_b128 v[190:193], v168 offset:18432
	ds_read_b128 v[194:197], v168 offset:19456
	ds_read_b128 v[198:201], v168 offset:20480
	ds_read_b128 v[202:205], v168 offset:21504
	ds_read_b128 v[206:209], v168 offset:22528
	ds_read_b128 v[210:213], v168 offset:23552
	global_load_lds_dwordx4 v[162:163], off
	v_lshl_add_u64 v[214:215], s[54:55], 0, v[130:131]
	s_mov_b32 m0, s74
	v_lshl_add_u64 v[216:217], s[56:57], 0, v[134:135]
	global_load_lds_dwordx4 v[214:215], off
	s_mov_b32 m0, s62
	v_lshl_add_u64 v[218:219], s[52:53], 0, v[132:133]
	global_load_lds_dwordx4 v[216:217], off
	v_lshl_add_u64 v[216:217], s[56:57], 0, v[130:131]
	s_mov_b32 m0, s75
	s_nop 0
	global_load_lds_dwordx4 v[216:217], off
	v_lshl_add_u64 v[216:217], s[52:53], 0, v[136:137]
	s_mov_b32 m0, s68
	s_nop 0
	global_load_lds_dwordx4 v[216:217], off
	s_mov_b32 m0, s69
	s_nop 0
	global_load_lds_dwordx4 v[218:219], off
	s_waitcnt vmcnt(8)
	s_waitcnt lgkmcnt(0)
	s_barrier
	s_setprio 0
	v_mfma_f32_16x16x32_bf16 v[62:65], v[142:145], v[182:185], v[62:65]
	v_mfma_f32_16x16x32_bf16 v[58:61], v[150:153], v[182:185], v[58:61]
	v_mfma_f32_16x16x32_bf16 v[46:49], v[142:145], v[190:193], v[46:49]
	v_mfma_f32_16x16x32_bf16 v[42:45], v[150:153], v[190:193], v[42:45]
	v_mfma_f32_16x16x32_bf16 v[30:33], v[142:145], v[198:201], v[30:33]
	v_mfma_f32_16x16x32_bf16 v[26:29], v[150:153], v[198:201], v[26:29]
	v_mfma_f32_16x16x32_bf16 v[14:17], v[142:145], v[206:209], v[14:17]
	v_mfma_f32_16x16x32_bf16 v[10:13], v[150:153], v[206:209], v[10:13]
	v_mfma_f32_16x16x32_bf16 v[62:65], v[146:149], v[186:189], v[62:65]
	v_mfma_f32_16x16x32_bf16 v[58:61], v[154:157], v[186:189], v[58:61]
	v_mfma_f32_16x16x32_bf16 v[46:49], v[146:149], v[194:197], v[46:49]
	v_mfma_f32_16x16x32_bf16 v[42:45], v[154:157], v[194:197], v[42:45]
	v_mfma_f32_16x16x32_bf16 v[30:33], v[146:149], v[202:205], v[30:33]
	v_mfma_f32_16x16x32_bf16 v[26:29], v[154:157], v[202:205], v[26:29]
	v_mfma_f32_16x16x32_bf16 v[14:17], v[146:149], v[210:213], v[14:17]
	v_mfma_f32_16x16x32_bf16 v[10:13], v[154:157], v[210:213], v[10:13]
	s_setprio 2
	s_setprio 0
	v_mfma_f32_16x16x32_bf16 v[54:57], v[158:161], v[182:185], v[54:57]
	v_mfma_f32_16x16x32_bf16 v[50:53], v[174:177], v[182:185], v[50:53]
	v_mfma_f32_16x16x32_bf16 v[38:41], v[158:161], v[190:193], v[38:41]
	v_mfma_f32_16x16x32_bf16 v[34:37], v[174:177], v[190:193], v[34:37]
	v_mfma_f32_16x16x32_bf16 v[22:25], v[158:161], v[198:201], v[22:25]
	v_mfma_f32_16x16x32_bf16 v[18:21], v[174:177], v[198:201], v[18:21]
	v_mfma_f32_16x16x32_bf16 v[6:9], v[158:161], v[206:209], v[6:9]
	v_mfma_f32_16x16x32_bf16 v[2:5], v[174:177], v[206:209], v[2:5]
	v_mfma_f32_16x16x32_bf16 v[54:57], v[170:173], v[186:189], v[54:57]
	v_mfma_f32_16x16x32_bf16 v[50:53], v[178:181], v[186:189], v[50:53]
	v_mfma_f32_16x16x32_bf16 v[38:41], v[170:173], v[194:197], v[38:41]
	v_mfma_f32_16x16x32_bf16 v[34:37], v[178:181], v[194:197], v[34:37]
	v_mfma_f32_16x16x32_bf16 v[22:25], v[170:173], v[202:205], v[22:25]
	v_mfma_f32_16x16x32_bf16 v[18:21], v[178:181], v[202:205], v[18:21]
	v_mfma_f32_16x16x32_bf16 v[6:9], v[170:173], v[210:213], v[6:9]
	v_mfma_f32_16x16x32_bf16 v[2:5], v[178:181], v[210:213], v[2:5]
	s_setprio 2
	s_barrier
; #define PG8_STAGE(bufoff, gbase, voff) do { _Pragma("unroll") for (int _i = 0; _i < 2; ++_i) \
;         __builtin_amdgcn_global_load_lds((const unsigned*)((const char*)(gbase) + (voff)[_i]), (LAS unsigned*)(lds + (bufoff) + ldsw + _i * 8192), 16, 0, 0); } while (0)
; #define PG8_LDA(dst, b, h) do { _Pragma("unroll") for (int m = 0; m < 4; ++m) _Pragma("unroll") for (int k = 0; k < 2; ++k) dst[m][k] = *(const LAS bf16x8*)(lds + PG8_SA(b, h) + aoff + m * 2048 + k * 1024); } while (0)
; #define PG8_LDB(dst, b, h) do { _Pragma("unroll") for (int n = 0; n < 2; ++n) _Pragma("unroll") for (int k = 0; k < 2; ++k) dst[n][k] = *(const LAS bf16x8*)(lds + PG8_SB(b, h) + boff + n * 2048 + k * 1024); } while (0)
; #define PG8_MMA(ai, bj, At, Bt) do { __builtin_amdgcn_s_setprio(1); _Pragma("unroll") for (int m = 0; m < 4; ++m) _Pragma("unroll") for (int n = 0; n < 2; ++n) _Pragma("unroll") for (int k = 0; k < 2; ++k) \
;         acc[ai][bj][m][n] = __builtin_amdgcn_mfma_f32_16x16x32_bf16(Bt[n][k], At[m][k], acc[ai][bj][m][n], 0, 0, 0); __builtin_amdgcn_s_setprio(0); } while (0)
; #define PG8_WAIT_V(n) asm volatile("s_waitcnt vmcnt(" #n ")" ::: "memory")
; #define PG8_WAIT_L(n) asm volatile("s_waitcnt lgkmcnt(" #n ")" ::: "memory")
; #define PG8_BAR __builtin_amdgcn_s_barrier()
; #define PG8_SCHED __builtin_amdgcn_sched_barrier(0)
; template <class Epi>
; __device__ __forceinline__ void gemm_phase(LAS unsigned char* lds, const Gemm g, int G, int c, const Epi& E) {
;     ...
;             PG8_LDB(B0, 1, 0); PG8_LDB(B1, 1, 1); PG8_SCHED; PG8_LDA(At, 1, 0); PG8_STAGE(PG8_SA(0, 1), a2 + hstepA, voffA);
;             PG8_WAIT_V(8); PG8_WAIT_L(0); PG8_BAR; PG8_MMA(0, 0, At, B0); PG8_MMA(0, 1, At, B1); PG8_BAR; PG8_SCHED;
;             PG8_LDA(At, 1, 1); PG8_STAGE(PG8_SB(1, 0), b3, voffB); PG8_STAGE(PG8_SB(1, 1), b3 + hstepB, voffB); PG8_STAGE(PG8_SA(1, 0), a3, voffA);
;             PG8_WAIT_V(8); PG8_WAIT_L(0); PG8_BAR; PG8_MMA(1, 0, At, B0); PG8_MMA(1, 1, At, B1); PG8_BAR; PG8_SCHED;
;         }
;         if (wr == 0) PG8_BAR;
	v_add_u32_e32 v154, s93, v165
	v_add_u32_e32 v178, s33, v165
	ds_read_b128 v[142:145], v154
	ds_read_b128 v[146:149], v154 offset:1024
	ds_read_b128 v[150:153], v154 offset:2048
	ds_read_b128 v[154:157], v154 offset:3072
	ds_read_b128 v[158:161], v178
	ds_read_b128 v[170:173], v178 offset:1024
	ds_read_b128 v[174:177], v178 offset:2048
	ds_read_b128 v[178:181], v178 offset:3072
	s_mov_b32 m0, s70
	v_lshl_add_u64 v[220:221], s[48:49], 0, v[136:137]
	ds_read_b128 v[182:185], v168 offset:32768
	ds_read_b128 v[186:189], v168 offset:33792
	ds_read_b128 v[190:193], v168 offset:34816
	ds_read_b128 v[194:197], v168 offset:35840
	ds_read_b128 v[198:201], v168 offset:36864
	ds_read_b128 v[202:205], v168 offset:37888
	ds_read_b128 v[206:209], v168 offset:38912
	ds_read_b128 v[210:213], v168 offset:39936
	global_load_lds_dwordx4 v[220:221], off
	v_lshl_add_u64 v[220:221], s[48:49], 0, v[132:133]
	s_mov_b32 m0, s71
	s_nop 0
	global_load_lds_dwordx4 v[220:221], off
	s_waitcnt vmcnt(8)
	s_waitcnt lgkmcnt(0)
	s_barrier
	s_setprio 0
	v_mfma_f32_16x16x32_bf16 v[126:129], v[142:145], v[182:185], v[126:129]
	v_mfma_f32_16x16x32_bf16 v[122:125], v[150:153], v[182:185], v[122:125]
	v_mfma_f32_16x16x32_bf16 v[110:113], v[142:145], v[190:193], v[110:113]
	v_mfma_f32_16x16x32_bf16 v[106:109], v[150:153], v[190:193], v[106:109]
	v_mfma_f32_16x16x32_bf16 v[94:97], v[142:145], v[198:201], v[94:97]
	v_mfma_f32_16x16x32_bf16 v[90:93], v[150:153], v[198:201], v[90:93]
	v_mfma_f32_16x16x32_bf16 v[78:81], v[142:145], v[206:209], v[78:81]
	v_mfma_f32_16x16x32_bf16 v[74:77], v[150:153], v[206:209], v[74:77]
	v_mfma_f32_16x16x32_bf16 v[126:129], v[146:149], v[186:189], v[126:129]
	v_mfma_f32_16x16x32_bf16 v[122:125], v[154:157], v[186:189], v[122:125]
	v_mfma_f32_16x16x32_bf16 v[110:113], v[146:149], v[194:197], v[110:113]
	v_mfma_f32_16x16x32_bf16 v[106:109], v[154:157], v[194:197], v[106:109]
	v_mfma_f32_16x16x32_bf16 v[94:97], v[146:149], v[202:205], v[94:97]
	v_mfma_f32_16x16x32_bf16 v[90:93], v[154:157], v[202:205], v[90:93]
	v_mfma_f32_16x16x32_bf16 v[78:81], v[146:149], v[210:213], v[78:81]
	v_mfma_f32_16x16x32_bf16 v[74:77], v[154:157], v[210:213], v[74:77]
	s_setprio 2
	s_setprio 0
	v_mfma_f32_16x16x32_bf16 v[118:121], v[158:161], v[182:185], v[118:121]
	v_mfma_f32_16x16x32_bf16 v[114:117], v[174:177], v[182:185], v[114:117]
	v_mfma_f32_16x16x32_bf16 v[102:105], v[158:161], v[190:193], v[102:105]
	v_mfma_f32_16x16x32_bf16 v[98:101], v[174:177], v[190:193], v[98:101]
	v_mfma_f32_16x16x32_bf16 v[86:89], v[158:161], v[198:201], v[86:89]
	v_mfma_f32_16x16x32_bf16 v[82:85], v[174:177], v[198:201], v[82:85]
	v_mfma_f32_16x16x32_bf16 v[70:73], v[158:161], v[206:209], v[70:73]
	v_mfma_f32_16x16x32_bf16 v[66:69], v[174:177], v[206:209], v[66:69]
	v_mfma_f32_16x16x32_bf16 v[118:121], v[170:173], v[186:189], v[118:121]
	v_mfma_f32_16x16x32_bf16 v[114:117], v[178:181], v[186:189], v[114:117]
	v_mfma_f32_16x16x32_bf16 v[102:105], v[170:173], v[194:197], v[102:105]
	v_mfma_f32_16x16x32_bf16 v[98:101], v[178:181], v[194:197], v[98:101]
	v_mfma_f32_16x16x32_bf16 v[86:89], v[170:173], v[202:205], v[86:89]
	v_mfma_f32_16x16x32_bf16 v[82:85], v[178:181], v[202:205], v[82:85]
	v_mfma_f32_16x16x32_bf16 v[70:73], v[170:173], v[210:213], v[70:73]
	v_mfma_f32_16x16x32_bf16 v[66:69], v[178:181], v[210:213], v[66:69]
	s_setprio 2
	s_barrier
	s_mov_b32 m0, s92
	v_lshl_add_u64 v[162:163], v[162:163], 0, s[18:19]
	ds_read_b128 v[182:185], v168 offset:49152
	ds_read_b128 v[186:189], v168 offset:50176
	ds_read_b128 v[190:193], v168 offset:51200
	ds_read_b128 v[194:197], v168 offset:52224
	ds_read_b128 v[198:201], v168 offset:53248
	ds_read_b128 v[202:205], v168 offset:54272
	ds_read_b128 v[206:209], v168 offset:55296
	ds_read_b128 v[210:213], v168 offset:56320
	global_load_lds_dwordx4 v[162:163], off
	v_lshl_add_u64 v[162:163], v[214:215], 0, s[18:19]
	s_mov_b32 m0, s90
	s_nop 0
	global_load_lds_dwordx4 v[162:163], off
	v_lshl_add_u64 v[162:163], s[46:47], 0, v[134:135]
	s_mov_b32 m0, s91
	s_nop 0
	global_load_lds_dwordx4 v[162:163], off
	v_lshl_add_u64 v[162:163], s[46:47], 0, v[130:131]
	s_mov_b32 m0, s89
	s_nop 0
	global_load_lds_dwordx4 v[162:163], off
	v_lshl_add_u64 v[162:163], v[216:217], 0, s[18:19]
	s_mov_b32 m0, s78
	s_nop 0
	global_load_lds_dwordx4 v[162:163], off
	v_lshl_add_u64 v[162:163], v[218:219], 0, s[18:19]
	s_mov_b32 m0, s79
	s_nop 0
	global_load_lds_dwordx4 v[162:163], off
	s_waitcnt vmcnt(8)
	s_waitcnt lgkmcnt(0)
	s_barrier
	s_setprio 0
	v_mfma_f32_16x16x32_bf16 v[62:65], v[142:145], v[182:185], v[62:65]
	v_mfma_f32_16x16x32_bf16 v[58:61], v[150:153], v[182:185], v[58:61]
	v_mfma_f32_16x16x32_bf16 v[46:49], v[142:145], v[190:193], v[46:49]
	v_mfma_f32_16x16x32_bf16 v[42:45], v[150:153], v[190:193], v[42:45]
	v_mfma_f32_16x16x32_bf16 v[30:33], v[142:145], v[198:201], v[30:33]
	v_mfma_f32_16x16x32_bf16 v[26:29], v[150:153], v[198:201], v[26:29]
	v_mfma_f32_16x16x32_bf16 v[14:17], v[142:145], v[206:209], v[14:17]
	v_mfma_f32_16x16x32_bf16 v[10:13], v[150:153], v[206:209], v[10:13]
	v_mfma_f32_16x16x32_bf16 v[62:65], v[146:149], v[186:189], v[62:65]
	v_mfma_f32_16x16x32_bf16 v[58:61], v[154:157], v[186:189], v[58:61]
	v_mfma_f32_16x16x32_bf16 v[46:49], v[146:149], v[194:197], v[46:49]
	v_mfma_f32_16x16x32_bf16 v[42:45], v[154:157], v[194:197], v[42:45]
	v_mfma_f32_16x16x32_bf16 v[30:33], v[146:149], v[202:205], v[30:33]
	v_mfma_f32_16x16x32_bf16 v[26:29], v[154:157], v[202:205], v[26:29]
	v_mfma_f32_16x16x32_bf16 v[14:17], v[146:149], v[210:213], v[14:17]
	v_mfma_f32_16x16x32_bf16 v[10:13], v[154:157], v[210:213], v[10:13]
	s_setprio 2
	s_setprio 0
	v_mfma_f32_16x16x32_bf16 v[54:57], v[158:161], v[182:185], v[54:57]
	v_mfma_f32_16x16x32_bf16 v[50:53], v[174:177], v[182:185], v[50:53]
	v_mfma_f32_16x16x32_bf16 v[38:41], v[158:161], v[190:193], v[38:41]
	v_mfma_f32_16x16x32_bf16 v[34:37], v[174:177], v[190:193], v[34:37]
	v_mfma_f32_16x16x32_bf16 v[22:25], v[158:161], v[198:201], v[22:25]
	v_mfma_f32_16x16x32_bf16 v[18:21], v[174:177], v[198:201], v[18:21]
	v_mfma_f32_16x16x32_bf16 v[6:9], v[158:161], v[206:209], v[6:9]
	v_mfma_f32_16x16x32_bf16 v[2:5], v[174:177], v[206:209], v[2:5]
	v_mfma_f32_16x16x32_bf16 v[54:57], v[170:173], v[186:189], v[54:57]
	v_mfma_f32_16x16x32_bf16 v[50:53], v[178:181], v[186:189], v[50:53]
	v_mfma_f32_16x16x32_bf16 v[38:41], v[170:173], v[194:197], v[38:41]
	v_mfma_f32_16x16x32_bf16 v[34:37], v[178:181], v[194:197], v[34:37]
	v_mfma_f32_16x16x32_bf16 v[22:25], v[170:173], v[202:205], v[22:25]
	v_mfma_f32_16x16x32_bf16 v[18:21], v[178:181], v[202:205], v[18:21]
	v_mfma_f32_16x16x32_bf16 v[6:9], v[170:173], v[210:213], v[6:9]
	v_mfma_f32_16x16x32_bf16 v[2:5], v[178:181], v[210:213], v[2:5]
	s_setprio 2
	s_barrier
	s_movk_i32 s48, 0x100
	s_andn2_b64 vcc, exec, s[4:5]
	s_mov_b64 s[46:47], -1
	s_mov_b64 s[4:5], 0
	s_cbranch_vccz .LBB0_1653
	s_and_b64 vcc, exec, s[20:21]
	s_cbranch_vccz .LBB0_1656
	s_barrier

; #define PG8_STAGE(bufoff, gbase, voff) do { _Pragma("unroll") for (int _i = 0; _i < 2; ++_i) \
;         __builtin_amdgcn_global_load_lds((const unsigned*)((const char*)(gbase) + (voff)[_i]), (LAS unsigned*)(lds + (bufoff) + ldsw + _i * 8192), 16, 0, 0); } while (0)
; #define PG8_LDA(dst, b, h) do { _Pragma("unroll") for (int m = 0; m < 4; ++m) _Pragma("unroll") for (int k = 0; k < 2; ++k) dst[m][k] = *(const LAS bf16x8*)(lds + PG8_SA(b, h) + aoff + m * 2048 + k * 1024); } while (0)
; #define PG8_LDB(dst, b, h) do { _Pragma("unroll") for (int n = 0; n < 2; ++n) _Pragma("unroll") for (int k = 0; k < 2; ++k) dst[n][k] = *(const LAS bf16x8*)(lds + PG8_SB(b, h) + boff + n * 2048 + k * 1024); } while (0)
; #define PG8_MMA(ai, bj, At, Bt) do { __builtin_amdgcn_s_setprio(1); _Pragma("unroll") for (int m = 0; m < 4; ++m) _Pragma("unroll") for (int n = 0; n < 2; ++n) _Pragma("unroll") for (int k = 0; k < 2; ++k) \
;         acc[ai][bj][m][n] = __builtin_amdgcn_mfma_f32_16x16x32_bf16(Bt[n][k], At[m][k], acc[ai][bj][m][n], 0, 0, 0); __builtin_amdgcn_s_setprio(0); } while (0)
; #define PG8_WAIT_V(n) asm volatile("s_waitcnt vmcnt(" #n ")" ::: "memory")
; template <class Epi>
; __device__ __forceinline__ void gemm_phase(LAS unsigned char* lds, const Gemm g, int G, int c, const Epi& E) {
;     ...
;     for (;;) {
;         const bool has_next = S.next(ui + 1, nxt);
;         const char* nA = has_next ? (const char*)(g.A + (size_t)nxt.pb * g.sA) + (size_t)nxt.pm * 2 * hstepA : cA;
;         const char* nB = has_next ? (const char*)(g.Bt + (size_t)nxt.pb * g.sB) + (size_t)nxt.pn * 2 * hstepB : cB;
; #pragma nounroll
;         for (int t = 0; t < nt; t += 2) {
;             const bool last = (t == nt - 2);
;             const char* a1 = cA + (size_t)(t + 1) * kstep;
;             const char* a2 = last ? nA : cA + (size_t)(t + 2) * kstep; const char* b2 = last ? nB : cB + (size_t)(t + 2) * kstep;
;             const char* a3 = a2 + kstep; const char* b3 = b2 + kstep;
;             PG8_LDB(B0, 0, 0); PG8_LDB(B1, 0, 1); PG8_SCHED; PG8_LDA(At, 0, 0); PG8_STAGE(PG8_SA(1, 1), a1 + hstepA, voffA);
;             PG8_WAIT_V(8); PG8_WAIT_L(0); PG8_BAR; PG8_MMA(0, 0, At, B0); PG8_MMA(0, 1, At, B1); PG8_BAR; PG8_SCHED;
;             PG8_LDA(At, 0, 1); PG8_STAGE(PG8_SB(0, 0), b2, voffB); PG8_STAGE(PG8_SB(0, 1), b2 + hstepB, voffB); PG8_STAGE(PG8_SA(0, 0), a2, voffA);
.LBB0_1824:
	s_ashr_i32 s15, s14, 31
	s_lshl_b64 s[18:19], s[14:15], 21
	s_add_u32 s18, s34, s18
	s_addc_u32 s19, s35, s19
	s_and_b64 s[24:25], s[2:3], exec
	s_cselect_b32 s15, s19, s41
	s_cselect_b32 s63, s18, s40
	s_ashr_i32 s11, s10, 31
	s_lshl_b64 s[24:25], s[10:11], 21
	s_add_u32 s11, s46, s24
	s_addc_u32 s33, s47, s25
	s_ashr_i32 s13, s12, 31
	s_lshl_b64 s[24:25], s[12:13], 21
	s_add_u32 s24, s11, s24
	s_addc_u32 s25, s33, s25
	s_and_b64 s[44:45], s[2:3], exec
	s_cselect_b32 s11, s25, s43
	s_cselect_b32 s13, s24, s42
	s_add_u32 s40, s40, 0x100080
	s_addc_u32 s41, s41, 0
	s_add_u32 s66, s42, 0x100
	s_addc_u32 s67, s43, 0
	s_mov_b32 s68, -2
	ds_read_b128 v[146:149], v152
	ds_read_b128 v[156:159], v152 offset:1024
	ds_read_b128 v[160:163], v152 offset:2048
	ds_read_b128 v[164:167], v152 offset:3072
	ds_read_b128 v[168:171], v153
	ds_read_b128 v[172:175], v153 offset:1024
	ds_read_b128 v[176:179], v153 offset:2048
	ds_read_b128 v[180:183], v153 offset:3072
	s_add_u32 s33, s40, 0xfff00080
	s_addc_u32 s42, s41, -1
	s_cmp_eq_u32 s68, 60
	s_cselect_b32 s45, s15, s42
	s_cselect_b32 s44, s63, s33
	s_cselect_b32 s43, s11, s67
	s_cselect_b32 s42, s13, s66
	v_lshl_add_u64 v[216:217], s[40:41], 0, v[138:139]
	s_add_i32 m0, s17, 0xc000
	ds_read_b128 v[184:187], v154
	ds_read_b128 v[188:191], v154 offset:1024
	ds_read_b128 v[192:195], v154 offset:2048
	ds_read_b128 v[196:199], v154 offset:3072
	ds_read_b128 v[200:203], v154 offset:4096
	ds_read_b128 v[204:207], v154 offset:5120
	ds_read_b128 v[208:211], v154 offset:6144
	ds_read_b128 v[212:215], v154 offset:7168
	global_load_lds_dwordx4 v[216:217], off
	v_lshl_add_u64 v[216:217], s[40:41], 0, v[140:141]
	s_add_i32 m0, s17, 0xe000
	s_nop 0
	global_load_lds_dwordx4 v[216:217], off
	s_waitcnt vmcnt(8)
	s_waitcnt lgkmcnt(0)
	s_barrier
	s_setprio 0
	v_mfma_f32_16x16x32_bf16 v[126:129], v[146:149], v[184:187], 0
	v_mfma_f32_16x16x32_bf16 v[122:125], v[160:163], v[184:187], 0
	v_mfma_f32_16x16x32_bf16 v[118:121], v[146:149], v[192:195], 0
	v_mfma_f32_16x16x32_bf16 v[110:113], v[160:163], v[192:195], 0
	v_mfma_f32_16x16x32_bf16 v[102:105], v[146:149], v[200:203], 0
	v_mfma_f32_16x16x32_bf16 v[94:97], v[160:163], v[200:203], 0
	v_mfma_f32_16x16x32_bf16 v[86:89], v[146:149], v[208:211], 0
	v_mfma_f32_16x16x32_bf16 v[78:81], v[160:163], v[208:211], 0
	v_mfma_f32_16x16x32_bf16 v[126:129], v[156:159], v[188:191], v[126:129]
	v_mfma_f32_16x16x32_bf16 v[122:125], v[164:167], v[188:191], v[122:125]
	v_mfma_f32_16x16x32_bf16 v[118:121], v[156:159], v[196:199], v[118:121]
	v_mfma_f32_16x16x32_bf16 v[110:113], v[164:167], v[196:199], v[110:113]
	v_mfma_f32_16x16x32_bf16 v[102:105], v[156:159], v[204:207], v[102:105]
	v_mfma_f32_16x16x32_bf16 v[94:97], v[164:167], v[204:207], v[94:97]
	v_mfma_f32_16x16x32_bf16 v[86:89], v[156:159], v[212:215], v[86:89]
	v_mfma_f32_16x16x32_bf16 v[78:81], v[164:167], v[212:215], v[78:81]
	s_setprio 2
	s_setprio 0
	v_mfma_f32_16x16x32_bf16 v[114:117], v[168:171], v[184:187], 0
	v_mfma_f32_16x16x32_bf16 v[106:109], v[176:179], v[184:187], 0
	v_mfma_f32_16x16x32_bf16 v[98:101], v[168:171], v[192:195], 0
	v_mfma_f32_16x16x32_bf16 v[90:93], v[176:179], v[192:195], 0
	v_mfma_f32_16x16x32_bf16 v[82:85], v[168:171], v[200:203], 0
	v_mfma_f32_16x16x32_bf16 v[74:77], v[176:179], v[200:203], 0
	v_mfma_f32_16x16x32_bf16 v[70:73], v[168:171], v[208:211], 0
	v_mfma_f32_16x16x32_bf16 v[66:69], v[176:179], v[208:211], 0
	v_mfma_f32_16x16x32_bf16 v[114:117], v[172:175], v[188:191], v[114:117]
	v_mfma_f32_16x16x32_bf16 v[106:109], v[180:183], v[188:191], v[106:109]
	v_mfma_f32_16x16x32_bf16 v[98:101], v[172:175], v[196:199], v[98:101]
	v_mfma_f32_16x16x32_bf16 v[90:93], v[180:183], v[196:199], v[90:93]
	v_mfma_f32_16x16x32_bf16 v[82:85], v[172:175], v[204:207], v[82:85]
	v_mfma_f32_16x16x32_bf16 v[74:77], v[180:183], v[204:207], v[74:77]
	v_mfma_f32_16x16x32_bf16 v[70:73], v[172:175], v[212:215], v[70:73]
	v_mfma_f32_16x16x32_bf16 v[66:69], v[180:183], v[212:215], v[66:69]
	s_setprio 2
	s_barrier
	s_add_i32 s33, s61, s52
	v_lshl_add_u64 v[216:217], s[42:43], 0, v[134:135]
	s_mov_b32 m0, s33
	ds_read_b128 v[184:187], v154 offset:16384
	ds_read_b128 v[188:191], v154 offset:17408
	ds_read_b128 v[192:195], v154 offset:18432
	ds_read_b128 v[196:199], v154 offset:19456
	ds_read_b128 v[200:203], v154 offset:20480
	ds_read_b128 v[204:207], v154 offset:21504
	ds_read_b128 v[208:211], v154 offset:22528
	ds_read_b128 v[212:215], v154 offset:23552
	global_load_lds_dwordx4 v[216:217], off
	s_add_i32 m0, s33, 0x2000
	s_add_u32 s64, s42, 0x100000
	v_lshl_add_u64 v[218:219], s[42:43], 0, v[130:131]
	s_addc_u32 s65, s43, 0
	s_add_i32 s33, s62, s52
	global_load_lds_dwordx4 v[218:219], off
	v_lshl_add_u64 v[220:221], s[64:65], 0, v[134:135]
	s_mov_b32 m0, s33
	v_lshl_add_u64 v[222:223], s[44:45], 0, v[132:133]
	global_load_lds_dwordx4 v[220:221], off
	v_lshl_add_u64 v[220:221], s[64:65], 0, v[130:131]
	s_add_i32 m0, s33, 0x2000
	s_nop 0
	global_load_lds_dwordx4 v[220:221], off
	v_lshl_add_u64 v[220:221], s[44:45], 0, v[136:137]
	s_mov_b32 m0, s17
	s_nop 0
	global_load_lds_dwordx4 v[220:221], off
	s_mov_b32 m0, s37
	s_nop 0
	global_load_lds_dwordx4 v[222:223], off
	s_waitcnt vmcnt(8)
	s_waitcnt lgkmcnt(0)
	s_barrier
; #define PG8_STAGE(bufoff, gbase, voff) do { _Pragma("unroll") for (int _i = 0; _i < 2; ++_i) \
;         __builtin_amdgcn_global_load_lds((const unsigned*)((const char*)(gbase) + (voff)[_i]), (LAS unsigned*)(lds + (bufoff) + ldsw + _i * 8192), 16, 0, 0); } while (0)
; #define PG8_LDA(dst, b, h) do { _Pragma("unroll") for (int m = 0; m < 4; ++m) _Pragma("unroll") for (int k = 0; k < 2; ++k) dst[m][k] = *(const LAS bf16x8*)(lds + PG8_SA(b, h) + aoff + m * 2048 + k * 1024); } while (0)
; #define PG8_LDB(dst, b, h) do { _Pragma("unroll") for (int n = 0; n < 2; ++n) _Pragma("unroll") for (int k = 0; k < 2; ++k) dst[n][k] = *(const LAS bf16x8*)(lds + PG8_SB(b, h) + boff + n * 2048 + k * 1024); } while (0)
; #define PG8_MMA(ai, bj, At, Bt) do { __builtin_amdgcn_s_setprio(1); _Pragma("unroll") for (int m = 0; m < 4; ++m) _Pragma("unroll") for (int n = 0; n < 2; ++n) _Pragma("unroll") for (int k = 0; k < 2; ++k) \
;         acc[ai][bj][m][n] = __builtin_amdgcn_mfma_f32_16x16x32_bf16(Bt[n][k], At[m][k], acc[ai][bj][m][n], 0, 0, 0); __builtin_amdgcn_s_setprio(0); } while (0)
; #define PG8_WAIT_V(n) asm volatile("s_waitcnt vmcnt(" #n ")" ::: "memory")
; #define PG8_WAIT_L(n) asm volatile("s_waitcnt lgkmcnt(" #n ")" ::: "memory")
; #define PG8_BAR __builtin_amdgcn_s_barrier()
; #define PG8_SCHED __builtin_amdgcn_sched_barrier(0)
; template <class Epi>
; __device__ __forceinline__ void gemm_phase(LAS unsigned char* lds, const Gemm g, int G, int c, const Epi& E) {
;     ...
;             PG8_WAIT_V(8); PG8_WAIT_L(0); PG8_BAR; PG8_MMA(0, 0, At, B0); PG8_MMA(0, 1, At, B1); PG8_BAR; PG8_SCHED;
;             PG8_LDA(At, 0, 1); PG8_STAGE(PG8_SB(0, 0), b2, voffB); PG8_STAGE(PG8_SB(0, 1), b2 + hstepB, voffB); PG8_STAGE(PG8_SA(0, 0), a2, voffA);
;             PG8_WAIT_V(8); PG8_WAIT_L(0); PG8_BAR; PG8_MMA(1, 0, At, B0); PG8_MMA(1, 1, At, B1); PG8_BAR; PG8_SCHED;
;             PG8_LDB(B0, 1, 0); PG8_LDB(B1, 1, 1); PG8_SCHED; PG8_LDA(At, 1, 0); PG8_STAGE(PG8_SA(0, 1), a2 + hstepA, voffA);
;             PG8_WAIT_V(8); PG8_WAIT_L(0); PG8_BAR; PG8_MMA(0, 0, At, B0); PG8_MMA(0, 1, At, B1); PG8_BAR; PG8_SCHED;
	s_setprio 0
	v_mfma_f32_16x16x32_bf16 v[62:65], v[146:149], v[184:187], 0
	v_mfma_f32_16x16x32_bf16 v[58:61], v[160:163], v[184:187], 0
	v_mfma_f32_16x16x32_bf16 v[54:57], v[146:149], v[192:195], 0
	v_mfma_f32_16x16x32_bf16 v[46:49], v[160:163], v[192:195], 0
	v_mfma_f32_16x16x32_bf16 v[38:41], v[146:149], v[200:203], 0
	v_mfma_f32_16x16x32_bf16 v[30:33], v[160:163], v[200:203], 0
	v_mfma_f32_16x16x32_bf16 v[22:25], v[146:149], v[208:211], 0
	v_mfma_f32_16x16x32_bf16 v[14:17], v[160:163], v[208:211], 0
	v_mfma_f32_16x16x32_bf16 v[62:65], v[156:159], v[188:191], v[62:65]
	v_mfma_f32_16x16x32_bf16 v[58:61], v[164:167], v[188:191], v[58:61]
	v_mfma_f32_16x16x32_bf16 v[54:57], v[156:159], v[196:199], v[54:57]
	v_mfma_f32_16x16x32_bf16 v[46:49], v[164:167], v[196:199], v[46:49]
	v_mfma_f32_16x16x32_bf16 v[38:41], v[156:159], v[204:207], v[38:41]
	v_mfma_f32_16x16x32_bf16 v[30:33], v[164:167], v[204:207], v[30:33]
	v_mfma_f32_16x16x32_bf16 v[22:25], v[156:159], v[212:215], v[22:25]
	v_mfma_f32_16x16x32_bf16 v[14:17], v[164:167], v[212:215], v[14:17]
	s_setprio 2
	s_setprio 0
	v_mfma_f32_16x16x32_bf16 v[50:53], v[168:171], v[184:187], 0
	v_mfma_f32_16x16x32_bf16 v[42:45], v[176:179], v[184:187], 0
	v_mfma_f32_16x16x32_bf16 v[34:37], v[168:171], v[192:195], 0
	v_mfma_f32_16x16x32_bf16 v[26:29], v[176:179], v[192:195], 0
	v_mfma_f32_16x16x32_bf16 v[18:21], v[168:171], v[200:203], 0
	v_mfma_f32_16x16x32_bf16 v[10:13], v[176:179], v[200:203], 0
	v_mfma_f32_16x16x32_bf16 v[6:9], v[168:171], v[208:211], 0
	v_mfma_f32_16x16x32_bf16 v[2:5], v[176:179], v[208:211], 0
	v_mfma_f32_16x16x32_bf16 v[50:53], v[172:175], v[188:191], v[50:53]
	v_mfma_f32_16x16x32_bf16 v[42:45], v[180:183], v[188:191], v[42:45]
	v_mfma_f32_16x16x32_bf16 v[34:37], v[172:175], v[196:199], v[34:37]
	v_mfma_f32_16x16x32_bf16 v[26:29], v[180:183], v[196:199], v[26:29]
	v_mfma_f32_16x16x32_bf16 v[18:21], v[172:175], v[204:207], v[18:21]
	v_mfma_f32_16x16x32_bf16 v[10:13], v[180:183], v[204:207], v[10:13]
	v_mfma_f32_16x16x32_bf16 v[6:9], v[172:175], v[212:215], v[6:9]
	v_mfma_f32_16x16x32_bf16 v[2:5], v[180:183], v[212:215], v[2:5]
	s_setprio 2
	s_barrier
	s_add_i32 s33, 0, 0x18000
	v_add_u32_e32 v155, s33, v151
	s_add_i32 s64, 0, 0x1c000
	ds_read_b128 v[146:149], v155
	ds_read_b128 v[156:159], v155 offset:1024
	ds_read_b128 v[160:163], v155 offset:2048
	ds_read_b128 v[164:167], v155 offset:3072
	v_add_u32_e32 v155, s64, v151
	ds_read_b128 v[168:171], v155
	ds_read_b128 v[172:175], v155 offset:1024
	ds_read_b128 v[176:179], v155 offset:2048
	ds_read_b128 v[180:183], v155 offset:3072
	s_add_u32 s44, s44, 0x100000
	s_addc_u32 s45, s45, 0
	s_mov_b32 m0, s39
	v_lshl_add_u64 v[226:227], s[44:45], 0, v[136:137]
	ds_read_b128 v[184:187], v154 offset:32768
	ds_read_b128 v[188:191], v154 offset:33792
	ds_read_b128 v[192:195], v154 offset:34816
	ds_read_b128 v[196:199], v154 offset:35840
	ds_read_b128 v[200:203], v154 offset:36864
	ds_read_b128 v[204:207], v154 offset:37888
	ds_read_b128 v[208:211], v154 offset:38912
	ds_read_b128 v[212:215], v154 offset:39936
	global_load_lds_dwordx4 v[226:227], off
	v_lshl_add_u64 v[226:227], s[44:45], 0, v[132:133]
	s_mov_b32 m0, s53
	s_nop 0
	global_load_lds_dwordx4 v[226:227], off
	s_waitcnt vmcnt(8)
	s_waitcnt lgkmcnt(0)
	s_barrier
	s_setprio 0
	v_mfma_f32_16x16x32_bf16 v[126:129], v[146:149], v[184:187], v[126:129]
	v_mfma_f32_16x16x32_bf16 v[122:125], v[160:163], v[184:187], v[122:125]
	v_mfma_f32_16x16x32_bf16 v[118:121], v[146:149], v[192:195], v[118:121]
	v_mfma_f32_16x16x32_bf16 v[110:113], v[160:163], v[192:195], v[110:113]
	v_mfma_f32_16x16x32_bf16 v[102:105], v[146:149], v[200:203], v[102:105]
	v_mfma_f32_16x16x32_bf16 v[94:97], v[160:163], v[200:203], v[94:97]
	v_mfma_f32_16x16x32_bf16 v[86:89], v[146:149], v[208:211], v[86:89]
	v_mfma_f32_16x16x32_bf16 v[78:81], v[160:163], v[208:211], v[78:81]
	v_mfma_f32_16x16x32_bf16 v[126:129], v[156:159], v[188:191], v[126:129]
	v_mfma_f32_16x16x32_bf16 v[122:125], v[164:167], v[188:191], v[122:125]
	v_mfma_f32_16x16x32_bf16 v[118:121], v[156:159], v[196:199], v[118:121]
	v_mfma_f32_16x16x32_bf16 v[110:113], v[164:167], v[196:199], v[110:113]
	v_mfma_f32_16x16x32_bf16 v[102:105], v[156:159], v[204:207], v[102:105]
	v_mfma_f32_16x16x32_bf16 v[94:97], v[164:167], v[204:207], v[94:97]
	v_mfma_f32_16x16x32_bf16 v[86:89], v[156:159], v[212:215], v[86:89]
	v_mfma_f32_16x16x32_bf16 v[78:81], v[164:167], v[212:215], v[78:81]
	s_setprio 2
	s_setprio 0
	v_mfma_f32_16x16x32_bf16 v[114:117], v[168:171], v[184:187], v[114:117]
	v_mfma_f32_16x16x32_bf16 v[106:109], v[176:179], v[184:187], v[106:109]
	v_mfma_f32_16x16x32_bf16 v[98:101], v[168:171], v[192:195], v[98:101]
	v_mfma_f32_16x16x32_bf16 v[90:93], v[176:179], v[192:195], v[90:93]
	v_mfma_f32_16x16x32_bf16 v[82:85], v[168:171], v[200:203], v[82:85]
	v_mfma_f32_16x16x32_bf16 v[74:77], v[176:179], v[200:203], v[74:77]
	v_mfma_f32_16x16x32_bf16 v[70:73], v[168:171], v[208:211], v[70:73]
	v_mfma_f32_16x16x32_bf16 v[66:69], v[176:179], v[208:211], v[66:69]
	v_mfma_f32_16x16x32_bf16 v[114:117], v[172:175], v[188:191], v[114:117]
	v_mfma_f32_16x16x32_bf16 v[106:109], v[180:183], v[188:191], v[106:109]
	v_mfma_f32_16x16x32_bf16 v[98:101], v[172:175], v[196:199], v[98:101]
	v_mfma_f32_16x16x32_bf16 v[90:93], v[180:183], v[196:199], v[90:93]
	v_mfma_f32_16x16x32_bf16 v[82:85], v[172:175], v[204:207], v[82:85]
	v_mfma_f32_16x16x32_bf16 v[74:77], v[180:183], v[204:207], v[74:77]
	v_mfma_f32_16x16x32_bf16 v[70:73], v[172:175], v[212:215], v[70:73]
	v_mfma_f32_16x16x32_bf16 v[66:69], v[180:183], v[212:215], v[66:69]
	s_setprio 2
	s_barrier
; #define PG8_STAGE(bufoff, gbase, voff) do { _Pragma("unroll") for (int _i = 0; _i < 2; ++_i) \
;         __builtin_amdgcn_global_load_lds((const unsigned*)((const char*)(gbase) + (voff)[_i]), (LAS unsigned*)(lds + (bufoff) + ldsw + _i * 8192), 16, 0, 0); } while (0)
; #define PG8_LDA(dst, b, h) do { _Pragma("unroll") for (int m = 0; m < 4; ++m) _Pragma("unroll") for (int k = 0; k < 2; ++k) dst[m][k] = *(const LAS bf16x8*)(lds + PG8_SA(b, h) + aoff + m * 2048 + k * 1024); } while (0)
; #define PG8_LDB(dst, b, h) do { _Pragma("unroll") for (int n = 0; n < 2; ++n) _Pragma("unroll") for (int k = 0; k < 2; ++k) dst[n][k] = *(const LAS bf16x8*)(lds + PG8_SB(b, h) + boff + n * 2048 + k * 1024); } while (0)
; #define PG8_WAIT_V(n) asm volatile("s_waitcnt vmcnt(" #n ")" ::: "memory")
; #define PG8_WAIT_L(n) asm volatile("s_waitcnt lgkmcnt(" #n ")" ::: "memory")
; template <class Epi>
; __device__ __forceinline__ void gemm_phase(LAS unsigned char* lds, const Gemm g, int G, int c, const Epi& E) {
;     ...
;         for (int t = 0; t < nt; t += 2) {
;             const bool last = (t == nt - 2);
;             const char* a1 = cA + (size_t)(t + 1) * kstep;
;             const char* a2 = last ? nA : cA + (size_t)(t + 2) * kstep; const char* b2 = last ? nB : cB + (size_t)(t + 2) * kstep;
;             const char* a3 = a2 + kstep; const char* b3 = b2 + kstep;
;             PG8_LDB(B0, 0, 0); PG8_LDB(B1, 0, 1); PG8_SCHED; PG8_LDA(At, 0, 0); PG8_STAGE(PG8_SA(1, 1), a1 + hstepA, voffA);
;             PG8_WAIT_V(8); PG8_WAIT_L(0); PG8_BAR; PG8_MMA(0, 0, At, B0); PG8_MMA(0, 1, At, B1); PG8_BAR; PG8_SCHED;
;             PG8_LDA(At, 0, 1); PG8_STAGE(PG8_SB(0, 0), b2, voffB); PG8_STAGE(PG8_SB(0, 1), b2 + hstepB, voffB); PG8_STAGE(PG8_SA(0, 0), a2, voffA);
;             PG8_WAIT_V(8); PG8_WAIT_L(0); PG8_BAR; PG8_MMA(1, 0, At, B0); PG8_MMA(1, 1, At, B1); PG8_BAR; PG8_SCHED;
;             PG8_LDB(B0, 1, 0); PG8_LDB(B1, 1, 1); PG8_SCHED; PG8_LDA(At, 1, 0); PG8_STAGE(PG8_SA(0, 1), a2 + hstepA, voffA);
;             PG8_WAIT_V(8); PG8_WAIT_L(0); PG8_BAR; PG8_MMA(0, 0, At, B0); PG8_MMA(0, 1, At, B1); PG8_BAR; PG8_SCHED;
;             PG8_LDA(At, 1, 1); PG8_STAGE(PG8_SB(1, 0), b3, voffB); PG8_STAGE(PG8_SB(1, 1), b3 + hstepB, voffB); PG8_STAGE(PG8_SA(1, 0), a3, voffA);
;             PG8_WAIT_V(8); PG8_WAIT_L(0); PG8_BAR; PG8_MMA(1, 0, At, B0); PG8_MMA(1, 1, At, B1); PG8_BAR; PG8_SCHED;
	s_add_i32 s33, s33, s52
	v_lshl_add_u64 v[216:217], v[216:217], 0, s[6:7]
	s_mov_b32 m0, s33
	ds_read_b128 v[184:187], v154 offset:49152
	ds_read_b128 v[188:191], v154 offset:50176
	ds_read_b128 v[192:195], v154 offset:51200
	ds_read_b128 v[196:199], v154 offset:52224
	ds_read_b128 v[200:203], v154 offset:53248
	ds_read_b128 v[204:207], v154 offset:54272
	ds_read_b128 v[208:211], v154 offset:55296
	ds_read_b128 v[212:215], v154 offset:56320
	global_load_lds_dwordx4 v[216:217], off
	s_add_i32 m0, s33, 0x2000
	s_add_u32 s42, s42, 0x100080
	v_lshl_add_u64 v[216:217], v[218:219], 0, s[6:7]
	s_addc_u32 s43, s43, 0
	s_add_i32 s33, s64, s52
	global_load_lds_dwordx4 v[216:217], off
	v_lshl_add_u64 v[216:217], s[42:43], 0, v[134:135]
	s_mov_b32 m0, s33
	s_nop 0
	global_load_lds_dwordx4 v[216:217], off
	v_lshl_add_u64 v[216:217], s[42:43], 0, v[130:131]
	s_add_i32 m0, s33, 0x2000
	s_nop 0
	global_load_lds_dwordx4 v[216:217], off
	v_lshl_add_u64 v[216:217], v[220:221], 0, s[6:7]
	s_mov_b32 m0, s59
	s_nop 0
	global_load_lds_dwordx4 v[216:217], off
	v_lshl_add_u64 v[216:217], v[222:223], 0, s[6:7]
	s_mov_b32 m0, s60
	s_nop 0
	global_load_lds_dwordx4 v[216:217], off
	s_waitcnt vmcnt(8)
	s_waitcnt lgkmcnt(0)
	s_barrier
	s_setprio 0
	v_mfma_f32_16x16x32_bf16 v[62:65], v[146:149], v[184:187], v[62:65]
	v_mfma_f32_16x16x32_bf16 v[58:61], v[160:163], v[184:187], v[58:61]
	v_mfma_f32_16x16x32_bf16 v[54:57], v[146:149], v[192:195], v[54:57]
	v_mfma_f32_16x16x32_bf16 v[46:49], v[160:163], v[192:195], v[46:49]
	v_mfma_f32_16x16x32_bf16 v[38:41], v[146:149], v[200:203], v[38:41]
	v_mfma_f32_16x16x32_bf16 v[30:33], v[160:163], v[200:203], v[30:33]
	v_mfma_f32_16x16x32_bf16 v[22:25], v[146:149], v[208:211], v[22:25]
	v_mfma_f32_16x16x32_bf16 v[14:17], v[160:163], v[208:211], v[14:17]
	v_mfma_f32_16x16x32_bf16 v[62:65], v[156:159], v[188:191], v[62:65]
	v_mfma_f32_16x16x32_bf16 v[58:61], v[164:167], v[188:191], v[58:61]
	v_mfma_f32_16x16x32_bf16 v[54:57], v[156:159], v[196:199], v[54:57]
	v_mfma_f32_16x16x32_bf16 v[46:49], v[164:167], v[196:199], v[46:49]
	v_mfma_f32_16x16x32_bf16 v[38:41], v[156:159], v[204:207], v[38:41]
	v_mfma_f32_16x16x32_bf16 v[30:33], v[164:167], v[204:207], v[30:33]
	v_mfma_f32_16x16x32_bf16 v[22:25], v[156:159], v[212:215], v[22:25]
	v_mfma_f32_16x16x32_bf16 v[14:17], v[164:167], v[212:215], v[14:17]
	s_setprio 2
	s_setprio 0
	v_mfma_f32_16x16x32_bf16 v[50:53], v[168:171], v[184:187], v[50:53]
	v_mfma_f32_16x16x32_bf16 v[42:45], v[176:179], v[184:187], v[42:45]
	v_mfma_f32_16x16x32_bf16 v[34:37], v[168:171], v[192:195], v[34:37]
	v_mfma_f32_16x16x32_bf16 v[26:29], v[176:179], v[192:195], v[26:29]
	v_mfma_f32_16x16x32_bf16 v[18:21], v[168:171], v[200:203], v[18:21]
	v_mfma_f32_16x16x32_bf16 v[10:13], v[176:179], v[200:203], v[10:13]
	v_mfma_f32_16x16x32_bf16 v[6:9], v[168:171], v[208:211], v[6:9]
	v_mfma_f32_16x16x32_bf16 v[2:5], v[176:179], v[208:211], v[2:5]
	v_mfma_f32_16x16x32_bf16 v[50:53], v[172:175], v[188:191], v[50:53]
	v_mfma_f32_16x16x32_bf16 v[42:45], v[180:183], v[188:191], v[42:45]
	v_mfma_f32_16x16x32_bf16 v[34:37], v[172:175], v[196:199], v[34:37]
	v_mfma_f32_16x16x32_bf16 v[26:29], v[180:183], v[196:199], v[26:29]
	v_mfma_f32_16x16x32_bf16 v[18:21], v[172:175], v[204:207], v[18:21]
	v_mfma_f32_16x16x32_bf16 v[10:13], v[180:183], v[204:207], v[10:13]
	v_mfma_f32_16x16x32_bf16 v[6:9], v[172:175], v[212:215], v[6:9]
	v_mfma_f32_16x16x32_bf16 v[2:5], v[180:183], v[212:215], v[2:5]
	s_setprio 2
	s_barrier
	s_add_i32 s68, s68, 2
	s_add_u32 s40, s40, 0x100
	s_addc_u32 s41, s41, 0
	s_add_u32 s66, s66, 0x100
	s_addc_u32 s67, s67, 0
	s_cmp_gt_u32 s68, 61
	s_cbranch_scc0 .LBB0_1825
.LBB0_1825:
	ds_read_b128 v[146:149], v152
	ds_read_b128 v[156:159], v152 offset:1024
	ds_read_b128 v[160:163], v152 offset:2048
	ds_read_b128 v[164:167], v152 offset:3072
	ds_read_b128 v[168:171], v153
	ds_read_b128 v[172:175], v153 offset:1024
	ds_read_b128 v[176:179], v153 offset:2048
	ds_read_b128 v[180:183], v153 offset:3072
	s_add_u32 s33, s40, 0xfff00080
	s_addc_u32 s42, s41, -1
	s_cmp_eq_u32 s68, 60
	s_cselect_b32 s45, s15, s42
	s_cselect_b32 s44, s63, s33
	s_cselect_b32 s43, s11, s67
	s_cselect_b32 s42, s13, s66
	v_lshl_add_u64 v[216:217], s[40:41], 0, v[138:139]
	s_add_i32 m0, s17, 0xc000
	ds_read_b128 v[184:187], v154
	ds_read_b128 v[188:191], v154 offset:1024
	ds_read_b128 v[192:195], v154 offset:2048
	ds_read_b128 v[196:199], v154 offset:3072
	ds_read_b128 v[200:203], v154 offset:4096
	ds_read_b128 v[204:207], v154 offset:5120
	ds_read_b128 v[208:211], v154 offset:6144
	ds_read_b128 v[212:215], v154 offset:7168
	global_load_lds_dwordx4 v[216:217], off
	v_lshl_add_u64 v[216:217], s[40:41], 0, v[140:141]
	s_add_i32 m0, s17, 0xe000
	s_nop 0
	global_load_lds_dwordx4 v[216:217], off
	s_waitcnt vmcnt(8)
	s_waitcnt lgkmcnt(0)
	s_barrier
; #define PG8_STAGE(bufoff, gbase, voff) do { _Pragma("unroll") for (int _i = 0; _i < 2; ++_i) \
;         __builtin_amdgcn_global_load_lds((const unsigned*)((const char*)(gbase) + (voff)[_i]), (LAS unsigned*)(lds + (bufoff) + ldsw + _i * 8192), 16, 0, 0); } while (0)
; #define PG8_LDA(dst, b, h) do { _Pragma("unroll") for (int m = 0; m < 4; ++m) _Pragma("unroll") for (int k = 0; k < 2; ++k) dst[m][k] = *(const LAS bf16x8*)(lds + PG8_SA(b, h) + aoff + m * 2048 + k * 1024); } while (0)
; #define PG8_MMA(ai, bj, At, Bt) do { __builtin_amdgcn_s_setprio(1); _Pragma("unroll") for (int m = 0; m < 4; ++m) _Pragma("unroll") for (int n = 0; n < 2; ++n) _Pragma("unroll") for (int k = 0; k < 2; ++k) \
;         acc[ai][bj][m][n] = __builtin_amdgcn_mfma_f32_16x16x32_bf16(Bt[n][k], At[m][k], acc[ai][bj][m][n], 0, 0, 0); __builtin_amdgcn_s_setprio(0); } while (0)
; #define PG8_WAIT_V(n) asm volatile("s_waitcnt vmcnt(" #n ")" ::: "memory")
; #define PG8_WAIT_L(n) asm volatile("s_waitcnt lgkmcnt(" #n ")" ::: "memory")
; #define PG8_BAR __builtin_amdgcn_s_barrier()
; #define PG8_SCHED __builtin_amdgcn_sched_barrier(0)
; template <class Epi>
; __device__ __forceinline__ void gemm_phase(LAS unsigned char* lds, const Gemm g, int G, int c, const Epi& E) {
;     ...
;             PG8_WAIT_V(8); PG8_WAIT_L(0); PG8_BAR; PG8_MMA(0, 0, At, B0); PG8_MMA(0, 1, At, B1); PG8_BAR; PG8_SCHED;
;             PG8_LDA(At, 0, 1); PG8_STAGE(PG8_SB(0, 0), b2, voffB); PG8_STAGE(PG8_SB(0, 1), b2 + hstepB, voffB); PG8_STAGE(PG8_SA(0, 0), a2, voffA);
;             PG8_WAIT_V(8); PG8_WAIT_L(0); PG8_BAR; PG8_MMA(1, 0, At, B0); PG8_MMA(1, 1, At, B1); PG8_BAR; PG8_SCHED;
	s_setprio 0
	v_mfma_f32_16x16x32_bf16 v[126:129], v[146:149], v[184:187], v[126:129]
	v_mfma_f32_16x16x32_bf16 v[122:125], v[160:163], v[184:187], v[122:125]
	v_mfma_f32_16x16x32_bf16 v[118:121], v[146:149], v[192:195], v[118:121]
	v_mfma_f32_16x16x32_bf16 v[110:113], v[160:163], v[192:195], v[110:113]
	v_mfma_f32_16x16x32_bf16 v[102:105], v[146:149], v[200:203], v[102:105]
	v_mfma_f32_16x16x32_bf16 v[94:97], v[160:163], v[200:203], v[94:97]
	v_mfma_f32_16x16x32_bf16 v[86:89], v[146:149], v[208:211], v[86:89]
	v_mfma_f32_16x16x32_bf16 v[78:81], v[160:163], v[208:211], v[78:81]
	v_mfma_f32_16x16x32_bf16 v[126:129], v[156:159], v[188:191], v[126:129]
	v_mfma_f32_16x16x32_bf16 v[122:125], v[164:167], v[188:191], v[122:125]
	v_mfma_f32_16x16x32_bf16 v[118:121], v[156:159], v[196:199], v[118:121]
	v_mfma_f32_16x16x32_bf16 v[110:113], v[164:167], v[196:199], v[110:113]
	v_mfma_f32_16x16x32_bf16 v[102:105], v[156:159], v[204:207], v[102:105]
	v_mfma_f32_16x16x32_bf16 v[94:97], v[164:167], v[204:207], v[94:97]
	v_mfma_f32_16x16x32_bf16 v[86:89], v[156:159], v[212:215], v[86:89]
	v_mfma_f32_16x16x32_bf16 v[78:81], v[164:167], v[212:215], v[78:81]
	s_setprio 2
	s_setprio 0
	v_mfma_f32_16x16x32_bf16 v[114:117], v[168:171], v[184:187], v[114:117]
	v_mfma_f32_16x16x32_bf16 v[106:109], v[176:179], v[184:187], v[106:109]
	v_mfma_f32_16x16x32_bf16 v[98:101], v[168:171], v[192:195], v[98:101]
	v_mfma_f32_16x16x32_bf16 v[90:93], v[176:179], v[192:195], v[90:93]
	v_mfma_f32_16x16x32_bf16 v[82:85], v[168:171], v[200:203], v[82:85]
	v_mfma_f32_16x16x32_bf16 v[74:77], v[176:179], v[200:203], v[74:77]
	v_mfma_f32_16x16x32_bf16 v[70:73], v[168:171], v[208:211], v[70:73]
	v_mfma_f32_16x16x32_bf16 v[66:69], v[176:179], v[208:211], v[66:69]
	v_mfma_f32_16x16x32_bf16 v[114:117], v[172:175], v[188:191], v[114:117]
	v_mfma_f32_16x16x32_bf16 v[106:109], v[180:183], v[188:191], v[106:109]
	v_mfma_f32_16x16x32_bf16 v[98:101], v[172:175], v[196:199], v[98:101]
	v_mfma_f32_16x16x32_bf16 v[90:93], v[180:183], v[196:199], v[90:93]
	v_mfma_f32_16x16x32_bf16 v[82:85], v[172:175], v[204:207], v[82:85]
	v_mfma_f32_16x16x32_bf16 v[74:77], v[180:183], v[204:207], v[74:77]
	v_mfma_f32_16x16x32_bf16 v[70:73], v[172:175], v[212:215], v[70:73]
	v_mfma_f32_16x16x32_bf16 v[66:69], v[180:183], v[212:215], v[66:69]
	s_setprio 2
	s_barrier
	s_add_i32 s33, s61, s52
	v_lshl_add_u64 v[216:217], s[42:43], 0, v[134:135]
	s_mov_b32 m0, s33
	ds_read_b128 v[184:187], v154 offset:16384
	ds_read_b128 v[188:191], v154 offset:17408
	ds_read_b128 v[192:195], v154 offset:18432
	ds_read_b128 v[196:199], v154 offset:19456
	ds_read_b128 v[200:203], v154 offset:20480
	ds_read_b128 v[204:207], v154 offset:21504
	ds_read_b128 v[208:211], v154 offset:22528
	ds_read_b128 v[212:215], v154 offset:23552
	global_load_lds_dwordx4 v[216:217], off
	s_add_i32 m0, s33, 0x2000
	s_add_u32 s64, s42, 0x100000
	v_lshl_add_u64 v[218:219], s[42:43], 0, v[130:131]
	s_addc_u32 s65, s43, 0
	s_add_i32 s33, s62, s52
	global_load_lds_dwordx4 v[218:219], off
	v_lshl_add_u64 v[220:221], s[64:65], 0, v[134:135]
	s_mov_b32 m0, s33
	v_lshl_add_u64 v[222:223], s[44:45], 0, v[132:133]
	global_load_lds_dwordx4 v[220:221], off
	v_lshl_add_u64 v[220:221], s[64:65], 0, v[130:131]
	s_add_i32 m0, s33, 0x2000
	s_nop 0
	global_load_lds_dwordx4 v[220:221], off
	v_lshl_add_u64 v[220:221], s[44:45], 0, v[136:137]
	s_mov_b32 m0, s17
	s_nop 0
	global_load_lds_dwordx4 v[220:221], off
	s_mov_b32 m0, s37
	s_nop 0
	global_load_lds_dwordx4 v[222:223], off
	s_waitcnt vmcnt(8)
	s_waitcnt lgkmcnt(0)
	s_barrier
	s_setprio 0
	v_mfma_f32_16x16x32_bf16 v[62:65], v[146:149], v[184:187], v[62:65]
	v_mfma_f32_16x16x32_bf16 v[58:61], v[160:163], v[184:187], v[58:61]
	v_mfma_f32_16x16x32_bf16 v[54:57], v[146:149], v[192:195], v[54:57]
	v_mfma_f32_16x16x32_bf16 v[46:49], v[160:163], v[192:195], v[46:49]
	v_mfma_f32_16x16x32_bf16 v[38:41], v[146:149], v[200:203], v[38:41]
	v_mfma_f32_16x16x32_bf16 v[30:33], v[160:163], v[200:203], v[30:33]
	v_mfma_f32_16x16x32_bf16 v[22:25], v[146:149], v[208:211], v[22:25]
	v_mfma_f32_16x16x32_bf16 v[14:17], v[160:163], v[208:211], v[14:17]
	v_mfma_f32_16x16x32_bf16 v[62:65], v[156:159], v[188:191], v[62:65]
	v_mfma_f32_16x16x32_bf16 v[58:61], v[164:167], v[188:191], v[58:61]
	v_mfma_f32_16x16x32_bf16 v[54:57], v[156:159], v[196:199], v[54:57]
	v_mfma_f32_16x16x32_bf16 v[46:49], v[164:167], v[196:199], v[46:49]
	v_mfma_f32_16x16x32_bf16 v[38:41], v[156:159], v[204:207], v[38:41]
	v_mfma_f32_16x16x32_bf16 v[30:33], v[164:167], v[204:207], v[30:33]
	v_mfma_f32_16x16x32_bf16 v[22:25], v[156:159], v[212:215], v[22:25]
	v_mfma_f32_16x16x32_bf16 v[14:17], v[164:167], v[212:215], v[14:17]
	s_setprio 2
	s_setprio 0
	v_mfma_f32_16x16x32_bf16 v[50:53], v[168:171], v[184:187], v[50:53]
	v_mfma_f32_16x16x32_bf16 v[42:45], v[176:179], v[184:187], v[42:45]
	v_mfma_f32_16x16x32_bf16 v[34:37], v[168:171], v[192:195], v[34:37]
	v_mfma_f32_16x16x32_bf16 v[26:29], v[176:179], v[192:195], v[26:29]
	v_mfma_f32_16x16x32_bf16 v[18:21], v[168:171], v[200:203], v[18:21]
	v_mfma_f32_16x16x32_bf16 v[10:13], v[176:179], v[200:203], v[10:13]
	v_mfma_f32_16x16x32_bf16 v[6:9], v[168:171], v[208:211], v[6:9]
	v_mfma_f32_16x16x32_bf16 v[2:5], v[176:179], v[208:211], v[2:5]
	v_mfma_f32_16x16x32_bf16 v[50:53], v[172:175], v[188:191], v[50:53]
	v_mfma_f32_16x16x32_bf16 v[42:45], v[180:183], v[188:191], v[42:45]
	v_mfma_f32_16x16x32_bf16 v[34:37], v[172:175], v[196:199], v[34:37]
	v_mfma_f32_16x16x32_bf16 v[26:29], v[180:183], v[196:199], v[26:29]
	v_mfma_f32_16x16x32_bf16 v[18:21], v[172:175], v[204:207], v[18:21]
	v_mfma_f32_16x16x32_bf16 v[10:13], v[180:183], v[204:207], v[10:13]
	v_mfma_f32_16x16x32_bf16 v[6:9], v[172:175], v[212:215], v[6:9]
	v_mfma_f32_16x16x32_bf16 v[2:5], v[180:183], v[212:215], v[2:5]
	s_setprio 2
	s_barrier
; #define PG8_STAGE(bufoff, gbase, voff) do { _Pragma("unroll") for (int _i = 0; _i < 2; ++_i) \
;         __builtin_amdgcn_global_load_lds((const unsigned*)((const char*)(gbase) + (voff)[_i]), (LAS unsigned*)(lds + (bufoff) + ldsw + _i * 8192), 16, 0, 0); } while (0)
; #define PG8_LDA(dst, b, h) do { _Pragma("unroll") for (int m = 0; m < 4; ++m) _Pragma("unroll") for (int k = 0; k < 2; ++k) dst[m][k] = *(const LAS bf16x8*)(lds + PG8_SA(b, h) + aoff + m * 2048 + k * 1024); } while (0)
; #define PG8_LDB(dst, b, h) do { _Pragma("unroll") for (int n = 0; n < 2; ++n) _Pragma("unroll") for (int k = 0; k < 2; ++k) dst[n][k] = *(const LAS bf16x8*)(lds + PG8_SB(b, h) + boff + n * 2048 + k * 1024); } while (0)
; #define PG8_MMA(ai, bj, At, Bt) do { __builtin_amdgcn_s_setprio(1); _Pragma("unroll") for (int m = 0; m < 4; ++m) _Pragma("unroll") for (int n = 0; n < 2; ++n) _Pragma("unroll") for (int k = 0; k < 2; ++k) \
;         acc[ai][bj][m][n] = __builtin_amdgcn_mfma_f32_16x16x32_bf16(Bt[n][k], At[m][k], acc[ai][bj][m][n], 0, 0, 0); __builtin_amdgcn_s_setprio(0); } while (0)
; #define PG8_WAIT_V(n) asm volatile("s_waitcnt vmcnt(" #n ")" ::: "memory")
; #define PG8_WAIT_L(n) asm volatile("s_waitcnt lgkmcnt(" #n ")" ::: "memory")
; #define PG8_BAR __builtin_amdgcn_s_barrier()
; #define PG8_SCHED __builtin_amdgcn_sched_barrier(0)
; template <class Epi>
; __device__ __forceinline__ void gemm_phase(LAS unsigned char* lds, const Gemm g, int G, int c, const Epi& E) {
;     ...
;             PG8_LDB(B0, 1, 0); PG8_LDB(B1, 1, 1); PG8_SCHED; PG8_LDA(At, 1, 0); PG8_STAGE(PG8_SA(0, 1), a2 + hstepA, voffA);
;             PG8_WAIT_V(8); PG8_WAIT_L(0); PG8_BAR; PG8_MMA(0, 0, At, B0); PG8_MMA(0, 1, At, B1); PG8_BAR; PG8_SCHED;
	s_add_i32 s33, 0, 0x18000
	v_add_u32_e32 v155, s33, v151
	s_add_i32 s64, 0, 0x1c000
	ds_read_b128 v[146:149], v155
	ds_read_b128 v[156:159], v155 offset:1024
	ds_read_b128 v[160:163], v155 offset:2048
	ds_read_b128 v[164:167], v155 offset:3072
	v_add_u32_e32 v155, s64, v151
	ds_read_b128 v[168:171], v155
	ds_read_b128 v[172:175], v155 offset:1024
	ds_read_b128 v[176:179], v155 offset:2048
	ds_read_b128 v[180:183], v155 offset:3072
	s_add_u32 s44, s44, 0x100000
	s_addc_u32 s45, s45, 0
	s_mov_b32 m0, s39
	v_lshl_add_u64 v[226:227], s[44:45], 0, v[136:137]
	ds_read_b128 v[184:187], v154 offset:32768
	ds_read_b128 v[188:191], v154 offset:33792
	ds_read_b128 v[192:195], v154 offset:34816
	ds_read_b128 v[196:199], v154 offset:35840
	ds_read_b128 v[200:203], v154 offset:36864
	ds_read_b128 v[204:207], v154 offset:37888
	ds_read_b128 v[208:211], v154 offset:38912
	ds_read_b128 v[212:215], v154 offset:39936
	global_load_lds_dwordx4 v[226:227], off
	v_lshl_add_u64 v[226:227], s[44:45], 0, v[132:133]
	s_mov_b32 m0, s53
	s_nop 0
	global_load_lds_dwordx4 v[226:227], off
	s_waitcnt vmcnt(8)
	s_waitcnt lgkmcnt(0)
	s_barrier
	s_setprio 0
	v_mfma_f32_16x16x32_bf16 v[126:129], v[146:149], v[184:187], v[126:129]
	v_mfma_f32_16x16x32_bf16 v[122:125], v[160:163], v[184:187], v[122:125]
	v_mfma_f32_16x16x32_bf16 v[118:121], v[146:149], v[192:195], v[118:121]
	v_mfma_f32_16x16x32_bf16 v[110:113], v[160:163], v[192:195], v[110:113]
	v_mfma_f32_16x16x32_bf16 v[102:105], v[146:149], v[200:203], v[102:105]
	v_mfma_f32_16x16x32_bf16 v[94:97], v[160:163], v[200:203], v[94:97]
	v_mfma_f32_16x16x32_bf16 v[86:89], v[146:149], v[208:211], v[86:89]
	v_mfma_f32_16x16x32_bf16 v[78:81], v[160:163], v[208:211], v[78:81]
	v_mfma_f32_16x16x32_bf16 v[126:129], v[156:159], v[188:191], v[126:129]
	v_mfma_f32_16x16x32_bf16 v[122:125], v[164:167], v[188:191], v[122:125]
	v_mfma_f32_16x16x32_bf16 v[118:121], v[156:159], v[196:199], v[118:121]
	v_mfma_f32_16x16x32_bf16 v[110:113], v[164:167], v[196:199], v[110:113]
	v_mfma_f32_16x16x32_bf16 v[102:105], v[156:159], v[204:207], v[102:105]
	v_mfma_f32_16x16x32_bf16 v[94:97], v[164:167], v[204:207], v[94:97]
	v_mfma_f32_16x16x32_bf16 v[86:89], v[156:159], v[212:215], v[86:89]
	v_mfma_f32_16x16x32_bf16 v[78:81], v[164:167], v[212:215], v[78:81]
	s_setprio 2
	s_setprio 0
	v_mfma_f32_16x16x32_bf16 v[114:117], v[168:171], v[184:187], v[114:117]
	v_mfma_f32_16x16x32_bf16 v[106:109], v[176:179], v[184:187], v[106:109]
	v_mfma_f32_16x16x32_bf16 v[98:101], v[168:171], v[192:195], v[98:101]
	v_mfma_f32_16x16x32_bf16 v[90:93], v[176:179], v[192:195], v[90:93]
	v_mfma_f32_16x16x32_bf16 v[82:85], v[168:171], v[200:203], v[82:85]
	v_mfma_f32_16x16x32_bf16 v[74:77], v[176:179], v[200:203], v[74:77]
	v_mfma_f32_16x16x32_bf16 v[70:73], v[168:171], v[208:211], v[70:73]
	v_mfma_f32_16x16x32_bf16 v[66:69], v[176:179], v[208:211], v[66:69]
	v_mfma_f32_16x16x32_bf16 v[114:117], v[172:175], v[188:191], v[114:117]
	v_mfma_f32_16x16x32_bf16 v[106:109], v[180:183], v[188:191], v[106:109]
	v_mfma_f32_16x16x32_bf16 v[98:101], v[172:175], v[196:199], v[98:101]
	v_mfma_f32_16x16x32_bf16 v[90:93], v[180:183], v[196:199], v[90:93]
	v_mfma_f32_16x16x32_bf16 v[82:85], v[172:175], v[204:207], v[82:85]
	v_mfma_f32_16x16x32_bf16 v[74:77], v[180:183], v[204:207], v[74:77]
	v_mfma_f32_16x16x32_bf16 v[70:73], v[172:175], v[212:215], v[70:73]
	v_mfma_f32_16x16x32_bf16 v[66:69], v[180:183], v[212:215], v[66:69]
	s_setprio 2
	s_barrier
; #define PG8_STAGE(bufoff, gbase, voff) do { _Pragma("unroll") for (int _i = 0; _i < 2; ++_i) \
;         __builtin_amdgcn_global_load_lds((const unsigned*)((const char*)(gbase) + (voff)[_i]), (LAS unsigned*)(lds + (bufoff) + ldsw + _i * 8192), 16, 0, 0); } while (0)
; #define PG8_LDA(dst, b, h) do { _Pragma("unroll") for (int m = 0; m < 4; ++m) _Pragma("unroll") for (int k = 0; k < 2; ++k) dst[m][k] = *(const LAS bf16x8*)(lds + PG8_SA(b, h) + aoff + m * 2048 + k * 1024); } while (0)
; #define PG8_MMA(ai, bj, At, Bt) do { __builtin_amdgcn_s_setprio(1); _Pragma("unroll") for (int m = 0; m < 4; ++m) _Pragma("unroll") for (int n = 0; n < 2; ++n) _Pragma("unroll") for (int k = 0; k < 2; ++k) \
;         acc[ai][bj][m][n] = __builtin_amdgcn_mfma_f32_16x16x32_bf16(Bt[n][k], At[m][k], acc[ai][bj][m][n], 0, 0, 0); __builtin_amdgcn_s_setprio(0); } while (0)
; #define PG8_WAIT_V(n) asm volatile("s_waitcnt vmcnt(" #n ")" ::: "memory")
; #define PG8_WAIT_L(n) asm volatile("s_waitcnt lgkmcnt(" #n ")" ::: "memory")
; #define PG8_BAR __builtin_amdgcn_s_barrier()
; #define PG8_SCHED __builtin_amdgcn_sched_barrier(0)
; template <class Epi>
; __device__ __forceinline__ void gemm_phase(LAS unsigned char* lds, const Gemm g, int G, int c, const Epi& E) {
;     ...
;             PG8_LDA(At, 1, 1); PG8_STAGE(PG8_SB(1, 0), b3, voffB); PG8_STAGE(PG8_SB(1, 1), b3 + hstepB, voffB); PG8_STAGE(PG8_SA(1, 0), a3, voffA);
;             PG8_WAIT_V(8); PG8_WAIT_L(0); PG8_BAR; PG8_MMA(1, 0, At, B0); PG8_MMA(1, 1, At, B1); PG8_BAR; PG8_SCHED;
;         }
;         if (wr == 0) PG8_BAR;
	s_add_i32 s33, s33, s52
	v_lshl_add_u64 v[216:217], v[216:217], 0, s[6:7]
	s_mov_b32 m0, s33
	ds_read_b128 v[184:187], v154 offset:49152
	ds_read_b128 v[188:191], v154 offset:50176
	ds_read_b128 v[192:195], v154 offset:51200
	ds_read_b128 v[196:199], v154 offset:52224
	ds_read_b128 v[200:203], v154 offset:53248
	ds_read_b128 v[204:207], v154 offset:54272
	ds_read_b128 v[208:211], v154 offset:55296
	ds_read_b128 v[212:215], v154 offset:56320
	global_load_lds_dwordx4 v[216:217], off
	s_add_i32 m0, s33, 0x2000
	s_add_u32 s42, s42, 0x100080
	v_lshl_add_u64 v[216:217], v[218:219], 0, s[6:7]
	s_addc_u32 s43, s43, 0
	s_add_i32 s33, s64, s52
	global_load_lds_dwordx4 v[216:217], off
	v_lshl_add_u64 v[216:217], s[42:43], 0, v[134:135]
	s_mov_b32 m0, s33
	s_nop 0
	global_load_lds_dwordx4 v[216:217], off
	v_lshl_add_u64 v[216:217], s[42:43], 0, v[130:131]
	s_add_i32 m0, s33, 0x2000
	s_nop 0
	global_load_lds_dwordx4 v[216:217], off
	v_lshl_add_u64 v[216:217], v[220:221], 0, s[6:7]
	s_mov_b32 m0, s59
	s_nop 0
	global_load_lds_dwordx4 v[216:217], off
	v_lshl_add_u64 v[216:217], v[222:223], 0, s[6:7]
	s_mov_b32 m0, s60
	s_nop 0
	global_load_lds_dwordx4 v[216:217], off
	s_waitcnt vmcnt(8)
	s_waitcnt lgkmcnt(0)
	s_barrier
	s_setprio 0
	v_mfma_f32_16x16x32_bf16 v[62:65], v[146:149], v[184:187], v[62:65]
	v_mfma_f32_16x16x32_bf16 v[58:61], v[160:163], v[184:187], v[58:61]
	v_mfma_f32_16x16x32_bf16 v[54:57], v[146:149], v[192:195], v[54:57]
	v_mfma_f32_16x16x32_bf16 v[46:49], v[160:163], v[192:195], v[46:49]
	v_mfma_f32_16x16x32_bf16 v[38:41], v[146:149], v[200:203], v[38:41]
	v_mfma_f32_16x16x32_bf16 v[30:33], v[160:163], v[200:203], v[30:33]
	v_mfma_f32_16x16x32_bf16 v[22:25], v[146:149], v[208:211], v[22:25]
	v_mfma_f32_16x16x32_bf16 v[14:17], v[160:163], v[208:211], v[14:17]
	v_mfma_f32_16x16x32_bf16 v[62:65], v[156:159], v[188:191], v[62:65]
	v_mfma_f32_16x16x32_bf16 v[58:61], v[164:167], v[188:191], v[58:61]
	v_mfma_f32_16x16x32_bf16 v[54:57], v[156:159], v[196:199], v[54:57]
	v_mfma_f32_16x16x32_bf16 v[46:49], v[164:167], v[196:199], v[46:49]
	v_mfma_f32_16x16x32_bf16 v[38:41], v[156:159], v[204:207], v[38:41]
	v_mfma_f32_16x16x32_bf16 v[30:33], v[164:167], v[204:207], v[30:33]
	v_mfma_f32_16x16x32_bf16 v[22:25], v[156:159], v[212:215], v[22:25]
	v_mfma_f32_16x16x32_bf16 v[14:17], v[164:167], v[212:215], v[14:17]
	s_setprio 2
	s_setprio 0
	v_mfma_f32_16x16x32_bf16 v[50:53], v[168:171], v[184:187], v[50:53]
	v_mfma_f32_16x16x32_bf16 v[42:45], v[176:179], v[184:187], v[42:45]
	v_mfma_f32_16x16x32_bf16 v[34:37], v[168:171], v[192:195], v[34:37]
	v_mfma_f32_16x16x32_bf16 v[26:29], v[176:179], v[192:195], v[26:29]
	v_mfma_f32_16x16x32_bf16 v[18:21], v[168:171], v[200:203], v[18:21]
	v_mfma_f32_16x16x32_bf16 v[10:13], v[176:179], v[200:203], v[10:13]
	v_mfma_f32_16x16x32_bf16 v[6:9], v[168:171], v[208:211], v[6:9]
	v_mfma_f32_16x16x32_bf16 v[2:5], v[176:179], v[208:211], v[2:5]
	v_mfma_f32_16x16x32_bf16 v[50:53], v[172:175], v[188:191], v[50:53]
	v_mfma_f32_16x16x32_bf16 v[42:45], v[180:183], v[188:191], v[42:45]
	v_mfma_f32_16x16x32_bf16 v[34:37], v[172:175], v[196:199], v[34:37]
	v_mfma_f32_16x16x32_bf16 v[26:29], v[180:183], v[196:199], v[26:29]
	v_mfma_f32_16x16x32_bf16 v[18:21], v[172:175], v[204:207], v[18:21]
	v_mfma_f32_16x16x32_bf16 v[10:13], v[180:183], v[204:207], v[10:13]
	v_mfma_f32_16x16x32_bf16 v[6:9], v[172:175], v[212:215], v[6:9]
	v_mfma_f32_16x16x32_bf16 v[2:5], v[180:183], v[212:215], v[2:5]
	s_setprio 2
	s_barrier
	s_add_i32 s68, s68, 2
	s_add_u32 s40, s40, 0x100
	s_addc_u32 s41, s41, 0
	s_add_u32 s66, s66, 0x100
	s_addc_u32 s67, s67, 0
	s_cmp_gt_u32 s68, 61
	s_cbranch_scc0 .LBB0_1825
	s_and_b64 vcc, exec, s[8:9]
	s_cbranch_vccz .LBB0_1828
	s_barrier

; #define PG8_STAGE(bufoff, gbase, voff) do { _Pragma("unroll") for (int _i = 0; _i < 2; ++_i) \
;         __builtin_amdgcn_global_load_lds((const unsigned*)((const char*)(gbase) + (voff)[_i]), (LAS unsigned*)(lds + (bufoff) + ldsw + _i * 8192), 16, 0, 0); } while (0)
; #define PG8_LDA(dst, b, h) do { _Pragma("unroll") for (int m = 0; m < 4; ++m) _Pragma("unroll") for (int k = 0; k < 2; ++k) dst[m][k] = *(const LAS bf16x8*)(lds + PG8_SA(b, h) + aoff + m * 2048 + k * 1024); } while (0)
; #define PG8_LDB(dst, b, h) do { _Pragma("unroll") for (int n = 0; n < 2; ++n) _Pragma("unroll") for (int k = 0; k < 2; ++k) dst[n][k] = *(const LAS bf16x8*)(lds + PG8_SB(b, h) + boff + n * 2048 + k * 1024); } while (0)
; #define PG8_MMA(ai, bj, At, Bt) do { __builtin_amdgcn_s_setprio(1); _Pragma("unroll") for (int m = 0; m < 4; ++m) _Pragma("unroll") for (int n = 0; n < 2; ++n) _Pragma("unroll") for (int k = 0; k < 2; ++k) \
;         acc[ai][bj][m][n] = __builtin_amdgcn_mfma_f32_16x16x32_bf16(Bt[n][k], At[m][k], acc[ai][bj][m][n], 0, 0, 0); __builtin_amdgcn_s_setprio(0); } while (0)
; #define PG8_WAIT_V(n) asm volatile("s_waitcnt vmcnt(" #n ")" ::: "memory")
; template <class Epi>
; __device__ __forceinline__ void gemm_phase(LAS unsigned char* lds, const Gemm g, int G, int c, const Epi& E) {
;     ...
;         const bool has_next = S.next(ui + 1, nxt);
;         const char* nA = has_next ? (const char*)(g.A + (size_t)nxt.pb * g.sA) + (size_t)nxt.pm * 2 * hstepA : cA;
;         const char* nB = has_next ? (const char*)(g.Bt + (size_t)nxt.pb * g.sB) + (size_t)nxt.pn * 2 * hstepB : cB;
; #pragma nounroll
;         for (int t = 0; t < nt; t += 2) {
;             const bool last = (t == nt - 2);
;             const char* a1 = cA + (size_t)(t + 1) * kstep;
;             const char* a2 = last ? nA : cA + (size_t)(t + 2) * kstep; const char* b2 = last ? nB : cB + (size_t)(t + 2) * kstep;
;             const char* a3 = a2 + kstep; const char* b3 = b2 + kstep;
;             PG8_LDB(B0, 0, 0); PG8_LDB(B1, 0, 1); PG8_SCHED; PG8_LDA(At, 0, 0); PG8_STAGE(PG8_SA(1, 1), a1 + hstepA, voffA);
;             PG8_WAIT_V(8); PG8_WAIT_L(0); PG8_BAR; PG8_MMA(0, 0, At, B0); PG8_MMA(0, 1, At, B1); PG8_BAR; PG8_SCHED;
;             PG8_LDA(At, 0, 1); PG8_STAGE(PG8_SB(0, 0), b2, voffB); PG8_STAGE(PG8_SB(0, 1), b2 + hstepB, voffB); PG8_STAGE(PG8_SA(0, 0), a2, voffA);
.LBB0_1930:
	s_ashr_i32 s15, s14, 31
	s_lshl_b64 s[20:21], s[14:15], 19
	s_add_u32 s20, s40, s20
	s_addc_u32 s21, s41, s21
	s_and_b64 s[4:5], s[4:5], exec
	s_cselect_b32 s15, s21, s37
	s_cselect_b32 s17, s20, s36
	s_add_u32 s4, s38, 0x40080
	s_addc_u32 s5, s39, 0
	s_add_u32 s60, s36, 0x100
	s_addc_u32 s61, s37, 0
	s_mov_b32 s62, -2
	s_waitcnt vmcnt(0)
	ds_read_b128 v[122:125], v168
	ds_read_b128 v[126:129], v168 offset:1024
	ds_read_b128 v[130:133], v168 offset:2048
	ds_read_b128 v[134:137], v168 offset:3072
	ds_read_b128 v[162:165], v169
	ds_read_b128 v[172:175], v169 offset:1024
	ds_read_b128 v[176:179], v169 offset:2048
	ds_read_b128 v[180:183], v169 offset:3072
	s_add_u32 s33, s4, 0xfffc0080
	s_addc_u32 s36, s5, -1
	s_cmp_eq_u32 s62, 12
	s_cselect_b32 s39, s19, s36
	s_cselect_b32 s38, s18, s33
	s_cselect_b32 s37, s15, s61
	s_cselect_b32 s36, s17, s60
	v_lshl_add_u64 v[216:217], s[4:5], 0, v[154:155]
	s_add_i32 m0, s23, 0xc000
	ds_read_b128 v[184:187], v170
	ds_read_b128 v[188:191], v170 offset:1024
	ds_read_b128 v[192:195], v170 offset:2048
	ds_read_b128 v[196:199], v170 offset:3072
	ds_read_b128 v[200:203], v170 offset:4096
	ds_read_b128 v[204:207], v170 offset:5120
	ds_read_b128 v[208:211], v170 offset:6144
	ds_read_b128 v[212:215], v170 offset:7168
	global_load_lds_dwordx4 v[216:217], off
	v_lshl_add_u64 v[216:217], s[4:5], 0, v[156:157]
	s_add_i32 m0, s23, 0xe000
	s_nop 0
	global_load_lds_dwordx4 v[216:217], off
	s_waitcnt vmcnt(8)
	s_waitcnt lgkmcnt(0)
	s_barrier
	s_setprio 0
	v_mfma_f32_16x16x32_bf16 v[142:145], v[122:125], v[184:187], 0
	v_mfma_f32_16x16x32_bf16 v[138:141], v[130:133], v[184:187], 0
	v_mfma_f32_16x16x32_bf16 v[118:121], v[122:125], v[192:195], 0
	v_mfma_f32_16x16x32_bf16 v[106:109], v[130:133], v[192:195], 0
	v_mfma_f32_16x16x32_bf16 v[102:105], v[122:125], v[200:203], 0
	v_mfma_f32_16x16x32_bf16 v[90:93], v[130:133], v[200:203], 0
	v_mfma_f32_16x16x32_bf16 v[86:89], v[122:125], v[208:211], 0
	v_mfma_f32_16x16x32_bf16 v[74:77], v[130:133], v[208:211], 0
	v_mfma_f32_16x16x32_bf16 v[142:145], v[126:129], v[188:191], v[142:145]
	v_mfma_f32_16x16x32_bf16 v[138:141], v[134:137], v[188:191], v[138:141]
	v_mfma_f32_16x16x32_bf16 v[118:121], v[126:129], v[196:199], v[118:121]
	v_mfma_f32_16x16x32_bf16 v[106:109], v[134:137], v[196:199], v[106:109]
	v_mfma_f32_16x16x32_bf16 v[102:105], v[126:129], v[204:207], v[102:105]
	v_mfma_f32_16x16x32_bf16 v[90:93], v[134:137], v[204:207], v[90:93]
	v_mfma_f32_16x16x32_bf16 v[86:89], v[126:129], v[212:215], v[86:89]
	v_mfma_f32_16x16x32_bf16 v[74:77], v[134:137], v[212:215], v[74:77]
	s_setprio 2
	s_setprio 0
	v_mfma_f32_16x16x32_bf16 v[114:117], v[162:165], v[184:187], 0
	v_mfma_f32_16x16x32_bf16 v[110:113], v[176:179], v[184:187], 0
	v_mfma_f32_16x16x32_bf16 v[98:101], v[162:165], v[192:195], 0
	v_mfma_f32_16x16x32_bf16 v[94:97], v[176:179], v[192:195], 0
	v_mfma_f32_16x16x32_bf16 v[82:85], v[162:165], v[200:203], 0
	v_mfma_f32_16x16x32_bf16 v[78:81], v[176:179], v[200:203], 0
	v_mfma_f32_16x16x32_bf16 v[70:73], v[162:165], v[208:211], 0
	v_mfma_f32_16x16x32_bf16 v[66:69], v[176:179], v[208:211], 0
	v_mfma_f32_16x16x32_bf16 v[114:117], v[172:175], v[188:191], v[114:117]
	v_mfma_f32_16x16x32_bf16 v[110:113], v[180:183], v[188:191], v[110:113]
	v_mfma_f32_16x16x32_bf16 v[98:101], v[172:175], v[196:199], v[98:101]
	v_mfma_f32_16x16x32_bf16 v[94:97], v[180:183], v[196:199], v[94:97]
	v_mfma_f32_16x16x32_bf16 v[82:85], v[172:175], v[204:207], v[82:85]
	v_mfma_f32_16x16x32_bf16 v[78:81], v[180:183], v[204:207], v[78:81]
	v_mfma_f32_16x16x32_bf16 v[70:73], v[172:175], v[212:215], v[70:73]
	v_mfma_f32_16x16x32_bf16 v[66:69], v[180:183], v[212:215], v[66:69]
	s_setprio 2
	s_barrier
	s_add_i32 s33, s56, s42
	v_lshl_add_u64 v[216:217], s[36:37], 0, v[150:151]
	s_mov_b32 m0, s33
	ds_read_b128 v[184:187], v170 offset:16384
	ds_read_b128 v[188:191], v170 offset:17408
	ds_read_b128 v[192:195], v170 offset:18432
	ds_read_b128 v[196:199], v170 offset:19456
	ds_read_b128 v[200:203], v170 offset:20480
	ds_read_b128 v[204:207], v170 offset:21504
	ds_read_b128 v[208:211], v170 offset:22528
	ds_read_b128 v[212:215], v170 offset:23552
	global_load_lds_dwordx4 v[216:217], off
	s_add_i32 m0, s33, 0x2000
	s_add_u32 s64, s36, 0x40000
	v_lshl_add_u64 v[218:219], s[36:37], 0, v[146:147]
	s_addc_u32 s65, s37, 0
	s_add_i32 s33, s57, s42
	global_load_lds_dwordx4 v[218:219], off
	v_lshl_add_u64 v[220:221], s[64:65], 0, v[150:151]
	s_mov_b32 m0, s33
	v_lshl_add_u64 v[222:223], s[38:39], 0, v[148:149]
	global_load_lds_dwordx4 v[220:221], off
	v_lshl_add_u64 v[220:221], s[64:65], 0, v[146:147]
	s_add_i32 m0, s33, 0x2000
	s_nop 0
	global_load_lds_dwordx4 v[220:221], off
	v_lshl_add_u64 v[220:221], s[38:39], 0, v[152:153]
	s_mov_b32 m0, s23
	s_nop 0
	global_load_lds_dwordx4 v[220:221], off
	s_mov_b32 m0, s25
	s_nop 0
	global_load_lds_dwordx4 v[222:223], off
	s_waitcnt vmcnt(8)
	s_waitcnt lgkmcnt(0)
	s_barrier
; #define PG8_STAGE(bufoff, gbase, voff) do { _Pragma("unroll") for (int _i = 0; _i < 2; ++_i) \
;         __builtin_amdgcn_global_load_lds((const unsigned*)((const char*)(gbase) + (voff)[_i]), (LAS unsigned*)(lds + (bufoff) + ldsw + _i * 8192), 16, 0, 0); } while (0)
; #define PG8_LDA(dst, b, h) do { _Pragma("unroll") for (int m = 0; m < 4; ++m) _Pragma("unroll") for (int k = 0; k < 2; ++k) dst[m][k] = *(const LAS bf16x8*)(lds + PG8_SA(b, h) + aoff + m * 2048 + k * 1024); } while (0)
; #define PG8_LDB(dst, b, h) do { _Pragma("unroll") for (int n = 0; n < 2; ++n) _Pragma("unroll") for (int k = 0; k < 2; ++k) dst[n][k] = *(const LAS bf16x8*)(lds + PG8_SB(b, h) + boff + n * 2048 + k * 1024); } while (0)
; #define PG8_MMA(ai, bj, At, Bt) do { __builtin_amdgcn_s_setprio(1); _Pragma("unroll") for (int m = 0; m < 4; ++m) _Pragma("unroll") for (int n = 0; n < 2; ++n) _Pragma("unroll") for (int k = 0; k < 2; ++k) \
;         acc[ai][bj][m][n] = __builtin_amdgcn_mfma_f32_16x16x32_bf16(Bt[n][k], At[m][k], acc[ai][bj][m][n], 0, 0, 0); __builtin_amdgcn_s_setprio(0); } while (0)
; #define PG8_WAIT_V(n) asm volatile("s_waitcnt vmcnt(" #n ")" ::: "memory")
; #define PG8_WAIT_L(n) asm volatile("s_waitcnt lgkmcnt(" #n ")" ::: "memory")
; #define PG8_BAR __builtin_amdgcn_s_barrier()
; #define PG8_SCHED __builtin_amdgcn_sched_barrier(0)
; template <class Epi>
; __device__ __forceinline__ void gemm_phase(LAS unsigned char* lds, const Gemm g, int G, int c, const Epi& E) {
;     ...
;             PG8_WAIT_V(8); PG8_WAIT_L(0); PG8_BAR; PG8_MMA(1, 0, At, B0); PG8_MMA(1, 1, At, B1); PG8_BAR; PG8_SCHED;
;             PG8_LDB(B0, 1, 0); PG8_LDB(B1, 1, 1); PG8_SCHED; PG8_LDA(At, 1, 0); PG8_STAGE(PG8_SA(0, 1), a2 + hstepA, voffA);
;             PG8_WAIT_V(8); PG8_WAIT_L(0); PG8_BAR; PG8_MMA(0, 0, At, B0); PG8_MMA(0, 1, At, B1); PG8_BAR; PG8_SCHED;
	s_setprio 0
	v_mfma_f32_16x16x32_bf16 v[62:65], v[122:125], v[184:187], 0
	v_mfma_f32_16x16x32_bf16 v[58:61], v[130:133], v[184:187], 0
	v_mfma_f32_16x16x32_bf16 v[54:57], v[122:125], v[192:195], 0
	v_mfma_f32_16x16x32_bf16 v[42:45], v[130:133], v[192:195], 0
	v_mfma_f32_16x16x32_bf16 v[38:41], v[122:125], v[200:203], 0
	v_mfma_f32_16x16x32_bf16 v[26:29], v[130:133], v[200:203], 0
	v_mfma_f32_16x16x32_bf16 v[22:25], v[122:125], v[208:211], 0
	v_mfma_f32_16x16x32_bf16 v[10:13], v[130:133], v[208:211], 0
	v_mfma_f32_16x16x32_bf16 v[62:65], v[126:129], v[188:191], v[62:65]
	v_mfma_f32_16x16x32_bf16 v[58:61], v[134:137], v[188:191], v[58:61]
	v_mfma_f32_16x16x32_bf16 v[54:57], v[126:129], v[196:199], v[54:57]
	v_mfma_f32_16x16x32_bf16 v[42:45], v[134:137], v[196:199], v[42:45]
	v_mfma_f32_16x16x32_bf16 v[38:41], v[126:129], v[204:207], v[38:41]
	v_mfma_f32_16x16x32_bf16 v[26:29], v[134:137], v[204:207], v[26:29]
	v_mfma_f32_16x16x32_bf16 v[22:25], v[126:129], v[212:215], v[22:25]
	v_mfma_f32_16x16x32_bf16 v[10:13], v[134:137], v[212:215], v[10:13]
	s_setprio 2
	s_setprio 0
	v_mfma_f32_16x16x32_bf16 v[50:53], v[162:165], v[184:187], 0
	v_mfma_f32_16x16x32_bf16 v[46:49], v[176:179], v[184:187], 0
	v_mfma_f32_16x16x32_bf16 v[34:37], v[162:165], v[192:195], 0
	v_mfma_f32_16x16x32_bf16 v[30:33], v[176:179], v[192:195], 0
	v_mfma_f32_16x16x32_bf16 v[18:21], v[162:165], v[200:203], 0
	v_mfma_f32_16x16x32_bf16 v[14:17], v[176:179], v[200:203], 0
	v_mfma_f32_16x16x32_bf16 v[6:9], v[162:165], v[208:211], 0
	v_mfma_f32_16x16x32_bf16 v[2:5], v[176:179], v[208:211], 0
	v_mfma_f32_16x16x32_bf16 v[50:53], v[172:175], v[188:191], v[50:53]
	v_mfma_f32_16x16x32_bf16 v[46:49], v[180:183], v[188:191], v[46:49]
	v_mfma_f32_16x16x32_bf16 v[34:37], v[172:175], v[196:199], v[34:37]
	v_mfma_f32_16x16x32_bf16 v[30:33], v[180:183], v[196:199], v[30:33]
	v_mfma_f32_16x16x32_bf16 v[18:21], v[172:175], v[204:207], v[18:21]
	v_mfma_f32_16x16x32_bf16 v[14:17], v[180:183], v[204:207], v[14:17]
	v_mfma_f32_16x16x32_bf16 v[6:9], v[172:175], v[212:215], v[6:9]
	v_mfma_f32_16x16x32_bf16 v[2:5], v[180:183], v[212:215], v[2:5]
	s_setprio 2
	s_barrier
	s_add_i32 s33, 0, 0x18000
	s_add_i32 s63, 0, 0x1c000
	v_add_u32_e32 v134, s33, v167
	v_add_u32_e32 v171, s63, v167
	ds_read_b128 v[122:125], v134
	ds_read_b128 v[126:129], v134 offset:1024
	ds_read_b128 v[130:133], v134 offset:2048
	ds_read_b128 v[134:137], v134 offset:3072
	ds_read_b128 v[162:165], v171
	ds_read_b128 v[172:175], v171 offset:1024
	ds_read_b128 v[176:179], v171 offset:2048
	ds_read_b128 v[180:183], v171 offset:3072
	s_add_u32 s38, s38, 0x40000
	s_addc_u32 s39, s39, 0
	s_mov_b32 m0, s44
	v_lshl_add_u64 v[224:225], s[38:39], 0, v[152:153]
	ds_read_b128 v[184:187], v170 offset:32768
	ds_read_b128 v[188:191], v170 offset:33792
	ds_read_b128 v[192:195], v170 offset:34816
	ds_read_b128 v[196:199], v170 offset:35840
	ds_read_b128 v[200:203], v170 offset:36864
	ds_read_b128 v[204:207], v170 offset:37888
	ds_read_b128 v[208:211], v170 offset:38912
	ds_read_b128 v[212:215], v170 offset:39936
	global_load_lds_dwordx4 v[224:225], off
	v_lshl_add_u64 v[224:225], s[38:39], 0, v[148:149]
	s_mov_b32 m0, s45
	s_nop 0
	global_load_lds_dwordx4 v[224:225], off
	s_waitcnt vmcnt(8)
	s_waitcnt lgkmcnt(0)
	s_barrier
	s_setprio 0
	v_mfma_f32_16x16x32_bf16 v[142:145], v[122:125], v[184:187], v[142:145]
	v_mfma_f32_16x16x32_bf16 v[138:141], v[130:133], v[184:187], v[138:141]
	v_mfma_f32_16x16x32_bf16 v[118:121], v[122:125], v[192:195], v[118:121]
	v_mfma_f32_16x16x32_bf16 v[106:109], v[130:133], v[192:195], v[106:109]
	v_mfma_f32_16x16x32_bf16 v[102:105], v[122:125], v[200:203], v[102:105]
	v_mfma_f32_16x16x32_bf16 v[90:93], v[130:133], v[200:203], v[90:93]
	v_mfma_f32_16x16x32_bf16 v[86:89], v[122:125], v[208:211], v[86:89]
	v_mfma_f32_16x16x32_bf16 v[74:77], v[130:133], v[208:211], v[74:77]
	v_mfma_f32_16x16x32_bf16 v[142:145], v[126:129], v[188:191], v[142:145]
	v_mfma_f32_16x16x32_bf16 v[138:141], v[134:137], v[188:191], v[138:141]
	v_mfma_f32_16x16x32_bf16 v[118:121], v[126:129], v[196:199], v[118:121]
	v_mfma_f32_16x16x32_bf16 v[106:109], v[134:137], v[196:199], v[106:109]
	v_mfma_f32_16x16x32_bf16 v[102:105], v[126:129], v[204:207], v[102:105]
	v_mfma_f32_16x16x32_bf16 v[90:93], v[134:137], v[204:207], v[90:93]
	v_mfma_f32_16x16x32_bf16 v[86:89], v[126:129], v[212:215], v[86:89]
	v_mfma_f32_16x16x32_bf16 v[74:77], v[134:137], v[212:215], v[74:77]
	s_setprio 2
	s_setprio 0
	v_mfma_f32_16x16x32_bf16 v[114:117], v[162:165], v[184:187], v[114:117]
	v_mfma_f32_16x16x32_bf16 v[110:113], v[176:179], v[184:187], v[110:113]
	v_mfma_f32_16x16x32_bf16 v[98:101], v[162:165], v[192:195], v[98:101]
	v_mfma_f32_16x16x32_bf16 v[94:97], v[176:179], v[192:195], v[94:97]
	v_mfma_f32_16x16x32_bf16 v[82:85], v[162:165], v[200:203], v[82:85]
	v_mfma_f32_16x16x32_bf16 v[78:81], v[176:179], v[200:203], v[78:81]
	v_mfma_f32_16x16x32_bf16 v[70:73], v[162:165], v[208:211], v[70:73]
	v_mfma_f32_16x16x32_bf16 v[66:69], v[176:179], v[208:211], v[66:69]
	v_mfma_f32_16x16x32_bf16 v[114:117], v[172:175], v[188:191], v[114:117]
	v_mfma_f32_16x16x32_bf16 v[110:113], v[180:183], v[188:191], v[110:113]
	v_mfma_f32_16x16x32_bf16 v[98:101], v[172:175], v[196:199], v[98:101]
	v_mfma_f32_16x16x32_bf16 v[94:97], v[180:183], v[196:199], v[94:97]
	v_mfma_f32_16x16x32_bf16 v[82:85], v[172:175], v[204:207], v[82:85]
	v_mfma_f32_16x16x32_bf16 v[78:81], v[180:183], v[204:207], v[78:81]
	v_mfma_f32_16x16x32_bf16 v[70:73], v[172:175], v[212:215], v[70:73]
	v_mfma_f32_16x16x32_bf16 v[66:69], v[180:183], v[212:215], v[66:69]
	s_setprio 2
	s_barrier
; #define PG8_STAGE(bufoff, gbase, voff) do { _Pragma("unroll") for (int _i = 0; _i < 2; ++_i) \
;         __builtin_amdgcn_global_load_lds((const unsigned*)((const char*)(gbase) + (voff)[_i]), (LAS unsigned*)(lds + (bufoff) + ldsw + _i * 8192), 16, 0, 0); } while (0)
; #define PG8_LDA(dst, b, h) do { _Pragma("unroll") for (int m = 0; m < 4; ++m) _Pragma("unroll") for (int k = 0; k < 2; ++k) dst[m][k] = *(const LAS bf16x8*)(lds + PG8_SA(b, h) + aoff + m * 2048 + k * 1024); } while (0)
; #define PG8_LDB(dst, b, h) do { _Pragma("unroll") for (int n = 0; n < 2; ++n) _Pragma("unroll") for (int k = 0; k < 2; ++k) dst[n][k] = *(const LAS bf16x8*)(lds + PG8_SB(b, h) + boff + n * 2048 + k * 1024); } while (0)
; #define PG8_MMA(ai, bj, At, Bt) do { __builtin_amdgcn_s_setprio(1); _Pragma("unroll") for (int m = 0; m < 4; ++m) _Pragma("unroll") for (int n = 0; n < 2; ++n) _Pragma("unroll") for (int k = 0; k < 2; ++k) \
;         acc[ai][bj][m][n] = __builtin_amdgcn_mfma_f32_16x16x32_bf16(Bt[n][k], At[m][k], acc[ai][bj][m][n], 0, 0, 0); __builtin_amdgcn_s_setprio(0); } while (0)
; #define PG8_WAIT_V(n) asm volatile("s_waitcnt vmcnt(" #n ")" ::: "memory")
; #define PG8_BAR __builtin_amdgcn_s_barrier()
; template <class Epi>
; __device__ __forceinline__ void gemm_phase(LAS unsigned char* lds, const Gemm g, int G, int c, const Epi& E) {
;     ...
;             PG8_LDB(B0, 0, 0); PG8_LDB(B1, 0, 1); PG8_SCHED; PG8_LDA(At, 0, 0); PG8_STAGE(PG8_SA(1, 1), a1 + hstepA, voffA);
;             PG8_WAIT_V(8); PG8_WAIT_L(0); PG8_BAR; PG8_MMA(0, 0, At, B0); PG8_MMA(0, 1, At, B1); PG8_BAR; PG8_SCHED;
;             PG8_LDA(At, 0, 1); PG8_STAGE(PG8_SB(0, 0), b2, voffB); PG8_STAGE(PG8_SB(0, 1), b2 + hstepB, voffB); PG8_STAGE(PG8_SA(0, 0), a2, voffA);
;             PG8_WAIT_V(8); PG8_WAIT_L(0); PG8_BAR; PG8_MMA(1, 0, At, B0); PG8_MMA(1, 1, At, B1); PG8_BAR; PG8_SCHED;
;             PG8_LDB(B0, 1, 0); PG8_LDB(B1, 1, 1); PG8_SCHED; PG8_LDA(At, 1, 0); PG8_STAGE(PG8_SA(0, 1), a2 + hstepA, voffA);
;             PG8_WAIT_V(8); PG8_WAIT_L(0); PG8_BAR; PG8_MMA(0, 0, At, B0); PG8_MMA(0, 1, At, B1); PG8_BAR; PG8_SCHED;
;             PG8_LDA(At, 1, 1); PG8_STAGE(PG8_SB(1, 0), b3, voffB); PG8_STAGE(PG8_SB(1, 1), b3 + hstepB, voffB); PG8_STAGE(PG8_SA(1, 0), a3, voffA);
;             PG8_WAIT_V(8); PG8_WAIT_L(0); PG8_BAR; PG8_MMA(1, 0, At, B0); PG8_MMA(1, 1, At, B1); PG8_BAR; PG8_SCHED;
	s_add_i32 s33, s33, s42
	v_lshl_add_u64 v[216:217], v[216:217], 0, s[10:11]
	s_mov_b32 m0, s33
	ds_read_b128 v[184:187], v170 offset:49152
	ds_read_b128 v[188:191], v170 offset:50176
	ds_read_b128 v[192:195], v170 offset:51200
	ds_read_b128 v[196:199], v170 offset:52224
	ds_read_b128 v[200:203], v170 offset:53248
	ds_read_b128 v[204:207], v170 offset:54272
	ds_read_b128 v[208:211], v170 offset:55296
	ds_read_b128 v[212:215], v170 offset:56320
	global_load_lds_dwordx4 v[216:217], off
	s_add_i32 m0, s33, 0x2000
	s_add_u32 s36, s36, 0x40080
	v_lshl_add_u64 v[216:217], v[218:219], 0, s[10:11]
	s_addc_u32 s37, s37, 0
	s_add_i32 s33, s63, s42
	global_load_lds_dwordx4 v[216:217], off
	v_lshl_add_u64 v[216:217], s[36:37], 0, v[150:151]
	s_mov_b32 m0, s33
	s_nop 0
	global_load_lds_dwordx4 v[216:217], off
	v_lshl_add_u64 v[216:217], s[36:37], 0, v[146:147]
	s_add_i32 m0, s33, 0x2000
	s_nop 0
	global_load_lds_dwordx4 v[216:217], off
	v_lshl_add_u64 v[216:217], v[220:221], 0, s[10:11]
	s_mov_b32 m0, s53
	s_nop 0
	global_load_lds_dwordx4 v[216:217], off
	v_lshl_add_u64 v[216:217], v[222:223], 0, s[10:11]
	s_mov_b32 m0, s54
	s_nop 0
	global_load_lds_dwordx4 v[216:217], off
	s_waitcnt vmcnt(8)
	s_waitcnt lgkmcnt(0)
	s_barrier
	s_setprio 0
	v_mfma_f32_16x16x32_bf16 v[62:65], v[122:125], v[184:187], v[62:65]
	v_mfma_f32_16x16x32_bf16 v[58:61], v[130:133], v[184:187], v[58:61]
	v_mfma_f32_16x16x32_bf16 v[54:57], v[122:125], v[192:195], v[54:57]
	v_mfma_f32_16x16x32_bf16 v[42:45], v[130:133], v[192:195], v[42:45]
	v_mfma_f32_16x16x32_bf16 v[38:41], v[122:125], v[200:203], v[38:41]
	v_mfma_f32_16x16x32_bf16 v[26:29], v[130:133], v[200:203], v[26:29]
	v_mfma_f32_16x16x32_bf16 v[22:25], v[122:125], v[208:211], v[22:25]
	v_mfma_f32_16x16x32_bf16 v[10:13], v[130:133], v[208:211], v[10:13]
	v_mfma_f32_16x16x32_bf16 v[62:65], v[126:129], v[188:191], v[62:65]
	v_mfma_f32_16x16x32_bf16 v[58:61], v[134:137], v[188:191], v[58:61]
	v_mfma_f32_16x16x32_bf16 v[54:57], v[126:129], v[196:199], v[54:57]
	v_mfma_f32_16x16x32_bf16 v[42:45], v[134:137], v[196:199], v[42:45]
	v_mfma_f32_16x16x32_bf16 v[38:41], v[126:129], v[204:207], v[38:41]
	v_mfma_f32_16x16x32_bf16 v[26:29], v[134:137], v[204:207], v[26:29]
	v_mfma_f32_16x16x32_bf16 v[22:25], v[126:129], v[212:215], v[22:25]
	v_mfma_f32_16x16x32_bf16 v[10:13], v[134:137], v[212:215], v[10:13]
	s_setprio 2
	s_setprio 0
	v_mfma_f32_16x16x32_bf16 v[50:53], v[162:165], v[184:187], v[50:53]
	v_mfma_f32_16x16x32_bf16 v[46:49], v[176:179], v[184:187], v[46:49]
	v_mfma_f32_16x16x32_bf16 v[34:37], v[162:165], v[192:195], v[34:37]
	v_mfma_f32_16x16x32_bf16 v[30:33], v[176:179], v[192:195], v[30:33]
	v_mfma_f32_16x16x32_bf16 v[18:21], v[162:165], v[200:203], v[18:21]
	v_mfma_f32_16x16x32_bf16 v[14:17], v[176:179], v[200:203], v[14:17]
	v_mfma_f32_16x16x32_bf16 v[6:9], v[162:165], v[208:211], v[6:9]
	v_mfma_f32_16x16x32_bf16 v[2:5], v[176:179], v[208:211], v[2:5]
	v_mfma_f32_16x16x32_bf16 v[50:53], v[172:175], v[188:191], v[50:53]
	v_mfma_f32_16x16x32_bf16 v[46:49], v[180:183], v[188:191], v[46:49]
	v_mfma_f32_16x16x32_bf16 v[34:37], v[172:175], v[196:199], v[34:37]
	v_mfma_f32_16x16x32_bf16 v[30:33], v[180:183], v[196:199], v[30:33]
	v_mfma_f32_16x16x32_bf16 v[18:21], v[172:175], v[204:207], v[18:21]
	v_mfma_f32_16x16x32_bf16 v[14:17], v[180:183], v[204:207], v[14:17]
	v_mfma_f32_16x16x32_bf16 v[6:9], v[172:175], v[212:215], v[6:9]
	v_mfma_f32_16x16x32_bf16 v[2:5], v[180:183], v[212:215], v[2:5]
	s_setprio 2
	s_barrier
	s_add_i32 s62, s62, 2
	s_add_u32 s4, s4, 0x100
	s_addc_u32 s5, s5, 0
	s_add_u32 s60, s60, 0x100
	s_addc_u32 s61, s61, 0
	s_cmp_gt_u32 s62, 13
	s_cbranch_scc0 .LBB0_1931
.LBB0_1931:
	ds_read_b128 v[122:125], v168
	ds_read_b128 v[126:129], v168 offset:1024
	ds_read_b128 v[130:133], v168 offset:2048
	ds_read_b128 v[134:137], v168 offset:3072
	ds_read_b128 v[162:165], v169
	ds_read_b128 v[172:175], v169 offset:1024
	ds_read_b128 v[176:179], v169 offset:2048
	ds_read_b128 v[180:183], v169 offset:3072
	s_add_u32 s33, s4, 0xfffc0080
	s_addc_u32 s36, s5, -1
	s_cmp_eq_u32 s62, 12
	s_cselect_b32 s39, s19, s36
	s_cselect_b32 s38, s18, s33
	s_cselect_b32 s37, s15, s61
	s_cselect_b32 s36, s17, s60
	v_lshl_add_u64 v[216:217], s[4:5], 0, v[154:155]
	s_add_i32 m0, s23, 0xc000
	ds_read_b128 v[184:187], v170
	ds_read_b128 v[188:191], v170 offset:1024
	ds_read_b128 v[192:195], v170 offset:2048
	ds_read_b128 v[196:199], v170 offset:3072
	ds_read_b128 v[200:203], v170 offset:4096
	ds_read_b128 v[204:207], v170 offset:5120
	ds_read_b128 v[208:211], v170 offset:6144
	ds_read_b128 v[212:215], v170 offset:7168
	global_load_lds_dwordx4 v[216:217], off
	v_lshl_add_u64 v[216:217], s[4:5], 0, v[156:157]
	s_add_i32 m0, s23, 0xe000
	s_nop 0
	global_load_lds_dwordx4 v[216:217], off
	s_waitcnt vmcnt(8)
	s_waitcnt lgkmcnt(0)
	s_barrier
; #define PG8_STAGE(bufoff, gbase, voff) do { _Pragma("unroll") for (int _i = 0; _i < 2; ++_i) \
;         __builtin_amdgcn_global_load_lds((const unsigned*)((const char*)(gbase) + (voff)[_i]), (LAS unsigned*)(lds + (bufoff) + ldsw + _i * 8192), 16, 0, 0); } while (0)
; #define PG8_LDA(dst, b, h) do { _Pragma("unroll") for (int m = 0; m < 4; ++m) _Pragma("unroll") for (int k = 0; k < 2; ++k) dst[m][k] = *(const LAS bf16x8*)(lds + PG8_SA(b, h) + aoff + m * 2048 + k * 1024); } while (0)
; #define PG8_MMA(ai, bj, At, Bt) do { __builtin_amdgcn_s_setprio(1); _Pragma("unroll") for (int m = 0; m < 4; ++m) _Pragma("unroll") for (int n = 0; n < 2; ++n) _Pragma("unroll") for (int k = 0; k < 2; ++k) \
;         acc[ai][bj][m][n] = __builtin_amdgcn_mfma_f32_16x16x32_bf16(Bt[n][k], At[m][k], acc[ai][bj][m][n], 0, 0, 0); __builtin_amdgcn_s_setprio(0); } while (0)
; #define PG8_WAIT_V(n) asm volatile("s_waitcnt vmcnt(" #n ")" ::: "memory")
; #define PG8_WAIT_L(n) asm volatile("s_waitcnt lgkmcnt(" #n ")" ::: "memory")
; #define PG8_BAR __builtin_amdgcn_s_barrier()
; #define PG8_SCHED __builtin_amdgcn_sched_barrier(0)
; template <class Epi>
; __device__ __forceinline__ void gemm_phase(LAS unsigned char* lds, const Gemm g, int G, int c, const Epi& E) {
;     ...
;             PG8_WAIT_V(8); PG8_WAIT_L(0); PG8_BAR; PG8_MMA(0, 0, At, B0); PG8_MMA(0, 1, At, B1); PG8_BAR; PG8_SCHED;
;             PG8_LDA(At, 0, 1); PG8_STAGE(PG8_SB(0, 0), b2, voffB); PG8_STAGE(PG8_SB(0, 1), b2 + hstepB, voffB); PG8_STAGE(PG8_SA(0, 0), a2, voffA);
;             PG8_WAIT_V(8); PG8_WAIT_L(0); PG8_BAR; PG8_MMA(1, 0, At, B0); PG8_MMA(1, 1, At, B1); PG8_BAR; PG8_SCHED;
	s_setprio 0
	v_mfma_f32_16x16x32_bf16 v[142:145], v[122:125], v[184:187], v[142:145]
	v_mfma_f32_16x16x32_bf16 v[138:141], v[130:133], v[184:187], v[138:141]
	v_mfma_f32_16x16x32_bf16 v[118:121], v[122:125], v[192:195], v[118:121]
	v_mfma_f32_16x16x32_bf16 v[106:109], v[130:133], v[192:195], v[106:109]
	v_mfma_f32_16x16x32_bf16 v[102:105], v[122:125], v[200:203], v[102:105]
	v_mfma_f32_16x16x32_bf16 v[90:93], v[130:133], v[200:203], v[90:93]
	v_mfma_f32_16x16x32_bf16 v[86:89], v[122:125], v[208:211], v[86:89]
	v_mfma_f32_16x16x32_bf16 v[74:77], v[130:133], v[208:211], v[74:77]
	v_mfma_f32_16x16x32_bf16 v[142:145], v[126:129], v[188:191], v[142:145]
	v_mfma_f32_16x16x32_bf16 v[138:141], v[134:137], v[188:191], v[138:141]
	v_mfma_f32_16x16x32_bf16 v[118:121], v[126:129], v[196:199], v[118:121]
	v_mfma_f32_16x16x32_bf16 v[106:109], v[134:137], v[196:199], v[106:109]
	v_mfma_f32_16x16x32_bf16 v[102:105], v[126:129], v[204:207], v[102:105]
	v_mfma_f32_16x16x32_bf16 v[90:93], v[134:137], v[204:207], v[90:93]
	v_mfma_f32_16x16x32_bf16 v[86:89], v[126:129], v[212:215], v[86:89]
	v_mfma_f32_16x16x32_bf16 v[74:77], v[134:137], v[212:215], v[74:77]
	s_setprio 2
	s_setprio 0
	v_mfma_f32_16x16x32_bf16 v[114:117], v[162:165], v[184:187], v[114:117]
	v_mfma_f32_16x16x32_bf16 v[110:113], v[176:179], v[184:187], v[110:113]
	v_mfma_f32_16x16x32_bf16 v[98:101], v[162:165], v[192:195], v[98:101]
	v_mfma_f32_16x16x32_bf16 v[94:97], v[176:179], v[192:195], v[94:97]
	v_mfma_f32_16x16x32_bf16 v[82:85], v[162:165], v[200:203], v[82:85]
	v_mfma_f32_16x16x32_bf16 v[78:81], v[176:179], v[200:203], v[78:81]
	v_mfma_f32_16x16x32_bf16 v[70:73], v[162:165], v[208:211], v[70:73]
	v_mfma_f32_16x16x32_bf16 v[66:69], v[176:179], v[208:211], v[66:69]
	v_mfma_f32_16x16x32_bf16 v[114:117], v[172:175], v[188:191], v[114:117]
	v_mfma_f32_16x16x32_bf16 v[110:113], v[180:183], v[188:191], v[110:113]
	v_mfma_f32_16x16x32_bf16 v[98:101], v[172:175], v[196:199], v[98:101]
	v_mfma_f32_16x16x32_bf16 v[94:97], v[180:183], v[196:199], v[94:97]
	v_mfma_f32_16x16x32_bf16 v[82:85], v[172:175], v[204:207], v[82:85]
	v_mfma_f32_16x16x32_bf16 v[78:81], v[180:183], v[204:207], v[78:81]
	v_mfma_f32_16x16x32_bf16 v[70:73], v[172:175], v[212:215], v[70:73]
	v_mfma_f32_16x16x32_bf16 v[66:69], v[180:183], v[212:215], v[66:69]
	s_setprio 2
	s_barrier
	s_add_i32 s33, s56, s42
	v_lshl_add_u64 v[216:217], s[36:37], 0, v[150:151]
	s_mov_b32 m0, s33
	ds_read_b128 v[184:187], v170 offset:16384
	ds_read_b128 v[188:191], v170 offset:17408
	ds_read_b128 v[192:195], v170 offset:18432
	ds_read_b128 v[196:199], v170 offset:19456
	ds_read_b128 v[200:203], v170 offset:20480
	ds_read_b128 v[204:207], v170 offset:21504
	ds_read_b128 v[208:211], v170 offset:22528
	ds_read_b128 v[212:215], v170 offset:23552
	global_load_lds_dwordx4 v[216:217], off
	s_add_i32 m0, s33, 0x2000
	s_add_u32 s64, s36, 0x40000
	v_lshl_add_u64 v[218:219], s[36:37], 0, v[146:147]
	s_addc_u32 s65, s37, 0
	s_add_i32 s33, s57, s42
	global_load_lds_dwordx4 v[218:219], off
	v_lshl_add_u64 v[220:221], s[64:65], 0, v[150:151]
	s_mov_b32 m0, s33
	v_lshl_add_u64 v[222:223], s[38:39], 0, v[148:149]
	global_load_lds_dwordx4 v[220:221], off
	v_lshl_add_u64 v[220:221], s[64:65], 0, v[146:147]
	s_add_i32 m0, s33, 0x2000
	s_nop 0
	global_load_lds_dwordx4 v[220:221], off
	v_lshl_add_u64 v[220:221], s[38:39], 0, v[152:153]
	s_mov_b32 m0, s23
	s_nop 0
	global_load_lds_dwordx4 v[220:221], off
	s_mov_b32 m0, s25
	s_nop 0
	global_load_lds_dwordx4 v[222:223], off
	s_waitcnt vmcnt(8)
	s_waitcnt lgkmcnt(0)
	s_barrier
	s_setprio 0
	v_mfma_f32_16x16x32_bf16 v[62:65], v[122:125], v[184:187], v[62:65]
	v_mfma_f32_16x16x32_bf16 v[58:61], v[130:133], v[184:187], v[58:61]
	v_mfma_f32_16x16x32_bf16 v[54:57], v[122:125], v[192:195], v[54:57]
	v_mfma_f32_16x16x32_bf16 v[42:45], v[130:133], v[192:195], v[42:45]
	v_mfma_f32_16x16x32_bf16 v[38:41], v[122:125], v[200:203], v[38:41]
	v_mfma_f32_16x16x32_bf16 v[26:29], v[130:133], v[200:203], v[26:29]
	v_mfma_f32_16x16x32_bf16 v[22:25], v[122:125], v[208:211], v[22:25]
	v_mfma_f32_16x16x32_bf16 v[10:13], v[130:133], v[208:211], v[10:13]
	v_mfma_f32_16x16x32_bf16 v[62:65], v[126:129], v[188:191], v[62:65]
	v_mfma_f32_16x16x32_bf16 v[58:61], v[134:137], v[188:191], v[58:61]
	v_mfma_f32_16x16x32_bf16 v[54:57], v[126:129], v[196:199], v[54:57]
	v_mfma_f32_16x16x32_bf16 v[42:45], v[134:137], v[196:199], v[42:45]
	v_mfma_f32_16x16x32_bf16 v[38:41], v[126:129], v[204:207], v[38:41]
	v_mfma_f32_16x16x32_bf16 v[26:29], v[134:137], v[204:207], v[26:29]
	v_mfma_f32_16x16x32_bf16 v[22:25], v[126:129], v[212:215], v[22:25]
	v_mfma_f32_16x16x32_bf16 v[10:13], v[134:137], v[212:215], v[10:13]
	s_setprio 2
	s_setprio 0
	v_mfma_f32_16x16x32_bf16 v[50:53], v[162:165], v[184:187], v[50:53]
	v_mfma_f32_16x16x32_bf16 v[46:49], v[176:179], v[184:187], v[46:49]
	v_mfma_f32_16x16x32_bf16 v[34:37], v[162:165], v[192:195], v[34:37]
	v_mfma_f32_16x16x32_bf16 v[30:33], v[176:179], v[192:195], v[30:33]
	v_mfma_f32_16x16x32_bf16 v[18:21], v[162:165], v[200:203], v[18:21]
	v_mfma_f32_16x16x32_bf16 v[14:17], v[176:179], v[200:203], v[14:17]
	v_mfma_f32_16x16x32_bf16 v[6:9], v[162:165], v[208:211], v[6:9]
	v_mfma_f32_16x16x32_bf16 v[2:5], v[176:179], v[208:211], v[2:5]
	v_mfma_f32_16x16x32_bf16 v[50:53], v[172:175], v[188:191], v[50:53]
	v_mfma_f32_16x16x32_bf16 v[46:49], v[180:183], v[188:191], v[46:49]
	v_mfma_f32_16x16x32_bf16 v[34:37], v[172:175], v[196:199], v[34:37]
	v_mfma_f32_16x16x32_bf16 v[30:33], v[180:183], v[196:199], v[30:33]
	v_mfma_f32_16x16x32_bf16 v[18:21], v[172:175], v[204:207], v[18:21]
	v_mfma_f32_16x16x32_bf16 v[14:17], v[180:183], v[204:207], v[14:17]
	v_mfma_f32_16x16x32_bf16 v[6:9], v[172:175], v[212:215], v[6:9]
	v_mfma_f32_16x16x32_bf16 v[2:5], v[180:183], v[212:215], v[2:5]
	s_setprio 2
	s_barrier
; #define PG8_STAGE(bufoff, gbase, voff) do { _Pragma("unroll") for (int _i = 0; _i < 2; ++_i) \
;         __builtin_amdgcn_global_load_lds((const unsigned*)((const char*)(gbase) + (voff)[_i]), (LAS unsigned*)(lds + (bufoff) + ldsw + _i * 8192), 16, 0, 0); } while (0)
; #define PG8_LDA(dst, b, h) do { _Pragma("unroll") for (int m = 0; m < 4; ++m) _Pragma("unroll") for (int k = 0; k < 2; ++k) dst[m][k] = *(const LAS bf16x8*)(lds + PG8_SA(b, h) + aoff + m * 2048 + k * 1024); } while (0)
; #define PG8_LDB(dst, b, h) do { _Pragma("unroll") for (int n = 0; n < 2; ++n) _Pragma("unroll") for (int k = 0; k < 2; ++k) dst[n][k] = *(const LAS bf16x8*)(lds + PG8_SB(b, h) + boff + n * 2048 + k * 1024); } while (0)
; #define PG8_MMA(ai, bj, At, Bt) do { __builtin_amdgcn_s_setprio(1); _Pragma("unroll") for (int m = 0; m < 4; ++m) _Pragma("unroll") for (int n = 0; n < 2; ++n) _Pragma("unroll") for (int k = 0; k < 2; ++k) \
;         acc[ai][bj][m][n] = __builtin_amdgcn_mfma_f32_16x16x32_bf16(Bt[n][k], At[m][k], acc[ai][bj][m][n], 0, 0, 0); __builtin_amdgcn_s_setprio(0); } while (0)
; #define PG8_WAIT_V(n) asm volatile("s_waitcnt vmcnt(" #n ")" ::: "memory")
; #define PG8_WAIT_L(n) asm volatile("s_waitcnt lgkmcnt(" #n ")" ::: "memory")
; #define PG8_BAR __builtin_amdgcn_s_barrier()
; #define PG8_SCHED __builtin_amdgcn_sched_barrier(0)
; template <class Epi>
; __device__ __forceinline__ void gemm_phase(LAS unsigned char* lds, const Gemm g, int G, int c, const Epi& E) {
;     ...
;             PG8_LDB(B0, 1, 0); PG8_LDB(B1, 1, 1); PG8_SCHED; PG8_LDA(At, 1, 0); PG8_STAGE(PG8_SA(0, 1), a2 + hstepA, voffA);
;             PG8_WAIT_V(8); PG8_WAIT_L(0); PG8_BAR; PG8_MMA(0, 0, At, B0); PG8_MMA(0, 1, At, B1); PG8_BAR; PG8_SCHED;
	s_add_i32 s33, 0, 0x18000
	s_add_i32 s63, 0, 0x1c000
	v_add_u32_e32 v134, s33, v167
	v_add_u32_e32 v171, s63, v167
	ds_read_b128 v[122:125], v134
	ds_read_b128 v[126:129], v134 offset:1024
	ds_read_b128 v[130:133], v134 offset:2048
	ds_read_b128 v[134:137], v134 offset:3072
	ds_read_b128 v[162:165], v171
	ds_read_b128 v[172:175], v171 offset:1024
	ds_read_b128 v[176:179], v171 offset:2048
	ds_read_b128 v[180:183], v171 offset:3072
	s_add_u32 s38, s38, 0x40000
	s_addc_u32 s39, s39, 0
	s_mov_b32 m0, s44
	v_lshl_add_u64 v[224:225], s[38:39], 0, v[152:153]
	ds_read_b128 v[184:187], v170 offset:32768
	ds_read_b128 v[188:191], v170 offset:33792
	ds_read_b128 v[192:195], v170 offset:34816
	ds_read_b128 v[196:199], v170 offset:35840
	ds_read_b128 v[200:203], v170 offset:36864
	ds_read_b128 v[204:207], v170 offset:37888
	ds_read_b128 v[208:211], v170 offset:38912
	ds_read_b128 v[212:215], v170 offset:39936
	global_load_lds_dwordx4 v[224:225], off
	v_lshl_add_u64 v[224:225], s[38:39], 0, v[148:149]
	s_mov_b32 m0, s45
	s_nop 0
	global_load_lds_dwordx4 v[224:225], off
	s_waitcnt vmcnt(8)
	s_waitcnt lgkmcnt(0)
	s_barrier
	s_setprio 0
	v_mfma_f32_16x16x32_bf16 v[142:145], v[122:125], v[184:187], v[142:145]
	v_mfma_f32_16x16x32_bf16 v[138:141], v[130:133], v[184:187], v[138:141]
	v_mfma_f32_16x16x32_bf16 v[118:121], v[122:125], v[192:195], v[118:121]
	v_mfma_f32_16x16x32_bf16 v[106:109], v[130:133], v[192:195], v[106:109]
	v_mfma_f32_16x16x32_bf16 v[102:105], v[122:125], v[200:203], v[102:105]
	v_mfma_f32_16x16x32_bf16 v[90:93], v[130:133], v[200:203], v[90:93]
	v_mfma_f32_16x16x32_bf16 v[86:89], v[122:125], v[208:211], v[86:89]
	v_mfma_f32_16x16x32_bf16 v[74:77], v[130:133], v[208:211], v[74:77]
	v_mfma_f32_16x16x32_bf16 v[142:145], v[126:129], v[188:191], v[142:145]
	v_mfma_f32_16x16x32_bf16 v[138:141], v[134:137], v[188:191], v[138:141]
	v_mfma_f32_16x16x32_bf16 v[118:121], v[126:129], v[196:199], v[118:121]
	v_mfma_f32_16x16x32_bf16 v[106:109], v[134:137], v[196:199], v[106:109]
	v_mfma_f32_16x16x32_bf16 v[102:105], v[126:129], v[204:207], v[102:105]
	v_mfma_f32_16x16x32_bf16 v[90:93], v[134:137], v[204:207], v[90:93]
	v_mfma_f32_16x16x32_bf16 v[86:89], v[126:129], v[212:215], v[86:89]
	v_mfma_f32_16x16x32_bf16 v[74:77], v[134:137], v[212:215], v[74:77]
	s_setprio 2
	s_setprio 0
	v_mfma_f32_16x16x32_bf16 v[114:117], v[162:165], v[184:187], v[114:117]
	v_mfma_f32_16x16x32_bf16 v[110:113], v[176:179], v[184:187], v[110:113]
	v_mfma_f32_16x16x32_bf16 v[98:101], v[162:165], v[192:195], v[98:101]
	v_mfma_f32_16x16x32_bf16 v[94:97], v[176:179], v[192:195], v[94:97]
	v_mfma_f32_16x16x32_bf16 v[82:85], v[162:165], v[200:203], v[82:85]
	v_mfma_f32_16x16x32_bf16 v[78:81], v[176:179], v[200:203], v[78:81]
	v_mfma_f32_16x16x32_bf16 v[70:73], v[162:165], v[208:211], v[70:73]
	v_mfma_f32_16x16x32_bf16 v[66:69], v[176:179], v[208:211], v[66:69]
	v_mfma_f32_16x16x32_bf16 v[114:117], v[172:175], v[188:191], v[114:117]
	v_mfma_f32_16x16x32_bf16 v[110:113], v[180:183], v[188:191], v[110:113]
	v_mfma_f32_16x16x32_bf16 v[98:101], v[172:175], v[196:199], v[98:101]
	v_mfma_f32_16x16x32_bf16 v[94:97], v[180:183], v[196:199], v[94:97]
	v_mfma_f32_16x16x32_bf16 v[82:85], v[172:175], v[204:207], v[82:85]
	v_mfma_f32_16x16x32_bf16 v[78:81], v[180:183], v[204:207], v[78:81]
	v_mfma_f32_16x16x32_bf16 v[70:73], v[172:175], v[212:215], v[70:73]
	v_mfma_f32_16x16x32_bf16 v[66:69], v[180:183], v[212:215], v[66:69]
	s_setprio 2
	s_barrier
; #define PG8_STAGE(bufoff, gbase, voff) do { _Pragma("unroll") for (int _i = 0; _i < 2; ++_i) \
;         __builtin_amdgcn_global_load_lds((const unsigned*)((const char*)(gbase) + (voff)[_i]), (LAS unsigned*)(lds + (bufoff) + ldsw + _i * 8192), 16, 0, 0); } while (0)
; #define PG8_LDA(dst, b, h) do { _Pragma("unroll") for (int m = 0; m < 4; ++m) _Pragma("unroll") for (int k = 0; k < 2; ++k) dst[m][k] = *(const LAS bf16x8*)(lds + PG8_SA(b, h) + aoff + m * 2048 + k * 1024); } while (0)
; #define PG8_MMA(ai, bj, At, Bt) do { __builtin_amdgcn_s_setprio(1); _Pragma("unroll") for (int m = 0; m < 4; ++m) _Pragma("unroll") for (int n = 0; n < 2; ++n) _Pragma("unroll") for (int k = 0; k < 2; ++k) \
;         acc[ai][bj][m][n] = __builtin_amdgcn_mfma_f32_16x16x32_bf16(Bt[n][k], At[m][k], acc[ai][bj][m][n], 0, 0, 0); __builtin_amdgcn_s_setprio(0); } while (0)
; #define PG8_WAIT_V(n) asm volatile("s_waitcnt vmcnt(" #n ")" ::: "memory")
; #define PG8_WAIT_L(n) asm volatile("s_waitcnt lgkmcnt(" #n ")" ::: "memory")
; #define PG8_BAR __builtin_amdgcn_s_barrier()
; #define PG8_SCHED __builtin_amdgcn_sched_barrier(0)
; template <class Epi>
; __device__ __forceinline__ void gemm_phase(LAS unsigned char* lds, const Gemm g, int G, int c, const Epi& E) {
;     ...
;             PG8_LDA(At, 1, 1); PG8_STAGE(PG8_SB(1, 0), b3, voffB); PG8_STAGE(PG8_SB(1, 1), b3 + hstepB, voffB); PG8_STAGE(PG8_SA(1, 0), a3, voffA);
;             PG8_WAIT_V(8); PG8_WAIT_L(0); PG8_BAR; PG8_MMA(1, 0, At, B0); PG8_MMA(1, 1, At, B1); PG8_BAR; PG8_SCHED;
;         }
;         if (wr == 0) PG8_BAR;
	s_add_i32 s33, s33, s42
	v_lshl_add_u64 v[216:217], v[216:217], 0, s[10:11]
	s_mov_b32 m0, s33
	ds_read_b128 v[184:187], v170 offset:49152
	ds_read_b128 v[188:191], v170 offset:50176
	ds_read_b128 v[192:195], v170 offset:51200
	ds_read_b128 v[196:199], v170 offset:52224
	ds_read_b128 v[200:203], v170 offset:53248
	ds_read_b128 v[204:207], v170 offset:54272
	ds_read_b128 v[208:211], v170 offset:55296
	ds_read_b128 v[212:215], v170 offset:56320
	global_load_lds_dwordx4 v[216:217], off
	s_add_i32 m0, s33, 0x2000
	s_add_u32 s36, s36, 0x40080
	v_lshl_add_u64 v[216:217], v[218:219], 0, s[10:11]
	s_addc_u32 s37, s37, 0
	s_add_i32 s33, s63, s42
	global_load_lds_dwordx4 v[216:217], off
	v_lshl_add_u64 v[216:217], s[36:37], 0, v[150:151]
	s_mov_b32 m0, s33
	s_nop 0
	global_load_lds_dwordx4 v[216:217], off
	v_lshl_add_u64 v[216:217], s[36:37], 0, v[146:147]
	s_add_i32 m0, s33, 0x2000
	s_nop 0
	global_load_lds_dwordx4 v[216:217], off
	v_lshl_add_u64 v[216:217], v[220:221], 0, s[10:11]
	s_mov_b32 m0, s53
	s_nop 0
	global_load_lds_dwordx4 v[216:217], off
	v_lshl_add_u64 v[216:217], v[222:223], 0, s[10:11]
	s_mov_b32 m0, s54
	s_nop 0
	global_load_lds_dwordx4 v[216:217], off
	s_waitcnt vmcnt(8)
	s_waitcnt lgkmcnt(0)
	s_barrier
	s_setprio 0
	v_mfma_f32_16x16x32_bf16 v[62:65], v[122:125], v[184:187], v[62:65]
	v_mfma_f32_16x16x32_bf16 v[58:61], v[130:133], v[184:187], v[58:61]
	v_mfma_f32_16x16x32_bf16 v[54:57], v[122:125], v[192:195], v[54:57]
	v_mfma_f32_16x16x32_bf16 v[42:45], v[130:133], v[192:195], v[42:45]
	v_mfma_f32_16x16x32_bf16 v[38:41], v[122:125], v[200:203], v[38:41]
	v_mfma_f32_16x16x32_bf16 v[26:29], v[130:133], v[200:203], v[26:29]
	v_mfma_f32_16x16x32_bf16 v[22:25], v[122:125], v[208:211], v[22:25]
	v_mfma_f32_16x16x32_bf16 v[10:13], v[130:133], v[208:211], v[10:13]
	v_mfma_f32_16x16x32_bf16 v[62:65], v[126:129], v[188:191], v[62:65]
	v_mfma_f32_16x16x32_bf16 v[58:61], v[134:137], v[188:191], v[58:61]
	v_mfma_f32_16x16x32_bf16 v[54:57], v[126:129], v[196:199], v[54:57]
	v_mfma_f32_16x16x32_bf16 v[42:45], v[134:137], v[196:199], v[42:45]
	v_mfma_f32_16x16x32_bf16 v[38:41], v[126:129], v[204:207], v[38:41]
	v_mfma_f32_16x16x32_bf16 v[26:29], v[134:137], v[204:207], v[26:29]
	v_mfma_f32_16x16x32_bf16 v[22:25], v[126:129], v[212:215], v[22:25]
	v_mfma_f32_16x16x32_bf16 v[10:13], v[134:137], v[212:215], v[10:13]
	s_setprio 2
	s_setprio 0
	v_mfma_f32_16x16x32_bf16 v[50:53], v[162:165], v[184:187], v[50:53]
	v_mfma_f32_16x16x32_bf16 v[46:49], v[176:179], v[184:187], v[46:49]
	v_mfma_f32_16x16x32_bf16 v[34:37], v[162:165], v[192:195], v[34:37]
	v_mfma_f32_16x16x32_bf16 v[30:33], v[176:179], v[192:195], v[30:33]
	v_mfma_f32_16x16x32_bf16 v[18:21], v[162:165], v[200:203], v[18:21]
	v_mfma_f32_16x16x32_bf16 v[14:17], v[176:179], v[200:203], v[14:17]
	v_mfma_f32_16x16x32_bf16 v[6:9], v[162:165], v[208:211], v[6:9]
	v_mfma_f32_16x16x32_bf16 v[2:5], v[176:179], v[208:211], v[2:5]
	v_mfma_f32_16x16x32_bf16 v[50:53], v[172:175], v[188:191], v[50:53]
	v_mfma_f32_16x16x32_bf16 v[46:49], v[180:183], v[188:191], v[46:49]
	v_mfma_f32_16x16x32_bf16 v[34:37], v[172:175], v[196:199], v[34:37]
	v_mfma_f32_16x16x32_bf16 v[30:33], v[180:183], v[196:199], v[30:33]
	v_mfma_f32_16x16x32_bf16 v[18:21], v[172:175], v[204:207], v[18:21]
	v_mfma_f32_16x16x32_bf16 v[14:17], v[180:183], v[204:207], v[14:17]
	v_mfma_f32_16x16x32_bf16 v[6:9], v[172:175], v[212:215], v[6:9]
	v_mfma_f32_16x16x32_bf16 v[2:5], v[180:183], v[212:215], v[2:5]
	s_setprio 2
	s_barrier
	s_add_i32 s62, s62, 2
	s_add_u32 s4, s4, 0x100
	s_addc_u32 s5, s5, 0
	s_add_u32 s60, s60, 0x100
	s_addc_u32 s61, s61, 0
	s_cmp_gt_u32 s62, 13
	s_cbranch_scc0 .LBB0_1931
	s_and_b64 vcc, exec, s[12:13]
	s_cbranch_vccz .LBB0_1934
	s_barrier

; #define PG8_STAGE(bufoff, gbase, voff) do { _Pragma("unroll") for (int _i = 0; _i < 2; ++_i) \
;         __builtin_amdgcn_global_load_lds((const unsigned*)((const char*)(gbase) + (voff)[_i]), (LAS unsigned*)(lds + (bufoff) + ldsw + _i * 8192), 16, 0, 0); } while (0)
; #define PG8_LDA(dst, b, h) do { _Pragma("unroll") for (int m = 0; m < 4; ++m) _Pragma("unroll") for (int k = 0; k < 2; ++k) dst[m][k] = *(const LAS bf16x8*)(lds + PG8_SA(b, h) + aoff + m * 2048 + k * 1024); } while (0)
; #define PG8_LDB(dst, b, h) do { _Pragma("unroll") for (int n = 0; n < 2; ++n) _Pragma("unroll") for (int k = 0; k < 2; ++k) dst[n][k] = *(const LAS bf16x8*)(lds + PG8_SB(b, h) + boff + n * 2048 + k * 1024); } while (0)
; #define PG8_MMA(ai, bj, At, Bt) do { __builtin_amdgcn_s_setprio(1); _Pragma("unroll") for (int m = 0; m < 4; ++m) _Pragma("unroll") for (int n = 0; n < 2; ++n) _Pragma("unroll") for (int k = 0; k < 2; ++k) \
;         acc[ai][bj][m][n] = __builtin_amdgcn_mfma_f32_16x16x32_bf16(Bt[n][k], At[m][k], acc[ai][bj][m][n], 0, 0, 0); __builtin_amdgcn_s_setprio(0); } while (0)
; #define PG8_WAIT_V(n) asm volatile("s_waitcnt vmcnt(" #n ")" ::: "memory")
; template <class Epi>
; __device__ __forceinline__ void gemm_phase(LAS unsigned char* lds, const Gemm g, int G, int c, const Epi& E) {
;     ...
;         const bool has_next = S.next(ui + 1, nxt);
;         const char* nA = has_next ? (const char*)(g.A + (size_t)nxt.pb * g.sA) + (size_t)nxt.pm * 2 * hstepA : cA;
;         const char* nB = has_next ? (const char*)(g.Bt + (size_t)nxt.pb * g.sB) + (size_t)nxt.pn * 2 * hstepB : cB;
; #pragma nounroll
;         for (int t = 0; t < nt; t += 2) {
;             const bool last = (t == nt - 2);
;             const char* a1 = cA + (size_t)(t + 1) * kstep;
;             const char* a2 = last ? nA : cA + (size_t)(t + 2) * kstep; const char* b2 = last ? nB : cB + (size_t)(t + 2) * kstep;
;             const char* a3 = a2 + kstep; const char* b3 = b2 + kstep;
;             PG8_LDB(B0, 0, 0); PG8_LDB(B1, 0, 1); PG8_SCHED; PG8_LDA(At, 0, 0); PG8_STAGE(PG8_SA(1, 1), a1 + hstepA, voffA);
;             PG8_WAIT_V(8); PG8_WAIT_L(0); PG8_BAR; PG8_MMA(0, 0, At, B0); PG8_MMA(0, 1, At, B1); PG8_BAR; PG8_SCHED;
;             PG8_LDA(At, 0, 1); PG8_STAGE(PG8_SB(0, 0), b2, voffB); PG8_STAGE(PG8_SB(0, 1), b2 + hstepB, voffB); PG8_STAGE(PG8_SA(0, 0), a2, voffA);
.LBB0_2083:
	s_ashr_i32 s17, s16, 31
	s_lshl_b64 s[22:23], s[16:17], 19
	s_add_u32 s22, s43, s22
	s_addc_u32 s23, s44, s23
	s_and_b64 s[4:5], s[4:5], exec
	s_cselect_b32 s17, s23, s39
	s_cselect_b32 s19, s22, s38
	s_add_u32 s4, s40, 0x40080
	s_addc_u32 s5, s41, 0
	s_add_u32 s66, s38, 0x100
	s_addc_u32 s67, s39, 0
	s_mov_b32 s68, -2
	ds_read_b128 v[152:155], v148
	ds_read_b128 v[156:159], v148 offset:1024
	ds_read_b128 v[160:163], v148 offset:2048
	ds_read_b128 v[164:167], v148 offset:3072
	ds_read_b128 v[168:171], v149
	ds_read_b128 v[172:175], v149 offset:1024
	ds_read_b128 v[176:179], v149 offset:2048
	ds_read_b128 v[180:183], v149 offset:3072
	s_add_u32 s33, s4, 0xfffc0080
	s_addc_u32 s38, s5, -1
	s_cmp_eq_u32 s68, 12
	s_cselect_b32 s41, s21, s38
	s_cselect_b32 s40, s20, s33
	s_cselect_b32 s39, s17, s67
	s_cselect_b32 s38, s19, s66
	v_lshl_add_u64 v[216:217], s[4:5], 0, v[138:139]
	s_add_i32 m0, s25, 0xc000
	ds_read_b128 v[184:187], v150
	ds_read_b128 v[188:191], v150 offset:1024
	ds_read_b128 v[192:195], v150 offset:2048
	ds_read_b128 v[196:199], v150 offset:3072
	ds_read_b128 v[200:203], v150 offset:4096
	ds_read_b128 v[204:207], v150 offset:5120
	ds_read_b128 v[208:211], v150 offset:6144
	ds_read_b128 v[212:215], v150 offset:7168
	global_load_lds_dwordx4 v[216:217], off
	v_lshl_add_u64 v[216:217], s[4:5], 0, v[140:141]
	s_add_i32 m0, s25, 0xe000
	s_nop 0
	global_load_lds_dwordx4 v[216:217], off
	s_waitcnt vmcnt(8)
	s_waitcnt lgkmcnt(0)
	s_barrier
	s_setprio 0
	v_mfma_f32_16x16x32_bf16 v[126:129], v[152:155], v[184:187], 0
	v_mfma_f32_16x16x32_bf16 v[122:125], v[160:163], v[184:187], 0
	v_mfma_f32_16x16x32_bf16 v[110:113], v[152:155], v[192:195], 0
	v_mfma_f32_16x16x32_bf16 v[106:109], v[160:163], v[192:195], 0
	v_mfma_f32_16x16x32_bf16 v[94:97], v[152:155], v[200:203], 0
	v_mfma_f32_16x16x32_bf16 v[90:93], v[160:163], v[200:203], 0
	v_mfma_f32_16x16x32_bf16 v[78:81], v[152:155], v[208:211], 0
	v_mfma_f32_16x16x32_bf16 v[74:77], v[160:163], v[208:211], 0
	v_mfma_f32_16x16x32_bf16 v[126:129], v[156:159], v[188:191], v[126:129]
	v_mfma_f32_16x16x32_bf16 v[122:125], v[164:167], v[188:191], v[122:125]
	v_mfma_f32_16x16x32_bf16 v[110:113], v[156:159], v[196:199], v[110:113]
	v_mfma_f32_16x16x32_bf16 v[106:109], v[164:167], v[196:199], v[106:109]
	v_mfma_f32_16x16x32_bf16 v[94:97], v[156:159], v[204:207], v[94:97]
	v_mfma_f32_16x16x32_bf16 v[90:93], v[164:167], v[204:207], v[90:93]
	v_mfma_f32_16x16x32_bf16 v[78:81], v[156:159], v[212:215], v[78:81]
	v_mfma_f32_16x16x32_bf16 v[74:77], v[164:167], v[212:215], v[74:77]
	s_setprio 2
	s_setprio 0
	v_mfma_f32_16x16x32_bf16 v[118:121], v[168:171], v[184:187], 0
	v_mfma_f32_16x16x32_bf16 v[114:117], v[176:179], v[184:187], 0
	v_mfma_f32_16x16x32_bf16 v[102:105], v[168:171], v[192:195], 0
	v_mfma_f32_16x16x32_bf16 v[98:101], v[176:179], v[192:195], 0
	v_mfma_f32_16x16x32_bf16 v[86:89], v[168:171], v[200:203], 0
	v_mfma_f32_16x16x32_bf16 v[82:85], v[176:179], v[200:203], 0
	v_mfma_f32_16x16x32_bf16 v[70:73], v[168:171], v[208:211], 0
	v_mfma_f32_16x16x32_bf16 v[66:69], v[176:179], v[208:211], 0
	v_mfma_f32_16x16x32_bf16 v[118:121], v[172:175], v[188:191], v[118:121]
	v_mfma_f32_16x16x32_bf16 v[114:117], v[180:183], v[188:191], v[114:117]
	v_mfma_f32_16x16x32_bf16 v[102:105], v[172:175], v[196:199], v[102:105]
	v_mfma_f32_16x16x32_bf16 v[98:101], v[180:183], v[196:199], v[98:101]
	v_mfma_f32_16x16x32_bf16 v[86:89], v[172:175], v[204:207], v[86:89]
	v_mfma_f32_16x16x32_bf16 v[82:85], v[180:183], v[204:207], v[82:85]
	v_mfma_f32_16x16x32_bf16 v[70:73], v[172:175], v[212:215], v[70:73]
	v_mfma_f32_16x16x32_bf16 v[66:69], v[180:183], v[212:215], v[66:69]
	s_setprio 2
	s_barrier
	s_add_i32 s33, s56, s46
	v_lshl_add_u64 v[216:217], s[38:39], 0, v[134:135]
	s_mov_b32 m0, s33
	ds_read_b128 v[184:187], v150 offset:16384
	ds_read_b128 v[188:191], v150 offset:17408
	ds_read_b128 v[192:195], v150 offset:18432
	ds_read_b128 v[196:199], v150 offset:19456
	ds_read_b128 v[200:203], v150 offset:20480
	ds_read_b128 v[204:207], v150 offset:21504
	ds_read_b128 v[208:211], v150 offset:22528
	ds_read_b128 v[212:215], v150 offset:23552
	global_load_lds_dwordx4 v[216:217], off
	s_add_i32 m0, s33, 0x2000
	s_add_u32 s70, s38, 0x40000
	v_lshl_add_u64 v[218:219], s[38:39], 0, v[130:131]
	s_addc_u32 s71, s39, 0
	s_add_i32 s33, s57, s46
	global_load_lds_dwordx4 v[218:219], off
	v_lshl_add_u64 v[220:221], s[70:71], 0, v[134:135]
	s_mov_b32 m0, s33
	v_lshl_add_u64 v[222:223], s[40:41], 0, v[132:133]
	global_load_lds_dwordx4 v[220:221], off
	v_lshl_add_u64 v[220:221], s[70:71], 0, v[130:131]
	s_add_i32 m0, s33, 0x2000
	s_nop 0
	global_load_lds_dwordx4 v[220:221], off
	v_lshl_add_u64 v[220:221], s[40:41], 0, v[136:137]
	s_mov_b32 m0, s25
	s_nop 0
	global_load_lds_dwordx4 v[220:221], off
	s_mov_b32 m0, s37
	s_nop 0
	global_load_lds_dwordx4 v[222:223], off
	s_waitcnt vmcnt(8)
	s_waitcnt lgkmcnt(0)
	s_barrier
; #define PG8_STAGE(bufoff, gbase, voff) do { _Pragma("unroll") for (int _i = 0; _i < 2; ++_i) \
;         __builtin_amdgcn_global_load_lds((const unsigned*)((const char*)(gbase) + (voff)[_i]), (LAS unsigned*)(lds + (bufoff) + ldsw + _i * 8192), 16, 0, 0); } while (0)
; #define PG8_LDA(dst, b, h) do { _Pragma("unroll") for (int m = 0; m < 4; ++m) _Pragma("unroll") for (int k = 0; k < 2; ++k) dst[m][k] = *(const LAS bf16x8*)(lds + PG8_SA(b, h) + aoff + m * 2048 + k * 1024); } while (0)
; #define PG8_LDB(dst, b, h) do { _Pragma("unroll") for (int n = 0; n < 2; ++n) _Pragma("unroll") for (int k = 0; k < 2; ++k) dst[n][k] = *(const LAS bf16x8*)(lds + PG8_SB(b, h) + boff + n * 2048 + k * 1024); } while (0)
; #define PG8_MMA(ai, bj, At, Bt) do { __builtin_amdgcn_s_setprio(1); _Pragma("unroll") for (int m = 0; m < 4; ++m) _Pragma("unroll") for (int n = 0; n < 2; ++n) _Pragma("unroll") for (int k = 0; k < 2; ++k) \
;         acc[ai][bj][m][n] = __builtin_amdgcn_mfma_f32_16x16x32_bf16(Bt[n][k], At[m][k], acc[ai][bj][m][n], 0, 0, 0); __builtin_amdgcn_s_setprio(0); } while (0)
; #define PG8_WAIT_V(n) asm volatile("s_waitcnt vmcnt(" #n ")" ::: "memory")
; #define PG8_WAIT_L(n) asm volatile("s_waitcnt lgkmcnt(" #n ")" ::: "memory")
; #define PG8_BAR __builtin_amdgcn_s_barrier()
; #define PG8_SCHED __builtin_amdgcn_sched_barrier(0)
; template <class Epi>
; __device__ __forceinline__ void gemm_phase(LAS unsigned char* lds, const Gemm g, int G, int c, const Epi& E) {
;     ...
;             PG8_WAIT_V(8); PG8_WAIT_L(0); PG8_BAR; PG8_MMA(1, 0, At, B0); PG8_MMA(1, 1, At, B1); PG8_BAR; PG8_SCHED;
;             PG8_LDB(B0, 1, 0); PG8_LDB(B1, 1, 1); PG8_SCHED; PG8_LDA(At, 1, 0); PG8_STAGE(PG8_SA(0, 1), a2 + hstepA, voffA);
;             PG8_WAIT_V(8); PG8_WAIT_L(0); PG8_BAR; PG8_MMA(0, 0, At, B0); PG8_MMA(0, 1, At, B1); PG8_BAR; PG8_SCHED;
	s_setprio 0
	v_mfma_f32_16x16x32_bf16 v[62:65], v[152:155], v[184:187], 0
	v_mfma_f32_16x16x32_bf16 v[58:61], v[160:163], v[184:187], 0
	v_mfma_f32_16x16x32_bf16 v[46:49], v[152:155], v[192:195], 0
	v_mfma_f32_16x16x32_bf16 v[42:45], v[160:163], v[192:195], 0
	v_mfma_f32_16x16x32_bf16 v[30:33], v[152:155], v[200:203], 0
	v_mfma_f32_16x16x32_bf16 v[26:29], v[160:163], v[200:203], 0
	v_mfma_f32_16x16x32_bf16 v[14:17], v[152:155], v[208:211], 0
	v_mfma_f32_16x16x32_bf16 v[10:13], v[160:163], v[208:211], 0
	v_mfma_f32_16x16x32_bf16 v[62:65], v[156:159], v[188:191], v[62:65]
	v_mfma_f32_16x16x32_bf16 v[58:61], v[164:167], v[188:191], v[58:61]
	v_mfma_f32_16x16x32_bf16 v[46:49], v[156:159], v[196:199], v[46:49]
	v_mfma_f32_16x16x32_bf16 v[42:45], v[164:167], v[196:199], v[42:45]
	v_mfma_f32_16x16x32_bf16 v[30:33], v[156:159], v[204:207], v[30:33]
	v_mfma_f32_16x16x32_bf16 v[26:29], v[164:167], v[204:207], v[26:29]
	v_mfma_f32_16x16x32_bf16 v[14:17], v[156:159], v[212:215], v[14:17]
	v_mfma_f32_16x16x32_bf16 v[10:13], v[164:167], v[212:215], v[10:13]
	s_setprio 2
	s_setprio 0
	v_mfma_f32_16x16x32_bf16 v[54:57], v[168:171], v[184:187], 0
	v_mfma_f32_16x16x32_bf16 v[50:53], v[176:179], v[184:187], 0
	v_mfma_f32_16x16x32_bf16 v[38:41], v[168:171], v[192:195], 0
	v_mfma_f32_16x16x32_bf16 v[34:37], v[176:179], v[192:195], 0
	v_mfma_f32_16x16x32_bf16 v[22:25], v[168:171], v[200:203], 0
	v_mfma_f32_16x16x32_bf16 v[18:21], v[176:179], v[200:203], 0
	v_mfma_f32_16x16x32_bf16 v[6:9], v[168:171], v[208:211], 0
	v_mfma_f32_16x16x32_bf16 v[2:5], v[176:179], v[208:211], 0
	v_mfma_f32_16x16x32_bf16 v[54:57], v[172:175], v[188:191], v[54:57]
	v_mfma_f32_16x16x32_bf16 v[50:53], v[180:183], v[188:191], v[50:53]
	v_mfma_f32_16x16x32_bf16 v[38:41], v[172:175], v[196:199], v[38:41]
	v_mfma_f32_16x16x32_bf16 v[34:37], v[180:183], v[196:199], v[34:37]
	v_mfma_f32_16x16x32_bf16 v[22:25], v[172:175], v[204:207], v[22:25]
	v_mfma_f32_16x16x32_bf16 v[18:21], v[180:183], v[204:207], v[18:21]
	v_mfma_f32_16x16x32_bf16 v[6:9], v[172:175], v[212:215], v[6:9]
	v_mfma_f32_16x16x32_bf16 v[2:5], v[180:183], v[212:215], v[2:5]
	s_setprio 2
	s_barrier
	s_add_i32 s33, 0, 0x18000
	s_add_i32 s69, 0, 0x1c000
	v_add_u32_e32 v164, s33, v147
	v_add_u32_e32 v180, s69, v147
	ds_read_b128 v[152:155], v164
	ds_read_b128 v[156:159], v164 offset:1024
	ds_read_b128 v[160:163], v164 offset:2048
	ds_read_b128 v[164:167], v164 offset:3072
	ds_read_b128 v[168:171], v180
	ds_read_b128 v[172:175], v180 offset:1024
	ds_read_b128 v[176:179], v180 offset:2048
	ds_read_b128 v[180:183], v180 offset:3072
	s_add_u32 s40, s40, 0x40000
	s_addc_u32 s41, s41, 0
	s_mov_b32 m0, s47
	v_lshl_add_u64 v[224:225], s[40:41], 0, v[136:137]
	ds_read_b128 v[184:187], v150 offset:32768
	ds_read_b128 v[188:191], v150 offset:33792
	ds_read_b128 v[192:195], v150 offset:34816
	ds_read_b128 v[196:199], v150 offset:35840
	ds_read_b128 v[200:203], v150 offset:36864
	ds_read_b128 v[204:207], v150 offset:37888
	ds_read_b128 v[208:211], v150 offset:38912
	ds_read_b128 v[212:215], v150 offset:39936
	global_load_lds_dwordx4 v[224:225], off
	v_lshl_add_u64 v[224:225], s[40:41], 0, v[132:133]
	s_mov_b32 m0, s48
	s_nop 0
	global_load_lds_dwordx4 v[224:225], off
	s_waitcnt vmcnt(8)
	s_waitcnt lgkmcnt(0)
	s_barrier
	s_setprio 0
	v_mfma_f32_16x16x32_bf16 v[126:129], v[152:155], v[184:187], v[126:129]
	v_mfma_f32_16x16x32_bf16 v[122:125], v[160:163], v[184:187], v[122:125]
	v_mfma_f32_16x16x32_bf16 v[110:113], v[152:155], v[192:195], v[110:113]
	v_mfma_f32_16x16x32_bf16 v[106:109], v[160:163], v[192:195], v[106:109]
	v_mfma_f32_16x16x32_bf16 v[94:97], v[152:155], v[200:203], v[94:97]
	v_mfma_f32_16x16x32_bf16 v[90:93], v[160:163], v[200:203], v[90:93]
	v_mfma_f32_16x16x32_bf16 v[78:81], v[152:155], v[208:211], v[78:81]
	v_mfma_f32_16x16x32_bf16 v[74:77], v[160:163], v[208:211], v[74:77]
	v_mfma_f32_16x16x32_bf16 v[126:129], v[156:159], v[188:191], v[126:129]
	v_mfma_f32_16x16x32_bf16 v[122:125], v[164:167], v[188:191], v[122:125]
	v_mfma_f32_16x16x32_bf16 v[110:113], v[156:159], v[196:199], v[110:113]
	v_mfma_f32_16x16x32_bf16 v[106:109], v[164:167], v[196:199], v[106:109]
	v_mfma_f32_16x16x32_bf16 v[94:97], v[156:159], v[204:207], v[94:97]
	v_mfma_f32_16x16x32_bf16 v[90:93], v[164:167], v[204:207], v[90:93]
	v_mfma_f32_16x16x32_bf16 v[78:81], v[156:159], v[212:215], v[78:81]
	v_mfma_f32_16x16x32_bf16 v[74:77], v[164:167], v[212:215], v[74:77]
	s_setprio 2
	s_setprio 0
	v_mfma_f32_16x16x32_bf16 v[118:121], v[168:171], v[184:187], v[118:121]
	v_mfma_f32_16x16x32_bf16 v[114:117], v[176:179], v[184:187], v[114:117]
	v_mfma_f32_16x16x32_bf16 v[102:105], v[168:171], v[192:195], v[102:105]
	v_mfma_f32_16x16x32_bf16 v[98:101], v[176:179], v[192:195], v[98:101]
	v_mfma_f32_16x16x32_bf16 v[86:89], v[168:171], v[200:203], v[86:89]
	v_mfma_f32_16x16x32_bf16 v[82:85], v[176:179], v[200:203], v[82:85]
	v_mfma_f32_16x16x32_bf16 v[70:73], v[168:171], v[208:211], v[70:73]
	v_mfma_f32_16x16x32_bf16 v[66:69], v[176:179], v[208:211], v[66:69]
	v_mfma_f32_16x16x32_bf16 v[118:121], v[172:175], v[188:191], v[118:121]
	v_mfma_f32_16x16x32_bf16 v[114:117], v[180:183], v[188:191], v[114:117]
	v_mfma_f32_16x16x32_bf16 v[102:105], v[172:175], v[196:199], v[102:105]
	v_mfma_f32_16x16x32_bf16 v[98:101], v[180:183], v[196:199], v[98:101]
	v_mfma_f32_16x16x32_bf16 v[86:89], v[172:175], v[204:207], v[86:89]
	v_mfma_f32_16x16x32_bf16 v[82:85], v[180:183], v[204:207], v[82:85]
	v_mfma_f32_16x16x32_bf16 v[70:73], v[172:175], v[212:215], v[70:73]
	v_mfma_f32_16x16x32_bf16 v[66:69], v[180:183], v[212:215], v[66:69]
	s_setprio 2
	s_barrier
; #define PG8_STAGE(bufoff, gbase, voff) do { _Pragma("unroll") for (int _i = 0; _i < 2; ++_i) \
;         __builtin_amdgcn_global_load_lds((const unsigned*)((const char*)(gbase) + (voff)[_i]), (LAS unsigned*)(lds + (bufoff) + ldsw + _i * 8192), 16, 0, 0); } while (0)
; #define PG8_LDA(dst, b, h) do { _Pragma("unroll") for (int m = 0; m < 4; ++m) _Pragma("unroll") for (int k = 0; k < 2; ++k) dst[m][k] = *(const LAS bf16x8*)(lds + PG8_SA(b, h) + aoff + m * 2048 + k * 1024); } while (0)
; #define PG8_LDB(dst, b, h) do { _Pragma("unroll") for (int n = 0; n < 2; ++n) _Pragma("unroll") for (int k = 0; k < 2; ++k) dst[n][k] = *(const LAS bf16x8*)(lds + PG8_SB(b, h) + boff + n * 2048 + k * 1024); } while (0)
; #define PG8_MMA(ai, bj, At, Bt) do { __builtin_amdgcn_s_setprio(1); _Pragma("unroll") for (int m = 0; m < 4; ++m) _Pragma("unroll") for (int n = 0; n < 2; ++n) _Pragma("unroll") for (int k = 0; k < 2; ++k) \
;         acc[ai][bj][m][n] = __builtin_amdgcn_mfma_f32_16x16x32_bf16(Bt[n][k], At[m][k], acc[ai][bj][m][n], 0, 0, 0); __builtin_amdgcn_s_setprio(0); } while (0)
; #define PG8_WAIT_V(n) asm volatile("s_waitcnt vmcnt(" #n ")" ::: "memory")
; #define PG8_BAR __builtin_amdgcn_s_barrier()
; template <class Epi>
; __device__ __forceinline__ void gemm_phase(LAS unsigned char* lds, const Gemm g, int G, int c, const Epi& E) {
;     ...
;             PG8_LDB(B0, 0, 0); PG8_LDB(B1, 0, 1); PG8_SCHED; PG8_LDA(At, 0, 0); PG8_STAGE(PG8_SA(1, 1), a1 + hstepA, voffA);
;             PG8_WAIT_V(8); PG8_WAIT_L(0); PG8_BAR; PG8_MMA(0, 0, At, B0); PG8_MMA(0, 1, At, B1); PG8_BAR; PG8_SCHED;
;             PG8_LDA(At, 0, 1); PG8_STAGE(PG8_SB(0, 0), b2, voffB); PG8_STAGE(PG8_SB(0, 1), b2 + hstepB, voffB); PG8_STAGE(PG8_SA(0, 0), a2, voffA);
;             PG8_WAIT_V(8); PG8_WAIT_L(0); PG8_BAR; PG8_MMA(1, 0, At, B0); PG8_MMA(1, 1, At, B1); PG8_BAR; PG8_SCHED;
;             PG8_LDB(B0, 1, 0); PG8_LDB(B1, 1, 1); PG8_SCHED; PG8_LDA(At, 1, 0); PG8_STAGE(PG8_SA(0, 1), a2 + hstepA, voffA);
;             PG8_WAIT_V(8); PG8_WAIT_L(0); PG8_BAR; PG8_MMA(0, 0, At, B0); PG8_MMA(0, 1, At, B1); PG8_BAR; PG8_SCHED;
;             PG8_LDA(At, 1, 1); PG8_STAGE(PG8_SB(1, 0), b3, voffB); PG8_STAGE(PG8_SB(1, 1), b3 + hstepB, voffB); PG8_STAGE(PG8_SA(1, 0), a3, voffA);
;             PG8_WAIT_V(8); PG8_WAIT_L(0); PG8_BAR; PG8_MMA(1, 0, At, B0); PG8_MMA(1, 1, At, B1); PG8_BAR; PG8_SCHED;
	s_add_i32 s33, s33, s46
	v_lshl_add_u64 v[216:217], v[216:217], 0, s[12:13]
	s_mov_b32 m0, s33
	ds_read_b128 v[184:187], v150 offset:49152
	ds_read_b128 v[188:191], v150 offset:50176
	ds_read_b128 v[192:195], v150 offset:51200
	ds_read_b128 v[196:199], v150 offset:52224
	ds_read_b128 v[200:203], v150 offset:53248
	ds_read_b128 v[204:207], v150 offset:54272
	ds_read_b128 v[208:211], v150 offset:55296
	ds_read_b128 v[212:215], v150 offset:56320
	global_load_lds_dwordx4 v[216:217], off
	s_add_i32 m0, s33, 0x2000
	s_add_u32 s38, s38, 0x40080
	v_lshl_add_u64 v[216:217], v[218:219], 0, s[12:13]
	s_addc_u32 s39, s39, 0
	s_add_i32 s33, s69, s46
	global_load_lds_dwordx4 v[216:217], off
	v_lshl_add_u64 v[216:217], s[38:39], 0, v[134:135]
	s_mov_b32 m0, s33
	s_nop 0
	global_load_lds_dwordx4 v[216:217], off
	v_lshl_add_u64 v[216:217], s[38:39], 0, v[130:131]
	s_add_i32 m0, s33, 0x2000
	s_nop 0
	global_load_lds_dwordx4 v[216:217], off
	v_lshl_add_u64 v[216:217], v[220:221], 0, s[12:13]
	s_mov_b32 m0, s53
	s_nop 0
	global_load_lds_dwordx4 v[216:217], off
	v_lshl_add_u64 v[216:217], v[222:223], 0, s[12:13]
	s_mov_b32 m0, s54
	s_nop 0
	global_load_lds_dwordx4 v[216:217], off
	s_waitcnt vmcnt(8)
	s_waitcnt lgkmcnt(0)
	s_barrier
	s_setprio 0
	v_mfma_f32_16x16x32_bf16 v[62:65], v[152:155], v[184:187], v[62:65]
	v_mfma_f32_16x16x32_bf16 v[58:61], v[160:163], v[184:187], v[58:61]
	v_mfma_f32_16x16x32_bf16 v[46:49], v[152:155], v[192:195], v[46:49]
	v_mfma_f32_16x16x32_bf16 v[42:45], v[160:163], v[192:195], v[42:45]
	v_mfma_f32_16x16x32_bf16 v[30:33], v[152:155], v[200:203], v[30:33]
	v_mfma_f32_16x16x32_bf16 v[26:29], v[160:163], v[200:203], v[26:29]
	v_mfma_f32_16x16x32_bf16 v[14:17], v[152:155], v[208:211], v[14:17]
	v_mfma_f32_16x16x32_bf16 v[10:13], v[160:163], v[208:211], v[10:13]
	v_mfma_f32_16x16x32_bf16 v[62:65], v[156:159], v[188:191], v[62:65]
	v_mfma_f32_16x16x32_bf16 v[58:61], v[164:167], v[188:191], v[58:61]
	v_mfma_f32_16x16x32_bf16 v[46:49], v[156:159], v[196:199], v[46:49]
	v_mfma_f32_16x16x32_bf16 v[42:45], v[164:167], v[196:199], v[42:45]
	v_mfma_f32_16x16x32_bf16 v[30:33], v[156:159], v[204:207], v[30:33]
	v_mfma_f32_16x16x32_bf16 v[26:29], v[164:167], v[204:207], v[26:29]
	v_mfma_f32_16x16x32_bf16 v[14:17], v[156:159], v[212:215], v[14:17]
	v_mfma_f32_16x16x32_bf16 v[10:13], v[164:167], v[212:215], v[10:13]
	s_setprio 2
	s_setprio 0
	v_mfma_f32_16x16x32_bf16 v[54:57], v[168:171], v[184:187], v[54:57]
	v_mfma_f32_16x16x32_bf16 v[50:53], v[176:179], v[184:187], v[50:53]
	v_mfma_f32_16x16x32_bf16 v[38:41], v[168:171], v[192:195], v[38:41]
	v_mfma_f32_16x16x32_bf16 v[34:37], v[176:179], v[192:195], v[34:37]
	v_mfma_f32_16x16x32_bf16 v[22:25], v[168:171], v[200:203], v[22:25]
	v_mfma_f32_16x16x32_bf16 v[18:21], v[176:179], v[200:203], v[18:21]
	v_mfma_f32_16x16x32_bf16 v[6:9], v[168:171], v[208:211], v[6:9]
	v_mfma_f32_16x16x32_bf16 v[2:5], v[176:179], v[208:211], v[2:5]
	v_mfma_f32_16x16x32_bf16 v[54:57], v[172:175], v[188:191], v[54:57]
	v_mfma_f32_16x16x32_bf16 v[50:53], v[180:183], v[188:191], v[50:53]
	v_mfma_f32_16x16x32_bf16 v[38:41], v[172:175], v[196:199], v[38:41]
	v_mfma_f32_16x16x32_bf16 v[34:37], v[180:183], v[196:199], v[34:37]
	v_mfma_f32_16x16x32_bf16 v[22:25], v[172:175], v[204:207], v[22:25]
	v_mfma_f32_16x16x32_bf16 v[18:21], v[180:183], v[204:207], v[18:21]
	v_mfma_f32_16x16x32_bf16 v[6:9], v[172:175], v[212:215], v[6:9]
	v_mfma_f32_16x16x32_bf16 v[2:5], v[180:183], v[212:215], v[2:5]
	s_setprio 2
	s_barrier
	s_add_i32 s68, s68, 2
	s_add_u32 s4, s4, 0x100
	s_addc_u32 s5, s5, 0
	s_add_u32 s66, s66, 0x100
	s_addc_u32 s67, s67, 0
	s_cmp_gt_u32 s68, 13
	s_cbranch_scc0 .LBB0_2084
.LBB0_2084:
	ds_read_b128 v[152:155], v148
	ds_read_b128 v[156:159], v148 offset:1024
	ds_read_b128 v[160:163], v148 offset:2048
	ds_read_b128 v[164:167], v148 offset:3072
	ds_read_b128 v[168:171], v149
	ds_read_b128 v[172:175], v149 offset:1024
	ds_read_b128 v[176:179], v149 offset:2048
	ds_read_b128 v[180:183], v149 offset:3072
	s_add_u32 s33, s4, 0xfffc0080
	s_addc_u32 s38, s5, -1
	s_cmp_eq_u32 s68, 12
	s_cselect_b32 s41, s21, s38
	s_cselect_b32 s40, s20, s33
	s_cselect_b32 s39, s17, s67
	s_cselect_b32 s38, s19, s66
	v_lshl_add_u64 v[216:217], s[4:5], 0, v[138:139]
	s_add_i32 m0, s25, 0xc000
	ds_read_b128 v[184:187], v150
	ds_read_b128 v[188:191], v150 offset:1024
	ds_read_b128 v[192:195], v150 offset:2048
	ds_read_b128 v[196:199], v150 offset:3072
	ds_read_b128 v[200:203], v150 offset:4096
	ds_read_b128 v[204:207], v150 offset:5120
	ds_read_b128 v[208:211], v150 offset:6144
	ds_read_b128 v[212:215], v150 offset:7168
	global_load_lds_dwordx4 v[216:217], off
	v_lshl_add_u64 v[216:217], s[4:5], 0, v[140:141]
	s_add_i32 m0, s25, 0xe000
	s_nop 0
	global_load_lds_dwordx4 v[216:217], off
	s_waitcnt vmcnt(8)
	s_waitcnt lgkmcnt(0)
	s_barrier
; #define PG8_STAGE(bufoff, gbase, voff) do { _Pragma("unroll") for (int _i = 0; _i < 2; ++_i) \
;         __builtin_amdgcn_global_load_lds((const unsigned*)((const char*)(gbase) + (voff)[_i]), (LAS unsigned*)(lds + (bufoff) + ldsw + _i * 8192), 16, 0, 0); } while (0)
; #define PG8_LDA(dst, b, h) do { _Pragma("unroll") for (int m = 0; m < 4; ++m) _Pragma("unroll") for (int k = 0; k < 2; ++k) dst[m][k] = *(const LAS bf16x8*)(lds + PG8_SA(b, h) + aoff + m * 2048 + k * 1024); } while (0)
; #define PG8_MMA(ai, bj, At, Bt) do { __builtin_amdgcn_s_setprio(1); _Pragma("unroll") for (int m = 0; m < 4; ++m) _Pragma("unroll") for (int n = 0; n < 2; ++n) _Pragma("unroll") for (int k = 0; k < 2; ++k) \
;         acc[ai][bj][m][n] = __builtin_amdgcn_mfma_f32_16x16x32_bf16(Bt[n][k], At[m][k], acc[ai][bj][m][n], 0, 0, 0); __builtin_amdgcn_s_setprio(0); } while (0)
; #define PG8_WAIT_V(n) asm volatile("s_waitcnt vmcnt(" #n ")" ::: "memory")
; #define PG8_WAIT_L(n) asm volatile("s_waitcnt lgkmcnt(" #n ")" ::: "memory")
; #define PG8_BAR __builtin_amdgcn_s_barrier()
; #define PG8_SCHED __builtin_amdgcn_sched_barrier(0)
; template <class Epi>
; __device__ __forceinline__ void gemm_phase(LAS unsigned char* lds, const Gemm g, int G, int c, const Epi& E) {
;     ...
;             PG8_WAIT_V(8); PG8_WAIT_L(0); PG8_BAR; PG8_MMA(0, 0, At, B0); PG8_MMA(0, 1, At, B1); PG8_BAR; PG8_SCHED;
;             PG8_LDA(At, 0, 1); PG8_STAGE(PG8_SB(0, 0), b2, voffB); PG8_STAGE(PG8_SB(0, 1), b2 + hstepB, voffB); PG8_STAGE(PG8_SA(0, 0), a2, voffA);
;             PG8_WAIT_V(8); PG8_WAIT_L(0); PG8_BAR; PG8_MMA(1, 0, At, B0); PG8_MMA(1, 1, At, B1); PG8_BAR; PG8_SCHED;
	s_setprio 0
	v_mfma_f32_16x16x32_bf16 v[126:129], v[152:155], v[184:187], v[126:129]
	v_mfma_f32_16x16x32_bf16 v[122:125], v[160:163], v[184:187], v[122:125]
	v_mfma_f32_16x16x32_bf16 v[110:113], v[152:155], v[192:195], v[110:113]
	v_mfma_f32_16x16x32_bf16 v[106:109], v[160:163], v[192:195], v[106:109]
	v_mfma_f32_16x16x32_bf16 v[94:97], v[152:155], v[200:203], v[94:97]
	v_mfma_f32_16x16x32_bf16 v[90:93], v[160:163], v[200:203], v[90:93]
	v_mfma_f32_16x16x32_bf16 v[78:81], v[152:155], v[208:211], v[78:81]
	v_mfma_f32_16x16x32_bf16 v[74:77], v[160:163], v[208:211], v[74:77]
	v_mfma_f32_16x16x32_bf16 v[126:129], v[156:159], v[188:191], v[126:129]
	v_mfma_f32_16x16x32_bf16 v[122:125], v[164:167], v[188:191], v[122:125]
	v_mfma_f32_16x16x32_bf16 v[110:113], v[156:159], v[196:199], v[110:113]
	v_mfma_f32_16x16x32_bf16 v[106:109], v[164:167], v[196:199], v[106:109]
	v_mfma_f32_16x16x32_bf16 v[94:97], v[156:159], v[204:207], v[94:97]
	v_mfma_f32_16x16x32_bf16 v[90:93], v[164:167], v[204:207], v[90:93]
	v_mfma_f32_16x16x32_bf16 v[78:81], v[156:159], v[212:215], v[78:81]
	v_mfma_f32_16x16x32_bf16 v[74:77], v[164:167], v[212:215], v[74:77]
	s_setprio 2
	s_setprio 0
	v_mfma_f32_16x16x32_bf16 v[118:121], v[168:171], v[184:187], v[118:121]
	v_mfma_f32_16x16x32_bf16 v[114:117], v[176:179], v[184:187], v[114:117]
	v_mfma_f32_16x16x32_bf16 v[102:105], v[168:171], v[192:195], v[102:105]
	v_mfma_f32_16x16x32_bf16 v[98:101], v[176:179], v[192:195], v[98:101]
	v_mfma_f32_16x16x32_bf16 v[86:89], v[168:171], v[200:203], v[86:89]
	v_mfma_f32_16x16x32_bf16 v[82:85], v[176:179], v[200:203], v[82:85]
	v_mfma_f32_16x16x32_bf16 v[70:73], v[168:171], v[208:211], v[70:73]
	v_mfma_f32_16x16x32_bf16 v[66:69], v[176:179], v[208:211], v[66:69]
	v_mfma_f32_16x16x32_bf16 v[118:121], v[172:175], v[188:191], v[118:121]
	v_mfma_f32_16x16x32_bf16 v[114:117], v[180:183], v[188:191], v[114:117]
	v_mfma_f32_16x16x32_bf16 v[102:105], v[172:175], v[196:199], v[102:105]
	v_mfma_f32_16x16x32_bf16 v[98:101], v[180:183], v[196:199], v[98:101]
	v_mfma_f32_16x16x32_bf16 v[86:89], v[172:175], v[204:207], v[86:89]
	v_mfma_f32_16x16x32_bf16 v[82:85], v[180:183], v[204:207], v[82:85]
	v_mfma_f32_16x16x32_bf16 v[70:73], v[172:175], v[212:215], v[70:73]
	v_mfma_f32_16x16x32_bf16 v[66:69], v[180:183], v[212:215], v[66:69]
	s_setprio 2
	s_barrier
	s_add_i32 s33, s56, s46
	v_lshl_add_u64 v[216:217], s[38:39], 0, v[134:135]
	s_mov_b32 m0, s33
	ds_read_b128 v[184:187], v150 offset:16384
	ds_read_b128 v[188:191], v150 offset:17408
	ds_read_b128 v[192:195], v150 offset:18432
	ds_read_b128 v[196:199], v150 offset:19456
	ds_read_b128 v[200:203], v150 offset:20480
	ds_read_b128 v[204:207], v150 offset:21504
	ds_read_b128 v[208:211], v150 offset:22528
	ds_read_b128 v[212:215], v150 offset:23552
	global_load_lds_dwordx4 v[216:217], off
	s_add_i32 m0, s33, 0x2000
	s_add_u32 s70, s38, 0x40000
	v_lshl_add_u64 v[218:219], s[38:39], 0, v[130:131]
	s_addc_u32 s71, s39, 0
	s_add_i32 s33, s57, s46
	global_load_lds_dwordx4 v[218:219], off
	v_lshl_add_u64 v[220:221], s[70:71], 0, v[134:135]
	s_mov_b32 m0, s33
	v_lshl_add_u64 v[222:223], s[40:41], 0, v[132:133]
	global_load_lds_dwordx4 v[220:221], off
	v_lshl_add_u64 v[220:221], s[70:71], 0, v[130:131]
	s_add_i32 m0, s33, 0x2000
	s_nop 0
	global_load_lds_dwordx4 v[220:221], off
	v_lshl_add_u64 v[220:221], s[40:41], 0, v[136:137]
	s_mov_b32 m0, s25
	s_nop 0
	global_load_lds_dwordx4 v[220:221], off
	s_mov_b32 m0, s37
	s_nop 0
	global_load_lds_dwordx4 v[222:223], off
	s_waitcnt vmcnt(8)
	s_waitcnt lgkmcnt(0)
	s_barrier
	s_setprio 0
	v_mfma_f32_16x16x32_bf16 v[62:65], v[152:155], v[184:187], v[62:65]
	v_mfma_f32_16x16x32_bf16 v[58:61], v[160:163], v[184:187], v[58:61]
	v_mfma_f32_16x16x32_bf16 v[46:49], v[152:155], v[192:195], v[46:49]
	v_mfma_f32_16x16x32_bf16 v[42:45], v[160:163], v[192:195], v[42:45]
	v_mfma_f32_16x16x32_bf16 v[30:33], v[152:155], v[200:203], v[30:33]
	v_mfma_f32_16x16x32_bf16 v[26:29], v[160:163], v[200:203], v[26:29]
	v_mfma_f32_16x16x32_bf16 v[14:17], v[152:155], v[208:211], v[14:17]
	v_mfma_f32_16x16x32_bf16 v[10:13], v[160:163], v[208:211], v[10:13]
	v_mfma_f32_16x16x32_bf16 v[62:65], v[156:159], v[188:191], v[62:65]
	v_mfma_f32_16x16x32_bf16 v[58:61], v[164:167], v[188:191], v[58:61]
	v_mfma_f32_16x16x32_bf16 v[46:49], v[156:159], v[196:199], v[46:49]
	v_mfma_f32_16x16x32_bf16 v[42:45], v[164:167], v[196:199], v[42:45]
	v_mfma_f32_16x16x32_bf16 v[30:33], v[156:159], v[204:207], v[30:33]
	v_mfma_f32_16x16x32_bf16 v[26:29], v[164:167], v[204:207], v[26:29]
	v_mfma_f32_16x16x32_bf16 v[14:17], v[156:159], v[212:215], v[14:17]
	v_mfma_f32_16x16x32_bf16 v[10:13], v[164:167], v[212:215], v[10:13]
	s_setprio 2
	s_setprio 0
	v_mfma_f32_16x16x32_bf16 v[54:57], v[168:171], v[184:187], v[54:57]
	v_mfma_f32_16x16x32_bf16 v[50:53], v[176:179], v[184:187], v[50:53]
	v_mfma_f32_16x16x32_bf16 v[38:41], v[168:171], v[192:195], v[38:41]
	v_mfma_f32_16x16x32_bf16 v[34:37], v[176:179], v[192:195], v[34:37]
	v_mfma_f32_16x16x32_bf16 v[22:25], v[168:171], v[200:203], v[22:25]
	v_mfma_f32_16x16x32_bf16 v[18:21], v[176:179], v[200:203], v[18:21]
	v_mfma_f32_16x16x32_bf16 v[6:9], v[168:171], v[208:211], v[6:9]
	v_mfma_f32_16x16x32_bf16 v[2:5], v[176:179], v[208:211], v[2:5]
	v_mfma_f32_16x16x32_bf16 v[54:57], v[172:175], v[188:191], v[54:57]
	v_mfma_f32_16x16x32_bf16 v[50:53], v[180:183], v[188:191], v[50:53]
	v_mfma_f32_16x16x32_bf16 v[38:41], v[172:175], v[196:199], v[38:41]
	v_mfma_f32_16x16x32_bf16 v[34:37], v[180:183], v[196:199], v[34:37]
	v_mfma_f32_16x16x32_bf16 v[22:25], v[172:175], v[204:207], v[22:25]
	v_mfma_f32_16x16x32_bf16 v[18:21], v[180:183], v[204:207], v[18:21]
	v_mfma_f32_16x16x32_bf16 v[6:9], v[172:175], v[212:215], v[6:9]
	v_mfma_f32_16x16x32_bf16 v[2:5], v[180:183], v[212:215], v[2:5]
	s_setprio 2
	s_barrier
; #define PG8_STAGE(bufoff, gbase, voff) do { _Pragma("unroll") for (int _i = 0; _i < 2; ++_i) \
;         __builtin_amdgcn_global_load_lds((const unsigned*)((const char*)(gbase) + (voff)[_i]), (LAS unsigned*)(lds + (bufoff) + ldsw + _i * 8192), 16, 0, 0); } while (0)
; #define PG8_LDA(dst, b, h) do { _Pragma("unroll") for (int m = 0; m < 4; ++m) _Pragma("unroll") for (int k = 0; k < 2; ++k) dst[m][k] = *(const LAS bf16x8*)(lds + PG8_SA(b, h) + aoff + m * 2048 + k * 1024); } while (0)
; #define PG8_LDB(dst, b, h) do { _Pragma("unroll") for (int n = 0; n < 2; ++n) _Pragma("unroll") for (int k = 0; k < 2; ++k) dst[n][k] = *(const LAS bf16x8*)(lds + PG8_SB(b, h) + boff + n * 2048 + k * 1024); } while (0)
; #define PG8_MMA(ai, bj, At, Bt) do { __builtin_amdgcn_s_setprio(1); _Pragma("unroll") for (int m = 0; m < 4; ++m) _Pragma("unroll") for (int n = 0; n < 2; ++n) _Pragma("unroll") for (int k = 0; k < 2; ++k) \
;         acc[ai][bj][m][n] = __builtin_amdgcn_mfma_f32_16x16x32_bf16(Bt[n][k], At[m][k], acc[ai][bj][m][n], 0, 0, 0); __builtin_amdgcn_s_setprio(0); } while (0)
; #define PG8_WAIT_V(n) asm volatile("s_waitcnt vmcnt(" #n ")" ::: "memory")
; #define PG8_WAIT_L(n) asm volatile("s_waitcnt lgkmcnt(" #n ")" ::: "memory")
; #define PG8_BAR __builtin_amdgcn_s_barrier()
; #define PG8_SCHED __builtin_amdgcn_sched_barrier(0)
; template <class Epi>
; __device__ __forceinline__ void gemm_phase(LAS unsigned char* lds, const Gemm g, int G, int c, const Epi& E) {
;     ...
;             PG8_LDB(B0, 1, 0); PG8_LDB(B1, 1, 1); PG8_SCHED; PG8_LDA(At, 1, 0); PG8_STAGE(PG8_SA(0, 1), a2 + hstepA, voffA);
;             PG8_WAIT_V(8); PG8_WAIT_L(0); PG8_BAR; PG8_MMA(0, 0, At, B0); PG8_MMA(0, 1, At, B1); PG8_BAR; PG8_SCHED;
	s_add_i32 s33, 0, 0x18000
	s_add_i32 s69, 0, 0x1c000
	v_add_u32_e32 v164, s33, v147
	v_add_u32_e32 v180, s69, v147
	ds_read_b128 v[152:155], v164
	ds_read_b128 v[156:159], v164 offset:1024
	ds_read_b128 v[160:163], v164 offset:2048
	ds_read_b128 v[164:167], v164 offset:3072
	ds_read_b128 v[168:171], v180
	ds_read_b128 v[172:175], v180 offset:1024
	ds_read_b128 v[176:179], v180 offset:2048
	ds_read_b128 v[180:183], v180 offset:3072
	s_add_u32 s40, s40, 0x40000
	s_addc_u32 s41, s41, 0
	s_mov_b32 m0, s47
	v_lshl_add_u64 v[224:225], s[40:41], 0, v[136:137]
	ds_read_b128 v[184:187], v150 offset:32768
	ds_read_b128 v[188:191], v150 offset:33792
	ds_read_b128 v[192:195], v150 offset:34816
	ds_read_b128 v[196:199], v150 offset:35840
	ds_read_b128 v[200:203], v150 offset:36864
	ds_read_b128 v[204:207], v150 offset:37888
	ds_read_b128 v[208:211], v150 offset:38912
	ds_read_b128 v[212:215], v150 offset:39936
	global_load_lds_dwordx4 v[224:225], off
	v_lshl_add_u64 v[224:225], s[40:41], 0, v[132:133]
	s_mov_b32 m0, s48
	s_nop 0
	global_load_lds_dwordx4 v[224:225], off
	s_waitcnt vmcnt(8)
	s_waitcnt lgkmcnt(0)
	s_barrier
	s_setprio 0
	v_mfma_f32_16x16x32_bf16 v[126:129], v[152:155], v[184:187], v[126:129]
	v_mfma_f32_16x16x32_bf16 v[122:125], v[160:163], v[184:187], v[122:125]
	v_mfma_f32_16x16x32_bf16 v[110:113], v[152:155], v[192:195], v[110:113]
	v_mfma_f32_16x16x32_bf16 v[106:109], v[160:163], v[192:195], v[106:109]
	v_mfma_f32_16x16x32_bf16 v[94:97], v[152:155], v[200:203], v[94:97]
	v_mfma_f32_16x16x32_bf16 v[90:93], v[160:163], v[200:203], v[90:93]
	v_mfma_f32_16x16x32_bf16 v[78:81], v[152:155], v[208:211], v[78:81]
	v_mfma_f32_16x16x32_bf16 v[74:77], v[160:163], v[208:211], v[74:77]
	v_mfma_f32_16x16x32_bf16 v[126:129], v[156:159], v[188:191], v[126:129]
	v_mfma_f32_16x16x32_bf16 v[122:125], v[164:167], v[188:191], v[122:125]
	v_mfma_f32_16x16x32_bf16 v[110:113], v[156:159], v[196:199], v[110:113]
	v_mfma_f32_16x16x32_bf16 v[106:109], v[164:167], v[196:199], v[106:109]
	v_mfma_f32_16x16x32_bf16 v[94:97], v[156:159], v[204:207], v[94:97]
	v_mfma_f32_16x16x32_bf16 v[90:93], v[164:167], v[204:207], v[90:93]
	v_mfma_f32_16x16x32_bf16 v[78:81], v[156:159], v[212:215], v[78:81]
	v_mfma_f32_16x16x32_bf16 v[74:77], v[164:167], v[212:215], v[74:77]
	s_setprio 2
	s_setprio 0
	v_mfma_f32_16x16x32_bf16 v[118:121], v[168:171], v[184:187], v[118:121]
	v_mfma_f32_16x16x32_bf16 v[114:117], v[176:179], v[184:187], v[114:117]
	v_mfma_f32_16x16x32_bf16 v[102:105], v[168:171], v[192:195], v[102:105]
	v_mfma_f32_16x16x32_bf16 v[98:101], v[176:179], v[192:195], v[98:101]
	v_mfma_f32_16x16x32_bf16 v[86:89], v[168:171], v[200:203], v[86:89]
	v_mfma_f32_16x16x32_bf16 v[82:85], v[176:179], v[200:203], v[82:85]
	v_mfma_f32_16x16x32_bf16 v[70:73], v[168:171], v[208:211], v[70:73]
	v_mfma_f32_16x16x32_bf16 v[66:69], v[176:179], v[208:211], v[66:69]
	v_mfma_f32_16x16x32_bf16 v[118:121], v[172:175], v[188:191], v[118:121]
	v_mfma_f32_16x16x32_bf16 v[114:117], v[180:183], v[188:191], v[114:117]
	v_mfma_f32_16x16x32_bf16 v[102:105], v[172:175], v[196:199], v[102:105]
	v_mfma_f32_16x16x32_bf16 v[98:101], v[180:183], v[196:199], v[98:101]
	v_mfma_f32_16x16x32_bf16 v[86:89], v[172:175], v[204:207], v[86:89]
	v_mfma_f32_16x16x32_bf16 v[82:85], v[180:183], v[204:207], v[82:85]
	v_mfma_f32_16x16x32_bf16 v[70:73], v[172:175], v[212:215], v[70:73]
	v_mfma_f32_16x16x32_bf16 v[66:69], v[180:183], v[212:215], v[66:69]
	s_setprio 2
	s_barrier
; #define PG8_STAGE(bufoff, gbase, voff) do { _Pragma("unroll") for (int _i = 0; _i < 2; ++_i) \
;         __builtin_amdgcn_global_load_lds((const unsigned*)((const char*)(gbase) + (voff)[_i]), (LAS unsigned*)(lds + (bufoff) + ldsw + _i * 8192), 16, 0, 0); } while (0)
; #define PG8_LDA(dst, b, h) do { _Pragma("unroll") for (int m = 0; m < 4; ++m) _Pragma("unroll") for (int k = 0; k < 2; ++k) dst[m][k] = *(const LAS bf16x8*)(lds + PG8_SA(b, h) + aoff + m * 2048 + k * 1024); } while (0)
; #define PG8_MMA(ai, bj, At, Bt) do { __builtin_amdgcn_s_setprio(1); _Pragma("unroll") for (int m = 0; m < 4; ++m) _Pragma("unroll") for (int n = 0; n < 2; ++n) _Pragma("unroll") for (int k = 0; k < 2; ++k) \
;         acc[ai][bj][m][n] = __builtin_amdgcn_mfma_f32_16x16x32_bf16(Bt[n][k], At[m][k], acc[ai][bj][m][n], 0, 0, 0); __builtin_amdgcn_s_setprio(0); } while (0)
; #define PG8_WAIT_V(n) asm volatile("s_waitcnt vmcnt(" #n ")" ::: "memory")
; #define PG8_WAIT_L(n) asm volatile("s_waitcnt lgkmcnt(" #n ")" ::: "memory")
; #define PG8_BAR __builtin_amdgcn_s_barrier()
; #define PG8_SCHED __builtin_amdgcn_sched_barrier(0)
; template <class Epi>
; __device__ __forceinline__ void gemm_phase(LAS unsigned char* lds, const Gemm g, int G, int c, const Epi& E) {
;     ...
;             PG8_LDA(At, 1, 1); PG8_STAGE(PG8_SB(1, 0), b3, voffB); PG8_STAGE(PG8_SB(1, 1), b3 + hstepB, voffB); PG8_STAGE(PG8_SA(1, 0), a3, voffA);
;             PG8_WAIT_V(8); PG8_WAIT_L(0); PG8_BAR; PG8_MMA(1, 0, At, B0); PG8_MMA(1, 1, At, B1); PG8_BAR; PG8_SCHED;
;         }
;         if (wr == 0) PG8_BAR;
	s_add_i32 s33, s33, s46
	v_lshl_add_u64 v[216:217], v[216:217], 0, s[12:13]
	s_mov_b32 m0, s33
	ds_read_b128 v[184:187], v150 offset:49152
	ds_read_b128 v[188:191], v150 offset:50176
	ds_read_b128 v[192:195], v150 offset:51200
	ds_read_b128 v[196:199], v150 offset:52224
	ds_read_b128 v[200:203], v150 offset:53248
	ds_read_b128 v[204:207], v150 offset:54272
	ds_read_b128 v[208:211], v150 offset:55296
	ds_read_b128 v[212:215], v150 offset:56320
	global_load_lds_dwordx4 v[216:217], off
	s_add_i32 m0, s33, 0x2000
	s_add_u32 s38, s38, 0x40080
	v_lshl_add_u64 v[216:217], v[218:219], 0, s[12:13]
	s_addc_u32 s39, s39, 0
	s_add_i32 s33, s69, s46
	global_load_lds_dwordx4 v[216:217], off
	v_lshl_add_u64 v[216:217], s[38:39], 0, v[134:135]
	s_mov_b32 m0, s33
	s_nop 0
	global_load_lds_dwordx4 v[216:217], off
	v_lshl_add_u64 v[216:217], s[38:39], 0, v[130:131]
	s_add_i32 m0, s33, 0x2000
	s_nop 0
	global_load_lds_dwordx4 v[216:217], off
	v_lshl_add_u64 v[216:217], v[220:221], 0, s[12:13]
	s_mov_b32 m0, s53
	s_nop 0
	global_load_lds_dwordx4 v[216:217], off
	v_lshl_add_u64 v[216:217], v[222:223], 0, s[12:13]
	s_mov_b32 m0, s54
	s_nop 0
	global_load_lds_dwordx4 v[216:217], off
	s_waitcnt vmcnt(8)
	s_waitcnt lgkmcnt(0)
	s_barrier
	s_setprio 0
	v_mfma_f32_16x16x32_bf16 v[62:65], v[152:155], v[184:187], v[62:65]
	v_mfma_f32_16x16x32_bf16 v[58:61], v[160:163], v[184:187], v[58:61]
	v_mfma_f32_16x16x32_bf16 v[46:49], v[152:155], v[192:195], v[46:49]
	v_mfma_f32_16x16x32_bf16 v[42:45], v[160:163], v[192:195], v[42:45]
	v_mfma_f32_16x16x32_bf16 v[30:33], v[152:155], v[200:203], v[30:33]
	v_mfma_f32_16x16x32_bf16 v[26:29], v[160:163], v[200:203], v[26:29]
	v_mfma_f32_16x16x32_bf16 v[14:17], v[152:155], v[208:211], v[14:17]
	v_mfma_f32_16x16x32_bf16 v[10:13], v[160:163], v[208:211], v[10:13]
	v_mfma_f32_16x16x32_bf16 v[62:65], v[156:159], v[188:191], v[62:65]
	v_mfma_f32_16x16x32_bf16 v[58:61], v[164:167], v[188:191], v[58:61]
	v_mfma_f32_16x16x32_bf16 v[46:49], v[156:159], v[196:199], v[46:49]
	v_mfma_f32_16x16x32_bf16 v[42:45], v[164:167], v[196:199], v[42:45]
	v_mfma_f32_16x16x32_bf16 v[30:33], v[156:159], v[204:207], v[30:33]
	v_mfma_f32_16x16x32_bf16 v[26:29], v[164:167], v[204:207], v[26:29]
	v_mfma_f32_16x16x32_bf16 v[14:17], v[156:159], v[212:215], v[14:17]
	v_mfma_f32_16x16x32_bf16 v[10:13], v[164:167], v[212:215], v[10:13]
	s_setprio 2
	s_setprio 0
	v_mfma_f32_16x16x32_bf16 v[54:57], v[168:171], v[184:187], v[54:57]
	v_mfma_f32_16x16x32_bf16 v[50:53], v[176:179], v[184:187], v[50:53]
	v_mfma_f32_16x16x32_bf16 v[38:41], v[168:171], v[192:195], v[38:41]
	v_mfma_f32_16x16x32_bf16 v[34:37], v[176:179], v[192:195], v[34:37]
	v_mfma_f32_16x16x32_bf16 v[22:25], v[168:171], v[200:203], v[22:25]
	v_mfma_f32_16x16x32_bf16 v[18:21], v[176:179], v[200:203], v[18:21]
	v_mfma_f32_16x16x32_bf16 v[6:9], v[168:171], v[208:211], v[6:9]
	v_mfma_f32_16x16x32_bf16 v[2:5], v[176:179], v[208:211], v[2:5]
	v_mfma_f32_16x16x32_bf16 v[54:57], v[172:175], v[188:191], v[54:57]
	v_mfma_f32_16x16x32_bf16 v[50:53], v[180:183], v[188:191], v[50:53]
	v_mfma_f32_16x16x32_bf16 v[38:41], v[172:175], v[196:199], v[38:41]
	v_mfma_f32_16x16x32_bf16 v[34:37], v[180:183], v[196:199], v[34:37]
	v_mfma_f32_16x16x32_bf16 v[22:25], v[172:175], v[204:207], v[22:25]
	v_mfma_f32_16x16x32_bf16 v[18:21], v[180:183], v[204:207], v[18:21]
	v_mfma_f32_16x16x32_bf16 v[6:9], v[172:175], v[212:215], v[6:9]
	v_mfma_f32_16x16x32_bf16 v[2:5], v[180:183], v[212:215], v[2:5]
	s_setprio 2
	s_barrier
	s_add_i32 s68, s68, 2
	s_add_u32 s4, s4, 0x100
	s_addc_u32 s5, s5, 0
	s_add_u32 s66, s66, 0x100
	s_addc_u32 s67, s67, 0
	s_cmp_gt_u32 s68, 13
	s_cbranch_scc0 .LBB0_2084
	s_and_b64 vcc, exec, s[14:15]
	s_cbranch_vccz .LBB0_2087
	s_barrier

; #define PG8_STAGE(bufoff, gbase, voff) do { _Pragma("unroll") for (int _i = 0; _i < 2; ++_i) \
;         __builtin_amdgcn_global_load_lds((const unsigned*)((const char*)(gbase) + (voff)[_i]), (LAS unsigned*)(lds + (bufoff) + ldsw + _i * 8192), 16, 0, 0); } while (0)
; #define PG8_LDA(dst, b, h) do { _Pragma("unroll") for (int m = 0; m < 4; ++m) _Pragma("unroll") for (int k = 0; k < 2; ++k) dst[m][k] = *(const LAS bf16x8*)(lds + PG8_SA(b, h) + aoff + m * 2048 + k * 1024); } while (0)
; #define PG8_LDB(dst, b, h) do { _Pragma("unroll") for (int n = 0; n < 2; ++n) _Pragma("unroll") for (int k = 0; k < 2; ++k) dst[n][k] = *(const LAS bf16x8*)(lds + PG8_SB(b, h) + boff + n * 2048 + k * 1024); } while (0)
; #define PG8_MMA(ai, bj, At, Bt) do { __builtin_amdgcn_s_setprio(1); _Pragma("unroll") for (int m = 0; m < 4; ++m) _Pragma("unroll") for (int n = 0; n < 2; ++n) _Pragma("unroll") for (int k = 0; k < 2; ++k) \
;         acc[ai][bj][m][n] = __builtin_amdgcn_mfma_f32_16x16x32_bf16(Bt[n][k], At[m][k], acc[ai][bj][m][n], 0, 0, 0); __builtin_amdgcn_s_setprio(0); } while (0)
; #define PG8_WAIT_V(n) asm volatile("s_waitcnt vmcnt(" #n ")" ::: "memory")
; template <class Epi>
; __device__ __forceinline__ void gemm_phase(LAS unsigned char* lds, const Gemm g, int G, int c, const Epi& E) {
;     ...
;         const bool has_next = S.next(ui + 1, nxt);
;         const char* nA = has_next ? (const char*)(g.A + (size_t)nxt.pb * g.sA) + (size_t)nxt.pm * 2 * hstepA : cA;
;         const char* nB = has_next ? (const char*)(g.Bt + (size_t)nxt.pb * g.sB) + (size_t)nxt.pn * 2 * hstepB : cB;
; #pragma nounroll
;         for (int t = 0; t < nt; t += 2) {
;             const bool last = (t == nt - 2);
;             const char* a1 = cA + (size_t)(t + 1) * kstep;
;             const char* a2 = last ? nA : cA + (size_t)(t + 2) * kstep; const char* b2 = last ? nB : cB + (size_t)(t + 2) * kstep;
;             const char* a3 = a2 + kstep; const char* b3 = b2 + kstep;
;             PG8_LDB(B0, 0, 0); PG8_LDB(B1, 0, 1); PG8_SCHED; PG8_LDA(At, 0, 0); PG8_STAGE(PG8_SA(1, 1), a1 + hstepA, voffA);
;             PG8_WAIT_V(8); PG8_WAIT_L(0); PG8_BAR; PG8_MMA(0, 0, At, B0); PG8_MMA(0, 1, At, B1); PG8_BAR; PG8_SCHED;
;             PG8_LDA(At, 0, 1); PG8_STAGE(PG8_SB(0, 0), b2, voffB); PG8_STAGE(PG8_SB(0, 1), b2 + hstepB, voffB); PG8_STAGE(PG8_SA(0, 0), a2, voffA);
.LBB0_2168:
	s_add_u32 s60, s20, 0x100
	s_addc_u32 s61, s21, 0
	s_mov_b32 s62, -2
	s_waitcnt vmcnt(0)
	ds_read_b128 v[106:109], v168
	ds_read_b128 v[110:113], v168 offset:1024
	ds_read_b128 v[114:117], v168 offset:2048
	ds_read_b128 v[118:121], v168 offset:3072
	ds_read_b128 v[162:165], v169
	ds_read_b128 v[172:175], v169 offset:1024
	ds_read_b128 v[176:179], v169 offset:2048
	ds_read_b128 v[180:183], v169 offset:3072
	s_add_u32 s20, s18, 0x100
	s_addc_u32 s21, s19, 0
	s_cmp_eq_u32 s62, 40
	s_cselect_b32 s25, s5, s21
	s_cselect_b32 s24, s4, s20
	s_cselect_b32 s23, s17, s61
	s_cselect_b32 s22, s16, s60
	v_lshl_add_u64 v[216:217], s[18:19], 0, v[154:155]
	s_add_i32 m0, s40, 0xc000
	ds_read_b128 v[184:187], v170
	ds_read_b128 v[188:191], v170 offset:1024
	ds_read_b128 v[192:195], v170 offset:2048
	ds_read_b128 v[196:199], v170 offset:3072
	ds_read_b128 v[200:203], v170 offset:4096
	ds_read_b128 v[204:207], v170 offset:5120
	ds_read_b128 v[208:211], v170 offset:6144
	ds_read_b128 v[212:215], v170 offset:7168
	global_load_lds_dwordx4 v[216:217], off
	v_lshl_add_u64 v[216:217], s[18:19], 0, v[156:157]
	s_add_i32 m0, s40, 0xe000
	s_nop 0
	global_load_lds_dwordx4 v[216:217], off
	s_waitcnt vmcnt(8)
	s_waitcnt lgkmcnt(0)
	s_barrier
	s_setprio 0
	v_mfma_f32_16x16x32_bf16 v[142:145], v[106:109], v[184:187], 0
	v_mfma_f32_16x16x32_bf16 v[138:141], v[114:117], v[184:187], 0
	v_mfma_f32_16x16x32_bf16 v[126:129], v[106:109], v[192:195], 0
	v_mfma_f32_16x16x32_bf16 v[122:125], v[114:117], v[192:195], 0
	v_mfma_f32_16x16x32_bf16 v[94:97], v[106:109], v[200:203], 0
	v_mfma_f32_16x16x32_bf16 v[90:93], v[114:117], v[200:203], 0
	v_mfma_f32_16x16x32_bf16 v[78:81], v[106:109], v[208:211], 0
	v_mfma_f32_16x16x32_bf16 v[74:77], v[114:117], v[208:211], 0
	v_mfma_f32_16x16x32_bf16 v[142:145], v[110:113], v[188:191], v[142:145]
	v_mfma_f32_16x16x32_bf16 v[138:141], v[118:121], v[188:191], v[138:141]
	v_mfma_f32_16x16x32_bf16 v[126:129], v[110:113], v[196:199], v[126:129]
	v_mfma_f32_16x16x32_bf16 v[122:125], v[118:121], v[196:199], v[122:125]
	v_mfma_f32_16x16x32_bf16 v[94:97], v[110:113], v[204:207], v[94:97]
	v_mfma_f32_16x16x32_bf16 v[90:93], v[118:121], v[204:207], v[90:93]
	v_mfma_f32_16x16x32_bf16 v[78:81], v[110:113], v[212:215], v[78:81]
	v_mfma_f32_16x16x32_bf16 v[74:77], v[118:121], v[212:215], v[74:77]
	s_setprio 2
	s_setprio 0
	v_mfma_f32_16x16x32_bf16 v[134:137], v[162:165], v[184:187], 0
	v_mfma_f32_16x16x32_bf16 v[130:133], v[176:179], v[184:187], 0
	v_mfma_f32_16x16x32_bf16 v[102:105], v[162:165], v[192:195], 0
	v_mfma_f32_16x16x32_bf16 v[98:101], v[176:179], v[192:195], 0
	v_mfma_f32_16x16x32_bf16 v[86:89], v[162:165], v[200:203], 0
	v_mfma_f32_16x16x32_bf16 v[82:85], v[176:179], v[200:203], 0
	v_mfma_f32_16x16x32_bf16 v[70:73], v[162:165], v[208:211], 0
	v_mfma_f32_16x16x32_bf16 v[66:69], v[176:179], v[208:211], 0
	v_mfma_f32_16x16x32_bf16 v[134:137], v[172:175], v[188:191], v[134:137]
	v_mfma_f32_16x16x32_bf16 v[130:133], v[180:183], v[188:191], v[130:133]
	v_mfma_f32_16x16x32_bf16 v[102:105], v[172:175], v[196:199], v[102:105]
	v_mfma_f32_16x16x32_bf16 v[98:101], v[180:183], v[196:199], v[98:101]
	v_mfma_f32_16x16x32_bf16 v[86:89], v[172:175], v[204:207], v[86:89]
	v_mfma_f32_16x16x32_bf16 v[82:85], v[180:183], v[204:207], v[82:85]
	v_mfma_f32_16x16x32_bf16 v[70:73], v[172:175], v[212:215], v[70:73]
	v_mfma_f32_16x16x32_bf16 v[66:69], v[180:183], v[212:215], v[66:69]
	s_setprio 2
	s_barrier
	s_add_i32 s18, s52, s38
	v_lshl_add_u64 v[216:217], s[22:23], 0, v[150:151]
	s_mov_b32 m0, s18
	ds_read_b128 v[184:187], v170 offset:16384
	ds_read_b128 v[188:191], v170 offset:17408
	ds_read_b128 v[192:195], v170 offset:18432
	ds_read_b128 v[196:199], v170 offset:19456
	ds_read_b128 v[200:203], v170 offset:20480
	ds_read_b128 v[204:207], v170 offset:21504
	ds_read_b128 v[208:211], v170 offset:22528
	ds_read_b128 v[212:215], v170 offset:23552
	global_load_lds_dwordx4 v[216:217], off
	s_add_i32 m0, s18, 0x2000
	s_add_u32 s18, s22, 0xb0000
	v_lshl_add_u64 v[218:219], s[22:23], 0, v[146:147]
	s_addc_u32 s19, s23, 0
	s_add_i32 s33, s53, s38
	global_load_lds_dwordx4 v[218:219], off
	v_lshl_add_u64 v[220:221], s[18:19], 0, v[150:151]
	s_mov_b32 m0, s33
	v_lshl_add_u64 v[222:223], s[24:25], 0, v[148:149]
	global_load_lds_dwordx4 v[220:221], off
	v_lshl_add_u64 v[220:221], s[18:19], 0, v[146:147]
	s_add_i32 m0, s33, 0x2000
	s_nop 0
	global_load_lds_dwordx4 v[220:221], off
	v_lshl_add_u64 v[220:221], s[24:25], 0, v[152:153]
	s_mov_b32 m0, s40
	s_nop 0
	global_load_lds_dwordx4 v[220:221], off
	s_mov_b32 m0, s41
	s_nop 0
	global_load_lds_dwordx4 v[222:223], off
	s_waitcnt vmcnt(8)
	s_waitcnt lgkmcnt(0)
	s_barrier
; #define PG8_STAGE(bufoff, gbase, voff) do { _Pragma("unroll") for (int _i = 0; _i < 2; ++_i) \
;         __builtin_amdgcn_global_load_lds((const unsigned*)((const char*)(gbase) + (voff)[_i]), (LAS unsigned*)(lds + (bufoff) + ldsw + _i * 8192), 16, 0, 0); } while (0)
; #define PG8_LDA(dst, b, h) do { _Pragma("unroll") for (int m = 0; m < 4; ++m) _Pragma("unroll") for (int k = 0; k < 2; ++k) dst[m][k] = *(const LAS bf16x8*)(lds + PG8_SA(b, h) + aoff + m * 2048 + k * 1024); } while (0)
; #define PG8_LDB(dst, b, h) do { _Pragma("unroll") for (int n = 0; n < 2; ++n) _Pragma("unroll") for (int k = 0; k < 2; ++k) dst[n][k] = *(const LAS bf16x8*)(lds + PG8_SB(b, h) + boff + n * 2048 + k * 1024); } while (0)
; #define PG8_MMA(ai, bj, At, Bt) do { __builtin_amdgcn_s_setprio(1); _Pragma("unroll") for (int m = 0; m < 4; ++m) _Pragma("unroll") for (int n = 0; n < 2; ++n) _Pragma("unroll") for (int k = 0; k < 2; ++k) \
;         acc[ai][bj][m][n] = __builtin_amdgcn_mfma_f32_16x16x32_bf16(Bt[n][k], At[m][k], acc[ai][bj][m][n], 0, 0, 0); __builtin_amdgcn_s_setprio(0); } while (0)
; #define PG8_WAIT_V(n) asm volatile("s_waitcnt vmcnt(" #n ")" ::: "memory")
; #define PG8_WAIT_L(n) asm volatile("s_waitcnt lgkmcnt(" #n ")" ::: "memory")
; #define PG8_BAR __builtin_amdgcn_s_barrier()
; #define PG8_SCHED __builtin_amdgcn_sched_barrier(0)
; template <class Epi>
; __device__ __forceinline__ void gemm_phase(LAS unsigned char* lds, const Gemm g, int G, int c, const Epi& E) {
;     ...
;             PG8_WAIT_V(8); PG8_WAIT_L(0); PG8_BAR; PG8_MMA(1, 0, At, B0); PG8_MMA(1, 1, At, B1); PG8_BAR; PG8_SCHED;
;             PG8_LDB(B0, 1, 0); PG8_LDB(B1, 1, 1); PG8_SCHED; PG8_LDA(At, 1, 0); PG8_STAGE(PG8_SA(0, 1), a2 + hstepA, voffA);
;             PG8_WAIT_V(8); PG8_WAIT_L(0); PG8_BAR; PG8_MMA(0, 0, At, B0); PG8_MMA(0, 1, At, B1); PG8_BAR; PG8_SCHED;
	s_setprio 0
	v_mfma_f32_16x16x32_bf16 v[62:65], v[106:109], v[184:187], 0
	v_mfma_f32_16x16x32_bf16 v[58:61], v[114:117], v[184:187], 0
	v_mfma_f32_16x16x32_bf16 v[46:49], v[106:109], v[192:195], 0
	v_mfma_f32_16x16x32_bf16 v[42:45], v[114:117], v[192:195], 0
	v_mfma_f32_16x16x32_bf16 v[30:33], v[106:109], v[200:203], 0
	v_mfma_f32_16x16x32_bf16 v[26:29], v[114:117], v[200:203], 0
	v_mfma_f32_16x16x32_bf16 v[14:17], v[106:109], v[208:211], 0
	v_mfma_f32_16x16x32_bf16 v[10:13], v[114:117], v[208:211], 0
	v_mfma_f32_16x16x32_bf16 v[62:65], v[110:113], v[188:191], v[62:65]
	v_mfma_f32_16x16x32_bf16 v[58:61], v[118:121], v[188:191], v[58:61]
	v_mfma_f32_16x16x32_bf16 v[46:49], v[110:113], v[196:199], v[46:49]
	v_mfma_f32_16x16x32_bf16 v[42:45], v[118:121], v[196:199], v[42:45]
	v_mfma_f32_16x16x32_bf16 v[30:33], v[110:113], v[204:207], v[30:33]
	v_mfma_f32_16x16x32_bf16 v[26:29], v[118:121], v[204:207], v[26:29]
	v_mfma_f32_16x16x32_bf16 v[14:17], v[110:113], v[212:215], v[14:17]
	v_mfma_f32_16x16x32_bf16 v[10:13], v[118:121], v[212:215], v[10:13]
	s_setprio 2
	s_setprio 0
	v_mfma_f32_16x16x32_bf16 v[54:57], v[162:165], v[184:187], 0
	v_mfma_f32_16x16x32_bf16 v[50:53], v[176:179], v[184:187], 0
	v_mfma_f32_16x16x32_bf16 v[38:41], v[162:165], v[192:195], 0
	v_mfma_f32_16x16x32_bf16 v[34:37], v[176:179], v[192:195], 0
	v_mfma_f32_16x16x32_bf16 v[22:25], v[162:165], v[200:203], 0
	v_mfma_f32_16x16x32_bf16 v[18:21], v[176:179], v[200:203], 0
	v_mfma_f32_16x16x32_bf16 v[6:9], v[162:165], v[208:211], 0
	v_mfma_f32_16x16x32_bf16 v[2:5], v[176:179], v[208:211], 0
	v_mfma_f32_16x16x32_bf16 v[54:57], v[172:175], v[188:191], v[54:57]
	v_mfma_f32_16x16x32_bf16 v[50:53], v[180:183], v[188:191], v[50:53]
	v_mfma_f32_16x16x32_bf16 v[38:41], v[172:175], v[196:199], v[38:41]
	v_mfma_f32_16x16x32_bf16 v[34:37], v[180:183], v[196:199], v[34:37]
	v_mfma_f32_16x16x32_bf16 v[22:25], v[172:175], v[204:207], v[22:25]
	v_mfma_f32_16x16x32_bf16 v[18:21], v[180:183], v[204:207], v[18:21]
	v_mfma_f32_16x16x32_bf16 v[6:9], v[172:175], v[212:215], v[6:9]
	v_mfma_f32_16x16x32_bf16 v[2:5], v[180:183], v[212:215], v[2:5]
	s_setprio 2
	s_barrier
	s_add_i32 s33, 0, 0x18000
	s_add_i32 s63, 0, 0x1c000
	v_add_u32_e32 v118, s33, v167
	v_add_u32_e32 v171, s63, v167
	ds_read_b128 v[106:109], v118
	ds_read_b128 v[110:113], v118 offset:1024
	ds_read_b128 v[114:117], v118 offset:2048
	ds_read_b128 v[118:121], v118 offset:3072
	ds_read_b128 v[162:165], v171
	ds_read_b128 v[172:175], v171 offset:1024
	ds_read_b128 v[176:179], v171 offset:2048
	ds_read_b128 v[180:183], v171 offset:3072
	s_add_u32 s18, s24, 0xb0000
	s_addc_u32 s19, s25, 0
	s_mov_b32 m0, s42
	v_lshl_add_u64 v[224:225], s[18:19], 0, v[152:153]
	ds_read_b128 v[184:187], v170 offset:32768
	ds_read_b128 v[188:191], v170 offset:33792
	ds_read_b128 v[192:195], v170 offset:34816
	ds_read_b128 v[196:199], v170 offset:35840
	ds_read_b128 v[200:203], v170 offset:36864
	ds_read_b128 v[204:207], v170 offset:37888
	ds_read_b128 v[208:211], v170 offset:38912
	ds_read_b128 v[212:215], v170 offset:39936
	global_load_lds_dwordx4 v[224:225], off
	v_lshl_add_u64 v[224:225], s[18:19], 0, v[148:149]
	s_mov_b32 m0, s43
	s_nop 0
	global_load_lds_dwordx4 v[224:225], off
	s_waitcnt vmcnt(8)
	s_waitcnt lgkmcnt(0)
	s_barrier
	s_setprio 0
	v_mfma_f32_16x16x32_bf16 v[142:145], v[106:109], v[184:187], v[142:145]
	v_mfma_f32_16x16x32_bf16 v[138:141], v[114:117], v[184:187], v[138:141]
	v_mfma_f32_16x16x32_bf16 v[126:129], v[106:109], v[192:195], v[126:129]
	v_mfma_f32_16x16x32_bf16 v[122:125], v[114:117], v[192:195], v[122:125]
	v_mfma_f32_16x16x32_bf16 v[94:97], v[106:109], v[200:203], v[94:97]
	v_mfma_f32_16x16x32_bf16 v[90:93], v[114:117], v[200:203], v[90:93]
	v_mfma_f32_16x16x32_bf16 v[78:81], v[106:109], v[208:211], v[78:81]
	v_mfma_f32_16x16x32_bf16 v[74:77], v[114:117], v[208:211], v[74:77]
	v_mfma_f32_16x16x32_bf16 v[142:145], v[110:113], v[188:191], v[142:145]
	v_mfma_f32_16x16x32_bf16 v[138:141], v[118:121], v[188:191], v[138:141]
	v_mfma_f32_16x16x32_bf16 v[126:129], v[110:113], v[196:199], v[126:129]
	v_mfma_f32_16x16x32_bf16 v[122:125], v[118:121], v[196:199], v[122:125]
	v_mfma_f32_16x16x32_bf16 v[94:97], v[110:113], v[204:207], v[94:97]
	v_mfma_f32_16x16x32_bf16 v[90:93], v[118:121], v[204:207], v[90:93]
	v_mfma_f32_16x16x32_bf16 v[78:81], v[110:113], v[212:215], v[78:81]
	v_mfma_f32_16x16x32_bf16 v[74:77], v[118:121], v[212:215], v[74:77]
	s_setprio 2
	s_setprio 0
	v_mfma_f32_16x16x32_bf16 v[134:137], v[162:165], v[184:187], v[134:137]
	v_mfma_f32_16x16x32_bf16 v[130:133], v[176:179], v[184:187], v[130:133]
	v_mfma_f32_16x16x32_bf16 v[102:105], v[162:165], v[192:195], v[102:105]
	v_mfma_f32_16x16x32_bf16 v[98:101], v[176:179], v[192:195], v[98:101]
	v_mfma_f32_16x16x32_bf16 v[86:89], v[162:165], v[200:203], v[86:89]
	v_mfma_f32_16x16x32_bf16 v[82:85], v[176:179], v[200:203], v[82:85]
	v_mfma_f32_16x16x32_bf16 v[70:73], v[162:165], v[208:211], v[70:73]
	v_mfma_f32_16x16x32_bf16 v[66:69], v[176:179], v[208:211], v[66:69]
	v_mfma_f32_16x16x32_bf16 v[134:137], v[172:175], v[188:191], v[134:137]
	v_mfma_f32_16x16x32_bf16 v[130:133], v[180:183], v[188:191], v[130:133]
	v_mfma_f32_16x16x32_bf16 v[102:105], v[172:175], v[196:199], v[102:105]
	v_mfma_f32_16x16x32_bf16 v[98:101], v[180:183], v[196:199], v[98:101]
	v_mfma_f32_16x16x32_bf16 v[86:89], v[172:175], v[204:207], v[86:89]
	v_mfma_f32_16x16x32_bf16 v[82:85], v[180:183], v[204:207], v[82:85]
	v_mfma_f32_16x16x32_bf16 v[70:73], v[172:175], v[212:215], v[70:73]
	v_mfma_f32_16x16x32_bf16 v[66:69], v[180:183], v[212:215], v[66:69]
	s_setprio 2
	s_barrier
; #define PG8_STAGE(bufoff, gbase, voff) do { _Pragma("unroll") for (int _i = 0; _i < 2; ++_i) \
;         __builtin_amdgcn_global_load_lds((const unsigned*)((const char*)(gbase) + (voff)[_i]), (LAS unsigned*)(lds + (bufoff) + ldsw + _i * 8192), 16, 0, 0); } while (0)
; #define PG8_LDA(dst, b, h) do { _Pragma("unroll") for (int m = 0; m < 4; ++m) _Pragma("unroll") for (int k = 0; k < 2; ++k) dst[m][k] = *(const LAS bf16x8*)(lds + PG8_SA(b, h) + aoff + m * 2048 + k * 1024); } while (0)
; #define PG8_LDB(dst, b, h) do { _Pragma("unroll") for (int n = 0; n < 2; ++n) _Pragma("unroll") for (int k = 0; k < 2; ++k) dst[n][k] = *(const LAS bf16x8*)(lds + PG8_SB(b, h) + boff + n * 2048 + k * 1024); } while (0)
; #define PG8_MMA(ai, bj, At, Bt) do { __builtin_amdgcn_s_setprio(1); _Pragma("unroll") for (int m = 0; m < 4; ++m) _Pragma("unroll") for (int n = 0; n < 2; ++n) _Pragma("unroll") for (int k = 0; k < 2; ++k) \
;         acc[ai][bj][m][n] = __builtin_amdgcn_mfma_f32_16x16x32_bf16(Bt[n][k], At[m][k], acc[ai][bj][m][n], 0, 0, 0); __builtin_amdgcn_s_setprio(0); } while (0)
; #define PG8_WAIT_V(n) asm volatile("s_waitcnt vmcnt(" #n ")" ::: "memory")
; #define PG8_BAR __builtin_amdgcn_s_barrier()
; template <class Epi>
; __device__ __forceinline__ void gemm_phase(LAS unsigned char* lds, const Gemm g, int G, int c, const Epi& E) {
;     ...
;             PG8_LDB(B0, 0, 0); PG8_LDB(B1, 0, 1); PG8_SCHED; PG8_LDA(At, 0, 0); PG8_STAGE(PG8_SA(1, 1), a1 + hstepA, voffA);
;             PG8_WAIT_V(8); PG8_WAIT_L(0); PG8_BAR; PG8_MMA(0, 0, At, B0); PG8_MMA(0, 1, At, B1); PG8_BAR; PG8_SCHED;
;             PG8_LDA(At, 0, 1); PG8_STAGE(PG8_SB(0, 0), b2, voffB); PG8_STAGE(PG8_SB(0, 1), b2 + hstepB, voffB); PG8_STAGE(PG8_SA(0, 0), a2, voffA);
;             PG8_WAIT_V(8); PG8_WAIT_L(0); PG8_BAR; PG8_MMA(1, 0, At, B0); PG8_MMA(1, 1, At, B1); PG8_BAR; PG8_SCHED;
;             PG8_LDB(B0, 1, 0); PG8_LDB(B1, 1, 1); PG8_SCHED; PG8_LDA(At, 1, 0); PG8_STAGE(PG8_SA(0, 1), a2 + hstepA, voffA);
;             PG8_WAIT_V(8); PG8_WAIT_L(0); PG8_BAR; PG8_MMA(0, 0, At, B0); PG8_MMA(0, 1, At, B1); PG8_BAR; PG8_SCHED;
;             PG8_LDA(At, 1, 1); PG8_STAGE(PG8_SB(1, 0), b3, voffB); PG8_STAGE(PG8_SB(1, 1), b3 + hstepB, voffB); PG8_STAGE(PG8_SA(1, 0), a3, voffA);
;             PG8_WAIT_V(8); PG8_WAIT_L(0); PG8_BAR; PG8_MMA(1, 0, At, B0); PG8_MMA(1, 1, At, B1); PG8_BAR; PG8_SCHED;
	s_add_i32 s18, s33, s38
	v_lshl_add_u64 v[216:217], v[216:217], 0, s[12:13]
	s_mov_b32 m0, s18
	ds_read_b128 v[184:187], v170 offset:49152
	ds_read_b128 v[188:191], v170 offset:50176
	ds_read_b128 v[192:195], v170 offset:51200
	ds_read_b128 v[196:199], v170 offset:52224
	ds_read_b128 v[200:203], v170 offset:53248
	ds_read_b128 v[204:207], v170 offset:54272
	ds_read_b128 v[208:211], v170 offset:55296
	ds_read_b128 v[212:215], v170 offset:56320
	global_load_lds_dwordx4 v[216:217], off
	s_add_i32 m0, s18, 0x2000
	s_add_u32 s18, s22, 0xb0080
	v_lshl_add_u64 v[216:217], v[218:219], 0, s[12:13]
	s_addc_u32 s19, s23, 0
	s_add_i32 s22, s63, s38
	global_load_lds_dwordx4 v[216:217], off
	v_lshl_add_u64 v[216:217], s[18:19], 0, v[150:151]
	s_mov_b32 m0, s22
	s_nop 0
	global_load_lds_dwordx4 v[216:217], off
	v_lshl_add_u64 v[216:217], s[18:19], 0, v[146:147]
	s_add_i32 m0, s22, 0x2000
	s_nop 0
	global_load_lds_dwordx4 v[216:217], off
	v_lshl_add_u64 v[216:217], v[220:221], 0, s[12:13]
	s_mov_b32 m0, s49
	s_nop 0
	global_load_lds_dwordx4 v[216:217], off
	v_lshl_add_u64 v[216:217], v[222:223], 0, s[12:13]
	s_mov_b32 m0, s50
	s_nop 0
	global_load_lds_dwordx4 v[216:217], off
	s_waitcnt vmcnt(8)
	s_waitcnt lgkmcnt(0)
	s_barrier
	s_setprio 0
	v_mfma_f32_16x16x32_bf16 v[62:65], v[106:109], v[184:187], v[62:65]
	v_mfma_f32_16x16x32_bf16 v[58:61], v[114:117], v[184:187], v[58:61]
	v_mfma_f32_16x16x32_bf16 v[46:49], v[106:109], v[192:195], v[46:49]
	v_mfma_f32_16x16x32_bf16 v[42:45], v[114:117], v[192:195], v[42:45]
	v_mfma_f32_16x16x32_bf16 v[30:33], v[106:109], v[200:203], v[30:33]
	v_mfma_f32_16x16x32_bf16 v[26:29], v[114:117], v[200:203], v[26:29]
	v_mfma_f32_16x16x32_bf16 v[14:17], v[106:109], v[208:211], v[14:17]
	v_mfma_f32_16x16x32_bf16 v[10:13], v[114:117], v[208:211], v[10:13]
	v_mfma_f32_16x16x32_bf16 v[62:65], v[110:113], v[188:191], v[62:65]
	v_mfma_f32_16x16x32_bf16 v[58:61], v[118:121], v[188:191], v[58:61]
	v_mfma_f32_16x16x32_bf16 v[46:49], v[110:113], v[196:199], v[46:49]
	v_mfma_f32_16x16x32_bf16 v[42:45], v[118:121], v[196:199], v[42:45]
	v_mfma_f32_16x16x32_bf16 v[30:33], v[110:113], v[204:207], v[30:33]
	v_mfma_f32_16x16x32_bf16 v[26:29], v[118:121], v[204:207], v[26:29]
	v_mfma_f32_16x16x32_bf16 v[14:17], v[110:113], v[212:215], v[14:17]
	v_mfma_f32_16x16x32_bf16 v[10:13], v[118:121], v[212:215], v[10:13]
	s_setprio 2
	s_setprio 0
	v_mfma_f32_16x16x32_bf16 v[54:57], v[162:165], v[184:187], v[54:57]
	v_mfma_f32_16x16x32_bf16 v[50:53], v[176:179], v[184:187], v[50:53]
	v_mfma_f32_16x16x32_bf16 v[38:41], v[162:165], v[192:195], v[38:41]
	v_mfma_f32_16x16x32_bf16 v[34:37], v[176:179], v[192:195], v[34:37]
	v_mfma_f32_16x16x32_bf16 v[22:25], v[162:165], v[200:203], v[22:25]
	v_mfma_f32_16x16x32_bf16 v[18:21], v[176:179], v[200:203], v[18:21]
	v_mfma_f32_16x16x32_bf16 v[6:9], v[162:165], v[208:211], v[6:9]
	v_mfma_f32_16x16x32_bf16 v[2:5], v[176:179], v[208:211], v[2:5]
	v_mfma_f32_16x16x32_bf16 v[54:57], v[172:175], v[188:191], v[54:57]
	v_mfma_f32_16x16x32_bf16 v[50:53], v[180:183], v[188:191], v[50:53]
	v_mfma_f32_16x16x32_bf16 v[38:41], v[172:175], v[196:199], v[38:41]
	v_mfma_f32_16x16x32_bf16 v[34:37], v[180:183], v[196:199], v[34:37]
	v_mfma_f32_16x16x32_bf16 v[22:25], v[172:175], v[204:207], v[22:25]
	v_mfma_f32_16x16x32_bf16 v[18:21], v[180:183], v[204:207], v[18:21]
	v_mfma_f32_16x16x32_bf16 v[6:9], v[172:175], v[212:215], v[6:9]
	v_mfma_f32_16x16x32_bf16 v[2:5], v[180:183], v[212:215], v[2:5]
	s_setprio 2
	s_barrier
	s_add_i32 s62, s62, 2
	s_add_u32 s60, s60, 0x100
	s_addc_u32 s61, s61, 0
	s_cmp_gt_u32 s62, 41
	s_mov_b64 s[18:19], s[20:21]
	s_cbranch_scc0 .LBB0_2169
.LBB0_2169:
	ds_read_b128 v[106:109], v168
	ds_read_b128 v[110:113], v168 offset:1024
	ds_read_b128 v[114:117], v168 offset:2048
	ds_read_b128 v[118:121], v168 offset:3072
	ds_read_b128 v[162:165], v169
	ds_read_b128 v[172:175], v169 offset:1024
	ds_read_b128 v[176:179], v169 offset:2048
	ds_read_b128 v[180:183], v169 offset:3072
	s_add_u32 s20, s18, 0x100
	s_addc_u32 s21, s19, 0
	s_cmp_eq_u32 s62, 40
	s_cselect_b32 s25, s5, s21
	s_cselect_b32 s24, s4, s20
	s_cselect_b32 s23, s17, s61
	s_cselect_b32 s22, s16, s60
	v_lshl_add_u64 v[216:217], s[18:19], 0, v[154:155]
	s_add_i32 m0, s40, 0xc000
	ds_read_b128 v[184:187], v170
	ds_read_b128 v[188:191], v170 offset:1024
	ds_read_b128 v[192:195], v170 offset:2048
	ds_read_b128 v[196:199], v170 offset:3072
	ds_read_b128 v[200:203], v170 offset:4096
	ds_read_b128 v[204:207], v170 offset:5120
	ds_read_b128 v[208:211], v170 offset:6144
	ds_read_b128 v[212:215], v170 offset:7168
	global_load_lds_dwordx4 v[216:217], off
	v_lshl_add_u64 v[216:217], s[18:19], 0, v[156:157]
	s_add_i32 m0, s40, 0xe000
	s_nop 0
	global_load_lds_dwordx4 v[216:217], off
	s_waitcnt vmcnt(8)
	s_waitcnt lgkmcnt(0)
	s_barrier
; #define PG8_STAGE(bufoff, gbase, voff) do { _Pragma("unroll") for (int _i = 0; _i < 2; ++_i) \
;         __builtin_amdgcn_global_load_lds((const unsigned*)((const char*)(gbase) + (voff)[_i]), (LAS unsigned*)(lds + (bufoff) + ldsw + _i * 8192), 16, 0, 0); } while (0)
; #define PG8_LDA(dst, b, h) do { _Pragma("unroll") for (int m = 0; m < 4; ++m) _Pragma("unroll") for (int k = 0; k < 2; ++k) dst[m][k] = *(const LAS bf16x8*)(lds + PG8_SA(b, h) + aoff + m * 2048 + k * 1024); } while (0)
; #define PG8_MMA(ai, bj, At, Bt) do { __builtin_amdgcn_s_setprio(1); _Pragma("unroll") for (int m = 0; m < 4; ++m) _Pragma("unroll") for (int n = 0; n < 2; ++n) _Pragma("unroll") for (int k = 0; k < 2; ++k) \
;         acc[ai][bj][m][n] = __builtin_amdgcn_mfma_f32_16x16x32_bf16(Bt[n][k], At[m][k], acc[ai][bj][m][n], 0, 0, 0); __builtin_amdgcn_s_setprio(0); } while (0)
; #define PG8_WAIT_V(n) asm volatile("s_waitcnt vmcnt(" #n ")" ::: "memory")
; #define PG8_WAIT_L(n) asm volatile("s_waitcnt lgkmcnt(" #n ")" ::: "memory")
; #define PG8_BAR __builtin_amdgcn_s_barrier()
; #define PG8_SCHED __builtin_amdgcn_sched_barrier(0)
; template <class Epi>
; __device__ __forceinline__ void gemm_phase(LAS unsigned char* lds, const Gemm g, int G, int c, const Epi& E) {
;     ...
;             PG8_WAIT_V(8); PG8_WAIT_L(0); PG8_BAR; PG8_MMA(0, 0, At, B0); PG8_MMA(0, 1, At, B1); PG8_BAR; PG8_SCHED;
;             PG8_LDA(At, 0, 1); PG8_STAGE(PG8_SB(0, 0), b2, voffB); PG8_STAGE(PG8_SB(0, 1), b2 + hstepB, voffB); PG8_STAGE(PG8_SA(0, 0), a2, voffA);
;             PG8_WAIT_V(8); PG8_WAIT_L(0); PG8_BAR; PG8_MMA(1, 0, At, B0); PG8_MMA(1, 1, At, B1); PG8_BAR; PG8_SCHED;
	s_setprio 0
	v_mfma_f32_16x16x32_bf16 v[142:145], v[106:109], v[184:187], v[142:145]
	v_mfma_f32_16x16x32_bf16 v[138:141], v[114:117], v[184:187], v[138:141]
	v_mfma_f32_16x16x32_bf16 v[126:129], v[106:109], v[192:195], v[126:129]
	v_mfma_f32_16x16x32_bf16 v[122:125], v[114:117], v[192:195], v[122:125]
	v_mfma_f32_16x16x32_bf16 v[94:97], v[106:109], v[200:203], v[94:97]
	v_mfma_f32_16x16x32_bf16 v[90:93], v[114:117], v[200:203], v[90:93]
	v_mfma_f32_16x16x32_bf16 v[78:81], v[106:109], v[208:211], v[78:81]
	v_mfma_f32_16x16x32_bf16 v[74:77], v[114:117], v[208:211], v[74:77]
	v_mfma_f32_16x16x32_bf16 v[142:145], v[110:113], v[188:191], v[142:145]
	v_mfma_f32_16x16x32_bf16 v[138:141], v[118:121], v[188:191], v[138:141]
	v_mfma_f32_16x16x32_bf16 v[126:129], v[110:113], v[196:199], v[126:129]
	v_mfma_f32_16x16x32_bf16 v[122:125], v[118:121], v[196:199], v[122:125]
	v_mfma_f32_16x16x32_bf16 v[94:97], v[110:113], v[204:207], v[94:97]
	v_mfma_f32_16x16x32_bf16 v[90:93], v[118:121], v[204:207], v[90:93]
	v_mfma_f32_16x16x32_bf16 v[78:81], v[110:113], v[212:215], v[78:81]
	v_mfma_f32_16x16x32_bf16 v[74:77], v[118:121], v[212:215], v[74:77]
	s_setprio 2
	s_setprio 0
	v_mfma_f32_16x16x32_bf16 v[134:137], v[162:165], v[184:187], v[134:137]
	v_mfma_f32_16x16x32_bf16 v[130:133], v[176:179], v[184:187], v[130:133]
	v_mfma_f32_16x16x32_bf16 v[102:105], v[162:165], v[192:195], v[102:105]
	v_mfma_f32_16x16x32_bf16 v[98:101], v[176:179], v[192:195], v[98:101]
	v_mfma_f32_16x16x32_bf16 v[86:89], v[162:165], v[200:203], v[86:89]
	v_mfma_f32_16x16x32_bf16 v[82:85], v[176:179], v[200:203], v[82:85]
	v_mfma_f32_16x16x32_bf16 v[70:73], v[162:165], v[208:211], v[70:73]
	v_mfma_f32_16x16x32_bf16 v[66:69], v[176:179], v[208:211], v[66:69]
	v_mfma_f32_16x16x32_bf16 v[134:137], v[172:175], v[188:191], v[134:137]
	v_mfma_f32_16x16x32_bf16 v[130:133], v[180:183], v[188:191], v[130:133]
	v_mfma_f32_16x16x32_bf16 v[102:105], v[172:175], v[196:199], v[102:105]
	v_mfma_f32_16x16x32_bf16 v[98:101], v[180:183], v[196:199], v[98:101]
	v_mfma_f32_16x16x32_bf16 v[86:89], v[172:175], v[204:207], v[86:89]
	v_mfma_f32_16x16x32_bf16 v[82:85], v[180:183], v[204:207], v[82:85]
	v_mfma_f32_16x16x32_bf16 v[70:73], v[172:175], v[212:215], v[70:73]
	v_mfma_f32_16x16x32_bf16 v[66:69], v[180:183], v[212:215], v[66:69]
	s_setprio 2
	s_barrier
	s_add_i32 s18, s52, s38
	v_lshl_add_u64 v[216:217], s[22:23], 0, v[150:151]
	s_mov_b32 m0, s18
	ds_read_b128 v[184:187], v170 offset:16384
	ds_read_b128 v[188:191], v170 offset:17408
	ds_read_b128 v[192:195], v170 offset:18432
	ds_read_b128 v[196:199], v170 offset:19456
	ds_read_b128 v[200:203], v170 offset:20480
	ds_read_b128 v[204:207], v170 offset:21504
	ds_read_b128 v[208:211], v170 offset:22528
	ds_read_b128 v[212:215], v170 offset:23552
	global_load_lds_dwordx4 v[216:217], off
	s_add_i32 m0, s18, 0x2000
	s_add_u32 s18, s22, 0xb0000
	v_lshl_add_u64 v[218:219], s[22:23], 0, v[146:147]
	s_addc_u32 s19, s23, 0
	s_add_i32 s33, s53, s38
	global_load_lds_dwordx4 v[218:219], off
	v_lshl_add_u64 v[220:221], s[18:19], 0, v[150:151]
	s_mov_b32 m0, s33
	v_lshl_add_u64 v[222:223], s[24:25], 0, v[148:149]
	global_load_lds_dwordx4 v[220:221], off
	v_lshl_add_u64 v[220:221], s[18:19], 0, v[146:147]
	s_add_i32 m0, s33, 0x2000
	s_nop 0
	global_load_lds_dwordx4 v[220:221], off
	v_lshl_add_u64 v[220:221], s[24:25], 0, v[152:153]
	s_mov_b32 m0, s40
	s_nop 0
	global_load_lds_dwordx4 v[220:221], off
	s_mov_b32 m0, s41
	s_nop 0
	global_load_lds_dwordx4 v[222:223], off
	s_waitcnt vmcnt(8)
	s_waitcnt lgkmcnt(0)
	s_barrier
	s_setprio 0
	v_mfma_f32_16x16x32_bf16 v[62:65], v[106:109], v[184:187], v[62:65]
	v_mfma_f32_16x16x32_bf16 v[58:61], v[114:117], v[184:187], v[58:61]
	v_mfma_f32_16x16x32_bf16 v[46:49], v[106:109], v[192:195], v[46:49]
	v_mfma_f32_16x16x32_bf16 v[42:45], v[114:117], v[192:195], v[42:45]
	v_mfma_f32_16x16x32_bf16 v[30:33], v[106:109], v[200:203], v[30:33]
	v_mfma_f32_16x16x32_bf16 v[26:29], v[114:117], v[200:203], v[26:29]
	v_mfma_f32_16x16x32_bf16 v[14:17], v[106:109], v[208:211], v[14:17]
	v_mfma_f32_16x16x32_bf16 v[10:13], v[114:117], v[208:211], v[10:13]
	v_mfma_f32_16x16x32_bf16 v[62:65], v[110:113], v[188:191], v[62:65]
	v_mfma_f32_16x16x32_bf16 v[58:61], v[118:121], v[188:191], v[58:61]
	v_mfma_f32_16x16x32_bf16 v[46:49], v[110:113], v[196:199], v[46:49]
	v_mfma_f32_16x16x32_bf16 v[42:45], v[118:121], v[196:199], v[42:45]
	v_mfma_f32_16x16x32_bf16 v[30:33], v[110:113], v[204:207], v[30:33]
	v_mfma_f32_16x16x32_bf16 v[26:29], v[118:121], v[204:207], v[26:29]
	v_mfma_f32_16x16x32_bf16 v[14:17], v[110:113], v[212:215], v[14:17]
	v_mfma_f32_16x16x32_bf16 v[10:13], v[118:121], v[212:215], v[10:13]
	s_setprio 2
	s_setprio 0
	v_mfma_f32_16x16x32_bf16 v[54:57], v[162:165], v[184:187], v[54:57]
	v_mfma_f32_16x16x32_bf16 v[50:53], v[176:179], v[184:187], v[50:53]
	v_mfma_f32_16x16x32_bf16 v[38:41], v[162:165], v[192:195], v[38:41]
	v_mfma_f32_16x16x32_bf16 v[34:37], v[176:179], v[192:195], v[34:37]
	v_mfma_f32_16x16x32_bf16 v[22:25], v[162:165], v[200:203], v[22:25]
	v_mfma_f32_16x16x32_bf16 v[18:21], v[176:179], v[200:203], v[18:21]
	v_mfma_f32_16x16x32_bf16 v[6:9], v[162:165], v[208:211], v[6:9]
	v_mfma_f32_16x16x32_bf16 v[2:5], v[176:179], v[208:211], v[2:5]
	v_mfma_f32_16x16x32_bf16 v[54:57], v[172:175], v[188:191], v[54:57]
	v_mfma_f32_16x16x32_bf16 v[50:53], v[180:183], v[188:191], v[50:53]
	v_mfma_f32_16x16x32_bf16 v[38:41], v[172:175], v[196:199], v[38:41]
	v_mfma_f32_16x16x32_bf16 v[34:37], v[180:183], v[196:199], v[34:37]
	v_mfma_f32_16x16x32_bf16 v[22:25], v[172:175], v[204:207], v[22:25]
	v_mfma_f32_16x16x32_bf16 v[18:21], v[180:183], v[204:207], v[18:21]
	v_mfma_f32_16x16x32_bf16 v[6:9], v[172:175], v[212:215], v[6:9]
	v_mfma_f32_16x16x32_bf16 v[2:5], v[180:183], v[212:215], v[2:5]
	s_setprio 2
	s_barrier
; #define PG8_STAGE(bufoff, gbase, voff) do { _Pragma("unroll") for (int _i = 0; _i < 2; ++_i) \
;         __builtin_amdgcn_global_load_lds((const unsigned*)((const char*)(gbase) + (voff)[_i]), (LAS unsigned*)(lds + (bufoff) + ldsw + _i * 8192), 16, 0, 0); } while (0)
; #define PG8_LDA(dst, b, h) do { _Pragma("unroll") for (int m = 0; m < 4; ++m) _Pragma("unroll") for (int k = 0; k < 2; ++k) dst[m][k] = *(const LAS bf16x8*)(lds + PG8_SA(b, h) + aoff + m * 2048 + k * 1024); } while (0)
; #define PG8_LDB(dst, b, h) do { _Pragma("unroll") for (int n = 0; n < 2; ++n) _Pragma("unroll") for (int k = 0; k < 2; ++k) dst[n][k] = *(const LAS bf16x8*)(lds + PG8_SB(b, h) + boff + n * 2048 + k * 1024); } while (0)
; #define PG8_MMA(ai, bj, At, Bt) do { __builtin_amdgcn_s_setprio(1); _Pragma("unroll") for (int m = 0; m < 4; ++m) _Pragma("unroll") for (int n = 0; n < 2; ++n) _Pragma("unroll") for (int k = 0; k < 2; ++k) \
;         acc[ai][bj][m][n] = __builtin_amdgcn_mfma_f32_16x16x32_bf16(Bt[n][k], At[m][k], acc[ai][bj][m][n], 0, 0, 0); __builtin_amdgcn_s_setprio(0); } while (0)
; #define PG8_WAIT_V(n) asm volatile("s_waitcnt vmcnt(" #n ")" ::: "memory")
; #define PG8_WAIT_L(n) asm volatile("s_waitcnt lgkmcnt(" #n ")" ::: "memory")
; #define PG8_BAR __builtin_amdgcn_s_barrier()
; #define PG8_SCHED __builtin_amdgcn_sched_barrier(0)
; template <class Epi>
; __device__ __forceinline__ void gemm_phase(LAS unsigned char* lds, const Gemm g, int G, int c, const Epi& E) {
;     ...
;             PG8_LDB(B0, 1, 0); PG8_LDB(B1, 1, 1); PG8_SCHED; PG8_LDA(At, 1, 0); PG8_STAGE(PG8_SA(0, 1), a2 + hstepA, voffA);
;             PG8_WAIT_V(8); PG8_WAIT_L(0); PG8_BAR; PG8_MMA(0, 0, At, B0); PG8_MMA(0, 1, At, B1); PG8_BAR; PG8_SCHED;
	s_add_i32 s33, 0, 0x18000
	s_add_i32 s63, 0, 0x1c000
	v_add_u32_e32 v118, s33, v167
	v_add_u32_e32 v171, s63, v167
	ds_read_b128 v[106:109], v118
	ds_read_b128 v[110:113], v118 offset:1024
	ds_read_b128 v[114:117], v118 offset:2048
	ds_read_b128 v[118:121], v118 offset:3072
	ds_read_b128 v[162:165], v171
	ds_read_b128 v[172:175], v171 offset:1024
	ds_read_b128 v[176:179], v171 offset:2048
	ds_read_b128 v[180:183], v171 offset:3072
	s_add_u32 s18, s24, 0xb0000
	s_addc_u32 s19, s25, 0
	s_mov_b32 m0, s42
	v_lshl_add_u64 v[224:225], s[18:19], 0, v[152:153]
	ds_read_b128 v[184:187], v170 offset:32768
	ds_read_b128 v[188:191], v170 offset:33792
	ds_read_b128 v[192:195], v170 offset:34816
	ds_read_b128 v[196:199], v170 offset:35840
	ds_read_b128 v[200:203], v170 offset:36864
	ds_read_b128 v[204:207], v170 offset:37888
	ds_read_b128 v[208:211], v170 offset:38912
	ds_read_b128 v[212:215], v170 offset:39936
	global_load_lds_dwordx4 v[224:225], off
	v_lshl_add_u64 v[224:225], s[18:19], 0, v[148:149]
	s_mov_b32 m0, s43
	s_nop 0
	global_load_lds_dwordx4 v[224:225], off
	s_waitcnt vmcnt(8)
	s_waitcnt lgkmcnt(0)
	s_barrier
	s_setprio 0
	v_mfma_f32_16x16x32_bf16 v[142:145], v[106:109], v[184:187], v[142:145]
	v_mfma_f32_16x16x32_bf16 v[138:141], v[114:117], v[184:187], v[138:141]
	v_mfma_f32_16x16x32_bf16 v[126:129], v[106:109], v[192:195], v[126:129]
	v_mfma_f32_16x16x32_bf16 v[122:125], v[114:117], v[192:195], v[122:125]
	v_mfma_f32_16x16x32_bf16 v[94:97], v[106:109], v[200:203], v[94:97]
	v_mfma_f32_16x16x32_bf16 v[90:93], v[114:117], v[200:203], v[90:93]
	v_mfma_f32_16x16x32_bf16 v[78:81], v[106:109], v[208:211], v[78:81]
	v_mfma_f32_16x16x32_bf16 v[74:77], v[114:117], v[208:211], v[74:77]
	v_mfma_f32_16x16x32_bf16 v[142:145], v[110:113], v[188:191], v[142:145]
	v_mfma_f32_16x16x32_bf16 v[138:141], v[118:121], v[188:191], v[138:141]
	v_mfma_f32_16x16x32_bf16 v[126:129], v[110:113], v[196:199], v[126:129]
	v_mfma_f32_16x16x32_bf16 v[122:125], v[118:121], v[196:199], v[122:125]
	v_mfma_f32_16x16x32_bf16 v[94:97], v[110:113], v[204:207], v[94:97]
	v_mfma_f32_16x16x32_bf16 v[90:93], v[118:121], v[204:207], v[90:93]
	v_mfma_f32_16x16x32_bf16 v[78:81], v[110:113], v[212:215], v[78:81]
	v_mfma_f32_16x16x32_bf16 v[74:77], v[118:121], v[212:215], v[74:77]
	s_setprio 2
	s_setprio 0
	v_mfma_f32_16x16x32_bf16 v[134:137], v[162:165], v[184:187], v[134:137]
	v_mfma_f32_16x16x32_bf16 v[130:133], v[176:179], v[184:187], v[130:133]
	v_mfma_f32_16x16x32_bf16 v[102:105], v[162:165], v[192:195], v[102:105]
	v_mfma_f32_16x16x32_bf16 v[98:101], v[176:179], v[192:195], v[98:101]
	v_mfma_f32_16x16x32_bf16 v[86:89], v[162:165], v[200:203], v[86:89]
	v_mfma_f32_16x16x32_bf16 v[82:85], v[176:179], v[200:203], v[82:85]
	v_mfma_f32_16x16x32_bf16 v[70:73], v[162:165], v[208:211], v[70:73]
	v_mfma_f32_16x16x32_bf16 v[66:69], v[176:179], v[208:211], v[66:69]
	v_mfma_f32_16x16x32_bf16 v[134:137], v[172:175], v[188:191], v[134:137]
	v_mfma_f32_16x16x32_bf16 v[130:133], v[180:183], v[188:191], v[130:133]
	v_mfma_f32_16x16x32_bf16 v[102:105], v[172:175], v[196:199], v[102:105]
	v_mfma_f32_16x16x32_bf16 v[98:101], v[180:183], v[196:199], v[98:101]
	v_mfma_f32_16x16x32_bf16 v[86:89], v[172:175], v[204:207], v[86:89]
	v_mfma_f32_16x16x32_bf16 v[82:85], v[180:183], v[204:207], v[82:85]
	v_mfma_f32_16x16x32_bf16 v[70:73], v[172:175], v[212:215], v[70:73]
	v_mfma_f32_16x16x32_bf16 v[66:69], v[180:183], v[212:215], v[66:69]
	s_setprio 2
	s_barrier
; #define PG8_STAGE(bufoff, gbase, voff) do { _Pragma("unroll") for (int _i = 0; _i < 2; ++_i) \
;         __builtin_amdgcn_global_load_lds((const unsigned*)((const char*)(gbase) + (voff)[_i]), (LAS unsigned*)(lds + (bufoff) + ldsw + _i * 8192), 16, 0, 0); } while (0)
; #define PG8_LDA(dst, b, h) do { _Pragma("unroll") for (int m = 0; m < 4; ++m) _Pragma("unroll") for (int k = 0; k < 2; ++k) dst[m][k] = *(const LAS bf16x8*)(lds + PG8_SA(b, h) + aoff + m * 2048 + k * 1024); } while (0)
; #define PG8_MMA(ai, bj, At, Bt) do { __builtin_amdgcn_s_setprio(1); _Pragma("unroll") for (int m = 0; m < 4; ++m) _Pragma("unroll") for (int n = 0; n < 2; ++n) _Pragma("unroll") for (int k = 0; k < 2; ++k) \
;         acc[ai][bj][m][n] = __builtin_amdgcn_mfma_f32_16x16x32_bf16(Bt[n][k], At[m][k], acc[ai][bj][m][n], 0, 0, 0); __builtin_amdgcn_s_setprio(0); } while (0)
; #define PG8_WAIT_V(n) asm volatile("s_waitcnt vmcnt(" #n ")" ::: "memory")
; #define PG8_WAIT_L(n) asm volatile("s_waitcnt lgkmcnt(" #n ")" ::: "memory")
; #define PG8_BAR __builtin_amdgcn_s_barrier()
; #define PG8_SCHED __builtin_amdgcn_sched_barrier(0)
; template <class Epi>
; __device__ __forceinline__ void gemm_phase(LAS unsigned char* lds, const Gemm g, int G, int c, const Epi& E) {
;     ...
;             PG8_LDA(At, 1, 1); PG8_STAGE(PG8_SB(1, 0), b3, voffB); PG8_STAGE(PG8_SB(1, 1), b3 + hstepB, voffB); PG8_STAGE(PG8_SA(1, 0), a3, voffA);
;             PG8_WAIT_V(8); PG8_WAIT_L(0); PG8_BAR; PG8_MMA(1, 0, At, B0); PG8_MMA(1, 1, At, B1); PG8_BAR; PG8_SCHED;
;         }
;         if (wr == 0) PG8_BAR;
	s_add_i32 s18, s33, s38
	v_lshl_add_u64 v[216:217], v[216:217], 0, s[12:13]
	s_mov_b32 m0, s18
	ds_read_b128 v[184:187], v170 offset:49152
	ds_read_b128 v[188:191], v170 offset:50176
	ds_read_b128 v[192:195], v170 offset:51200
	ds_read_b128 v[196:199], v170 offset:52224
	ds_read_b128 v[200:203], v170 offset:53248
	ds_read_b128 v[204:207], v170 offset:54272
	ds_read_b128 v[208:211], v170 offset:55296
	ds_read_b128 v[212:215], v170 offset:56320
	global_load_lds_dwordx4 v[216:217], off
	s_add_i32 m0, s18, 0x2000
	s_add_u32 s18, s22, 0xb0080
	v_lshl_add_u64 v[216:217], v[218:219], 0, s[12:13]
	s_addc_u32 s19, s23, 0
	s_add_i32 s22, s63, s38
	global_load_lds_dwordx4 v[216:217], off
	v_lshl_add_u64 v[216:217], s[18:19], 0, v[150:151]
	s_mov_b32 m0, s22
	s_nop 0
	global_load_lds_dwordx4 v[216:217], off
	v_lshl_add_u64 v[216:217], s[18:19], 0, v[146:147]
	s_add_i32 m0, s22, 0x2000
	s_nop 0
	global_load_lds_dwordx4 v[216:217], off
	v_lshl_add_u64 v[216:217], v[220:221], 0, s[12:13]
	s_mov_b32 m0, s49
	s_nop 0
	global_load_lds_dwordx4 v[216:217], off
	v_lshl_add_u64 v[216:217], v[222:223], 0, s[12:13]
	s_mov_b32 m0, s50
	s_nop 0
	global_load_lds_dwordx4 v[216:217], off
	s_waitcnt vmcnt(8)
	s_waitcnt lgkmcnt(0)
	s_barrier
	s_setprio 0
	v_mfma_f32_16x16x32_bf16 v[62:65], v[106:109], v[184:187], v[62:65]
	v_mfma_f32_16x16x32_bf16 v[58:61], v[114:117], v[184:187], v[58:61]
	v_mfma_f32_16x16x32_bf16 v[46:49], v[106:109], v[192:195], v[46:49]
	v_mfma_f32_16x16x32_bf16 v[42:45], v[114:117], v[192:195], v[42:45]
	v_mfma_f32_16x16x32_bf16 v[30:33], v[106:109], v[200:203], v[30:33]
	v_mfma_f32_16x16x32_bf16 v[26:29], v[114:117], v[200:203], v[26:29]
	v_mfma_f32_16x16x32_bf16 v[14:17], v[106:109], v[208:211], v[14:17]
	v_mfma_f32_16x16x32_bf16 v[10:13], v[114:117], v[208:211], v[10:13]
	v_mfma_f32_16x16x32_bf16 v[62:65], v[110:113], v[188:191], v[62:65]
	v_mfma_f32_16x16x32_bf16 v[58:61], v[118:121], v[188:191], v[58:61]
	v_mfma_f32_16x16x32_bf16 v[46:49], v[110:113], v[196:199], v[46:49]
	v_mfma_f32_16x16x32_bf16 v[42:45], v[118:121], v[196:199], v[42:45]
	v_mfma_f32_16x16x32_bf16 v[30:33], v[110:113], v[204:207], v[30:33]
	v_mfma_f32_16x16x32_bf16 v[26:29], v[118:121], v[204:207], v[26:29]
	v_mfma_f32_16x16x32_bf16 v[14:17], v[110:113], v[212:215], v[14:17]
	v_mfma_f32_16x16x32_bf16 v[10:13], v[118:121], v[212:215], v[10:13]
	s_setprio 2
	s_setprio 0
	v_mfma_f32_16x16x32_bf16 v[54:57], v[162:165], v[184:187], v[54:57]
	v_mfma_f32_16x16x32_bf16 v[50:53], v[176:179], v[184:187], v[50:53]
	v_mfma_f32_16x16x32_bf16 v[38:41], v[162:165], v[192:195], v[38:41]
	v_mfma_f32_16x16x32_bf16 v[34:37], v[176:179], v[192:195], v[34:37]
	v_mfma_f32_16x16x32_bf16 v[22:25], v[162:165], v[200:203], v[22:25]
	v_mfma_f32_16x16x32_bf16 v[18:21], v[176:179], v[200:203], v[18:21]
	v_mfma_f32_16x16x32_bf16 v[6:9], v[162:165], v[208:211], v[6:9]
	v_mfma_f32_16x16x32_bf16 v[2:5], v[176:179], v[208:211], v[2:5]
	v_mfma_f32_16x16x32_bf16 v[54:57], v[172:175], v[188:191], v[54:57]
	v_mfma_f32_16x16x32_bf16 v[50:53], v[180:183], v[188:191], v[50:53]
	v_mfma_f32_16x16x32_bf16 v[38:41], v[172:175], v[196:199], v[38:41]
	v_mfma_f32_16x16x32_bf16 v[34:37], v[180:183], v[196:199], v[34:37]
	v_mfma_f32_16x16x32_bf16 v[22:25], v[172:175], v[204:207], v[22:25]
	v_mfma_f32_16x16x32_bf16 v[18:21], v[180:183], v[204:207], v[18:21]
	v_mfma_f32_16x16x32_bf16 v[6:9], v[172:175], v[212:215], v[6:9]
	v_mfma_f32_16x16x32_bf16 v[2:5], v[180:183], v[212:215], v[2:5]
	s_setprio 2
	s_barrier
	s_add_i32 s62, s62, 2
	s_add_u32 s60, s60, 0x100
	s_addc_u32 s61, s61, 0
	s_cmp_gt_u32 s62, 41
	s_mov_b64 s[18:19], s[20:21]
	s_cbranch_scc0 .LBB0_2169
	s_and_b64 vcc, exec, s[14:15]
	s_cbranch_vccz .LBB0_2172
	s_barrier
